# top-k main loop (three of four layers): second half of the query fragment requested with the first at the top of the iteration, copied into place later
# baseline (speedup 1.0000x reference)
.LBB0_987:
	v_add_u32_e32 v2, v58, v53
	v_ashrrev_i32_e32 v3, 31, v2
	v_lshlrev_b64 v[2:3], 12, v[2:3]
	v_lshl_add_u64 v[56:57], v[54:55], 0, v[2:3]
	global_load_dwordx4 v[42:45], v[56:57], off
	global_load_dwordx4 v[38:41], v[56:57], off offset:64
	global_load_dwordx4 v[34:37], v[56:57], off offset:128
	global_load_dwordx4 v[30:33], v[56:57], off offset:192
	global_load_dwordx4 v[216:219], v[56:57], off offset:256
	global_load_dwordx4 v[220:223], v[56:57], off offset:320
	global_load_dwordx4 v[224:227], v[56:57], off offset:384
	global_load_dwordx4 v[228:231], v[56:57], off offset:448
	ds_read_b128 v[2:5], v64
	ds_read_b128 v[6:9], v64 offset:64
	v_add_u32_e32 v46, 8, v46
	s_waitcnt vmcnt(7) lgkmcnt(1)
	v_mfma_f32_16x16x32_bf16 v[2:5], v[42:45], v[2:5], 0
	ds_read_b128 v[10:13], v64 offset:4672
	ds_read_b128 v[14:17], v64 offset:9280
	ds_read_b128 v[18:21], v64 offset:13888
	s_waitcnt vmcnt(6) lgkmcnt(3)
	v_mfma_f32_16x16x32_bf16 v[2:5], v[38:41], v[6:9], v[2:5]
	ds_read_b128 v[6:9], v64 offset:128
	ds_read_b128 v[22:25], v64 offset:18496
	ds_read_b128 v[26:29], v64 offset:23104
	s_waitcnt vmcnt(5) lgkmcnt(2)
	v_mfma_f32_16x16x32_bf16 v[2:5], v[34:37], v[6:9], v[2:5]
	ds_read_b128 v[6:9], v64 offset:192
	ds_read_b128 v[80:83], v64 offset:27712
	s_waitcnt vmcnt(4) lgkmcnt(1)
	v_mfma_f32_16x16x32_bf16 v[2:5], v[30:33], v[6:9], v[2:5]
	ds_read_b128 v[6:9], v64 offset:4608
	s_waitcnt lgkmcnt(0)
	v_mfma_f32_16x16x32_bf16 v[6:9], v[42:45], v[6:9], 0
	v_mfma_f32_16x16x32_bf16 v[6:9], v[38:41], v[10:13], v[6:9]
	ds_read_b128 v[10:13], v64 offset:4736
	s_waitcnt lgkmcnt(0)
	v_mfma_f32_16x16x32_bf16 v[6:9], v[34:37], v[10:13], v[6:9]
	ds_read_b128 v[10:13], v64 offset:4800
	s_waitcnt lgkmcnt(0)
	v_mfma_f32_16x16x32_bf16 v[6:9], v[30:33], v[10:13], v[6:9]
	ds_read_b128 v[10:13], v64 offset:9216
	s_waitcnt lgkmcnt(0)
	v_mfma_f32_16x16x32_bf16 v[10:13], v[42:45], v[10:13], 0
	v_mfma_f32_16x16x32_bf16 v[10:13], v[38:41], v[14:17], v[10:13]
	ds_read_b128 v[14:17], v64 offset:9344
	s_waitcnt lgkmcnt(0)
	v_mfma_f32_16x16x32_bf16 v[10:13], v[34:37], v[14:17], v[10:13]
	ds_read_b128 v[14:17], v64 offset:9408
	s_waitcnt lgkmcnt(0)
	v_mfma_f32_16x16x32_bf16 v[10:13], v[30:33], v[14:17], v[10:13]
	ds_read_b128 v[14:17], v64 offset:13824
	s_waitcnt lgkmcnt(0)
	v_mfma_f32_16x16x32_bf16 v[14:17], v[42:45], v[14:17], 0
	v_mfma_f32_16x16x32_bf16 v[14:17], v[38:41], v[18:21], v[14:17]
	ds_read_b128 v[18:21], v64 offset:13952
	s_waitcnt lgkmcnt(0)
	v_mfma_f32_16x16x32_bf16 v[14:17], v[34:37], v[18:21], v[14:17]
	ds_read_b128 v[18:21], v64 offset:14016
	s_waitcnt lgkmcnt(0)
	v_mfma_f32_16x16x32_bf16 v[14:17], v[30:33], v[18:21], v[14:17]
	ds_read_b128 v[18:21], v64 offset:18432
	s_waitcnt lgkmcnt(0)
	v_mfma_f32_16x16x32_bf16 v[18:21], v[42:45], v[18:21], 0
	v_mfma_f32_16x16x32_bf16 v[18:21], v[38:41], v[22:25], v[18:21]
	ds_read_b128 v[22:25], v64 offset:18560
	s_waitcnt lgkmcnt(0)
	v_mfma_f32_16x16x32_bf16 v[18:21], v[34:37], v[22:25], v[18:21]
	ds_read_b128 v[22:25], v64 offset:18624
	s_waitcnt lgkmcnt(0)
	v_mfma_f32_16x16x32_bf16 v[18:21], v[30:33], v[22:25], v[18:21]
	ds_read_b128 v[22:25], v64 offset:23040
	s_waitcnt lgkmcnt(0)
	v_mfma_f32_16x16x32_bf16 v[22:25], v[42:45], v[22:25], 0
	v_mfma_f32_16x16x32_bf16 v[22:25], v[38:41], v[26:29], v[22:25]
	ds_read_b128 v[26:29], v64 offset:23168
	s_waitcnt lgkmcnt(0)
	v_mfma_f32_16x16x32_bf16 v[22:25], v[34:37], v[26:29], v[22:25]
	ds_read_b128 v[26:29], v64 offset:23232
	s_waitcnt lgkmcnt(0)
	v_mfma_f32_16x16x32_bf16 v[22:25], v[30:33], v[26:29], v[22:25]
	ds_read_b128 v[26:29], v64 offset:27648
	s_waitcnt lgkmcnt(0)
	v_mfma_f32_16x16x32_bf16 v[26:29], v[42:45], v[26:29], 0
	v_mfma_f32_16x16x32_bf16 v[26:29], v[38:41], v[80:83], v[26:29]
	ds_read_b128 v[80:83], v64 offset:27776
	s_waitcnt lgkmcnt(0)
	v_mfma_f32_16x16x32_bf16 v[26:29], v[34:37], v[80:83], v[26:29]
	ds_read_b128 v[80:83], v64 offset:27840
	s_waitcnt lgkmcnt(0)
	v_mfma_f32_16x16x32_bf16 v[26:29], v[30:33], v[80:83], v[26:29]
	ds_read_b128 v[80:83], v64 offset:32256
	s_waitcnt lgkmcnt(0)
	v_mfma_f32_16x16x32_bf16 v[42:45], v[42:45], v[80:83], 0
	ds_read_b128 v[80:83], v64 offset:32320
	s_waitcnt lgkmcnt(0)
	v_mfma_f32_16x16x32_bf16 v[38:41], v[38:41], v[80:83], v[42:45]
	s_nop 4
	ds_read_b128 v[42:45], v64 offset:32384
	s_waitcnt lgkmcnt(0)
	v_mfma_f32_16x16x32_bf16 v[34:37], v[34:37], v[42:45], v[38:41]
	s_nop 2
	ds_read_b128 v[38:41], v64 offset:32448
	s_waitcnt lgkmcnt(0)
	v_mfma_f32_16x16x32_bf16 v[30:33], v[30:33], v[38:41], v[34:37]
	s_nop 2
	v_ashrrev_i32_e32 v34, 31, v2
	v_bitop3_b32 v2, v34, v2, s2 bitop3:0x36
	v_ashrrev_i32_e32 v34, 31, v6
	v_bitop3_b32 v6, v34, v6, s2 bitop3:0x36
	v_ashrrev_i32_e32 v34, 31, v10
	v_bitop3_b32 v10, v34, v10, s2 bitop3:0x36
	v_ashrrev_i32_e32 v34, 31, v14
	v_bitop3_b32 v14, v34, v14, s2 bitop3:0x36
	v_ashrrev_i32_e32 v34, 31, v18
	v_bitop3_b32 v18, v34, v18, s2 bitop3:0x36
	v_ashrrev_i32_e32 v34, 31, v22
	v_bitop3_b32 v22, v34, v22, s2 bitop3:0x36
	v_ashrrev_i32_e32 v34, 31, v26
	v_bitop3_b32 v26, v34, v26, s2 bitop3:0x36
	v_ashrrev_i32_e32 v34, 31, v30
	v_bitop3_b32 v30, v34, v30, s2 bitop3:0x36
	v_and_or_b32 v2, v2, s55, v60
	v_and_or_b32 v6, v6, s55, v65
	v_and_or_b32 v10, v10, s55, v66
	v_and_or_b32 v14, v14, s55, v67
	v_and_or_b32 v18, v18, s55, v68
	v_and_or_b32 v22, v22, s55, v69
	v_and_or_b32 v26, v26, s55, v70
	v_and_or_b32 v30, v30, s55, v71
	v_max_u32_e32 v34, v2, v6
	v_min_u32_e32 v2, v2, v6
	v_max_u32_e32 v6, v10, v14
	v_min_u32_e32 v10, v10, v14
	v_max_u32_e32 v14, v18, v22
	v_min_u32_e32 v18, v18, v22
	v_max_u32_e32 v22, v26, v30
	v_min_u32_e32 v26, v26, v30
	v_max_u32_e32 v30, v34, v6
	v_min_u32_e32 v6, v34, v6
	v_max_u32_e32 v34, v2, v10
	v_min_u32_e32 v2, v2, v10
	v_max_u32_e32 v10, v14, v22
	v_min_u32_e32 v14, v14, v22
	v_max_u32_e32 v22, v18, v26
	v_min_u32_e32 v18, v18, v26
	v_max_u32_e32 v26, v34, v6
	v_min_u32_e32 v6, v34, v6
	v_max_u32_e32 v34, v22, v14
	v_min_u32_e32 v14, v22, v14
	v_max_u32_e32 v22, v30, v10
	v_min_u32_e32 v10, v30, v10
	v_max_u32_e32 v30, v26, v34
	v_min_u32_e32 v26, v26, v34
	v_max_u32_e32 v34, v6, v14
	v_min_u32_e32 v6, v6, v14
	v_max_u32_e32 v14, v2, v18
	v_min_u32_e32 v2, v2, v18
	v_max_u32_e32 v18, v34, v10
	v_min_u32_e32 v10, v34, v10
	v_max_u32_e32 v34, v14, v26
	v_min_u32_e32 v14, v14, v26
	v_max_u32_e32 v26, v30, v18
	v_min_u32_e32 v18, v30, v18
	v_max_u32_e32 v30, v34, v10
	v_min_u32_e32 v10, v34, v10
	v_max_u32_e32 v34, v14, v6
	v_min_u32_e32 v6, v14, v6
	v_max_u32_dpp v14, v22, v22 quad_perm:[1,0,3,2] row_mask:0xf bank_mask:0xf bound_ctrl:1
	s_nop 1
	v_max_u32_dpp v14, v14, v14 quad_perm:[2,3,0,1] row_mask:0xf bank_mask:0xf bound_ctrl:1
	s_nop 1
	v_max_u32_dpp v14, v14, v14 row_half_mirror row_mask:0xf bank_mask:0xf bound_ctrl:1
	s_nop 1
	v_max_u32_dpp v14, v14, v14 row_mirror row_mask:0xf bank_mask:0xf bound_ctrl:1
	v_cmp_eq_u32_e32 vcc, v22, v14
	v_cndmask_b32_e64 v35, 0, v14, s[8:9]
	s_nop 0
	v_cndmask_b32_e32 v14, v22, v26, vcc
	v_cndmask_b32_e32 v22, v26, v18, vcc
	v_cndmask_b32_e32 v18, v18, v30, vcc
	v_cndmask_b32_e32 v26, v30, v10, vcc
	v_cndmask_b32_e32 v10, v10, v34, vcc
	v_cndmask_b32_e32 v30, v34, v6, vcc
	v_max_u32_dpp v34, v14, v14 quad_perm:[1,0,3,2] row_mask:0xf bank_mask:0xf bound_ctrl:1
	v_cndmask_b32_e32 v6, v6, v2, vcc
	v_cndmask_b32_e64 v2, v2, 0, vcc
	v_max_u32_dpp v34, v34, v34 quad_perm:[2,3,0,1] row_mask:0xf bank_mask:0xf bound_ctrl:1
	s_nop 1
	v_max_u32_dpp v34, v34, v34 row_half_mirror row_mask:0xf bank_mask:0xf bound_ctrl:1
	s_nop 1
	v_max_u32_dpp v34, v34, v34 row_mirror row_mask:0xf bank_mask:0xf bound_ctrl:1
	v_cmp_eq_u32_e32 vcc, v14, v34
	v_cndmask_b32_e64 v35, v35, v34, s[10:11]
	s_nop 0
	v_cndmask_b32_e32 v14, v14, v22, vcc
	v_cndmask_b32_e32 v22, v22, v18, vcc
	v_cndmask_b32_e32 v18, v18, v26, vcc
	v_max_u32_dpp v34, v14, v14 quad_perm:[1,0,3,2] row_mask:0xf bank_mask:0xf bound_ctrl:1
	v_cndmask_b32_e32 v26, v26, v10, vcc
	v_cndmask_b32_e32 v10, v10, v30, vcc
	v_max_u32_dpp v34, v34, v34 quad_perm:[2,3,0,1] row_mask:0xf bank_mask:0xf bound_ctrl:1
	v_cndmask_b32_e32 v30, v30, v6, vcc
	v_cndmask_b32_e32 v6, v6, v2, vcc
	v_max_u32_dpp v34, v34, v34 row_half_mirror row_mask:0xf bank_mask:0xf bound_ctrl:1
	v_cndmask_b32_e64 v2, v2, 0, vcc
	s_nop 0
	v_max_u32_dpp v34, v34, v34 row_mirror row_mask:0xf bank_mask:0xf bound_ctrl:1
	v_cmp_eq_u32_e32 vcc, v14, v34
	v_cndmask_b32_e64 v35, v35, v34, s[12:13]
	s_nop 0
	v_cndmask_b32_e32 v14, v14, v22, vcc
	v_cndmask_b32_e32 v22, v22, v18, vcc
	v_cndmask_b32_e32 v18, v18, v26, vcc
	v_max_u32_dpp v34, v14, v14 quad_perm:[1,0,3,2] row_mask:0xf bank_mask:0xf bound_ctrl:1
	v_cndmask_b32_e32 v26, v26, v10, vcc
	v_cndmask_b32_e32 v10, v10, v30, vcc
	v_max_u32_dpp v34, v34, v34 quad_perm:[2,3,0,1] row_mask:0xf bank_mask:0xf bound_ctrl:1
	v_cndmask_b32_e32 v30, v30, v6, vcc
	v_cndmask_b32_e32 v6, v6, v2, vcc
	v_max_u32_dpp v34, v34, v34 row_half_mirror row_mask:0xf bank_mask:0xf bound_ctrl:1
	v_cndmask_b32_e64 v2, v2, 0, vcc
	s_nop 0
	v_max_u32_dpp v34, v34, v34 row_mirror row_mask:0xf bank_mask:0xf bound_ctrl:1
	v_cmp_eq_u32_e32 vcc, v14, v34
	v_cndmask_b32_e64 v35, v35, v34, s[14:15]
	s_nop 0
	v_cndmask_b32_e32 v14, v14, v22, vcc
	v_cndmask_b32_e32 v22, v22, v18, vcc
	v_cndmask_b32_e32 v18, v18, v26, vcc
	v_max_u32_dpp v34, v14, v14 quad_perm:[1,0,3,2] row_mask:0xf bank_mask:0xf bound_ctrl:1
	v_cndmask_b32_e32 v26, v26, v10, vcc
	v_cndmask_b32_e32 v10, v10, v30, vcc
	v_max_u32_dpp v34, v34, v34 quad_perm:[2,3,0,1] row_mask:0xf bank_mask:0xf bound_ctrl:1
	v_cndmask_b32_e32 v30, v30, v6, vcc
	v_cndmask_b32_e32 v6, v6, v2, vcc
	v_max_u32_dpp v34, v34, v34 row_half_mirror row_mask:0xf bank_mask:0xf bound_ctrl:1
	v_cndmask_b32_e64 v2, v2, 0, vcc
	s_nop 0
	v_max_u32_dpp v34, v34, v34 row_mirror row_mask:0xf bank_mask:0xf bound_ctrl:1
	v_cmp_eq_u32_e32 vcc, v14, v34
	v_cndmask_b32_e64 v35, v35, v34, s[16:17]
	s_nop 0
	v_cndmask_b32_e32 v14, v14, v22, vcc
	v_cndmask_b32_e32 v22, v22, v18, vcc
	v_cndmask_b32_e32 v18, v18, v26, vcc
	v_max_u32_dpp v34, v14, v14 quad_perm:[1,0,3,2] row_mask:0xf bank_mask:0xf bound_ctrl:1
	v_cndmask_b32_e32 v26, v26, v10, vcc
	v_cndmask_b32_e32 v10, v10, v30, vcc
	v_max_u32_dpp v34, v34, v34 quad_perm:[2,3,0,1] row_mask:0xf bank_mask:0xf bound_ctrl:1
	v_cndmask_b32_e32 v30, v30, v6, vcc
	v_cndmask_b32_e32 v6, v6, v2, vcc
	v_max_u32_dpp v34, v34, v34 row_half_mirror row_mask:0xf bank_mask:0xf bound_ctrl:1
	v_cndmask_b32_e64 v2, v2, 0, vcc
	s_nop 0
	v_max_u32_dpp v34, v34, v34 row_mirror row_mask:0xf bank_mask:0xf bound_ctrl:1
	v_cmp_eq_u32_e32 vcc, v14, v34
	v_cndmask_b32_e64 v35, v35, v34, s[18:19]
	s_nop 0
	v_cndmask_b32_e32 v14, v14, v22, vcc
	v_cndmask_b32_e32 v22, v22, v18, vcc
	v_cndmask_b32_e32 v18, v18, v26, vcc
	v_max_u32_dpp v34, v14, v14 quad_perm:[1,0,3,2] row_mask:0xf bank_mask:0xf bound_ctrl:1
	v_cndmask_b32_e32 v26, v26, v10, vcc
	v_cndmask_b32_e32 v10, v10, v30, vcc
	v_max_u32_dpp v34, v34, v34 quad_perm:[2,3,0,1] row_mask:0xf bank_mask:0xf bound_ctrl:1
	v_cndmask_b32_e32 v30, v30, v6, vcc
	v_cndmask_b32_e32 v6, v6, v2, vcc
	v_max_u32_dpp v34, v34, v34 row_half_mirror row_mask:0xf bank_mask:0xf bound_ctrl:1
	v_cndmask_b32_e64 v2, v2, 0, vcc
	s_nop 0
	v_max_u32_dpp v34, v34, v34 row_mirror row_mask:0xf bank_mask:0xf bound_ctrl:1
	v_cmp_eq_u32_e32 vcc, v14, v34
	v_cndmask_b32_e64 v35, v35, v34, s[20:21]
	s_nop 0
	v_cndmask_b32_e32 v14, v14, v22, vcc
	v_cndmask_b32_e32 v22, v22, v18, vcc
	v_cndmask_b32_e32 v18, v18, v26, vcc
	v_max_u32_dpp v34, v14, v14 quad_perm:[1,0,3,2] row_mask:0xf bank_mask:0xf bound_ctrl:1
	v_cndmask_b32_e32 v26, v26, v10, vcc
	v_cndmask_b32_e32 v10, v10, v30, vcc
	v_max_u32_dpp v34, v34, v34 quad_perm:[2,3,0,1] row_mask:0xf bank_mask:0xf bound_ctrl:1
	v_cndmask_b32_e32 v30, v30, v6, vcc
	v_cndmask_b32_e32 v6, v6, v2, vcc
	v_max_u32_dpp v34, v34, v34 row_half_mirror row_mask:0xf bank_mask:0xf bound_ctrl:1
	v_cndmask_b32_e64 v2, v2, 0, vcc
	s_nop 0
	v_max_u32_dpp v34, v34, v34 row_mirror row_mask:0xf bank_mask:0xf bound_ctrl:1
	v_cmp_eq_u32_e32 vcc, v14, v34
	v_cndmask_b32_e64 v35, v35, v34, s[22:23]
	s_nop 0
	v_cndmask_b32_e32 v14, v14, v22, vcc
	v_cndmask_b32_e32 v22, v22, v18, vcc
	v_cndmask_b32_e32 v18, v18, v26, vcc
	v_max_u32_dpp v34, v14, v14 quad_perm:[1,0,3,2] row_mask:0xf bank_mask:0xf bound_ctrl:1
	v_cndmask_b32_e32 v26, v26, v10, vcc
	v_cndmask_b32_e32 v10, v10, v30, vcc
	v_max_u32_dpp v34, v34, v34 quad_perm:[2,3,0,1] row_mask:0xf bank_mask:0xf bound_ctrl:1
	v_cndmask_b32_e32 v30, v30, v6, vcc
	v_cndmask_b32_e32 v6, v6, v2, vcc
	v_max_u32_dpp v34, v34, v34 row_half_mirror row_mask:0xf bank_mask:0xf bound_ctrl:1
	v_cndmask_b32_e64 v2, v2, 0, vcc
	s_nop 0
	v_max_u32_dpp v34, v34, v34 row_mirror row_mask:0xf bank_mask:0xf bound_ctrl:1
	v_cmp_eq_u32_e32 vcc, v14, v34
	v_cndmask_b32_e64 v35, v35, v34, s[24:25]
	s_nop 0
	v_cndmask_b32_e32 v14, v14, v22, vcc
	v_cndmask_b32_e32 v22, v22, v18, vcc
	v_cndmask_b32_e32 v18, v18, v26, vcc
	v_cndmask_b32_e32 v26, v26, v10, vcc
	v_cndmask_b32_e32 v10, v10, v30, vcc
	v_cndmask_b32_e32 v30, v30, v6, vcc
	v_cndmask_b32_e32 v2, v6, v2, vcc
	v_max_u32_dpp v6, v14, v14 quad_perm:[1,0,3,2] row_mask:0xf bank_mask:0xf bound_ctrl:1
	s_nop 1
	v_max_u32_dpp v6, v6, v6 quad_perm:[2,3,0,1] row_mask:0xf bank_mask:0xf bound_ctrl:1
	s_nop 1
	v_max_u32_dpp v6, v6, v6 row_half_mirror row_mask:0xf bank_mask:0xf bound_ctrl:1
	s_nop 1
	v_max_u32_dpp v6, v6, v6 row_mirror row_mask:0xf bank_mask:0xf bound_ctrl:1
	v_cmp_eq_u32_e32 vcc, v14, v6
	v_cndmask_b32_e64 v34, v35, v6, s[26:27]
	s_nop 0
	v_cndmask_b32_e32 v6, v14, v22, vcc
	v_cndmask_b32_e32 v14, v22, v18, vcc
	v_cndmask_b32_e32 v18, v18, v26, vcc
	v_cndmask_b32_e32 v22, v26, v10, vcc
	v_max_u32_dpp v26, v6, v6 quad_perm:[1,0,3,2] row_mask:0xf bank_mask:0xf bound_ctrl:1
	v_cndmask_b32_e32 v10, v10, v30, vcc
	v_cndmask_b32_e32 v2, v30, v2, vcc
	v_max_u32_dpp v26, v26, v26 quad_perm:[2,3,0,1] row_mask:0xf bank_mask:0xf bound_ctrl:1
	s_nop 1
	v_max_u32_dpp v26, v26, v26 row_half_mirror row_mask:0xf bank_mask:0xf bound_ctrl:1
	s_nop 1
	v_max_u32_dpp v26, v26, v26 row_mirror row_mask:0xf bank_mask:0xf bound_ctrl:1
	v_cmp_eq_u32_e32 vcc, v6, v26
	v_cndmask_b32_e64 v30, v34, v26, s[28:29]
	s_nop 0
	v_cndmask_b32_e32 v6, v6, v14, vcc
	v_cndmask_b32_e32 v14, v14, v18, vcc
	v_cndmask_b32_e32 v18, v18, v22, vcc
	v_cndmask_b32_e32 v22, v22, v10, vcc
	v_cndmask_b32_e32 v2, v10, v2, vcc
	v_max_u32_dpp v10, v6, v6 quad_perm:[1,0,3,2] row_mask:0xf bank_mask:0xf bound_ctrl:1
	s_nop 1
	v_max_u32_dpp v10, v10, v10 quad_perm:[2,3,0,1] row_mask:0xf bank_mask:0xf bound_ctrl:1
	s_nop 1
	v_max_u32_dpp v10, v10, v10 row_half_mirror row_mask:0xf bank_mask:0xf bound_ctrl:1
	s_nop 1
	v_max_u32_dpp v10, v10, v10 row_mirror row_mask:0xf bank_mask:0xf bound_ctrl:1
	v_cmp_eq_u32_e32 vcc, v6, v10
	v_cndmask_b32_e64 v26, v30, v10, s[30:31]
	s_nop 0
	v_cndmask_b32_e32 v6, v6, v14, vcc
	v_cndmask_b32_e32 v10, v14, v18, vcc
	v_cndmask_b32_e32 v14, v18, v22, vcc
	v_max_u32_dpp v18, v6, v6 quad_perm:[1,0,3,2] row_mask:0xf bank_mask:0xf bound_ctrl:1
	v_cndmask_b32_e32 v2, v22, v2, vcc
	s_nop 0
	v_max_u32_dpp v18, v18, v18 quad_perm:[2,3,0,1] row_mask:0xf bank_mask:0xf bound_ctrl:1
	s_nop 1
	v_max_u32_dpp v18, v18, v18 row_half_mirror row_mask:0xf bank_mask:0xf bound_ctrl:1
	s_nop 1
	v_max_u32_dpp v18, v18, v18 row_mirror row_mask:0xf bank_mask:0xf bound_ctrl:1
	v_cmp_eq_u32_e32 vcc, v6, v18
	v_cndmask_b32_e64 v22, v26, v18, s[34:35]
	s_nop 0
	v_cndmask_b32_e32 v6, v6, v10, vcc
	v_cndmask_b32_e32 v10, v10, v14, vcc
	v_cndmask_b32_e32 v2, v14, v2, vcc
	v_max_u32_dpp v14, v6, v6 quad_perm:[1,0,3,2] row_mask:0xf bank_mask:0xf bound_ctrl:1
	s_nop 1
	v_max_u32_dpp v14, v14, v14 quad_perm:[2,3,0,1] row_mask:0xf bank_mask:0xf bound_ctrl:1
	s_nop 1
	v_max_u32_dpp v14, v14, v14 row_half_mirror row_mask:0xf bank_mask:0xf bound_ctrl:1
	s_nop 1
	v_max_u32_dpp v14, v14, v14 row_mirror row_mask:0xf bank_mask:0xf bound_ctrl:1
	v_cmp_eq_u32_e32 vcc, v6, v14
	v_cndmask_b32_e64 v18, v22, v14, s[36:37]
	s_nop 0
	v_cndmask_b32_e32 v6, v6, v10, vcc
	v_cndmask_b32_e32 v2, v10, v2, vcc
	s_nop 0
	v_max_u32_dpp v10, v6, v6 quad_perm:[1,0,3,2] row_mask:0xf bank_mask:0xf bound_ctrl:1
	s_nop 1
	v_max_u32_dpp v10, v10, v10 quad_perm:[2,3,0,1] row_mask:0xf bank_mask:0xf bound_ctrl:1
	s_nop 1
	v_max_u32_dpp v10, v10, v10 row_half_mirror row_mask:0xf bank_mask:0xf bound_ctrl:1
	s_nop 1
	v_max_u32_dpp v10, v10, v10 row_mirror row_mask:0xf bank_mask:0xf bound_ctrl:1
	v_cmp_eq_u32_e32 vcc, v6, v10
	v_cndmask_b32_e64 v14, v18, v10, s[38:39]
	v_ashrrev_i32_e32 v10, 31, v19
	v_cndmask_b32_e32 v2, v6, v2, vcc
	v_ashrrev_i32_e32 v6, 31, v11
	v_bitop3_b32 v6, v6, v11, s2 bitop3:0x36
	v_max_u32_dpp v2, v2, v2 quad_perm:[1,0,3,2] row_mask:0xf bank_mask:0xf bound_ctrl:1
	v_ashrrev_i32_e32 v11, 31, v23
	v_bitop3_b32 v10, v10, v19, s2 bitop3:0x36
	v_max_u32_dpp v2, v2, v2 quad_perm:[2,3,0,1] row_mask:0xf bank_mask:0xf bound_ctrl:1
	v_bitop3_b32 v11, v11, v23, s2 bitop3:0x36
	v_and_or_b32 v6, v6, s55, v66
	v_max_u32_dpp v2, v2, v2 row_half_mirror row_mask:0xf bank_mask:0xf bound_ctrl:1
	v_and_or_b32 v10, v10, s55, v68
	v_and_or_b32 v11, v11, s55, v69
	v_max_u32_dpp v2, v2, v2 row_mirror row_mask:0xf bank_mask:0xf bound_ctrl:1
	v_cndmask_b32_e64 v82, v14, v2, s[40:41]
	v_ashrrev_i32_e32 v2, 31, v3
	v_bitop3_b32 v2, v2, v3, s2 bitop3:0x36
	v_ashrrev_i32_e32 v3, 31, v7
	v_bitop3_b32 v3, v3, v7, s2 bitop3:0x36
	v_ashrrev_i32_e32 v7, 31, v15
	v_bitop3_b32 v7, v7, v15, s2 bitop3:0x36
	v_ashrrev_i32_e32 v14, 31, v27
	v_ashrrev_i32_e32 v15, 31, v31
	v_bitop3_b32 v14, v14, v27, s2 bitop3:0x36
	v_bitop3_b32 v15, v15, v31, s2 bitop3:0x36
	v_and_or_b32 v2, v2, s55, v60
	v_and_or_b32 v3, v3, s55, v65
	v_and_or_b32 v7, v7, s55, v67
	v_and_or_b32 v14, v14, s55, v70
	v_and_or_b32 v15, v15, s55, v71
	v_max_u32_e32 v18, v2, v3
	v_min_u32_e32 v2, v2, v3
	v_max_u32_e32 v3, v6, v7
	v_min_u32_e32 v6, v6, v7
	v_max_u32_e32 v7, v10, v11
	v_min_u32_e32 v10, v10, v11
	v_max_u32_e32 v11, v14, v15
	v_min_u32_e32 v14, v14, v15
	v_max_u32_e32 v15, v18, v3
	v_min_u32_e32 v3, v18, v3
	v_max_u32_e32 v18, v2, v6
	v_min_u32_e32 v2, v2, v6
	v_max_u32_e32 v6, v7, v11
	v_min_u32_e32 v7, v7, v11
	v_max_u32_e32 v11, v10, v14
	v_min_u32_e32 v10, v10, v14
	v_max_u32_e32 v14, v18, v3
	v_min_u32_e32 v3, v18, v3
	v_max_u32_e32 v18, v11, v7
	v_min_u32_e32 v7, v11, v7
	v_max_u32_e32 v11, v15, v6
	v_min_u32_e32 v6, v15, v6
	v_max_u32_e32 v15, v14, v18
	v_min_u32_e32 v14, v14, v18
	v_max_u32_e32 v18, v3, v7
	v_min_u32_e32 v3, v3, v7
	v_max_u32_e32 v7, v2, v10
	v_min_u32_e32 v2, v2, v10
	v_max_u32_e32 v10, v18, v6
	v_min_u32_e32 v6, v18, v6
	v_max_u32_e32 v18, v7, v14
	v_min_u32_e32 v7, v7, v14
	v_max_u32_e32 v14, v15, v10
	v_min_u32_e32 v10, v15, v10
	v_max_u32_e32 v15, v18, v6
	v_min_u32_e32 v6, v18, v6
	v_max_u32_e32 v18, v7, v3
	v_min_u32_e32 v3, v7, v3
	v_max_u32_dpp v7, v11, v11 quad_perm:[1,0,3,2] row_mask:0xf bank_mask:0xf bound_ctrl:1
	s_nop 1
	v_max_u32_dpp v7, v7, v7 quad_perm:[2,3,0,1] row_mask:0xf bank_mask:0xf bound_ctrl:1
	s_nop 1
	v_max_u32_dpp v7, v7, v7 row_half_mirror row_mask:0xf bank_mask:0xf bound_ctrl:1
	s_nop 1
	v_max_u32_dpp v7, v7, v7 row_mirror row_mask:0xf bank_mask:0xf bound_ctrl:1
	v_cmp_eq_u32_e32 vcc, v11, v7
	v_cndmask_b32_e64 v19, 0, v7, s[8:9]
	s_nop 0
	v_cndmask_b32_e32 v7, v11, v14, vcc
	v_cndmask_b32_e32 v11, v14, v10, vcc
	v_cndmask_b32_e32 v10, v10, v15, vcc
	v_cndmask_b32_e32 v14, v15, v6, vcc
	v_cndmask_b32_e32 v6, v6, v18, vcc
	v_cndmask_b32_e32 v15, v18, v3, vcc
	v_max_u32_dpp v18, v7, v7 quad_perm:[1,0,3,2] row_mask:0xf bank_mask:0xf bound_ctrl:1
	v_cndmask_b32_e32 v3, v3, v2, vcc
	v_cndmask_b32_e64 v2, v2, 0, vcc
	v_max_u32_dpp v18, v18, v18 quad_perm:[2,3,0,1] row_mask:0xf bank_mask:0xf bound_ctrl:1
	s_nop 1
	v_max_u32_dpp v18, v18, v18 row_half_mirror row_mask:0xf bank_mask:0xf bound_ctrl:1
	s_nop 1
	v_max_u32_dpp v18, v18, v18 row_mirror row_mask:0xf bank_mask:0xf bound_ctrl:1
	v_cmp_eq_u32_e32 vcc, v7, v18
	v_cndmask_b32_e64 v19, v19, v18, s[10:11]
	s_nop 0
	v_cndmask_b32_e32 v7, v7, v11, vcc
	v_cndmask_b32_e32 v11, v11, v10, vcc
	v_cndmask_b32_e32 v10, v10, v14, vcc
	v_max_u32_dpp v18, v7, v7 quad_perm:[1,0,3,2] row_mask:0xf bank_mask:0xf bound_ctrl:1
	v_cndmask_b32_e32 v14, v14, v6, vcc
	v_cndmask_b32_e32 v6, v6, v15, vcc
	v_max_u32_dpp v18, v18, v18 quad_perm:[2,3,0,1] row_mask:0xf bank_mask:0xf bound_ctrl:1
	v_cndmask_b32_e32 v15, v15, v3, vcc
	v_cndmask_b32_e32 v3, v3, v2, vcc
	v_max_u32_dpp v18, v18, v18 row_half_mirror row_mask:0xf bank_mask:0xf bound_ctrl:1
	v_cndmask_b32_e64 v2, v2, 0, vcc
	s_nop 0
	v_max_u32_dpp v18, v18, v18 row_mirror row_mask:0xf bank_mask:0xf bound_ctrl:1
	v_cmp_eq_u32_e32 vcc, v7, v18
	v_cndmask_b32_e64 v19, v19, v18, s[12:13]
	s_nop 0
	v_cndmask_b32_e32 v7, v7, v11, vcc
	v_cndmask_b32_e32 v11, v11, v10, vcc
	v_cndmask_b32_e32 v10, v10, v14, vcc
	v_max_u32_dpp v18, v7, v7 quad_perm:[1,0,3,2] row_mask:0xf bank_mask:0xf bound_ctrl:1
	v_cndmask_b32_e32 v14, v14, v6, vcc
	v_cndmask_b32_e32 v6, v6, v15, vcc
	v_max_u32_dpp v18, v18, v18 quad_perm:[2,3,0,1] row_mask:0xf bank_mask:0xf bound_ctrl:1
	v_cndmask_b32_e32 v15, v15, v3, vcc
	v_cndmask_b32_e32 v3, v3, v2, vcc
	v_max_u32_dpp v18, v18, v18 row_half_mirror row_mask:0xf bank_mask:0xf bound_ctrl:1
	v_cndmask_b32_e64 v2, v2, 0, vcc
	s_nop 0
	v_max_u32_dpp v18, v18, v18 row_mirror row_mask:0xf bank_mask:0xf bound_ctrl:1
	v_cmp_eq_u32_e32 vcc, v7, v18
	v_cndmask_b32_e64 v19, v19, v18, s[14:15]
	s_nop 0
	v_cndmask_b32_e32 v7, v7, v11, vcc
	v_cndmask_b32_e32 v11, v11, v10, vcc
	v_cndmask_b32_e32 v10, v10, v14, vcc
	v_max_u32_dpp v18, v7, v7 quad_perm:[1,0,3,2] row_mask:0xf bank_mask:0xf bound_ctrl:1
	v_cndmask_b32_e32 v14, v14, v6, vcc
	v_cndmask_b32_e32 v6, v6, v15, vcc
	v_max_u32_dpp v18, v18, v18 quad_perm:[2,3,0,1] row_mask:0xf bank_mask:0xf bound_ctrl:1
	v_cndmask_b32_e32 v15, v15, v3, vcc
	v_cndmask_b32_e32 v3, v3, v2, vcc
	v_max_u32_dpp v18, v18, v18 row_half_mirror row_mask:0xf bank_mask:0xf bound_ctrl:1
	v_cndmask_b32_e64 v2, v2, 0, vcc
	s_nop 0
	v_max_u32_dpp v18, v18, v18 row_mirror row_mask:0xf bank_mask:0xf bound_ctrl:1
	v_cmp_eq_u32_e32 vcc, v7, v18
	v_cndmask_b32_e64 v19, v19, v18, s[16:17]
	s_nop 0
	v_cndmask_b32_e32 v7, v7, v11, vcc
	v_cndmask_b32_e32 v11, v11, v10, vcc
	v_cndmask_b32_e32 v10, v10, v14, vcc
	v_max_u32_dpp v18, v7, v7 quad_perm:[1,0,3,2] row_mask:0xf bank_mask:0xf bound_ctrl:1
	v_cndmask_b32_e32 v14, v14, v6, vcc
	v_cndmask_b32_e32 v6, v6, v15, vcc
	v_max_u32_dpp v18, v18, v18 quad_perm:[2,3,0,1] row_mask:0xf bank_mask:0xf bound_ctrl:1
	v_cndmask_b32_e32 v15, v15, v3, vcc
	v_cndmask_b32_e32 v3, v3, v2, vcc
	v_max_u32_dpp v18, v18, v18 row_half_mirror row_mask:0xf bank_mask:0xf bound_ctrl:1
	v_cndmask_b32_e64 v2, v2, 0, vcc
	s_nop 0
	v_max_u32_dpp v18, v18, v18 row_mirror row_mask:0xf bank_mask:0xf bound_ctrl:1
	v_cmp_eq_u32_e32 vcc, v7, v18
	v_cndmask_b32_e64 v19, v19, v18, s[18:19]
	s_nop 0
	v_cndmask_b32_e32 v7, v7, v11, vcc
	v_cndmask_b32_e32 v11, v11, v10, vcc
	v_cndmask_b32_e32 v10, v10, v14, vcc
	v_max_u32_dpp v18, v7, v7 quad_perm:[1,0,3,2] row_mask:0xf bank_mask:0xf bound_ctrl:1
	v_cndmask_b32_e32 v14, v14, v6, vcc
	v_cndmask_b32_e32 v6, v6, v15, vcc
	v_max_u32_dpp v18, v18, v18 quad_perm:[2,3,0,1] row_mask:0xf bank_mask:0xf bound_ctrl:1
	v_cndmask_b32_e32 v15, v15, v3, vcc
	v_cndmask_b32_e32 v3, v3, v2, vcc
	v_max_u32_dpp v18, v18, v18 row_half_mirror row_mask:0xf bank_mask:0xf bound_ctrl:1
	v_cndmask_b32_e64 v2, v2, 0, vcc
	s_nop 0
	v_max_u32_dpp v18, v18, v18 row_mirror row_mask:0xf bank_mask:0xf bound_ctrl:1
	v_cmp_eq_u32_e32 vcc, v7, v18
	v_cndmask_b32_e64 v19, v19, v18, s[20:21]
	s_nop 0
	v_cndmask_b32_e32 v7, v7, v11, vcc
	v_cndmask_b32_e32 v11, v11, v10, vcc
	v_cndmask_b32_e32 v10, v10, v14, vcc
	v_max_u32_dpp v18, v7, v7 quad_perm:[1,0,3,2] row_mask:0xf bank_mask:0xf bound_ctrl:1
	v_cndmask_b32_e32 v14, v14, v6, vcc
	v_cndmask_b32_e32 v6, v6, v15, vcc
	v_max_u32_dpp v18, v18, v18 quad_perm:[2,3,0,1] row_mask:0xf bank_mask:0xf bound_ctrl:1
	v_cndmask_b32_e32 v15, v15, v3, vcc
	v_cndmask_b32_e32 v3, v3, v2, vcc
	v_max_u32_dpp v18, v18, v18 row_half_mirror row_mask:0xf bank_mask:0xf bound_ctrl:1
	v_cndmask_b32_e64 v2, v2, 0, vcc
	s_nop 0
	v_max_u32_dpp v18, v18, v18 row_mirror row_mask:0xf bank_mask:0xf bound_ctrl:1
	v_cmp_eq_u32_e32 vcc, v7, v18
	v_cndmask_b32_e64 v19, v19, v18, s[22:23]
	s_nop 0
	v_cndmask_b32_e32 v7, v7, v11, vcc
	v_cndmask_b32_e32 v11, v11, v10, vcc
	v_cndmask_b32_e32 v10, v10, v14, vcc
	v_max_u32_dpp v18, v7, v7 quad_perm:[1,0,3,2] row_mask:0xf bank_mask:0xf bound_ctrl:1
	v_cndmask_b32_e32 v14, v14, v6, vcc
	v_cndmask_b32_e32 v6, v6, v15, vcc
	v_max_u32_dpp v18, v18, v18 quad_perm:[2,3,0,1] row_mask:0xf bank_mask:0xf bound_ctrl:1
	v_cndmask_b32_e32 v15, v15, v3, vcc
	v_cndmask_b32_e32 v3, v3, v2, vcc
	v_max_u32_dpp v18, v18, v18 row_half_mirror row_mask:0xf bank_mask:0xf bound_ctrl:1
	v_cndmask_b32_e64 v2, v2, 0, vcc
	s_nop 0
	v_max_u32_dpp v18, v18, v18 row_mirror row_mask:0xf bank_mask:0xf bound_ctrl:1
	v_cmp_eq_u32_e32 vcc, v7, v18
	v_cndmask_b32_e64 v19, v19, v18, s[24:25]
	s_nop 0
	v_cndmask_b32_e32 v7, v7, v11, vcc
	v_cndmask_b32_e32 v11, v11, v10, vcc
	v_cndmask_b32_e32 v10, v10, v14, vcc
	v_cndmask_b32_e32 v14, v14, v6, vcc
	v_cndmask_b32_e32 v6, v6, v15, vcc
	v_cndmask_b32_e32 v15, v15, v3, vcc
	v_cndmask_b32_e32 v2, v3, v2, vcc
	v_max_u32_dpp v3, v7, v7 quad_perm:[1,0,3,2] row_mask:0xf bank_mask:0xf bound_ctrl:1
	s_nop 1
	v_max_u32_dpp v3, v3, v3 quad_perm:[2,3,0,1] row_mask:0xf bank_mask:0xf bound_ctrl:1
	s_nop 1
	v_max_u32_dpp v3, v3, v3 row_half_mirror row_mask:0xf bank_mask:0xf bound_ctrl:1
	s_nop 1
	v_max_u32_dpp v3, v3, v3 row_mirror row_mask:0xf bank_mask:0xf bound_ctrl:1
	v_cmp_eq_u32_e32 vcc, v7, v3
	v_cndmask_b32_e64 v18, v19, v3, s[26:27]
	s_nop 0
	v_cndmask_b32_e32 v3, v7, v11, vcc
	v_cndmask_b32_e32 v7, v11, v10, vcc
	v_cndmask_b32_e32 v10, v10, v14, vcc
	v_cndmask_b32_e32 v11, v14, v6, vcc
	v_max_u32_dpp v14, v3, v3 quad_perm:[1,0,3,2] row_mask:0xf bank_mask:0xf bound_ctrl:1
	v_cndmask_b32_e32 v6, v6, v15, vcc
	v_cndmask_b32_e32 v2, v15, v2, vcc
	v_max_u32_dpp v14, v14, v14 quad_perm:[2,3,0,1] row_mask:0xf bank_mask:0xf bound_ctrl:1
	s_nop 1
	v_max_u32_dpp v14, v14, v14 row_half_mirror row_mask:0xf bank_mask:0xf bound_ctrl:1
	s_nop 1
	v_max_u32_dpp v14, v14, v14 row_mirror row_mask:0xf bank_mask:0xf bound_ctrl:1
	v_cmp_eq_u32_e32 vcc, v3, v14
	v_cndmask_b32_e64 v15, v18, v14, s[28:29]
	s_nop 0
	v_cndmask_b32_e32 v3, v3, v7, vcc
	v_cndmask_b32_e32 v7, v7, v10, vcc
	v_cndmask_b32_e32 v10, v10, v11, vcc
	v_cndmask_b32_e32 v11, v11, v6, vcc
	v_cndmask_b32_e32 v2, v6, v2, vcc
	v_max_u32_dpp v6, v3, v3 quad_perm:[1,0,3,2] row_mask:0xf bank_mask:0xf bound_ctrl:1
	s_nop 1
	v_max_u32_dpp v6, v6, v6 quad_perm:[2,3,0,1] row_mask:0xf bank_mask:0xf bound_ctrl:1
	s_nop 1
	v_max_u32_dpp v6, v6, v6 row_half_mirror row_mask:0xf bank_mask:0xf bound_ctrl:1
	s_nop 1
	v_max_u32_dpp v6, v6, v6 row_mirror row_mask:0xf bank_mask:0xf bound_ctrl:1
	v_cmp_eq_u32_e32 vcc, v3, v6
	v_cndmask_b32_e64 v14, v15, v6, s[30:31]
	s_nop 0
	v_cndmask_b32_e32 v3, v3, v7, vcc
	v_cndmask_b32_e32 v6, v7, v10, vcc
	v_cndmask_b32_e32 v7, v10, v11, vcc
	v_max_u32_dpp v10, v3, v3 quad_perm:[1,0,3,2] row_mask:0xf bank_mask:0xf bound_ctrl:1
	v_cndmask_b32_e32 v2, v11, v2, vcc
	s_nop 0
	v_max_u32_dpp v10, v10, v10 quad_perm:[2,3,0,1] row_mask:0xf bank_mask:0xf bound_ctrl:1
	s_nop 1
	v_max_u32_dpp v10, v10, v10 row_half_mirror row_mask:0xf bank_mask:0xf bound_ctrl:1
	s_nop 1
	v_max_u32_dpp v10, v10, v10 row_mirror row_mask:0xf bank_mask:0xf bound_ctrl:1
	v_cmp_eq_u32_e32 vcc, v3, v10
	v_cndmask_b32_e64 v11, v14, v10, s[34:35]
	s_nop 0
	v_cndmask_b32_e32 v3, v3, v6, vcc
	v_cndmask_b32_e32 v6, v6, v7, vcc
	v_cndmask_b32_e32 v2, v7, v2, vcc
	v_max_u32_dpp v7, v3, v3 quad_perm:[1,0,3,2] row_mask:0xf bank_mask:0xf bound_ctrl:1
	s_nop 1
	v_max_u32_dpp v7, v7, v7 quad_perm:[2,3,0,1] row_mask:0xf bank_mask:0xf bound_ctrl:1
	s_nop 1
	v_max_u32_dpp v7, v7, v7 row_half_mirror row_mask:0xf bank_mask:0xf bound_ctrl:1
	s_nop 1
	v_max_u32_dpp v7, v7, v7 row_mirror row_mask:0xf bank_mask:0xf bound_ctrl:1
	v_cmp_eq_u32_e32 vcc, v3, v7
	v_cndmask_b32_e64 v10, v11, v7, s[36:37]
	v_ashrrev_i32_e32 v11, 31, v32
	v_cndmask_b32_e32 v3, v3, v6, vcc
	v_cndmask_b32_e32 v2, v6, v2, vcc
	v_bitop3_b32 v11, v11, v32, s2 bitop3:0x36
	v_max_u32_dpp v6, v3, v3 quad_perm:[1,0,3,2] row_mask:0xf bank_mask:0xf bound_ctrl:1
	v_and_or_b32 v11, v11, s55, v71
	s_nop 0
	v_max_u32_dpp v6, v6, v6 quad_perm:[2,3,0,1] row_mask:0xf bank_mask:0xf bound_ctrl:1
	s_nop 1
	v_max_u32_dpp v6, v6, v6 row_half_mirror row_mask:0xf bank_mask:0xf bound_ctrl:1
	s_nop 1
	v_max_u32_dpp v6, v6, v6 row_mirror row_mask:0xf bank_mask:0xf bound_ctrl:1
	v_cmp_eq_u32_e32 vcc, v3, v6
	v_cndmask_b32_e64 v7, v10, v6, s[38:39]
	v_ashrrev_i32_e32 v6, 31, v16
	v_cndmask_b32_e32 v2, v3, v2, vcc
	v_ashrrev_i32_e32 v3, 31, v8
	v_bitop3_b32 v3, v3, v8, s2 bitop3:0x36
	v_max_u32_dpp v2, v2, v2 quad_perm:[1,0,3,2] row_mask:0xf bank_mask:0xf bound_ctrl:1
	v_ashrrev_i32_e32 v8, 31, v24
	v_ashrrev_i32_e32 v10, 31, v28
	v_max_u32_dpp v2, v2, v2 quad_perm:[2,3,0,1] row_mask:0xf bank_mask:0xf bound_ctrl:1
	v_bitop3_b32 v6, v6, v16, s2 bitop3:0x36
	v_bitop3_b32 v8, v8, v24, s2 bitop3:0x36
	v_max_u32_dpp v2, v2, v2 row_half_mirror row_mask:0xf bank_mask:0xf bound_ctrl:1
	v_bitop3_b32 v10, v10, v28, s2 bitop3:0x36
	v_and_or_b32 v3, v3, s55, v65
	v_max_u32_dpp v2, v2, v2 row_mirror row_mask:0xf bank_mask:0xf bound_ctrl:1
	v_cndmask_b32_e64 v81, v7, v2, s[40:41]
	v_ashrrev_i32_e32 v2, 31, v4
	v_bitop3_b32 v2, v2, v4, s2 bitop3:0x36
	v_ashrrev_i32_e32 v4, 31, v12
	v_ashrrev_i32_e32 v7, 31, v20
	v_bitop3_b32 v4, v4, v12, s2 bitop3:0x36
	v_bitop3_b32 v7, v7, v20, s2 bitop3:0x36
	v_and_or_b32 v2, v2, s55, v60
	v_and_or_b32 v4, v4, s55, v66
	v_and_or_b32 v6, v6, s55, v67
	v_and_or_b32 v7, v7, s55, v68
	v_and_or_b32 v8, v8, s55, v69
	v_and_or_b32 v10, v10, s55, v70
	v_max_u32_e32 v12, v2, v3
	v_min_u32_e32 v2, v2, v3
	v_max_u32_e32 v3, v4, v6
	v_min_u32_e32 v4, v4, v6
	v_max_u32_e32 v6, v7, v8
	v_min_u32_e32 v7, v7, v8
	v_max_u32_e32 v8, v10, v11
	v_min_u32_e32 v10, v10, v11
	v_max_u32_e32 v11, v12, v3
	v_min_u32_e32 v3, v12, v3
	v_max_u32_e32 v12, v2, v4
	v_min_u32_e32 v2, v2, v4
	v_max_u32_e32 v4, v6, v8
	v_min_u32_e32 v6, v6, v8
	v_max_u32_e32 v8, v7, v10
	v_min_u32_e32 v7, v7, v10
	v_max_u32_e32 v10, v12, v3
	v_min_u32_e32 v3, v12, v3
	v_max_u32_e32 v12, v8, v6
	v_min_u32_e32 v6, v8, v6
	v_max_u32_e32 v8, v11, v4
	v_min_u32_e32 v4, v11, v4
	v_max_u32_e32 v11, v10, v12
	v_min_u32_e32 v10, v10, v12
	v_max_u32_e32 v12, v3, v6
	v_min_u32_e32 v3, v3, v6
	v_max_u32_e32 v6, v2, v7
	v_min_u32_e32 v2, v2, v7
	v_max_u32_e32 v7, v12, v4
	v_min_u32_e32 v4, v12, v4
	v_max_u32_e32 v12, v6, v10
	v_min_u32_e32 v6, v6, v10
	v_max_u32_e32 v10, v11, v7
	v_min_u32_e32 v7, v11, v7
	v_max_u32_e32 v11, v12, v4
	v_min_u32_e32 v4, v12, v4
	v_max_u32_e32 v12, v6, v3
	v_min_u32_e32 v3, v6, v3
	v_max_u32_dpp v6, v8, v8 quad_perm:[1,0,3,2] row_mask:0xf bank_mask:0xf bound_ctrl:1
	s_nop 1
	v_max_u32_dpp v6, v6, v6 quad_perm:[2,3,0,1] row_mask:0xf bank_mask:0xf bound_ctrl:1
	s_nop 1
	v_max_u32_dpp v6, v6, v6 row_half_mirror row_mask:0xf bank_mask:0xf bound_ctrl:1
	s_nop 1
	v_max_u32_dpp v6, v6, v6 row_mirror row_mask:0xf bank_mask:0xf bound_ctrl:1
	v_cmp_eq_u32_e32 vcc, v8, v6
	v_cndmask_b32_e64 v14, 0, v6, s[8:9]
	s_nop 0
	v_cndmask_b32_e32 v6, v8, v10, vcc
	v_cndmask_b32_e32 v8, v10, v7, vcc
	v_cndmask_b32_e32 v7, v7, v11, vcc
	v_cndmask_b32_e32 v10, v11, v4, vcc
	v_cndmask_b32_e32 v4, v4, v12, vcc
	v_cndmask_b32_e32 v11, v12, v3, vcc
	v_max_u32_dpp v12, v6, v6 quad_perm:[1,0,3,2] row_mask:0xf bank_mask:0xf bound_ctrl:1
	v_cndmask_b32_e32 v3, v3, v2, vcc
	v_cndmask_b32_e64 v2, v2, 0, vcc
	v_max_u32_dpp v12, v12, v12 quad_perm:[2,3,0,1] row_mask:0xf bank_mask:0xf bound_ctrl:1
	s_nop 1
	v_max_u32_dpp v12, v12, v12 row_half_mirror row_mask:0xf bank_mask:0xf bound_ctrl:1
	s_nop 1
	v_max_u32_dpp v12, v12, v12 row_mirror row_mask:0xf bank_mask:0xf bound_ctrl:1
	v_cmp_eq_u32_e32 vcc, v6, v12
	v_cndmask_b32_e64 v14, v14, v12, s[10:11]
	s_nop 0
	v_cndmask_b32_e32 v6, v6, v8, vcc
	v_cndmask_b32_e32 v8, v8, v7, vcc
	v_cndmask_b32_e32 v7, v7, v10, vcc
	v_max_u32_dpp v12, v6, v6 quad_perm:[1,0,3,2] row_mask:0xf bank_mask:0xf bound_ctrl:1
	v_cndmask_b32_e32 v10, v10, v4, vcc
	v_cndmask_b32_e32 v4, v4, v11, vcc
	v_max_u32_dpp v12, v12, v12 quad_perm:[2,3,0,1] row_mask:0xf bank_mask:0xf bound_ctrl:1
	v_cndmask_b32_e32 v11, v11, v3, vcc
	v_cndmask_b32_e32 v3, v3, v2, vcc
	v_max_u32_dpp v12, v12, v12 row_half_mirror row_mask:0xf bank_mask:0xf bound_ctrl:1
	v_cndmask_b32_e64 v2, v2, 0, vcc
	s_nop 0
	v_max_u32_dpp v12, v12, v12 row_mirror row_mask:0xf bank_mask:0xf bound_ctrl:1
	v_cmp_eq_u32_e32 vcc, v6, v12
	v_cndmask_b32_e64 v14, v14, v12, s[12:13]
	s_nop 0
	v_cndmask_b32_e32 v6, v6, v8, vcc
	v_cndmask_b32_e32 v8, v8, v7, vcc
	v_cndmask_b32_e32 v7, v7, v10, vcc
	v_max_u32_dpp v12, v6, v6 quad_perm:[1,0,3,2] row_mask:0xf bank_mask:0xf bound_ctrl:1
	v_cndmask_b32_e32 v10, v10, v4, vcc
	v_cndmask_b32_e32 v4, v4, v11, vcc
	v_max_u32_dpp v12, v12, v12 quad_perm:[2,3,0,1] row_mask:0xf bank_mask:0xf bound_ctrl:1
	v_cndmask_b32_e32 v11, v11, v3, vcc
	v_cndmask_b32_e32 v3, v3, v2, vcc
	v_max_u32_dpp v12, v12, v12 row_half_mirror row_mask:0xf bank_mask:0xf bound_ctrl:1
	v_cndmask_b32_e64 v2, v2, 0, vcc
	s_nop 0
	v_max_u32_dpp v12, v12, v12 row_mirror row_mask:0xf bank_mask:0xf bound_ctrl:1
	v_cmp_eq_u32_e32 vcc, v6, v12
	v_cndmask_b32_e64 v14, v14, v12, s[14:15]
	s_nop 0
	v_cndmask_b32_e32 v6, v6, v8, vcc
	v_cndmask_b32_e32 v8, v8, v7, vcc
	v_cndmask_b32_e32 v7, v7, v10, vcc
	v_max_u32_dpp v12, v6, v6 quad_perm:[1,0,3,2] row_mask:0xf bank_mask:0xf bound_ctrl:1
	v_cndmask_b32_e32 v10, v10, v4, vcc
	v_cndmask_b32_e32 v4, v4, v11, vcc
	v_max_u32_dpp v12, v12, v12 quad_perm:[2,3,0,1] row_mask:0xf bank_mask:0xf bound_ctrl:1
	v_cndmask_b32_e32 v11, v11, v3, vcc
	v_cndmask_b32_e32 v3, v3, v2, vcc
	v_max_u32_dpp v12, v12, v12 row_half_mirror row_mask:0xf bank_mask:0xf bound_ctrl:1
	v_cndmask_b32_e64 v2, v2, 0, vcc
	s_nop 0
	v_max_u32_dpp v12, v12, v12 row_mirror row_mask:0xf bank_mask:0xf bound_ctrl:1
	v_cmp_eq_u32_e32 vcc, v6, v12
	v_cndmask_b32_e64 v14, v14, v12, s[16:17]
	s_nop 0
	v_cndmask_b32_e32 v6, v6, v8, vcc
	v_cndmask_b32_e32 v8, v8, v7, vcc
	v_cndmask_b32_e32 v7, v7, v10, vcc
	v_max_u32_dpp v12, v6, v6 quad_perm:[1,0,3,2] row_mask:0xf bank_mask:0xf bound_ctrl:1
	v_cndmask_b32_e32 v10, v10, v4, vcc
	v_cndmask_b32_e32 v4, v4, v11, vcc
	v_max_u32_dpp v12, v12, v12 quad_perm:[2,3,0,1] row_mask:0xf bank_mask:0xf bound_ctrl:1
	v_cndmask_b32_e32 v11, v11, v3, vcc
	v_cndmask_b32_e32 v3, v3, v2, vcc
	v_max_u32_dpp v12, v12, v12 row_half_mirror row_mask:0xf bank_mask:0xf bound_ctrl:1
	v_cndmask_b32_e64 v2, v2, 0, vcc
	s_nop 0
	v_max_u32_dpp v12, v12, v12 row_mirror row_mask:0xf bank_mask:0xf bound_ctrl:1
	v_cmp_eq_u32_e32 vcc, v6, v12
	v_cndmask_b32_e64 v14, v14, v12, s[18:19]
	s_nop 0
	v_cndmask_b32_e32 v6, v6, v8, vcc
	v_cndmask_b32_e32 v8, v8, v7, vcc
	v_cndmask_b32_e32 v7, v7, v10, vcc
	v_max_u32_dpp v12, v6, v6 quad_perm:[1,0,3,2] row_mask:0xf bank_mask:0xf bound_ctrl:1
	v_cndmask_b32_e32 v10, v10, v4, vcc
	v_cndmask_b32_e32 v4, v4, v11, vcc
	v_max_u32_dpp v12, v12, v12 quad_perm:[2,3,0,1] row_mask:0xf bank_mask:0xf bound_ctrl:1
	v_cndmask_b32_e32 v11, v11, v3, vcc
	v_cndmask_b32_e32 v3, v3, v2, vcc
	v_max_u32_dpp v12, v12, v12 row_half_mirror row_mask:0xf bank_mask:0xf bound_ctrl:1
	v_cndmask_b32_e64 v2, v2, 0, vcc
	s_nop 0
	v_max_u32_dpp v12, v12, v12 row_mirror row_mask:0xf bank_mask:0xf bound_ctrl:1
	v_cmp_eq_u32_e32 vcc, v6, v12
	v_cndmask_b32_e64 v14, v14, v12, s[20:21]
	s_nop 0
	v_cndmask_b32_e32 v6, v6, v8, vcc
	v_cndmask_b32_e32 v8, v8, v7, vcc
	v_cndmask_b32_e32 v7, v7, v10, vcc
	v_max_u32_dpp v12, v6, v6 quad_perm:[1,0,3,2] row_mask:0xf bank_mask:0xf bound_ctrl:1
	v_cndmask_b32_e32 v10, v10, v4, vcc
	v_cndmask_b32_e32 v4, v4, v11, vcc
	v_max_u32_dpp v12, v12, v12 quad_perm:[2,3,0,1] row_mask:0xf bank_mask:0xf bound_ctrl:1
	v_cndmask_b32_e32 v11, v11, v3, vcc
	v_cndmask_b32_e32 v3, v3, v2, vcc
	v_max_u32_dpp v12, v12, v12 row_half_mirror row_mask:0xf bank_mask:0xf bound_ctrl:1
	v_cndmask_b32_e64 v2, v2, 0, vcc
	s_nop 0
	v_max_u32_dpp v12, v12, v12 row_mirror row_mask:0xf bank_mask:0xf bound_ctrl:1
	v_cmp_eq_u32_e32 vcc, v6, v12
	v_cndmask_b32_e64 v14, v14, v12, s[22:23]
	s_nop 0
	v_cndmask_b32_e32 v6, v6, v8, vcc
	v_cndmask_b32_e32 v8, v8, v7, vcc
	v_cndmask_b32_e32 v7, v7, v10, vcc
	v_max_u32_dpp v12, v6, v6 quad_perm:[1,0,3,2] row_mask:0xf bank_mask:0xf bound_ctrl:1
	v_cndmask_b32_e32 v10, v10, v4, vcc
	v_cndmask_b32_e32 v4, v4, v11, vcc
	v_max_u32_dpp v12, v12, v12 quad_perm:[2,3,0,1] row_mask:0xf bank_mask:0xf bound_ctrl:1
	v_cndmask_b32_e32 v11, v11, v3, vcc
	v_cndmask_b32_e32 v3, v3, v2, vcc
	v_max_u32_dpp v12, v12, v12 row_half_mirror row_mask:0xf bank_mask:0xf bound_ctrl:1
	v_cndmask_b32_e64 v2, v2, 0, vcc
	s_nop 0
	v_max_u32_dpp v12, v12, v12 row_mirror row_mask:0xf bank_mask:0xf bound_ctrl:1
	v_cmp_eq_u32_e32 vcc, v6, v12
	v_cndmask_b32_e64 v14, v14, v12, s[24:25]
	s_nop 0
	v_cndmask_b32_e32 v6, v6, v8, vcc
	v_cndmask_b32_e32 v8, v8, v7, vcc
	v_cndmask_b32_e32 v7, v7, v10, vcc
	v_cndmask_b32_e32 v10, v10, v4, vcc
	v_cndmask_b32_e32 v4, v4, v11, vcc
	v_cndmask_b32_e32 v11, v11, v3, vcc
	v_cndmask_b32_e32 v2, v3, v2, vcc
	v_max_u32_dpp v3, v6, v6 quad_perm:[1,0,3,2] row_mask:0xf bank_mask:0xf bound_ctrl:1
	s_nop 1
	v_max_u32_dpp v3, v3, v3 quad_perm:[2,3,0,1] row_mask:0xf bank_mask:0xf bound_ctrl:1
	s_nop 1
	v_max_u32_dpp v3, v3, v3 row_half_mirror row_mask:0xf bank_mask:0xf bound_ctrl:1
	s_nop 1
	v_max_u32_dpp v3, v3, v3 row_mirror row_mask:0xf bank_mask:0xf bound_ctrl:1
	v_cmp_eq_u32_e32 vcc, v6, v3
	v_cndmask_b32_e64 v12, v14, v3, s[26:27]
	s_nop 0
	v_cndmask_b32_e32 v3, v6, v8, vcc
	v_cndmask_b32_e32 v6, v8, v7, vcc
	v_cndmask_b32_e32 v7, v7, v10, vcc
	v_cndmask_b32_e32 v8, v10, v4, vcc
	v_max_u32_dpp v10, v3, v3 quad_perm:[1,0,3,2] row_mask:0xf bank_mask:0xf bound_ctrl:1
	v_cndmask_b32_e32 v4, v4, v11, vcc
	v_cndmask_b32_e32 v2, v11, v2, vcc
	v_max_u32_dpp v10, v10, v10 quad_perm:[2,3,0,1] row_mask:0xf bank_mask:0xf bound_ctrl:1
	s_nop 1
	v_max_u32_dpp v10, v10, v10 row_half_mirror row_mask:0xf bank_mask:0xf bound_ctrl:1
	s_nop 1
	v_max_u32_dpp v10, v10, v10 row_mirror row_mask:0xf bank_mask:0xf bound_ctrl:1
	v_cmp_eq_u32_e32 vcc, v3, v10
	v_cndmask_b32_e64 v11, v12, v10, s[28:29]
	s_nop 0
	v_cndmask_b32_e32 v3, v3, v6, vcc
	v_cndmask_b32_e32 v6, v6, v7, vcc
	v_cndmask_b32_e32 v7, v7, v8, vcc
	v_cndmask_b32_e32 v8, v8, v4, vcc
	v_cndmask_b32_e32 v2, v4, v2, vcc
	v_max_u32_dpp v4, v3, v3 quad_perm:[1,0,3,2] row_mask:0xf bank_mask:0xf bound_ctrl:1
	s_nop 1
	v_max_u32_dpp v4, v4, v4 quad_perm:[2,3,0,1] row_mask:0xf bank_mask:0xf bound_ctrl:1
	s_nop 1
	v_max_u32_dpp v4, v4, v4 row_half_mirror row_mask:0xf bank_mask:0xf bound_ctrl:1
	s_nop 1
	v_max_u32_dpp v4, v4, v4 row_mirror row_mask:0xf bank_mask:0xf bound_ctrl:1
	v_cmp_eq_u32_e32 vcc, v3, v4
	v_cndmask_b32_e64 v10, v11, v4, s[30:31]
	s_nop 0
	v_cndmask_b32_e32 v3, v3, v6, vcc
	v_cndmask_b32_e32 v4, v6, v7, vcc
	v_cndmask_b32_e32 v6, v7, v8, vcc
	v_max_u32_dpp v7, v3, v3 quad_perm:[1,0,3,2] row_mask:0xf bank_mask:0xf bound_ctrl:1
	v_cndmask_b32_e32 v2, v8, v2, vcc
	s_nop 0
	v_max_u32_dpp v7, v7, v7 quad_perm:[2,3,0,1] row_mask:0xf bank_mask:0xf bound_ctrl:1
	s_nop 1
	v_max_u32_dpp v7, v7, v7 row_half_mirror row_mask:0xf bank_mask:0xf bound_ctrl:1
	s_nop 1
	v_max_u32_dpp v7, v7, v7 row_mirror row_mask:0xf bank_mask:0xf bound_ctrl:1
	v_cmp_eq_u32_e32 vcc, v3, v7
	v_cndmask_b32_e64 v8, v10, v7, s[34:35]
	s_nop 0
	v_cndmask_b32_e32 v3, v3, v4, vcc
	v_cndmask_b32_e32 v4, v4, v6, vcc
	v_cndmask_b32_e32 v2, v6, v2, vcc
	v_max_u32_dpp v6, v3, v3 quad_perm:[1,0,3,2] row_mask:0xf bank_mask:0xf bound_ctrl:1
	s_nop 1
	v_max_u32_dpp v6, v6, v6 quad_perm:[2,3,0,1] row_mask:0xf bank_mask:0xf bound_ctrl:1
	s_nop 1
	v_max_u32_dpp v6, v6, v6 row_half_mirror row_mask:0xf bank_mask:0xf bound_ctrl:1
	s_nop 1
	v_max_u32_dpp v6, v6, v6 row_mirror row_mask:0xf bank_mask:0xf bound_ctrl:1
	v_cmp_eq_u32_e32 vcc, v3, v6
	v_cndmask_b32_e64 v7, v8, v6, s[36:37]
	v_ashrrev_i32_e32 v8, 31, v29
	v_cndmask_b32_e32 v3, v3, v4, vcc
	v_cndmask_b32_e32 v2, v4, v2, vcc
	v_bitop3_b32 v8, v8, v29, s2 bitop3:0x36
	v_max_u32_dpp v4, v3, v3 quad_perm:[1,0,3,2] row_mask:0xf bank_mask:0xf bound_ctrl:1
	v_and_or_b32 v8, v8, s55, v70
	s_nop 0
	v_max_u32_dpp v4, v4, v4 quad_perm:[2,3,0,1] row_mask:0xf bank_mask:0xf bound_ctrl:1
	s_nop 1
	v_max_u32_dpp v4, v4, v4 row_half_mirror row_mask:0xf bank_mask:0xf bound_ctrl:1
	s_nop 1
	v_max_u32_dpp v4, v4, v4 row_mirror row_mask:0xf bank_mask:0xf bound_ctrl:1
	v_cmp_eq_u32_e32 vcc, v3, v4
	v_cndmask_b32_e64 v6, v7, v4, s[38:39]
	v_ashrrev_i32_e32 v4, 31, v13
	v_cndmask_b32_e32 v2, v3, v2, vcc
	v_ashrrev_i32_e32 v3, 31, v9
	v_bitop3_b32 v3, v3, v9, s2 bitop3:0x36
	v_max_u32_dpp v2, v2, v2 quad_perm:[1,0,3,2] row_mask:0xf bank_mask:0xf bound_ctrl:1
	v_ashrrev_i32_e32 v7, 31, v25
	v_ashrrev_i32_e32 v9, 31, v33
	v_max_u32_dpp v2, v2, v2 quad_perm:[2,3,0,1] row_mask:0xf bank_mask:0xf bound_ctrl:1
	v_bitop3_b32 v4, v4, v13, s2 bitop3:0x36
	v_bitop3_b32 v7, v7, v25, s2 bitop3:0x36
	v_max_u32_dpp v2, v2, v2 row_half_mirror row_mask:0xf bank_mask:0xf bound_ctrl:1
	v_bitop3_b32 v9, v9, v33, s2 bitop3:0x36
	v_and_or_b32 v3, v3, s55, v65
	v_max_u32_dpp v2, v2, v2 row_mirror row_mask:0xf bank_mask:0xf bound_ctrl:1
	v_cndmask_b32_e64 v80, v6, v2, s[40:41]
	v_ashrrev_i32_e32 v2, 31, v5
	v_bitop3_b32 v2, v2, v5, s2 bitop3:0x36
	v_ashrrev_i32_e32 v5, 31, v17
	v_ashrrev_i32_e32 v6, 31, v21
	v_bitop3_b32 v5, v5, v17, s2 bitop3:0x36
	v_bitop3_b32 v6, v6, v21, s2 bitop3:0x36
	v_and_or_b32 v2, v2, s55, v60
	v_and_or_b32 v4, v4, s55, v66
	v_and_or_b32 v5, v5, s55, v67
	v_and_or_b32 v6, v6, s55, v68
	v_and_or_b32 v7, v7, s55, v69
	v_and_or_b32 v9, v9, s55, v71
	v_max_u32_e32 v10, v2, v3
	v_min_u32_e32 v2, v2, v3
	v_max_u32_e32 v3, v4, v5
	v_min_u32_e32 v4, v4, v5
	v_max_u32_e32 v5, v6, v7
	v_min_u32_e32 v6, v6, v7
	v_max_u32_e32 v7, v8, v9
	v_min_u32_e32 v8, v8, v9
	v_max_u32_e32 v9, v10, v3
	v_min_u32_e32 v3, v10, v3
	v_max_u32_e32 v10, v2, v4
	v_min_u32_e32 v2, v2, v4
	v_max_u32_e32 v4, v5, v7
	v_min_u32_e32 v5, v5, v7
	v_max_u32_e32 v7, v6, v8
	v_min_u32_e32 v6, v6, v8
	v_max_u32_e32 v8, v10, v3
	v_min_u32_e32 v3, v10, v3
	v_max_u32_e32 v10, v7, v5
	v_min_u32_e32 v5, v7, v5
	v_max_u32_e32 v7, v9, v4
	v_min_u32_e32 v4, v9, v4
	v_max_u32_e32 v9, v8, v10
	v_min_u32_e32 v8, v8, v10
	v_max_u32_e32 v10, v3, v5
	v_min_u32_e32 v3, v3, v5
	v_max_u32_e32 v5, v2, v6
	v_min_u32_e32 v2, v2, v6
	v_max_u32_e32 v6, v10, v4
	v_min_u32_e32 v4, v10, v4
	v_max_u32_e32 v10, v5, v8
	v_min_u32_e32 v5, v5, v8
	v_max_u32_e32 v8, v9, v6
	v_min_u32_e32 v6, v9, v6
	v_max_u32_e32 v9, v10, v4
	v_min_u32_e32 v4, v10, v4
	v_max_u32_e32 v10, v5, v3
	v_min_u32_e32 v3, v5, v3
	v_max_u32_dpp v5, v7, v7 quad_perm:[1,0,3,2] row_mask:0xf bank_mask:0xf bound_ctrl:1
	s_nop 1
	v_max_u32_dpp v5, v5, v5 quad_perm:[2,3,0,1] row_mask:0xf bank_mask:0xf bound_ctrl:1
	s_nop 1
	v_max_u32_dpp v5, v5, v5 row_half_mirror row_mask:0xf bank_mask:0xf bound_ctrl:1
	s_nop 1
	v_max_u32_dpp v5, v5, v5 row_mirror row_mask:0xf bank_mask:0xf bound_ctrl:1
	v_cmp_eq_u32_e32 vcc, v7, v5
	v_cndmask_b32_e64 v11, 0, v5, s[8:9]
	s_nop 0
	v_cndmask_b32_e32 v5, v7, v8, vcc
	v_cndmask_b32_e32 v7, v8, v6, vcc
	v_cndmask_b32_e32 v6, v6, v9, vcc
	v_cndmask_b32_e32 v8, v9, v4, vcc
	v_cndmask_b32_e32 v4, v4, v10, vcc
	v_cndmask_b32_e32 v9, v10, v3, vcc
	v_max_u32_dpp v10, v5, v5 quad_perm:[1,0,3,2] row_mask:0xf bank_mask:0xf bound_ctrl:1
	v_cndmask_b32_e32 v3, v3, v2, vcc
	v_cndmask_b32_e64 v2, v2, 0, vcc
	v_max_u32_dpp v10, v10, v10 quad_perm:[2,3,0,1] row_mask:0xf bank_mask:0xf bound_ctrl:1
	s_nop 1
	v_max_u32_dpp v10, v10, v10 row_half_mirror row_mask:0xf bank_mask:0xf bound_ctrl:1
	s_nop 1
	v_max_u32_dpp v10, v10, v10 row_mirror row_mask:0xf bank_mask:0xf bound_ctrl:1
	v_cmp_eq_u32_e32 vcc, v5, v10
	v_cndmask_b32_e64 v11, v11, v10, s[10:11]
	s_nop 0
	v_cndmask_b32_e32 v5, v5, v7, vcc
	v_cndmask_b32_e32 v7, v7, v6, vcc
	v_cndmask_b32_e32 v6, v6, v8, vcc
	v_max_u32_dpp v10, v5, v5 quad_perm:[1,0,3,2] row_mask:0xf bank_mask:0xf bound_ctrl:1
	v_cndmask_b32_e32 v8, v8, v4, vcc
	v_cndmask_b32_e32 v4, v4, v9, vcc
	v_max_u32_dpp v10, v10, v10 quad_perm:[2,3,0,1] row_mask:0xf bank_mask:0xf bound_ctrl:1
	v_cndmask_b32_e32 v9, v9, v3, vcc
	v_cndmask_b32_e32 v3, v3, v2, vcc
	v_max_u32_dpp v10, v10, v10 row_half_mirror row_mask:0xf bank_mask:0xf bound_ctrl:1
	v_cndmask_b32_e64 v2, v2, 0, vcc
	s_nop 0
	v_max_u32_dpp v10, v10, v10 row_mirror row_mask:0xf bank_mask:0xf bound_ctrl:1
	v_cmp_eq_u32_e32 vcc, v5, v10
	v_cndmask_b32_e64 v11, v11, v10, s[12:13]
	s_nop 0
	v_cndmask_b32_e32 v5, v5, v7, vcc
	v_cndmask_b32_e32 v7, v7, v6, vcc
	v_cndmask_b32_e32 v6, v6, v8, vcc
	v_max_u32_dpp v10, v5, v5 quad_perm:[1,0,3,2] row_mask:0xf bank_mask:0xf bound_ctrl:1
	v_cndmask_b32_e32 v8, v8, v4, vcc
	v_cndmask_b32_e32 v4, v4, v9, vcc
	v_max_u32_dpp v10, v10, v10 quad_perm:[2,3,0,1] row_mask:0xf bank_mask:0xf bound_ctrl:1
	v_cndmask_b32_e32 v9, v9, v3, vcc
	v_cndmask_b32_e32 v3, v3, v2, vcc
	v_max_u32_dpp v10, v10, v10 row_half_mirror row_mask:0xf bank_mask:0xf bound_ctrl:1
	v_cndmask_b32_e64 v2, v2, 0, vcc
	s_nop 0
	v_max_u32_dpp v10, v10, v10 row_mirror row_mask:0xf bank_mask:0xf bound_ctrl:1
	v_cmp_eq_u32_e32 vcc, v5, v10
	v_cndmask_b32_e64 v11, v11, v10, s[14:15]
	s_nop 0
	v_cndmask_b32_e32 v5, v5, v7, vcc
	v_cndmask_b32_e32 v7, v7, v6, vcc
	v_cndmask_b32_e32 v6, v6, v8, vcc
	v_max_u32_dpp v10, v5, v5 quad_perm:[1,0,3,2] row_mask:0xf bank_mask:0xf bound_ctrl:1
	v_cndmask_b32_e32 v8, v8, v4, vcc
	v_cndmask_b32_e32 v4, v4, v9, vcc
	v_max_u32_dpp v10, v10, v10 quad_perm:[2,3,0,1] row_mask:0xf bank_mask:0xf bound_ctrl:1
	v_cndmask_b32_e32 v9, v9, v3, vcc
	v_cndmask_b32_e32 v3, v3, v2, vcc
	v_max_u32_dpp v10, v10, v10 row_half_mirror row_mask:0xf bank_mask:0xf bound_ctrl:1
	v_cndmask_b32_e64 v2, v2, 0, vcc
	s_nop 0
	v_max_u32_dpp v10, v10, v10 row_mirror row_mask:0xf bank_mask:0xf bound_ctrl:1
	v_cmp_eq_u32_e32 vcc, v5, v10
	v_cndmask_b32_e64 v11, v11, v10, s[16:17]
	s_nop 0
	v_cndmask_b32_e32 v5, v5, v7, vcc
	v_cndmask_b32_e32 v7, v7, v6, vcc
	v_cndmask_b32_e32 v6, v6, v8, vcc
	v_max_u32_dpp v10, v5, v5 quad_perm:[1,0,3,2] row_mask:0xf bank_mask:0xf bound_ctrl:1
	v_cndmask_b32_e32 v8, v8, v4, vcc
	v_cndmask_b32_e32 v4, v4, v9, vcc
	v_max_u32_dpp v10, v10, v10 quad_perm:[2,3,0,1] row_mask:0xf bank_mask:0xf bound_ctrl:1
	v_cndmask_b32_e32 v9, v9, v3, vcc
	v_cndmask_b32_e32 v3, v3, v2, vcc
	v_max_u32_dpp v10, v10, v10 row_half_mirror row_mask:0xf bank_mask:0xf bound_ctrl:1
	v_cndmask_b32_e64 v2, v2, 0, vcc
	s_nop 0
	v_max_u32_dpp v10, v10, v10 row_mirror row_mask:0xf bank_mask:0xf bound_ctrl:1
	v_cmp_eq_u32_e32 vcc, v5, v10
	v_cndmask_b32_e64 v11, v11, v10, s[18:19]
	s_nop 0
	v_cndmask_b32_e32 v5, v5, v7, vcc
	v_cndmask_b32_e32 v7, v7, v6, vcc
	v_cndmask_b32_e32 v6, v6, v8, vcc
	v_max_u32_dpp v10, v5, v5 quad_perm:[1,0,3,2] row_mask:0xf bank_mask:0xf bound_ctrl:1
	v_cndmask_b32_e32 v8, v8, v4, vcc
	v_cndmask_b32_e32 v4, v4, v9, vcc
	v_max_u32_dpp v10, v10, v10 quad_perm:[2,3,0,1] row_mask:0xf bank_mask:0xf bound_ctrl:1
	v_cndmask_b32_e32 v9, v9, v3, vcc
	v_cndmask_b32_e32 v3, v3, v2, vcc
	v_max_u32_dpp v10, v10, v10 row_half_mirror row_mask:0xf bank_mask:0xf bound_ctrl:1
	v_cndmask_b32_e64 v2, v2, 0, vcc
	s_nop 0
	v_max_u32_dpp v10, v10, v10 row_mirror row_mask:0xf bank_mask:0xf bound_ctrl:1
	v_cmp_eq_u32_e32 vcc, v5, v10
	v_cndmask_b32_e64 v11, v11, v10, s[20:21]
	s_nop 0
	v_cndmask_b32_e32 v5, v5, v7, vcc
	v_cndmask_b32_e32 v7, v7, v6, vcc
	v_cndmask_b32_e32 v6, v6, v8, vcc
	v_max_u32_dpp v10, v5, v5 quad_perm:[1,0,3,2] row_mask:0xf bank_mask:0xf bound_ctrl:1
	v_cndmask_b32_e32 v8, v8, v4, vcc
	v_cndmask_b32_e32 v4, v4, v9, vcc
	v_max_u32_dpp v10, v10, v10 quad_perm:[2,3,0,1] row_mask:0xf bank_mask:0xf bound_ctrl:1
	v_cndmask_b32_e32 v9, v9, v3, vcc
	v_cndmask_b32_e32 v3, v3, v2, vcc
	v_max_u32_dpp v10, v10, v10 row_half_mirror row_mask:0xf bank_mask:0xf bound_ctrl:1
	v_cndmask_b32_e64 v2, v2, 0, vcc
	s_nop 0
	v_max_u32_dpp v10, v10, v10 row_mirror row_mask:0xf bank_mask:0xf bound_ctrl:1
	v_cmp_eq_u32_e32 vcc, v5, v10
	v_cndmask_b32_e64 v11, v11, v10, s[22:23]
	s_nop 0
	v_cndmask_b32_e32 v5, v5, v7, vcc
	v_cndmask_b32_e32 v7, v7, v6, vcc
	v_cndmask_b32_e32 v6, v6, v8, vcc
	v_max_u32_dpp v10, v5, v5 quad_perm:[1,0,3,2] row_mask:0xf bank_mask:0xf bound_ctrl:1
	v_cndmask_b32_e32 v8, v8, v4, vcc
	v_cndmask_b32_e32 v4, v4, v9, vcc
	v_max_u32_dpp v10, v10, v10 quad_perm:[2,3,0,1] row_mask:0xf bank_mask:0xf bound_ctrl:1
	v_cndmask_b32_e32 v9, v9, v3, vcc
	v_cndmask_b32_e32 v3, v3, v2, vcc
	v_max_u32_dpp v10, v10, v10 row_half_mirror row_mask:0xf bank_mask:0xf bound_ctrl:1
	v_cndmask_b32_e64 v2, v2, 0, vcc
	s_nop 0
	v_max_u32_dpp v10, v10, v10 row_mirror row_mask:0xf bank_mask:0xf bound_ctrl:1
	v_cmp_eq_u32_e32 vcc, v5, v10
	v_cndmask_b32_e64 v11, v11, v10, s[24:25]
	s_nop 0
	v_cndmask_b32_e32 v5, v5, v7, vcc
	v_cndmask_b32_e32 v7, v7, v6, vcc
	v_cndmask_b32_e32 v6, v6, v8, vcc
	v_cndmask_b32_e32 v8, v8, v4, vcc
	v_cndmask_b32_e32 v4, v4, v9, vcc
	v_cndmask_b32_e32 v9, v9, v3, vcc
	v_cndmask_b32_e32 v2, v3, v2, vcc
	v_max_u32_dpp v3, v5, v5 quad_perm:[1,0,3,2] row_mask:0xf bank_mask:0xf bound_ctrl:1
	s_nop 1
	v_max_u32_dpp v3, v3, v3 quad_perm:[2,3,0,1] row_mask:0xf bank_mask:0xf bound_ctrl:1
	s_nop 1
	v_max_u32_dpp v3, v3, v3 row_half_mirror row_mask:0xf bank_mask:0xf bound_ctrl:1
	s_nop 1
	v_max_u32_dpp v3, v3, v3 row_mirror row_mask:0xf bank_mask:0xf bound_ctrl:1
	v_cmp_eq_u32_e32 vcc, v5, v3
	v_cndmask_b32_e64 v10, v11, v3, s[26:27]
	s_nop 0
	v_cndmask_b32_e32 v3, v5, v7, vcc
	v_cndmask_b32_e32 v5, v7, v6, vcc
	v_cndmask_b32_e32 v6, v6, v8, vcc
	v_cndmask_b32_e32 v7, v8, v4, vcc
	v_max_u32_dpp v8, v3, v3 quad_perm:[1,0,3,2] row_mask:0xf bank_mask:0xf bound_ctrl:1
	v_cndmask_b32_e32 v4, v4, v9, vcc
	v_cndmask_b32_e32 v2, v9, v2, vcc
	v_max_u32_dpp v8, v8, v8 quad_perm:[2,3,0,1] row_mask:0xf bank_mask:0xf bound_ctrl:1
	s_nop 1
	v_max_u32_dpp v8, v8, v8 row_half_mirror row_mask:0xf bank_mask:0xf bound_ctrl:1
	s_nop 1
	v_max_u32_dpp v8, v8, v8 row_mirror row_mask:0xf bank_mask:0xf bound_ctrl:1
	v_cmp_eq_u32_e32 vcc, v3, v8
	v_cndmask_b32_e64 v9, v10, v8, s[28:29]
	s_nop 0
	v_cndmask_b32_e32 v3, v3, v5, vcc
	v_cndmask_b32_e32 v5, v5, v6, vcc
	v_cndmask_b32_e32 v6, v6, v7, vcc
	v_cndmask_b32_e32 v7, v7, v4, vcc
	v_cndmask_b32_e32 v2, v4, v2, vcc
	v_max_u32_dpp v4, v3, v3 quad_perm:[1,0,3,2] row_mask:0xf bank_mask:0xf bound_ctrl:1
	s_nop 1
	v_max_u32_dpp v4, v4, v4 quad_perm:[2,3,0,1] row_mask:0xf bank_mask:0xf bound_ctrl:1
	s_nop 1
	v_max_u32_dpp v4, v4, v4 row_half_mirror row_mask:0xf bank_mask:0xf bound_ctrl:1
	s_nop 1
	v_max_u32_dpp v4, v4, v4 row_mirror row_mask:0xf bank_mask:0xf bound_ctrl:1
	v_cmp_eq_u32_e32 vcc, v3, v4
	v_cndmask_b32_e64 v8, v9, v4, s[30:31]
	s_nop 0
	v_cndmask_b32_e32 v3, v3, v5, vcc
	v_cndmask_b32_e32 v4, v5, v6, vcc
	v_cndmask_b32_e32 v5, v6, v7, vcc
	v_max_u32_dpp v6, v3, v3 quad_perm:[1,0,3,2] row_mask:0xf bank_mask:0xf bound_ctrl:1
	v_cndmask_b32_e32 v2, v7, v2, vcc
	s_nop 0
	v_max_u32_dpp v6, v6, v6 quad_perm:[2,3,0,1] row_mask:0xf bank_mask:0xf bound_ctrl:1
	s_nop 1
	v_max_u32_dpp v6, v6, v6 row_half_mirror row_mask:0xf bank_mask:0xf bound_ctrl:1
	s_nop 1
	v_max_u32_dpp v6, v6, v6 row_mirror row_mask:0xf bank_mask:0xf bound_ctrl:1
	v_cmp_eq_u32_e32 vcc, v3, v6
	v_cndmask_b32_e64 v7, v8, v6, s[34:35]
	s_nop 0
	v_cndmask_b32_e32 v3, v3, v4, vcc
	v_cndmask_b32_e32 v4, v4, v5, vcc
	v_cndmask_b32_e32 v2, v5, v2, vcc
	v_max_u32_dpp v5, v3, v3 quad_perm:[1,0,3,2] row_mask:0xf bank_mask:0xf bound_ctrl:1
	s_nop 1
	v_max_u32_dpp v5, v5, v5 quad_perm:[2,3,0,1] row_mask:0xf bank_mask:0xf bound_ctrl:1
	s_nop 1
	v_max_u32_dpp v5, v5, v5 row_half_mirror row_mask:0xf bank_mask:0xf bound_ctrl:1
	s_nop 1
	v_max_u32_dpp v5, v5, v5 row_mirror row_mask:0xf bank_mask:0xf bound_ctrl:1
	v_cmp_eq_u32_e32 vcc, v3, v5
	v_cndmask_b32_e64 v6, v7, v5, s[36:37]
	s_nop 0
	v_cndmask_b32_e32 v3, v3, v4, vcc
	v_cndmask_b32_e32 v2, v4, v2, vcc
	s_nop 0
	v_max_u32_dpp v4, v3, v3 quad_perm:[1,0,3,2] row_mask:0xf bank_mask:0xf bound_ctrl:1
	s_nop 1
	v_max_u32_dpp v4, v4, v4 quad_perm:[2,3,0,1] row_mask:0xf bank_mask:0xf bound_ctrl:1
	s_nop 1
	v_max_u32_dpp v4, v4, v4 row_half_mirror row_mask:0xf bank_mask:0xf bound_ctrl:1
	s_nop 1
	v_max_u32_dpp v4, v4, v4 row_mirror row_mask:0xf bank_mask:0xf bound_ctrl:1
	v_cmp_eq_u32_e32 vcc, v3, v4
	v_cndmask_b32_e64 v5, v6, v4, s[38:39]
	s_nop 0
	v_cndmask_b32_e32 v2, v3, v2, vcc
	s_nop 1
	v_max_u32_dpp v2, v2, v2 quad_perm:[1,0,3,2] row_mask:0xf bank_mask:0xf bound_ctrl:1
	s_nop 1
	v_max_u32_dpp v2, v2, v2 quad_perm:[2,3,0,1] row_mask:0xf bank_mask:0xf bound_ctrl:1
	s_nop 1
	v_max_u32_dpp v2, v2, v2 row_half_mirror row_mask:0xf bank_mask:0xf bound_ctrl:1
	s_nop 1
	v_max_u32_dpp v2, v2, v2 row_mirror row_mask:0xf bank_mask:0xf bound_ctrl:1
	v_cndmask_b32_e64 v79, v5, v2, s[40:41]
	s_waitcnt vmcnt(0)
	v_mov_b32_e32 v14, v216
	v_mov_b32_e32 v15, v217
	v_mov_b32_e32 v16, v218
	v_mov_b32_e32 v17, v219
	v_mov_b32_e32 v10, v220
	v_mov_b32_e32 v11, v221
	v_mov_b32_e32 v12, v222
	v_mov_b32_e32 v13, v223
	v_mov_b32_e32 v6, v224
	v_mov_b32_e32 v7, v225
	v_mov_b32_e32 v8, v226
	v_mov_b32_e32 v9, v227
	v_mov_b32_e32 v2, v228
	v_mov_b32_e32 v3, v229
	v_mov_b32_e32 v4, v230
	v_mov_b32_e32 v5, v231
	ds_read_b128 v[18:21], v64 offset:36864
	ds_read_b128 v[22:25], v64 offset:36928
	s_waitcnt vmcnt(3) lgkmcnt(1)
	v_mfma_f32_16x16x32_bf16 v[18:21], v[14:17], v[18:21], 0
	ds_read_b128 v[26:29], v64 offset:41536
	ds_read_b128 v[30:33], v64 offset:46144
	ds_read_b128 v[34:37], v64 offset:50752
	s_waitcnt vmcnt(2) lgkmcnt(3)
	v_mfma_f32_16x16x32_bf16 v[18:21], v[10:13], v[22:25], v[18:21]
	ds_read_b128 v[22:25], v64 offset:36992
	ds_read_b128 v[38:41], v64 offset:55360
	ds_read_b128 v[42:45], v64 offset:59968
	s_waitcnt vmcnt(1) lgkmcnt(2)
	v_mfma_f32_16x16x32_bf16 v[18:21], v[6:9], v[22:25], v[18:21]
	ds_read_b128 v[22:25], v64 offset:37056
	ds_read_b128 v[84:87], v64 offset:64576
	s_waitcnt vmcnt(0) lgkmcnt(1)
	v_mfma_f32_16x16x32_bf16 v[18:21], v[2:5], v[22:25], v[18:21]
	ds_read_b128 v[22:25], v64 offset:41472
	s_waitcnt lgkmcnt(0)
	v_mfma_f32_16x16x32_bf16 v[22:25], v[14:17], v[22:25], 0
	v_mfma_f32_16x16x32_bf16 v[22:25], v[10:13], v[26:29], v[22:25]
	ds_read_b128 v[26:29], v64 offset:41600
	s_waitcnt lgkmcnt(0)
	v_mfma_f32_16x16x32_bf16 v[22:25], v[6:9], v[26:29], v[22:25]
	ds_read_b128 v[26:29], v64 offset:41664
	s_waitcnt lgkmcnt(0)
	v_mfma_f32_16x16x32_bf16 v[22:25], v[2:5], v[26:29], v[22:25]
	ds_read_b128 v[26:29], v64 offset:46080
	s_waitcnt lgkmcnt(0)
	v_mfma_f32_16x16x32_bf16 v[26:29], v[14:17], v[26:29], 0
	v_mfma_f32_16x16x32_bf16 v[26:29], v[10:13], v[30:33], v[26:29]
	ds_read_b128 v[30:33], v64 offset:46208
	s_waitcnt lgkmcnt(0)
	v_mfma_f32_16x16x32_bf16 v[26:29], v[6:9], v[30:33], v[26:29]
	ds_read_b128 v[30:33], v64 offset:46272
	s_waitcnt lgkmcnt(0)
	v_mfma_f32_16x16x32_bf16 v[26:29], v[2:5], v[30:33], v[26:29]
	ds_read_b128 v[30:33], v64 offset:50688
	s_waitcnt lgkmcnt(0)
	v_mfma_f32_16x16x32_bf16 v[30:33], v[14:17], v[30:33], 0
	v_mfma_f32_16x16x32_bf16 v[30:33], v[10:13], v[34:37], v[30:33]
	ds_read_b128 v[34:37], v64 offset:50816
	s_waitcnt lgkmcnt(0)
	v_mfma_f32_16x16x32_bf16 v[30:33], v[6:9], v[34:37], v[30:33]
	ds_read_b128 v[34:37], v64 offset:50880
	s_waitcnt lgkmcnt(0)
	v_mfma_f32_16x16x32_bf16 v[30:33], v[2:5], v[34:37], v[30:33]
	ds_read_b128 v[34:37], v64 offset:55296
	s_waitcnt lgkmcnt(0)
	v_mfma_f32_16x16x32_bf16 v[34:37], v[14:17], v[34:37], 0
	v_mfma_f32_16x16x32_bf16 v[34:37], v[10:13], v[38:41], v[34:37]
	ds_read_b128 v[38:41], v64 offset:55424
	s_waitcnt lgkmcnt(0)
	v_mfma_f32_16x16x32_bf16 v[34:37], v[6:9], v[38:41], v[34:37]
	ds_read_b128 v[38:41], v64 offset:55488
	s_waitcnt lgkmcnt(0)
	v_mfma_f32_16x16x32_bf16 v[34:37], v[2:5], v[38:41], v[34:37]
	ds_read_b128 v[38:41], v64 offset:59904
	s_waitcnt lgkmcnt(0)
	v_mfma_f32_16x16x32_bf16 v[38:41], v[14:17], v[38:41], 0
	v_mfma_f32_16x16x32_bf16 v[38:41], v[10:13], v[42:45], v[38:41]
	ds_read_b128 v[42:45], v64 offset:60032
	s_waitcnt lgkmcnt(0)
	v_mfma_f32_16x16x32_bf16 v[38:41], v[6:9], v[42:45], v[38:41]
	ds_read_b128 v[42:45], v64 offset:60096
	s_waitcnt lgkmcnt(0)
	v_mfma_f32_16x16x32_bf16 v[38:41], v[2:5], v[42:45], v[38:41]
	ds_read_b128 v[42:45], v64 offset:64512
	s_waitcnt lgkmcnt(0)
	v_mfma_f32_16x16x32_bf16 v[42:45], v[14:17], v[42:45], 0
	v_mfma_f32_16x16x32_bf16 v[42:45], v[10:13], v[84:87], v[42:45]
	ds_read_b128 v[84:87], v64 offset:64640
	s_waitcnt lgkmcnt(0)
	v_mfma_f32_16x16x32_bf16 v[42:45], v[6:9], v[84:87], v[42:45]
	ds_read_b128 v[84:87], v64 offset:64704
	s_waitcnt lgkmcnt(0)
	v_mfma_f32_16x16x32_bf16 v[42:45], v[2:5], v[84:87], v[42:45]
	ds_read_b128 v[84:87], v72
	s_waitcnt lgkmcnt(0)
	v_mfma_f32_16x16x32_bf16 v[14:17], v[14:17], v[84:87], 0
	ds_read_b128 v[84:87], v73
	s_waitcnt lgkmcnt(0)
	v_mfma_f32_16x16x32_bf16 v[10:13], v[10:13], v[84:87], v[14:17]
	s_nop 4
	ds_read_b128 v[14:17], v74
	s_waitcnt lgkmcnt(0)
	v_mfma_f32_16x16x32_bf16 v[6:9], v[6:9], v[14:17], v[10:13]
	s_nop 2
	ds_read_b128 v[10:13], v75
	s_waitcnt lgkmcnt(0)
	v_mfma_f32_16x16x32_bf16 v[2:5], v[2:5], v[10:13], v[6:9]
	v_ashrrev_i32_e32 v10, 31, v34
	s_nop 1
	v_ashrrev_i32_e32 v6, 31, v18
	v_ashrrev_i32_e32 v7, 31, v22
	v_ashrrev_i32_e32 v8, 31, v26
	v_ashrrev_i32_e32 v9, 31, v30
	v_ashrrev_i32_e32 v11, 31, v38
	v_ashrrev_i32_e32 v12, 31, v42
	v_ashrrev_i32_e32 v13, 31, v2
	v_bitop3_b32 v6, v6, v18, s2 bitop3:0x36
	v_bitop3_b32 v7, v7, v22, s2 bitop3:0x36
	v_bitop3_b32 v8, v8, v26, s2 bitop3:0x36
	v_bitop3_b32 v9, v9, v30, s2 bitop3:0x36
	v_bitop3_b32 v10, v10, v34, s2 bitop3:0x36
	v_bitop3_b32 v11, v11, v38, s2 bitop3:0x36
	v_bitop3_b32 v12, v12, v42, s2 bitop3:0x36
	v_bitop3_b32 v2, v13, v2, s2 bitop3:0x36
	v_and_or_b32 v6, v6, s55, v60
	v_and_or_b32 v7, v7, s55, v65
	v_and_or_b32 v8, v8, s55, v66
	v_and_or_b32 v9, v9, s55, v67
	v_and_or_b32 v10, v10, s55, v68
	v_and_or_b32 v11, v11, s55, v69
	v_and_or_b32 v12, v12, s55, v70
	v_and_or_b32 v2, v2, s55, v71
	v_max_u32_e32 v13, v6, v7
	v_min_u32_e32 v6, v6, v7
	v_max_u32_e32 v7, v8, v9
	v_min_u32_e32 v8, v8, v9
	v_max_u32_e32 v9, v10, v11
	v_min_u32_e32 v10, v10, v11
	v_max_u32_e32 v11, v12, v2
	v_min_u32_e32 v2, v12, v2
	v_max_u32_e32 v12, v13, v7
	v_min_u32_e32 v7, v13, v7
	v_max_u32_e32 v13, v6, v8
	v_min_u32_e32 v6, v6, v8
	v_max_u32_e32 v8, v9, v11
	v_min_u32_e32 v9, v9, v11
	v_max_u32_e32 v11, v10, v2
	v_min_u32_e32 v2, v10, v2
	v_max_u32_e32 v10, v13, v7
	v_min_u32_e32 v7, v13, v7
	v_max_u32_e32 v13, v11, v9
	v_min_u32_e32 v9, v11, v9
	v_max_u32_e32 v11, v12, v8
	v_min_u32_e32 v8, v12, v8
	v_max_u32_e32 v12, v10, v13
	v_min_u32_e32 v10, v10, v13
	v_max_u32_e32 v13, v7, v9
	v_min_u32_e32 v7, v7, v9
	v_max_u32_e32 v9, v6, v2
	v_min_u32_e32 v2, v6, v2
	v_max_u32_e32 v6, v13, v8
	v_min_u32_e32 v8, v13, v8
	v_max_u32_e32 v13, v9, v10
	v_min_u32_e32 v9, v9, v10
	v_max_u32_e32 v10, v12, v6
	v_min_u32_e32 v6, v12, v6
	v_max_u32_e32 v12, v13, v8
	v_min_u32_e32 v8, v13, v8
	v_max_u32_e32 v13, v9, v7
	v_min_u32_e32 v7, v9, v7
	v_max_u32_dpp v9, v11, v11 quad_perm:[1,0,3,2] row_mask:0xf bank_mask:0xf bound_ctrl:1
	s_nop 1
	v_max_u32_dpp v9, v9, v9 quad_perm:[2,3,0,1] row_mask:0xf bank_mask:0xf bound_ctrl:1
	s_nop 1
	v_max_u32_dpp v9, v9, v9 row_half_mirror row_mask:0xf bank_mask:0xf bound_ctrl:1
	s_nop 1
	v_max_u32_dpp v9, v9, v9 row_mirror row_mask:0xf bank_mask:0xf bound_ctrl:1
	v_cmp_eq_u32_e32 vcc, v11, v9
	v_cndmask_b32_e64 v14, 0, v9, s[8:9]
	s_nop 0
	v_cndmask_b32_e32 v9, v11, v10, vcc
	v_cndmask_b32_e32 v10, v10, v6, vcc
	v_cndmask_b32_e32 v6, v6, v12, vcc
	v_cndmask_b32_e32 v11, v12, v8, vcc
	v_cndmask_b32_e32 v8, v8, v13, vcc
	v_cndmask_b32_e32 v12, v13, v7, vcc
	v_max_u32_dpp v13, v9, v9 quad_perm:[1,0,3,2] row_mask:0xf bank_mask:0xf bound_ctrl:1
	v_cndmask_b32_e32 v7, v7, v2, vcc
	v_cndmask_b32_e64 v2, v2, 0, vcc
	v_max_u32_dpp v13, v13, v13 quad_perm:[2,3,0,1] row_mask:0xf bank_mask:0xf bound_ctrl:1
	s_nop 1
	v_max_u32_dpp v13, v13, v13 row_half_mirror row_mask:0xf bank_mask:0xf bound_ctrl:1
	s_nop 1
	v_max_u32_dpp v13, v13, v13 row_mirror row_mask:0xf bank_mask:0xf bound_ctrl:1
	v_cmp_eq_u32_e32 vcc, v9, v13
	v_cndmask_b32_e64 v14, v14, v13, s[10:11]
	s_nop 0
	v_cndmask_b32_e32 v9, v9, v10, vcc
	v_cndmask_b32_e32 v10, v10, v6, vcc
	v_cndmask_b32_e32 v6, v6, v11, vcc
	v_max_u32_dpp v13, v9, v9 quad_perm:[1,0,3,2] row_mask:0xf bank_mask:0xf bound_ctrl:1
	v_cndmask_b32_e32 v11, v11, v8, vcc
	v_cndmask_b32_e32 v8, v8, v12, vcc
	v_max_u32_dpp v13, v13, v13 quad_perm:[2,3,0,1] row_mask:0xf bank_mask:0xf bound_ctrl:1
	v_cndmask_b32_e32 v12, v12, v7, vcc
	v_cndmask_b32_e32 v7, v7, v2, vcc
	v_max_u32_dpp v13, v13, v13 row_half_mirror row_mask:0xf bank_mask:0xf bound_ctrl:1
	v_cndmask_b32_e64 v2, v2, 0, vcc
	s_nop 0
	v_max_u32_dpp v13, v13, v13 row_mirror row_mask:0xf bank_mask:0xf bound_ctrl:1
	v_cmp_eq_u32_e32 vcc, v9, v13
	v_cndmask_b32_e64 v14, v14, v13, s[12:13]
	s_nop 0
	v_cndmask_b32_e32 v9, v9, v10, vcc
	v_cndmask_b32_e32 v10, v10, v6, vcc
	v_cndmask_b32_e32 v6, v6, v11, vcc
	v_max_u32_dpp v13, v9, v9 quad_perm:[1,0,3,2] row_mask:0xf bank_mask:0xf bound_ctrl:1
	v_cndmask_b32_e32 v11, v11, v8, vcc
	v_cndmask_b32_e32 v8, v8, v12, vcc
	v_max_u32_dpp v13, v13, v13 quad_perm:[2,3,0,1] row_mask:0xf bank_mask:0xf bound_ctrl:1
	v_cndmask_b32_e32 v12, v12, v7, vcc
	v_cndmask_b32_e32 v7, v7, v2, vcc
	v_max_u32_dpp v13, v13, v13 row_half_mirror row_mask:0xf bank_mask:0xf bound_ctrl:1
	v_cndmask_b32_e64 v2, v2, 0, vcc
	s_nop 0
	v_max_u32_dpp v13, v13, v13 row_mirror row_mask:0xf bank_mask:0xf bound_ctrl:1
	v_cmp_eq_u32_e32 vcc, v9, v13
	v_cndmask_b32_e64 v14, v14, v13, s[14:15]
	s_nop 0
	v_cndmask_b32_e32 v9, v9, v10, vcc
	v_cndmask_b32_e32 v10, v10, v6, vcc
	v_cndmask_b32_e32 v6, v6, v11, vcc
	v_max_u32_dpp v13, v9, v9 quad_perm:[1,0,3,2] row_mask:0xf bank_mask:0xf bound_ctrl:1
	v_cndmask_b32_e32 v11, v11, v8, vcc
	v_cndmask_b32_e32 v8, v8, v12, vcc
	v_max_u32_dpp v13, v13, v13 quad_perm:[2,3,0,1] row_mask:0xf bank_mask:0xf bound_ctrl:1
	v_cndmask_b32_e32 v12, v12, v7, vcc
	v_cndmask_b32_e32 v7, v7, v2, vcc
	v_max_u32_dpp v13, v13, v13 row_half_mirror row_mask:0xf bank_mask:0xf bound_ctrl:1
	v_cndmask_b32_e64 v2, v2, 0, vcc
	s_nop 0
	v_max_u32_dpp v13, v13, v13 row_mirror row_mask:0xf bank_mask:0xf bound_ctrl:1
	v_cmp_eq_u32_e32 vcc, v9, v13
	v_cndmask_b32_e64 v14, v14, v13, s[16:17]
	s_nop 0
	v_cndmask_b32_e32 v9, v9, v10, vcc
	v_cndmask_b32_e32 v10, v10, v6, vcc
	v_cndmask_b32_e32 v6, v6, v11, vcc
	v_max_u32_dpp v13, v9, v9 quad_perm:[1,0,3,2] row_mask:0xf bank_mask:0xf bound_ctrl:1
	v_cndmask_b32_e32 v11, v11, v8, vcc
	v_cndmask_b32_e32 v8, v8, v12, vcc
	v_max_u32_dpp v13, v13, v13 quad_perm:[2,3,0,1] row_mask:0xf bank_mask:0xf bound_ctrl:1
	v_cndmask_b32_e32 v12, v12, v7, vcc
	v_cndmask_b32_e32 v7, v7, v2, vcc
	v_max_u32_dpp v13, v13, v13 row_half_mirror row_mask:0xf bank_mask:0xf bound_ctrl:1
	v_cndmask_b32_e64 v2, v2, 0, vcc
	s_nop 0
	v_max_u32_dpp v13, v13, v13 row_mirror row_mask:0xf bank_mask:0xf bound_ctrl:1
	v_cmp_eq_u32_e32 vcc, v9, v13
	v_cndmask_b32_e64 v14, v14, v13, s[18:19]
	s_nop 0
	v_cndmask_b32_e32 v9, v9, v10, vcc
	v_cndmask_b32_e32 v10, v10, v6, vcc
	v_cndmask_b32_e32 v6, v6, v11, vcc
	v_max_u32_dpp v13, v9, v9 quad_perm:[1,0,3,2] row_mask:0xf bank_mask:0xf bound_ctrl:1
	v_cndmask_b32_e32 v11, v11, v8, vcc
	v_cndmask_b32_e32 v8, v8, v12, vcc
	v_max_u32_dpp v13, v13, v13 quad_perm:[2,3,0,1] row_mask:0xf bank_mask:0xf bound_ctrl:1
	v_cndmask_b32_e32 v12, v12, v7, vcc
	v_cndmask_b32_e32 v7, v7, v2, vcc
	v_max_u32_dpp v13, v13, v13 row_half_mirror row_mask:0xf bank_mask:0xf bound_ctrl:1
	v_cndmask_b32_e64 v2, v2, 0, vcc
	s_nop 0
	v_max_u32_dpp v13, v13, v13 row_mirror row_mask:0xf bank_mask:0xf bound_ctrl:1
	v_cmp_eq_u32_e32 vcc, v9, v13
	v_cndmask_b32_e64 v14, v14, v13, s[20:21]
	s_nop 0
	v_cndmask_b32_e32 v9, v9, v10, vcc
	v_cndmask_b32_e32 v10, v10, v6, vcc
	v_cndmask_b32_e32 v6, v6, v11, vcc
	v_max_u32_dpp v13, v9, v9 quad_perm:[1,0,3,2] row_mask:0xf bank_mask:0xf bound_ctrl:1
	v_cndmask_b32_e32 v11, v11, v8, vcc
	v_cndmask_b32_e32 v8, v8, v12, vcc
	v_max_u32_dpp v13, v13, v13 quad_perm:[2,3,0,1] row_mask:0xf bank_mask:0xf bound_ctrl:1
	v_cndmask_b32_e32 v12, v12, v7, vcc
	v_cndmask_b32_e32 v7, v7, v2, vcc
	v_max_u32_dpp v13, v13, v13 row_half_mirror row_mask:0xf bank_mask:0xf bound_ctrl:1
	v_cndmask_b32_e64 v2, v2, 0, vcc
	s_nop 0
	v_max_u32_dpp v13, v13, v13 row_mirror row_mask:0xf bank_mask:0xf bound_ctrl:1
	v_cmp_eq_u32_e32 vcc, v9, v13
	v_cndmask_b32_e64 v14, v14, v13, s[22:23]
	s_nop 0
	v_cndmask_b32_e32 v9, v9, v10, vcc
	v_cndmask_b32_e32 v10, v10, v6, vcc
	v_cndmask_b32_e32 v6, v6, v11, vcc
	v_max_u32_dpp v13, v9, v9 quad_perm:[1,0,3,2] row_mask:0xf bank_mask:0xf bound_ctrl:1
	v_cndmask_b32_e32 v11, v11, v8, vcc
	v_cndmask_b32_e32 v8, v8, v12, vcc
	v_max_u32_dpp v13, v13, v13 quad_perm:[2,3,0,1] row_mask:0xf bank_mask:0xf bound_ctrl:1
	v_cndmask_b32_e32 v12, v12, v7, vcc
	v_cndmask_b32_e32 v7, v7, v2, vcc
	v_max_u32_dpp v13, v13, v13 row_half_mirror row_mask:0xf bank_mask:0xf bound_ctrl:1
	v_cndmask_b32_e64 v2, v2, 0, vcc
	s_nop 0
	v_max_u32_dpp v13, v13, v13 row_mirror row_mask:0xf bank_mask:0xf bound_ctrl:1
	v_cmp_eq_u32_e32 vcc, v9, v13
	v_cndmask_b32_e64 v14, v14, v13, s[24:25]
	s_nop 0
	v_cndmask_b32_e32 v9, v9, v10, vcc
	v_cndmask_b32_e32 v10, v10, v6, vcc
	v_cndmask_b32_e32 v6, v6, v11, vcc
	v_cndmask_b32_e32 v11, v11, v8, vcc
	v_cndmask_b32_e32 v8, v8, v12, vcc
	v_cndmask_b32_e32 v12, v12, v7, vcc
	v_cndmask_b32_e32 v2, v7, v2, vcc
	v_max_u32_dpp v7, v9, v9 quad_perm:[1,0,3,2] row_mask:0xf bank_mask:0xf bound_ctrl:1
	s_nop 1
	v_max_u32_dpp v7, v7, v7 quad_perm:[2,3,0,1] row_mask:0xf bank_mask:0xf bound_ctrl:1
	s_nop 1
	v_max_u32_dpp v7, v7, v7 row_half_mirror row_mask:0xf bank_mask:0xf bound_ctrl:1
	s_nop 1
	v_max_u32_dpp v7, v7, v7 row_mirror row_mask:0xf bank_mask:0xf bound_ctrl:1
	v_cmp_eq_u32_e32 vcc, v9, v7
	v_cndmask_b32_e64 v13, v14, v7, s[26:27]
	s_nop 0
	v_cndmask_b32_e32 v7, v9, v10, vcc
	v_cndmask_b32_e32 v9, v10, v6, vcc
	v_cndmask_b32_e32 v6, v6, v11, vcc
	v_cndmask_b32_e32 v10, v11, v8, vcc
	v_max_u32_dpp v11, v7, v7 quad_perm:[1,0,3,2] row_mask:0xf bank_mask:0xf bound_ctrl:1
	v_cndmask_b32_e32 v8, v8, v12, vcc
	v_cndmask_b32_e32 v2, v12, v2, vcc
	v_max_u32_dpp v11, v11, v11 quad_perm:[2,3,0,1] row_mask:0xf bank_mask:0xf bound_ctrl:1
	s_nop 1
	v_max_u32_dpp v11, v11, v11 row_half_mirror row_mask:0xf bank_mask:0xf bound_ctrl:1
	s_nop 1
	v_max_u32_dpp v11, v11, v11 row_mirror row_mask:0xf bank_mask:0xf bound_ctrl:1
	v_cmp_eq_u32_e32 vcc, v7, v11
	v_cndmask_b32_e64 v12, v13, v11, s[28:29]
	v_ashrrev_i32_e32 v13, 31, v3
	v_cndmask_b32_e32 v7, v7, v9, vcc
	v_cndmask_b32_e32 v9, v9, v6, vcc
	v_cndmask_b32_e32 v6, v6, v10, vcc
	v_cndmask_b32_e32 v10, v10, v8, vcc
	v_cndmask_b32_e32 v2, v8, v2, vcc
	v_max_u32_dpp v8, v7, v7 quad_perm:[1,0,3,2] row_mask:0xf bank_mask:0xf bound_ctrl:1
	v_bitop3_b32 v3, v13, v3, s2 bitop3:0x36
	v_and_or_b32 v3, v3, s55, v71
	v_max_u32_dpp v8, v8, v8 quad_perm:[2,3,0,1] row_mask:0xf bank_mask:0xf bound_ctrl:1
	s_nop 1
	v_max_u32_dpp v8, v8, v8 row_half_mirror row_mask:0xf bank_mask:0xf bound_ctrl:1
	s_nop 1
	v_max_u32_dpp v8, v8, v8 row_mirror row_mask:0xf bank_mask:0xf bound_ctrl:1
	v_cmp_eq_u32_e32 vcc, v7, v8
	v_cndmask_b32_e64 v11, v12, v8, s[30:31]
	v_ashrrev_i32_e32 v12, 31, v43
	v_cndmask_b32_e32 v7, v7, v9, vcc
	v_cndmask_b32_e32 v8, v9, v6, vcc
	v_cndmask_b32_e32 v6, v6, v10, vcc
	v_max_u32_dpp v9, v7, v7 quad_perm:[1,0,3,2] row_mask:0xf bank_mask:0xf bound_ctrl:1
	v_cndmask_b32_e32 v2, v10, v2, vcc
	v_bitop3_b32 v12, v12, v43, s2 bitop3:0x36
	v_max_u32_dpp v9, v9, v9 quad_perm:[2,3,0,1] row_mask:0xf bank_mask:0xf bound_ctrl:1
	v_and_or_b32 v12, v12, s55, v70
	s_nop 0
	v_max_u32_dpp v9, v9, v9 row_half_mirror row_mask:0xf bank_mask:0xf bound_ctrl:1
	s_nop 1
	v_max_u32_dpp v9, v9, v9 row_mirror row_mask:0xf bank_mask:0xf bound_ctrl:1
	v_cmp_eq_u32_e32 vcc, v7, v9
	v_cndmask_b32_e64 v10, v11, v9, s[34:35]
	v_ashrrev_i32_e32 v11, 31, v39
	v_cndmask_b32_e32 v7, v7, v8, vcc
	v_cndmask_b32_e32 v8, v8, v6, vcc
	v_cndmask_b32_e32 v2, v6, v2, vcc
	v_max_u32_dpp v6, v7, v7 quad_perm:[1,0,3,2] row_mask:0xf bank_mask:0xf bound_ctrl:1
	v_bitop3_b32 v11, v11, v39, s2 bitop3:0x36
	v_and_or_b32 v11, v11, s55, v69
	v_max_u32_dpp v6, v6, v6 quad_perm:[2,3,0,1] row_mask:0xf bank_mask:0xf bound_ctrl:1
	s_nop 1
	v_max_u32_dpp v6, v6, v6 row_half_mirror row_mask:0xf bank_mask:0xf bound_ctrl:1
	s_nop 1
	v_max_u32_dpp v6, v6, v6 row_mirror row_mask:0xf bank_mask:0xf bound_ctrl:1
	v_cmp_eq_u32_e32 vcc, v7, v6
	v_cndmask_b32_e64 v9, v10, v6, s[36:37]
	v_ashrrev_i32_e32 v10, 31, v35
	v_cndmask_b32_e32 v6, v7, v8, vcc
	v_cndmask_b32_e32 v2, v8, v2, vcc
	v_bitop3_b32 v10, v10, v35, s2 bitop3:0x36
	v_max_u32_dpp v7, v6, v6 quad_perm:[1,0,3,2] row_mask:0xf bank_mask:0xf bound_ctrl:1
	v_and_or_b32 v10, v10, s55, v68
	s_nop 0
	v_max_u32_dpp v7, v7, v7 quad_perm:[2,3,0,1] row_mask:0xf bank_mask:0xf bound_ctrl:1
	s_nop 1
	v_max_u32_dpp v7, v7, v7 row_half_mirror row_mask:0xf bank_mask:0xf bound_ctrl:1
	s_nop 1
	v_max_u32_dpp v7, v7, v7 row_mirror row_mask:0xf bank_mask:0xf bound_ctrl:1
	v_cmp_eq_u32_e32 vcc, v6, v7
	v_cndmask_b32_e64 v8, v9, v7, s[38:39]
	v_ashrrev_i32_e32 v7, 31, v27
	v_cndmask_b32_e32 v2, v6, v2, vcc
	v_ashrrev_i32_e32 v6, 31, v23
	v_ashrrev_i32_e32 v9, 31, v31
	v_max_u32_dpp v2, v2, v2 quad_perm:[1,0,3,2] row_mask:0xf bank_mask:0xf bound_ctrl:1
	v_bitop3_b32 v6, v6, v23, s2 bitop3:0x36
	v_bitop3_b32 v7, v7, v27, s2 bitop3:0x36
	v_max_u32_dpp v2, v2, v2 quad_perm:[2,3,0,1] row_mask:0xf bank_mask:0xf bound_ctrl:1
	v_bitop3_b32 v9, v9, v31, s2 bitop3:0x36
	v_and_or_b32 v6, v6, s55, v65
	v_max_u32_dpp v2, v2, v2 row_half_mirror row_mask:0xf bank_mask:0xf bound_ctrl:1
	v_and_or_b32 v7, v7, s55, v66
	v_and_or_b32 v9, v9, s55, v67
	v_max_u32_dpp v2, v2, v2 row_mirror row_mask:0xf bank_mask:0xf bound_ctrl:1
	v_cndmask_b32_e64 v8, v8, v2, s[40:41]
	v_ashrrev_i32_e32 v2, 31, v19
	v_bitop3_b32 v2, v2, v19, s2 bitop3:0x36
	v_and_or_b32 v2, v2, s55, v60
	v_max_u32_e32 v13, v2, v6
	v_min_u32_e32 v2, v2, v6
	v_max_u32_e32 v6, v7, v9
	v_min_u32_e32 v7, v7, v9
	v_max_u32_e32 v9, v10, v11
	v_min_u32_e32 v10, v10, v11
	v_max_u32_e32 v11, v12, v3
	v_min_u32_e32 v3, v12, v3
	v_max_u32_e32 v12, v13, v6
	v_min_u32_e32 v6, v13, v6
	v_max_u32_e32 v13, v2, v7
	v_min_u32_e32 v2, v2, v7
	v_max_u32_e32 v7, v9, v11
	v_min_u32_e32 v9, v9, v11
	v_max_u32_e32 v11, v10, v3
	v_min_u32_e32 v3, v10, v3
	v_max_u32_e32 v10, v13, v6
	v_min_u32_e32 v6, v13, v6
	v_max_u32_e32 v13, v11, v9
	v_min_u32_e32 v9, v11, v9
	v_max_u32_e32 v11, v12, v7
	v_min_u32_e32 v7, v12, v7
	v_max_u32_e32 v12, v10, v13
	v_min_u32_e32 v10, v10, v13
	v_max_u32_e32 v13, v6, v9
	v_min_u32_e32 v6, v6, v9
	v_max_u32_e32 v9, v2, v3
	v_min_u32_e32 v2, v2, v3
	v_max_u32_e32 v3, v13, v7
	v_min_u32_e32 v7, v13, v7
	v_max_u32_e32 v13, v9, v10
	v_min_u32_e32 v9, v9, v10
	v_max_u32_e32 v10, v12, v3
	v_min_u32_e32 v3, v12, v3
	v_max_u32_e32 v12, v13, v7
	v_min_u32_e32 v7, v13, v7
	v_max_u32_e32 v13, v9, v6
	v_min_u32_e32 v6, v9, v6
	v_max_u32_dpp v9, v11, v11 quad_perm:[1,0,3,2] row_mask:0xf bank_mask:0xf bound_ctrl:1
	s_nop 1
	v_max_u32_dpp v9, v9, v9 quad_perm:[2,3,0,1] row_mask:0xf bank_mask:0xf bound_ctrl:1
	s_nop 1
	v_max_u32_dpp v9, v9, v9 row_half_mirror row_mask:0xf bank_mask:0xf bound_ctrl:1
	s_nop 1
	v_max_u32_dpp v9, v9, v9 row_mirror row_mask:0xf bank_mask:0xf bound_ctrl:1
	v_cmp_eq_u32_e32 vcc, v11, v9
	v_cndmask_b32_e64 v14, 0, v9, s[8:9]
	s_nop 0
	v_cndmask_b32_e32 v9, v11, v10, vcc
	v_cndmask_b32_e32 v10, v10, v3, vcc
	v_cndmask_b32_e32 v3, v3, v12, vcc
	v_cndmask_b32_e32 v11, v12, v7, vcc
	v_cndmask_b32_e32 v7, v7, v13, vcc
	v_cndmask_b32_e32 v12, v13, v6, vcc
	v_max_u32_dpp v13, v9, v9 quad_perm:[1,0,3,2] row_mask:0xf bank_mask:0xf bound_ctrl:1
	v_cndmask_b32_e32 v6, v6, v2, vcc
	v_cndmask_b32_e64 v2, v2, 0, vcc
	v_max_u32_dpp v13, v13, v13 quad_perm:[2,3,0,1] row_mask:0xf bank_mask:0xf bound_ctrl:1
	s_nop 1
	v_max_u32_dpp v13, v13, v13 row_half_mirror row_mask:0xf bank_mask:0xf bound_ctrl:1
	s_nop 1
	v_max_u32_dpp v13, v13, v13 row_mirror row_mask:0xf bank_mask:0xf bound_ctrl:1
	v_cmp_eq_u32_e32 vcc, v9, v13
	v_cndmask_b32_e64 v14, v14, v13, s[10:11]
	s_nop 0
	v_cndmask_b32_e32 v9, v9, v10, vcc
	v_cndmask_b32_e32 v10, v10, v3, vcc
	v_cndmask_b32_e32 v3, v3, v11, vcc
	v_max_u32_dpp v13, v9, v9 quad_perm:[1,0,3,2] row_mask:0xf bank_mask:0xf bound_ctrl:1
	v_cndmask_b32_e32 v11, v11, v7, vcc
	v_cndmask_b32_e32 v7, v7, v12, vcc
	v_max_u32_dpp v13, v13, v13 quad_perm:[2,3,0,1] row_mask:0xf bank_mask:0xf bound_ctrl:1
	v_cndmask_b32_e32 v12, v12, v6, vcc
	v_cndmask_b32_e32 v6, v6, v2, vcc
	v_max_u32_dpp v13, v13, v13 row_half_mirror row_mask:0xf bank_mask:0xf bound_ctrl:1
	v_cndmask_b32_e64 v2, v2, 0, vcc
	s_nop 0
	v_max_u32_dpp v13, v13, v13 row_mirror row_mask:0xf bank_mask:0xf bound_ctrl:1
	v_cmp_eq_u32_e32 vcc, v9, v13
	v_cndmask_b32_e64 v14, v14, v13, s[12:13]
	s_nop 0
	v_cndmask_b32_e32 v9, v9, v10, vcc
	v_cndmask_b32_e32 v10, v10, v3, vcc
	v_cndmask_b32_e32 v3, v3, v11, vcc
	v_max_u32_dpp v13, v9, v9 quad_perm:[1,0,3,2] row_mask:0xf bank_mask:0xf bound_ctrl:1
	v_cndmask_b32_e32 v11, v11, v7, vcc
	v_cndmask_b32_e32 v7, v7, v12, vcc
	v_max_u32_dpp v13, v13, v13 quad_perm:[2,3,0,1] row_mask:0xf bank_mask:0xf bound_ctrl:1
	v_cndmask_b32_e32 v12, v12, v6, vcc
	v_cndmask_b32_e32 v6, v6, v2, vcc
	v_max_u32_dpp v13, v13, v13 row_half_mirror row_mask:0xf bank_mask:0xf bound_ctrl:1
	v_cndmask_b32_e64 v2, v2, 0, vcc
	s_nop 0
	v_max_u32_dpp v13, v13, v13 row_mirror row_mask:0xf bank_mask:0xf bound_ctrl:1
	v_cmp_eq_u32_e32 vcc, v9, v13
	v_cndmask_b32_e64 v14, v14, v13, s[14:15]
	s_nop 0
	v_cndmask_b32_e32 v9, v9, v10, vcc
	v_cndmask_b32_e32 v10, v10, v3, vcc
	v_cndmask_b32_e32 v3, v3, v11, vcc
	v_max_u32_dpp v13, v9, v9 quad_perm:[1,0,3,2] row_mask:0xf bank_mask:0xf bound_ctrl:1
	v_cndmask_b32_e32 v11, v11, v7, vcc
	v_cndmask_b32_e32 v7, v7, v12, vcc
	v_max_u32_dpp v13, v13, v13 quad_perm:[2,3,0,1] row_mask:0xf bank_mask:0xf bound_ctrl:1
	v_cndmask_b32_e32 v12, v12, v6, vcc
	v_cndmask_b32_e32 v6, v6, v2, vcc
	v_max_u32_dpp v13, v13, v13 row_half_mirror row_mask:0xf bank_mask:0xf bound_ctrl:1
	v_cndmask_b32_e64 v2, v2, 0, vcc
	s_nop 0
	v_max_u32_dpp v13, v13, v13 row_mirror row_mask:0xf bank_mask:0xf bound_ctrl:1
	v_cmp_eq_u32_e32 vcc, v9, v13
	v_cndmask_b32_e64 v14, v14, v13, s[16:17]
	s_nop 0
	v_cndmask_b32_e32 v9, v9, v10, vcc
	v_cndmask_b32_e32 v10, v10, v3, vcc
	v_cndmask_b32_e32 v3, v3, v11, vcc
	v_max_u32_dpp v13, v9, v9 quad_perm:[1,0,3,2] row_mask:0xf bank_mask:0xf bound_ctrl:1
	v_cndmask_b32_e32 v11, v11, v7, vcc
	v_cndmask_b32_e32 v7, v7, v12, vcc
	v_max_u32_dpp v13, v13, v13 quad_perm:[2,3,0,1] row_mask:0xf bank_mask:0xf bound_ctrl:1
	v_cndmask_b32_e32 v12, v12, v6, vcc
	v_cndmask_b32_e32 v6, v6, v2, vcc
	v_max_u32_dpp v13, v13, v13 row_half_mirror row_mask:0xf bank_mask:0xf bound_ctrl:1
	v_cndmask_b32_e64 v2, v2, 0, vcc
	s_nop 0
	v_max_u32_dpp v13, v13, v13 row_mirror row_mask:0xf bank_mask:0xf bound_ctrl:1
	v_cmp_eq_u32_e32 vcc, v9, v13
	v_cndmask_b32_e64 v14, v14, v13, s[18:19]
	s_nop 0
	v_cndmask_b32_e32 v9, v9, v10, vcc
	v_cndmask_b32_e32 v10, v10, v3, vcc
	v_cndmask_b32_e32 v3, v3, v11, vcc
	v_max_u32_dpp v13, v9, v9 quad_perm:[1,0,3,2] row_mask:0xf bank_mask:0xf bound_ctrl:1
	v_cndmask_b32_e32 v11, v11, v7, vcc
	v_cndmask_b32_e32 v7, v7, v12, vcc
	v_max_u32_dpp v13, v13, v13 quad_perm:[2,3,0,1] row_mask:0xf bank_mask:0xf bound_ctrl:1
	v_cndmask_b32_e32 v12, v12, v6, vcc
	v_cndmask_b32_e32 v6, v6, v2, vcc
	v_max_u32_dpp v13, v13, v13 row_half_mirror row_mask:0xf bank_mask:0xf bound_ctrl:1
	v_cndmask_b32_e64 v2, v2, 0, vcc
	s_nop 0
	v_max_u32_dpp v13, v13, v13 row_mirror row_mask:0xf bank_mask:0xf bound_ctrl:1
	v_cmp_eq_u32_e32 vcc, v9, v13
	v_cndmask_b32_e64 v14, v14, v13, s[20:21]
	s_nop 0
	v_cndmask_b32_e32 v9, v9, v10, vcc
	v_cndmask_b32_e32 v10, v10, v3, vcc
	v_cndmask_b32_e32 v3, v3, v11, vcc
	v_max_u32_dpp v13, v9, v9 quad_perm:[1,0,3,2] row_mask:0xf bank_mask:0xf bound_ctrl:1
	v_cndmask_b32_e32 v11, v11, v7, vcc
	v_cndmask_b32_e32 v7, v7, v12, vcc
	v_max_u32_dpp v13, v13, v13 quad_perm:[2,3,0,1] row_mask:0xf bank_mask:0xf bound_ctrl:1
	v_cndmask_b32_e32 v12, v12, v6, vcc
	v_cndmask_b32_e32 v6, v6, v2, vcc
	v_max_u32_dpp v13, v13, v13 row_half_mirror row_mask:0xf bank_mask:0xf bound_ctrl:1
	v_cndmask_b32_e64 v2, v2, 0, vcc
	s_nop 0
	v_max_u32_dpp v13, v13, v13 row_mirror row_mask:0xf bank_mask:0xf bound_ctrl:1
	v_cmp_eq_u32_e32 vcc, v9, v13
	v_cndmask_b32_e64 v14, v14, v13, s[22:23]
	s_nop 0
	v_cndmask_b32_e32 v9, v9, v10, vcc
	v_cndmask_b32_e32 v10, v10, v3, vcc
	v_cndmask_b32_e32 v3, v3, v11, vcc
	v_max_u32_dpp v13, v9, v9 quad_perm:[1,0,3,2] row_mask:0xf bank_mask:0xf bound_ctrl:1
	v_cndmask_b32_e32 v11, v11, v7, vcc
	v_cndmask_b32_e32 v7, v7, v12, vcc
	v_max_u32_dpp v13, v13, v13 quad_perm:[2,3,0,1] row_mask:0xf bank_mask:0xf bound_ctrl:1
	v_cndmask_b32_e32 v12, v12, v6, vcc
	v_cndmask_b32_e32 v6, v6, v2, vcc
	v_max_u32_dpp v13, v13, v13 row_half_mirror row_mask:0xf bank_mask:0xf bound_ctrl:1
	v_cndmask_b32_e64 v2, v2, 0, vcc
	s_nop 0
	v_max_u32_dpp v13, v13, v13 row_mirror row_mask:0xf bank_mask:0xf bound_ctrl:1
	v_cmp_eq_u32_e32 vcc, v9, v13
	v_cndmask_b32_e64 v14, v14, v13, s[24:25]
	s_nop 0
	v_cndmask_b32_e32 v9, v9, v10, vcc
	v_cndmask_b32_e32 v10, v10, v3, vcc
	v_cndmask_b32_e32 v3, v3, v11, vcc
	v_cndmask_b32_e32 v11, v11, v7, vcc
	v_cndmask_b32_e32 v7, v7, v12, vcc
	v_cndmask_b32_e32 v12, v12, v6, vcc
	v_cndmask_b32_e32 v2, v6, v2, vcc
	v_max_u32_dpp v6, v9, v9 quad_perm:[1,0,3,2] row_mask:0xf bank_mask:0xf bound_ctrl:1
	s_nop 1
	v_max_u32_dpp v6, v6, v6 quad_perm:[2,3,0,1] row_mask:0xf bank_mask:0xf bound_ctrl:1
	s_nop 1
	v_max_u32_dpp v6, v6, v6 row_half_mirror row_mask:0xf bank_mask:0xf bound_ctrl:1
	s_nop 1
	v_max_u32_dpp v6, v6, v6 row_mirror row_mask:0xf bank_mask:0xf bound_ctrl:1
	v_cmp_eq_u32_e32 vcc, v9, v6
	v_cndmask_b32_e64 v13, v14, v6, s[26:27]
	s_nop 0
	v_cndmask_b32_e32 v6, v9, v10, vcc
	v_cndmask_b32_e32 v9, v10, v3, vcc
	v_cndmask_b32_e32 v3, v3, v11, vcc
	v_cndmask_b32_e32 v10, v11, v7, vcc
	v_max_u32_dpp v11, v6, v6 quad_perm:[1,0,3,2] row_mask:0xf bank_mask:0xf bound_ctrl:1
	v_cndmask_b32_e32 v7, v7, v12, vcc
	v_cndmask_b32_e32 v2, v12, v2, vcc
	v_max_u32_dpp v11, v11, v11 quad_perm:[2,3,0,1] row_mask:0xf bank_mask:0xf bound_ctrl:1
	s_nop 1
	v_max_u32_dpp v11, v11, v11 row_half_mirror row_mask:0xf bank_mask:0xf bound_ctrl:1
	s_nop 1
	v_max_u32_dpp v11, v11, v11 row_mirror row_mask:0xf bank_mask:0xf bound_ctrl:1
	v_cmp_eq_u32_e32 vcc, v6, v11
	v_cndmask_b32_e64 v12, v13, v11, s[28:29]
	v_ashrrev_i32_e32 v13, 31, v4
	v_cndmask_b32_e32 v6, v6, v9, vcc
	v_cndmask_b32_e32 v9, v9, v3, vcc
	v_cndmask_b32_e32 v3, v3, v10, vcc
	v_cndmask_b32_e32 v10, v10, v7, vcc
	v_cndmask_b32_e32 v2, v7, v2, vcc
	v_max_u32_dpp v7, v6, v6 quad_perm:[1,0,3,2] row_mask:0xf bank_mask:0xf bound_ctrl:1
	v_bitop3_b32 v4, v13, v4, s2 bitop3:0x36
	v_and_or_b32 v4, v4, s55, v71
	v_max_u32_dpp v7, v7, v7 quad_perm:[2,3,0,1] row_mask:0xf bank_mask:0xf bound_ctrl:1
	s_nop 1
	v_max_u32_dpp v7, v7, v7 row_half_mirror row_mask:0xf bank_mask:0xf bound_ctrl:1
	s_nop 1
	v_max_u32_dpp v7, v7, v7 row_mirror row_mask:0xf bank_mask:0xf bound_ctrl:1
	v_cmp_eq_u32_e32 vcc, v6, v7
	v_cndmask_b32_e64 v11, v12, v7, s[30:31]
	v_ashrrev_i32_e32 v12, 31, v44
	v_cndmask_b32_e32 v6, v6, v9, vcc
	v_cndmask_b32_e32 v7, v9, v3, vcc
	v_cndmask_b32_e32 v3, v3, v10, vcc
	v_max_u32_dpp v9, v6, v6 quad_perm:[1,0,3,2] row_mask:0xf bank_mask:0xf bound_ctrl:1
	v_cndmask_b32_e32 v2, v10, v2, vcc
	v_bitop3_b32 v12, v12, v44, s2 bitop3:0x36
	v_max_u32_dpp v9, v9, v9 quad_perm:[2,3,0,1] row_mask:0xf bank_mask:0xf bound_ctrl:1
	v_and_or_b32 v12, v12, s55, v70
	s_nop 0
	v_max_u32_dpp v9, v9, v9 row_half_mirror row_mask:0xf bank_mask:0xf bound_ctrl:1
	s_nop 1
	v_max_u32_dpp v9, v9, v9 row_mirror row_mask:0xf bank_mask:0xf bound_ctrl:1
	v_cmp_eq_u32_e32 vcc, v6, v9
	v_cndmask_b32_e64 v10, v11, v9, s[34:35]
	v_ashrrev_i32_e32 v11, 31, v40
	v_cndmask_b32_e32 v6, v6, v7, vcc
	v_cndmask_b32_e32 v7, v7, v3, vcc
	v_cndmask_b32_e32 v2, v3, v2, vcc
	v_max_u32_dpp v3, v6, v6 quad_perm:[1,0,3,2] row_mask:0xf bank_mask:0xf bound_ctrl:1
	v_bitop3_b32 v11, v11, v40, s2 bitop3:0x36
	v_and_or_b32 v11, v11, s55, v69
	v_max_u32_dpp v3, v3, v3 quad_perm:[2,3,0,1] row_mask:0xf bank_mask:0xf bound_ctrl:1
	s_nop 1
	v_max_u32_dpp v3, v3, v3 row_half_mirror row_mask:0xf bank_mask:0xf bound_ctrl:1
	s_nop 1
	v_max_u32_dpp v3, v3, v3 row_mirror row_mask:0xf bank_mask:0xf bound_ctrl:1
	v_cmp_eq_u32_e32 vcc, v6, v3
	v_cndmask_b32_e64 v9, v10, v3, s[36:37]
	v_ashrrev_i32_e32 v10, 31, v36
	v_cndmask_b32_e32 v3, v6, v7, vcc
	v_cndmask_b32_e32 v2, v7, v2, vcc
	v_bitop3_b32 v10, v10, v36, s2 bitop3:0x36
	v_max_u32_dpp v6, v3, v3 quad_perm:[1,0,3,2] row_mask:0xf bank_mask:0xf bound_ctrl:1
	v_and_or_b32 v10, v10, s55, v68
	s_nop 0
	v_max_u32_dpp v6, v6, v6 quad_perm:[2,3,0,1] row_mask:0xf bank_mask:0xf bound_ctrl:1
	s_nop 1
	v_max_u32_dpp v6, v6, v6 row_half_mirror row_mask:0xf bank_mask:0xf bound_ctrl:1
	s_nop 1
	v_max_u32_dpp v6, v6, v6 row_mirror row_mask:0xf bank_mask:0xf bound_ctrl:1
	v_cmp_eq_u32_e32 vcc, v3, v6
	v_cndmask_b32_e64 v7, v9, v6, s[38:39]
	v_ashrrev_i32_e32 v6, 31, v28
	v_cndmask_b32_e32 v2, v3, v2, vcc
	v_ashrrev_i32_e32 v3, 31, v24
	v_ashrrev_i32_e32 v9, 31, v32
	v_max_u32_dpp v2, v2, v2 quad_perm:[1,0,3,2] row_mask:0xf bank_mask:0xf bound_ctrl:1
	v_bitop3_b32 v3, v3, v24, s2 bitop3:0x36
	v_bitop3_b32 v6, v6, v28, s2 bitop3:0x36
	v_max_u32_dpp v2, v2, v2 quad_perm:[2,3,0,1] row_mask:0xf bank_mask:0xf bound_ctrl:1
	v_bitop3_b32 v9, v9, v32, s2 bitop3:0x36
	v_and_or_b32 v3, v3, s55, v65
	v_max_u32_dpp v2, v2, v2 row_half_mirror row_mask:0xf bank_mask:0xf bound_ctrl:1
	v_and_or_b32 v6, v6, s55, v66
	v_and_or_b32 v9, v9, s55, v67
	v_max_u32_dpp v2, v2, v2 row_mirror row_mask:0xf bank_mask:0xf bound_ctrl:1
	v_cndmask_b32_e64 v7, v7, v2, s[40:41]
	v_ashrrev_i32_e32 v2, 31, v20
	v_bitop3_b32 v2, v2, v20, s2 bitop3:0x36
	v_and_or_b32 v2, v2, s55, v60
	v_max_u32_e32 v13, v2, v3
	v_min_u32_e32 v2, v2, v3
	v_max_u32_e32 v3, v6, v9
	v_min_u32_e32 v6, v6, v9
	v_max_u32_e32 v9, v10, v11
	v_min_u32_e32 v10, v10, v11
	v_max_u32_e32 v11, v12, v4
	v_min_u32_e32 v4, v12, v4
	v_max_u32_e32 v12, v13, v3
	v_min_u32_e32 v3, v13, v3
	v_max_u32_e32 v13, v2, v6
	v_min_u32_e32 v2, v2, v6
	v_max_u32_e32 v6, v9, v11
	v_min_u32_e32 v9, v9, v11
	v_max_u32_e32 v11, v10, v4
	v_min_u32_e32 v4, v10, v4
	v_max_u32_e32 v10, v13, v3
	v_min_u32_e32 v3, v13, v3
	v_max_u32_e32 v13, v11, v9
	v_min_u32_e32 v9, v11, v9
	v_max_u32_e32 v11, v12, v6
	v_min_u32_e32 v6, v12, v6
	v_max_u32_e32 v12, v10, v13
	v_min_u32_e32 v10, v10, v13
	v_max_u32_e32 v13, v3, v9
	v_min_u32_e32 v3, v3, v9
	v_max_u32_e32 v9, v2, v4
	v_min_u32_e32 v2, v2, v4
	v_max_u32_e32 v4, v13, v6
	v_min_u32_e32 v6, v13, v6
	v_max_u32_e32 v13, v9, v10
	v_min_u32_e32 v9, v9, v10
	v_max_u32_e32 v10, v12, v4
	v_min_u32_e32 v4, v12, v4
	v_max_u32_e32 v12, v13, v6
	v_min_u32_e32 v6, v13, v6
	v_max_u32_e32 v13, v9, v3
	v_min_u32_e32 v3, v9, v3
	v_max_u32_dpp v9, v11, v11 quad_perm:[1,0,3,2] row_mask:0xf bank_mask:0xf bound_ctrl:1
	s_nop 1
	v_max_u32_dpp v9, v9, v9 quad_perm:[2,3,0,1] row_mask:0xf bank_mask:0xf bound_ctrl:1
	s_nop 1
	v_max_u32_dpp v9, v9, v9 row_half_mirror row_mask:0xf bank_mask:0xf bound_ctrl:1
	s_nop 1
	v_max_u32_dpp v9, v9, v9 row_mirror row_mask:0xf bank_mask:0xf bound_ctrl:1
	v_cmp_eq_u32_e32 vcc, v11, v9
	v_cndmask_b32_e64 v14, 0, v9, s[8:9]
	s_nop 0
	v_cndmask_b32_e32 v9, v11, v10, vcc
	v_cndmask_b32_e32 v10, v10, v4, vcc
	v_cndmask_b32_e32 v4, v4, v12, vcc
	v_cndmask_b32_e32 v11, v12, v6, vcc
	v_cndmask_b32_e32 v6, v6, v13, vcc
	v_cndmask_b32_e32 v12, v13, v3, vcc
	v_max_u32_dpp v13, v9, v9 quad_perm:[1,0,3,2] row_mask:0xf bank_mask:0xf bound_ctrl:1
	v_cndmask_b32_e32 v3, v3, v2, vcc
	v_cndmask_b32_e64 v2, v2, 0, vcc
	v_max_u32_dpp v13, v13, v13 quad_perm:[2,3,0,1] row_mask:0xf bank_mask:0xf bound_ctrl:1
	s_nop 1
	v_max_u32_dpp v13, v13, v13 row_half_mirror row_mask:0xf bank_mask:0xf bound_ctrl:1
	s_nop 1
	v_max_u32_dpp v13, v13, v13 row_mirror row_mask:0xf bank_mask:0xf bound_ctrl:1
	v_cmp_eq_u32_e32 vcc, v9, v13
	v_cndmask_b32_e64 v14, v14, v13, s[10:11]
	s_nop 0
	v_cndmask_b32_e32 v9, v9, v10, vcc
	v_cndmask_b32_e32 v10, v10, v4, vcc
	v_cndmask_b32_e32 v4, v4, v11, vcc
	v_max_u32_dpp v13, v9, v9 quad_perm:[1,0,3,2] row_mask:0xf bank_mask:0xf bound_ctrl:1
	v_cndmask_b32_e32 v11, v11, v6, vcc
	v_cndmask_b32_e32 v6, v6, v12, vcc
	v_max_u32_dpp v13, v13, v13 quad_perm:[2,3,0,1] row_mask:0xf bank_mask:0xf bound_ctrl:1
	v_cndmask_b32_e32 v12, v12, v3, vcc
	v_cndmask_b32_e32 v3, v3, v2, vcc
	v_max_u32_dpp v13, v13, v13 row_half_mirror row_mask:0xf bank_mask:0xf bound_ctrl:1
	v_cndmask_b32_e64 v2, v2, 0, vcc
	s_nop 0
	v_max_u32_dpp v13, v13, v13 row_mirror row_mask:0xf bank_mask:0xf bound_ctrl:1
	v_cmp_eq_u32_e32 vcc, v9, v13
	v_cndmask_b32_e64 v14, v14, v13, s[12:13]
	s_nop 0
	v_cndmask_b32_e32 v9, v9, v10, vcc
	v_cndmask_b32_e32 v10, v10, v4, vcc
	v_cndmask_b32_e32 v4, v4, v11, vcc
	v_max_u32_dpp v13, v9, v9 quad_perm:[1,0,3,2] row_mask:0xf bank_mask:0xf bound_ctrl:1
	v_cndmask_b32_e32 v11, v11, v6, vcc
	v_cndmask_b32_e32 v6, v6, v12, vcc
	v_max_u32_dpp v13, v13, v13 quad_perm:[2,3,0,1] row_mask:0xf bank_mask:0xf bound_ctrl:1
	v_cndmask_b32_e32 v12, v12, v3, vcc
	v_cndmask_b32_e32 v3, v3, v2, vcc
	v_max_u32_dpp v13, v13, v13 row_half_mirror row_mask:0xf bank_mask:0xf bound_ctrl:1
	v_cndmask_b32_e64 v2, v2, 0, vcc
	s_nop 0
	v_max_u32_dpp v13, v13, v13 row_mirror row_mask:0xf bank_mask:0xf bound_ctrl:1
	v_cmp_eq_u32_e32 vcc, v9, v13
	v_cndmask_b32_e64 v14, v14, v13, s[14:15]
	s_nop 0
	v_cndmask_b32_e32 v9, v9, v10, vcc
	v_cndmask_b32_e32 v10, v10, v4, vcc
	v_cndmask_b32_e32 v4, v4, v11, vcc
	v_max_u32_dpp v13, v9, v9 quad_perm:[1,0,3,2] row_mask:0xf bank_mask:0xf bound_ctrl:1
	v_cndmask_b32_e32 v11, v11, v6, vcc
	v_cndmask_b32_e32 v6, v6, v12, vcc
	v_max_u32_dpp v13, v13, v13 quad_perm:[2,3,0,1] row_mask:0xf bank_mask:0xf bound_ctrl:1
	v_cndmask_b32_e32 v12, v12, v3, vcc
	v_cndmask_b32_e32 v3, v3, v2, vcc
	v_max_u32_dpp v13, v13, v13 row_half_mirror row_mask:0xf bank_mask:0xf bound_ctrl:1
	v_cndmask_b32_e64 v2, v2, 0, vcc
	s_nop 0
	v_max_u32_dpp v13, v13, v13 row_mirror row_mask:0xf bank_mask:0xf bound_ctrl:1
	v_cmp_eq_u32_e32 vcc, v9, v13
	v_cndmask_b32_e64 v14, v14, v13, s[16:17]
	s_nop 0
	v_cndmask_b32_e32 v9, v9, v10, vcc
	v_cndmask_b32_e32 v10, v10, v4, vcc
	v_cndmask_b32_e32 v4, v4, v11, vcc
	v_max_u32_dpp v13, v9, v9 quad_perm:[1,0,3,2] row_mask:0xf bank_mask:0xf bound_ctrl:1
	v_cndmask_b32_e32 v11, v11, v6, vcc
	v_cndmask_b32_e32 v6, v6, v12, vcc
	v_max_u32_dpp v13, v13, v13 quad_perm:[2,3,0,1] row_mask:0xf bank_mask:0xf bound_ctrl:1
	v_cndmask_b32_e32 v12, v12, v3, vcc
	v_cndmask_b32_e32 v3, v3, v2, vcc
	v_max_u32_dpp v13, v13, v13 row_half_mirror row_mask:0xf bank_mask:0xf bound_ctrl:1
	v_cndmask_b32_e64 v2, v2, 0, vcc
	s_nop 0
	v_max_u32_dpp v13, v13, v13 row_mirror row_mask:0xf bank_mask:0xf bound_ctrl:1
	v_cmp_eq_u32_e32 vcc, v9, v13
	v_cndmask_b32_e64 v14, v14, v13, s[18:19]
	s_nop 0
	v_cndmask_b32_e32 v9, v9, v10, vcc
	v_cndmask_b32_e32 v10, v10, v4, vcc
	v_cndmask_b32_e32 v4, v4, v11, vcc
	v_max_u32_dpp v13, v9, v9 quad_perm:[1,0,3,2] row_mask:0xf bank_mask:0xf bound_ctrl:1
	v_cndmask_b32_e32 v11, v11, v6, vcc
	v_cndmask_b32_e32 v6, v6, v12, vcc
	v_max_u32_dpp v13, v13, v13 quad_perm:[2,3,0,1] row_mask:0xf bank_mask:0xf bound_ctrl:1
	v_cndmask_b32_e32 v12, v12, v3, vcc
	v_cndmask_b32_e32 v3, v3, v2, vcc
	v_max_u32_dpp v13, v13, v13 row_half_mirror row_mask:0xf bank_mask:0xf bound_ctrl:1
	v_cndmask_b32_e64 v2, v2, 0, vcc
	s_nop 0
	v_max_u32_dpp v13, v13, v13 row_mirror row_mask:0xf bank_mask:0xf bound_ctrl:1
	v_cmp_eq_u32_e32 vcc, v9, v13
	v_cndmask_b32_e64 v14, v14, v13, s[20:21]
	s_nop 0
	v_cndmask_b32_e32 v9, v9, v10, vcc
	v_cndmask_b32_e32 v10, v10, v4, vcc
	v_cndmask_b32_e32 v4, v4, v11, vcc
	v_max_u32_dpp v13, v9, v9 quad_perm:[1,0,3,2] row_mask:0xf bank_mask:0xf bound_ctrl:1
	v_cndmask_b32_e32 v11, v11, v6, vcc
	v_cndmask_b32_e32 v6, v6, v12, vcc
	v_max_u32_dpp v13, v13, v13 quad_perm:[2,3,0,1] row_mask:0xf bank_mask:0xf bound_ctrl:1
	v_cndmask_b32_e32 v12, v12, v3, vcc
	v_cndmask_b32_e32 v3, v3, v2, vcc
	v_max_u32_dpp v13, v13, v13 row_half_mirror row_mask:0xf bank_mask:0xf bound_ctrl:1
	v_cndmask_b32_e64 v2, v2, 0, vcc
	s_nop 0
	v_max_u32_dpp v13, v13, v13 row_mirror row_mask:0xf bank_mask:0xf bound_ctrl:1
	v_cmp_eq_u32_e32 vcc, v9, v13
	v_cndmask_b32_e64 v14, v14, v13, s[22:23]
	s_nop 0
	v_cndmask_b32_e32 v9, v9, v10, vcc
	v_cndmask_b32_e32 v10, v10, v4, vcc
	v_cndmask_b32_e32 v4, v4, v11, vcc
	v_max_u32_dpp v13, v9, v9 quad_perm:[1,0,3,2] row_mask:0xf bank_mask:0xf bound_ctrl:1
	v_cndmask_b32_e32 v11, v11, v6, vcc
	v_cndmask_b32_e32 v6, v6, v12, vcc
	v_max_u32_dpp v13, v13, v13 quad_perm:[2,3,0,1] row_mask:0xf bank_mask:0xf bound_ctrl:1
	v_cndmask_b32_e32 v12, v12, v3, vcc
	v_cndmask_b32_e32 v3, v3, v2, vcc
	v_max_u32_dpp v13, v13, v13 row_half_mirror row_mask:0xf bank_mask:0xf bound_ctrl:1
	v_cndmask_b32_e64 v2, v2, 0, vcc
	s_nop 0
	v_max_u32_dpp v13, v13, v13 row_mirror row_mask:0xf bank_mask:0xf bound_ctrl:1
	v_cmp_eq_u32_e32 vcc, v9, v13
	v_cndmask_b32_e64 v14, v14, v13, s[24:25]
	s_nop 0
	v_cndmask_b32_e32 v9, v9, v10, vcc
	v_cndmask_b32_e32 v10, v10, v4, vcc
	v_cndmask_b32_e32 v4, v4, v11, vcc
	v_cndmask_b32_e32 v11, v11, v6, vcc
	v_cndmask_b32_e32 v6, v6, v12, vcc
	v_cndmask_b32_e32 v12, v12, v3, vcc
	v_cndmask_b32_e32 v2, v3, v2, vcc
	v_max_u32_dpp v3, v9, v9 quad_perm:[1,0,3,2] row_mask:0xf bank_mask:0xf bound_ctrl:1
	s_nop 1
	v_max_u32_dpp v3, v3, v3 quad_perm:[2,3,0,1] row_mask:0xf bank_mask:0xf bound_ctrl:1
	s_nop 1
	v_max_u32_dpp v3, v3, v3 row_half_mirror row_mask:0xf bank_mask:0xf bound_ctrl:1
	s_nop 1
	v_max_u32_dpp v3, v3, v3 row_mirror row_mask:0xf bank_mask:0xf bound_ctrl:1
	v_cmp_eq_u32_e32 vcc, v9, v3
	v_cndmask_b32_e64 v13, v14, v3, s[26:27]
	s_nop 0
	v_cndmask_b32_e32 v3, v9, v10, vcc
	v_cndmask_b32_e32 v9, v10, v4, vcc
	v_cndmask_b32_e32 v4, v4, v11, vcc
	v_cndmask_b32_e32 v10, v11, v6, vcc
	v_max_u32_dpp v11, v3, v3 quad_perm:[1,0,3,2] row_mask:0xf bank_mask:0xf bound_ctrl:1
	v_cndmask_b32_e32 v6, v6, v12, vcc
	v_cndmask_b32_e32 v2, v12, v2, vcc
	v_max_u32_dpp v11, v11, v11 quad_perm:[2,3,0,1] row_mask:0xf bank_mask:0xf bound_ctrl:1
	s_nop 1
	v_max_u32_dpp v11, v11, v11 row_half_mirror row_mask:0xf bank_mask:0xf bound_ctrl:1
	s_nop 1
	v_max_u32_dpp v11, v11, v11 row_mirror row_mask:0xf bank_mask:0xf bound_ctrl:1
	v_cmp_eq_u32_e32 vcc, v3, v11
	v_cndmask_b32_e64 v12, v13, v11, s[28:29]
	v_ashrrev_i32_e32 v13, 31, v5
	v_cndmask_b32_e32 v3, v3, v9, vcc
	v_cndmask_b32_e32 v9, v9, v4, vcc
	v_cndmask_b32_e32 v4, v4, v10, vcc
	v_cndmask_b32_e32 v10, v10, v6, vcc
	v_cndmask_b32_e32 v2, v6, v2, vcc
	v_max_u32_dpp v6, v3, v3 quad_perm:[1,0,3,2] row_mask:0xf bank_mask:0xf bound_ctrl:1
	v_bitop3_b32 v5, v13, v5, s2 bitop3:0x36
	v_and_or_b32 v5, v5, s55, v71
	v_max_u32_dpp v6, v6, v6 quad_perm:[2,3,0,1] row_mask:0xf bank_mask:0xf bound_ctrl:1
	s_nop 1
	v_max_u32_dpp v6, v6, v6 row_half_mirror row_mask:0xf bank_mask:0xf bound_ctrl:1
	s_nop 1
	v_max_u32_dpp v6, v6, v6 row_mirror row_mask:0xf bank_mask:0xf bound_ctrl:1
	v_cmp_eq_u32_e32 vcc, v3, v6
	v_cndmask_b32_e64 v11, v12, v6, s[30:31]
	v_ashrrev_i32_e32 v12, 31, v45
	v_cndmask_b32_e32 v3, v3, v9, vcc
	v_cndmask_b32_e32 v6, v9, v4, vcc
	v_cndmask_b32_e32 v4, v4, v10, vcc
	v_max_u32_dpp v9, v3, v3 quad_perm:[1,0,3,2] row_mask:0xf bank_mask:0xf bound_ctrl:1
	v_cndmask_b32_e32 v2, v10, v2, vcc
	v_bitop3_b32 v12, v12, v45, s2 bitop3:0x36
	v_max_u32_dpp v9, v9, v9 quad_perm:[2,3,0,1] row_mask:0xf bank_mask:0xf bound_ctrl:1
	v_and_or_b32 v12, v12, s55, v70
	s_nop 0
	v_max_u32_dpp v9, v9, v9 row_half_mirror row_mask:0xf bank_mask:0xf bound_ctrl:1
	s_nop 1
	v_max_u32_dpp v9, v9, v9 row_mirror row_mask:0xf bank_mask:0xf bound_ctrl:1
	v_cmp_eq_u32_e32 vcc, v3, v9
	v_cndmask_b32_e64 v10, v11, v9, s[34:35]
	v_ashrrev_i32_e32 v11, 31, v41
	v_cndmask_b32_e32 v3, v3, v6, vcc
	v_cndmask_b32_e32 v6, v6, v4, vcc
	v_cndmask_b32_e32 v2, v4, v2, vcc
	v_max_u32_dpp v4, v3, v3 quad_perm:[1,0,3,2] row_mask:0xf bank_mask:0xf bound_ctrl:1
	v_bitop3_b32 v11, v11, v41, s2 bitop3:0x36
	v_and_or_b32 v11, v11, s55, v69
	v_max_u32_dpp v4, v4, v4 quad_perm:[2,3,0,1] row_mask:0xf bank_mask:0xf bound_ctrl:1
	s_nop 1
	v_max_u32_dpp v4, v4, v4 row_half_mirror row_mask:0xf bank_mask:0xf bound_ctrl:1
	s_nop 1
	v_max_u32_dpp v4, v4, v4 row_mirror row_mask:0xf bank_mask:0xf bound_ctrl:1
	v_cmp_eq_u32_e32 vcc, v3, v4
	v_cndmask_b32_e64 v9, v10, v4, s[36:37]
	v_ashrrev_i32_e32 v10, 31, v37
	v_cndmask_b32_e32 v3, v3, v6, vcc
	v_cndmask_b32_e32 v2, v6, v2, vcc
	v_bitop3_b32 v10, v10, v37, s2 bitop3:0x36
	v_max_u32_dpp v4, v3, v3 quad_perm:[1,0,3,2] row_mask:0xf bank_mask:0xf bound_ctrl:1
	v_and_or_b32 v10, v10, s55, v68
	s_nop 0
	v_max_u32_dpp v4, v4, v4 quad_perm:[2,3,0,1] row_mask:0xf bank_mask:0xf bound_ctrl:1
	s_nop 1
	v_max_u32_dpp v4, v4, v4 row_half_mirror row_mask:0xf bank_mask:0xf bound_ctrl:1
	s_nop 1
	v_max_u32_dpp v4, v4, v4 row_mirror row_mask:0xf bank_mask:0xf bound_ctrl:1
	v_cmp_eq_u32_e32 vcc, v3, v4
	v_cndmask_b32_e64 v6, v9, v4, s[38:39]
	v_ashrrev_i32_e32 v4, 31, v29
	v_cndmask_b32_e32 v2, v3, v2, vcc
	v_ashrrev_i32_e32 v3, 31, v25
	v_ashrrev_i32_e32 v9, 31, v33
	v_max_u32_dpp v2, v2, v2 quad_perm:[1,0,3,2] row_mask:0xf bank_mask:0xf bound_ctrl:1
	v_bitop3_b32 v3, v3, v25, s2 bitop3:0x36
	v_bitop3_b32 v4, v4, v29, s2 bitop3:0x36
	v_max_u32_dpp v2, v2, v2 quad_perm:[2,3,0,1] row_mask:0xf bank_mask:0xf bound_ctrl:1
	v_bitop3_b32 v9, v9, v33, s2 bitop3:0x36
	v_and_or_b32 v3, v3, s55, v65
	v_max_u32_dpp v2, v2, v2 row_half_mirror row_mask:0xf bank_mask:0xf bound_ctrl:1
	v_and_or_b32 v4, v4, s55, v66
	v_and_or_b32 v9, v9, s55, v67
	v_max_u32_dpp v2, v2, v2 row_mirror row_mask:0xf bank_mask:0xf bound_ctrl:1
	v_cndmask_b32_e64 v6, v6, v2, s[40:41]
	v_ashrrev_i32_e32 v2, 31, v21
	v_bitop3_b32 v2, v2, v21, s2 bitop3:0x36
	v_and_or_b32 v2, v2, s55, v60
	v_max_u32_e32 v13, v2, v3
	v_min_u32_e32 v2, v2, v3
	v_max_u32_e32 v3, v4, v9
	v_min_u32_e32 v4, v4, v9
	v_max_u32_e32 v9, v10, v11
	v_min_u32_e32 v10, v10, v11
	v_max_u32_e32 v11, v12, v5
	v_min_u32_e32 v5, v12, v5
	v_max_u32_e32 v12, v13, v3
	v_min_u32_e32 v3, v13, v3
	v_max_u32_e32 v13, v2, v4
	v_min_u32_e32 v2, v2, v4
	v_max_u32_e32 v4, v9, v11
	v_min_u32_e32 v9, v9, v11
	v_max_u32_e32 v11, v10, v5
	v_min_u32_e32 v5, v10, v5
	v_max_u32_e32 v10, v13, v3
	v_min_u32_e32 v3, v13, v3
	v_max_u32_e32 v13, v11, v9
	v_min_u32_e32 v9, v11, v9
	v_max_u32_e32 v11, v12, v4
	v_min_u32_e32 v4, v12, v4
	v_max_u32_e32 v12, v10, v13
	v_min_u32_e32 v10, v10, v13
	v_max_u32_e32 v13, v3, v9
	v_min_u32_e32 v3, v3, v9
	v_max_u32_e32 v9, v2, v5
	v_min_u32_e32 v2, v2, v5
	v_max_u32_e32 v5, v13, v4
	v_min_u32_e32 v4, v13, v4
	v_max_u32_e32 v13, v9, v10
	v_min_u32_e32 v9, v9, v10
	v_max_u32_e32 v10, v12, v5
	v_min_u32_e32 v5, v12, v5
	v_max_u32_e32 v12, v13, v4
	v_min_u32_e32 v4, v13, v4
	v_max_u32_e32 v13, v9, v3
	v_min_u32_e32 v3, v9, v3
	v_max_u32_dpp v9, v11, v11 quad_perm:[1,0,3,2] row_mask:0xf bank_mask:0xf bound_ctrl:1
	s_nop 1
	v_max_u32_dpp v9, v9, v9 quad_perm:[2,3,0,1] row_mask:0xf bank_mask:0xf bound_ctrl:1
	s_nop 1
	v_max_u32_dpp v9, v9, v9 row_half_mirror row_mask:0xf bank_mask:0xf bound_ctrl:1
	s_nop 1
	v_max_u32_dpp v9, v9, v9 row_mirror row_mask:0xf bank_mask:0xf bound_ctrl:1
	v_cmp_eq_u32_e32 vcc, v11, v9
	v_cndmask_b32_e64 v14, 0, v9, s[8:9]
	s_nop 0
	v_cndmask_b32_e32 v9, v11, v10, vcc
	v_cndmask_b32_e32 v10, v10, v5, vcc
	v_cndmask_b32_e32 v5, v5, v12, vcc
	v_cndmask_b32_e32 v11, v12, v4, vcc
	v_cndmask_b32_e32 v4, v4, v13, vcc
	v_cndmask_b32_e32 v12, v13, v3, vcc
	v_max_u32_dpp v13, v9, v9 quad_perm:[1,0,3,2] row_mask:0xf bank_mask:0xf bound_ctrl:1
	v_cndmask_b32_e32 v3, v3, v2, vcc
	v_cndmask_b32_e64 v2, v2, 0, vcc
	v_max_u32_dpp v13, v13, v13 quad_perm:[2,3,0,1] row_mask:0xf bank_mask:0xf bound_ctrl:1
	s_nop 1
	v_max_u32_dpp v13, v13, v13 row_half_mirror row_mask:0xf bank_mask:0xf bound_ctrl:1
	s_nop 1
	v_max_u32_dpp v13, v13, v13 row_mirror row_mask:0xf bank_mask:0xf bound_ctrl:1
	v_cmp_eq_u32_e32 vcc, v9, v13
	v_cndmask_b32_e64 v14, v14, v13, s[10:11]
	s_nop 0
	v_cndmask_b32_e32 v9, v9, v10, vcc
	v_cndmask_b32_e32 v10, v10, v5, vcc
	v_cndmask_b32_e32 v5, v5, v11, vcc
	v_max_u32_dpp v13, v9, v9 quad_perm:[1,0,3,2] row_mask:0xf bank_mask:0xf bound_ctrl:1
	v_cndmask_b32_e32 v11, v11, v4, vcc
	v_cndmask_b32_e32 v4, v4, v12, vcc
	v_max_u32_dpp v13, v13, v13 quad_perm:[2,3,0,1] row_mask:0xf bank_mask:0xf bound_ctrl:1
	v_cndmask_b32_e32 v12, v12, v3, vcc
	v_cndmask_b32_e32 v3, v3, v2, vcc
	v_max_u32_dpp v13, v13, v13 row_half_mirror row_mask:0xf bank_mask:0xf bound_ctrl:1
	v_cndmask_b32_e64 v2, v2, 0, vcc
	s_nop 0
	v_max_u32_dpp v13, v13, v13 row_mirror row_mask:0xf bank_mask:0xf bound_ctrl:1
	v_cmp_eq_u32_e32 vcc, v9, v13
	v_cndmask_b32_e64 v14, v14, v13, s[12:13]
	s_nop 0
	v_cndmask_b32_e32 v9, v9, v10, vcc
	v_cndmask_b32_e32 v10, v10, v5, vcc
	v_cndmask_b32_e32 v5, v5, v11, vcc
	v_max_u32_dpp v13, v9, v9 quad_perm:[1,0,3,2] row_mask:0xf bank_mask:0xf bound_ctrl:1
	v_cndmask_b32_e32 v11, v11, v4, vcc
	v_cndmask_b32_e32 v4, v4, v12, vcc
	v_max_u32_dpp v13, v13, v13 quad_perm:[2,3,0,1] row_mask:0xf bank_mask:0xf bound_ctrl:1
	v_cndmask_b32_e32 v12, v12, v3, vcc
	v_cndmask_b32_e32 v3, v3, v2, vcc
	v_max_u32_dpp v13, v13, v13 row_half_mirror row_mask:0xf bank_mask:0xf bound_ctrl:1
	v_cndmask_b32_e64 v2, v2, 0, vcc
	s_nop 0
	v_max_u32_dpp v13, v13, v13 row_mirror row_mask:0xf bank_mask:0xf bound_ctrl:1
	v_cmp_eq_u32_e32 vcc, v9, v13
	v_cndmask_b32_e64 v14, v14, v13, s[14:15]
	s_nop 0
	v_cndmask_b32_e32 v9, v9, v10, vcc
	v_cndmask_b32_e32 v10, v10, v5, vcc
	v_cndmask_b32_e32 v5, v5, v11, vcc
	v_max_u32_dpp v13, v9, v9 quad_perm:[1,0,3,2] row_mask:0xf bank_mask:0xf bound_ctrl:1
	v_cndmask_b32_e32 v11, v11, v4, vcc
	v_cndmask_b32_e32 v4, v4, v12, vcc
	v_max_u32_dpp v13, v13, v13 quad_perm:[2,3,0,1] row_mask:0xf bank_mask:0xf bound_ctrl:1
	v_cndmask_b32_e32 v12, v12, v3, vcc
	v_cndmask_b32_e32 v3, v3, v2, vcc
	v_max_u32_dpp v13, v13, v13 row_half_mirror row_mask:0xf bank_mask:0xf bound_ctrl:1
	v_cndmask_b32_e64 v2, v2, 0, vcc
	s_nop 0
	v_max_u32_dpp v13, v13, v13 row_mirror row_mask:0xf bank_mask:0xf bound_ctrl:1
	v_cmp_eq_u32_e32 vcc, v9, v13
	v_cndmask_b32_e64 v14, v14, v13, s[16:17]
	s_nop 0
	v_cndmask_b32_e32 v9, v9, v10, vcc
	v_cndmask_b32_e32 v10, v10, v5, vcc
	v_cndmask_b32_e32 v5, v5, v11, vcc
	v_max_u32_dpp v13, v9, v9 quad_perm:[1,0,3,2] row_mask:0xf bank_mask:0xf bound_ctrl:1
	v_cndmask_b32_e32 v11, v11, v4, vcc
	v_cndmask_b32_e32 v4, v4, v12, vcc
	v_max_u32_dpp v13, v13, v13 quad_perm:[2,3,0,1] row_mask:0xf bank_mask:0xf bound_ctrl:1
	v_cndmask_b32_e32 v12, v12, v3, vcc
	v_cndmask_b32_e32 v3, v3, v2, vcc
	v_max_u32_dpp v13, v13, v13 row_half_mirror row_mask:0xf bank_mask:0xf bound_ctrl:1
	v_cndmask_b32_e64 v2, v2, 0, vcc
	s_nop 0
	v_max_u32_dpp v13, v13, v13 row_mirror row_mask:0xf bank_mask:0xf bound_ctrl:1
	v_cmp_eq_u32_e32 vcc, v9, v13
	v_cndmask_b32_e64 v14, v14, v13, s[18:19]
	s_nop 0
	v_cndmask_b32_e32 v9, v9, v10, vcc
	v_cndmask_b32_e32 v10, v10, v5, vcc
	v_cndmask_b32_e32 v5, v5, v11, vcc
	v_max_u32_dpp v13, v9, v9 quad_perm:[1,0,3,2] row_mask:0xf bank_mask:0xf bound_ctrl:1
	v_cndmask_b32_e32 v11, v11, v4, vcc
	v_cndmask_b32_e32 v4, v4, v12, vcc
	v_max_u32_dpp v13, v13, v13 quad_perm:[2,3,0,1] row_mask:0xf bank_mask:0xf bound_ctrl:1
	v_cndmask_b32_e32 v12, v12, v3, vcc
	v_cndmask_b32_e32 v3, v3, v2, vcc
	v_max_u32_dpp v13, v13, v13 row_half_mirror row_mask:0xf bank_mask:0xf bound_ctrl:1
	v_cndmask_b32_e64 v2, v2, 0, vcc
	s_nop 0
	v_max_u32_dpp v13, v13, v13 row_mirror row_mask:0xf bank_mask:0xf bound_ctrl:1
	v_cmp_eq_u32_e32 vcc, v9, v13
	v_cndmask_b32_e64 v14, v14, v13, s[20:21]
	s_nop 0
	v_cndmask_b32_e32 v9, v9, v10, vcc
	v_cndmask_b32_e32 v10, v10, v5, vcc
	v_cndmask_b32_e32 v5, v5, v11, vcc
	v_max_u32_dpp v13, v9, v9 quad_perm:[1,0,3,2] row_mask:0xf bank_mask:0xf bound_ctrl:1
	v_cndmask_b32_e32 v11, v11, v4, vcc
	v_cndmask_b32_e32 v4, v4, v12, vcc
	v_max_u32_dpp v13, v13, v13 quad_perm:[2,3,0,1] row_mask:0xf bank_mask:0xf bound_ctrl:1
	v_cndmask_b32_e32 v12, v12, v3, vcc
	v_cndmask_b32_e32 v3, v3, v2, vcc
	v_max_u32_dpp v13, v13, v13 row_half_mirror row_mask:0xf bank_mask:0xf bound_ctrl:1
	v_cndmask_b32_e64 v2, v2, 0, vcc
	s_nop 0
	v_max_u32_dpp v13, v13, v13 row_mirror row_mask:0xf bank_mask:0xf bound_ctrl:1
	v_cmp_eq_u32_e32 vcc, v9, v13
	v_cndmask_b32_e64 v14, v14, v13, s[22:23]
	s_nop 0
	v_cndmask_b32_e32 v9, v9, v10, vcc
	v_cndmask_b32_e32 v10, v10, v5, vcc
	v_cndmask_b32_e32 v5, v5, v11, vcc
	v_max_u32_dpp v13, v9, v9 quad_perm:[1,0,3,2] row_mask:0xf bank_mask:0xf bound_ctrl:1
	v_cndmask_b32_e32 v11, v11, v4, vcc
	v_cndmask_b32_e32 v4, v4, v12, vcc
	v_max_u32_dpp v13, v13, v13 quad_perm:[2,3,0,1] row_mask:0xf bank_mask:0xf bound_ctrl:1
	v_cndmask_b32_e32 v12, v12, v3, vcc
	v_cndmask_b32_e32 v3, v3, v2, vcc
	v_max_u32_dpp v13, v13, v13 row_half_mirror row_mask:0xf bank_mask:0xf bound_ctrl:1
	v_cndmask_b32_e64 v2, v2, 0, vcc
	s_nop 0
	v_max_u32_dpp v13, v13, v13 row_mirror row_mask:0xf bank_mask:0xf bound_ctrl:1
	v_cmp_eq_u32_e32 vcc, v9, v13
	v_cndmask_b32_e64 v14, v14, v13, s[24:25]
	s_nop 0
	v_cndmask_b32_e32 v9, v9, v10, vcc
	v_cndmask_b32_e32 v10, v10, v5, vcc
	v_cndmask_b32_e32 v5, v5, v11, vcc
	v_cndmask_b32_e32 v11, v11, v4, vcc
	v_cndmask_b32_e32 v4, v4, v12, vcc
	v_cndmask_b32_e32 v12, v12, v3, vcc
	v_cndmask_b32_e32 v2, v3, v2, vcc
	v_max_u32_dpp v3, v9, v9 quad_perm:[1,0,3,2] row_mask:0xf bank_mask:0xf bound_ctrl:1
	s_nop 1
	v_max_u32_dpp v3, v3, v3 quad_perm:[2,3,0,1] row_mask:0xf bank_mask:0xf bound_ctrl:1
	s_nop 1
	v_max_u32_dpp v3, v3, v3 row_half_mirror row_mask:0xf bank_mask:0xf bound_ctrl:1
	s_nop 1
	v_max_u32_dpp v3, v3, v3 row_mirror row_mask:0xf bank_mask:0xf bound_ctrl:1
	v_cmp_eq_u32_e32 vcc, v9, v3
	v_cndmask_b32_e64 v13, v14, v3, s[26:27]
	s_nop 0
	v_cndmask_b32_e32 v3, v9, v10, vcc
	v_cndmask_b32_e32 v9, v10, v5, vcc
	v_cndmask_b32_e32 v5, v5, v11, vcc
	v_cndmask_b32_e32 v10, v11, v4, vcc
	v_max_u32_dpp v11, v3, v3 quad_perm:[1,0,3,2] row_mask:0xf bank_mask:0xf bound_ctrl:1
	v_cndmask_b32_e32 v4, v4, v12, vcc
	v_cndmask_b32_e32 v2, v12, v2, vcc
	v_max_u32_dpp v11, v11, v11 quad_perm:[2,3,0,1] row_mask:0xf bank_mask:0xf bound_ctrl:1
	s_nop 1
	v_max_u32_dpp v11, v11, v11 row_half_mirror row_mask:0xf bank_mask:0xf bound_ctrl:1
	s_nop 1
	v_max_u32_dpp v11, v11, v11 row_mirror row_mask:0xf bank_mask:0xf bound_ctrl:1
	v_cmp_eq_u32_e32 vcc, v3, v11
	v_cndmask_b32_e64 v12, v13, v11, s[28:29]
	s_nop 0
	v_cndmask_b32_e32 v3, v3, v9, vcc
	v_cndmask_b32_e32 v9, v9, v5, vcc
	v_cndmask_b32_e32 v5, v5, v10, vcc
	v_cndmask_b32_e32 v10, v10, v4, vcc
	v_cndmask_b32_e32 v2, v4, v2, vcc
	v_max_u32_dpp v4, v3, v3 quad_perm:[1,0,3,2] row_mask:0xf bank_mask:0xf bound_ctrl:1
	s_nop 1
	v_max_u32_dpp v4, v4, v4 quad_perm:[2,3,0,1] row_mask:0xf bank_mask:0xf bound_ctrl:1
	s_nop 1
	v_max_u32_dpp v4, v4, v4 row_half_mirror row_mask:0xf bank_mask:0xf bound_ctrl:1
	s_nop 1
	v_max_u32_dpp v4, v4, v4 row_mirror row_mask:0xf bank_mask:0xf bound_ctrl:1
	v_cmp_eq_u32_e32 vcc, v3, v4
	v_cndmask_b32_e64 v11, v12, v4, s[30:31]
	s_nop 0
	v_cndmask_b32_e32 v3, v3, v9, vcc
	v_cndmask_b32_e32 v4, v9, v5, vcc
	v_cndmask_b32_e32 v5, v5, v10, vcc
	v_max_u32_dpp v9, v3, v3 quad_perm:[1,0,3,2] row_mask:0xf bank_mask:0xf bound_ctrl:1
	v_cndmask_b32_e32 v2, v10, v2, vcc
	s_nop 0
	v_max_u32_dpp v9, v9, v9 quad_perm:[2,3,0,1] row_mask:0xf bank_mask:0xf bound_ctrl:1
	s_nop 1
	v_max_u32_dpp v9, v9, v9 row_half_mirror row_mask:0xf bank_mask:0xf bound_ctrl:1
	s_nop 1
	v_max_u32_dpp v9, v9, v9 row_mirror row_mask:0xf bank_mask:0xf bound_ctrl:1
	v_cmp_eq_u32_e32 vcc, v3, v9
	v_cndmask_b32_e64 v10, v11, v9, s[34:35]
	s_nop 0
	v_cndmask_b32_e32 v3, v3, v4, vcc
	v_cndmask_b32_e32 v4, v4, v5, vcc
	v_cndmask_b32_e32 v2, v5, v2, vcc
	v_max_u32_dpp v5, v3, v3 quad_perm:[1,0,3,2] row_mask:0xf bank_mask:0xf bound_ctrl:1
	s_nop 1
	v_max_u32_dpp v5, v5, v5 quad_perm:[2,3,0,1] row_mask:0xf bank_mask:0xf bound_ctrl:1
	s_nop 1
	v_max_u32_dpp v5, v5, v5 row_half_mirror row_mask:0xf bank_mask:0xf bound_ctrl:1
	s_nop 1
	v_max_u32_dpp v5, v5, v5 row_mirror row_mask:0xf bank_mask:0xf bound_ctrl:1
	v_cmp_eq_u32_e32 vcc, v3, v5
	v_cndmask_b32_e64 v9, v10, v5, s[36:37]
	s_nop 0
	v_cndmask_b32_e32 v3, v3, v4, vcc
	v_cndmask_b32_e32 v2, v4, v2, vcc
	s_nop 0
	v_max_u32_dpp v4, v3, v3 quad_perm:[1,0,3,2] row_mask:0xf bank_mask:0xf bound_ctrl:1
	s_nop 1
	v_max_u32_dpp v4, v4, v4 quad_perm:[2,3,0,1] row_mask:0xf bank_mask:0xf bound_ctrl:1
	s_nop 1
	v_max_u32_dpp v4, v4, v4 row_half_mirror row_mask:0xf bank_mask:0xf bound_ctrl:1
	s_nop 1
	v_max_u32_dpp v4, v4, v4 row_mirror row_mask:0xf bank_mask:0xf bound_ctrl:1
	v_cmp_eq_u32_e32 vcc, v3, v4
	v_cndmask_b32_e64 v5, v9, v4, s[38:39]
	s_nop 0
	v_cndmask_b32_e32 v2, v3, v2, vcc
	v_cmp_lt_i32_e32 vcc, -1, v82
	s_nop 0
	v_max_u32_dpp v2, v2, v2 quad_perm:[1,0,3,2] row_mask:0xf bank_mask:0xf bound_ctrl:1
	v_cndmask_b32_e64 v3, v77, -1, vcc
	v_cmp_lt_i32_e32 vcc, -1, v8
	v_max_u32_dpp v2, v2, v2 quad_perm:[2,3,0,1] row_mask:0xf bank_mask:0xf bound_ctrl:1
	v_bitop3_b32 v3, v3, v82, s55 bitop3:0x78
	s_nop 0
	v_max_u32_dpp v2, v2, v2 row_half_mirror row_mask:0xf bank_mask:0xf bound_ctrl:1
	s_nop 1
	v_max_u32_dpp v2, v2, v2 row_mirror row_mask:0xf bank_mask:0xf bound_ctrl:1
	v_cndmask_b32_e64 v4, v5, v2, s[40:41]
	v_cndmask_b32_e64 v5, v77, -1, vcc
	v_bitop3_b32 v5, v5, v8, s55 bitop3:0x78
	ds_write_b32 v61, v5
	v_bitop3_b32 v5, v82, s77, v82 bitop3:0xc
	ds_write_b32 v61, v5 offset:64
	v_bitop3_b32 v5, v8, s77, v8 bitop3:0xc
	ds_write_b32 v61, v5 offset:128
	ds_read_b32 v5, v59
	v_add_u32_e32 v2, v63, v53
	v_add_u32_e32 v53, 0x80, v53
	s_waitcnt lgkmcnt(0)
	v_add_f32_e32 v5, v5, v3
	v_ashrrev_i32_e32 v8, 31, v5
	v_bitop3_b32 v5, v8, v5, s2 bitop3:0x36
	v_and_or_b32 v5, v5, s96, v62
	s_nop 1
	v_max_u32_dpp v8, v5, v5 quad_perm:[1,0,3,2] row_mask:0xf bank_mask:0xf bound_ctrl:1
	s_nop 1
	v_max_u32_dpp v8, v8, v8 quad_perm:[2,3,0,1] row_mask:0xf bank_mask:0xf bound_ctrl:1
	s_nop 1
	v_max_u32_dpp v8, v8, v8 row_half_mirror row_mask:0xf bank_mask:0xf bound_ctrl:1
	s_nop 1
	v_max_u32_dpp v8, v8, v8 row_mirror row_mask:0xf bank_mask:0xf bound_ctrl:1
	v_cmp_eq_u32_e32 vcc, v5, v8
	v_cndmask_b32_e64 v9, 0, v8, s[8:9]
	s_nop 0
	v_cndmask_b32_e64 v5, 0, 1, vcc
	v_lshl_add_u32 v10, v5, 2, v59
	ds_read_b32 v11, v10
	v_subbrev_co_u32_e32 v8, vcc, 0, v62, vcc
	s_waitcnt lgkmcnt(0)
	v_add_f32_e32 v11, v11, v3
	v_ashrrev_i32_e32 v12, 31, v11
	v_bitop3_b32 v11, v12, v11, s2 bitop3:0x36
	v_and_or_b32 v8, v11, s96, v8
	s_nop 1
	v_max_u32_dpp v11, v8, v8 quad_perm:[1,0,3,2] row_mask:0xf bank_mask:0xf bound_ctrl:1
	s_nop 1
	v_max_u32_dpp v11, v11, v11 quad_perm:[2,3,0,1] row_mask:0xf bank_mask:0xf bound_ctrl:1
	s_nop 1
	v_max_u32_dpp v11, v11, v11 row_half_mirror row_mask:0xf bank_mask:0xf bound_ctrl:1
	s_nop 1
	v_max_u32_dpp v11, v11, v11 row_mirror row_mask:0xf bank_mask:0xf bound_ctrl:1
	v_cmp_eq_u32_e32 vcc, v8, v11
	v_cndmask_b32_e64 v9, v9, v11, s[10:11]
	s_nop 0
	v_cndmask_b32_e64 v8, 0, 1, vcc
	v_lshl_add_u32 v10, v8, 2, v10
	ds_read_b32 v13, v10
	v_addc_co_u32_e32 v11, vcc, 0, v5, vcc
	v_sub_u32_e32 v12, v62, v11
	s_waitcnt lgkmcnt(0)
	v_add_f32_e32 v13, v13, v3
	v_ashrrev_i32_e32 v14, 31, v13
	v_bitop3_b32 v13, v14, v13, s2 bitop3:0x36
	v_and_or_b32 v12, v13, s96, v12
	s_nop 1
	v_max_u32_dpp v13, v12, v12 quad_perm:[1,0,3,2] row_mask:0xf bank_mask:0xf bound_ctrl:1
	s_nop 1
	v_max_u32_dpp v13, v13, v13 quad_perm:[2,3,0,1] row_mask:0xf bank_mask:0xf bound_ctrl:1
	s_nop 1
	v_max_u32_dpp v13, v13, v13 row_half_mirror row_mask:0xf bank_mask:0xf bound_ctrl:1
	s_nop 1
	v_max_u32_dpp v13, v13, v13 row_mirror row_mask:0xf bank_mask:0xf bound_ctrl:1
	v_cmp_eq_u32_e32 vcc, v12, v13
	v_cndmask_b32_e64 v9, v9, v13, s[12:13]
	s_nop 0
	v_cndmask_b32_e64 v12, 0, 1, vcc
	v_lshl_add_u32 v10, v12, 2, v10
	ds_read_b32 v13, v10
	v_addc_co_u32_e32 v5, vcc, v8, v5, vcc
	v_sub_u32_e32 v8, v62, v5
	s_waitcnt lgkmcnt(0)
	v_add_f32_e32 v13, v13, v3
	v_ashrrev_i32_e32 v14, 31, v13
	v_bitop3_b32 v13, v14, v13, s2 bitop3:0x36
	v_and_or_b32 v8, v13, s96, v8
	s_nop 1
	v_max_u32_dpp v13, v8, v8 quad_perm:[1,0,3,2] row_mask:0xf bank_mask:0xf bound_ctrl:1
	s_nop 1
	v_max_u32_dpp v13, v13, v13 quad_perm:[2,3,0,1] row_mask:0xf bank_mask:0xf bound_ctrl:1
	s_nop 1
	v_max_u32_dpp v13, v13, v13 row_half_mirror row_mask:0xf bank_mask:0xf bound_ctrl:1
	s_nop 1
	v_max_u32_dpp v13, v13, v13 row_mirror row_mask:0xf bank_mask:0xf bound_ctrl:1
	v_cmp_eq_u32_e32 vcc, v8, v13
	v_cndmask_b32_e64 v9, v9, v13, s[14:15]
	s_nop 0
	v_cndmask_b32_e64 v8, 0, 1, vcc
	v_lshl_add_u32 v10, v8, 2, v10
	ds_read_b32 v13, v10
	v_addc_co_u32_e32 v11, vcc, v11, v12, vcc
	v_sub_u32_e32 v12, v62, v11
	s_waitcnt lgkmcnt(0)
	v_add_f32_e32 v13, v13, v3
	v_ashrrev_i32_e32 v14, 31, v13
	v_bitop3_b32 v13, v14, v13, s2 bitop3:0x36
	v_and_or_b32 v12, v13, s96, v12
	s_nop 1
	v_max_u32_dpp v13, v12, v12 quad_perm:[1,0,3,2] row_mask:0xf bank_mask:0xf bound_ctrl:1
	s_nop 1
	v_max_u32_dpp v13, v13, v13 quad_perm:[2,3,0,1] row_mask:0xf bank_mask:0xf bound_ctrl:1
	s_nop 1
	v_max_u32_dpp v13, v13, v13 row_half_mirror row_mask:0xf bank_mask:0xf bound_ctrl:1
	s_nop 1
	v_max_u32_dpp v13, v13, v13 row_mirror row_mask:0xf bank_mask:0xf bound_ctrl:1
	v_cmp_eq_u32_e32 vcc, v12, v13
	v_cndmask_b32_e64 v9, v9, v13, s[16:17]
	s_nop 0
	v_cndmask_b32_e64 v12, 0, 1, vcc
	v_lshl_add_u32 v10, v12, 2, v10
	ds_read_b32 v13, v10
	v_addc_co_u32_e32 v5, vcc, v5, v8, vcc
	v_sub_u32_e32 v8, v62, v5
	s_waitcnt lgkmcnt(0)
	v_add_f32_e32 v13, v13, v3
	v_ashrrev_i32_e32 v14, 31, v13
	v_bitop3_b32 v13, v14, v13, s2 bitop3:0x36
	v_and_or_b32 v8, v13, s96, v8
	s_nop 1
	v_max_u32_dpp v13, v8, v8 quad_perm:[1,0,3,2] row_mask:0xf bank_mask:0xf bound_ctrl:1
	s_nop 1
	v_max_u32_dpp v13, v13, v13 quad_perm:[2,3,0,1] row_mask:0xf bank_mask:0xf bound_ctrl:1
	s_nop 1
	v_max_u32_dpp v13, v13, v13 row_half_mirror row_mask:0xf bank_mask:0xf bound_ctrl:1
	s_nop 1
	v_max_u32_dpp v13, v13, v13 row_mirror row_mask:0xf bank_mask:0xf bound_ctrl:1
	v_cmp_eq_u32_e32 vcc, v8, v13
	v_cndmask_b32_e64 v9, v9, v13, s[18:19]
	s_nop 0
	v_cndmask_b32_e64 v8, 0, 1, vcc
	v_lshl_add_u32 v10, v8, 2, v10
	ds_read_b32 v13, v10
	v_addc_co_u32_e32 v11, vcc, v11, v12, vcc
	v_sub_u32_e32 v12, v62, v11
	s_waitcnt lgkmcnt(0)
	v_add_f32_e32 v13, v13, v3
	v_ashrrev_i32_e32 v14, 31, v13
	v_bitop3_b32 v13, v14, v13, s2 bitop3:0x36
	v_and_or_b32 v12, v13, s96, v12
	s_nop 1
	v_max_u32_dpp v13, v12, v12 quad_perm:[1,0,3,2] row_mask:0xf bank_mask:0xf bound_ctrl:1
	s_nop 1
	v_max_u32_dpp v13, v13, v13 quad_perm:[2,3,0,1] row_mask:0xf bank_mask:0xf bound_ctrl:1
	s_nop 1
	v_max_u32_dpp v13, v13, v13 row_half_mirror row_mask:0xf bank_mask:0xf bound_ctrl:1
	s_nop 1
	v_max_u32_dpp v13, v13, v13 row_mirror row_mask:0xf bank_mask:0xf bound_ctrl:1
	v_cmp_eq_u32_e32 vcc, v12, v13
	v_cndmask_b32_e64 v9, v9, v13, s[20:21]
	s_nop 0
	v_cndmask_b32_e64 v12, 0, 1, vcc
	v_lshl_add_u32 v10, v12, 2, v10
	ds_read_b32 v13, v10
	v_addc_co_u32_e32 v5, vcc, v5, v8, vcc
	v_sub_u32_e32 v8, v62, v5
	s_waitcnt lgkmcnt(0)
	v_add_f32_e32 v13, v13, v3
	v_ashrrev_i32_e32 v14, 31, v13
	v_bitop3_b32 v13, v14, v13, s2 bitop3:0x36
	v_and_or_b32 v8, v13, s96, v8
	s_nop 1
	v_max_u32_dpp v13, v8, v8 quad_perm:[1,0,3,2] row_mask:0xf bank_mask:0xf bound_ctrl:1
	s_nop 1
	v_max_u32_dpp v13, v13, v13 quad_perm:[2,3,0,1] row_mask:0xf bank_mask:0xf bound_ctrl:1
	s_nop 1
	v_max_u32_dpp v13, v13, v13 row_half_mirror row_mask:0xf bank_mask:0xf bound_ctrl:1
	s_nop 1
	v_max_u32_dpp v13, v13, v13 row_mirror row_mask:0xf bank_mask:0xf bound_ctrl:1
	v_cmp_eq_u32_e32 vcc, v8, v13
	v_cndmask_b32_e64 v9, v9, v13, s[22:23]
	s_nop 0
	v_cndmask_b32_e64 v8, 0, 1, vcc
	v_lshl_add_u32 v10, v8, 2, v10
	ds_read_b32 v13, v10
	v_addc_co_u32_e32 v11, vcc, v11, v12, vcc
	v_sub_u32_e32 v12, v62, v11
	s_waitcnt lgkmcnt(0)
	v_add_f32_e32 v13, v13, v3
	v_ashrrev_i32_e32 v14, 31, v13
	v_bitop3_b32 v13, v14, v13, s2 bitop3:0x36
	v_and_or_b32 v12, v13, s96, v12
	s_nop 1
	v_max_u32_dpp v13, v12, v12 quad_perm:[1,0,3,2] row_mask:0xf bank_mask:0xf bound_ctrl:1
	s_nop 1
	v_max_u32_dpp v13, v13, v13 quad_perm:[2,3,0,1] row_mask:0xf bank_mask:0xf bound_ctrl:1
	s_nop 1
	v_max_u32_dpp v13, v13, v13 row_half_mirror row_mask:0xf bank_mask:0xf bound_ctrl:1
	s_nop 1
	v_max_u32_dpp v13, v13, v13 row_mirror row_mask:0xf bank_mask:0xf bound_ctrl:1
	v_cmp_eq_u32_e32 vcc, v12, v13
	v_cndmask_b32_e64 v9, v9, v13, s[24:25]
	s_nop 0
	v_cndmask_b32_e64 v12, 0, 1, vcc
	v_lshl_add_u32 v10, v12, 2, v10
	ds_read_b32 v13, v10
	v_addc_co_u32_e32 v5, vcc, v5, v8, vcc
	v_sub_u32_e32 v8, v62, v5
	s_waitcnt lgkmcnt(0)
	v_add_f32_e32 v13, v13, v3
	v_ashrrev_i32_e32 v14, 31, v13
	v_bitop3_b32 v13, v14, v13, s2 bitop3:0x36
	v_and_or_b32 v8, v13, s96, v8
	s_nop 1
	v_max_u32_dpp v13, v8, v8 quad_perm:[1,0,3,2] row_mask:0xf bank_mask:0xf bound_ctrl:1
	s_nop 1
	v_max_u32_dpp v13, v13, v13 quad_perm:[2,3,0,1] row_mask:0xf bank_mask:0xf bound_ctrl:1
	s_nop 1
	v_max_u32_dpp v13, v13, v13 row_half_mirror row_mask:0xf bank_mask:0xf bound_ctrl:1
	s_nop 1
	v_max_u32_dpp v13, v13, v13 row_mirror row_mask:0xf bank_mask:0xf bound_ctrl:1
	v_cmp_eq_u32_e32 vcc, v8, v13
	v_cndmask_b32_e64 v9, v9, v13, s[26:27]
	s_nop 0
	v_cndmask_b32_e64 v8, 0, 1, vcc
	v_lshl_add_u32 v10, v8, 2, v10
	ds_read_b32 v13, v10
	v_addc_co_u32_e32 v11, vcc, v11, v12, vcc
	v_sub_u32_e32 v12, v62, v11
	s_waitcnt lgkmcnt(0)
	v_add_f32_e32 v13, v13, v3
	v_ashrrev_i32_e32 v14, 31, v13
	v_bitop3_b32 v13, v14, v13, s2 bitop3:0x36
	v_and_or_b32 v12, v13, s96, v12
	s_nop 1
	v_max_u32_dpp v13, v12, v12 quad_perm:[1,0,3,2] row_mask:0xf bank_mask:0xf bound_ctrl:1
	s_nop 1
	v_max_u32_dpp v13, v13, v13 quad_perm:[2,3,0,1] row_mask:0xf bank_mask:0xf bound_ctrl:1
	s_nop 1
	v_max_u32_dpp v13, v13, v13 row_half_mirror row_mask:0xf bank_mask:0xf bound_ctrl:1
	s_nop 1
	v_max_u32_dpp v13, v13, v13 row_mirror row_mask:0xf bank_mask:0xf bound_ctrl:1
	v_cmp_eq_u32_e32 vcc, v12, v13
	v_cndmask_b32_e64 v9, v9, v13, s[28:29]
	s_nop 0
	v_cndmask_b32_e64 v12, 0, 1, vcc
	v_lshl_add_u32 v10, v12, 2, v10
	ds_read_b32 v13, v10
	v_addc_co_u32_e32 v5, vcc, v5, v8, vcc
	v_sub_u32_e32 v8, v62, v5
	s_waitcnt lgkmcnt(0)
	v_add_f32_e32 v13, v13, v3
	v_ashrrev_i32_e32 v14, 31, v13
	v_bitop3_b32 v13, v14, v13, s2 bitop3:0x36
	v_and_or_b32 v8, v13, s96, v8
	s_nop 1
	v_max_u32_dpp v13, v8, v8 quad_perm:[1,0,3,2] row_mask:0xf bank_mask:0xf bound_ctrl:1
	s_nop 1
	v_max_u32_dpp v13, v13, v13 quad_perm:[2,3,0,1] row_mask:0xf bank_mask:0xf bound_ctrl:1
	s_nop 1
	v_max_u32_dpp v13, v13, v13 row_half_mirror row_mask:0xf bank_mask:0xf bound_ctrl:1
	s_nop 1
	v_max_u32_dpp v13, v13, v13 row_mirror row_mask:0xf bank_mask:0xf bound_ctrl:1
	v_cmp_eq_u32_e32 vcc, v8, v13
	v_cndmask_b32_e64 v9, v9, v13, s[30:31]
	s_nop 0
	v_cndmask_b32_e64 v8, 0, 1, vcc
	v_lshl_add_u32 v10, v8, 2, v10
	ds_read_b32 v13, v10
	v_addc_co_u32_e32 v11, vcc, v11, v12, vcc
	v_sub_u32_e32 v12, v62, v11
	s_waitcnt lgkmcnt(0)
	v_add_f32_e32 v13, v13, v3
	v_ashrrev_i32_e32 v14, 31, v13
	v_bitop3_b32 v13, v14, v13, s2 bitop3:0x36
	v_and_or_b32 v12, v13, s96, v12
	s_nop 1
	v_max_u32_dpp v13, v12, v12 quad_perm:[1,0,3,2] row_mask:0xf bank_mask:0xf bound_ctrl:1
	s_nop 1
	v_max_u32_dpp v13, v13, v13 quad_perm:[2,3,0,1] row_mask:0xf bank_mask:0xf bound_ctrl:1
	s_nop 1
	v_max_u32_dpp v13, v13, v13 row_half_mirror row_mask:0xf bank_mask:0xf bound_ctrl:1
	s_nop 1
	v_max_u32_dpp v13, v13, v13 row_mirror row_mask:0xf bank_mask:0xf bound_ctrl:1
	v_cmp_eq_u32_e32 vcc, v12, v13
	v_cndmask_b32_e64 v9, v9, v13, s[34:35]
	s_nop 0
	v_cndmask_b32_e64 v12, 0, 1, vcc
	v_lshl_add_u32 v10, v12, 2, v10
	ds_read_b32 v13, v10
	v_addc_co_u32_e32 v5, vcc, v5, v8, vcc
	v_sub_u32_e32 v8, v62, v5
	s_waitcnt lgkmcnt(0)
	v_add_f32_e32 v13, v13, v3
	v_ashrrev_i32_e32 v14, 31, v13
	v_bitop3_b32 v13, v14, v13, s2 bitop3:0x36
	v_and_or_b32 v8, v13, s96, v8
	s_nop 1
	v_max_u32_dpp v13, v8, v8 quad_perm:[1,0,3,2] row_mask:0xf bank_mask:0xf bound_ctrl:1
	s_nop 1
	v_max_u32_dpp v13, v13, v13 quad_perm:[2,3,0,1] row_mask:0xf bank_mask:0xf bound_ctrl:1
	s_nop 1
	v_max_u32_dpp v13, v13, v13 row_half_mirror row_mask:0xf bank_mask:0xf bound_ctrl:1
	s_nop 1
	v_max_u32_dpp v13, v13, v13 row_mirror row_mask:0xf bank_mask:0xf bound_ctrl:1
	v_cmp_eq_u32_e32 vcc, v8, v13
	v_cndmask_b32_e64 v9, v9, v13, s[36:37]
	s_nop 0
	v_cndmask_b32_e64 v8, 0, 1, vcc
	v_lshl_add_u32 v10, v8, 2, v10
	v_addc_co_u32_e32 v11, vcc, v11, v12, vcc
	ds_read_b32 v12, v10
	v_sub_u32_e32 v11, v62, v11
	s_waitcnt lgkmcnt(0)
	v_add_f32_e32 v12, v12, v3
	v_ashrrev_i32_e32 v13, 31, v12
	v_bitop3_b32 v12, v13, v12, s2 bitop3:0x36
	v_and_or_b32 v11, v12, s96, v11
	s_nop 1
	v_max_u32_dpp v12, v11, v11 quad_perm:[1,0,3,2] row_mask:0xf bank_mask:0xf bound_ctrl:1
	s_nop 1
	v_max_u32_dpp v12, v12, v12 quad_perm:[2,3,0,1] row_mask:0xf bank_mask:0xf bound_ctrl:1
	s_nop 1
	v_max_u32_dpp v12, v12, v12 row_half_mirror row_mask:0xf bank_mask:0xf bound_ctrl:1
	s_nop 1
	v_max_u32_dpp v12, v12, v12 row_mirror row_mask:0xf bank_mask:0xf bound_ctrl:1
	v_cmp_eq_u32_e32 vcc, v11, v12
	v_cndmask_b32_e64 v9, v9, v12, s[38:39]
	s_nop 0
	v_cndmask_b32_e64 v11, 0, 1, vcc
	v_addc_co_u32_e32 v5, vcc, v5, v8, vcc
	v_lshl_add_u32 v8, v11, 2, v10
	ds_read_b32 v8, v8
	v_sub_u32_e32 v5, v62, v5
	s_waitcnt lgkmcnt(0)
	v_add_f32_e32 v3, v8, v3
	v_ashrrev_i32_e32 v8, 31, v3
	v_bitop3_b32 v3, v8, v3, s2 bitop3:0x36
	v_and_or_b32 v3, v3, s96, v5
	s_nop 1
	v_max_u32_dpp v3, v3, v3 quad_perm:[1,0,3,2] row_mask:0xf bank_mask:0xf bound_ctrl:1
	s_nop 1
	v_max_u32_dpp v3, v3, v3 quad_perm:[2,3,0,1] row_mask:0xf bank_mask:0xf bound_ctrl:1
	s_nop 1
	v_max_u32_dpp v3, v3, v3 row_half_mirror row_mask:0xf bank_mask:0xf bound_ctrl:1
	s_nop 1
	v_max_u32_dpp v3, v3, v3 row_mirror row_mask:0xf bank_mask:0xf bound_ctrl:1
	v_cndmask_b32_e64 v3, v9, v3, s[40:41]
	v_cmp_lt_i32_e32 vcc, -1, v3
	v_not_b32_e32 v5, v3
	v_bitop3_b32 v9, v3, 15, v3 bitop3:0xc
	v_cndmask_b32_e64 v8, v77, -1, vcc
	v_bitop3_b32 v8, v8, v3, s96 bitop3:0x78
	v_max_u32_dpp v3, v3, v3 quad_perm:[1,0,3,2] row_mask:0xf bank_mask:0xf bound_ctrl:1
	v_lshrrev_b32_e32 v5, 2, v5
	v_and_b32_e32 v5, 60, v5
	v_max_u32_dpp v3, v3, v3 quad_perm:[2,3,0,1] row_mask:0xf bank_mask:0xf bound_ctrl:1
	v_add_u32_e32 v5, v59, v5
	v_lshl_add_u32 v9, v9, 2, v59
	v_max_u32_dpp v3, v3, v3 row_half_mirror row_mask:0xf bank_mask:0xf bound_ctrl:1
	ds_read_b32 v5, v5 offset:64
	ds_read_b32 v9, v9 offset:128
	v_max_u32_dpp v3, v3, v3 row_mirror row_mask:0xf bank_mask:0xf bound_ctrl:1
	v_cmp_lt_i32_e32 vcc, -1, v3
	s_waitcnt lgkmcnt(0)
	v_lshl_add_u32 v5, v5, 7, v9
	v_cndmask_b32_e64 v10, v77, -1, vcc
	v_bitop3_b32 v3, v10, v3, s96 bitop3:0x78
	v_sub_f32_e32 v3, v8, v3
	v_mul_f32_e32 v3, 0x3fb8aa3b, v3
	v_exp_f32_e32 v12, v3
	s_nop 1
	v_add_f32_dpp v3, v12, v12 quad_perm:[1,0,3,2] row_mask:0xf bank_mask:0xf bound_ctrl:1
	s_nop 1
	v_add_f32_dpp v3, v3, v3 quad_perm:[2,3,0,1] row_mask:0xf bank_mask:0xf bound_ctrl:1
	s_nop 1
	v_add_f32_dpp v3, v3, v3 row_half_mirror row_mask:0xf bank_mask:0xf bound_ctrl:1
	s_nop 1
	v_add_f32_dpp v13, v3, v3 row_mirror row_mask:0xf bank_mask:0xf bound_ctrl:1
	v_ashrrev_i32_e32 v3, 31, v2
	v_lshlrev_b64 v[8:9], 9, v[2:3]
	v_or_b32_e32 v8, v8, v78
	v_lshl_add_u64 v[10:11], s[52:53], 0, v[8:9]
	v_div_scale_f32 v3, s[46:47], v13, v13, v12
	global_store_dword v[10:11], v5, off
	v_rcp_f32_e32 v5, v3
	v_lshl_add_u64 v[8:9], s[58:59], 0, v[8:9]
	v_fma_f32 v10, -v3, v5, 1.0
	v_fmac_f32_e32 v5, v10, v5
	v_div_scale_f32 v10, vcc, v12, v13, v12
	v_mul_f32_e32 v11, v10, v5
	v_fma_f32 v14, -v3, v11, v10
	v_fmac_f32_e32 v11, v14, v5
	v_fma_f32 v3, -v3, v11, v10
	v_div_fmas_f32 v3, v3, v5, v11
	v_div_fixup_f32 v3, v3, v13, v12
	v_cmp_lt_i32_e32 vcc, -1, v81
	global_store_dword v[8:9], v3, off
	s_nop 0
	v_cndmask_b32_e64 v3, v77, -1, vcc
	v_cmp_lt_i32_e32 vcc, -1, v7
	v_bitop3_b32 v3, v3, v81, s55 bitop3:0x78
	s_nop 0
	v_cndmask_b32_e64 v5, v77, -1, vcc
	v_bitop3_b32 v5, v5, v7, s55 bitop3:0x78
	ds_write_b32 v61, v5
	v_bitop3_b32 v5, v81, s77, v81 bitop3:0xc
	ds_write_b32 v61, v5 offset:64
	v_bitop3_b32 v5, v7, s77, v7 bitop3:0xc
	ds_write_b32 v61, v5 offset:128
	ds_read_b32 v5, v59
	s_waitcnt lgkmcnt(0)
	v_add_f32_e32 v5, v5, v3
	v_ashrrev_i32_e32 v7, 31, v5
	v_bitop3_b32 v5, v7, v5, s2 bitop3:0x36
	v_and_or_b32 v5, v5, s96, v62
	s_nop 1
	v_max_u32_dpp v7, v5, v5 quad_perm:[1,0,3,2] row_mask:0xf bank_mask:0xf bound_ctrl:1
	s_nop 1
	v_max_u32_dpp v7, v7, v7 quad_perm:[2,3,0,1] row_mask:0xf bank_mask:0xf bound_ctrl:1
	s_nop 1
	v_max_u32_dpp v7, v7, v7 row_half_mirror row_mask:0xf bank_mask:0xf bound_ctrl:1
	s_nop 1
	v_max_u32_dpp v7, v7, v7 row_mirror row_mask:0xf bank_mask:0xf bound_ctrl:1
	v_cmp_eq_u32_e32 vcc, v5, v7
	v_cndmask_b32_e64 v8, 0, v7, s[8:9]
	s_nop 0
	v_cndmask_b32_e64 v5, 0, 1, vcc
	v_lshl_add_u32 v9, v5, 2, v59
	ds_read_b32 v10, v9
	v_subbrev_co_u32_e32 v7, vcc, 0, v62, vcc
	s_waitcnt lgkmcnt(0)
	v_add_f32_e32 v10, v10, v3
	v_ashrrev_i32_e32 v11, 31, v10
	v_bitop3_b32 v10, v11, v10, s2 bitop3:0x36
	v_and_or_b32 v7, v10, s96, v7
	s_nop 1
	v_max_u32_dpp v10, v7, v7 quad_perm:[1,0,3,2] row_mask:0xf bank_mask:0xf bound_ctrl:1
	s_nop 1
	v_max_u32_dpp v10, v10, v10 quad_perm:[2,3,0,1] row_mask:0xf bank_mask:0xf bound_ctrl:1
	s_nop 1
	v_max_u32_dpp v10, v10, v10 row_half_mirror row_mask:0xf bank_mask:0xf bound_ctrl:1
	s_nop 1
	v_max_u32_dpp v10, v10, v10 row_mirror row_mask:0xf bank_mask:0xf bound_ctrl:1
	v_cmp_eq_u32_e32 vcc, v7, v10
	v_cndmask_b32_e64 v8, v8, v10, s[10:11]
	s_nop 0
	v_cndmask_b32_e64 v7, 0, 1, vcc
	v_lshl_add_u32 v9, v7, 2, v9
	ds_read_b32 v12, v9
	v_addc_co_u32_e32 v10, vcc, 0, v5, vcc
	v_sub_u32_e32 v11, v62, v10
	s_waitcnt lgkmcnt(0)
	v_add_f32_e32 v12, v12, v3
	v_ashrrev_i32_e32 v13, 31, v12
	v_bitop3_b32 v12, v13, v12, s2 bitop3:0x36
	v_and_or_b32 v11, v12, s96, v11
	s_nop 1
	v_max_u32_dpp v12, v11, v11 quad_perm:[1,0,3,2] row_mask:0xf bank_mask:0xf bound_ctrl:1
	s_nop 1
	v_max_u32_dpp v12, v12, v12 quad_perm:[2,3,0,1] row_mask:0xf bank_mask:0xf bound_ctrl:1
	s_nop 1
	v_max_u32_dpp v12, v12, v12 row_half_mirror row_mask:0xf bank_mask:0xf bound_ctrl:1
	s_nop 1
	v_max_u32_dpp v12, v12, v12 row_mirror row_mask:0xf bank_mask:0xf bound_ctrl:1
	v_cmp_eq_u32_e32 vcc, v11, v12
	v_cndmask_b32_e64 v8, v8, v12, s[12:13]
	s_nop 0
	v_cndmask_b32_e64 v11, 0, 1, vcc
	v_lshl_add_u32 v9, v11, 2, v9
	ds_read_b32 v12, v9
	v_addc_co_u32_e32 v5, vcc, v7, v5, vcc
	v_sub_u32_e32 v7, v62, v5
	s_waitcnt lgkmcnt(0)
	v_add_f32_e32 v12, v12, v3
	v_ashrrev_i32_e32 v13, 31, v12
	v_bitop3_b32 v12, v13, v12, s2 bitop3:0x36
	v_and_or_b32 v7, v12, s96, v7
	s_nop 1
	v_max_u32_dpp v12, v7, v7 quad_perm:[1,0,3,2] row_mask:0xf bank_mask:0xf bound_ctrl:1
	s_nop 1
	v_max_u32_dpp v12, v12, v12 quad_perm:[2,3,0,1] row_mask:0xf bank_mask:0xf bound_ctrl:1
	s_nop 1
	v_max_u32_dpp v12, v12, v12 row_half_mirror row_mask:0xf bank_mask:0xf bound_ctrl:1
	s_nop 1
	v_max_u32_dpp v12, v12, v12 row_mirror row_mask:0xf bank_mask:0xf bound_ctrl:1
	v_cmp_eq_u32_e32 vcc, v7, v12
	v_cndmask_b32_e64 v8, v8, v12, s[14:15]
	s_nop 0
	v_cndmask_b32_e64 v7, 0, 1, vcc
	v_lshl_add_u32 v9, v7, 2, v9
	ds_read_b32 v12, v9
	v_addc_co_u32_e32 v10, vcc, v10, v11, vcc
	v_sub_u32_e32 v11, v62, v10
	s_waitcnt lgkmcnt(0)
	v_add_f32_e32 v12, v12, v3
	v_ashrrev_i32_e32 v13, 31, v12
	v_bitop3_b32 v12, v13, v12, s2 bitop3:0x36
	v_and_or_b32 v11, v12, s96, v11
	s_nop 1
	v_max_u32_dpp v12, v11, v11 quad_perm:[1,0,3,2] row_mask:0xf bank_mask:0xf bound_ctrl:1
	s_nop 1
	v_max_u32_dpp v12, v12, v12 quad_perm:[2,3,0,1] row_mask:0xf bank_mask:0xf bound_ctrl:1
	s_nop 1
	v_max_u32_dpp v12, v12, v12 row_half_mirror row_mask:0xf bank_mask:0xf bound_ctrl:1
	s_nop 1
	v_max_u32_dpp v12, v12, v12 row_mirror row_mask:0xf bank_mask:0xf bound_ctrl:1
	v_cmp_eq_u32_e32 vcc, v11, v12
	v_cndmask_b32_e64 v8, v8, v12, s[16:17]
	s_nop 0
	v_cndmask_b32_e64 v11, 0, 1, vcc
	v_lshl_add_u32 v9, v11, 2, v9
	ds_read_b32 v12, v9
	v_addc_co_u32_e32 v5, vcc, v5, v7, vcc
	v_sub_u32_e32 v7, v62, v5
	s_waitcnt lgkmcnt(0)
	v_add_f32_e32 v12, v12, v3
	v_ashrrev_i32_e32 v13, 31, v12
	v_bitop3_b32 v12, v13, v12, s2 bitop3:0x36
	v_and_or_b32 v7, v12, s96, v7
	s_nop 1
	v_max_u32_dpp v12, v7, v7 quad_perm:[1,0,3,2] row_mask:0xf bank_mask:0xf bound_ctrl:1
	s_nop 1
	v_max_u32_dpp v12, v12, v12 quad_perm:[2,3,0,1] row_mask:0xf bank_mask:0xf bound_ctrl:1
	s_nop 1
	v_max_u32_dpp v12, v12, v12 row_half_mirror row_mask:0xf bank_mask:0xf bound_ctrl:1
	s_nop 1
	v_max_u32_dpp v12, v12, v12 row_mirror row_mask:0xf bank_mask:0xf bound_ctrl:1
	v_cmp_eq_u32_e32 vcc, v7, v12
	v_cndmask_b32_e64 v8, v8, v12, s[18:19]
	s_nop 0
	v_cndmask_b32_e64 v7, 0, 1, vcc
	v_lshl_add_u32 v9, v7, 2, v9
	ds_read_b32 v12, v9
	v_addc_co_u32_e32 v10, vcc, v10, v11, vcc
	v_sub_u32_e32 v11, v62, v10
	s_waitcnt lgkmcnt(0)
	v_add_f32_e32 v12, v12, v3
	v_ashrrev_i32_e32 v13, 31, v12
	v_bitop3_b32 v12, v13, v12, s2 bitop3:0x36
	v_and_or_b32 v11, v12, s96, v11
	s_nop 1
	v_max_u32_dpp v12, v11, v11 quad_perm:[1,0,3,2] row_mask:0xf bank_mask:0xf bound_ctrl:1
	s_nop 1
	v_max_u32_dpp v12, v12, v12 quad_perm:[2,3,0,1] row_mask:0xf bank_mask:0xf bound_ctrl:1
	s_nop 1
	v_max_u32_dpp v12, v12, v12 row_half_mirror row_mask:0xf bank_mask:0xf bound_ctrl:1
	s_nop 1
	v_max_u32_dpp v12, v12, v12 row_mirror row_mask:0xf bank_mask:0xf bound_ctrl:1
	v_cmp_eq_u32_e32 vcc, v11, v12
	v_cndmask_b32_e64 v8, v8, v12, s[20:21]
	s_nop 0
	v_cndmask_b32_e64 v11, 0, 1, vcc
	v_lshl_add_u32 v9, v11, 2, v9
	ds_read_b32 v12, v9
	v_addc_co_u32_e32 v5, vcc, v5, v7, vcc
	v_sub_u32_e32 v7, v62, v5
	s_waitcnt lgkmcnt(0)
	v_add_f32_e32 v12, v12, v3
	v_ashrrev_i32_e32 v13, 31, v12
	v_bitop3_b32 v12, v13, v12, s2 bitop3:0x36
	v_and_or_b32 v7, v12, s96, v7
	s_nop 1
	v_max_u32_dpp v12, v7, v7 quad_perm:[1,0,3,2] row_mask:0xf bank_mask:0xf bound_ctrl:1
	s_nop 1
	v_max_u32_dpp v12, v12, v12 quad_perm:[2,3,0,1] row_mask:0xf bank_mask:0xf bound_ctrl:1
	s_nop 1
	v_max_u32_dpp v12, v12, v12 row_half_mirror row_mask:0xf bank_mask:0xf bound_ctrl:1
	s_nop 1
	v_max_u32_dpp v12, v12, v12 row_mirror row_mask:0xf bank_mask:0xf bound_ctrl:1
	v_cmp_eq_u32_e32 vcc, v7, v12
	v_cndmask_b32_e64 v8, v8, v12, s[22:23]
	s_nop 0
	v_cndmask_b32_e64 v7, 0, 1, vcc
	v_lshl_add_u32 v9, v7, 2, v9
	ds_read_b32 v12, v9
	v_addc_co_u32_e32 v10, vcc, v10, v11, vcc
	v_sub_u32_e32 v11, v62, v10
	s_waitcnt lgkmcnt(0)
	v_add_f32_e32 v12, v12, v3
	v_ashrrev_i32_e32 v13, 31, v12
	v_bitop3_b32 v12, v13, v12, s2 bitop3:0x36
	v_and_or_b32 v11, v12, s96, v11
	s_nop 1
	v_max_u32_dpp v12, v11, v11 quad_perm:[1,0,3,2] row_mask:0xf bank_mask:0xf bound_ctrl:1
	s_nop 1
	v_max_u32_dpp v12, v12, v12 quad_perm:[2,3,0,1] row_mask:0xf bank_mask:0xf bound_ctrl:1
	s_nop 1
	v_max_u32_dpp v12, v12, v12 row_half_mirror row_mask:0xf bank_mask:0xf bound_ctrl:1
	s_nop 1
	v_max_u32_dpp v12, v12, v12 row_mirror row_mask:0xf bank_mask:0xf bound_ctrl:1
	v_cmp_eq_u32_e32 vcc, v11, v12
	v_cndmask_b32_e64 v8, v8, v12, s[24:25]
	s_nop 0
	v_cndmask_b32_e64 v11, 0, 1, vcc
	v_lshl_add_u32 v9, v11, 2, v9
	ds_read_b32 v12, v9
	v_addc_co_u32_e32 v5, vcc, v5, v7, vcc
	v_sub_u32_e32 v7, v62, v5
	s_waitcnt lgkmcnt(0)
	v_add_f32_e32 v12, v12, v3
	v_ashrrev_i32_e32 v13, 31, v12
	v_bitop3_b32 v12, v13, v12, s2 bitop3:0x36
	v_and_or_b32 v7, v12, s96, v7
	s_nop 1
	v_max_u32_dpp v12, v7, v7 quad_perm:[1,0,3,2] row_mask:0xf bank_mask:0xf bound_ctrl:1
	s_nop 1
	v_max_u32_dpp v12, v12, v12 quad_perm:[2,3,0,1] row_mask:0xf bank_mask:0xf bound_ctrl:1
	s_nop 1
	v_max_u32_dpp v12, v12, v12 row_half_mirror row_mask:0xf bank_mask:0xf bound_ctrl:1
	s_nop 1
	v_max_u32_dpp v12, v12, v12 row_mirror row_mask:0xf bank_mask:0xf bound_ctrl:1
	v_cmp_eq_u32_e32 vcc, v7, v12
	v_cndmask_b32_e64 v8, v8, v12, s[26:27]
	s_nop 0
	v_cndmask_b32_e64 v7, 0, 1, vcc
	v_lshl_add_u32 v9, v7, 2, v9
	ds_read_b32 v12, v9
	v_addc_co_u32_e32 v10, vcc, v10, v11, vcc
	v_sub_u32_e32 v11, v62, v10
	s_waitcnt lgkmcnt(0)
	v_add_f32_e32 v12, v12, v3
	v_ashrrev_i32_e32 v13, 31, v12
	v_bitop3_b32 v12, v13, v12, s2 bitop3:0x36
	v_and_or_b32 v11, v12, s96, v11
	s_nop 1
	v_max_u32_dpp v12, v11, v11 quad_perm:[1,0,3,2] row_mask:0xf bank_mask:0xf bound_ctrl:1
	s_nop 1
	v_max_u32_dpp v12, v12, v12 quad_perm:[2,3,0,1] row_mask:0xf bank_mask:0xf bound_ctrl:1
	s_nop 1
	v_max_u32_dpp v12, v12, v12 row_half_mirror row_mask:0xf bank_mask:0xf bound_ctrl:1
	s_nop 1
	v_max_u32_dpp v12, v12, v12 row_mirror row_mask:0xf bank_mask:0xf bound_ctrl:1
	v_cmp_eq_u32_e32 vcc, v11, v12
	v_cndmask_b32_e64 v8, v8, v12, s[28:29]
	s_nop 0
	v_cndmask_b32_e64 v11, 0, 1, vcc
	v_lshl_add_u32 v9, v11, 2, v9
	ds_read_b32 v12, v9
	v_addc_co_u32_e32 v5, vcc, v5, v7, vcc
	v_sub_u32_e32 v7, v62, v5
	s_waitcnt lgkmcnt(0)
	v_add_f32_e32 v12, v12, v3
	v_ashrrev_i32_e32 v13, 31, v12
	v_bitop3_b32 v12, v13, v12, s2 bitop3:0x36
	v_and_or_b32 v7, v12, s96, v7
	s_nop 1
	v_max_u32_dpp v12, v7, v7 quad_perm:[1,0,3,2] row_mask:0xf bank_mask:0xf bound_ctrl:1
	s_nop 1
	v_max_u32_dpp v12, v12, v12 quad_perm:[2,3,0,1] row_mask:0xf bank_mask:0xf bound_ctrl:1
	s_nop 1
	v_max_u32_dpp v12, v12, v12 row_half_mirror row_mask:0xf bank_mask:0xf bound_ctrl:1
	s_nop 1
	v_max_u32_dpp v12, v12, v12 row_mirror row_mask:0xf bank_mask:0xf bound_ctrl:1
	v_cmp_eq_u32_e32 vcc, v7, v12
	v_cndmask_b32_e64 v8, v8, v12, s[30:31]
	s_nop 0
	v_cndmask_b32_e64 v7, 0, 1, vcc
	v_lshl_add_u32 v9, v7, 2, v9
	ds_read_b32 v12, v9
	v_addc_co_u32_e32 v10, vcc, v10, v11, vcc
	v_sub_u32_e32 v11, v62, v10
	s_waitcnt lgkmcnt(0)
	v_add_f32_e32 v12, v12, v3
	v_ashrrev_i32_e32 v13, 31, v12
	v_bitop3_b32 v12, v13, v12, s2 bitop3:0x36
	v_and_or_b32 v11, v12, s96, v11
	s_nop 1
	v_max_u32_dpp v12, v11, v11 quad_perm:[1,0,3,2] row_mask:0xf bank_mask:0xf bound_ctrl:1
	s_nop 1
	v_max_u32_dpp v12, v12, v12 quad_perm:[2,3,0,1] row_mask:0xf bank_mask:0xf bound_ctrl:1
	s_nop 1
	v_max_u32_dpp v12, v12, v12 row_half_mirror row_mask:0xf bank_mask:0xf bound_ctrl:1
	s_nop 1
	v_max_u32_dpp v12, v12, v12 row_mirror row_mask:0xf bank_mask:0xf bound_ctrl:1
	v_cmp_eq_u32_e32 vcc, v11, v12
	v_cndmask_b32_e64 v8, v8, v12, s[34:35]
	s_nop 0
	v_cndmask_b32_e64 v11, 0, 1, vcc
	v_lshl_add_u32 v9, v11, 2, v9
	ds_read_b32 v12, v9
	v_addc_co_u32_e32 v5, vcc, v5, v7, vcc
	v_sub_u32_e32 v7, v62, v5
	s_waitcnt lgkmcnt(0)
	v_add_f32_e32 v12, v12, v3
	v_ashrrev_i32_e32 v13, 31, v12
	v_bitop3_b32 v12, v13, v12, s2 bitop3:0x36
	v_and_or_b32 v7, v12, s96, v7
	s_nop 1
	v_max_u32_dpp v12, v7, v7 quad_perm:[1,0,3,2] row_mask:0xf bank_mask:0xf bound_ctrl:1
	s_nop 1
	v_max_u32_dpp v12, v12, v12 quad_perm:[2,3,0,1] row_mask:0xf bank_mask:0xf bound_ctrl:1
	s_nop 1
	v_max_u32_dpp v12, v12, v12 row_half_mirror row_mask:0xf bank_mask:0xf bound_ctrl:1
	s_nop 1
	v_max_u32_dpp v12, v12, v12 row_mirror row_mask:0xf bank_mask:0xf bound_ctrl:1
	v_cmp_eq_u32_e32 vcc, v7, v12
	v_cndmask_b32_e64 v8, v8, v12, s[36:37]
	s_nop 0
	v_cndmask_b32_e64 v7, 0, 1, vcc
	v_lshl_add_u32 v9, v7, 2, v9
	v_addc_co_u32_e32 v10, vcc, v10, v11, vcc
	ds_read_b32 v11, v9
	v_sub_u32_e32 v10, v62, v10
	s_waitcnt lgkmcnt(0)
	v_add_f32_e32 v11, v11, v3
	v_ashrrev_i32_e32 v12, 31, v11
	v_bitop3_b32 v11, v12, v11, s2 bitop3:0x36
	v_and_or_b32 v10, v11, s96, v10
	s_nop 1
	v_max_u32_dpp v11, v10, v10 quad_perm:[1,0,3,2] row_mask:0xf bank_mask:0xf bound_ctrl:1
	s_nop 1
	v_max_u32_dpp v11, v11, v11 quad_perm:[2,3,0,1] row_mask:0xf bank_mask:0xf bound_ctrl:1
	s_nop 1
	v_max_u32_dpp v11, v11, v11 row_half_mirror row_mask:0xf bank_mask:0xf bound_ctrl:1
	s_nop 1
	v_max_u32_dpp v11, v11, v11 row_mirror row_mask:0xf bank_mask:0xf bound_ctrl:1
	v_cmp_eq_u32_e32 vcc, v10, v11
	v_cndmask_b32_e64 v8, v8, v11, s[38:39]
	s_nop 0
	v_cndmask_b32_e64 v10, 0, 1, vcc
	v_addc_co_u32_e32 v5, vcc, v5, v7, vcc
	v_lshl_add_u32 v7, v10, 2, v9
	ds_read_b32 v7, v7
	v_sub_u32_e32 v5, v62, v5
	s_waitcnt lgkmcnt(0)
	v_add_f32_e32 v3, v7, v3
	v_ashrrev_i32_e32 v7, 31, v3
	v_bitop3_b32 v3, v7, v3, s2 bitop3:0x36
	v_and_or_b32 v3, v3, s96, v5
	s_nop 1
	v_max_u32_dpp v3, v3, v3 quad_perm:[1,0,3,2] row_mask:0xf bank_mask:0xf bound_ctrl:1
	s_nop 1
	v_max_u32_dpp v3, v3, v3 quad_perm:[2,3,0,1] row_mask:0xf bank_mask:0xf bound_ctrl:1
	s_nop 1
	v_max_u32_dpp v3, v3, v3 row_half_mirror row_mask:0xf bank_mask:0xf bound_ctrl:1
	s_nop 1
	v_max_u32_dpp v3, v3, v3 row_mirror row_mask:0xf bank_mask:0xf bound_ctrl:1
	v_cndmask_b32_e64 v3, v8, v3, s[40:41]
	v_cmp_lt_i32_e32 vcc, -1, v3
	v_not_b32_e32 v5, v3
	v_bitop3_b32 v8, v3, 15, v3 bitop3:0xc
	v_cndmask_b32_e64 v7, v77, -1, vcc
	v_bitop3_b32 v7, v7, v3, s96 bitop3:0x78
	v_max_u32_dpp v3, v3, v3 quad_perm:[1,0,3,2] row_mask:0xf bank_mask:0xf bound_ctrl:1
	v_lshrrev_b32_e32 v5, 2, v5
	v_and_b32_e32 v5, 60, v5
	v_max_u32_dpp v3, v3, v3 quad_perm:[2,3,0,1] row_mask:0xf bank_mask:0xf bound_ctrl:1
	v_add_u32_e32 v5, v59, v5
	v_lshl_add_u32 v8, v8, 2, v59
	v_max_u32_dpp v3, v3, v3 row_half_mirror row_mask:0xf bank_mask:0xf bound_ctrl:1
	ds_read_b32 v5, v5 offset:64
	ds_read_b32 v10, v8 offset:128
	v_max_u32_dpp v3, v3, v3 row_mirror row_mask:0xf bank_mask:0xf bound_ctrl:1
	v_cmp_lt_i32_e32 vcc, -1, v3
	s_waitcnt lgkmcnt(0)
	v_lshl_add_u32 v5, v5, 7, v10
	v_cndmask_b32_e64 v8, v77, -1, vcc
	v_bitop3_b32 v3, v8, v3, s96 bitop3:0x78
	v_sub_f32_e32 v3, v7, v3
	v_mul_f32_e32 v3, 0x3fb8aa3b, v3
	v_exp_f32_e32 v3, v3
	v_add_u32_e32 v8, 1, v2
	v_ashrrev_i32_e32 v9, 31, v8
	v_lshlrev_b64 v[8:9], 9, v[8:9]
	v_add_f32_dpp v7, v3, v3 quad_perm:[1,0,3,2] row_mask:0xf bank_mask:0xf bound_ctrl:1
	v_or_b32_e32 v8, v8, v78
	v_lshl_add_u64 v[10:11], s[52:53], 0, v[8:9]
	v_add_f32_dpp v7, v7, v7 quad_perm:[2,3,0,1] row_mask:0xf bank_mask:0xf bound_ctrl:1
	global_store_dword v[10:11], v5, off
	v_lshl_add_u64 v[8:9], s[58:59], 0, v[8:9]
	v_add_f32_dpp v7, v7, v7 row_half_mirror row_mask:0xf bank_mask:0xf bound_ctrl:1
	s_nop 1
	v_add_f32_dpp v7, v7, v7 row_mirror row_mask:0xf bank_mask:0xf bound_ctrl:1
	v_div_scale_f32 v5, s[46:47], v7, v7, v3
	v_rcp_f32_e32 v10, v5
	s_nop 0
	v_fma_f32 v11, -v5, v10, 1.0
	v_fmac_f32_e32 v10, v11, v10
	v_div_scale_f32 v11, vcc, v3, v7, v3
	v_mul_f32_e32 v12, v11, v10
	v_fma_f32 v13, -v5, v12, v11
	v_fmac_f32_e32 v12, v13, v10
	v_fma_f32 v5, -v5, v12, v11
	v_div_fmas_f32 v5, v5, v10, v12
	v_div_fixup_f32 v3, v5, v7, v3
	v_cmp_lt_i32_e32 vcc, -1, v80
	global_store_dword v[8:9], v3, off
	s_nop 0
	v_cndmask_b32_e64 v3, v77, -1, vcc
	v_cmp_lt_i32_e32 vcc, -1, v6
	v_bitop3_b32 v3, v3, v80, s55 bitop3:0x78
	s_nop 0
	v_cndmask_b32_e64 v5, v77, -1, vcc
	v_bitop3_b32 v5, v5, v6, s55 bitop3:0x78
	ds_write_b32 v61, v5
	v_bitop3_b32 v5, v80, s77, v80 bitop3:0xc
	ds_write_b32 v61, v5 offset:64
	v_bitop3_b32 v5, v6, s77, v6 bitop3:0xc
	ds_write_b32 v61, v5 offset:128
	ds_read_b32 v5, v59
	s_waitcnt lgkmcnt(0)
	v_add_f32_e32 v5, v5, v3
	v_ashrrev_i32_e32 v6, 31, v5
	v_bitop3_b32 v5, v6, v5, s2 bitop3:0x36
	v_and_or_b32 v5, v5, s96, v62
	s_nop 1
	v_max_u32_dpp v6, v5, v5 quad_perm:[1,0,3,2] row_mask:0xf bank_mask:0xf bound_ctrl:1
	s_nop 1
	v_max_u32_dpp v6, v6, v6 quad_perm:[2,3,0,1] row_mask:0xf bank_mask:0xf bound_ctrl:1
	s_nop 1
	v_max_u32_dpp v6, v6, v6 row_half_mirror row_mask:0xf bank_mask:0xf bound_ctrl:1
	s_nop 1
	v_max_u32_dpp v6, v6, v6 row_mirror row_mask:0xf bank_mask:0xf bound_ctrl:1
	v_cmp_eq_u32_e32 vcc, v5, v6
	v_cndmask_b32_e64 v7, 0, v6, s[8:9]
	s_nop 0
	v_cndmask_b32_e64 v5, 0, 1, vcc
	v_lshl_add_u32 v8, v5, 2, v59
	ds_read_b32 v9, v8
	v_subbrev_co_u32_e32 v6, vcc, 0, v62, vcc
	s_waitcnt lgkmcnt(0)
	v_add_f32_e32 v9, v9, v3
	v_ashrrev_i32_e32 v10, 31, v9
	v_bitop3_b32 v9, v10, v9, s2 bitop3:0x36
	v_and_or_b32 v6, v9, s96, v6
	s_nop 1
	v_max_u32_dpp v9, v6, v6 quad_perm:[1,0,3,2] row_mask:0xf bank_mask:0xf bound_ctrl:1
	s_nop 1
	v_max_u32_dpp v9, v9, v9 quad_perm:[2,3,0,1] row_mask:0xf bank_mask:0xf bound_ctrl:1
	s_nop 1
	v_max_u32_dpp v9, v9, v9 row_half_mirror row_mask:0xf bank_mask:0xf bound_ctrl:1
	s_nop 1
	v_max_u32_dpp v9, v9, v9 row_mirror row_mask:0xf bank_mask:0xf bound_ctrl:1
	v_cmp_eq_u32_e32 vcc, v6, v9
	v_cndmask_b32_e64 v7, v7, v9, s[10:11]
	s_nop 0
	v_cndmask_b32_e64 v6, 0, 1, vcc
	v_lshl_add_u32 v8, v6, 2, v8
	ds_read_b32 v11, v8
	v_addc_co_u32_e32 v9, vcc, 0, v5, vcc
	v_sub_u32_e32 v10, v62, v9
	s_waitcnt lgkmcnt(0)
	v_add_f32_e32 v11, v11, v3
	v_ashrrev_i32_e32 v12, 31, v11
	v_bitop3_b32 v11, v12, v11, s2 bitop3:0x36
	v_and_or_b32 v10, v11, s96, v10
	s_nop 1
	v_max_u32_dpp v11, v10, v10 quad_perm:[1,0,3,2] row_mask:0xf bank_mask:0xf bound_ctrl:1
	s_nop 1
	v_max_u32_dpp v11, v11, v11 quad_perm:[2,3,0,1] row_mask:0xf bank_mask:0xf bound_ctrl:1
	s_nop 1
	v_max_u32_dpp v11, v11, v11 row_half_mirror row_mask:0xf bank_mask:0xf bound_ctrl:1
	s_nop 1
	v_max_u32_dpp v11, v11, v11 row_mirror row_mask:0xf bank_mask:0xf bound_ctrl:1
	v_cmp_eq_u32_e32 vcc, v10, v11
	v_cndmask_b32_e64 v7, v7, v11, s[12:13]
	s_nop 0
	v_cndmask_b32_e64 v10, 0, 1, vcc
	v_lshl_add_u32 v8, v10, 2, v8
	ds_read_b32 v11, v8
	v_addc_co_u32_e32 v5, vcc, v6, v5, vcc
	v_sub_u32_e32 v6, v62, v5
	s_waitcnt lgkmcnt(0)
	v_add_f32_e32 v11, v11, v3
	v_ashrrev_i32_e32 v12, 31, v11
	v_bitop3_b32 v11, v12, v11, s2 bitop3:0x36
	v_and_or_b32 v6, v11, s96, v6
	s_nop 1
	v_max_u32_dpp v11, v6, v6 quad_perm:[1,0,3,2] row_mask:0xf bank_mask:0xf bound_ctrl:1
	s_nop 1
	v_max_u32_dpp v11, v11, v11 quad_perm:[2,3,0,1] row_mask:0xf bank_mask:0xf bound_ctrl:1
	s_nop 1
	v_max_u32_dpp v11, v11, v11 row_half_mirror row_mask:0xf bank_mask:0xf bound_ctrl:1
	s_nop 1
	v_max_u32_dpp v11, v11, v11 row_mirror row_mask:0xf bank_mask:0xf bound_ctrl:1
	v_cmp_eq_u32_e32 vcc, v6, v11
	v_cndmask_b32_e64 v7, v7, v11, s[14:15]
	s_nop 0
	v_cndmask_b32_e64 v6, 0, 1, vcc
	v_lshl_add_u32 v8, v6, 2, v8
	ds_read_b32 v11, v8
	v_addc_co_u32_e32 v9, vcc, v9, v10, vcc
	v_sub_u32_e32 v10, v62, v9
	s_waitcnt lgkmcnt(0)
	v_add_f32_e32 v11, v11, v3
	v_ashrrev_i32_e32 v12, 31, v11
	v_bitop3_b32 v11, v12, v11, s2 bitop3:0x36
	v_and_or_b32 v10, v11, s96, v10
	s_nop 1
	v_max_u32_dpp v11, v10, v10 quad_perm:[1,0,3,2] row_mask:0xf bank_mask:0xf bound_ctrl:1
	s_nop 1
	v_max_u32_dpp v11, v11, v11 quad_perm:[2,3,0,1] row_mask:0xf bank_mask:0xf bound_ctrl:1
	s_nop 1
	v_max_u32_dpp v11, v11, v11 row_half_mirror row_mask:0xf bank_mask:0xf bound_ctrl:1
	s_nop 1
	v_max_u32_dpp v11, v11, v11 row_mirror row_mask:0xf bank_mask:0xf bound_ctrl:1
	v_cmp_eq_u32_e32 vcc, v10, v11
	v_cndmask_b32_e64 v7, v7, v11, s[16:17]
	s_nop 0
	v_cndmask_b32_e64 v10, 0, 1, vcc
	v_lshl_add_u32 v8, v10, 2, v8
	ds_read_b32 v11, v8
	v_addc_co_u32_e32 v5, vcc, v5, v6, vcc
	v_sub_u32_e32 v6, v62, v5
	s_waitcnt lgkmcnt(0)
	v_add_f32_e32 v11, v11, v3
	v_ashrrev_i32_e32 v12, 31, v11
	v_bitop3_b32 v11, v12, v11, s2 bitop3:0x36
	v_and_or_b32 v6, v11, s96, v6
	s_nop 1
	v_max_u32_dpp v11, v6, v6 quad_perm:[1,0,3,2] row_mask:0xf bank_mask:0xf bound_ctrl:1
	s_nop 1
	v_max_u32_dpp v11, v11, v11 quad_perm:[2,3,0,1] row_mask:0xf bank_mask:0xf bound_ctrl:1
	s_nop 1
	v_max_u32_dpp v11, v11, v11 row_half_mirror row_mask:0xf bank_mask:0xf bound_ctrl:1
	s_nop 1
	v_max_u32_dpp v11, v11, v11 row_mirror row_mask:0xf bank_mask:0xf bound_ctrl:1
	v_cmp_eq_u32_e32 vcc, v6, v11
	v_cndmask_b32_e64 v7, v7, v11, s[18:19]
	s_nop 0
	v_cndmask_b32_e64 v6, 0, 1, vcc
	v_lshl_add_u32 v8, v6, 2, v8
	ds_read_b32 v11, v8
	v_addc_co_u32_e32 v9, vcc, v9, v10, vcc
	v_sub_u32_e32 v10, v62, v9
	s_waitcnt lgkmcnt(0)
	v_add_f32_e32 v11, v11, v3
	v_ashrrev_i32_e32 v12, 31, v11
	v_bitop3_b32 v11, v12, v11, s2 bitop3:0x36
	v_and_or_b32 v10, v11, s96, v10
	s_nop 1
	v_max_u32_dpp v11, v10, v10 quad_perm:[1,0,3,2] row_mask:0xf bank_mask:0xf bound_ctrl:1
	s_nop 1
	v_max_u32_dpp v11, v11, v11 quad_perm:[2,3,0,1] row_mask:0xf bank_mask:0xf bound_ctrl:1
	s_nop 1
	v_max_u32_dpp v11, v11, v11 row_half_mirror row_mask:0xf bank_mask:0xf bound_ctrl:1
	s_nop 1
	v_max_u32_dpp v11, v11, v11 row_mirror row_mask:0xf bank_mask:0xf bound_ctrl:1
	v_cmp_eq_u32_e32 vcc, v10, v11
	v_cndmask_b32_e64 v7, v7, v11, s[20:21]
	s_nop 0
	v_cndmask_b32_e64 v10, 0, 1, vcc
	v_lshl_add_u32 v8, v10, 2, v8
	ds_read_b32 v11, v8
	v_addc_co_u32_e32 v5, vcc, v5, v6, vcc
	v_sub_u32_e32 v6, v62, v5
	s_waitcnt lgkmcnt(0)
	v_add_f32_e32 v11, v11, v3
	v_ashrrev_i32_e32 v12, 31, v11
	v_bitop3_b32 v11, v12, v11, s2 bitop3:0x36
	v_and_or_b32 v6, v11, s96, v6
	s_nop 1
	v_max_u32_dpp v11, v6, v6 quad_perm:[1,0,3,2] row_mask:0xf bank_mask:0xf bound_ctrl:1
	s_nop 1
	v_max_u32_dpp v11, v11, v11 quad_perm:[2,3,0,1] row_mask:0xf bank_mask:0xf bound_ctrl:1
	s_nop 1
	v_max_u32_dpp v11, v11, v11 row_half_mirror row_mask:0xf bank_mask:0xf bound_ctrl:1
	s_nop 1
	v_max_u32_dpp v11, v11, v11 row_mirror row_mask:0xf bank_mask:0xf bound_ctrl:1
	v_cmp_eq_u32_e32 vcc, v6, v11
	v_cndmask_b32_e64 v7, v7, v11, s[22:23]
	s_nop 0
	v_cndmask_b32_e64 v6, 0, 1, vcc
	v_lshl_add_u32 v8, v6, 2, v8
	ds_read_b32 v11, v8
	v_addc_co_u32_e32 v9, vcc, v9, v10, vcc
	v_sub_u32_e32 v10, v62, v9
	s_waitcnt lgkmcnt(0)
	v_add_f32_e32 v11, v11, v3
	v_ashrrev_i32_e32 v12, 31, v11
	v_bitop3_b32 v11, v12, v11, s2 bitop3:0x36
	v_and_or_b32 v10, v11, s96, v10
	s_nop 1
	v_max_u32_dpp v11, v10, v10 quad_perm:[1,0,3,2] row_mask:0xf bank_mask:0xf bound_ctrl:1
	s_nop 1
	v_max_u32_dpp v11, v11, v11 quad_perm:[2,3,0,1] row_mask:0xf bank_mask:0xf bound_ctrl:1
	s_nop 1
	v_max_u32_dpp v11, v11, v11 row_half_mirror row_mask:0xf bank_mask:0xf bound_ctrl:1
	s_nop 1
	v_max_u32_dpp v11, v11, v11 row_mirror row_mask:0xf bank_mask:0xf bound_ctrl:1
	v_cmp_eq_u32_e32 vcc, v10, v11
	v_cndmask_b32_e64 v7, v7, v11, s[24:25]
	s_nop 0
	v_cndmask_b32_e64 v10, 0, 1, vcc
	v_lshl_add_u32 v8, v10, 2, v8
	ds_read_b32 v11, v8
	v_addc_co_u32_e32 v5, vcc, v5, v6, vcc
	v_sub_u32_e32 v6, v62, v5
	s_waitcnt lgkmcnt(0)
	v_add_f32_e32 v11, v11, v3
	v_ashrrev_i32_e32 v12, 31, v11
	v_bitop3_b32 v11, v12, v11, s2 bitop3:0x36
	v_and_or_b32 v6, v11, s96, v6
	s_nop 1
	v_max_u32_dpp v11, v6, v6 quad_perm:[1,0,3,2] row_mask:0xf bank_mask:0xf bound_ctrl:1
	s_nop 1
	v_max_u32_dpp v11, v11, v11 quad_perm:[2,3,0,1] row_mask:0xf bank_mask:0xf bound_ctrl:1
	s_nop 1
	v_max_u32_dpp v11, v11, v11 row_half_mirror row_mask:0xf bank_mask:0xf bound_ctrl:1
	s_nop 1
	v_max_u32_dpp v11, v11, v11 row_mirror row_mask:0xf bank_mask:0xf bound_ctrl:1
	v_cmp_eq_u32_e32 vcc, v6, v11
	v_cndmask_b32_e64 v7, v7, v11, s[26:27]
	s_nop 0
	v_cndmask_b32_e64 v6, 0, 1, vcc
	v_lshl_add_u32 v8, v6, 2, v8
	ds_read_b32 v11, v8
	v_addc_co_u32_e32 v9, vcc, v9, v10, vcc
	v_sub_u32_e32 v10, v62, v9
	s_waitcnt lgkmcnt(0)
	v_add_f32_e32 v11, v11, v3
	v_ashrrev_i32_e32 v12, 31, v11
	v_bitop3_b32 v11, v12, v11, s2 bitop3:0x36
	v_and_or_b32 v10, v11, s96, v10
	s_nop 1
	v_max_u32_dpp v11, v10, v10 quad_perm:[1,0,3,2] row_mask:0xf bank_mask:0xf bound_ctrl:1
	s_nop 1
	v_max_u32_dpp v11, v11, v11 quad_perm:[2,3,0,1] row_mask:0xf bank_mask:0xf bound_ctrl:1
	s_nop 1
	v_max_u32_dpp v11, v11, v11 row_half_mirror row_mask:0xf bank_mask:0xf bound_ctrl:1
	s_nop 1
	v_max_u32_dpp v11, v11, v11 row_mirror row_mask:0xf bank_mask:0xf bound_ctrl:1
	v_cmp_eq_u32_e32 vcc, v10, v11
	v_cndmask_b32_e64 v7, v7, v11, s[28:29]
	s_nop 0
	v_cndmask_b32_e64 v10, 0, 1, vcc
	v_lshl_add_u32 v8, v10, 2, v8
	ds_read_b32 v11, v8
	v_addc_co_u32_e32 v5, vcc, v5, v6, vcc
	v_sub_u32_e32 v6, v62, v5
	s_waitcnt lgkmcnt(0)
	v_add_f32_e32 v11, v11, v3
	v_ashrrev_i32_e32 v12, 31, v11
	v_bitop3_b32 v11, v12, v11, s2 bitop3:0x36
	v_and_or_b32 v6, v11, s96, v6
	s_nop 1
	v_max_u32_dpp v11, v6, v6 quad_perm:[1,0,3,2] row_mask:0xf bank_mask:0xf bound_ctrl:1
	s_nop 1
	v_max_u32_dpp v11, v11, v11 quad_perm:[2,3,0,1] row_mask:0xf bank_mask:0xf bound_ctrl:1
	s_nop 1
	v_max_u32_dpp v11, v11, v11 row_half_mirror row_mask:0xf bank_mask:0xf bound_ctrl:1
	s_nop 1
	v_max_u32_dpp v11, v11, v11 row_mirror row_mask:0xf bank_mask:0xf bound_ctrl:1
	v_cmp_eq_u32_e32 vcc, v6, v11
	v_cndmask_b32_e64 v7, v7, v11, s[30:31]
	s_nop 0
	v_cndmask_b32_e64 v6, 0, 1, vcc
	v_lshl_add_u32 v8, v6, 2, v8
	ds_read_b32 v11, v8
	v_addc_co_u32_e32 v9, vcc, v9, v10, vcc
	v_sub_u32_e32 v10, v62, v9
	s_waitcnt lgkmcnt(0)
	v_add_f32_e32 v11, v11, v3
	v_ashrrev_i32_e32 v12, 31, v11
	v_bitop3_b32 v11, v12, v11, s2 bitop3:0x36
	v_and_or_b32 v10, v11, s96, v10
	s_nop 1
	v_max_u32_dpp v11, v10, v10 quad_perm:[1,0,3,2] row_mask:0xf bank_mask:0xf bound_ctrl:1
	s_nop 1
	v_max_u32_dpp v11, v11, v11 quad_perm:[2,3,0,1] row_mask:0xf bank_mask:0xf bound_ctrl:1
	s_nop 1
	v_max_u32_dpp v11, v11, v11 row_half_mirror row_mask:0xf bank_mask:0xf bound_ctrl:1
	s_nop 1
	v_max_u32_dpp v11, v11, v11 row_mirror row_mask:0xf bank_mask:0xf bound_ctrl:1
	v_cmp_eq_u32_e32 vcc, v10, v11
	v_cndmask_b32_e64 v7, v7, v11, s[34:35]
	s_nop 0
	v_cndmask_b32_e64 v10, 0, 1, vcc
	v_lshl_add_u32 v8, v10, 2, v8
	ds_read_b32 v11, v8
	v_addc_co_u32_e32 v5, vcc, v5, v6, vcc
	v_sub_u32_e32 v6, v62, v5
	s_waitcnt lgkmcnt(0)
	v_add_f32_e32 v11, v11, v3
	v_ashrrev_i32_e32 v12, 31, v11
	v_bitop3_b32 v11, v12, v11, s2 bitop3:0x36
	v_and_or_b32 v6, v11, s96, v6
	s_nop 1
	v_max_u32_dpp v11, v6, v6 quad_perm:[1,0,3,2] row_mask:0xf bank_mask:0xf bound_ctrl:1
	s_nop 1
	v_max_u32_dpp v11, v11, v11 quad_perm:[2,3,0,1] row_mask:0xf bank_mask:0xf bound_ctrl:1
	s_nop 1
	v_max_u32_dpp v11, v11, v11 row_half_mirror row_mask:0xf bank_mask:0xf bound_ctrl:1
	s_nop 1
	v_max_u32_dpp v11, v11, v11 row_mirror row_mask:0xf bank_mask:0xf bound_ctrl:1
	v_cmp_eq_u32_e32 vcc, v6, v11
	v_cndmask_b32_e64 v7, v7, v11, s[36:37]
	s_nop 0
	v_cndmask_b32_e64 v6, 0, 1, vcc
	v_lshl_add_u32 v8, v6, 2, v8
	v_addc_co_u32_e32 v9, vcc, v9, v10, vcc
	ds_read_b32 v10, v8
	v_sub_u32_e32 v9, v62, v9
	s_waitcnt lgkmcnt(0)
	v_add_f32_e32 v10, v10, v3
	v_ashrrev_i32_e32 v11, 31, v10
	v_bitop3_b32 v10, v11, v10, s2 bitop3:0x36
	v_and_or_b32 v9, v10, s96, v9
	s_nop 1
	v_max_u32_dpp v10, v9, v9 quad_perm:[1,0,3,2] row_mask:0xf bank_mask:0xf bound_ctrl:1
	s_nop 1
	v_max_u32_dpp v10, v10, v10 quad_perm:[2,3,0,1] row_mask:0xf bank_mask:0xf bound_ctrl:1
	s_nop 1
	v_max_u32_dpp v10, v10, v10 row_half_mirror row_mask:0xf bank_mask:0xf bound_ctrl:1
	s_nop 1
	v_max_u32_dpp v10, v10, v10 row_mirror row_mask:0xf bank_mask:0xf bound_ctrl:1
	v_cmp_eq_u32_e32 vcc, v9, v10
	v_cndmask_b32_e64 v7, v7, v10, s[38:39]
	s_nop 0
	v_cndmask_b32_e64 v9, 0, 1, vcc
	v_addc_co_u32_e32 v5, vcc, v5, v6, vcc
	v_lshl_add_u32 v6, v9, 2, v8
	ds_read_b32 v6, v6
	v_sub_u32_e32 v5, v62, v5
	s_waitcnt lgkmcnt(0)
	v_add_f32_e32 v3, v6, v3
	v_ashrrev_i32_e32 v6, 31, v3
	v_bitop3_b32 v3, v6, v3, s2 bitop3:0x36
	v_and_or_b32 v3, v3, s96, v5
	s_nop 1
	v_max_u32_dpp v3, v3, v3 quad_perm:[1,0,3,2] row_mask:0xf bank_mask:0xf bound_ctrl:1
	s_nop 1
	v_max_u32_dpp v3, v3, v3 quad_perm:[2,3,0,1] row_mask:0xf bank_mask:0xf bound_ctrl:1
	s_nop 1
	v_max_u32_dpp v3, v3, v3 row_half_mirror row_mask:0xf bank_mask:0xf bound_ctrl:1
	s_nop 1
	v_max_u32_dpp v3, v3, v3 row_mirror row_mask:0xf bank_mask:0xf bound_ctrl:1
	v_cndmask_b32_e64 v3, v7, v3, s[40:41]
	v_cmp_lt_i32_e32 vcc, -1, v3
	v_not_b32_e32 v5, v3
	v_bitop3_b32 v7, v3, 15, v3 bitop3:0xc
	v_cndmask_b32_e64 v6, v77, -1, vcc
	v_bitop3_b32 v6, v6, v3, s96 bitop3:0x78
	v_max_u32_dpp v3, v3, v3 quad_perm:[1,0,3,2] row_mask:0xf bank_mask:0xf bound_ctrl:1
	v_lshrrev_b32_e32 v5, 2, v5
	v_and_b32_e32 v5, 60, v5
	v_max_u32_dpp v3, v3, v3 quad_perm:[2,3,0,1] row_mask:0xf bank_mask:0xf bound_ctrl:1
	v_add_u32_e32 v5, v59, v5
	v_lshl_add_u32 v7, v7, 2, v59
	v_max_u32_dpp v3, v3, v3 row_half_mirror row_mask:0xf bank_mask:0xf bound_ctrl:1
	ds_read_b32 v5, v5 offset:64
	ds_read_b32 v8, v7 offset:128
	v_max_u32_dpp v3, v3, v3 row_mirror row_mask:0xf bank_mask:0xf bound_ctrl:1
	v_cmp_lt_i32_e32 vcc, -1, v3
	s_waitcnt lgkmcnt(0)
	v_lshl_add_u32 v5, v5, 7, v8
	v_cndmask_b32_e64 v7, v77, -1, vcc
	v_bitop3_b32 v3, v7, v3, s96 bitop3:0x78
	v_sub_f32_e32 v3, v6, v3
	v_mul_f32_e32 v3, 0x3fb8aa3b, v3
	v_exp_f32_e32 v3, v3
	s_nop 1
	v_add_f32_dpp v6, v3, v3 quad_perm:[1,0,3,2] row_mask:0xf bank_mask:0xf bound_ctrl:1
	s_nop 1
	v_add_f32_dpp v6, v6, v6 quad_perm:[2,3,0,1] row_mask:0xf bank_mask:0xf bound_ctrl:1
	s_nop 1
	v_add_f32_dpp v6, v6, v6 row_half_mirror row_mask:0xf bank_mask:0xf bound_ctrl:1
	s_nop 1
	v_add_f32_dpp v10, v6, v6 row_mirror row_mask:0xf bank_mask:0xf bound_ctrl:1
	v_add_u32_e32 v6, 2, v2
	v_ashrrev_i32_e32 v7, 31, v6
	v_lshlrev_b64 v[6:7], 9, v[6:7]
	v_or_b32_e32 v6, v6, v78
	v_lshl_add_u64 v[8:9], s[52:53], 0, v[6:7]
	global_store_dword v[8:9], v5, off
	v_div_scale_f32 v5, s[46:47], v10, v10, v3
	v_rcp_f32_e32 v8, v5
	v_lshl_add_u64 v[6:7], s[58:59], 0, v[6:7]
	v_add_u32_e32 v2, 3, v2
	v_fma_f32 v9, -v5, v8, 1.0
	v_fmac_f32_e32 v8, v9, v8
	v_div_scale_f32 v9, vcc, v3, v10, v3
	v_mul_f32_e32 v11, v9, v8
	v_fma_f32 v12, -v5, v11, v9
	v_fmac_f32_e32 v11, v12, v8
	v_fma_f32 v5, -v5, v11, v9
	v_div_fmas_f32 v5, v5, v8, v11
	v_div_fixup_f32 v3, v5, v10, v3
	v_cmp_lt_i32_e32 vcc, -1, v79
	global_store_dword v[6:7], v3, off
	s_nop 0
	v_cndmask_b32_e64 v3, v77, -1, vcc
	v_cmp_lt_i32_e32 vcc, -1, v4
	v_bitop3_b32 v3, v3, v79, s55 bitop3:0x78
	s_nop 0
	v_cndmask_b32_e64 v5, v77, -1, vcc
	v_bitop3_b32 v5, v5, v4, s55 bitop3:0x78
	ds_write_b32 v61, v5
	v_bitop3_b32 v4, v4, s77, v4 bitop3:0xc
	ds_write_b32 v61, v4 offset:128
	ds_read_b32 v4, v59
	v_bitop3_b32 v5, v79, s77, v79 bitop3:0xc
	ds_write_b32 v61, v5 offset:64
	s_waitcnt lgkmcnt(1)
	v_add_f32_e32 v4, v4, v3
	v_ashrrev_i32_e32 v5, 31, v4
	v_bitop3_b32 v4, v5, v4, s2 bitop3:0x36
	v_and_or_b32 v4, v4, s96, v62
	s_nop 1
	v_max_u32_dpp v5, v4, v4 quad_perm:[1,0,3,2] row_mask:0xf bank_mask:0xf bound_ctrl:1
	s_nop 1
	v_max_u32_dpp v5, v5, v5 quad_perm:[2,3,0,1] row_mask:0xf bank_mask:0xf bound_ctrl:1
	s_nop 1
	v_max_u32_dpp v5, v5, v5 row_half_mirror row_mask:0xf bank_mask:0xf bound_ctrl:1
	s_nop 1
	v_max_u32_dpp v5, v5, v5 row_mirror row_mask:0xf bank_mask:0xf bound_ctrl:1
	v_cmp_eq_u32_e32 vcc, v4, v5
	v_cndmask_b32_e64 v6, 0, v5, s[8:9]
	s_nop 0
	v_cndmask_b32_e64 v4, 0, 1, vcc
	v_lshl_add_u32 v7, v4, 2, v59
	ds_read_b32 v8, v7
	v_subbrev_co_u32_e32 v5, vcc, 0, v62, vcc
	s_waitcnt lgkmcnt(0)
	v_add_f32_e32 v8, v8, v3
	v_ashrrev_i32_e32 v9, 31, v8
	v_bitop3_b32 v8, v9, v8, s2 bitop3:0x36
	v_and_or_b32 v5, v8, s96, v5
	s_nop 1
	v_max_u32_dpp v8, v5, v5 quad_perm:[1,0,3,2] row_mask:0xf bank_mask:0xf bound_ctrl:1
	s_nop 1
	v_max_u32_dpp v8, v8, v8 quad_perm:[2,3,0,1] row_mask:0xf bank_mask:0xf bound_ctrl:1
	s_nop 1
	v_max_u32_dpp v8, v8, v8 row_half_mirror row_mask:0xf bank_mask:0xf bound_ctrl:1
	s_nop 1
	v_max_u32_dpp v8, v8, v8 row_mirror row_mask:0xf bank_mask:0xf bound_ctrl:1
	v_cmp_eq_u32_e32 vcc, v5, v8
	v_cndmask_b32_e64 v6, v6, v8, s[10:11]
	s_nop 0
	v_cndmask_b32_e64 v5, 0, 1, vcc
	v_lshl_add_u32 v7, v5, 2, v7
	ds_read_b32 v10, v7
	v_addc_co_u32_e32 v8, vcc, 0, v4, vcc
	v_sub_u32_e32 v9, v62, v8
	s_waitcnt lgkmcnt(0)
	v_add_f32_e32 v10, v10, v3
	v_ashrrev_i32_e32 v11, 31, v10
	v_bitop3_b32 v10, v11, v10, s2 bitop3:0x36
	v_and_or_b32 v9, v10, s96, v9
	s_nop 1
	v_max_u32_dpp v10, v9, v9 quad_perm:[1,0,3,2] row_mask:0xf bank_mask:0xf bound_ctrl:1
	s_nop 1
	v_max_u32_dpp v10, v10, v10 quad_perm:[2,3,0,1] row_mask:0xf bank_mask:0xf bound_ctrl:1
	s_nop 1
	v_max_u32_dpp v10, v10, v10 row_half_mirror row_mask:0xf bank_mask:0xf bound_ctrl:1
	s_nop 1
	v_max_u32_dpp v10, v10, v10 row_mirror row_mask:0xf bank_mask:0xf bound_ctrl:1
	v_cmp_eq_u32_e32 vcc, v9, v10
	v_cndmask_b32_e64 v6, v6, v10, s[12:13]
	s_nop 0
	v_cndmask_b32_e64 v9, 0, 1, vcc
	v_lshl_add_u32 v7, v9, 2, v7
	ds_read_b32 v10, v7
	v_addc_co_u32_e32 v4, vcc, v5, v4, vcc
	v_sub_u32_e32 v5, v62, v4
	s_waitcnt lgkmcnt(0)
	v_add_f32_e32 v10, v10, v3
	v_ashrrev_i32_e32 v11, 31, v10
	v_bitop3_b32 v10, v11, v10, s2 bitop3:0x36
	v_and_or_b32 v5, v10, s96, v5
	s_nop 1
	v_max_u32_dpp v10, v5, v5 quad_perm:[1,0,3,2] row_mask:0xf bank_mask:0xf bound_ctrl:1
	s_nop 1
	v_max_u32_dpp v10, v10, v10 quad_perm:[2,3,0,1] row_mask:0xf bank_mask:0xf bound_ctrl:1
	s_nop 1
	v_max_u32_dpp v10, v10, v10 row_half_mirror row_mask:0xf bank_mask:0xf bound_ctrl:1
	s_nop 1
	v_max_u32_dpp v10, v10, v10 row_mirror row_mask:0xf bank_mask:0xf bound_ctrl:1
	v_cmp_eq_u32_e32 vcc, v5, v10
	v_cndmask_b32_e64 v6, v6, v10, s[14:15]
	s_nop 0
	v_cndmask_b32_e64 v5, 0, 1, vcc
	v_lshl_add_u32 v7, v5, 2, v7
	ds_read_b32 v10, v7
	v_addc_co_u32_e32 v8, vcc, v8, v9, vcc
	v_sub_u32_e32 v9, v62, v8
	s_waitcnt lgkmcnt(0)
	v_add_f32_e32 v10, v10, v3
	v_ashrrev_i32_e32 v11, 31, v10
	v_bitop3_b32 v10, v11, v10, s2 bitop3:0x36
	v_and_or_b32 v9, v10, s96, v9
	s_nop 1
	v_max_u32_dpp v10, v9, v9 quad_perm:[1,0,3,2] row_mask:0xf bank_mask:0xf bound_ctrl:1
	s_nop 1
	v_max_u32_dpp v10, v10, v10 quad_perm:[2,3,0,1] row_mask:0xf bank_mask:0xf bound_ctrl:1
	s_nop 1
	v_max_u32_dpp v10, v10, v10 row_half_mirror row_mask:0xf bank_mask:0xf bound_ctrl:1
	s_nop 1
	v_max_u32_dpp v10, v10, v10 row_mirror row_mask:0xf bank_mask:0xf bound_ctrl:1
	v_cmp_eq_u32_e32 vcc, v9, v10
	v_cndmask_b32_e64 v6, v6, v10, s[16:17]
	s_nop 0
	v_cndmask_b32_e64 v9, 0, 1, vcc
	v_lshl_add_u32 v7, v9, 2, v7
	ds_read_b32 v10, v7
	v_addc_co_u32_e32 v4, vcc, v4, v5, vcc
	v_sub_u32_e32 v5, v62, v4
	s_waitcnt lgkmcnt(0)
	v_add_f32_e32 v10, v10, v3
	v_ashrrev_i32_e32 v11, 31, v10
	v_bitop3_b32 v10, v11, v10, s2 bitop3:0x36
	v_and_or_b32 v5, v10, s96, v5
	s_nop 1
	v_max_u32_dpp v10, v5, v5 quad_perm:[1,0,3,2] row_mask:0xf bank_mask:0xf bound_ctrl:1
	s_nop 1
	v_max_u32_dpp v10, v10, v10 quad_perm:[2,3,0,1] row_mask:0xf bank_mask:0xf bound_ctrl:1
	s_nop 1
	v_max_u32_dpp v10, v10, v10 row_half_mirror row_mask:0xf bank_mask:0xf bound_ctrl:1
	s_nop 1
	v_max_u32_dpp v10, v10, v10 row_mirror row_mask:0xf bank_mask:0xf bound_ctrl:1
	v_cmp_eq_u32_e32 vcc, v5, v10
	v_cndmask_b32_e64 v6, v6, v10, s[18:19]
	s_nop 0
	v_cndmask_b32_e64 v5, 0, 1, vcc
	v_lshl_add_u32 v7, v5, 2, v7
	ds_read_b32 v10, v7
	v_addc_co_u32_e32 v8, vcc, v8, v9, vcc
	v_sub_u32_e32 v9, v62, v8
	s_waitcnt lgkmcnt(0)
	v_add_f32_e32 v10, v10, v3
	v_ashrrev_i32_e32 v11, 31, v10
	v_bitop3_b32 v10, v11, v10, s2 bitop3:0x36
	v_and_or_b32 v9, v10, s96, v9
	s_nop 1
	v_max_u32_dpp v10, v9, v9 quad_perm:[1,0,3,2] row_mask:0xf bank_mask:0xf bound_ctrl:1
	s_nop 1
	v_max_u32_dpp v10, v10, v10 quad_perm:[2,3,0,1] row_mask:0xf bank_mask:0xf bound_ctrl:1
	s_nop 1
	v_max_u32_dpp v10, v10, v10 row_half_mirror row_mask:0xf bank_mask:0xf bound_ctrl:1
	s_nop 1
	v_max_u32_dpp v10, v10, v10 row_mirror row_mask:0xf bank_mask:0xf bound_ctrl:1
	v_cmp_eq_u32_e32 vcc, v9, v10
	v_cndmask_b32_e64 v6, v6, v10, s[20:21]
	s_nop 0
	v_cndmask_b32_e64 v9, 0, 1, vcc
	v_lshl_add_u32 v7, v9, 2, v7
	ds_read_b32 v10, v7
	v_addc_co_u32_e32 v4, vcc, v4, v5, vcc
	v_sub_u32_e32 v5, v62, v4
	s_waitcnt lgkmcnt(0)
	v_add_f32_e32 v10, v10, v3
	v_ashrrev_i32_e32 v11, 31, v10
	v_bitop3_b32 v10, v11, v10, s2 bitop3:0x36
	v_and_or_b32 v5, v10, s96, v5
	s_nop 1
	v_max_u32_dpp v10, v5, v5 quad_perm:[1,0,3,2] row_mask:0xf bank_mask:0xf bound_ctrl:1
	s_nop 1
	v_max_u32_dpp v10, v10, v10 quad_perm:[2,3,0,1] row_mask:0xf bank_mask:0xf bound_ctrl:1
	s_nop 1
	v_max_u32_dpp v10, v10, v10 row_half_mirror row_mask:0xf bank_mask:0xf bound_ctrl:1
	s_nop 1
	v_max_u32_dpp v10, v10, v10 row_mirror row_mask:0xf bank_mask:0xf bound_ctrl:1
	v_cmp_eq_u32_e32 vcc, v5, v10
	v_cndmask_b32_e64 v6, v6, v10, s[22:23]
	s_nop 0
	v_cndmask_b32_e64 v5, 0, 1, vcc
	v_lshl_add_u32 v7, v5, 2, v7
	ds_read_b32 v10, v7
	v_addc_co_u32_e32 v8, vcc, v8, v9, vcc
	v_sub_u32_e32 v9, v62, v8
	s_waitcnt lgkmcnt(0)
	v_add_f32_e32 v10, v10, v3
	v_ashrrev_i32_e32 v11, 31, v10
	v_bitop3_b32 v10, v11, v10, s2 bitop3:0x36
	v_and_or_b32 v9, v10, s96, v9
	s_nop 1
	v_max_u32_dpp v10, v9, v9 quad_perm:[1,0,3,2] row_mask:0xf bank_mask:0xf bound_ctrl:1
	s_nop 1
	v_max_u32_dpp v10, v10, v10 quad_perm:[2,3,0,1] row_mask:0xf bank_mask:0xf bound_ctrl:1
	s_nop 1
	v_max_u32_dpp v10, v10, v10 row_half_mirror row_mask:0xf bank_mask:0xf bound_ctrl:1
	s_nop 1
	v_max_u32_dpp v10, v10, v10 row_mirror row_mask:0xf bank_mask:0xf bound_ctrl:1
	v_cmp_eq_u32_e32 vcc, v9, v10
	v_cndmask_b32_e64 v6, v6, v10, s[24:25]
	s_nop 0
	v_cndmask_b32_e64 v9, 0, 1, vcc
	v_lshl_add_u32 v7, v9, 2, v7
	ds_read_b32 v10, v7
	v_addc_co_u32_e32 v4, vcc, v4, v5, vcc
	v_sub_u32_e32 v5, v62, v4
	s_waitcnt lgkmcnt(0)
	v_add_f32_e32 v10, v10, v3
	v_ashrrev_i32_e32 v11, 31, v10
	v_bitop3_b32 v10, v11, v10, s2 bitop3:0x36
	v_and_or_b32 v5, v10, s96, v5
	s_nop 1
	v_max_u32_dpp v10, v5, v5 quad_perm:[1,0,3,2] row_mask:0xf bank_mask:0xf bound_ctrl:1
	s_nop 1
	v_max_u32_dpp v10, v10, v10 quad_perm:[2,3,0,1] row_mask:0xf bank_mask:0xf bound_ctrl:1
	s_nop 1
	v_max_u32_dpp v10, v10, v10 row_half_mirror row_mask:0xf bank_mask:0xf bound_ctrl:1
	s_nop 1
	v_max_u32_dpp v10, v10, v10 row_mirror row_mask:0xf bank_mask:0xf bound_ctrl:1
	v_cmp_eq_u32_e32 vcc, v5, v10
	v_cndmask_b32_e64 v6, v6, v10, s[26:27]
	s_nop 0
	v_cndmask_b32_e64 v5, 0, 1, vcc
	v_lshl_add_u32 v7, v5, 2, v7
	ds_read_b32 v10, v7
	v_addc_co_u32_e32 v8, vcc, v8, v9, vcc
	v_sub_u32_e32 v9, v62, v8
	s_waitcnt lgkmcnt(0)
	v_add_f32_e32 v10, v10, v3
	v_ashrrev_i32_e32 v11, 31, v10
	v_bitop3_b32 v10, v11, v10, s2 bitop3:0x36
	v_and_or_b32 v9, v10, s96, v9
	s_nop 1
	v_max_u32_dpp v10, v9, v9 quad_perm:[1,0,3,2] row_mask:0xf bank_mask:0xf bound_ctrl:1
	s_nop 1
	v_max_u32_dpp v10, v10, v10 quad_perm:[2,3,0,1] row_mask:0xf bank_mask:0xf bound_ctrl:1
	s_nop 1
	v_max_u32_dpp v10, v10, v10 row_half_mirror row_mask:0xf bank_mask:0xf bound_ctrl:1
	s_nop 1
	v_max_u32_dpp v10, v10, v10 row_mirror row_mask:0xf bank_mask:0xf bound_ctrl:1
	v_cmp_eq_u32_e32 vcc, v9, v10
	v_cndmask_b32_e64 v6, v6, v10, s[28:29]
	s_nop 0
	v_cndmask_b32_e64 v9, 0, 1, vcc
	v_lshl_add_u32 v7, v9, 2, v7
	ds_read_b32 v10, v7
	v_addc_co_u32_e32 v4, vcc, v4, v5, vcc
	v_sub_u32_e32 v5, v62, v4
	s_waitcnt lgkmcnt(0)
	v_add_f32_e32 v10, v10, v3
	v_ashrrev_i32_e32 v11, 31, v10
	v_bitop3_b32 v10, v11, v10, s2 bitop3:0x36
	v_and_or_b32 v5, v10, s96, v5
	s_nop 1
	v_max_u32_dpp v10, v5, v5 quad_perm:[1,0,3,2] row_mask:0xf bank_mask:0xf bound_ctrl:1
	s_nop 1
	v_max_u32_dpp v10, v10, v10 quad_perm:[2,3,0,1] row_mask:0xf bank_mask:0xf bound_ctrl:1
	s_nop 1
	v_max_u32_dpp v10, v10, v10 row_half_mirror row_mask:0xf bank_mask:0xf bound_ctrl:1
	s_nop 1
	v_max_u32_dpp v10, v10, v10 row_mirror row_mask:0xf bank_mask:0xf bound_ctrl:1
	v_cmp_eq_u32_e32 vcc, v5, v10
	v_cndmask_b32_e64 v6, v6, v10, s[30:31]
	s_nop 0
	v_cndmask_b32_e64 v5, 0, 1, vcc
	v_lshl_add_u32 v7, v5, 2, v7
	ds_read_b32 v10, v7
	v_addc_co_u32_e32 v8, vcc, v8, v9, vcc
	v_sub_u32_e32 v9, v62, v8
	s_waitcnt lgkmcnt(0)
	v_add_f32_e32 v10, v10, v3
	v_ashrrev_i32_e32 v11, 31, v10
	v_bitop3_b32 v10, v11, v10, s2 bitop3:0x36
	v_and_or_b32 v9, v10, s96, v9
	s_nop 1
	v_max_u32_dpp v10, v9, v9 quad_perm:[1,0,3,2] row_mask:0xf bank_mask:0xf bound_ctrl:1
	s_nop 1
	v_max_u32_dpp v10, v10, v10 quad_perm:[2,3,0,1] row_mask:0xf bank_mask:0xf bound_ctrl:1
	s_nop 1
	v_max_u32_dpp v10, v10, v10 row_half_mirror row_mask:0xf bank_mask:0xf bound_ctrl:1
	s_nop 1
	v_max_u32_dpp v10, v10, v10 row_mirror row_mask:0xf bank_mask:0xf bound_ctrl:1
	v_cmp_eq_u32_e32 vcc, v9, v10
	v_cndmask_b32_e64 v6, v6, v10, s[34:35]
	s_nop 0
	v_cndmask_b32_e64 v9, 0, 1, vcc
	v_lshl_add_u32 v7, v9, 2, v7
	ds_read_b32 v10, v7
	v_addc_co_u32_e32 v4, vcc, v4, v5, vcc
	v_sub_u32_e32 v5, v62, v4
	s_waitcnt lgkmcnt(0)
	v_add_f32_e32 v10, v10, v3
	v_ashrrev_i32_e32 v11, 31, v10
	v_bitop3_b32 v10, v11, v10, s2 bitop3:0x36
	v_and_or_b32 v5, v10, s96, v5
	s_nop 1
	v_max_u32_dpp v10, v5, v5 quad_perm:[1,0,3,2] row_mask:0xf bank_mask:0xf bound_ctrl:1
	s_nop 1
	v_max_u32_dpp v10, v10, v10 quad_perm:[2,3,0,1] row_mask:0xf bank_mask:0xf bound_ctrl:1
	s_nop 1
	v_max_u32_dpp v10, v10, v10 row_half_mirror row_mask:0xf bank_mask:0xf bound_ctrl:1
	s_nop 1
	v_max_u32_dpp v10, v10, v10 row_mirror row_mask:0xf bank_mask:0xf bound_ctrl:1
	v_cmp_eq_u32_e32 vcc, v5, v10
	v_cndmask_b32_e64 v6, v6, v10, s[36:37]
	s_nop 0
	v_cndmask_b32_e64 v5, 0, 1, vcc
	v_lshl_add_u32 v7, v5, 2, v7
	v_addc_co_u32_e32 v8, vcc, v8, v9, vcc
	ds_read_b32 v9, v7
	v_sub_u32_e32 v8, v62, v8
	s_waitcnt lgkmcnt(0)
	v_add_f32_e32 v9, v9, v3
	v_ashrrev_i32_e32 v10, 31, v9
	v_bitop3_b32 v9, v10, v9, s2 bitop3:0x36
	v_and_or_b32 v8, v9, s96, v8
	s_nop 1
	v_max_u32_dpp v9, v8, v8 quad_perm:[1,0,3,2] row_mask:0xf bank_mask:0xf bound_ctrl:1
	s_nop 1
	v_max_u32_dpp v9, v9, v9 quad_perm:[2,3,0,1] row_mask:0xf bank_mask:0xf bound_ctrl:1
	s_nop 1
	v_max_u32_dpp v9, v9, v9 row_half_mirror row_mask:0xf bank_mask:0xf bound_ctrl:1
	s_nop 1
	v_max_u32_dpp v9, v9, v9 row_mirror row_mask:0xf bank_mask:0xf bound_ctrl:1
	v_cmp_eq_u32_e32 vcc, v8, v9
	v_cndmask_b32_e64 v6, v6, v9, s[38:39]
	s_nop 0
	v_cndmask_b32_e64 v8, 0, 1, vcc
	v_addc_co_u32_e32 v4, vcc, v4, v5, vcc
	v_lshl_add_u32 v5, v8, 2, v7
	ds_read_b32 v5, v5
	v_sub_u32_e32 v4, v62, v4
	s_waitcnt lgkmcnt(0)
	v_add_f32_e32 v3, v5, v3
	v_ashrrev_i32_e32 v5, 31, v3
	v_bitop3_b32 v3, v5, v3, s2 bitop3:0x36
	v_and_or_b32 v3, v3, s96, v4
	s_nop 1
	v_max_u32_dpp v3, v3, v3 quad_perm:[1,0,3,2] row_mask:0xf bank_mask:0xf bound_ctrl:1
	s_nop 1
	v_max_u32_dpp v3, v3, v3 quad_perm:[2,3,0,1] row_mask:0xf bank_mask:0xf bound_ctrl:1
	s_nop 1
	v_max_u32_dpp v3, v3, v3 row_half_mirror row_mask:0xf bank_mask:0xf bound_ctrl:1
	s_nop 1
	v_max_u32_dpp v3, v3, v3 row_mirror row_mask:0xf bank_mask:0xf bound_ctrl:1
	v_cndmask_b32_e64 v3, v6, v3, s[40:41]
	v_cmp_lt_i32_e32 vcc, -1, v3
	v_not_b32_e32 v4, v3
	v_bitop3_b32 v6, v3, 15, v3 bitop3:0xc
	v_cndmask_b32_e64 v5, v77, -1, vcc
	v_bitop3_b32 v5, v5, v3, s96 bitop3:0x78
	v_max_u32_dpp v3, v3, v3 quad_perm:[1,0,3,2] row_mask:0xf bank_mask:0xf bound_ctrl:1
	v_lshrrev_b32_e32 v4, 2, v4
	v_and_b32_e32 v4, 60, v4
	v_max_u32_dpp v3, v3, v3 quad_perm:[2,3,0,1] row_mask:0xf bank_mask:0xf bound_ctrl:1
	v_add_u32_e32 v4, v59, v4
	v_lshl_add_u32 v6, v6, 2, v59
	v_max_u32_dpp v3, v3, v3 row_half_mirror row_mask:0xf bank_mask:0xf bound_ctrl:1
	ds_read_b32 v4, v4 offset:64
	ds_read_b32 v6, v6 offset:128
	v_max_u32_dpp v3, v3, v3 row_mirror row_mask:0xf bank_mask:0xf bound_ctrl:1
	v_cmp_lt_i32_e32 vcc, -1, v3
	s_waitcnt lgkmcnt(0)
	v_lshl_add_u32 v6, v4, 7, v6
	v_cndmask_b32_e64 v7, v77, -1, vcc
	v_bitop3_b32 v3, v7, v3, s96 bitop3:0x78
	v_sub_f32_e32 v3, v5, v3
	v_mul_f32_e32 v3, 0x3fb8aa3b, v3
	v_exp_f32_e32 v7, v3
	s_nop 1
	v_add_f32_dpp v3, v7, v7 quad_perm:[1,0,3,2] row_mask:0xf bank_mask:0xf bound_ctrl:1
	s_nop 1
	v_add_f32_dpp v3, v3, v3 quad_perm:[2,3,0,1] row_mask:0xf bank_mask:0xf bound_ctrl:1
	s_nop 1
	v_add_f32_dpp v3, v3, v3 row_half_mirror row_mask:0xf bank_mask:0xf bound_ctrl:1
	s_nop 1
	v_add_f32_dpp v8, v3, v3 row_mirror row_mask:0xf bank_mask:0xf bound_ctrl:1
	v_ashrrev_i32_e32 v3, 31, v2
	v_lshlrev_b64 v[2:3], 9, v[2:3]
	v_or_b32_e32 v2, v2, v78
	v_lshl_add_u64 v[4:5], s[52:53], 0, v[2:3]
	global_store_dword v[4:5], v6, off
	v_div_scale_f32 v4, s[46:47], v8, v8, v7
	v_rcp_f32_e32 v5, v4
	v_lshl_add_u64 v[2:3], s[58:59], 0, v[2:3]
	v_fma_f32 v6, -v4, v5, 1.0
	v_fmac_f32_e32 v5, v6, v5
	v_div_scale_f32 v6, vcc, v7, v8, v7
	v_mul_f32_e32 v9, v6, v5
	v_fma_f32 v10, -v4, v9, v6
	v_fmac_f32_e32 v9, v10, v5
	v_fma_f32 v4, -v4, v9, v6
	v_div_fmas_f32 v4, v4, v5, v9
	v_cmp_le_i32_e32 vcc, s44, v46
	v_div_fixup_f32 v4, v4, v8, v7
	s_or_b64 s[70:71], vcc, s[70:71]
	global_store_dword v[2:3], v4, off
	s_andn2_b64 exec, exec, s[70:71]
	s_cbranch_execnz .LBB0_987
	s_branch .LBB0_981

.LBB0_2020:
	v_add_u32_e32 v2, v59, v53
	v_ashrrev_i32_e32 v3, 31, v2
	v_lshlrev_b64 v[2:3], 12, v[2:3]
	v_lshl_add_u64 v[56:57], v[54:55], 0, v[2:3]
	global_load_dwordx4 v[42:45], v[56:57], off
	global_load_dwordx4 v[38:41], v[56:57], off offset:64
	global_load_dwordx4 v[34:37], v[56:57], off offset:128
	global_load_dwordx4 v[30:33], v[56:57], off offset:192
	global_load_dwordx4 v[216:219], v[56:57], off offset:256
	global_load_dwordx4 v[220:223], v[56:57], off offset:320
	global_load_dwordx4 v[224:227], v[56:57], off offset:384
	global_load_dwordx4 v[228:231], v[56:57], off offset:448
	ds_read_b128 v[2:5], v65
	ds_read_b128 v[6:9], v65 offset:64
	v_add_u32_e32 v46, 8, v46
	s_waitcnt vmcnt(7) lgkmcnt(1)
	v_mfma_f32_16x16x32_bf16 v[2:5], v[42:45], v[2:5], 0
	ds_read_b128 v[10:13], v65 offset:4672
	ds_read_b128 v[14:17], v65 offset:9280
	ds_read_b128 v[18:21], v65 offset:13888
	s_waitcnt vmcnt(6) lgkmcnt(3)
	v_mfma_f32_16x16x32_bf16 v[2:5], v[38:41], v[6:9], v[2:5]
	ds_read_b128 v[6:9], v65 offset:128
	ds_read_b128 v[22:25], v65 offset:18496
	ds_read_b128 v[26:29], v65 offset:23104
	s_waitcnt vmcnt(5) lgkmcnt(2)
	v_mfma_f32_16x16x32_bf16 v[2:5], v[34:37], v[6:9], v[2:5]
	ds_read_b128 v[6:9], v65 offset:192
	ds_read_b128 v[80:83], v65 offset:27712
	s_waitcnt vmcnt(4) lgkmcnt(1)
	v_mfma_f32_16x16x32_bf16 v[2:5], v[30:33], v[6:9], v[2:5]
	ds_read_b128 v[6:9], v65 offset:4608
	s_waitcnt lgkmcnt(0)
	v_mfma_f32_16x16x32_bf16 v[6:9], v[42:45], v[6:9], 0
	v_mfma_f32_16x16x32_bf16 v[6:9], v[38:41], v[10:13], v[6:9]
	ds_read_b128 v[10:13], v65 offset:4736
	s_waitcnt lgkmcnt(0)
	v_mfma_f32_16x16x32_bf16 v[6:9], v[34:37], v[10:13], v[6:9]
	ds_read_b128 v[10:13], v65 offset:4800
	s_waitcnt lgkmcnt(0)
	v_mfma_f32_16x16x32_bf16 v[6:9], v[30:33], v[10:13], v[6:9]
	ds_read_b128 v[10:13], v65 offset:9216
	s_waitcnt lgkmcnt(0)
	v_mfma_f32_16x16x32_bf16 v[10:13], v[42:45], v[10:13], 0
	v_mfma_f32_16x16x32_bf16 v[10:13], v[38:41], v[14:17], v[10:13]
	ds_read_b128 v[14:17], v65 offset:9344
	s_waitcnt lgkmcnt(0)
	v_mfma_f32_16x16x32_bf16 v[10:13], v[34:37], v[14:17], v[10:13]
	ds_read_b128 v[14:17], v65 offset:9408
	s_waitcnt lgkmcnt(0)
	v_mfma_f32_16x16x32_bf16 v[10:13], v[30:33], v[14:17], v[10:13]
	ds_read_b128 v[14:17], v65 offset:13824
	s_waitcnt lgkmcnt(0)
	v_mfma_f32_16x16x32_bf16 v[14:17], v[42:45], v[14:17], 0
	v_mfma_f32_16x16x32_bf16 v[14:17], v[38:41], v[18:21], v[14:17]
	ds_read_b128 v[18:21], v65 offset:13952
	s_waitcnt lgkmcnt(0)
	v_mfma_f32_16x16x32_bf16 v[14:17], v[34:37], v[18:21], v[14:17]
	ds_read_b128 v[18:21], v65 offset:14016
	s_waitcnt lgkmcnt(0)
	v_mfma_f32_16x16x32_bf16 v[14:17], v[30:33], v[18:21], v[14:17]
	ds_read_b128 v[18:21], v65 offset:18432
	s_waitcnt lgkmcnt(0)
	v_mfma_f32_16x16x32_bf16 v[18:21], v[42:45], v[18:21], 0
	v_mfma_f32_16x16x32_bf16 v[18:21], v[38:41], v[22:25], v[18:21]
	ds_read_b128 v[22:25], v65 offset:18560
	s_waitcnt lgkmcnt(0)
	v_mfma_f32_16x16x32_bf16 v[18:21], v[34:37], v[22:25], v[18:21]
	ds_read_b128 v[22:25], v65 offset:18624
	s_waitcnt lgkmcnt(0)
	v_mfma_f32_16x16x32_bf16 v[18:21], v[30:33], v[22:25], v[18:21]
	ds_read_b128 v[22:25], v65 offset:23040
	s_waitcnt lgkmcnt(0)
	v_mfma_f32_16x16x32_bf16 v[22:25], v[42:45], v[22:25], 0
	v_mfma_f32_16x16x32_bf16 v[22:25], v[38:41], v[26:29], v[22:25]
	ds_read_b128 v[26:29], v65 offset:23168
	s_waitcnt lgkmcnt(0)
	v_mfma_f32_16x16x32_bf16 v[22:25], v[34:37], v[26:29], v[22:25]
	ds_read_b128 v[26:29], v65 offset:23232
	s_waitcnt lgkmcnt(0)
	v_mfma_f32_16x16x32_bf16 v[22:25], v[30:33], v[26:29], v[22:25]
	ds_read_b128 v[26:29], v65 offset:27648
	s_waitcnt lgkmcnt(0)
	v_mfma_f32_16x16x32_bf16 v[26:29], v[42:45], v[26:29], 0
	v_mfma_f32_16x16x32_bf16 v[26:29], v[38:41], v[80:83], v[26:29]
	ds_read_b128 v[80:83], v65 offset:27776
	s_waitcnt lgkmcnt(0)
	v_mfma_f32_16x16x32_bf16 v[26:29], v[34:37], v[80:83], v[26:29]
	ds_read_b128 v[80:83], v65 offset:27840
	s_waitcnt lgkmcnt(0)
	v_mfma_f32_16x16x32_bf16 v[26:29], v[30:33], v[80:83], v[26:29]
	ds_read_b128 v[80:83], v65 offset:32256
	s_waitcnt lgkmcnt(0)
	v_mfma_f32_16x16x32_bf16 v[42:45], v[42:45], v[80:83], 0
	ds_read_b128 v[80:83], v65 offset:32320
	s_waitcnt lgkmcnt(0)
	v_mfma_f32_16x16x32_bf16 v[38:41], v[38:41], v[80:83], v[42:45]
	s_nop 4
	ds_read_b128 v[42:45], v65 offset:32384
	s_waitcnt lgkmcnt(0)
	v_mfma_f32_16x16x32_bf16 v[34:37], v[34:37], v[42:45], v[38:41]
	s_nop 2
	ds_read_b128 v[38:41], v65 offset:32448
	s_waitcnt lgkmcnt(0)
	v_mfma_f32_16x16x32_bf16 v[30:33], v[30:33], v[38:41], v[34:37]
	s_nop 2
	v_ashrrev_i32_e32 v34, 31, v2
	v_bitop3_b32 v2, v34, v2, s87 bitop3:0x36
	v_ashrrev_i32_e32 v34, 31, v6
	v_bitop3_b32 v6, v34, v6, s87 bitop3:0x36
	v_ashrrev_i32_e32 v34, 31, v10
	v_bitop3_b32 v10, v34, v10, s87 bitop3:0x36
	v_ashrrev_i32_e32 v34, 31, v14
	v_bitop3_b32 v14, v34, v14, s87 bitop3:0x36
	v_ashrrev_i32_e32 v34, 31, v18
	v_bitop3_b32 v18, v34, v18, s87 bitop3:0x36
	v_ashrrev_i32_e32 v34, 31, v22
	v_bitop3_b32 v22, v34, v22, s87 bitop3:0x36
	v_ashrrev_i32_e32 v34, 31, v26
	v_bitop3_b32 v26, v34, v26, s87 bitop3:0x36
	v_ashrrev_i32_e32 v34, 31, v30
	v_bitop3_b32 v30, v34, v30, s87 bitop3:0x36
	v_and_or_b32 v2, v2, s96, v61
	v_and_or_b32 v6, v6, s96, v66
	v_and_or_b32 v10, v10, s96, v67
	v_and_or_b32 v14, v14, s96, v68
	v_and_or_b32 v18, v18, s96, v69
	v_and_or_b32 v22, v22, s96, v70
	v_and_or_b32 v26, v26, s96, v71
	v_and_or_b32 v30, v30, s96, v72
	v_max_u32_e32 v34, v2, v6
	v_min_u32_e32 v2, v2, v6
	v_max_u32_e32 v6, v10, v14
	v_min_u32_e32 v10, v10, v14
	v_max_u32_e32 v14, v18, v22
	v_min_u32_e32 v18, v18, v22
	v_max_u32_e32 v22, v26, v30
	v_min_u32_e32 v26, v26, v30
	v_max_u32_e32 v30, v34, v6
	v_min_u32_e32 v6, v34, v6
	v_max_u32_e32 v34, v2, v10
	v_min_u32_e32 v2, v2, v10
	v_max_u32_e32 v10, v14, v22
	v_min_u32_e32 v14, v14, v22
	v_max_u32_e32 v22, v18, v26
	v_min_u32_e32 v18, v18, v26
	v_max_u32_e32 v26, v34, v6
	v_min_u32_e32 v6, v34, v6
	v_max_u32_e32 v34, v22, v14
	v_min_u32_e32 v14, v22, v14
	v_max_u32_e32 v22, v30, v10
	v_min_u32_e32 v10, v30, v10
	v_max_u32_e32 v30, v26, v34
	v_min_u32_e32 v26, v26, v34
	v_max_u32_e32 v34, v6, v14
	v_min_u32_e32 v6, v6, v14
	v_max_u32_e32 v14, v2, v18
	v_min_u32_e32 v2, v2, v18
	v_max_u32_e32 v18, v34, v10
	v_min_u32_e32 v10, v34, v10
	v_max_u32_e32 v34, v14, v26
	v_min_u32_e32 v14, v14, v26
	v_max_u32_e32 v26, v30, v18
	v_min_u32_e32 v18, v30, v18
	v_max_u32_e32 v30, v34, v10
	v_min_u32_e32 v10, v34, v10
	v_max_u32_e32 v34, v14, v6
	v_min_u32_e32 v6, v14, v6
	v_max_u32_dpp v14, v22, v22 quad_perm:[1,0,3,2] row_mask:0xf bank_mask:0xf bound_ctrl:1
	s_nop 1
	v_max_u32_dpp v14, v14, v14 quad_perm:[2,3,0,1] row_mask:0xf bank_mask:0xf bound_ctrl:1
	s_nop 1
	v_max_u32_dpp v14, v14, v14 row_half_mirror row_mask:0xf bank_mask:0xf bound_ctrl:1
	s_nop 1
	v_max_u32_dpp v14, v14, v14 row_mirror row_mask:0xf bank_mask:0xf bound_ctrl:1
	v_cmp_eq_u32_e32 vcc, v22, v14
	v_cndmask_b32_e64 v35, 0, v14, s[8:9]
	s_nop 0
	v_cndmask_b32_e32 v14, v22, v26, vcc
	v_cndmask_b32_e32 v22, v26, v18, vcc
	v_cndmask_b32_e32 v18, v18, v30, vcc
	v_cndmask_b32_e32 v26, v30, v10, vcc
	v_cndmask_b32_e32 v10, v10, v34, vcc
	v_cndmask_b32_e32 v30, v34, v6, vcc
	v_max_u32_dpp v34, v14, v14 quad_perm:[1,0,3,2] row_mask:0xf bank_mask:0xf bound_ctrl:1
	v_cndmask_b32_e32 v6, v6, v2, vcc
	v_cndmask_b32_e64 v2, v2, 0, vcc
	v_max_u32_dpp v34, v34, v34 quad_perm:[2,3,0,1] row_mask:0xf bank_mask:0xf bound_ctrl:1
	s_nop 1
	v_max_u32_dpp v34, v34, v34 row_half_mirror row_mask:0xf bank_mask:0xf bound_ctrl:1
	s_nop 1
	v_max_u32_dpp v34, v34, v34 row_mirror row_mask:0xf bank_mask:0xf bound_ctrl:1
	v_cmp_eq_u32_e32 vcc, v14, v34
	v_cndmask_b32_e64 v35, v35, v34, s[10:11]
	s_nop 0
	v_cndmask_b32_e32 v14, v14, v22, vcc
	v_cndmask_b32_e32 v22, v22, v18, vcc
	v_cndmask_b32_e32 v18, v18, v26, vcc
	v_max_u32_dpp v34, v14, v14 quad_perm:[1,0,3,2] row_mask:0xf bank_mask:0xf bound_ctrl:1
	v_cndmask_b32_e32 v26, v26, v10, vcc
	v_cndmask_b32_e32 v10, v10, v30, vcc
	v_max_u32_dpp v34, v34, v34 quad_perm:[2,3,0,1] row_mask:0xf bank_mask:0xf bound_ctrl:1
	v_cndmask_b32_e32 v30, v30, v6, vcc
	v_cndmask_b32_e32 v6, v6, v2, vcc
	v_max_u32_dpp v34, v34, v34 row_half_mirror row_mask:0xf bank_mask:0xf bound_ctrl:1
	v_cndmask_b32_e64 v2, v2, 0, vcc
	s_nop 0
	v_max_u32_dpp v34, v34, v34 row_mirror row_mask:0xf bank_mask:0xf bound_ctrl:1
	v_cmp_eq_u32_e32 vcc, v14, v34
	v_cndmask_b32_e64 v35, v35, v34, s[12:13]
	s_nop 0
	v_cndmask_b32_e32 v14, v14, v22, vcc
	v_cndmask_b32_e32 v22, v22, v18, vcc
	v_cndmask_b32_e32 v18, v18, v26, vcc
	v_max_u32_dpp v34, v14, v14 quad_perm:[1,0,3,2] row_mask:0xf bank_mask:0xf bound_ctrl:1
	v_cndmask_b32_e32 v26, v26, v10, vcc
	v_cndmask_b32_e32 v10, v10, v30, vcc
	v_max_u32_dpp v34, v34, v34 quad_perm:[2,3,0,1] row_mask:0xf bank_mask:0xf bound_ctrl:1
	v_cndmask_b32_e32 v30, v30, v6, vcc
	v_cndmask_b32_e32 v6, v6, v2, vcc
	v_max_u32_dpp v34, v34, v34 row_half_mirror row_mask:0xf bank_mask:0xf bound_ctrl:1
	v_cndmask_b32_e64 v2, v2, 0, vcc
	s_nop 0
	v_max_u32_dpp v34, v34, v34 row_mirror row_mask:0xf bank_mask:0xf bound_ctrl:1
	v_cmp_eq_u32_e32 vcc, v14, v34
	v_cndmask_b32_e64 v35, v35, v34, s[14:15]
	s_nop 0
	v_cndmask_b32_e32 v14, v14, v22, vcc
	v_cndmask_b32_e32 v22, v22, v18, vcc
	v_cndmask_b32_e32 v18, v18, v26, vcc
	v_max_u32_dpp v34, v14, v14 quad_perm:[1,0,3,2] row_mask:0xf bank_mask:0xf bound_ctrl:1
	v_cndmask_b32_e32 v26, v26, v10, vcc
	v_cndmask_b32_e32 v10, v10, v30, vcc
	v_max_u32_dpp v34, v34, v34 quad_perm:[2,3,0,1] row_mask:0xf bank_mask:0xf bound_ctrl:1
	v_cndmask_b32_e32 v30, v30, v6, vcc
	v_cndmask_b32_e32 v6, v6, v2, vcc
	v_max_u32_dpp v34, v34, v34 row_half_mirror row_mask:0xf bank_mask:0xf bound_ctrl:1
	v_cndmask_b32_e64 v2, v2, 0, vcc
	s_nop 0
	v_max_u32_dpp v34, v34, v34 row_mirror row_mask:0xf bank_mask:0xf bound_ctrl:1
	v_cmp_eq_u32_e32 vcc, v14, v34
	v_cndmask_b32_e64 v35, v35, v34, s[16:17]
	s_nop 0
	v_cndmask_b32_e32 v14, v14, v22, vcc
	v_cndmask_b32_e32 v22, v22, v18, vcc
	v_cndmask_b32_e32 v18, v18, v26, vcc
	v_max_u32_dpp v34, v14, v14 quad_perm:[1,0,3,2] row_mask:0xf bank_mask:0xf bound_ctrl:1
	v_cndmask_b32_e32 v26, v26, v10, vcc
	v_cndmask_b32_e32 v10, v10, v30, vcc
	v_max_u32_dpp v34, v34, v34 quad_perm:[2,3,0,1] row_mask:0xf bank_mask:0xf bound_ctrl:1
	v_cndmask_b32_e32 v30, v30, v6, vcc
	v_cndmask_b32_e32 v6, v6, v2, vcc
	v_max_u32_dpp v34, v34, v34 row_half_mirror row_mask:0xf bank_mask:0xf bound_ctrl:1
	v_cndmask_b32_e64 v2, v2, 0, vcc
	s_nop 0
	v_max_u32_dpp v34, v34, v34 row_mirror row_mask:0xf bank_mask:0xf bound_ctrl:1
	v_cmp_eq_u32_e32 vcc, v14, v34
	v_cndmask_b32_e64 v35, v35, v34, s[18:19]
	s_nop 0
	v_cndmask_b32_e32 v14, v14, v22, vcc
	v_cndmask_b32_e32 v22, v22, v18, vcc
	v_cndmask_b32_e32 v18, v18, v26, vcc
	v_max_u32_dpp v34, v14, v14 quad_perm:[1,0,3,2] row_mask:0xf bank_mask:0xf bound_ctrl:1
	v_cndmask_b32_e32 v26, v26, v10, vcc
	v_cndmask_b32_e32 v10, v10, v30, vcc
	v_max_u32_dpp v34, v34, v34 quad_perm:[2,3,0,1] row_mask:0xf bank_mask:0xf bound_ctrl:1
	v_cndmask_b32_e32 v30, v30, v6, vcc
	v_cndmask_b32_e32 v6, v6, v2, vcc
	v_max_u32_dpp v34, v34, v34 row_half_mirror row_mask:0xf bank_mask:0xf bound_ctrl:1
	v_cndmask_b32_e64 v2, v2, 0, vcc
	s_nop 0
	v_max_u32_dpp v34, v34, v34 row_mirror row_mask:0xf bank_mask:0xf bound_ctrl:1
	v_cmp_eq_u32_e32 vcc, v14, v34
	v_cndmask_b32_e64 v35, v35, v34, s[20:21]
	s_nop 0
	v_cndmask_b32_e32 v14, v14, v22, vcc
	v_cndmask_b32_e32 v22, v22, v18, vcc
	v_cndmask_b32_e32 v18, v18, v26, vcc
	v_max_u32_dpp v34, v14, v14 quad_perm:[1,0,3,2] row_mask:0xf bank_mask:0xf bound_ctrl:1
	v_cndmask_b32_e32 v26, v26, v10, vcc
	v_cndmask_b32_e32 v10, v10, v30, vcc
	v_max_u32_dpp v34, v34, v34 quad_perm:[2,3,0,1] row_mask:0xf bank_mask:0xf bound_ctrl:1
	v_cndmask_b32_e32 v30, v30, v6, vcc
	v_cndmask_b32_e32 v6, v6, v2, vcc
	v_max_u32_dpp v34, v34, v34 row_half_mirror row_mask:0xf bank_mask:0xf bound_ctrl:1
	v_cndmask_b32_e64 v2, v2, 0, vcc
	s_nop 0
	v_max_u32_dpp v34, v34, v34 row_mirror row_mask:0xf bank_mask:0xf bound_ctrl:1
	v_cmp_eq_u32_e32 vcc, v14, v34
	v_cndmask_b32_e64 v35, v35, v34, s[22:23]
	s_nop 0
	v_cndmask_b32_e32 v14, v14, v22, vcc
	v_cndmask_b32_e32 v22, v22, v18, vcc
	v_cndmask_b32_e32 v18, v18, v26, vcc
	v_max_u32_dpp v34, v14, v14 quad_perm:[1,0,3,2] row_mask:0xf bank_mask:0xf bound_ctrl:1
	v_cndmask_b32_e32 v26, v26, v10, vcc
	v_cndmask_b32_e32 v10, v10, v30, vcc
	v_max_u32_dpp v34, v34, v34 quad_perm:[2,3,0,1] row_mask:0xf bank_mask:0xf bound_ctrl:1
	v_cndmask_b32_e32 v30, v30, v6, vcc
	v_cndmask_b32_e32 v6, v6, v2, vcc
	v_max_u32_dpp v34, v34, v34 row_half_mirror row_mask:0xf bank_mask:0xf bound_ctrl:1
	v_cndmask_b32_e64 v2, v2, 0, vcc
	s_nop 0
	v_max_u32_dpp v34, v34, v34 row_mirror row_mask:0xf bank_mask:0xf bound_ctrl:1
	v_cmp_eq_u32_e32 vcc, v14, v34
	v_cndmask_b32_e64 v35, v35, v34, s[24:25]
	s_nop 0
	v_cndmask_b32_e32 v14, v14, v22, vcc
	v_cndmask_b32_e32 v22, v22, v18, vcc
	v_cndmask_b32_e32 v18, v18, v26, vcc
	v_cndmask_b32_e32 v26, v26, v10, vcc
	v_cndmask_b32_e32 v10, v10, v30, vcc
	v_cndmask_b32_e32 v30, v30, v6, vcc
	v_cndmask_b32_e32 v2, v6, v2, vcc
	v_max_u32_dpp v6, v14, v14 quad_perm:[1,0,3,2] row_mask:0xf bank_mask:0xf bound_ctrl:1
	s_nop 1
	v_max_u32_dpp v6, v6, v6 quad_perm:[2,3,0,1] row_mask:0xf bank_mask:0xf bound_ctrl:1
	s_nop 1
	v_max_u32_dpp v6, v6, v6 row_half_mirror row_mask:0xf bank_mask:0xf bound_ctrl:1
	s_nop 1
	v_max_u32_dpp v6, v6, v6 row_mirror row_mask:0xf bank_mask:0xf bound_ctrl:1
	v_cmp_eq_u32_e32 vcc, v14, v6
	v_cndmask_b32_e64 v34, v35, v6, s[26:27]
	s_nop 0
	v_cndmask_b32_e32 v6, v14, v22, vcc
	v_cndmask_b32_e32 v14, v22, v18, vcc
	v_cndmask_b32_e32 v18, v18, v26, vcc
	v_cndmask_b32_e32 v22, v26, v10, vcc
	v_max_u32_dpp v26, v6, v6 quad_perm:[1,0,3,2] row_mask:0xf bank_mask:0xf bound_ctrl:1
	v_cndmask_b32_e32 v10, v10, v30, vcc
	v_cndmask_b32_e32 v2, v30, v2, vcc
	v_max_u32_dpp v26, v26, v26 quad_perm:[2,3,0,1] row_mask:0xf bank_mask:0xf bound_ctrl:1
	s_nop 1
	v_max_u32_dpp v26, v26, v26 row_half_mirror row_mask:0xf bank_mask:0xf bound_ctrl:1
	s_nop 1
	v_max_u32_dpp v26, v26, v26 row_mirror row_mask:0xf bank_mask:0xf bound_ctrl:1
	v_cmp_eq_u32_e32 vcc, v6, v26
	v_cndmask_b32_e64 v30, v34, v26, s[28:29]
	s_nop 0
	v_cndmask_b32_e32 v6, v6, v14, vcc
	v_cndmask_b32_e32 v14, v14, v18, vcc
	v_cndmask_b32_e32 v18, v18, v22, vcc
	v_cndmask_b32_e32 v22, v22, v10, vcc
	v_cndmask_b32_e32 v2, v10, v2, vcc
	v_max_u32_dpp v10, v6, v6 quad_perm:[1,0,3,2] row_mask:0xf bank_mask:0xf bound_ctrl:1
	s_nop 1
	v_max_u32_dpp v10, v10, v10 quad_perm:[2,3,0,1] row_mask:0xf bank_mask:0xf bound_ctrl:1
	s_nop 1
	v_max_u32_dpp v10, v10, v10 row_half_mirror row_mask:0xf bank_mask:0xf bound_ctrl:1
	s_nop 1
	v_max_u32_dpp v10, v10, v10 row_mirror row_mask:0xf bank_mask:0xf bound_ctrl:1
	v_cmp_eq_u32_e32 vcc, v6, v10
	v_cndmask_b32_e64 v26, v30, v10, s[30:31]
	s_nop 0
	v_cndmask_b32_e32 v6, v6, v14, vcc
	v_cndmask_b32_e32 v10, v14, v18, vcc
	v_cndmask_b32_e32 v14, v18, v22, vcc
	v_max_u32_dpp v18, v6, v6 quad_perm:[1,0,3,2] row_mask:0xf bank_mask:0xf bound_ctrl:1
	v_cndmask_b32_e32 v2, v22, v2, vcc
	s_nop 0
	v_max_u32_dpp v18, v18, v18 quad_perm:[2,3,0,1] row_mask:0xf bank_mask:0xf bound_ctrl:1
	s_nop 1
	v_max_u32_dpp v18, v18, v18 row_half_mirror row_mask:0xf bank_mask:0xf bound_ctrl:1
	s_nop 1
	v_max_u32_dpp v18, v18, v18 row_mirror row_mask:0xf bank_mask:0xf bound_ctrl:1
	v_cmp_eq_u32_e32 vcc, v6, v18
	v_cndmask_b32_e64 v22, v26, v18, s[34:35]
	s_nop 0
	v_cndmask_b32_e32 v6, v6, v10, vcc
	v_cndmask_b32_e32 v10, v10, v14, vcc
	v_cndmask_b32_e32 v2, v14, v2, vcc
	v_max_u32_dpp v14, v6, v6 quad_perm:[1,0,3,2] row_mask:0xf bank_mask:0xf bound_ctrl:1
	s_nop 1
	v_max_u32_dpp v14, v14, v14 quad_perm:[2,3,0,1] row_mask:0xf bank_mask:0xf bound_ctrl:1
	s_nop 1
	v_max_u32_dpp v14, v14, v14 row_half_mirror row_mask:0xf bank_mask:0xf bound_ctrl:1
	s_nop 1
	v_max_u32_dpp v14, v14, v14 row_mirror row_mask:0xf bank_mask:0xf bound_ctrl:1
	v_cmp_eq_u32_e32 vcc, v6, v14
	v_cndmask_b32_e64 v18, v22, v14, s[36:37]
	s_nop 0
	v_cndmask_b32_e32 v6, v6, v10, vcc
	v_cndmask_b32_e32 v2, v10, v2, vcc
	s_nop 0
	v_max_u32_dpp v10, v6, v6 quad_perm:[1,0,3,2] row_mask:0xf bank_mask:0xf bound_ctrl:1
	s_nop 1
	v_max_u32_dpp v10, v10, v10 quad_perm:[2,3,0,1] row_mask:0xf bank_mask:0xf bound_ctrl:1
	s_nop 1
	v_max_u32_dpp v10, v10, v10 row_half_mirror row_mask:0xf bank_mask:0xf bound_ctrl:1
	s_nop 1
	v_max_u32_dpp v10, v10, v10 row_mirror row_mask:0xf bank_mask:0xf bound_ctrl:1
	v_cmp_eq_u32_e32 vcc, v6, v10
	v_cndmask_b32_e64 v14, v18, v10, s[38:39]
	v_ashrrev_i32_e32 v10, 31, v19
	v_cndmask_b32_e32 v2, v6, v2, vcc
	v_ashrrev_i32_e32 v6, 31, v11
	v_bitop3_b32 v6, v6, v11, s87 bitop3:0x36
	v_max_u32_dpp v2, v2, v2 quad_perm:[1,0,3,2] row_mask:0xf bank_mask:0xf bound_ctrl:1
	v_ashrrev_i32_e32 v11, 31, v23
	v_bitop3_b32 v10, v10, v19, s87 bitop3:0x36
	v_max_u32_dpp v2, v2, v2 quad_perm:[2,3,0,1] row_mask:0xf bank_mask:0xf bound_ctrl:1
	v_bitop3_b32 v11, v11, v23, s87 bitop3:0x36
	v_and_or_b32 v6, v6, s96, v67
	v_max_u32_dpp v2, v2, v2 row_half_mirror row_mask:0xf bank_mask:0xf bound_ctrl:1
	v_and_or_b32 v10, v10, s96, v69
	v_and_or_b32 v11, v11, s96, v70
	v_max_u32_dpp v2, v2, v2 row_mirror row_mask:0xf bank_mask:0xf bound_ctrl:1
	v_cndmask_b32_e64 v83, v14, v2, s[40:41]
	v_ashrrev_i32_e32 v2, 31, v3
	v_bitop3_b32 v2, v2, v3, s87 bitop3:0x36
	v_ashrrev_i32_e32 v3, 31, v7
	v_bitop3_b32 v3, v3, v7, s87 bitop3:0x36
	v_ashrrev_i32_e32 v7, 31, v15
	v_bitop3_b32 v7, v7, v15, s87 bitop3:0x36
	v_ashrrev_i32_e32 v14, 31, v27
	v_ashrrev_i32_e32 v15, 31, v31
	v_bitop3_b32 v14, v14, v27, s87 bitop3:0x36
	v_bitop3_b32 v15, v15, v31, s87 bitop3:0x36
	v_and_or_b32 v2, v2, s96, v61
	v_and_or_b32 v3, v3, s96, v66
	v_and_or_b32 v7, v7, s96, v68
	v_and_or_b32 v14, v14, s96, v71
	v_and_or_b32 v15, v15, s96, v72
	v_max_u32_e32 v18, v2, v3
	v_min_u32_e32 v2, v2, v3
	v_max_u32_e32 v3, v6, v7
	v_min_u32_e32 v6, v6, v7
	v_max_u32_e32 v7, v10, v11
	v_min_u32_e32 v10, v10, v11
	v_max_u32_e32 v11, v14, v15
	v_min_u32_e32 v14, v14, v15
	v_max_u32_e32 v15, v18, v3
	v_min_u32_e32 v3, v18, v3
	v_max_u32_e32 v18, v2, v6
	v_min_u32_e32 v2, v2, v6
	v_max_u32_e32 v6, v7, v11
	v_min_u32_e32 v7, v7, v11
	v_max_u32_e32 v11, v10, v14
	v_min_u32_e32 v10, v10, v14
	v_max_u32_e32 v14, v18, v3
	v_min_u32_e32 v3, v18, v3
	v_max_u32_e32 v18, v11, v7
	v_min_u32_e32 v7, v11, v7
	v_max_u32_e32 v11, v15, v6
	v_min_u32_e32 v6, v15, v6
	v_max_u32_e32 v15, v14, v18
	v_min_u32_e32 v14, v14, v18
	v_max_u32_e32 v18, v3, v7
	v_min_u32_e32 v3, v3, v7
	v_max_u32_e32 v7, v2, v10
	v_min_u32_e32 v2, v2, v10
	v_max_u32_e32 v10, v18, v6
	v_min_u32_e32 v6, v18, v6
	v_max_u32_e32 v18, v7, v14
	v_min_u32_e32 v7, v7, v14
	v_max_u32_e32 v14, v15, v10
	v_min_u32_e32 v10, v15, v10
	v_max_u32_e32 v15, v18, v6
	v_min_u32_e32 v6, v18, v6
	v_max_u32_e32 v18, v7, v3
	v_min_u32_e32 v3, v7, v3
	v_max_u32_dpp v7, v11, v11 quad_perm:[1,0,3,2] row_mask:0xf bank_mask:0xf bound_ctrl:1
	s_nop 1
	v_max_u32_dpp v7, v7, v7 quad_perm:[2,3,0,1] row_mask:0xf bank_mask:0xf bound_ctrl:1
	s_nop 1
	v_max_u32_dpp v7, v7, v7 row_half_mirror row_mask:0xf bank_mask:0xf bound_ctrl:1
	s_nop 1
	v_max_u32_dpp v7, v7, v7 row_mirror row_mask:0xf bank_mask:0xf bound_ctrl:1
	v_cmp_eq_u32_e32 vcc, v11, v7
	v_cndmask_b32_e64 v19, 0, v7, s[8:9]
	s_nop 0
	v_cndmask_b32_e32 v7, v11, v14, vcc
	v_cndmask_b32_e32 v11, v14, v10, vcc
	v_cndmask_b32_e32 v10, v10, v15, vcc
	v_cndmask_b32_e32 v14, v15, v6, vcc
	v_cndmask_b32_e32 v6, v6, v18, vcc
	v_cndmask_b32_e32 v15, v18, v3, vcc
	v_max_u32_dpp v18, v7, v7 quad_perm:[1,0,3,2] row_mask:0xf bank_mask:0xf bound_ctrl:1
	v_cndmask_b32_e32 v3, v3, v2, vcc
	v_cndmask_b32_e64 v2, v2, 0, vcc
	v_max_u32_dpp v18, v18, v18 quad_perm:[2,3,0,1] row_mask:0xf bank_mask:0xf bound_ctrl:1
	s_nop 1
	v_max_u32_dpp v18, v18, v18 row_half_mirror row_mask:0xf bank_mask:0xf bound_ctrl:1
	s_nop 1
	v_max_u32_dpp v18, v18, v18 row_mirror row_mask:0xf bank_mask:0xf bound_ctrl:1
	v_cmp_eq_u32_e32 vcc, v7, v18
	v_cndmask_b32_e64 v19, v19, v18, s[10:11]
	s_nop 0
	v_cndmask_b32_e32 v7, v7, v11, vcc
	v_cndmask_b32_e32 v11, v11, v10, vcc
	v_cndmask_b32_e32 v10, v10, v14, vcc
	v_max_u32_dpp v18, v7, v7 quad_perm:[1,0,3,2] row_mask:0xf bank_mask:0xf bound_ctrl:1
	v_cndmask_b32_e32 v14, v14, v6, vcc
	v_cndmask_b32_e32 v6, v6, v15, vcc
	v_max_u32_dpp v18, v18, v18 quad_perm:[2,3,0,1] row_mask:0xf bank_mask:0xf bound_ctrl:1
	v_cndmask_b32_e32 v15, v15, v3, vcc
	v_cndmask_b32_e32 v3, v3, v2, vcc
	v_max_u32_dpp v18, v18, v18 row_half_mirror row_mask:0xf bank_mask:0xf bound_ctrl:1
	v_cndmask_b32_e64 v2, v2, 0, vcc
	s_nop 0
	v_max_u32_dpp v18, v18, v18 row_mirror row_mask:0xf bank_mask:0xf bound_ctrl:1
	v_cmp_eq_u32_e32 vcc, v7, v18
	v_cndmask_b32_e64 v19, v19, v18, s[12:13]
	s_nop 0
	v_cndmask_b32_e32 v7, v7, v11, vcc
	v_cndmask_b32_e32 v11, v11, v10, vcc
	v_cndmask_b32_e32 v10, v10, v14, vcc
	v_max_u32_dpp v18, v7, v7 quad_perm:[1,0,3,2] row_mask:0xf bank_mask:0xf bound_ctrl:1
	v_cndmask_b32_e32 v14, v14, v6, vcc
	v_cndmask_b32_e32 v6, v6, v15, vcc
	v_max_u32_dpp v18, v18, v18 quad_perm:[2,3,0,1] row_mask:0xf bank_mask:0xf bound_ctrl:1
	v_cndmask_b32_e32 v15, v15, v3, vcc
	v_cndmask_b32_e32 v3, v3, v2, vcc
	v_max_u32_dpp v18, v18, v18 row_half_mirror row_mask:0xf bank_mask:0xf bound_ctrl:1
	v_cndmask_b32_e64 v2, v2, 0, vcc
	s_nop 0
	v_max_u32_dpp v18, v18, v18 row_mirror row_mask:0xf bank_mask:0xf bound_ctrl:1
	v_cmp_eq_u32_e32 vcc, v7, v18
	v_cndmask_b32_e64 v19, v19, v18, s[14:15]
	s_nop 0
	v_cndmask_b32_e32 v7, v7, v11, vcc
	v_cndmask_b32_e32 v11, v11, v10, vcc
	v_cndmask_b32_e32 v10, v10, v14, vcc
	v_max_u32_dpp v18, v7, v7 quad_perm:[1,0,3,2] row_mask:0xf bank_mask:0xf bound_ctrl:1
	v_cndmask_b32_e32 v14, v14, v6, vcc
	v_cndmask_b32_e32 v6, v6, v15, vcc
	v_max_u32_dpp v18, v18, v18 quad_perm:[2,3,0,1] row_mask:0xf bank_mask:0xf bound_ctrl:1
	v_cndmask_b32_e32 v15, v15, v3, vcc
	v_cndmask_b32_e32 v3, v3, v2, vcc
	v_max_u32_dpp v18, v18, v18 row_half_mirror row_mask:0xf bank_mask:0xf bound_ctrl:1
	v_cndmask_b32_e64 v2, v2, 0, vcc
	s_nop 0
	v_max_u32_dpp v18, v18, v18 row_mirror row_mask:0xf bank_mask:0xf bound_ctrl:1
	v_cmp_eq_u32_e32 vcc, v7, v18
	v_cndmask_b32_e64 v19, v19, v18, s[16:17]
	s_nop 0
	v_cndmask_b32_e32 v7, v7, v11, vcc
	v_cndmask_b32_e32 v11, v11, v10, vcc
	v_cndmask_b32_e32 v10, v10, v14, vcc
	v_max_u32_dpp v18, v7, v7 quad_perm:[1,0,3,2] row_mask:0xf bank_mask:0xf bound_ctrl:1
	v_cndmask_b32_e32 v14, v14, v6, vcc
	v_cndmask_b32_e32 v6, v6, v15, vcc
	v_max_u32_dpp v18, v18, v18 quad_perm:[2,3,0,1] row_mask:0xf bank_mask:0xf bound_ctrl:1
	v_cndmask_b32_e32 v15, v15, v3, vcc
	v_cndmask_b32_e32 v3, v3, v2, vcc
	v_max_u32_dpp v18, v18, v18 row_half_mirror row_mask:0xf bank_mask:0xf bound_ctrl:1
	v_cndmask_b32_e64 v2, v2, 0, vcc
	s_nop 0
	v_max_u32_dpp v18, v18, v18 row_mirror row_mask:0xf bank_mask:0xf bound_ctrl:1
	v_cmp_eq_u32_e32 vcc, v7, v18
	v_cndmask_b32_e64 v19, v19, v18, s[18:19]
	s_nop 0
	v_cndmask_b32_e32 v7, v7, v11, vcc
	v_cndmask_b32_e32 v11, v11, v10, vcc
	v_cndmask_b32_e32 v10, v10, v14, vcc
	v_max_u32_dpp v18, v7, v7 quad_perm:[1,0,3,2] row_mask:0xf bank_mask:0xf bound_ctrl:1
	v_cndmask_b32_e32 v14, v14, v6, vcc
	v_cndmask_b32_e32 v6, v6, v15, vcc
	v_max_u32_dpp v18, v18, v18 quad_perm:[2,3,0,1] row_mask:0xf bank_mask:0xf bound_ctrl:1
	v_cndmask_b32_e32 v15, v15, v3, vcc
	v_cndmask_b32_e32 v3, v3, v2, vcc
	v_max_u32_dpp v18, v18, v18 row_half_mirror row_mask:0xf bank_mask:0xf bound_ctrl:1
	v_cndmask_b32_e64 v2, v2, 0, vcc
	s_nop 0
	v_max_u32_dpp v18, v18, v18 row_mirror row_mask:0xf bank_mask:0xf bound_ctrl:1
	v_cmp_eq_u32_e32 vcc, v7, v18
	v_cndmask_b32_e64 v19, v19, v18, s[20:21]
	s_nop 0
	v_cndmask_b32_e32 v7, v7, v11, vcc
	v_cndmask_b32_e32 v11, v11, v10, vcc
	v_cndmask_b32_e32 v10, v10, v14, vcc
	v_max_u32_dpp v18, v7, v7 quad_perm:[1,0,3,2] row_mask:0xf bank_mask:0xf bound_ctrl:1
	v_cndmask_b32_e32 v14, v14, v6, vcc
	v_cndmask_b32_e32 v6, v6, v15, vcc
	v_max_u32_dpp v18, v18, v18 quad_perm:[2,3,0,1] row_mask:0xf bank_mask:0xf bound_ctrl:1
	v_cndmask_b32_e32 v15, v15, v3, vcc
	v_cndmask_b32_e32 v3, v3, v2, vcc
	v_max_u32_dpp v18, v18, v18 row_half_mirror row_mask:0xf bank_mask:0xf bound_ctrl:1
	v_cndmask_b32_e64 v2, v2, 0, vcc
	s_nop 0
	v_max_u32_dpp v18, v18, v18 row_mirror row_mask:0xf bank_mask:0xf bound_ctrl:1
	v_cmp_eq_u32_e32 vcc, v7, v18
	v_cndmask_b32_e64 v19, v19, v18, s[22:23]
	s_nop 0
	v_cndmask_b32_e32 v7, v7, v11, vcc
	v_cndmask_b32_e32 v11, v11, v10, vcc
	v_cndmask_b32_e32 v10, v10, v14, vcc
	v_max_u32_dpp v18, v7, v7 quad_perm:[1,0,3,2] row_mask:0xf bank_mask:0xf bound_ctrl:1
	v_cndmask_b32_e32 v14, v14, v6, vcc
	v_cndmask_b32_e32 v6, v6, v15, vcc
	v_max_u32_dpp v18, v18, v18 quad_perm:[2,3,0,1] row_mask:0xf bank_mask:0xf bound_ctrl:1
	v_cndmask_b32_e32 v15, v15, v3, vcc
	v_cndmask_b32_e32 v3, v3, v2, vcc
	v_max_u32_dpp v18, v18, v18 row_half_mirror row_mask:0xf bank_mask:0xf bound_ctrl:1
	v_cndmask_b32_e64 v2, v2, 0, vcc
	s_nop 0
	v_max_u32_dpp v18, v18, v18 row_mirror row_mask:0xf bank_mask:0xf bound_ctrl:1
	v_cmp_eq_u32_e32 vcc, v7, v18
	v_cndmask_b32_e64 v19, v19, v18, s[24:25]
	s_nop 0
	v_cndmask_b32_e32 v7, v7, v11, vcc
	v_cndmask_b32_e32 v11, v11, v10, vcc
	v_cndmask_b32_e32 v10, v10, v14, vcc
	v_cndmask_b32_e32 v14, v14, v6, vcc
	v_cndmask_b32_e32 v6, v6, v15, vcc
	v_cndmask_b32_e32 v15, v15, v3, vcc
	v_cndmask_b32_e32 v2, v3, v2, vcc
	v_max_u32_dpp v3, v7, v7 quad_perm:[1,0,3,2] row_mask:0xf bank_mask:0xf bound_ctrl:1
	s_nop 1
	v_max_u32_dpp v3, v3, v3 quad_perm:[2,3,0,1] row_mask:0xf bank_mask:0xf bound_ctrl:1
	s_nop 1
	v_max_u32_dpp v3, v3, v3 row_half_mirror row_mask:0xf bank_mask:0xf bound_ctrl:1
	s_nop 1
	v_max_u32_dpp v3, v3, v3 row_mirror row_mask:0xf bank_mask:0xf bound_ctrl:1
	v_cmp_eq_u32_e32 vcc, v7, v3
	v_cndmask_b32_e64 v18, v19, v3, s[26:27]
	s_nop 0
	v_cndmask_b32_e32 v3, v7, v11, vcc
	v_cndmask_b32_e32 v7, v11, v10, vcc
	v_cndmask_b32_e32 v10, v10, v14, vcc
	v_cndmask_b32_e32 v11, v14, v6, vcc
	v_max_u32_dpp v14, v3, v3 quad_perm:[1,0,3,2] row_mask:0xf bank_mask:0xf bound_ctrl:1
	v_cndmask_b32_e32 v6, v6, v15, vcc
	v_cndmask_b32_e32 v2, v15, v2, vcc
	v_max_u32_dpp v14, v14, v14 quad_perm:[2,3,0,1] row_mask:0xf bank_mask:0xf bound_ctrl:1
	s_nop 1
	v_max_u32_dpp v14, v14, v14 row_half_mirror row_mask:0xf bank_mask:0xf bound_ctrl:1
	s_nop 1
	v_max_u32_dpp v14, v14, v14 row_mirror row_mask:0xf bank_mask:0xf bound_ctrl:1
	v_cmp_eq_u32_e32 vcc, v3, v14
	v_cndmask_b32_e64 v15, v18, v14, s[28:29]
	s_nop 0
	v_cndmask_b32_e32 v3, v3, v7, vcc
	v_cndmask_b32_e32 v7, v7, v10, vcc
	v_cndmask_b32_e32 v10, v10, v11, vcc
	v_cndmask_b32_e32 v11, v11, v6, vcc
	v_cndmask_b32_e32 v2, v6, v2, vcc
	v_max_u32_dpp v6, v3, v3 quad_perm:[1,0,3,2] row_mask:0xf bank_mask:0xf bound_ctrl:1
	s_nop 1
	v_max_u32_dpp v6, v6, v6 quad_perm:[2,3,0,1] row_mask:0xf bank_mask:0xf bound_ctrl:1
	s_nop 1
	v_max_u32_dpp v6, v6, v6 row_half_mirror row_mask:0xf bank_mask:0xf bound_ctrl:1
	s_nop 1
	v_max_u32_dpp v6, v6, v6 row_mirror row_mask:0xf bank_mask:0xf bound_ctrl:1
	v_cmp_eq_u32_e32 vcc, v3, v6
	v_cndmask_b32_e64 v14, v15, v6, s[30:31]
	s_nop 0
	v_cndmask_b32_e32 v3, v3, v7, vcc
	v_cndmask_b32_e32 v6, v7, v10, vcc
	v_cndmask_b32_e32 v7, v10, v11, vcc
	v_max_u32_dpp v10, v3, v3 quad_perm:[1,0,3,2] row_mask:0xf bank_mask:0xf bound_ctrl:1
	v_cndmask_b32_e32 v2, v11, v2, vcc
	s_nop 0
	v_max_u32_dpp v10, v10, v10 quad_perm:[2,3,0,1] row_mask:0xf bank_mask:0xf bound_ctrl:1
	s_nop 1
	v_max_u32_dpp v10, v10, v10 row_half_mirror row_mask:0xf bank_mask:0xf bound_ctrl:1
	s_nop 1
	v_max_u32_dpp v10, v10, v10 row_mirror row_mask:0xf bank_mask:0xf bound_ctrl:1
	v_cmp_eq_u32_e32 vcc, v3, v10
	v_cndmask_b32_e64 v11, v14, v10, s[34:35]
	s_nop 0
	v_cndmask_b32_e32 v3, v3, v6, vcc
	v_cndmask_b32_e32 v6, v6, v7, vcc
	v_cndmask_b32_e32 v2, v7, v2, vcc
	v_max_u32_dpp v7, v3, v3 quad_perm:[1,0,3,2] row_mask:0xf bank_mask:0xf bound_ctrl:1
	s_nop 1
	v_max_u32_dpp v7, v7, v7 quad_perm:[2,3,0,1] row_mask:0xf bank_mask:0xf bound_ctrl:1
	s_nop 1
	v_max_u32_dpp v7, v7, v7 row_half_mirror row_mask:0xf bank_mask:0xf bound_ctrl:1
	s_nop 1
	v_max_u32_dpp v7, v7, v7 row_mirror row_mask:0xf bank_mask:0xf bound_ctrl:1
	v_cmp_eq_u32_e32 vcc, v3, v7
	v_cndmask_b32_e64 v10, v11, v7, s[36:37]
	v_ashrrev_i32_e32 v11, 31, v32
	v_cndmask_b32_e32 v3, v3, v6, vcc
	v_cndmask_b32_e32 v2, v6, v2, vcc
	v_bitop3_b32 v11, v11, v32, s87 bitop3:0x36
	v_max_u32_dpp v6, v3, v3 quad_perm:[1,0,3,2] row_mask:0xf bank_mask:0xf bound_ctrl:1
	v_and_or_b32 v11, v11, s96, v72
	s_nop 0
	v_max_u32_dpp v6, v6, v6 quad_perm:[2,3,0,1] row_mask:0xf bank_mask:0xf bound_ctrl:1
	s_nop 1
	v_max_u32_dpp v6, v6, v6 row_half_mirror row_mask:0xf bank_mask:0xf bound_ctrl:1
	s_nop 1
	v_max_u32_dpp v6, v6, v6 row_mirror row_mask:0xf bank_mask:0xf bound_ctrl:1
	v_cmp_eq_u32_e32 vcc, v3, v6
	v_cndmask_b32_e64 v7, v10, v6, s[38:39]
	v_ashrrev_i32_e32 v6, 31, v16
	v_cndmask_b32_e32 v2, v3, v2, vcc
	v_ashrrev_i32_e32 v3, 31, v8
	v_bitop3_b32 v3, v3, v8, s87 bitop3:0x36
	v_max_u32_dpp v2, v2, v2 quad_perm:[1,0,3,2] row_mask:0xf bank_mask:0xf bound_ctrl:1
	v_ashrrev_i32_e32 v8, 31, v24
	v_ashrrev_i32_e32 v10, 31, v28
	v_max_u32_dpp v2, v2, v2 quad_perm:[2,3,0,1] row_mask:0xf bank_mask:0xf bound_ctrl:1
	v_bitop3_b32 v6, v6, v16, s87 bitop3:0x36
	v_bitop3_b32 v8, v8, v24, s87 bitop3:0x36
	v_max_u32_dpp v2, v2, v2 row_half_mirror row_mask:0xf bank_mask:0xf bound_ctrl:1
	v_bitop3_b32 v10, v10, v28, s87 bitop3:0x36
	v_and_or_b32 v3, v3, s96, v66
	v_max_u32_dpp v2, v2, v2 row_mirror row_mask:0xf bank_mask:0xf bound_ctrl:1
	v_cndmask_b32_e64 v82, v7, v2, s[40:41]
	v_ashrrev_i32_e32 v2, 31, v4
	v_bitop3_b32 v2, v2, v4, s87 bitop3:0x36
	v_ashrrev_i32_e32 v4, 31, v12
	v_ashrrev_i32_e32 v7, 31, v20
	v_bitop3_b32 v4, v4, v12, s87 bitop3:0x36
	v_bitop3_b32 v7, v7, v20, s87 bitop3:0x36
	v_and_or_b32 v2, v2, s96, v61
	v_and_or_b32 v4, v4, s96, v67
	v_and_or_b32 v6, v6, s96, v68
	v_and_or_b32 v7, v7, s96, v69
	v_and_or_b32 v8, v8, s96, v70
	v_and_or_b32 v10, v10, s96, v71
	v_max_u32_e32 v12, v2, v3
	v_min_u32_e32 v2, v2, v3
	v_max_u32_e32 v3, v4, v6
	v_min_u32_e32 v4, v4, v6
	v_max_u32_e32 v6, v7, v8
	v_min_u32_e32 v7, v7, v8
	v_max_u32_e32 v8, v10, v11
	v_min_u32_e32 v10, v10, v11
	v_max_u32_e32 v11, v12, v3
	v_min_u32_e32 v3, v12, v3
	v_max_u32_e32 v12, v2, v4
	v_min_u32_e32 v2, v2, v4
	v_max_u32_e32 v4, v6, v8
	v_min_u32_e32 v6, v6, v8
	v_max_u32_e32 v8, v7, v10
	v_min_u32_e32 v7, v7, v10
	v_max_u32_e32 v10, v12, v3
	v_min_u32_e32 v3, v12, v3
	v_max_u32_e32 v12, v8, v6
	v_min_u32_e32 v6, v8, v6
	v_max_u32_e32 v8, v11, v4
	v_min_u32_e32 v4, v11, v4
	v_max_u32_e32 v11, v10, v12
	v_min_u32_e32 v10, v10, v12
	v_max_u32_e32 v12, v3, v6
	v_min_u32_e32 v3, v3, v6
	v_max_u32_e32 v6, v2, v7
	v_min_u32_e32 v2, v2, v7
	v_max_u32_e32 v7, v12, v4
	v_min_u32_e32 v4, v12, v4
	v_max_u32_e32 v12, v6, v10
	v_min_u32_e32 v6, v6, v10
	v_max_u32_e32 v10, v11, v7
	v_min_u32_e32 v7, v11, v7
	v_max_u32_e32 v11, v12, v4
	v_min_u32_e32 v4, v12, v4
	v_max_u32_e32 v12, v6, v3
	v_min_u32_e32 v3, v6, v3
	v_max_u32_dpp v6, v8, v8 quad_perm:[1,0,3,2] row_mask:0xf bank_mask:0xf bound_ctrl:1
	s_nop 1
	v_max_u32_dpp v6, v6, v6 quad_perm:[2,3,0,1] row_mask:0xf bank_mask:0xf bound_ctrl:1
	s_nop 1
	v_max_u32_dpp v6, v6, v6 row_half_mirror row_mask:0xf bank_mask:0xf bound_ctrl:1
	s_nop 1
	v_max_u32_dpp v6, v6, v6 row_mirror row_mask:0xf bank_mask:0xf bound_ctrl:1
	v_cmp_eq_u32_e32 vcc, v8, v6
	v_cndmask_b32_e64 v14, 0, v6, s[8:9]
	s_nop 0
	v_cndmask_b32_e32 v6, v8, v10, vcc
	v_cndmask_b32_e32 v8, v10, v7, vcc
	v_cndmask_b32_e32 v7, v7, v11, vcc
	v_cndmask_b32_e32 v10, v11, v4, vcc
	v_cndmask_b32_e32 v4, v4, v12, vcc
	v_cndmask_b32_e32 v11, v12, v3, vcc
	v_max_u32_dpp v12, v6, v6 quad_perm:[1,0,3,2] row_mask:0xf bank_mask:0xf bound_ctrl:1
	v_cndmask_b32_e32 v3, v3, v2, vcc
	v_cndmask_b32_e64 v2, v2, 0, vcc
	v_max_u32_dpp v12, v12, v12 quad_perm:[2,3,0,1] row_mask:0xf bank_mask:0xf bound_ctrl:1
	s_nop 1
	v_max_u32_dpp v12, v12, v12 row_half_mirror row_mask:0xf bank_mask:0xf bound_ctrl:1
	s_nop 1
	v_max_u32_dpp v12, v12, v12 row_mirror row_mask:0xf bank_mask:0xf bound_ctrl:1
	v_cmp_eq_u32_e32 vcc, v6, v12
	v_cndmask_b32_e64 v14, v14, v12, s[10:11]
	s_nop 0
	v_cndmask_b32_e32 v6, v6, v8, vcc
	v_cndmask_b32_e32 v8, v8, v7, vcc
	v_cndmask_b32_e32 v7, v7, v10, vcc
	v_max_u32_dpp v12, v6, v6 quad_perm:[1,0,3,2] row_mask:0xf bank_mask:0xf bound_ctrl:1
	v_cndmask_b32_e32 v10, v10, v4, vcc
	v_cndmask_b32_e32 v4, v4, v11, vcc
	v_max_u32_dpp v12, v12, v12 quad_perm:[2,3,0,1] row_mask:0xf bank_mask:0xf bound_ctrl:1
	v_cndmask_b32_e32 v11, v11, v3, vcc
	v_cndmask_b32_e32 v3, v3, v2, vcc
	v_max_u32_dpp v12, v12, v12 row_half_mirror row_mask:0xf bank_mask:0xf bound_ctrl:1
	v_cndmask_b32_e64 v2, v2, 0, vcc
	s_nop 0
	v_max_u32_dpp v12, v12, v12 row_mirror row_mask:0xf bank_mask:0xf bound_ctrl:1
	v_cmp_eq_u32_e32 vcc, v6, v12
	v_cndmask_b32_e64 v14, v14, v12, s[12:13]
	s_nop 0
	v_cndmask_b32_e32 v6, v6, v8, vcc
	v_cndmask_b32_e32 v8, v8, v7, vcc
	v_cndmask_b32_e32 v7, v7, v10, vcc
	v_max_u32_dpp v12, v6, v6 quad_perm:[1,0,3,2] row_mask:0xf bank_mask:0xf bound_ctrl:1
	v_cndmask_b32_e32 v10, v10, v4, vcc
	v_cndmask_b32_e32 v4, v4, v11, vcc
	v_max_u32_dpp v12, v12, v12 quad_perm:[2,3,0,1] row_mask:0xf bank_mask:0xf bound_ctrl:1
	v_cndmask_b32_e32 v11, v11, v3, vcc
	v_cndmask_b32_e32 v3, v3, v2, vcc
	v_max_u32_dpp v12, v12, v12 row_half_mirror row_mask:0xf bank_mask:0xf bound_ctrl:1
	v_cndmask_b32_e64 v2, v2, 0, vcc
	s_nop 0
	v_max_u32_dpp v12, v12, v12 row_mirror row_mask:0xf bank_mask:0xf bound_ctrl:1
	v_cmp_eq_u32_e32 vcc, v6, v12
	v_cndmask_b32_e64 v14, v14, v12, s[14:15]
	s_nop 0
	v_cndmask_b32_e32 v6, v6, v8, vcc
	v_cndmask_b32_e32 v8, v8, v7, vcc
	v_cndmask_b32_e32 v7, v7, v10, vcc
	v_max_u32_dpp v12, v6, v6 quad_perm:[1,0,3,2] row_mask:0xf bank_mask:0xf bound_ctrl:1
	v_cndmask_b32_e32 v10, v10, v4, vcc
	v_cndmask_b32_e32 v4, v4, v11, vcc
	v_max_u32_dpp v12, v12, v12 quad_perm:[2,3,0,1] row_mask:0xf bank_mask:0xf bound_ctrl:1
	v_cndmask_b32_e32 v11, v11, v3, vcc
	v_cndmask_b32_e32 v3, v3, v2, vcc
	v_max_u32_dpp v12, v12, v12 row_half_mirror row_mask:0xf bank_mask:0xf bound_ctrl:1
	v_cndmask_b32_e64 v2, v2, 0, vcc
	s_nop 0
	v_max_u32_dpp v12, v12, v12 row_mirror row_mask:0xf bank_mask:0xf bound_ctrl:1
	v_cmp_eq_u32_e32 vcc, v6, v12
	v_cndmask_b32_e64 v14, v14, v12, s[16:17]
	s_nop 0
	v_cndmask_b32_e32 v6, v6, v8, vcc
	v_cndmask_b32_e32 v8, v8, v7, vcc
	v_cndmask_b32_e32 v7, v7, v10, vcc
	v_max_u32_dpp v12, v6, v6 quad_perm:[1,0,3,2] row_mask:0xf bank_mask:0xf bound_ctrl:1
	v_cndmask_b32_e32 v10, v10, v4, vcc
	v_cndmask_b32_e32 v4, v4, v11, vcc
	v_max_u32_dpp v12, v12, v12 quad_perm:[2,3,0,1] row_mask:0xf bank_mask:0xf bound_ctrl:1
	v_cndmask_b32_e32 v11, v11, v3, vcc
	v_cndmask_b32_e32 v3, v3, v2, vcc
	v_max_u32_dpp v12, v12, v12 row_half_mirror row_mask:0xf bank_mask:0xf bound_ctrl:1
	v_cndmask_b32_e64 v2, v2, 0, vcc
	s_nop 0
	v_max_u32_dpp v12, v12, v12 row_mirror row_mask:0xf bank_mask:0xf bound_ctrl:1
	v_cmp_eq_u32_e32 vcc, v6, v12
	v_cndmask_b32_e64 v14, v14, v12, s[18:19]
	s_nop 0
	v_cndmask_b32_e32 v6, v6, v8, vcc
	v_cndmask_b32_e32 v8, v8, v7, vcc
	v_cndmask_b32_e32 v7, v7, v10, vcc
	v_max_u32_dpp v12, v6, v6 quad_perm:[1,0,3,2] row_mask:0xf bank_mask:0xf bound_ctrl:1
	v_cndmask_b32_e32 v10, v10, v4, vcc
	v_cndmask_b32_e32 v4, v4, v11, vcc
	v_max_u32_dpp v12, v12, v12 quad_perm:[2,3,0,1] row_mask:0xf bank_mask:0xf bound_ctrl:1
	v_cndmask_b32_e32 v11, v11, v3, vcc
	v_cndmask_b32_e32 v3, v3, v2, vcc
	v_max_u32_dpp v12, v12, v12 row_half_mirror row_mask:0xf bank_mask:0xf bound_ctrl:1
	v_cndmask_b32_e64 v2, v2, 0, vcc
	s_nop 0
	v_max_u32_dpp v12, v12, v12 row_mirror row_mask:0xf bank_mask:0xf bound_ctrl:1
	v_cmp_eq_u32_e32 vcc, v6, v12
	v_cndmask_b32_e64 v14, v14, v12, s[20:21]
	s_nop 0
	v_cndmask_b32_e32 v6, v6, v8, vcc
	v_cndmask_b32_e32 v8, v8, v7, vcc
	v_cndmask_b32_e32 v7, v7, v10, vcc
	v_max_u32_dpp v12, v6, v6 quad_perm:[1,0,3,2] row_mask:0xf bank_mask:0xf bound_ctrl:1
	v_cndmask_b32_e32 v10, v10, v4, vcc
	v_cndmask_b32_e32 v4, v4, v11, vcc
	v_max_u32_dpp v12, v12, v12 quad_perm:[2,3,0,1] row_mask:0xf bank_mask:0xf bound_ctrl:1
	v_cndmask_b32_e32 v11, v11, v3, vcc
	v_cndmask_b32_e32 v3, v3, v2, vcc
	v_max_u32_dpp v12, v12, v12 row_half_mirror row_mask:0xf bank_mask:0xf bound_ctrl:1
	v_cndmask_b32_e64 v2, v2, 0, vcc
	s_nop 0
	v_max_u32_dpp v12, v12, v12 row_mirror row_mask:0xf bank_mask:0xf bound_ctrl:1
	v_cmp_eq_u32_e32 vcc, v6, v12
	v_cndmask_b32_e64 v14, v14, v12, s[22:23]
	s_nop 0
	v_cndmask_b32_e32 v6, v6, v8, vcc
	v_cndmask_b32_e32 v8, v8, v7, vcc
	v_cndmask_b32_e32 v7, v7, v10, vcc
	v_max_u32_dpp v12, v6, v6 quad_perm:[1,0,3,2] row_mask:0xf bank_mask:0xf bound_ctrl:1
	v_cndmask_b32_e32 v10, v10, v4, vcc
	v_cndmask_b32_e32 v4, v4, v11, vcc
	v_max_u32_dpp v12, v12, v12 quad_perm:[2,3,0,1] row_mask:0xf bank_mask:0xf bound_ctrl:1
	v_cndmask_b32_e32 v11, v11, v3, vcc
	v_cndmask_b32_e32 v3, v3, v2, vcc
	v_max_u32_dpp v12, v12, v12 row_half_mirror row_mask:0xf bank_mask:0xf bound_ctrl:1
	v_cndmask_b32_e64 v2, v2, 0, vcc
	s_nop 0
	v_max_u32_dpp v12, v12, v12 row_mirror row_mask:0xf bank_mask:0xf bound_ctrl:1
	v_cmp_eq_u32_e32 vcc, v6, v12
	v_cndmask_b32_e64 v14, v14, v12, s[24:25]
	s_nop 0
	v_cndmask_b32_e32 v6, v6, v8, vcc
	v_cndmask_b32_e32 v8, v8, v7, vcc
	v_cndmask_b32_e32 v7, v7, v10, vcc
	v_cndmask_b32_e32 v10, v10, v4, vcc
	v_cndmask_b32_e32 v4, v4, v11, vcc
	v_cndmask_b32_e32 v11, v11, v3, vcc
	v_cndmask_b32_e32 v2, v3, v2, vcc
	v_max_u32_dpp v3, v6, v6 quad_perm:[1,0,3,2] row_mask:0xf bank_mask:0xf bound_ctrl:1
	s_nop 1
	v_max_u32_dpp v3, v3, v3 quad_perm:[2,3,0,1] row_mask:0xf bank_mask:0xf bound_ctrl:1
	s_nop 1
	v_max_u32_dpp v3, v3, v3 row_half_mirror row_mask:0xf bank_mask:0xf bound_ctrl:1
	s_nop 1
	v_max_u32_dpp v3, v3, v3 row_mirror row_mask:0xf bank_mask:0xf bound_ctrl:1
	v_cmp_eq_u32_e32 vcc, v6, v3
	v_cndmask_b32_e64 v12, v14, v3, s[26:27]
	s_nop 0
	v_cndmask_b32_e32 v3, v6, v8, vcc
	v_cndmask_b32_e32 v6, v8, v7, vcc
	v_cndmask_b32_e32 v7, v7, v10, vcc
	v_cndmask_b32_e32 v8, v10, v4, vcc
	v_max_u32_dpp v10, v3, v3 quad_perm:[1,0,3,2] row_mask:0xf bank_mask:0xf bound_ctrl:1
	v_cndmask_b32_e32 v4, v4, v11, vcc
	v_cndmask_b32_e32 v2, v11, v2, vcc
	v_max_u32_dpp v10, v10, v10 quad_perm:[2,3,0,1] row_mask:0xf bank_mask:0xf bound_ctrl:1
	s_nop 1
	v_max_u32_dpp v10, v10, v10 row_half_mirror row_mask:0xf bank_mask:0xf bound_ctrl:1
	s_nop 1
	v_max_u32_dpp v10, v10, v10 row_mirror row_mask:0xf bank_mask:0xf bound_ctrl:1
	v_cmp_eq_u32_e32 vcc, v3, v10
	v_cndmask_b32_e64 v11, v12, v10, s[28:29]
	s_nop 0
	v_cndmask_b32_e32 v3, v3, v6, vcc
	v_cndmask_b32_e32 v6, v6, v7, vcc
	v_cndmask_b32_e32 v7, v7, v8, vcc
	v_cndmask_b32_e32 v8, v8, v4, vcc
	v_cndmask_b32_e32 v2, v4, v2, vcc
	v_max_u32_dpp v4, v3, v3 quad_perm:[1,0,3,2] row_mask:0xf bank_mask:0xf bound_ctrl:1
	s_nop 1
	v_max_u32_dpp v4, v4, v4 quad_perm:[2,3,0,1] row_mask:0xf bank_mask:0xf bound_ctrl:1
	s_nop 1
	v_max_u32_dpp v4, v4, v4 row_half_mirror row_mask:0xf bank_mask:0xf bound_ctrl:1
	s_nop 1
	v_max_u32_dpp v4, v4, v4 row_mirror row_mask:0xf bank_mask:0xf bound_ctrl:1
	v_cmp_eq_u32_e32 vcc, v3, v4
	v_cndmask_b32_e64 v10, v11, v4, s[30:31]
	s_nop 0
	v_cndmask_b32_e32 v3, v3, v6, vcc
	v_cndmask_b32_e32 v4, v6, v7, vcc
	v_cndmask_b32_e32 v6, v7, v8, vcc
	v_max_u32_dpp v7, v3, v3 quad_perm:[1,0,3,2] row_mask:0xf bank_mask:0xf bound_ctrl:1
	v_cndmask_b32_e32 v2, v8, v2, vcc
	s_nop 0
	v_max_u32_dpp v7, v7, v7 quad_perm:[2,3,0,1] row_mask:0xf bank_mask:0xf bound_ctrl:1
	s_nop 1
	v_max_u32_dpp v7, v7, v7 row_half_mirror row_mask:0xf bank_mask:0xf bound_ctrl:1
	s_nop 1
	v_max_u32_dpp v7, v7, v7 row_mirror row_mask:0xf bank_mask:0xf bound_ctrl:1
	v_cmp_eq_u32_e32 vcc, v3, v7
	v_cndmask_b32_e64 v8, v10, v7, s[34:35]
	s_nop 0
	v_cndmask_b32_e32 v3, v3, v4, vcc
	v_cndmask_b32_e32 v4, v4, v6, vcc
	v_cndmask_b32_e32 v2, v6, v2, vcc
	v_max_u32_dpp v6, v3, v3 quad_perm:[1,0,3,2] row_mask:0xf bank_mask:0xf bound_ctrl:1
	s_nop 1
	v_max_u32_dpp v6, v6, v6 quad_perm:[2,3,0,1] row_mask:0xf bank_mask:0xf bound_ctrl:1
	s_nop 1
	v_max_u32_dpp v6, v6, v6 row_half_mirror row_mask:0xf bank_mask:0xf bound_ctrl:1
	s_nop 1
	v_max_u32_dpp v6, v6, v6 row_mirror row_mask:0xf bank_mask:0xf bound_ctrl:1
	v_cmp_eq_u32_e32 vcc, v3, v6
	v_cndmask_b32_e64 v7, v8, v6, s[36:37]
	v_ashrrev_i32_e32 v8, 31, v29
	v_cndmask_b32_e32 v3, v3, v4, vcc
	v_cndmask_b32_e32 v2, v4, v2, vcc
	v_bitop3_b32 v8, v8, v29, s87 bitop3:0x36
	v_max_u32_dpp v4, v3, v3 quad_perm:[1,0,3,2] row_mask:0xf bank_mask:0xf bound_ctrl:1
	v_and_or_b32 v8, v8, s96, v71
	s_nop 0
	v_max_u32_dpp v4, v4, v4 quad_perm:[2,3,0,1] row_mask:0xf bank_mask:0xf bound_ctrl:1
	s_nop 1
	v_max_u32_dpp v4, v4, v4 row_half_mirror row_mask:0xf bank_mask:0xf bound_ctrl:1
	s_nop 1
	v_max_u32_dpp v4, v4, v4 row_mirror row_mask:0xf bank_mask:0xf bound_ctrl:1
	v_cmp_eq_u32_e32 vcc, v3, v4
	v_cndmask_b32_e64 v6, v7, v4, s[38:39]
	v_ashrrev_i32_e32 v4, 31, v13
	v_cndmask_b32_e32 v2, v3, v2, vcc
	v_ashrrev_i32_e32 v3, 31, v9
	v_bitop3_b32 v3, v3, v9, s87 bitop3:0x36
	v_max_u32_dpp v2, v2, v2 quad_perm:[1,0,3,2] row_mask:0xf bank_mask:0xf bound_ctrl:1
	v_ashrrev_i32_e32 v7, 31, v25
	v_ashrrev_i32_e32 v9, 31, v33
	v_max_u32_dpp v2, v2, v2 quad_perm:[2,3,0,1] row_mask:0xf bank_mask:0xf bound_ctrl:1
	v_bitop3_b32 v4, v4, v13, s87 bitop3:0x36
	v_bitop3_b32 v7, v7, v25, s87 bitop3:0x36
	v_max_u32_dpp v2, v2, v2 row_half_mirror row_mask:0xf bank_mask:0xf bound_ctrl:1
	v_bitop3_b32 v9, v9, v33, s87 bitop3:0x36
	v_and_or_b32 v3, v3, s96, v66
	v_max_u32_dpp v2, v2, v2 row_mirror row_mask:0xf bank_mask:0xf bound_ctrl:1
	v_cndmask_b32_e64 v81, v6, v2, s[40:41]
	v_ashrrev_i32_e32 v2, 31, v5
	v_bitop3_b32 v2, v2, v5, s87 bitop3:0x36
	v_ashrrev_i32_e32 v5, 31, v17
	v_ashrrev_i32_e32 v6, 31, v21
	v_bitop3_b32 v5, v5, v17, s87 bitop3:0x36
	v_bitop3_b32 v6, v6, v21, s87 bitop3:0x36
	v_and_or_b32 v2, v2, s96, v61
	v_and_or_b32 v4, v4, s96, v67
	v_and_or_b32 v5, v5, s96, v68
	v_and_or_b32 v6, v6, s96, v69
	v_and_or_b32 v7, v7, s96, v70
	v_and_or_b32 v9, v9, s96, v72
	v_max_u32_e32 v10, v2, v3
	v_min_u32_e32 v2, v2, v3
	v_max_u32_e32 v3, v4, v5
	v_min_u32_e32 v4, v4, v5
	v_max_u32_e32 v5, v6, v7
	v_min_u32_e32 v6, v6, v7
	v_max_u32_e32 v7, v8, v9
	v_min_u32_e32 v8, v8, v9
	v_max_u32_e32 v9, v10, v3
	v_min_u32_e32 v3, v10, v3
	v_max_u32_e32 v10, v2, v4
	v_min_u32_e32 v2, v2, v4
	v_max_u32_e32 v4, v5, v7
	v_min_u32_e32 v5, v5, v7
	v_max_u32_e32 v7, v6, v8
	v_min_u32_e32 v6, v6, v8
	v_max_u32_e32 v8, v10, v3
	v_min_u32_e32 v3, v10, v3
	v_max_u32_e32 v10, v7, v5
	v_min_u32_e32 v5, v7, v5
	v_max_u32_e32 v7, v9, v4
	v_min_u32_e32 v4, v9, v4
	v_max_u32_e32 v9, v8, v10
	v_min_u32_e32 v8, v8, v10
	v_max_u32_e32 v10, v3, v5
	v_min_u32_e32 v3, v3, v5
	v_max_u32_e32 v5, v2, v6
	v_min_u32_e32 v2, v2, v6
	v_max_u32_e32 v6, v10, v4
	v_min_u32_e32 v4, v10, v4
	v_max_u32_e32 v10, v5, v8
	v_min_u32_e32 v5, v5, v8
	v_max_u32_e32 v8, v9, v6
	v_min_u32_e32 v6, v9, v6
	v_max_u32_e32 v9, v10, v4
	v_min_u32_e32 v4, v10, v4
	v_max_u32_e32 v10, v5, v3
	v_min_u32_e32 v3, v5, v3
	v_max_u32_dpp v5, v7, v7 quad_perm:[1,0,3,2] row_mask:0xf bank_mask:0xf bound_ctrl:1
	s_nop 1
	v_max_u32_dpp v5, v5, v5 quad_perm:[2,3,0,1] row_mask:0xf bank_mask:0xf bound_ctrl:1
	s_nop 1
	v_max_u32_dpp v5, v5, v5 row_half_mirror row_mask:0xf bank_mask:0xf bound_ctrl:1
	s_nop 1
	v_max_u32_dpp v5, v5, v5 row_mirror row_mask:0xf bank_mask:0xf bound_ctrl:1
	v_cmp_eq_u32_e32 vcc, v7, v5
	v_cndmask_b32_e64 v11, 0, v5, s[8:9]
	s_nop 0
	v_cndmask_b32_e32 v5, v7, v8, vcc
	v_cndmask_b32_e32 v7, v8, v6, vcc
	v_cndmask_b32_e32 v6, v6, v9, vcc
	v_cndmask_b32_e32 v8, v9, v4, vcc
	v_cndmask_b32_e32 v4, v4, v10, vcc
	v_cndmask_b32_e32 v9, v10, v3, vcc
	v_max_u32_dpp v10, v5, v5 quad_perm:[1,0,3,2] row_mask:0xf bank_mask:0xf bound_ctrl:1
	v_cndmask_b32_e32 v3, v3, v2, vcc
	v_cndmask_b32_e64 v2, v2, 0, vcc
	v_max_u32_dpp v10, v10, v10 quad_perm:[2,3,0,1] row_mask:0xf bank_mask:0xf bound_ctrl:1
	s_nop 1
	v_max_u32_dpp v10, v10, v10 row_half_mirror row_mask:0xf bank_mask:0xf bound_ctrl:1
	s_nop 1
	v_max_u32_dpp v10, v10, v10 row_mirror row_mask:0xf bank_mask:0xf bound_ctrl:1
	v_cmp_eq_u32_e32 vcc, v5, v10
	v_cndmask_b32_e64 v11, v11, v10, s[10:11]
	s_nop 0
	v_cndmask_b32_e32 v5, v5, v7, vcc
	v_cndmask_b32_e32 v7, v7, v6, vcc
	v_cndmask_b32_e32 v6, v6, v8, vcc
	v_max_u32_dpp v10, v5, v5 quad_perm:[1,0,3,2] row_mask:0xf bank_mask:0xf bound_ctrl:1
	v_cndmask_b32_e32 v8, v8, v4, vcc
	v_cndmask_b32_e32 v4, v4, v9, vcc
	v_max_u32_dpp v10, v10, v10 quad_perm:[2,3,0,1] row_mask:0xf bank_mask:0xf bound_ctrl:1
	v_cndmask_b32_e32 v9, v9, v3, vcc
	v_cndmask_b32_e32 v3, v3, v2, vcc
	v_max_u32_dpp v10, v10, v10 row_half_mirror row_mask:0xf bank_mask:0xf bound_ctrl:1
	v_cndmask_b32_e64 v2, v2, 0, vcc
	s_nop 0
	v_max_u32_dpp v10, v10, v10 row_mirror row_mask:0xf bank_mask:0xf bound_ctrl:1
	v_cmp_eq_u32_e32 vcc, v5, v10
	v_cndmask_b32_e64 v11, v11, v10, s[12:13]
	s_nop 0
	v_cndmask_b32_e32 v5, v5, v7, vcc
	v_cndmask_b32_e32 v7, v7, v6, vcc
	v_cndmask_b32_e32 v6, v6, v8, vcc
	v_max_u32_dpp v10, v5, v5 quad_perm:[1,0,3,2] row_mask:0xf bank_mask:0xf bound_ctrl:1
	v_cndmask_b32_e32 v8, v8, v4, vcc
	v_cndmask_b32_e32 v4, v4, v9, vcc
	v_max_u32_dpp v10, v10, v10 quad_perm:[2,3,0,1] row_mask:0xf bank_mask:0xf bound_ctrl:1
	v_cndmask_b32_e32 v9, v9, v3, vcc
	v_cndmask_b32_e32 v3, v3, v2, vcc
	v_max_u32_dpp v10, v10, v10 row_half_mirror row_mask:0xf bank_mask:0xf bound_ctrl:1
	v_cndmask_b32_e64 v2, v2, 0, vcc
	s_nop 0
	v_max_u32_dpp v10, v10, v10 row_mirror row_mask:0xf bank_mask:0xf bound_ctrl:1
	v_cmp_eq_u32_e32 vcc, v5, v10
	v_cndmask_b32_e64 v11, v11, v10, s[14:15]
	s_nop 0
	v_cndmask_b32_e32 v5, v5, v7, vcc
	v_cndmask_b32_e32 v7, v7, v6, vcc
	v_cndmask_b32_e32 v6, v6, v8, vcc
	v_max_u32_dpp v10, v5, v5 quad_perm:[1,0,3,2] row_mask:0xf bank_mask:0xf bound_ctrl:1
	v_cndmask_b32_e32 v8, v8, v4, vcc
	v_cndmask_b32_e32 v4, v4, v9, vcc
	v_max_u32_dpp v10, v10, v10 quad_perm:[2,3,0,1] row_mask:0xf bank_mask:0xf bound_ctrl:1
	v_cndmask_b32_e32 v9, v9, v3, vcc
	v_cndmask_b32_e32 v3, v3, v2, vcc
	v_max_u32_dpp v10, v10, v10 row_half_mirror row_mask:0xf bank_mask:0xf bound_ctrl:1
	v_cndmask_b32_e64 v2, v2, 0, vcc
	s_nop 0
	v_max_u32_dpp v10, v10, v10 row_mirror row_mask:0xf bank_mask:0xf bound_ctrl:1
	v_cmp_eq_u32_e32 vcc, v5, v10
	v_cndmask_b32_e64 v11, v11, v10, s[16:17]
	s_nop 0
	v_cndmask_b32_e32 v5, v5, v7, vcc
	v_cndmask_b32_e32 v7, v7, v6, vcc
	v_cndmask_b32_e32 v6, v6, v8, vcc
	v_max_u32_dpp v10, v5, v5 quad_perm:[1,0,3,2] row_mask:0xf bank_mask:0xf bound_ctrl:1
	v_cndmask_b32_e32 v8, v8, v4, vcc
	v_cndmask_b32_e32 v4, v4, v9, vcc
	v_max_u32_dpp v10, v10, v10 quad_perm:[2,3,0,1] row_mask:0xf bank_mask:0xf bound_ctrl:1
	v_cndmask_b32_e32 v9, v9, v3, vcc
	v_cndmask_b32_e32 v3, v3, v2, vcc
	v_max_u32_dpp v10, v10, v10 row_half_mirror row_mask:0xf bank_mask:0xf bound_ctrl:1
	v_cndmask_b32_e64 v2, v2, 0, vcc
	s_nop 0
	v_max_u32_dpp v10, v10, v10 row_mirror row_mask:0xf bank_mask:0xf bound_ctrl:1
	v_cmp_eq_u32_e32 vcc, v5, v10
	v_cndmask_b32_e64 v11, v11, v10, s[18:19]
	s_nop 0
	v_cndmask_b32_e32 v5, v5, v7, vcc
	v_cndmask_b32_e32 v7, v7, v6, vcc
	v_cndmask_b32_e32 v6, v6, v8, vcc
	v_max_u32_dpp v10, v5, v5 quad_perm:[1,0,3,2] row_mask:0xf bank_mask:0xf bound_ctrl:1
	v_cndmask_b32_e32 v8, v8, v4, vcc
	v_cndmask_b32_e32 v4, v4, v9, vcc
	v_max_u32_dpp v10, v10, v10 quad_perm:[2,3,0,1] row_mask:0xf bank_mask:0xf bound_ctrl:1
	v_cndmask_b32_e32 v9, v9, v3, vcc
	v_cndmask_b32_e32 v3, v3, v2, vcc
	v_max_u32_dpp v10, v10, v10 row_half_mirror row_mask:0xf bank_mask:0xf bound_ctrl:1
	v_cndmask_b32_e64 v2, v2, 0, vcc
	s_nop 0
	v_max_u32_dpp v10, v10, v10 row_mirror row_mask:0xf bank_mask:0xf bound_ctrl:1
	v_cmp_eq_u32_e32 vcc, v5, v10
	v_cndmask_b32_e64 v11, v11, v10, s[20:21]
	s_nop 0
	v_cndmask_b32_e32 v5, v5, v7, vcc
	v_cndmask_b32_e32 v7, v7, v6, vcc
	v_cndmask_b32_e32 v6, v6, v8, vcc
	v_max_u32_dpp v10, v5, v5 quad_perm:[1,0,3,2] row_mask:0xf bank_mask:0xf bound_ctrl:1
	v_cndmask_b32_e32 v8, v8, v4, vcc
	v_cndmask_b32_e32 v4, v4, v9, vcc
	v_max_u32_dpp v10, v10, v10 quad_perm:[2,3,0,1] row_mask:0xf bank_mask:0xf bound_ctrl:1
	v_cndmask_b32_e32 v9, v9, v3, vcc
	v_cndmask_b32_e32 v3, v3, v2, vcc
	v_max_u32_dpp v10, v10, v10 row_half_mirror row_mask:0xf bank_mask:0xf bound_ctrl:1
	v_cndmask_b32_e64 v2, v2, 0, vcc
	s_nop 0
	v_max_u32_dpp v10, v10, v10 row_mirror row_mask:0xf bank_mask:0xf bound_ctrl:1
	v_cmp_eq_u32_e32 vcc, v5, v10
	v_cndmask_b32_e64 v11, v11, v10, s[22:23]
	s_nop 0
	v_cndmask_b32_e32 v5, v5, v7, vcc
	v_cndmask_b32_e32 v7, v7, v6, vcc
	v_cndmask_b32_e32 v6, v6, v8, vcc
	v_max_u32_dpp v10, v5, v5 quad_perm:[1,0,3,2] row_mask:0xf bank_mask:0xf bound_ctrl:1
	v_cndmask_b32_e32 v8, v8, v4, vcc
	v_cndmask_b32_e32 v4, v4, v9, vcc
	v_max_u32_dpp v10, v10, v10 quad_perm:[2,3,0,1] row_mask:0xf bank_mask:0xf bound_ctrl:1
	v_cndmask_b32_e32 v9, v9, v3, vcc
	v_cndmask_b32_e32 v3, v3, v2, vcc
	v_max_u32_dpp v10, v10, v10 row_half_mirror row_mask:0xf bank_mask:0xf bound_ctrl:1
	v_cndmask_b32_e64 v2, v2, 0, vcc
	s_nop 0
	v_max_u32_dpp v10, v10, v10 row_mirror row_mask:0xf bank_mask:0xf bound_ctrl:1
	v_cmp_eq_u32_e32 vcc, v5, v10
	v_cndmask_b32_e64 v11, v11, v10, s[24:25]
	s_nop 0
	v_cndmask_b32_e32 v5, v5, v7, vcc
	v_cndmask_b32_e32 v7, v7, v6, vcc
	v_cndmask_b32_e32 v6, v6, v8, vcc
	v_cndmask_b32_e32 v8, v8, v4, vcc
	v_cndmask_b32_e32 v4, v4, v9, vcc
	v_cndmask_b32_e32 v9, v9, v3, vcc
	v_cndmask_b32_e32 v2, v3, v2, vcc
	v_max_u32_dpp v3, v5, v5 quad_perm:[1,0,3,2] row_mask:0xf bank_mask:0xf bound_ctrl:1
	s_nop 1
	v_max_u32_dpp v3, v3, v3 quad_perm:[2,3,0,1] row_mask:0xf bank_mask:0xf bound_ctrl:1
	s_nop 1
	v_max_u32_dpp v3, v3, v3 row_half_mirror row_mask:0xf bank_mask:0xf bound_ctrl:1
	s_nop 1
	v_max_u32_dpp v3, v3, v3 row_mirror row_mask:0xf bank_mask:0xf bound_ctrl:1
	v_cmp_eq_u32_e32 vcc, v5, v3
	v_cndmask_b32_e64 v10, v11, v3, s[26:27]
	s_nop 0
	v_cndmask_b32_e32 v3, v5, v7, vcc
	v_cndmask_b32_e32 v5, v7, v6, vcc
	v_cndmask_b32_e32 v6, v6, v8, vcc
	v_cndmask_b32_e32 v7, v8, v4, vcc
	v_max_u32_dpp v8, v3, v3 quad_perm:[1,0,3,2] row_mask:0xf bank_mask:0xf bound_ctrl:1
	v_cndmask_b32_e32 v4, v4, v9, vcc
	v_cndmask_b32_e32 v2, v9, v2, vcc
	v_max_u32_dpp v8, v8, v8 quad_perm:[2,3,0,1] row_mask:0xf bank_mask:0xf bound_ctrl:1
	s_nop 1
	v_max_u32_dpp v8, v8, v8 row_half_mirror row_mask:0xf bank_mask:0xf bound_ctrl:1
	s_nop 1
	v_max_u32_dpp v8, v8, v8 row_mirror row_mask:0xf bank_mask:0xf bound_ctrl:1
	v_cmp_eq_u32_e32 vcc, v3, v8
	v_cndmask_b32_e64 v9, v10, v8, s[28:29]
	s_nop 0
	v_cndmask_b32_e32 v3, v3, v5, vcc
	v_cndmask_b32_e32 v5, v5, v6, vcc
	v_cndmask_b32_e32 v6, v6, v7, vcc
	v_cndmask_b32_e32 v7, v7, v4, vcc
	v_cndmask_b32_e32 v2, v4, v2, vcc
	v_max_u32_dpp v4, v3, v3 quad_perm:[1,0,3,2] row_mask:0xf bank_mask:0xf bound_ctrl:1
	s_nop 1
	v_max_u32_dpp v4, v4, v4 quad_perm:[2,3,0,1] row_mask:0xf bank_mask:0xf bound_ctrl:1
	s_nop 1
	v_max_u32_dpp v4, v4, v4 row_half_mirror row_mask:0xf bank_mask:0xf bound_ctrl:1
	s_nop 1
	v_max_u32_dpp v4, v4, v4 row_mirror row_mask:0xf bank_mask:0xf bound_ctrl:1
	v_cmp_eq_u32_e32 vcc, v3, v4
	v_cndmask_b32_e64 v8, v9, v4, s[30:31]
	s_nop 0
	v_cndmask_b32_e32 v3, v3, v5, vcc
	v_cndmask_b32_e32 v4, v5, v6, vcc
	v_cndmask_b32_e32 v5, v6, v7, vcc
	v_max_u32_dpp v6, v3, v3 quad_perm:[1,0,3,2] row_mask:0xf bank_mask:0xf bound_ctrl:1
	v_cndmask_b32_e32 v2, v7, v2, vcc
	s_nop 0
	v_max_u32_dpp v6, v6, v6 quad_perm:[2,3,0,1] row_mask:0xf bank_mask:0xf bound_ctrl:1
	s_nop 1
	v_max_u32_dpp v6, v6, v6 row_half_mirror row_mask:0xf bank_mask:0xf bound_ctrl:1
	s_nop 1
	v_max_u32_dpp v6, v6, v6 row_mirror row_mask:0xf bank_mask:0xf bound_ctrl:1
	v_cmp_eq_u32_e32 vcc, v3, v6
	v_cndmask_b32_e64 v7, v8, v6, s[34:35]
	s_nop 0
	v_cndmask_b32_e32 v3, v3, v4, vcc
	v_cndmask_b32_e32 v4, v4, v5, vcc
	v_cndmask_b32_e32 v2, v5, v2, vcc
	v_max_u32_dpp v5, v3, v3 quad_perm:[1,0,3,2] row_mask:0xf bank_mask:0xf bound_ctrl:1
	s_nop 1
	v_max_u32_dpp v5, v5, v5 quad_perm:[2,3,0,1] row_mask:0xf bank_mask:0xf bound_ctrl:1
	s_nop 1
	v_max_u32_dpp v5, v5, v5 row_half_mirror row_mask:0xf bank_mask:0xf bound_ctrl:1
	s_nop 1
	v_max_u32_dpp v5, v5, v5 row_mirror row_mask:0xf bank_mask:0xf bound_ctrl:1
	v_cmp_eq_u32_e32 vcc, v3, v5
	v_cndmask_b32_e64 v6, v7, v5, s[36:37]
	s_nop 0
	v_cndmask_b32_e32 v3, v3, v4, vcc
	v_cndmask_b32_e32 v2, v4, v2, vcc
	s_nop 0
	v_max_u32_dpp v4, v3, v3 quad_perm:[1,0,3,2] row_mask:0xf bank_mask:0xf bound_ctrl:1
	s_nop 1
	v_max_u32_dpp v4, v4, v4 quad_perm:[2,3,0,1] row_mask:0xf bank_mask:0xf bound_ctrl:1
	s_nop 1
	v_max_u32_dpp v4, v4, v4 row_half_mirror row_mask:0xf bank_mask:0xf bound_ctrl:1
	s_nop 1
	v_max_u32_dpp v4, v4, v4 row_mirror row_mask:0xf bank_mask:0xf bound_ctrl:1
	v_cmp_eq_u32_e32 vcc, v3, v4
	v_cndmask_b32_e64 v5, v6, v4, s[38:39]
	s_nop 0
	v_cndmask_b32_e32 v2, v3, v2, vcc
	s_nop 1
	v_max_u32_dpp v2, v2, v2 quad_perm:[1,0,3,2] row_mask:0xf bank_mask:0xf bound_ctrl:1
	s_nop 1
	v_max_u32_dpp v2, v2, v2 quad_perm:[2,3,0,1] row_mask:0xf bank_mask:0xf bound_ctrl:1
	s_nop 1
	v_max_u32_dpp v2, v2, v2 row_half_mirror row_mask:0xf bank_mask:0xf bound_ctrl:1
	s_nop 1
	v_max_u32_dpp v2, v2, v2 row_mirror row_mask:0xf bank_mask:0xf bound_ctrl:1
	v_cndmask_b32_e64 v80, v5, v2, s[40:41]
	s_waitcnt vmcnt(0)
	v_mov_b32_e32 v14, v216
	v_mov_b32_e32 v15, v217
	v_mov_b32_e32 v16, v218
	v_mov_b32_e32 v17, v219
	v_mov_b32_e32 v10, v220
	v_mov_b32_e32 v11, v221
	v_mov_b32_e32 v12, v222
	v_mov_b32_e32 v13, v223
	v_mov_b32_e32 v6, v224
	v_mov_b32_e32 v7, v225
	v_mov_b32_e32 v8, v226
	v_mov_b32_e32 v9, v227
	v_mov_b32_e32 v2, v228
	v_mov_b32_e32 v3, v229
	v_mov_b32_e32 v4, v230
	v_mov_b32_e32 v5, v231
	ds_read_b128 v[18:21], v65 offset:36864
	ds_read_b128 v[22:25], v65 offset:36928
	s_waitcnt vmcnt(3) lgkmcnt(1)
	v_mfma_f32_16x16x32_bf16 v[18:21], v[14:17], v[18:21], 0
	ds_read_b128 v[26:29], v65 offset:41536
	ds_read_b128 v[30:33], v65 offset:46144
	ds_read_b128 v[34:37], v65 offset:50752
	s_waitcnt vmcnt(2) lgkmcnt(3)
	v_mfma_f32_16x16x32_bf16 v[18:21], v[10:13], v[22:25], v[18:21]
	ds_read_b128 v[22:25], v65 offset:36992
	ds_read_b128 v[38:41], v65 offset:55360
	ds_read_b128 v[42:45], v65 offset:59968
	s_waitcnt vmcnt(1) lgkmcnt(2)
	v_mfma_f32_16x16x32_bf16 v[18:21], v[6:9], v[22:25], v[18:21]
	ds_read_b128 v[22:25], v65 offset:37056
	ds_read_b128 v[84:87], v65 offset:64576
	s_waitcnt vmcnt(0) lgkmcnt(1)
	v_mfma_f32_16x16x32_bf16 v[18:21], v[2:5], v[22:25], v[18:21]
	ds_read_b128 v[22:25], v65 offset:41472
	s_waitcnt lgkmcnt(0)
	v_mfma_f32_16x16x32_bf16 v[22:25], v[14:17], v[22:25], 0
	v_mfma_f32_16x16x32_bf16 v[22:25], v[10:13], v[26:29], v[22:25]
	ds_read_b128 v[26:29], v65 offset:41600
	s_waitcnt lgkmcnt(0)
	v_mfma_f32_16x16x32_bf16 v[22:25], v[6:9], v[26:29], v[22:25]
	ds_read_b128 v[26:29], v65 offset:41664
	s_waitcnt lgkmcnt(0)
	v_mfma_f32_16x16x32_bf16 v[22:25], v[2:5], v[26:29], v[22:25]
	ds_read_b128 v[26:29], v65 offset:46080
	s_waitcnt lgkmcnt(0)
	v_mfma_f32_16x16x32_bf16 v[26:29], v[14:17], v[26:29], 0
	v_mfma_f32_16x16x32_bf16 v[26:29], v[10:13], v[30:33], v[26:29]
	ds_read_b128 v[30:33], v65 offset:46208
	s_waitcnt lgkmcnt(0)
	v_mfma_f32_16x16x32_bf16 v[26:29], v[6:9], v[30:33], v[26:29]
	ds_read_b128 v[30:33], v65 offset:46272
	s_waitcnt lgkmcnt(0)
	v_mfma_f32_16x16x32_bf16 v[26:29], v[2:5], v[30:33], v[26:29]
	ds_read_b128 v[30:33], v65 offset:50688
	s_waitcnt lgkmcnt(0)
	v_mfma_f32_16x16x32_bf16 v[30:33], v[14:17], v[30:33], 0
	v_mfma_f32_16x16x32_bf16 v[30:33], v[10:13], v[34:37], v[30:33]
	ds_read_b128 v[34:37], v65 offset:50816
	s_waitcnt lgkmcnt(0)
	v_mfma_f32_16x16x32_bf16 v[30:33], v[6:9], v[34:37], v[30:33]
	ds_read_b128 v[34:37], v65 offset:50880
	s_waitcnt lgkmcnt(0)
	v_mfma_f32_16x16x32_bf16 v[30:33], v[2:5], v[34:37], v[30:33]
	ds_read_b128 v[34:37], v65 offset:55296
	s_waitcnt lgkmcnt(0)
	v_mfma_f32_16x16x32_bf16 v[34:37], v[14:17], v[34:37], 0
	v_mfma_f32_16x16x32_bf16 v[34:37], v[10:13], v[38:41], v[34:37]
	ds_read_b128 v[38:41], v65 offset:55424
	s_waitcnt lgkmcnt(0)
	v_mfma_f32_16x16x32_bf16 v[34:37], v[6:9], v[38:41], v[34:37]
	ds_read_b128 v[38:41], v65 offset:55488
	s_waitcnt lgkmcnt(0)
	v_mfma_f32_16x16x32_bf16 v[34:37], v[2:5], v[38:41], v[34:37]
	ds_read_b128 v[38:41], v65 offset:59904
	s_waitcnt lgkmcnt(0)
	v_mfma_f32_16x16x32_bf16 v[38:41], v[14:17], v[38:41], 0
	v_mfma_f32_16x16x32_bf16 v[38:41], v[10:13], v[42:45], v[38:41]
	ds_read_b128 v[42:45], v65 offset:60032
	s_waitcnt lgkmcnt(0)
	v_mfma_f32_16x16x32_bf16 v[38:41], v[6:9], v[42:45], v[38:41]
	ds_read_b128 v[42:45], v65 offset:60096
	s_waitcnt lgkmcnt(0)
	v_mfma_f32_16x16x32_bf16 v[38:41], v[2:5], v[42:45], v[38:41]
	ds_read_b128 v[42:45], v65 offset:64512
	s_waitcnt lgkmcnt(0)
	v_mfma_f32_16x16x32_bf16 v[42:45], v[14:17], v[42:45], 0
	v_mfma_f32_16x16x32_bf16 v[42:45], v[10:13], v[84:87], v[42:45]
	ds_read_b128 v[84:87], v65 offset:64640
	s_waitcnt lgkmcnt(0)
	v_mfma_f32_16x16x32_bf16 v[42:45], v[6:9], v[84:87], v[42:45]
	ds_read_b128 v[84:87], v65 offset:64704
	s_waitcnt lgkmcnt(0)
	v_mfma_f32_16x16x32_bf16 v[42:45], v[2:5], v[84:87], v[42:45]
	ds_read_b128 v[84:87], v73
	s_waitcnt lgkmcnt(0)
	v_mfma_f32_16x16x32_bf16 v[14:17], v[14:17], v[84:87], 0
	ds_read_b128 v[84:87], v74
	s_waitcnt lgkmcnt(0)
	v_mfma_f32_16x16x32_bf16 v[10:13], v[10:13], v[84:87], v[14:17]
	s_nop 4
	ds_read_b128 v[14:17], v75
	s_waitcnt lgkmcnt(0)
	v_mfma_f32_16x16x32_bf16 v[6:9], v[6:9], v[14:17], v[10:13]
	s_nop 2
	ds_read_b128 v[10:13], v76
	s_waitcnt lgkmcnt(0)
	v_mfma_f32_16x16x32_bf16 v[2:5], v[2:5], v[10:13], v[6:9]
	v_ashrrev_i32_e32 v10, 31, v34
	s_nop 1
	v_ashrrev_i32_e32 v6, 31, v18
	v_ashrrev_i32_e32 v7, 31, v22
	v_ashrrev_i32_e32 v8, 31, v26
	v_ashrrev_i32_e32 v9, 31, v30
	v_ashrrev_i32_e32 v11, 31, v38
	v_ashrrev_i32_e32 v12, 31, v42
	v_ashrrev_i32_e32 v13, 31, v2
	v_bitop3_b32 v6, v6, v18, s87 bitop3:0x36
	v_bitop3_b32 v7, v7, v22, s87 bitop3:0x36
	v_bitop3_b32 v8, v8, v26, s87 bitop3:0x36
	v_bitop3_b32 v9, v9, v30, s87 bitop3:0x36
	v_bitop3_b32 v10, v10, v34, s87 bitop3:0x36
	v_bitop3_b32 v11, v11, v38, s87 bitop3:0x36
	v_bitop3_b32 v12, v12, v42, s87 bitop3:0x36
	v_bitop3_b32 v2, v13, v2, s87 bitop3:0x36
	v_and_or_b32 v6, v6, s96, v61
	v_and_or_b32 v7, v7, s96, v66
	v_and_or_b32 v8, v8, s96, v67
	v_and_or_b32 v9, v9, s96, v68
	v_and_or_b32 v10, v10, s96, v69
	v_and_or_b32 v11, v11, s96, v70
	v_and_or_b32 v12, v12, s96, v71
	v_and_or_b32 v2, v2, s96, v72
	v_max_u32_e32 v13, v6, v7
	v_min_u32_e32 v6, v6, v7
	v_max_u32_e32 v7, v8, v9
	v_min_u32_e32 v8, v8, v9
	v_max_u32_e32 v9, v10, v11
	v_min_u32_e32 v10, v10, v11
	v_max_u32_e32 v11, v12, v2
	v_min_u32_e32 v2, v12, v2
	v_max_u32_e32 v12, v13, v7
	v_min_u32_e32 v7, v13, v7
	v_max_u32_e32 v13, v6, v8
	v_min_u32_e32 v6, v6, v8
	v_max_u32_e32 v8, v9, v11
	v_min_u32_e32 v9, v9, v11
	v_max_u32_e32 v11, v10, v2
	v_min_u32_e32 v2, v10, v2
	v_max_u32_e32 v10, v13, v7
	v_min_u32_e32 v7, v13, v7
	v_max_u32_e32 v13, v11, v9
	v_min_u32_e32 v9, v11, v9
	v_max_u32_e32 v11, v12, v8
	v_min_u32_e32 v8, v12, v8
	v_max_u32_e32 v12, v10, v13
	v_min_u32_e32 v10, v10, v13
	v_max_u32_e32 v13, v7, v9
	v_min_u32_e32 v7, v7, v9
	v_max_u32_e32 v9, v6, v2
	v_min_u32_e32 v2, v6, v2
	v_max_u32_e32 v6, v13, v8
	v_min_u32_e32 v8, v13, v8
	v_max_u32_e32 v13, v9, v10
	v_min_u32_e32 v9, v9, v10
	v_max_u32_e32 v10, v12, v6
	v_min_u32_e32 v6, v12, v6
	v_max_u32_e32 v12, v13, v8
	v_min_u32_e32 v8, v13, v8
	v_max_u32_e32 v13, v9, v7
	v_min_u32_e32 v7, v9, v7
	v_max_u32_dpp v9, v11, v11 quad_perm:[1,0,3,2] row_mask:0xf bank_mask:0xf bound_ctrl:1
	s_nop 1
	v_max_u32_dpp v9, v9, v9 quad_perm:[2,3,0,1] row_mask:0xf bank_mask:0xf bound_ctrl:1
	s_nop 1
	v_max_u32_dpp v9, v9, v9 row_half_mirror row_mask:0xf bank_mask:0xf bound_ctrl:1
	s_nop 1
	v_max_u32_dpp v9, v9, v9 row_mirror row_mask:0xf bank_mask:0xf bound_ctrl:1
	v_cmp_eq_u32_e32 vcc, v11, v9
	v_cndmask_b32_e64 v14, 0, v9, s[8:9]
	s_nop 0
	v_cndmask_b32_e32 v9, v11, v10, vcc
	v_cndmask_b32_e32 v10, v10, v6, vcc
	v_cndmask_b32_e32 v6, v6, v12, vcc
	v_cndmask_b32_e32 v11, v12, v8, vcc
	v_cndmask_b32_e32 v8, v8, v13, vcc
	v_cndmask_b32_e32 v12, v13, v7, vcc
	v_max_u32_dpp v13, v9, v9 quad_perm:[1,0,3,2] row_mask:0xf bank_mask:0xf bound_ctrl:1
	v_cndmask_b32_e32 v7, v7, v2, vcc
	v_cndmask_b32_e64 v2, v2, 0, vcc
	v_max_u32_dpp v13, v13, v13 quad_perm:[2,3,0,1] row_mask:0xf bank_mask:0xf bound_ctrl:1
	s_nop 1
	v_max_u32_dpp v13, v13, v13 row_half_mirror row_mask:0xf bank_mask:0xf bound_ctrl:1
	s_nop 1
	v_max_u32_dpp v13, v13, v13 row_mirror row_mask:0xf bank_mask:0xf bound_ctrl:1
	v_cmp_eq_u32_e32 vcc, v9, v13
	v_cndmask_b32_e64 v14, v14, v13, s[10:11]
	s_nop 0
	v_cndmask_b32_e32 v9, v9, v10, vcc
	v_cndmask_b32_e32 v10, v10, v6, vcc
	v_cndmask_b32_e32 v6, v6, v11, vcc
	v_max_u32_dpp v13, v9, v9 quad_perm:[1,0,3,2] row_mask:0xf bank_mask:0xf bound_ctrl:1
	v_cndmask_b32_e32 v11, v11, v8, vcc
	v_cndmask_b32_e32 v8, v8, v12, vcc
	v_max_u32_dpp v13, v13, v13 quad_perm:[2,3,0,1] row_mask:0xf bank_mask:0xf bound_ctrl:1
	v_cndmask_b32_e32 v12, v12, v7, vcc
	v_cndmask_b32_e32 v7, v7, v2, vcc
	v_max_u32_dpp v13, v13, v13 row_half_mirror row_mask:0xf bank_mask:0xf bound_ctrl:1
	v_cndmask_b32_e64 v2, v2, 0, vcc
	s_nop 0
	v_max_u32_dpp v13, v13, v13 row_mirror row_mask:0xf bank_mask:0xf bound_ctrl:1
	v_cmp_eq_u32_e32 vcc, v9, v13
	v_cndmask_b32_e64 v14, v14, v13, s[12:13]
	s_nop 0
	v_cndmask_b32_e32 v9, v9, v10, vcc
	v_cndmask_b32_e32 v10, v10, v6, vcc
	v_cndmask_b32_e32 v6, v6, v11, vcc
	v_max_u32_dpp v13, v9, v9 quad_perm:[1,0,3,2] row_mask:0xf bank_mask:0xf bound_ctrl:1
	v_cndmask_b32_e32 v11, v11, v8, vcc
	v_cndmask_b32_e32 v8, v8, v12, vcc
	v_max_u32_dpp v13, v13, v13 quad_perm:[2,3,0,1] row_mask:0xf bank_mask:0xf bound_ctrl:1
	v_cndmask_b32_e32 v12, v12, v7, vcc
	v_cndmask_b32_e32 v7, v7, v2, vcc
	v_max_u32_dpp v13, v13, v13 row_half_mirror row_mask:0xf bank_mask:0xf bound_ctrl:1
	v_cndmask_b32_e64 v2, v2, 0, vcc
	s_nop 0
	v_max_u32_dpp v13, v13, v13 row_mirror row_mask:0xf bank_mask:0xf bound_ctrl:1
	v_cmp_eq_u32_e32 vcc, v9, v13
	v_cndmask_b32_e64 v14, v14, v13, s[14:15]
	s_nop 0
	v_cndmask_b32_e32 v9, v9, v10, vcc
	v_cndmask_b32_e32 v10, v10, v6, vcc
	v_cndmask_b32_e32 v6, v6, v11, vcc
	v_max_u32_dpp v13, v9, v9 quad_perm:[1,0,3,2] row_mask:0xf bank_mask:0xf bound_ctrl:1
	v_cndmask_b32_e32 v11, v11, v8, vcc
	v_cndmask_b32_e32 v8, v8, v12, vcc
	v_max_u32_dpp v13, v13, v13 quad_perm:[2,3,0,1] row_mask:0xf bank_mask:0xf bound_ctrl:1
	v_cndmask_b32_e32 v12, v12, v7, vcc
	v_cndmask_b32_e32 v7, v7, v2, vcc
	v_max_u32_dpp v13, v13, v13 row_half_mirror row_mask:0xf bank_mask:0xf bound_ctrl:1
	v_cndmask_b32_e64 v2, v2, 0, vcc
	s_nop 0
	v_max_u32_dpp v13, v13, v13 row_mirror row_mask:0xf bank_mask:0xf bound_ctrl:1
	v_cmp_eq_u32_e32 vcc, v9, v13
	v_cndmask_b32_e64 v14, v14, v13, s[16:17]
	s_nop 0
	v_cndmask_b32_e32 v9, v9, v10, vcc
	v_cndmask_b32_e32 v10, v10, v6, vcc
	v_cndmask_b32_e32 v6, v6, v11, vcc
	v_max_u32_dpp v13, v9, v9 quad_perm:[1,0,3,2] row_mask:0xf bank_mask:0xf bound_ctrl:1
	v_cndmask_b32_e32 v11, v11, v8, vcc
	v_cndmask_b32_e32 v8, v8, v12, vcc
	v_max_u32_dpp v13, v13, v13 quad_perm:[2,3,0,1] row_mask:0xf bank_mask:0xf bound_ctrl:1
	v_cndmask_b32_e32 v12, v12, v7, vcc
	v_cndmask_b32_e32 v7, v7, v2, vcc
	v_max_u32_dpp v13, v13, v13 row_half_mirror row_mask:0xf bank_mask:0xf bound_ctrl:1
	v_cndmask_b32_e64 v2, v2, 0, vcc
	s_nop 0
	v_max_u32_dpp v13, v13, v13 row_mirror row_mask:0xf bank_mask:0xf bound_ctrl:1
	v_cmp_eq_u32_e32 vcc, v9, v13
	v_cndmask_b32_e64 v14, v14, v13, s[18:19]
	s_nop 0
	v_cndmask_b32_e32 v9, v9, v10, vcc
	v_cndmask_b32_e32 v10, v10, v6, vcc
	v_cndmask_b32_e32 v6, v6, v11, vcc
	v_max_u32_dpp v13, v9, v9 quad_perm:[1,0,3,2] row_mask:0xf bank_mask:0xf bound_ctrl:1
	v_cndmask_b32_e32 v11, v11, v8, vcc
	v_cndmask_b32_e32 v8, v8, v12, vcc
	v_max_u32_dpp v13, v13, v13 quad_perm:[2,3,0,1] row_mask:0xf bank_mask:0xf bound_ctrl:1
	v_cndmask_b32_e32 v12, v12, v7, vcc
	v_cndmask_b32_e32 v7, v7, v2, vcc
	v_max_u32_dpp v13, v13, v13 row_half_mirror row_mask:0xf bank_mask:0xf bound_ctrl:1
	v_cndmask_b32_e64 v2, v2, 0, vcc
	s_nop 0
	v_max_u32_dpp v13, v13, v13 row_mirror row_mask:0xf bank_mask:0xf bound_ctrl:1
	v_cmp_eq_u32_e32 vcc, v9, v13
	v_cndmask_b32_e64 v14, v14, v13, s[20:21]
	s_nop 0
	v_cndmask_b32_e32 v9, v9, v10, vcc
	v_cndmask_b32_e32 v10, v10, v6, vcc
	v_cndmask_b32_e32 v6, v6, v11, vcc
	v_max_u32_dpp v13, v9, v9 quad_perm:[1,0,3,2] row_mask:0xf bank_mask:0xf bound_ctrl:1
	v_cndmask_b32_e32 v11, v11, v8, vcc
	v_cndmask_b32_e32 v8, v8, v12, vcc
	v_max_u32_dpp v13, v13, v13 quad_perm:[2,3,0,1] row_mask:0xf bank_mask:0xf bound_ctrl:1
	v_cndmask_b32_e32 v12, v12, v7, vcc
	v_cndmask_b32_e32 v7, v7, v2, vcc
	v_max_u32_dpp v13, v13, v13 row_half_mirror row_mask:0xf bank_mask:0xf bound_ctrl:1
	v_cndmask_b32_e64 v2, v2, 0, vcc
	s_nop 0
	v_max_u32_dpp v13, v13, v13 row_mirror row_mask:0xf bank_mask:0xf bound_ctrl:1
	v_cmp_eq_u32_e32 vcc, v9, v13
	v_cndmask_b32_e64 v14, v14, v13, s[22:23]
	s_nop 0
	v_cndmask_b32_e32 v9, v9, v10, vcc
	v_cndmask_b32_e32 v10, v10, v6, vcc
	v_cndmask_b32_e32 v6, v6, v11, vcc
	v_max_u32_dpp v13, v9, v9 quad_perm:[1,0,3,2] row_mask:0xf bank_mask:0xf bound_ctrl:1
	v_cndmask_b32_e32 v11, v11, v8, vcc
	v_cndmask_b32_e32 v8, v8, v12, vcc
	v_max_u32_dpp v13, v13, v13 quad_perm:[2,3,0,1] row_mask:0xf bank_mask:0xf bound_ctrl:1
	v_cndmask_b32_e32 v12, v12, v7, vcc
	v_cndmask_b32_e32 v7, v7, v2, vcc
	v_max_u32_dpp v13, v13, v13 row_half_mirror row_mask:0xf bank_mask:0xf bound_ctrl:1
	v_cndmask_b32_e64 v2, v2, 0, vcc
	s_nop 0
	v_max_u32_dpp v13, v13, v13 row_mirror row_mask:0xf bank_mask:0xf bound_ctrl:1
	v_cmp_eq_u32_e32 vcc, v9, v13
	v_cndmask_b32_e64 v14, v14, v13, s[24:25]
	s_nop 0
	v_cndmask_b32_e32 v9, v9, v10, vcc
	v_cndmask_b32_e32 v10, v10, v6, vcc
	v_cndmask_b32_e32 v6, v6, v11, vcc
	v_cndmask_b32_e32 v11, v11, v8, vcc
	v_cndmask_b32_e32 v8, v8, v12, vcc
	v_cndmask_b32_e32 v12, v12, v7, vcc
	v_cndmask_b32_e32 v2, v7, v2, vcc
	v_max_u32_dpp v7, v9, v9 quad_perm:[1,0,3,2] row_mask:0xf bank_mask:0xf bound_ctrl:1
	s_nop 1
	v_max_u32_dpp v7, v7, v7 quad_perm:[2,3,0,1] row_mask:0xf bank_mask:0xf bound_ctrl:1
	s_nop 1
	v_max_u32_dpp v7, v7, v7 row_half_mirror row_mask:0xf bank_mask:0xf bound_ctrl:1
	s_nop 1
	v_max_u32_dpp v7, v7, v7 row_mirror row_mask:0xf bank_mask:0xf bound_ctrl:1
	v_cmp_eq_u32_e32 vcc, v9, v7
	v_cndmask_b32_e64 v13, v14, v7, s[26:27]
	s_nop 0
	v_cndmask_b32_e32 v7, v9, v10, vcc
	v_cndmask_b32_e32 v9, v10, v6, vcc
	v_cndmask_b32_e32 v6, v6, v11, vcc
	v_cndmask_b32_e32 v10, v11, v8, vcc
	v_max_u32_dpp v11, v7, v7 quad_perm:[1,0,3,2] row_mask:0xf bank_mask:0xf bound_ctrl:1
	v_cndmask_b32_e32 v8, v8, v12, vcc
	v_cndmask_b32_e32 v2, v12, v2, vcc
	v_max_u32_dpp v11, v11, v11 quad_perm:[2,3,0,1] row_mask:0xf bank_mask:0xf bound_ctrl:1
	s_nop 1
	v_max_u32_dpp v11, v11, v11 row_half_mirror row_mask:0xf bank_mask:0xf bound_ctrl:1
	s_nop 1
	v_max_u32_dpp v11, v11, v11 row_mirror row_mask:0xf bank_mask:0xf bound_ctrl:1
	v_cmp_eq_u32_e32 vcc, v7, v11
	v_cndmask_b32_e64 v12, v13, v11, s[28:29]
	v_ashrrev_i32_e32 v13, 31, v3
	v_cndmask_b32_e32 v7, v7, v9, vcc
	v_cndmask_b32_e32 v9, v9, v6, vcc
	v_cndmask_b32_e32 v6, v6, v10, vcc
	v_cndmask_b32_e32 v10, v10, v8, vcc
	v_cndmask_b32_e32 v2, v8, v2, vcc
	v_max_u32_dpp v8, v7, v7 quad_perm:[1,0,3,2] row_mask:0xf bank_mask:0xf bound_ctrl:1
	v_bitop3_b32 v3, v13, v3, s87 bitop3:0x36
	v_and_or_b32 v3, v3, s96, v72
	v_max_u32_dpp v8, v8, v8 quad_perm:[2,3,0,1] row_mask:0xf bank_mask:0xf bound_ctrl:1
	s_nop 1
	v_max_u32_dpp v8, v8, v8 row_half_mirror row_mask:0xf bank_mask:0xf bound_ctrl:1
	s_nop 1
	v_max_u32_dpp v8, v8, v8 row_mirror row_mask:0xf bank_mask:0xf bound_ctrl:1
	v_cmp_eq_u32_e32 vcc, v7, v8
	v_cndmask_b32_e64 v11, v12, v8, s[30:31]
	v_ashrrev_i32_e32 v12, 31, v43
	v_cndmask_b32_e32 v7, v7, v9, vcc
	v_cndmask_b32_e32 v8, v9, v6, vcc
	v_cndmask_b32_e32 v6, v6, v10, vcc
	v_max_u32_dpp v9, v7, v7 quad_perm:[1,0,3,2] row_mask:0xf bank_mask:0xf bound_ctrl:1
	v_cndmask_b32_e32 v2, v10, v2, vcc
	v_bitop3_b32 v12, v12, v43, s87 bitop3:0x36
	v_max_u32_dpp v9, v9, v9 quad_perm:[2,3,0,1] row_mask:0xf bank_mask:0xf bound_ctrl:1
	v_and_or_b32 v12, v12, s96, v71
	s_nop 0
	v_max_u32_dpp v9, v9, v9 row_half_mirror row_mask:0xf bank_mask:0xf bound_ctrl:1
	s_nop 1
	v_max_u32_dpp v9, v9, v9 row_mirror row_mask:0xf bank_mask:0xf bound_ctrl:1
	v_cmp_eq_u32_e32 vcc, v7, v9
	v_cndmask_b32_e64 v10, v11, v9, s[34:35]
	v_ashrrev_i32_e32 v11, 31, v39
	v_cndmask_b32_e32 v7, v7, v8, vcc
	v_cndmask_b32_e32 v8, v8, v6, vcc
	v_cndmask_b32_e32 v2, v6, v2, vcc
	v_max_u32_dpp v6, v7, v7 quad_perm:[1,0,3,2] row_mask:0xf bank_mask:0xf bound_ctrl:1
	v_bitop3_b32 v11, v11, v39, s87 bitop3:0x36
	v_and_or_b32 v11, v11, s96, v70
	v_max_u32_dpp v6, v6, v6 quad_perm:[2,3,0,1] row_mask:0xf bank_mask:0xf bound_ctrl:1
	s_nop 1
	v_max_u32_dpp v6, v6, v6 row_half_mirror row_mask:0xf bank_mask:0xf bound_ctrl:1
	s_nop 1
	v_max_u32_dpp v6, v6, v6 row_mirror row_mask:0xf bank_mask:0xf bound_ctrl:1
	v_cmp_eq_u32_e32 vcc, v7, v6
	v_cndmask_b32_e64 v9, v10, v6, s[36:37]
	v_ashrrev_i32_e32 v10, 31, v35
	v_cndmask_b32_e32 v6, v7, v8, vcc
	v_cndmask_b32_e32 v2, v8, v2, vcc
	v_bitop3_b32 v10, v10, v35, s87 bitop3:0x36
	v_max_u32_dpp v7, v6, v6 quad_perm:[1,0,3,2] row_mask:0xf bank_mask:0xf bound_ctrl:1
	v_and_or_b32 v10, v10, s96, v69
	s_nop 0
	v_max_u32_dpp v7, v7, v7 quad_perm:[2,3,0,1] row_mask:0xf bank_mask:0xf bound_ctrl:1
	s_nop 1
	v_max_u32_dpp v7, v7, v7 row_half_mirror row_mask:0xf bank_mask:0xf bound_ctrl:1
	s_nop 1
	v_max_u32_dpp v7, v7, v7 row_mirror row_mask:0xf bank_mask:0xf bound_ctrl:1
	v_cmp_eq_u32_e32 vcc, v6, v7
	v_cndmask_b32_e64 v8, v9, v7, s[38:39]
	v_ashrrev_i32_e32 v7, 31, v27
	v_cndmask_b32_e32 v2, v6, v2, vcc
	v_ashrrev_i32_e32 v6, 31, v23
	v_ashrrev_i32_e32 v9, 31, v31
	v_max_u32_dpp v2, v2, v2 quad_perm:[1,0,3,2] row_mask:0xf bank_mask:0xf bound_ctrl:1
	v_bitop3_b32 v6, v6, v23, s87 bitop3:0x36
	v_bitop3_b32 v7, v7, v27, s87 bitop3:0x36
	v_max_u32_dpp v2, v2, v2 quad_perm:[2,3,0,1] row_mask:0xf bank_mask:0xf bound_ctrl:1
	v_bitop3_b32 v9, v9, v31, s87 bitop3:0x36
	v_and_or_b32 v6, v6, s96, v66
	v_max_u32_dpp v2, v2, v2 row_half_mirror row_mask:0xf bank_mask:0xf bound_ctrl:1
	v_and_or_b32 v7, v7, s96, v67
	v_and_or_b32 v9, v9, s96, v68
	v_max_u32_dpp v2, v2, v2 row_mirror row_mask:0xf bank_mask:0xf bound_ctrl:1
	v_cndmask_b32_e64 v8, v8, v2, s[40:41]
	v_ashrrev_i32_e32 v2, 31, v19
	v_bitop3_b32 v2, v2, v19, s87 bitop3:0x36
	v_and_or_b32 v2, v2, s96, v61
	v_max_u32_e32 v13, v2, v6
	v_min_u32_e32 v2, v2, v6
	v_max_u32_e32 v6, v7, v9
	v_min_u32_e32 v7, v7, v9
	v_max_u32_e32 v9, v10, v11
	v_min_u32_e32 v10, v10, v11
	v_max_u32_e32 v11, v12, v3
	v_min_u32_e32 v3, v12, v3
	v_max_u32_e32 v12, v13, v6
	v_min_u32_e32 v6, v13, v6
	v_max_u32_e32 v13, v2, v7
	v_min_u32_e32 v2, v2, v7
	v_max_u32_e32 v7, v9, v11
	v_min_u32_e32 v9, v9, v11
	v_max_u32_e32 v11, v10, v3
	v_min_u32_e32 v3, v10, v3
	v_max_u32_e32 v10, v13, v6
	v_min_u32_e32 v6, v13, v6
	v_max_u32_e32 v13, v11, v9
	v_min_u32_e32 v9, v11, v9
	v_max_u32_e32 v11, v12, v7
	v_min_u32_e32 v7, v12, v7
	v_max_u32_e32 v12, v10, v13
	v_min_u32_e32 v10, v10, v13
	v_max_u32_e32 v13, v6, v9
	v_min_u32_e32 v6, v6, v9
	v_max_u32_e32 v9, v2, v3
	v_min_u32_e32 v2, v2, v3
	v_max_u32_e32 v3, v13, v7
	v_min_u32_e32 v7, v13, v7
	v_max_u32_e32 v13, v9, v10
	v_min_u32_e32 v9, v9, v10
	v_max_u32_e32 v10, v12, v3
	v_min_u32_e32 v3, v12, v3
	v_max_u32_e32 v12, v13, v7
	v_min_u32_e32 v7, v13, v7
	v_max_u32_e32 v13, v9, v6
	v_min_u32_e32 v6, v9, v6
	v_max_u32_dpp v9, v11, v11 quad_perm:[1,0,3,2] row_mask:0xf bank_mask:0xf bound_ctrl:1
	s_nop 1
	v_max_u32_dpp v9, v9, v9 quad_perm:[2,3,0,1] row_mask:0xf bank_mask:0xf bound_ctrl:1
	s_nop 1
	v_max_u32_dpp v9, v9, v9 row_half_mirror row_mask:0xf bank_mask:0xf bound_ctrl:1
	s_nop 1
	v_max_u32_dpp v9, v9, v9 row_mirror row_mask:0xf bank_mask:0xf bound_ctrl:1
	v_cmp_eq_u32_e32 vcc, v11, v9
	v_cndmask_b32_e64 v14, 0, v9, s[8:9]
	s_nop 0
	v_cndmask_b32_e32 v9, v11, v10, vcc
	v_cndmask_b32_e32 v10, v10, v3, vcc
	v_cndmask_b32_e32 v3, v3, v12, vcc
	v_cndmask_b32_e32 v11, v12, v7, vcc
	v_cndmask_b32_e32 v7, v7, v13, vcc
	v_cndmask_b32_e32 v12, v13, v6, vcc
	v_max_u32_dpp v13, v9, v9 quad_perm:[1,0,3,2] row_mask:0xf bank_mask:0xf bound_ctrl:1
	v_cndmask_b32_e32 v6, v6, v2, vcc
	v_cndmask_b32_e64 v2, v2, 0, vcc
	v_max_u32_dpp v13, v13, v13 quad_perm:[2,3,0,1] row_mask:0xf bank_mask:0xf bound_ctrl:1
	s_nop 1
	v_max_u32_dpp v13, v13, v13 row_half_mirror row_mask:0xf bank_mask:0xf bound_ctrl:1
	s_nop 1
	v_max_u32_dpp v13, v13, v13 row_mirror row_mask:0xf bank_mask:0xf bound_ctrl:1
	v_cmp_eq_u32_e32 vcc, v9, v13
	v_cndmask_b32_e64 v14, v14, v13, s[10:11]
	s_nop 0
	v_cndmask_b32_e32 v9, v9, v10, vcc
	v_cndmask_b32_e32 v10, v10, v3, vcc
	v_cndmask_b32_e32 v3, v3, v11, vcc
	v_max_u32_dpp v13, v9, v9 quad_perm:[1,0,3,2] row_mask:0xf bank_mask:0xf bound_ctrl:1
	v_cndmask_b32_e32 v11, v11, v7, vcc
	v_cndmask_b32_e32 v7, v7, v12, vcc
	v_max_u32_dpp v13, v13, v13 quad_perm:[2,3,0,1] row_mask:0xf bank_mask:0xf bound_ctrl:1
	v_cndmask_b32_e32 v12, v12, v6, vcc
	v_cndmask_b32_e32 v6, v6, v2, vcc
	v_max_u32_dpp v13, v13, v13 row_half_mirror row_mask:0xf bank_mask:0xf bound_ctrl:1
	v_cndmask_b32_e64 v2, v2, 0, vcc
	s_nop 0
	v_max_u32_dpp v13, v13, v13 row_mirror row_mask:0xf bank_mask:0xf bound_ctrl:1
	v_cmp_eq_u32_e32 vcc, v9, v13
	v_cndmask_b32_e64 v14, v14, v13, s[12:13]
	s_nop 0
	v_cndmask_b32_e32 v9, v9, v10, vcc
	v_cndmask_b32_e32 v10, v10, v3, vcc
	v_cndmask_b32_e32 v3, v3, v11, vcc
	v_max_u32_dpp v13, v9, v9 quad_perm:[1,0,3,2] row_mask:0xf bank_mask:0xf bound_ctrl:1
	v_cndmask_b32_e32 v11, v11, v7, vcc
	v_cndmask_b32_e32 v7, v7, v12, vcc
	v_max_u32_dpp v13, v13, v13 quad_perm:[2,3,0,1] row_mask:0xf bank_mask:0xf bound_ctrl:1
	v_cndmask_b32_e32 v12, v12, v6, vcc
	v_cndmask_b32_e32 v6, v6, v2, vcc
	v_max_u32_dpp v13, v13, v13 row_half_mirror row_mask:0xf bank_mask:0xf bound_ctrl:1
	v_cndmask_b32_e64 v2, v2, 0, vcc
	s_nop 0
	v_max_u32_dpp v13, v13, v13 row_mirror row_mask:0xf bank_mask:0xf bound_ctrl:1
	v_cmp_eq_u32_e32 vcc, v9, v13
	v_cndmask_b32_e64 v14, v14, v13, s[14:15]
	s_nop 0
	v_cndmask_b32_e32 v9, v9, v10, vcc
	v_cndmask_b32_e32 v10, v10, v3, vcc
	v_cndmask_b32_e32 v3, v3, v11, vcc
	v_max_u32_dpp v13, v9, v9 quad_perm:[1,0,3,2] row_mask:0xf bank_mask:0xf bound_ctrl:1
	v_cndmask_b32_e32 v11, v11, v7, vcc
	v_cndmask_b32_e32 v7, v7, v12, vcc
	v_max_u32_dpp v13, v13, v13 quad_perm:[2,3,0,1] row_mask:0xf bank_mask:0xf bound_ctrl:1
	v_cndmask_b32_e32 v12, v12, v6, vcc
	v_cndmask_b32_e32 v6, v6, v2, vcc
	v_max_u32_dpp v13, v13, v13 row_half_mirror row_mask:0xf bank_mask:0xf bound_ctrl:1
	v_cndmask_b32_e64 v2, v2, 0, vcc
	s_nop 0
	v_max_u32_dpp v13, v13, v13 row_mirror row_mask:0xf bank_mask:0xf bound_ctrl:1
	v_cmp_eq_u32_e32 vcc, v9, v13
	v_cndmask_b32_e64 v14, v14, v13, s[16:17]
	s_nop 0
	v_cndmask_b32_e32 v9, v9, v10, vcc
	v_cndmask_b32_e32 v10, v10, v3, vcc
	v_cndmask_b32_e32 v3, v3, v11, vcc
	v_max_u32_dpp v13, v9, v9 quad_perm:[1,0,3,2] row_mask:0xf bank_mask:0xf bound_ctrl:1
	v_cndmask_b32_e32 v11, v11, v7, vcc
	v_cndmask_b32_e32 v7, v7, v12, vcc
	v_max_u32_dpp v13, v13, v13 quad_perm:[2,3,0,1] row_mask:0xf bank_mask:0xf bound_ctrl:1
	v_cndmask_b32_e32 v12, v12, v6, vcc
	v_cndmask_b32_e32 v6, v6, v2, vcc
	v_max_u32_dpp v13, v13, v13 row_half_mirror row_mask:0xf bank_mask:0xf bound_ctrl:1
	v_cndmask_b32_e64 v2, v2, 0, vcc
	s_nop 0
	v_max_u32_dpp v13, v13, v13 row_mirror row_mask:0xf bank_mask:0xf bound_ctrl:1
	v_cmp_eq_u32_e32 vcc, v9, v13
	v_cndmask_b32_e64 v14, v14, v13, s[18:19]
	s_nop 0
	v_cndmask_b32_e32 v9, v9, v10, vcc
	v_cndmask_b32_e32 v10, v10, v3, vcc
	v_cndmask_b32_e32 v3, v3, v11, vcc
	v_max_u32_dpp v13, v9, v9 quad_perm:[1,0,3,2] row_mask:0xf bank_mask:0xf bound_ctrl:1
	v_cndmask_b32_e32 v11, v11, v7, vcc
	v_cndmask_b32_e32 v7, v7, v12, vcc
	v_max_u32_dpp v13, v13, v13 quad_perm:[2,3,0,1] row_mask:0xf bank_mask:0xf bound_ctrl:1
	v_cndmask_b32_e32 v12, v12, v6, vcc
	v_cndmask_b32_e32 v6, v6, v2, vcc
	v_max_u32_dpp v13, v13, v13 row_half_mirror row_mask:0xf bank_mask:0xf bound_ctrl:1
	v_cndmask_b32_e64 v2, v2, 0, vcc
	s_nop 0
	v_max_u32_dpp v13, v13, v13 row_mirror row_mask:0xf bank_mask:0xf bound_ctrl:1
	v_cmp_eq_u32_e32 vcc, v9, v13
	v_cndmask_b32_e64 v14, v14, v13, s[20:21]
	s_nop 0
	v_cndmask_b32_e32 v9, v9, v10, vcc
	v_cndmask_b32_e32 v10, v10, v3, vcc
	v_cndmask_b32_e32 v3, v3, v11, vcc
	v_max_u32_dpp v13, v9, v9 quad_perm:[1,0,3,2] row_mask:0xf bank_mask:0xf bound_ctrl:1
	v_cndmask_b32_e32 v11, v11, v7, vcc
	v_cndmask_b32_e32 v7, v7, v12, vcc
	v_max_u32_dpp v13, v13, v13 quad_perm:[2,3,0,1] row_mask:0xf bank_mask:0xf bound_ctrl:1
	v_cndmask_b32_e32 v12, v12, v6, vcc
	v_cndmask_b32_e32 v6, v6, v2, vcc
	v_max_u32_dpp v13, v13, v13 row_half_mirror row_mask:0xf bank_mask:0xf bound_ctrl:1
	v_cndmask_b32_e64 v2, v2, 0, vcc
	s_nop 0
	v_max_u32_dpp v13, v13, v13 row_mirror row_mask:0xf bank_mask:0xf bound_ctrl:1
	v_cmp_eq_u32_e32 vcc, v9, v13
	v_cndmask_b32_e64 v14, v14, v13, s[22:23]
	s_nop 0
	v_cndmask_b32_e32 v9, v9, v10, vcc
	v_cndmask_b32_e32 v10, v10, v3, vcc
	v_cndmask_b32_e32 v3, v3, v11, vcc
	v_max_u32_dpp v13, v9, v9 quad_perm:[1,0,3,2] row_mask:0xf bank_mask:0xf bound_ctrl:1
	v_cndmask_b32_e32 v11, v11, v7, vcc
	v_cndmask_b32_e32 v7, v7, v12, vcc
	v_max_u32_dpp v13, v13, v13 quad_perm:[2,3,0,1] row_mask:0xf bank_mask:0xf bound_ctrl:1
	v_cndmask_b32_e32 v12, v12, v6, vcc
	v_cndmask_b32_e32 v6, v6, v2, vcc
	v_max_u32_dpp v13, v13, v13 row_half_mirror row_mask:0xf bank_mask:0xf bound_ctrl:1
	v_cndmask_b32_e64 v2, v2, 0, vcc
	s_nop 0
	v_max_u32_dpp v13, v13, v13 row_mirror row_mask:0xf bank_mask:0xf bound_ctrl:1
	v_cmp_eq_u32_e32 vcc, v9, v13
	v_cndmask_b32_e64 v14, v14, v13, s[24:25]
	s_nop 0
	v_cndmask_b32_e32 v9, v9, v10, vcc
	v_cndmask_b32_e32 v10, v10, v3, vcc
	v_cndmask_b32_e32 v3, v3, v11, vcc
	v_cndmask_b32_e32 v11, v11, v7, vcc
	v_cndmask_b32_e32 v7, v7, v12, vcc
	v_cndmask_b32_e32 v12, v12, v6, vcc
	v_cndmask_b32_e32 v2, v6, v2, vcc
	v_max_u32_dpp v6, v9, v9 quad_perm:[1,0,3,2] row_mask:0xf bank_mask:0xf bound_ctrl:1
	s_nop 1
	v_max_u32_dpp v6, v6, v6 quad_perm:[2,3,0,1] row_mask:0xf bank_mask:0xf bound_ctrl:1
	s_nop 1
	v_max_u32_dpp v6, v6, v6 row_half_mirror row_mask:0xf bank_mask:0xf bound_ctrl:1
	s_nop 1
	v_max_u32_dpp v6, v6, v6 row_mirror row_mask:0xf bank_mask:0xf bound_ctrl:1
	v_cmp_eq_u32_e32 vcc, v9, v6
	v_cndmask_b32_e64 v13, v14, v6, s[26:27]
	s_nop 0
	v_cndmask_b32_e32 v6, v9, v10, vcc
	v_cndmask_b32_e32 v9, v10, v3, vcc
	v_cndmask_b32_e32 v3, v3, v11, vcc
	v_cndmask_b32_e32 v10, v11, v7, vcc
	v_max_u32_dpp v11, v6, v6 quad_perm:[1,0,3,2] row_mask:0xf bank_mask:0xf bound_ctrl:1
	v_cndmask_b32_e32 v7, v7, v12, vcc
	v_cndmask_b32_e32 v2, v12, v2, vcc
	v_max_u32_dpp v11, v11, v11 quad_perm:[2,3,0,1] row_mask:0xf bank_mask:0xf bound_ctrl:1
	s_nop 1
	v_max_u32_dpp v11, v11, v11 row_half_mirror row_mask:0xf bank_mask:0xf bound_ctrl:1
	s_nop 1
	v_max_u32_dpp v11, v11, v11 row_mirror row_mask:0xf bank_mask:0xf bound_ctrl:1
	v_cmp_eq_u32_e32 vcc, v6, v11
	v_cndmask_b32_e64 v12, v13, v11, s[28:29]
	v_ashrrev_i32_e32 v13, 31, v4
	v_cndmask_b32_e32 v6, v6, v9, vcc
	v_cndmask_b32_e32 v9, v9, v3, vcc
	v_cndmask_b32_e32 v3, v3, v10, vcc
	v_cndmask_b32_e32 v10, v10, v7, vcc
	v_cndmask_b32_e32 v2, v7, v2, vcc
	v_max_u32_dpp v7, v6, v6 quad_perm:[1,0,3,2] row_mask:0xf bank_mask:0xf bound_ctrl:1
	v_bitop3_b32 v4, v13, v4, s87 bitop3:0x36
	v_and_or_b32 v4, v4, s96, v72
	v_max_u32_dpp v7, v7, v7 quad_perm:[2,3,0,1] row_mask:0xf bank_mask:0xf bound_ctrl:1
	s_nop 1
	v_max_u32_dpp v7, v7, v7 row_half_mirror row_mask:0xf bank_mask:0xf bound_ctrl:1
	s_nop 1
	v_max_u32_dpp v7, v7, v7 row_mirror row_mask:0xf bank_mask:0xf bound_ctrl:1
	v_cmp_eq_u32_e32 vcc, v6, v7
	v_cndmask_b32_e64 v11, v12, v7, s[30:31]
	v_ashrrev_i32_e32 v12, 31, v44
	v_cndmask_b32_e32 v6, v6, v9, vcc
	v_cndmask_b32_e32 v7, v9, v3, vcc
	v_cndmask_b32_e32 v3, v3, v10, vcc
	v_max_u32_dpp v9, v6, v6 quad_perm:[1,0,3,2] row_mask:0xf bank_mask:0xf bound_ctrl:1
	v_cndmask_b32_e32 v2, v10, v2, vcc
	v_bitop3_b32 v12, v12, v44, s87 bitop3:0x36
	v_max_u32_dpp v9, v9, v9 quad_perm:[2,3,0,1] row_mask:0xf bank_mask:0xf bound_ctrl:1
	v_and_or_b32 v12, v12, s96, v71
	s_nop 0
	v_max_u32_dpp v9, v9, v9 row_half_mirror row_mask:0xf bank_mask:0xf bound_ctrl:1
	s_nop 1
	v_max_u32_dpp v9, v9, v9 row_mirror row_mask:0xf bank_mask:0xf bound_ctrl:1
	v_cmp_eq_u32_e32 vcc, v6, v9
	v_cndmask_b32_e64 v10, v11, v9, s[34:35]
	v_ashrrev_i32_e32 v11, 31, v40
	v_cndmask_b32_e32 v6, v6, v7, vcc
	v_cndmask_b32_e32 v7, v7, v3, vcc
	v_cndmask_b32_e32 v2, v3, v2, vcc
	v_max_u32_dpp v3, v6, v6 quad_perm:[1,0,3,2] row_mask:0xf bank_mask:0xf bound_ctrl:1
	v_bitop3_b32 v11, v11, v40, s87 bitop3:0x36
	v_and_or_b32 v11, v11, s96, v70
	v_max_u32_dpp v3, v3, v3 quad_perm:[2,3,0,1] row_mask:0xf bank_mask:0xf bound_ctrl:1
	s_nop 1
	v_max_u32_dpp v3, v3, v3 row_half_mirror row_mask:0xf bank_mask:0xf bound_ctrl:1
	s_nop 1
	v_max_u32_dpp v3, v3, v3 row_mirror row_mask:0xf bank_mask:0xf bound_ctrl:1
	v_cmp_eq_u32_e32 vcc, v6, v3
	v_cndmask_b32_e64 v9, v10, v3, s[36:37]
	v_ashrrev_i32_e32 v10, 31, v36
	v_cndmask_b32_e32 v3, v6, v7, vcc
	v_cndmask_b32_e32 v2, v7, v2, vcc
	v_bitop3_b32 v10, v10, v36, s87 bitop3:0x36
	v_max_u32_dpp v6, v3, v3 quad_perm:[1,0,3,2] row_mask:0xf bank_mask:0xf bound_ctrl:1
	v_and_or_b32 v10, v10, s96, v69
	s_nop 0
	v_max_u32_dpp v6, v6, v6 quad_perm:[2,3,0,1] row_mask:0xf bank_mask:0xf bound_ctrl:1
	s_nop 1
	v_max_u32_dpp v6, v6, v6 row_half_mirror row_mask:0xf bank_mask:0xf bound_ctrl:1
	s_nop 1
	v_max_u32_dpp v6, v6, v6 row_mirror row_mask:0xf bank_mask:0xf bound_ctrl:1
	v_cmp_eq_u32_e32 vcc, v3, v6
	v_cndmask_b32_e64 v7, v9, v6, s[38:39]
	v_ashrrev_i32_e32 v6, 31, v28
	v_cndmask_b32_e32 v2, v3, v2, vcc
	v_ashrrev_i32_e32 v3, 31, v24
	v_ashrrev_i32_e32 v9, 31, v32
	v_max_u32_dpp v2, v2, v2 quad_perm:[1,0,3,2] row_mask:0xf bank_mask:0xf bound_ctrl:1
	v_bitop3_b32 v3, v3, v24, s87 bitop3:0x36
	v_bitop3_b32 v6, v6, v28, s87 bitop3:0x36
	v_max_u32_dpp v2, v2, v2 quad_perm:[2,3,0,1] row_mask:0xf bank_mask:0xf bound_ctrl:1
	v_bitop3_b32 v9, v9, v32, s87 bitop3:0x36
	v_and_or_b32 v3, v3, s96, v66
	v_max_u32_dpp v2, v2, v2 row_half_mirror row_mask:0xf bank_mask:0xf bound_ctrl:1
	v_and_or_b32 v6, v6, s96, v67
	v_and_or_b32 v9, v9, s96, v68
	v_max_u32_dpp v2, v2, v2 row_mirror row_mask:0xf bank_mask:0xf bound_ctrl:1
	v_cndmask_b32_e64 v7, v7, v2, s[40:41]
	v_ashrrev_i32_e32 v2, 31, v20
	v_bitop3_b32 v2, v2, v20, s87 bitop3:0x36
	v_and_or_b32 v2, v2, s96, v61
	v_max_u32_e32 v13, v2, v3
	v_min_u32_e32 v2, v2, v3
	v_max_u32_e32 v3, v6, v9
	v_min_u32_e32 v6, v6, v9
	v_max_u32_e32 v9, v10, v11
	v_min_u32_e32 v10, v10, v11
	v_max_u32_e32 v11, v12, v4
	v_min_u32_e32 v4, v12, v4
	v_max_u32_e32 v12, v13, v3
	v_min_u32_e32 v3, v13, v3
	v_max_u32_e32 v13, v2, v6
	v_min_u32_e32 v2, v2, v6
	v_max_u32_e32 v6, v9, v11
	v_min_u32_e32 v9, v9, v11
	v_max_u32_e32 v11, v10, v4
	v_min_u32_e32 v4, v10, v4
	v_max_u32_e32 v10, v13, v3
	v_min_u32_e32 v3, v13, v3
	v_max_u32_e32 v13, v11, v9
	v_min_u32_e32 v9, v11, v9
	v_max_u32_e32 v11, v12, v6
	v_min_u32_e32 v6, v12, v6
	v_max_u32_e32 v12, v10, v13
	v_min_u32_e32 v10, v10, v13
	v_max_u32_e32 v13, v3, v9
	v_min_u32_e32 v3, v3, v9
	v_max_u32_e32 v9, v2, v4
	v_min_u32_e32 v2, v2, v4
	v_max_u32_e32 v4, v13, v6
	v_min_u32_e32 v6, v13, v6
	v_max_u32_e32 v13, v9, v10
	v_min_u32_e32 v9, v9, v10
	v_max_u32_e32 v10, v12, v4
	v_min_u32_e32 v4, v12, v4
	v_max_u32_e32 v12, v13, v6
	v_min_u32_e32 v6, v13, v6
	v_max_u32_e32 v13, v9, v3
	v_min_u32_e32 v3, v9, v3
	v_max_u32_dpp v9, v11, v11 quad_perm:[1,0,3,2] row_mask:0xf bank_mask:0xf bound_ctrl:1
	s_nop 1
	v_max_u32_dpp v9, v9, v9 quad_perm:[2,3,0,1] row_mask:0xf bank_mask:0xf bound_ctrl:1
	s_nop 1
	v_max_u32_dpp v9, v9, v9 row_half_mirror row_mask:0xf bank_mask:0xf bound_ctrl:1
	s_nop 1
	v_max_u32_dpp v9, v9, v9 row_mirror row_mask:0xf bank_mask:0xf bound_ctrl:1
	v_cmp_eq_u32_e32 vcc, v11, v9
	v_cndmask_b32_e64 v14, 0, v9, s[8:9]
	s_nop 0
	v_cndmask_b32_e32 v9, v11, v10, vcc
	v_cndmask_b32_e32 v10, v10, v4, vcc
	v_cndmask_b32_e32 v4, v4, v12, vcc
	v_cndmask_b32_e32 v11, v12, v6, vcc
	v_cndmask_b32_e32 v6, v6, v13, vcc
	v_cndmask_b32_e32 v12, v13, v3, vcc
	v_max_u32_dpp v13, v9, v9 quad_perm:[1,0,3,2] row_mask:0xf bank_mask:0xf bound_ctrl:1
	v_cndmask_b32_e32 v3, v3, v2, vcc
	v_cndmask_b32_e64 v2, v2, 0, vcc
	v_max_u32_dpp v13, v13, v13 quad_perm:[2,3,0,1] row_mask:0xf bank_mask:0xf bound_ctrl:1
	s_nop 1
	v_max_u32_dpp v13, v13, v13 row_half_mirror row_mask:0xf bank_mask:0xf bound_ctrl:1
	s_nop 1
	v_max_u32_dpp v13, v13, v13 row_mirror row_mask:0xf bank_mask:0xf bound_ctrl:1
	v_cmp_eq_u32_e32 vcc, v9, v13
	v_cndmask_b32_e64 v14, v14, v13, s[10:11]
	s_nop 0
	v_cndmask_b32_e32 v9, v9, v10, vcc
	v_cndmask_b32_e32 v10, v10, v4, vcc
	v_cndmask_b32_e32 v4, v4, v11, vcc
	v_max_u32_dpp v13, v9, v9 quad_perm:[1,0,3,2] row_mask:0xf bank_mask:0xf bound_ctrl:1
	v_cndmask_b32_e32 v11, v11, v6, vcc
	v_cndmask_b32_e32 v6, v6, v12, vcc
	v_max_u32_dpp v13, v13, v13 quad_perm:[2,3,0,1] row_mask:0xf bank_mask:0xf bound_ctrl:1
	v_cndmask_b32_e32 v12, v12, v3, vcc
	v_cndmask_b32_e32 v3, v3, v2, vcc
	v_max_u32_dpp v13, v13, v13 row_half_mirror row_mask:0xf bank_mask:0xf bound_ctrl:1
	v_cndmask_b32_e64 v2, v2, 0, vcc
	s_nop 0
	v_max_u32_dpp v13, v13, v13 row_mirror row_mask:0xf bank_mask:0xf bound_ctrl:1
	v_cmp_eq_u32_e32 vcc, v9, v13
	v_cndmask_b32_e64 v14, v14, v13, s[12:13]
	s_nop 0
	v_cndmask_b32_e32 v9, v9, v10, vcc
	v_cndmask_b32_e32 v10, v10, v4, vcc
	v_cndmask_b32_e32 v4, v4, v11, vcc
	v_max_u32_dpp v13, v9, v9 quad_perm:[1,0,3,2] row_mask:0xf bank_mask:0xf bound_ctrl:1
	v_cndmask_b32_e32 v11, v11, v6, vcc
	v_cndmask_b32_e32 v6, v6, v12, vcc
	v_max_u32_dpp v13, v13, v13 quad_perm:[2,3,0,1] row_mask:0xf bank_mask:0xf bound_ctrl:1
	v_cndmask_b32_e32 v12, v12, v3, vcc
	v_cndmask_b32_e32 v3, v3, v2, vcc
	v_max_u32_dpp v13, v13, v13 row_half_mirror row_mask:0xf bank_mask:0xf bound_ctrl:1
	v_cndmask_b32_e64 v2, v2, 0, vcc
	s_nop 0
	v_max_u32_dpp v13, v13, v13 row_mirror row_mask:0xf bank_mask:0xf bound_ctrl:1
	v_cmp_eq_u32_e32 vcc, v9, v13
	v_cndmask_b32_e64 v14, v14, v13, s[14:15]
	s_nop 0
	v_cndmask_b32_e32 v9, v9, v10, vcc
	v_cndmask_b32_e32 v10, v10, v4, vcc
	v_cndmask_b32_e32 v4, v4, v11, vcc
	v_max_u32_dpp v13, v9, v9 quad_perm:[1,0,3,2] row_mask:0xf bank_mask:0xf bound_ctrl:1
	v_cndmask_b32_e32 v11, v11, v6, vcc
	v_cndmask_b32_e32 v6, v6, v12, vcc
	v_max_u32_dpp v13, v13, v13 quad_perm:[2,3,0,1] row_mask:0xf bank_mask:0xf bound_ctrl:1
	v_cndmask_b32_e32 v12, v12, v3, vcc
	v_cndmask_b32_e32 v3, v3, v2, vcc
	v_max_u32_dpp v13, v13, v13 row_half_mirror row_mask:0xf bank_mask:0xf bound_ctrl:1
	v_cndmask_b32_e64 v2, v2, 0, vcc
	s_nop 0
	v_max_u32_dpp v13, v13, v13 row_mirror row_mask:0xf bank_mask:0xf bound_ctrl:1
	v_cmp_eq_u32_e32 vcc, v9, v13
	v_cndmask_b32_e64 v14, v14, v13, s[16:17]
	s_nop 0
	v_cndmask_b32_e32 v9, v9, v10, vcc
	v_cndmask_b32_e32 v10, v10, v4, vcc
	v_cndmask_b32_e32 v4, v4, v11, vcc
	v_max_u32_dpp v13, v9, v9 quad_perm:[1,0,3,2] row_mask:0xf bank_mask:0xf bound_ctrl:1
	v_cndmask_b32_e32 v11, v11, v6, vcc
	v_cndmask_b32_e32 v6, v6, v12, vcc
	v_max_u32_dpp v13, v13, v13 quad_perm:[2,3,0,1] row_mask:0xf bank_mask:0xf bound_ctrl:1
	v_cndmask_b32_e32 v12, v12, v3, vcc
	v_cndmask_b32_e32 v3, v3, v2, vcc
	v_max_u32_dpp v13, v13, v13 row_half_mirror row_mask:0xf bank_mask:0xf bound_ctrl:1
	v_cndmask_b32_e64 v2, v2, 0, vcc
	s_nop 0
	v_max_u32_dpp v13, v13, v13 row_mirror row_mask:0xf bank_mask:0xf bound_ctrl:1
	v_cmp_eq_u32_e32 vcc, v9, v13
	v_cndmask_b32_e64 v14, v14, v13, s[18:19]
	s_nop 0
	v_cndmask_b32_e32 v9, v9, v10, vcc
	v_cndmask_b32_e32 v10, v10, v4, vcc
	v_cndmask_b32_e32 v4, v4, v11, vcc
	v_max_u32_dpp v13, v9, v9 quad_perm:[1,0,3,2] row_mask:0xf bank_mask:0xf bound_ctrl:1
	v_cndmask_b32_e32 v11, v11, v6, vcc
	v_cndmask_b32_e32 v6, v6, v12, vcc
	v_max_u32_dpp v13, v13, v13 quad_perm:[2,3,0,1] row_mask:0xf bank_mask:0xf bound_ctrl:1
	v_cndmask_b32_e32 v12, v12, v3, vcc
	v_cndmask_b32_e32 v3, v3, v2, vcc
	v_max_u32_dpp v13, v13, v13 row_half_mirror row_mask:0xf bank_mask:0xf bound_ctrl:1
	v_cndmask_b32_e64 v2, v2, 0, vcc
	s_nop 0
	v_max_u32_dpp v13, v13, v13 row_mirror row_mask:0xf bank_mask:0xf bound_ctrl:1
	v_cmp_eq_u32_e32 vcc, v9, v13
	v_cndmask_b32_e64 v14, v14, v13, s[20:21]
	s_nop 0
	v_cndmask_b32_e32 v9, v9, v10, vcc
	v_cndmask_b32_e32 v10, v10, v4, vcc
	v_cndmask_b32_e32 v4, v4, v11, vcc
	v_max_u32_dpp v13, v9, v9 quad_perm:[1,0,3,2] row_mask:0xf bank_mask:0xf bound_ctrl:1
	v_cndmask_b32_e32 v11, v11, v6, vcc
	v_cndmask_b32_e32 v6, v6, v12, vcc
	v_max_u32_dpp v13, v13, v13 quad_perm:[2,3,0,1] row_mask:0xf bank_mask:0xf bound_ctrl:1
	v_cndmask_b32_e32 v12, v12, v3, vcc
	v_cndmask_b32_e32 v3, v3, v2, vcc
	v_max_u32_dpp v13, v13, v13 row_half_mirror row_mask:0xf bank_mask:0xf bound_ctrl:1
	v_cndmask_b32_e64 v2, v2, 0, vcc
	s_nop 0
	v_max_u32_dpp v13, v13, v13 row_mirror row_mask:0xf bank_mask:0xf bound_ctrl:1
	v_cmp_eq_u32_e32 vcc, v9, v13
	v_cndmask_b32_e64 v14, v14, v13, s[22:23]
	s_nop 0
	v_cndmask_b32_e32 v9, v9, v10, vcc
	v_cndmask_b32_e32 v10, v10, v4, vcc
	v_cndmask_b32_e32 v4, v4, v11, vcc
	v_max_u32_dpp v13, v9, v9 quad_perm:[1,0,3,2] row_mask:0xf bank_mask:0xf bound_ctrl:1
	v_cndmask_b32_e32 v11, v11, v6, vcc
	v_cndmask_b32_e32 v6, v6, v12, vcc
	v_max_u32_dpp v13, v13, v13 quad_perm:[2,3,0,1] row_mask:0xf bank_mask:0xf bound_ctrl:1
	v_cndmask_b32_e32 v12, v12, v3, vcc
	v_cndmask_b32_e32 v3, v3, v2, vcc
	v_max_u32_dpp v13, v13, v13 row_half_mirror row_mask:0xf bank_mask:0xf bound_ctrl:1
	v_cndmask_b32_e64 v2, v2, 0, vcc
	s_nop 0
	v_max_u32_dpp v13, v13, v13 row_mirror row_mask:0xf bank_mask:0xf bound_ctrl:1
	v_cmp_eq_u32_e32 vcc, v9, v13
	v_cndmask_b32_e64 v14, v14, v13, s[24:25]
	s_nop 0
	v_cndmask_b32_e32 v9, v9, v10, vcc
	v_cndmask_b32_e32 v10, v10, v4, vcc
	v_cndmask_b32_e32 v4, v4, v11, vcc
	v_cndmask_b32_e32 v11, v11, v6, vcc
	v_cndmask_b32_e32 v6, v6, v12, vcc
	v_cndmask_b32_e32 v12, v12, v3, vcc
	v_cndmask_b32_e32 v2, v3, v2, vcc
	v_max_u32_dpp v3, v9, v9 quad_perm:[1,0,3,2] row_mask:0xf bank_mask:0xf bound_ctrl:1
	s_nop 1
	v_max_u32_dpp v3, v3, v3 quad_perm:[2,3,0,1] row_mask:0xf bank_mask:0xf bound_ctrl:1
	s_nop 1
	v_max_u32_dpp v3, v3, v3 row_half_mirror row_mask:0xf bank_mask:0xf bound_ctrl:1
	s_nop 1
	v_max_u32_dpp v3, v3, v3 row_mirror row_mask:0xf bank_mask:0xf bound_ctrl:1
	v_cmp_eq_u32_e32 vcc, v9, v3
	v_cndmask_b32_e64 v13, v14, v3, s[26:27]
	s_nop 0
	v_cndmask_b32_e32 v3, v9, v10, vcc
	v_cndmask_b32_e32 v9, v10, v4, vcc
	v_cndmask_b32_e32 v4, v4, v11, vcc
	v_cndmask_b32_e32 v10, v11, v6, vcc
	v_max_u32_dpp v11, v3, v3 quad_perm:[1,0,3,2] row_mask:0xf bank_mask:0xf bound_ctrl:1
	v_cndmask_b32_e32 v6, v6, v12, vcc
	v_cndmask_b32_e32 v2, v12, v2, vcc
	v_max_u32_dpp v11, v11, v11 quad_perm:[2,3,0,1] row_mask:0xf bank_mask:0xf bound_ctrl:1
	s_nop 1
	v_max_u32_dpp v11, v11, v11 row_half_mirror row_mask:0xf bank_mask:0xf bound_ctrl:1
	s_nop 1
	v_max_u32_dpp v11, v11, v11 row_mirror row_mask:0xf bank_mask:0xf bound_ctrl:1
	v_cmp_eq_u32_e32 vcc, v3, v11
	v_cndmask_b32_e64 v12, v13, v11, s[28:29]
	v_ashrrev_i32_e32 v13, 31, v5
	v_cndmask_b32_e32 v3, v3, v9, vcc
	v_cndmask_b32_e32 v9, v9, v4, vcc
	v_cndmask_b32_e32 v4, v4, v10, vcc
	v_cndmask_b32_e32 v10, v10, v6, vcc
	v_cndmask_b32_e32 v2, v6, v2, vcc
	v_max_u32_dpp v6, v3, v3 quad_perm:[1,0,3,2] row_mask:0xf bank_mask:0xf bound_ctrl:1
	v_bitop3_b32 v5, v13, v5, s87 bitop3:0x36
	v_and_or_b32 v5, v5, s96, v72
	v_max_u32_dpp v6, v6, v6 quad_perm:[2,3,0,1] row_mask:0xf bank_mask:0xf bound_ctrl:1
	s_nop 1
	v_max_u32_dpp v6, v6, v6 row_half_mirror row_mask:0xf bank_mask:0xf bound_ctrl:1
	s_nop 1
	v_max_u32_dpp v6, v6, v6 row_mirror row_mask:0xf bank_mask:0xf bound_ctrl:1
	v_cmp_eq_u32_e32 vcc, v3, v6
	v_cndmask_b32_e64 v11, v12, v6, s[30:31]
	v_ashrrev_i32_e32 v12, 31, v45
	v_cndmask_b32_e32 v3, v3, v9, vcc
	v_cndmask_b32_e32 v6, v9, v4, vcc
	v_cndmask_b32_e32 v4, v4, v10, vcc
	v_max_u32_dpp v9, v3, v3 quad_perm:[1,0,3,2] row_mask:0xf bank_mask:0xf bound_ctrl:1
	v_cndmask_b32_e32 v2, v10, v2, vcc
	v_bitop3_b32 v12, v12, v45, s87 bitop3:0x36
	v_max_u32_dpp v9, v9, v9 quad_perm:[2,3,0,1] row_mask:0xf bank_mask:0xf bound_ctrl:1
	v_and_or_b32 v12, v12, s96, v71
	s_nop 0
	v_max_u32_dpp v9, v9, v9 row_half_mirror row_mask:0xf bank_mask:0xf bound_ctrl:1
	s_nop 1
	v_max_u32_dpp v9, v9, v9 row_mirror row_mask:0xf bank_mask:0xf bound_ctrl:1
	v_cmp_eq_u32_e32 vcc, v3, v9
	v_cndmask_b32_e64 v10, v11, v9, s[34:35]
	v_ashrrev_i32_e32 v11, 31, v41
	v_cndmask_b32_e32 v3, v3, v6, vcc
	v_cndmask_b32_e32 v6, v6, v4, vcc
	v_cndmask_b32_e32 v2, v4, v2, vcc
	v_max_u32_dpp v4, v3, v3 quad_perm:[1,0,3,2] row_mask:0xf bank_mask:0xf bound_ctrl:1
	v_bitop3_b32 v11, v11, v41, s87 bitop3:0x36
	v_and_or_b32 v11, v11, s96, v70
	v_max_u32_dpp v4, v4, v4 quad_perm:[2,3,0,1] row_mask:0xf bank_mask:0xf bound_ctrl:1
	s_nop 1
	v_max_u32_dpp v4, v4, v4 row_half_mirror row_mask:0xf bank_mask:0xf bound_ctrl:1
	s_nop 1
	v_max_u32_dpp v4, v4, v4 row_mirror row_mask:0xf bank_mask:0xf bound_ctrl:1
	v_cmp_eq_u32_e32 vcc, v3, v4
	v_cndmask_b32_e64 v9, v10, v4, s[36:37]
	v_ashrrev_i32_e32 v10, 31, v37
	v_cndmask_b32_e32 v3, v3, v6, vcc
	v_cndmask_b32_e32 v2, v6, v2, vcc
	v_bitop3_b32 v10, v10, v37, s87 bitop3:0x36
	v_max_u32_dpp v4, v3, v3 quad_perm:[1,0,3,2] row_mask:0xf bank_mask:0xf bound_ctrl:1
	v_and_or_b32 v10, v10, s96, v69
	s_nop 0
	v_max_u32_dpp v4, v4, v4 quad_perm:[2,3,0,1] row_mask:0xf bank_mask:0xf bound_ctrl:1
	s_nop 1
	v_max_u32_dpp v4, v4, v4 row_half_mirror row_mask:0xf bank_mask:0xf bound_ctrl:1
	s_nop 1
	v_max_u32_dpp v4, v4, v4 row_mirror row_mask:0xf bank_mask:0xf bound_ctrl:1
	v_cmp_eq_u32_e32 vcc, v3, v4
	v_cndmask_b32_e64 v6, v9, v4, s[38:39]
	v_ashrrev_i32_e32 v4, 31, v29
	v_cndmask_b32_e32 v2, v3, v2, vcc
	v_ashrrev_i32_e32 v3, 31, v25
	v_ashrrev_i32_e32 v9, 31, v33
	v_max_u32_dpp v2, v2, v2 quad_perm:[1,0,3,2] row_mask:0xf bank_mask:0xf bound_ctrl:1
	v_bitop3_b32 v3, v3, v25, s87 bitop3:0x36
	v_bitop3_b32 v4, v4, v29, s87 bitop3:0x36
	v_max_u32_dpp v2, v2, v2 quad_perm:[2,3,0,1] row_mask:0xf bank_mask:0xf bound_ctrl:1
	v_bitop3_b32 v9, v9, v33, s87 bitop3:0x36
	v_and_or_b32 v3, v3, s96, v66
	v_max_u32_dpp v2, v2, v2 row_half_mirror row_mask:0xf bank_mask:0xf bound_ctrl:1
	v_and_or_b32 v4, v4, s96, v67
	v_and_or_b32 v9, v9, s96, v68
	v_max_u32_dpp v2, v2, v2 row_mirror row_mask:0xf bank_mask:0xf bound_ctrl:1
	v_cndmask_b32_e64 v6, v6, v2, s[40:41]
	v_ashrrev_i32_e32 v2, 31, v21
	v_bitop3_b32 v2, v2, v21, s87 bitop3:0x36
	v_and_or_b32 v2, v2, s96, v61
	v_max_u32_e32 v13, v2, v3
	v_min_u32_e32 v2, v2, v3
	v_max_u32_e32 v3, v4, v9
	v_min_u32_e32 v4, v4, v9
	v_max_u32_e32 v9, v10, v11
	v_min_u32_e32 v10, v10, v11
	v_max_u32_e32 v11, v12, v5
	v_min_u32_e32 v5, v12, v5
	v_max_u32_e32 v12, v13, v3
	v_min_u32_e32 v3, v13, v3
	v_max_u32_e32 v13, v2, v4
	v_min_u32_e32 v2, v2, v4
	v_max_u32_e32 v4, v9, v11
	v_min_u32_e32 v9, v9, v11
	v_max_u32_e32 v11, v10, v5
	v_min_u32_e32 v5, v10, v5
	v_max_u32_e32 v10, v13, v3
	v_min_u32_e32 v3, v13, v3
	v_max_u32_e32 v13, v11, v9
	v_min_u32_e32 v9, v11, v9
	v_max_u32_e32 v11, v12, v4
	v_min_u32_e32 v4, v12, v4
	v_max_u32_e32 v12, v10, v13
	v_min_u32_e32 v10, v10, v13
	v_max_u32_e32 v13, v3, v9
	v_min_u32_e32 v3, v3, v9
	v_max_u32_e32 v9, v2, v5
	v_min_u32_e32 v2, v2, v5
	v_max_u32_e32 v5, v13, v4
	v_min_u32_e32 v4, v13, v4
	v_max_u32_e32 v13, v9, v10
	v_min_u32_e32 v9, v9, v10
	v_max_u32_e32 v10, v12, v5
	v_min_u32_e32 v5, v12, v5
	v_max_u32_e32 v12, v13, v4
	v_min_u32_e32 v4, v13, v4
	v_max_u32_e32 v13, v9, v3
	v_min_u32_e32 v3, v9, v3
	v_max_u32_dpp v9, v11, v11 quad_perm:[1,0,3,2] row_mask:0xf bank_mask:0xf bound_ctrl:1
	s_nop 1
	v_max_u32_dpp v9, v9, v9 quad_perm:[2,3,0,1] row_mask:0xf bank_mask:0xf bound_ctrl:1
	s_nop 1
	v_max_u32_dpp v9, v9, v9 row_half_mirror row_mask:0xf bank_mask:0xf bound_ctrl:1
	s_nop 1
	v_max_u32_dpp v9, v9, v9 row_mirror row_mask:0xf bank_mask:0xf bound_ctrl:1
	v_cmp_eq_u32_e32 vcc, v11, v9
	v_cndmask_b32_e64 v14, 0, v9, s[8:9]
	s_nop 0
	v_cndmask_b32_e32 v9, v11, v10, vcc
	v_cndmask_b32_e32 v10, v10, v5, vcc
	v_cndmask_b32_e32 v5, v5, v12, vcc
	v_cndmask_b32_e32 v11, v12, v4, vcc
	v_cndmask_b32_e32 v4, v4, v13, vcc
	v_cndmask_b32_e32 v12, v13, v3, vcc
	v_max_u32_dpp v13, v9, v9 quad_perm:[1,0,3,2] row_mask:0xf bank_mask:0xf bound_ctrl:1
	v_cndmask_b32_e32 v3, v3, v2, vcc
	v_cndmask_b32_e64 v2, v2, 0, vcc
	v_max_u32_dpp v13, v13, v13 quad_perm:[2,3,0,1] row_mask:0xf bank_mask:0xf bound_ctrl:1
	s_nop 1
	v_max_u32_dpp v13, v13, v13 row_half_mirror row_mask:0xf bank_mask:0xf bound_ctrl:1
	s_nop 1
	v_max_u32_dpp v13, v13, v13 row_mirror row_mask:0xf bank_mask:0xf bound_ctrl:1
	v_cmp_eq_u32_e32 vcc, v9, v13
	v_cndmask_b32_e64 v14, v14, v13, s[10:11]
	s_nop 0
	v_cndmask_b32_e32 v9, v9, v10, vcc
	v_cndmask_b32_e32 v10, v10, v5, vcc
	v_cndmask_b32_e32 v5, v5, v11, vcc
	v_max_u32_dpp v13, v9, v9 quad_perm:[1,0,3,2] row_mask:0xf bank_mask:0xf bound_ctrl:1
	v_cndmask_b32_e32 v11, v11, v4, vcc
	v_cndmask_b32_e32 v4, v4, v12, vcc
	v_max_u32_dpp v13, v13, v13 quad_perm:[2,3,0,1] row_mask:0xf bank_mask:0xf bound_ctrl:1
	v_cndmask_b32_e32 v12, v12, v3, vcc
	v_cndmask_b32_e32 v3, v3, v2, vcc
	v_max_u32_dpp v13, v13, v13 row_half_mirror row_mask:0xf bank_mask:0xf bound_ctrl:1
	v_cndmask_b32_e64 v2, v2, 0, vcc
	s_nop 0
	v_max_u32_dpp v13, v13, v13 row_mirror row_mask:0xf bank_mask:0xf bound_ctrl:1
	v_cmp_eq_u32_e32 vcc, v9, v13
	v_cndmask_b32_e64 v14, v14, v13, s[12:13]
	s_nop 0
	v_cndmask_b32_e32 v9, v9, v10, vcc
	v_cndmask_b32_e32 v10, v10, v5, vcc
	v_cndmask_b32_e32 v5, v5, v11, vcc
	v_max_u32_dpp v13, v9, v9 quad_perm:[1,0,3,2] row_mask:0xf bank_mask:0xf bound_ctrl:1
	v_cndmask_b32_e32 v11, v11, v4, vcc
	v_cndmask_b32_e32 v4, v4, v12, vcc
	v_max_u32_dpp v13, v13, v13 quad_perm:[2,3,0,1] row_mask:0xf bank_mask:0xf bound_ctrl:1
	v_cndmask_b32_e32 v12, v12, v3, vcc
	v_cndmask_b32_e32 v3, v3, v2, vcc
	v_max_u32_dpp v13, v13, v13 row_half_mirror row_mask:0xf bank_mask:0xf bound_ctrl:1
	v_cndmask_b32_e64 v2, v2, 0, vcc
	s_nop 0
	v_max_u32_dpp v13, v13, v13 row_mirror row_mask:0xf bank_mask:0xf bound_ctrl:1
	v_cmp_eq_u32_e32 vcc, v9, v13
	v_cndmask_b32_e64 v14, v14, v13, s[14:15]
	s_nop 0
	v_cndmask_b32_e32 v9, v9, v10, vcc
	v_cndmask_b32_e32 v10, v10, v5, vcc
	v_cndmask_b32_e32 v5, v5, v11, vcc
	v_max_u32_dpp v13, v9, v9 quad_perm:[1,0,3,2] row_mask:0xf bank_mask:0xf bound_ctrl:1
	v_cndmask_b32_e32 v11, v11, v4, vcc
	v_cndmask_b32_e32 v4, v4, v12, vcc
	v_max_u32_dpp v13, v13, v13 quad_perm:[2,3,0,1] row_mask:0xf bank_mask:0xf bound_ctrl:1
	v_cndmask_b32_e32 v12, v12, v3, vcc
	v_cndmask_b32_e32 v3, v3, v2, vcc
	v_max_u32_dpp v13, v13, v13 row_half_mirror row_mask:0xf bank_mask:0xf bound_ctrl:1
	v_cndmask_b32_e64 v2, v2, 0, vcc
	s_nop 0
	v_max_u32_dpp v13, v13, v13 row_mirror row_mask:0xf bank_mask:0xf bound_ctrl:1
	v_cmp_eq_u32_e32 vcc, v9, v13
	v_cndmask_b32_e64 v14, v14, v13, s[16:17]
	s_nop 0
	v_cndmask_b32_e32 v9, v9, v10, vcc
	v_cndmask_b32_e32 v10, v10, v5, vcc
	v_cndmask_b32_e32 v5, v5, v11, vcc
	v_max_u32_dpp v13, v9, v9 quad_perm:[1,0,3,2] row_mask:0xf bank_mask:0xf bound_ctrl:1
	v_cndmask_b32_e32 v11, v11, v4, vcc
	v_cndmask_b32_e32 v4, v4, v12, vcc
	v_max_u32_dpp v13, v13, v13 quad_perm:[2,3,0,1] row_mask:0xf bank_mask:0xf bound_ctrl:1
	v_cndmask_b32_e32 v12, v12, v3, vcc
	v_cndmask_b32_e32 v3, v3, v2, vcc
	v_max_u32_dpp v13, v13, v13 row_half_mirror row_mask:0xf bank_mask:0xf bound_ctrl:1
	v_cndmask_b32_e64 v2, v2, 0, vcc
	s_nop 0
	v_max_u32_dpp v13, v13, v13 row_mirror row_mask:0xf bank_mask:0xf bound_ctrl:1
	v_cmp_eq_u32_e32 vcc, v9, v13
	v_cndmask_b32_e64 v14, v14, v13, s[18:19]
	s_nop 0
	v_cndmask_b32_e32 v9, v9, v10, vcc
	v_cndmask_b32_e32 v10, v10, v5, vcc
	v_cndmask_b32_e32 v5, v5, v11, vcc
	v_max_u32_dpp v13, v9, v9 quad_perm:[1,0,3,2] row_mask:0xf bank_mask:0xf bound_ctrl:1
	v_cndmask_b32_e32 v11, v11, v4, vcc
	v_cndmask_b32_e32 v4, v4, v12, vcc
	v_max_u32_dpp v13, v13, v13 quad_perm:[2,3,0,1] row_mask:0xf bank_mask:0xf bound_ctrl:1
	v_cndmask_b32_e32 v12, v12, v3, vcc
	v_cndmask_b32_e32 v3, v3, v2, vcc
	v_max_u32_dpp v13, v13, v13 row_half_mirror row_mask:0xf bank_mask:0xf bound_ctrl:1
	v_cndmask_b32_e64 v2, v2, 0, vcc
	s_nop 0
	v_max_u32_dpp v13, v13, v13 row_mirror row_mask:0xf bank_mask:0xf bound_ctrl:1
	v_cmp_eq_u32_e32 vcc, v9, v13
	v_cndmask_b32_e64 v14, v14, v13, s[20:21]
	s_nop 0
	v_cndmask_b32_e32 v9, v9, v10, vcc
	v_cndmask_b32_e32 v10, v10, v5, vcc
	v_cndmask_b32_e32 v5, v5, v11, vcc
	v_max_u32_dpp v13, v9, v9 quad_perm:[1,0,3,2] row_mask:0xf bank_mask:0xf bound_ctrl:1
	v_cndmask_b32_e32 v11, v11, v4, vcc
	v_cndmask_b32_e32 v4, v4, v12, vcc
	v_max_u32_dpp v13, v13, v13 quad_perm:[2,3,0,1] row_mask:0xf bank_mask:0xf bound_ctrl:1
	v_cndmask_b32_e32 v12, v12, v3, vcc
	v_cndmask_b32_e32 v3, v3, v2, vcc
	v_max_u32_dpp v13, v13, v13 row_half_mirror row_mask:0xf bank_mask:0xf bound_ctrl:1
	v_cndmask_b32_e64 v2, v2, 0, vcc
	s_nop 0
	v_max_u32_dpp v13, v13, v13 row_mirror row_mask:0xf bank_mask:0xf bound_ctrl:1
	v_cmp_eq_u32_e32 vcc, v9, v13
	v_cndmask_b32_e64 v14, v14, v13, s[22:23]
	s_nop 0
	v_cndmask_b32_e32 v9, v9, v10, vcc
	v_cndmask_b32_e32 v10, v10, v5, vcc
	v_cndmask_b32_e32 v5, v5, v11, vcc
	v_max_u32_dpp v13, v9, v9 quad_perm:[1,0,3,2] row_mask:0xf bank_mask:0xf bound_ctrl:1
	v_cndmask_b32_e32 v11, v11, v4, vcc
	v_cndmask_b32_e32 v4, v4, v12, vcc
	v_max_u32_dpp v13, v13, v13 quad_perm:[2,3,0,1] row_mask:0xf bank_mask:0xf bound_ctrl:1
	v_cndmask_b32_e32 v12, v12, v3, vcc
	v_cndmask_b32_e32 v3, v3, v2, vcc
	v_max_u32_dpp v13, v13, v13 row_half_mirror row_mask:0xf bank_mask:0xf bound_ctrl:1
	v_cndmask_b32_e64 v2, v2, 0, vcc
	s_nop 0
	v_max_u32_dpp v13, v13, v13 row_mirror row_mask:0xf bank_mask:0xf bound_ctrl:1
	v_cmp_eq_u32_e32 vcc, v9, v13
	v_cndmask_b32_e64 v14, v14, v13, s[24:25]
	s_nop 0
	v_cndmask_b32_e32 v9, v9, v10, vcc
	v_cndmask_b32_e32 v10, v10, v5, vcc
	v_cndmask_b32_e32 v5, v5, v11, vcc
	v_cndmask_b32_e32 v11, v11, v4, vcc
	v_cndmask_b32_e32 v4, v4, v12, vcc
	v_cndmask_b32_e32 v12, v12, v3, vcc
	v_cndmask_b32_e32 v2, v3, v2, vcc
	v_max_u32_dpp v3, v9, v9 quad_perm:[1,0,3,2] row_mask:0xf bank_mask:0xf bound_ctrl:1
	s_nop 1
	v_max_u32_dpp v3, v3, v3 quad_perm:[2,3,0,1] row_mask:0xf bank_mask:0xf bound_ctrl:1
	s_nop 1
	v_max_u32_dpp v3, v3, v3 row_half_mirror row_mask:0xf bank_mask:0xf bound_ctrl:1
	s_nop 1
	v_max_u32_dpp v3, v3, v3 row_mirror row_mask:0xf bank_mask:0xf bound_ctrl:1
	v_cmp_eq_u32_e32 vcc, v9, v3
	v_cndmask_b32_e64 v13, v14, v3, s[26:27]
	s_nop 0
	v_cndmask_b32_e32 v3, v9, v10, vcc
	v_cndmask_b32_e32 v9, v10, v5, vcc
	v_cndmask_b32_e32 v5, v5, v11, vcc
	v_cndmask_b32_e32 v10, v11, v4, vcc
	v_max_u32_dpp v11, v3, v3 quad_perm:[1,0,3,2] row_mask:0xf bank_mask:0xf bound_ctrl:1
	v_cndmask_b32_e32 v4, v4, v12, vcc
	v_cndmask_b32_e32 v2, v12, v2, vcc
	v_max_u32_dpp v11, v11, v11 quad_perm:[2,3,0,1] row_mask:0xf bank_mask:0xf bound_ctrl:1
	s_nop 1
	v_max_u32_dpp v11, v11, v11 row_half_mirror row_mask:0xf bank_mask:0xf bound_ctrl:1
	s_nop 1
	v_max_u32_dpp v11, v11, v11 row_mirror row_mask:0xf bank_mask:0xf bound_ctrl:1
	v_cmp_eq_u32_e32 vcc, v3, v11
	v_cndmask_b32_e64 v12, v13, v11, s[28:29]
	s_nop 0
	v_cndmask_b32_e32 v3, v3, v9, vcc
	v_cndmask_b32_e32 v9, v9, v5, vcc
	v_cndmask_b32_e32 v5, v5, v10, vcc
	v_cndmask_b32_e32 v10, v10, v4, vcc
	v_cndmask_b32_e32 v2, v4, v2, vcc
	v_max_u32_dpp v4, v3, v3 quad_perm:[1,0,3,2] row_mask:0xf bank_mask:0xf bound_ctrl:1
	s_nop 1
	v_max_u32_dpp v4, v4, v4 quad_perm:[2,3,0,1] row_mask:0xf bank_mask:0xf bound_ctrl:1
	s_nop 1
	v_max_u32_dpp v4, v4, v4 row_half_mirror row_mask:0xf bank_mask:0xf bound_ctrl:1
	s_nop 1
	v_max_u32_dpp v4, v4, v4 row_mirror row_mask:0xf bank_mask:0xf bound_ctrl:1
	v_cmp_eq_u32_e32 vcc, v3, v4
	v_cndmask_b32_e64 v11, v12, v4, s[30:31]
	s_nop 0
	v_cndmask_b32_e32 v3, v3, v9, vcc
	v_cndmask_b32_e32 v4, v9, v5, vcc
	v_cndmask_b32_e32 v5, v5, v10, vcc
	v_max_u32_dpp v9, v3, v3 quad_perm:[1,0,3,2] row_mask:0xf bank_mask:0xf bound_ctrl:1
	v_cndmask_b32_e32 v2, v10, v2, vcc
	s_nop 0
	v_max_u32_dpp v9, v9, v9 quad_perm:[2,3,0,1] row_mask:0xf bank_mask:0xf bound_ctrl:1
	s_nop 1
	v_max_u32_dpp v9, v9, v9 row_half_mirror row_mask:0xf bank_mask:0xf bound_ctrl:1
	s_nop 1
	v_max_u32_dpp v9, v9, v9 row_mirror row_mask:0xf bank_mask:0xf bound_ctrl:1
	v_cmp_eq_u32_e32 vcc, v3, v9
	v_cndmask_b32_e64 v10, v11, v9, s[34:35]
	s_nop 0
	v_cndmask_b32_e32 v3, v3, v4, vcc
	v_cndmask_b32_e32 v4, v4, v5, vcc
	v_cndmask_b32_e32 v2, v5, v2, vcc
	v_max_u32_dpp v5, v3, v3 quad_perm:[1,0,3,2] row_mask:0xf bank_mask:0xf bound_ctrl:1
	s_nop 1
	v_max_u32_dpp v5, v5, v5 quad_perm:[2,3,0,1] row_mask:0xf bank_mask:0xf bound_ctrl:1
	s_nop 1
	v_max_u32_dpp v5, v5, v5 row_half_mirror row_mask:0xf bank_mask:0xf bound_ctrl:1
	s_nop 1
	v_max_u32_dpp v5, v5, v5 row_mirror row_mask:0xf bank_mask:0xf bound_ctrl:1
	v_cmp_eq_u32_e32 vcc, v3, v5
	v_cndmask_b32_e64 v9, v10, v5, s[36:37]
	s_nop 0
	v_cndmask_b32_e32 v3, v3, v4, vcc
	v_cndmask_b32_e32 v2, v4, v2, vcc
	s_nop 0
	v_max_u32_dpp v4, v3, v3 quad_perm:[1,0,3,2] row_mask:0xf bank_mask:0xf bound_ctrl:1
	s_nop 1
	v_max_u32_dpp v4, v4, v4 quad_perm:[2,3,0,1] row_mask:0xf bank_mask:0xf bound_ctrl:1
	s_nop 1
	v_max_u32_dpp v4, v4, v4 row_half_mirror row_mask:0xf bank_mask:0xf bound_ctrl:1
	s_nop 1
	v_max_u32_dpp v4, v4, v4 row_mirror row_mask:0xf bank_mask:0xf bound_ctrl:1
	v_cmp_eq_u32_e32 vcc, v3, v4
	v_cndmask_b32_e64 v5, v9, v4, s[38:39]
	s_nop 0
	v_cndmask_b32_e32 v2, v3, v2, vcc
	v_cmp_lt_i32_e32 vcc, -1, v83
	s_nop 0
	v_max_u32_dpp v2, v2, v2 quad_perm:[1,0,3,2] row_mask:0xf bank_mask:0xf bound_ctrl:1
	v_cndmask_b32_e64 v3, v78, -1, vcc
	v_cmp_lt_i32_e32 vcc, -1, v8
	v_max_u32_dpp v2, v2, v2 quad_perm:[2,3,0,1] row_mask:0xf bank_mask:0xf bound_ctrl:1
	v_bitop3_b32 v3, v3, v83, s96 bitop3:0x78
	s_nop 0
	v_max_u32_dpp v2, v2, v2 row_half_mirror row_mask:0xf bank_mask:0xf bound_ctrl:1
	s_nop 1
	v_max_u32_dpp v2, v2, v2 row_mirror row_mask:0xf bank_mask:0xf bound_ctrl:1
	v_cndmask_b32_e64 v4, v5, v2, s[40:41]
	v_cndmask_b32_e64 v5, v78, -1, vcc
	v_bitop3_b32 v5, v5, v8, s96 bitop3:0x78
	ds_write_b32 v62, v5
	v_bitop3_b32 v5, v83, s77, v83 bitop3:0xc
	ds_write_b32 v62, v5 offset:64
	v_bitop3_b32 v5, v8, s77, v8 bitop3:0xc
	ds_write_b32 v62, v5 offset:128
	ds_read_b32 v5, v60
	v_add_u32_e32 v2, v64, v53
	v_add_u32_e32 v53, 0x80, v53
	s_waitcnt lgkmcnt(0)
	v_add_f32_e32 v5, v5, v3
	v_ashrrev_i32_e32 v8, 31, v5
	v_bitop3_b32 v5, v8, v5, s87 bitop3:0x36
	v_and_or_b32 v5, v5, s97, v63
	s_nop 1
	v_max_u32_dpp v8, v5, v5 quad_perm:[1,0,3,2] row_mask:0xf bank_mask:0xf bound_ctrl:1
	s_nop 1
	v_max_u32_dpp v8, v8, v8 quad_perm:[2,3,0,1] row_mask:0xf bank_mask:0xf bound_ctrl:1
	s_nop 1
	v_max_u32_dpp v8, v8, v8 row_half_mirror row_mask:0xf bank_mask:0xf bound_ctrl:1
	s_nop 1
	v_max_u32_dpp v8, v8, v8 row_mirror row_mask:0xf bank_mask:0xf bound_ctrl:1
	v_cmp_eq_u32_e32 vcc, v5, v8
	v_cndmask_b32_e64 v9, 0, v8, s[8:9]
	s_nop 0
	v_cndmask_b32_e64 v5, 0, 1, vcc
	v_lshl_add_u32 v10, v5, 2, v60
	ds_read_b32 v11, v10
	v_subbrev_co_u32_e32 v8, vcc, 0, v63, vcc
	s_waitcnt lgkmcnt(0)
	v_add_f32_e32 v11, v11, v3
	v_ashrrev_i32_e32 v12, 31, v11
	v_bitop3_b32 v11, v12, v11, s87 bitop3:0x36
	v_and_or_b32 v8, v11, s97, v8
	s_nop 1
	v_max_u32_dpp v11, v8, v8 quad_perm:[1,0,3,2] row_mask:0xf bank_mask:0xf bound_ctrl:1
	s_nop 1
	v_max_u32_dpp v11, v11, v11 quad_perm:[2,3,0,1] row_mask:0xf bank_mask:0xf bound_ctrl:1
	s_nop 1
	v_max_u32_dpp v11, v11, v11 row_half_mirror row_mask:0xf bank_mask:0xf bound_ctrl:1
	s_nop 1
	v_max_u32_dpp v11, v11, v11 row_mirror row_mask:0xf bank_mask:0xf bound_ctrl:1
	v_cmp_eq_u32_e32 vcc, v8, v11
	v_cndmask_b32_e64 v9, v9, v11, s[10:11]
	s_nop 0
	v_cndmask_b32_e64 v8, 0, 1, vcc
	v_lshl_add_u32 v10, v8, 2, v10
	ds_read_b32 v13, v10
	v_addc_co_u32_e32 v11, vcc, 0, v5, vcc
	v_sub_u32_e32 v12, v63, v11
	s_waitcnt lgkmcnt(0)
	v_add_f32_e32 v13, v13, v3
	v_ashrrev_i32_e32 v14, 31, v13
	v_bitop3_b32 v13, v14, v13, s87 bitop3:0x36
	v_and_or_b32 v12, v13, s97, v12
	s_nop 1
	v_max_u32_dpp v13, v12, v12 quad_perm:[1,0,3,2] row_mask:0xf bank_mask:0xf bound_ctrl:1
	s_nop 1
	v_max_u32_dpp v13, v13, v13 quad_perm:[2,3,0,1] row_mask:0xf bank_mask:0xf bound_ctrl:1
	s_nop 1
	v_max_u32_dpp v13, v13, v13 row_half_mirror row_mask:0xf bank_mask:0xf bound_ctrl:1
	s_nop 1
	v_max_u32_dpp v13, v13, v13 row_mirror row_mask:0xf bank_mask:0xf bound_ctrl:1
	v_cmp_eq_u32_e32 vcc, v12, v13
	v_cndmask_b32_e64 v9, v9, v13, s[12:13]
	s_nop 0
	v_cndmask_b32_e64 v12, 0, 1, vcc
	v_lshl_add_u32 v10, v12, 2, v10
	ds_read_b32 v13, v10
	v_addc_co_u32_e32 v5, vcc, v8, v5, vcc
	v_sub_u32_e32 v8, v63, v5
	s_waitcnt lgkmcnt(0)
	v_add_f32_e32 v13, v13, v3
	v_ashrrev_i32_e32 v14, 31, v13
	v_bitop3_b32 v13, v14, v13, s87 bitop3:0x36
	v_and_or_b32 v8, v13, s97, v8
	s_nop 1
	v_max_u32_dpp v13, v8, v8 quad_perm:[1,0,3,2] row_mask:0xf bank_mask:0xf bound_ctrl:1
	s_nop 1
	v_max_u32_dpp v13, v13, v13 quad_perm:[2,3,0,1] row_mask:0xf bank_mask:0xf bound_ctrl:1
	s_nop 1
	v_max_u32_dpp v13, v13, v13 row_half_mirror row_mask:0xf bank_mask:0xf bound_ctrl:1
	s_nop 1
	v_max_u32_dpp v13, v13, v13 row_mirror row_mask:0xf bank_mask:0xf bound_ctrl:1
	v_cmp_eq_u32_e32 vcc, v8, v13
	v_cndmask_b32_e64 v9, v9, v13, s[14:15]
	s_nop 0
	v_cndmask_b32_e64 v8, 0, 1, vcc
	v_lshl_add_u32 v10, v8, 2, v10
	ds_read_b32 v13, v10
	v_addc_co_u32_e32 v11, vcc, v11, v12, vcc
	v_sub_u32_e32 v12, v63, v11
	s_waitcnt lgkmcnt(0)
	v_add_f32_e32 v13, v13, v3
	v_ashrrev_i32_e32 v14, 31, v13
	v_bitop3_b32 v13, v14, v13, s87 bitop3:0x36
	v_and_or_b32 v12, v13, s97, v12
	s_nop 1
	v_max_u32_dpp v13, v12, v12 quad_perm:[1,0,3,2] row_mask:0xf bank_mask:0xf bound_ctrl:1
	s_nop 1
	v_max_u32_dpp v13, v13, v13 quad_perm:[2,3,0,1] row_mask:0xf bank_mask:0xf bound_ctrl:1
	s_nop 1
	v_max_u32_dpp v13, v13, v13 row_half_mirror row_mask:0xf bank_mask:0xf bound_ctrl:1
	s_nop 1
	v_max_u32_dpp v13, v13, v13 row_mirror row_mask:0xf bank_mask:0xf bound_ctrl:1
	v_cmp_eq_u32_e32 vcc, v12, v13
	v_cndmask_b32_e64 v9, v9, v13, s[16:17]
	s_nop 0
	v_cndmask_b32_e64 v12, 0, 1, vcc
	v_lshl_add_u32 v10, v12, 2, v10
	ds_read_b32 v13, v10
	v_addc_co_u32_e32 v5, vcc, v5, v8, vcc
	v_sub_u32_e32 v8, v63, v5
	s_waitcnt lgkmcnt(0)
	v_add_f32_e32 v13, v13, v3
	v_ashrrev_i32_e32 v14, 31, v13
	v_bitop3_b32 v13, v14, v13, s87 bitop3:0x36
	v_and_or_b32 v8, v13, s97, v8
	s_nop 1
	v_max_u32_dpp v13, v8, v8 quad_perm:[1,0,3,2] row_mask:0xf bank_mask:0xf bound_ctrl:1
	s_nop 1
	v_max_u32_dpp v13, v13, v13 quad_perm:[2,3,0,1] row_mask:0xf bank_mask:0xf bound_ctrl:1
	s_nop 1
	v_max_u32_dpp v13, v13, v13 row_half_mirror row_mask:0xf bank_mask:0xf bound_ctrl:1
	s_nop 1
	v_max_u32_dpp v13, v13, v13 row_mirror row_mask:0xf bank_mask:0xf bound_ctrl:1
	v_cmp_eq_u32_e32 vcc, v8, v13
	v_cndmask_b32_e64 v9, v9, v13, s[18:19]
	s_nop 0
	v_cndmask_b32_e64 v8, 0, 1, vcc
	v_lshl_add_u32 v10, v8, 2, v10
	ds_read_b32 v13, v10
	v_addc_co_u32_e32 v11, vcc, v11, v12, vcc
	v_sub_u32_e32 v12, v63, v11
	s_waitcnt lgkmcnt(0)
	v_add_f32_e32 v13, v13, v3
	v_ashrrev_i32_e32 v14, 31, v13
	v_bitop3_b32 v13, v14, v13, s87 bitop3:0x36
	v_and_or_b32 v12, v13, s97, v12
	s_nop 1
	v_max_u32_dpp v13, v12, v12 quad_perm:[1,0,3,2] row_mask:0xf bank_mask:0xf bound_ctrl:1
	s_nop 1
	v_max_u32_dpp v13, v13, v13 quad_perm:[2,3,0,1] row_mask:0xf bank_mask:0xf bound_ctrl:1
	s_nop 1
	v_max_u32_dpp v13, v13, v13 row_half_mirror row_mask:0xf bank_mask:0xf bound_ctrl:1
	s_nop 1
	v_max_u32_dpp v13, v13, v13 row_mirror row_mask:0xf bank_mask:0xf bound_ctrl:1
	v_cmp_eq_u32_e32 vcc, v12, v13
	v_cndmask_b32_e64 v9, v9, v13, s[20:21]
	s_nop 0
	v_cndmask_b32_e64 v12, 0, 1, vcc
	v_lshl_add_u32 v10, v12, 2, v10
	ds_read_b32 v13, v10
	v_addc_co_u32_e32 v5, vcc, v5, v8, vcc
	v_sub_u32_e32 v8, v63, v5
	s_waitcnt lgkmcnt(0)
	v_add_f32_e32 v13, v13, v3
	v_ashrrev_i32_e32 v14, 31, v13
	v_bitop3_b32 v13, v14, v13, s87 bitop3:0x36
	v_and_or_b32 v8, v13, s97, v8
	s_nop 1
	v_max_u32_dpp v13, v8, v8 quad_perm:[1,0,3,2] row_mask:0xf bank_mask:0xf bound_ctrl:1
	s_nop 1
	v_max_u32_dpp v13, v13, v13 quad_perm:[2,3,0,1] row_mask:0xf bank_mask:0xf bound_ctrl:1
	s_nop 1
	v_max_u32_dpp v13, v13, v13 row_half_mirror row_mask:0xf bank_mask:0xf bound_ctrl:1
	s_nop 1
	v_max_u32_dpp v13, v13, v13 row_mirror row_mask:0xf bank_mask:0xf bound_ctrl:1
	v_cmp_eq_u32_e32 vcc, v8, v13
	v_cndmask_b32_e64 v9, v9, v13, s[22:23]
	s_nop 0
	v_cndmask_b32_e64 v8, 0, 1, vcc
	v_lshl_add_u32 v10, v8, 2, v10
	ds_read_b32 v13, v10
	v_addc_co_u32_e32 v11, vcc, v11, v12, vcc
	v_sub_u32_e32 v12, v63, v11
	s_waitcnt lgkmcnt(0)
	v_add_f32_e32 v13, v13, v3
	v_ashrrev_i32_e32 v14, 31, v13
	v_bitop3_b32 v13, v14, v13, s87 bitop3:0x36
	v_and_or_b32 v12, v13, s97, v12
	s_nop 1
	v_max_u32_dpp v13, v12, v12 quad_perm:[1,0,3,2] row_mask:0xf bank_mask:0xf bound_ctrl:1
	s_nop 1
	v_max_u32_dpp v13, v13, v13 quad_perm:[2,3,0,1] row_mask:0xf bank_mask:0xf bound_ctrl:1
	s_nop 1
	v_max_u32_dpp v13, v13, v13 row_half_mirror row_mask:0xf bank_mask:0xf bound_ctrl:1
	s_nop 1
	v_max_u32_dpp v13, v13, v13 row_mirror row_mask:0xf bank_mask:0xf bound_ctrl:1
	v_cmp_eq_u32_e32 vcc, v12, v13
	v_cndmask_b32_e64 v9, v9, v13, s[24:25]
	s_nop 0
	v_cndmask_b32_e64 v12, 0, 1, vcc
	v_lshl_add_u32 v10, v12, 2, v10
	ds_read_b32 v13, v10
	v_addc_co_u32_e32 v5, vcc, v5, v8, vcc
	v_sub_u32_e32 v8, v63, v5
	s_waitcnt lgkmcnt(0)
	v_add_f32_e32 v13, v13, v3
	v_ashrrev_i32_e32 v14, 31, v13
	v_bitop3_b32 v13, v14, v13, s87 bitop3:0x36
	v_and_or_b32 v8, v13, s97, v8
	s_nop 1
	v_max_u32_dpp v13, v8, v8 quad_perm:[1,0,3,2] row_mask:0xf bank_mask:0xf bound_ctrl:1
	s_nop 1
	v_max_u32_dpp v13, v13, v13 quad_perm:[2,3,0,1] row_mask:0xf bank_mask:0xf bound_ctrl:1
	s_nop 1
	v_max_u32_dpp v13, v13, v13 row_half_mirror row_mask:0xf bank_mask:0xf bound_ctrl:1
	s_nop 1
	v_max_u32_dpp v13, v13, v13 row_mirror row_mask:0xf bank_mask:0xf bound_ctrl:1
	v_cmp_eq_u32_e32 vcc, v8, v13
	v_cndmask_b32_e64 v9, v9, v13, s[26:27]
	s_nop 0
	v_cndmask_b32_e64 v8, 0, 1, vcc
	v_lshl_add_u32 v10, v8, 2, v10
	ds_read_b32 v13, v10
	v_addc_co_u32_e32 v11, vcc, v11, v12, vcc
	v_sub_u32_e32 v12, v63, v11
	s_waitcnt lgkmcnt(0)
	v_add_f32_e32 v13, v13, v3
	v_ashrrev_i32_e32 v14, 31, v13
	v_bitop3_b32 v13, v14, v13, s87 bitop3:0x36
	v_and_or_b32 v12, v13, s97, v12
	s_nop 1
	v_max_u32_dpp v13, v12, v12 quad_perm:[1,0,3,2] row_mask:0xf bank_mask:0xf bound_ctrl:1
	s_nop 1
	v_max_u32_dpp v13, v13, v13 quad_perm:[2,3,0,1] row_mask:0xf bank_mask:0xf bound_ctrl:1
	s_nop 1
	v_max_u32_dpp v13, v13, v13 row_half_mirror row_mask:0xf bank_mask:0xf bound_ctrl:1
	s_nop 1
	v_max_u32_dpp v13, v13, v13 row_mirror row_mask:0xf bank_mask:0xf bound_ctrl:1
	v_cmp_eq_u32_e32 vcc, v12, v13
	v_cndmask_b32_e64 v9, v9, v13, s[28:29]
	s_nop 0
	v_cndmask_b32_e64 v12, 0, 1, vcc
	v_lshl_add_u32 v10, v12, 2, v10
	ds_read_b32 v13, v10
	v_addc_co_u32_e32 v5, vcc, v5, v8, vcc
	v_sub_u32_e32 v8, v63, v5
	s_waitcnt lgkmcnt(0)
	v_add_f32_e32 v13, v13, v3
	v_ashrrev_i32_e32 v14, 31, v13
	v_bitop3_b32 v13, v14, v13, s87 bitop3:0x36
	v_and_or_b32 v8, v13, s97, v8
	s_nop 1
	v_max_u32_dpp v13, v8, v8 quad_perm:[1,0,3,2] row_mask:0xf bank_mask:0xf bound_ctrl:1
	s_nop 1
	v_max_u32_dpp v13, v13, v13 quad_perm:[2,3,0,1] row_mask:0xf bank_mask:0xf bound_ctrl:1
	s_nop 1
	v_max_u32_dpp v13, v13, v13 row_half_mirror row_mask:0xf bank_mask:0xf bound_ctrl:1
	s_nop 1
	v_max_u32_dpp v13, v13, v13 row_mirror row_mask:0xf bank_mask:0xf bound_ctrl:1
	v_cmp_eq_u32_e32 vcc, v8, v13
	v_cndmask_b32_e64 v9, v9, v13, s[30:31]
	s_nop 0
	v_cndmask_b32_e64 v8, 0, 1, vcc
	v_lshl_add_u32 v10, v8, 2, v10
	ds_read_b32 v13, v10
	v_addc_co_u32_e32 v11, vcc, v11, v12, vcc
	v_sub_u32_e32 v12, v63, v11
	s_waitcnt lgkmcnt(0)
	v_add_f32_e32 v13, v13, v3
	v_ashrrev_i32_e32 v14, 31, v13
	v_bitop3_b32 v13, v14, v13, s87 bitop3:0x36
	v_and_or_b32 v12, v13, s97, v12
	s_nop 1
	v_max_u32_dpp v13, v12, v12 quad_perm:[1,0,3,2] row_mask:0xf bank_mask:0xf bound_ctrl:1
	s_nop 1
	v_max_u32_dpp v13, v13, v13 quad_perm:[2,3,0,1] row_mask:0xf bank_mask:0xf bound_ctrl:1
	s_nop 1
	v_max_u32_dpp v13, v13, v13 row_half_mirror row_mask:0xf bank_mask:0xf bound_ctrl:1
	s_nop 1
	v_max_u32_dpp v13, v13, v13 row_mirror row_mask:0xf bank_mask:0xf bound_ctrl:1
	v_cmp_eq_u32_e32 vcc, v12, v13
	v_cndmask_b32_e64 v9, v9, v13, s[34:35]
	s_nop 0
	v_cndmask_b32_e64 v12, 0, 1, vcc
	v_lshl_add_u32 v10, v12, 2, v10
	ds_read_b32 v13, v10
	v_addc_co_u32_e32 v5, vcc, v5, v8, vcc
	v_sub_u32_e32 v8, v63, v5
	s_waitcnt lgkmcnt(0)
	v_add_f32_e32 v13, v13, v3
	v_ashrrev_i32_e32 v14, 31, v13
	v_bitop3_b32 v13, v14, v13, s87 bitop3:0x36
	v_and_or_b32 v8, v13, s97, v8
	s_nop 1
	v_max_u32_dpp v13, v8, v8 quad_perm:[1,0,3,2] row_mask:0xf bank_mask:0xf bound_ctrl:1
	s_nop 1
	v_max_u32_dpp v13, v13, v13 quad_perm:[2,3,0,1] row_mask:0xf bank_mask:0xf bound_ctrl:1
	s_nop 1
	v_max_u32_dpp v13, v13, v13 row_half_mirror row_mask:0xf bank_mask:0xf bound_ctrl:1
	s_nop 1
	v_max_u32_dpp v13, v13, v13 row_mirror row_mask:0xf bank_mask:0xf bound_ctrl:1
	v_cmp_eq_u32_e32 vcc, v8, v13
	v_cndmask_b32_e64 v9, v9, v13, s[36:37]
	s_nop 0
	v_cndmask_b32_e64 v8, 0, 1, vcc
	v_lshl_add_u32 v10, v8, 2, v10
	v_addc_co_u32_e32 v11, vcc, v11, v12, vcc
	ds_read_b32 v12, v10
	v_sub_u32_e32 v11, v63, v11
	s_waitcnt lgkmcnt(0)
	v_add_f32_e32 v12, v12, v3
	v_ashrrev_i32_e32 v13, 31, v12
	v_bitop3_b32 v12, v13, v12, s87 bitop3:0x36
	v_and_or_b32 v11, v12, s97, v11
	s_nop 1
	v_max_u32_dpp v12, v11, v11 quad_perm:[1,0,3,2] row_mask:0xf bank_mask:0xf bound_ctrl:1
	s_nop 1
	v_max_u32_dpp v12, v12, v12 quad_perm:[2,3,0,1] row_mask:0xf bank_mask:0xf bound_ctrl:1
	s_nop 1
	v_max_u32_dpp v12, v12, v12 row_half_mirror row_mask:0xf bank_mask:0xf bound_ctrl:1
	s_nop 1
	v_max_u32_dpp v12, v12, v12 row_mirror row_mask:0xf bank_mask:0xf bound_ctrl:1
	v_cmp_eq_u32_e32 vcc, v11, v12
	v_cndmask_b32_e64 v9, v9, v12, s[38:39]
	s_nop 0
	v_cndmask_b32_e64 v11, 0, 1, vcc
	v_addc_co_u32_e32 v5, vcc, v5, v8, vcc
	v_lshl_add_u32 v8, v11, 2, v10
	ds_read_b32 v8, v8
	v_sub_u32_e32 v5, v63, v5
	s_waitcnt lgkmcnt(0)
	v_add_f32_e32 v3, v8, v3
	v_ashrrev_i32_e32 v8, 31, v3
	v_bitop3_b32 v3, v8, v3, s87 bitop3:0x36
	v_and_or_b32 v3, v3, s97, v5
	s_nop 1
	v_max_u32_dpp v3, v3, v3 quad_perm:[1,0,3,2] row_mask:0xf bank_mask:0xf bound_ctrl:1
	s_nop 1
	v_max_u32_dpp v3, v3, v3 quad_perm:[2,3,0,1] row_mask:0xf bank_mask:0xf bound_ctrl:1
	s_nop 1
	v_max_u32_dpp v3, v3, v3 row_half_mirror row_mask:0xf bank_mask:0xf bound_ctrl:1
	s_nop 1
	v_max_u32_dpp v3, v3, v3 row_mirror row_mask:0xf bank_mask:0xf bound_ctrl:1
	v_cndmask_b32_e64 v3, v9, v3, s[40:41]
	v_cmp_lt_i32_e32 vcc, -1, v3
	v_not_b32_e32 v5, v3
	v_bitop3_b32 v9, v3, 15, v3 bitop3:0xc
	v_cndmask_b32_e64 v8, v78, -1, vcc
	v_bitop3_b32 v8, v8, v3, s97 bitop3:0x78
	v_max_u32_dpp v3, v3, v3 quad_perm:[1,0,3,2] row_mask:0xf bank_mask:0xf bound_ctrl:1
	v_lshrrev_b32_e32 v5, 2, v5
	v_and_b32_e32 v5, 60, v5
	v_max_u32_dpp v3, v3, v3 quad_perm:[2,3,0,1] row_mask:0xf bank_mask:0xf bound_ctrl:1
	v_add_u32_e32 v5, v60, v5
	v_lshl_add_u32 v9, v9, 2, v60
	v_max_u32_dpp v3, v3, v3 row_half_mirror row_mask:0xf bank_mask:0xf bound_ctrl:1
	ds_read_b32 v5, v5 offset:64
	ds_read_b32 v9, v9 offset:128
	v_max_u32_dpp v3, v3, v3 row_mirror row_mask:0xf bank_mask:0xf bound_ctrl:1
	v_cmp_lt_i32_e32 vcc, -1, v3
	s_waitcnt lgkmcnt(0)
	v_lshl_add_u32 v5, v5, 7, v9
	v_cndmask_b32_e64 v10, v78, -1, vcc
	v_bitop3_b32 v3, v10, v3, s97 bitop3:0x78
	v_sub_f32_e32 v3, v8, v3
	v_mul_f32_e32 v3, 0x3fb8aa3b, v3
	v_exp_f32_e32 v12, v3
	s_nop 1
	v_add_f32_dpp v3, v12, v12 quad_perm:[1,0,3,2] row_mask:0xf bank_mask:0xf bound_ctrl:1
	s_nop 1
	v_add_f32_dpp v3, v3, v3 quad_perm:[2,3,0,1] row_mask:0xf bank_mask:0xf bound_ctrl:1
	s_nop 1
	v_add_f32_dpp v3, v3, v3 row_half_mirror row_mask:0xf bank_mask:0xf bound_ctrl:1
	s_nop 1
	v_add_f32_dpp v13, v3, v3 row_mirror row_mask:0xf bank_mask:0xf bound_ctrl:1
	v_ashrrev_i32_e32 v3, 31, v2
	v_lshlrev_b64 v[8:9], 9, v[2:3]
	v_or_b32_e32 v8, v8, v79
	v_lshl_add_u64 v[10:11], s[50:51], 0, v[8:9]
	v_div_scale_f32 v3, s[46:47], v13, v13, v12
	global_store_dword v[10:11], v5, off
	v_rcp_f32_e32 v5, v3
	v_lshl_add_u64 v[8:9], s[58:59], 0, v[8:9]
	v_fma_f32 v10, -v3, v5, 1.0
	v_fmac_f32_e32 v5, v10, v5
	v_div_scale_f32 v10, vcc, v12, v13, v12
	v_mul_f32_e32 v11, v10, v5
	v_fma_f32 v14, -v3, v11, v10
	v_fmac_f32_e32 v11, v14, v5
	v_fma_f32 v3, -v3, v11, v10
	v_div_fmas_f32 v3, v3, v5, v11
	v_div_fixup_f32 v3, v3, v13, v12
	v_cmp_lt_i32_e32 vcc, -1, v82
	global_store_dword v[8:9], v3, off
	s_nop 0
	v_cndmask_b32_e64 v3, v78, -1, vcc
	v_cmp_lt_i32_e32 vcc, -1, v7
	v_bitop3_b32 v3, v3, v82, s96 bitop3:0x78
	s_nop 0
	v_cndmask_b32_e64 v5, v78, -1, vcc
	v_bitop3_b32 v5, v5, v7, s96 bitop3:0x78
	ds_write_b32 v62, v5
	v_bitop3_b32 v5, v82, s77, v82 bitop3:0xc
	ds_write_b32 v62, v5 offset:64
	v_bitop3_b32 v5, v7, s77, v7 bitop3:0xc
	ds_write_b32 v62, v5 offset:128
	ds_read_b32 v5, v60
	s_waitcnt lgkmcnt(0)
	v_add_f32_e32 v5, v5, v3
	v_ashrrev_i32_e32 v7, 31, v5
	v_bitop3_b32 v5, v7, v5, s87 bitop3:0x36
	v_and_or_b32 v5, v5, s97, v63
	s_nop 1
	v_max_u32_dpp v7, v5, v5 quad_perm:[1,0,3,2] row_mask:0xf bank_mask:0xf bound_ctrl:1
	s_nop 1
	v_max_u32_dpp v7, v7, v7 quad_perm:[2,3,0,1] row_mask:0xf bank_mask:0xf bound_ctrl:1
	s_nop 1
	v_max_u32_dpp v7, v7, v7 row_half_mirror row_mask:0xf bank_mask:0xf bound_ctrl:1
	s_nop 1
	v_max_u32_dpp v7, v7, v7 row_mirror row_mask:0xf bank_mask:0xf bound_ctrl:1
	v_cmp_eq_u32_e32 vcc, v5, v7
	v_cndmask_b32_e64 v8, 0, v7, s[8:9]
	s_nop 0
	v_cndmask_b32_e64 v5, 0, 1, vcc
	v_lshl_add_u32 v9, v5, 2, v60
	ds_read_b32 v10, v9
	v_subbrev_co_u32_e32 v7, vcc, 0, v63, vcc
	s_waitcnt lgkmcnt(0)
	v_add_f32_e32 v10, v10, v3
	v_ashrrev_i32_e32 v11, 31, v10
	v_bitop3_b32 v10, v11, v10, s87 bitop3:0x36
	v_and_or_b32 v7, v10, s97, v7
	s_nop 1
	v_max_u32_dpp v10, v7, v7 quad_perm:[1,0,3,2] row_mask:0xf bank_mask:0xf bound_ctrl:1
	s_nop 1
	v_max_u32_dpp v10, v10, v10 quad_perm:[2,3,0,1] row_mask:0xf bank_mask:0xf bound_ctrl:1
	s_nop 1
	v_max_u32_dpp v10, v10, v10 row_half_mirror row_mask:0xf bank_mask:0xf bound_ctrl:1
	s_nop 1
	v_max_u32_dpp v10, v10, v10 row_mirror row_mask:0xf bank_mask:0xf bound_ctrl:1
	v_cmp_eq_u32_e32 vcc, v7, v10
	v_cndmask_b32_e64 v8, v8, v10, s[10:11]
	s_nop 0
	v_cndmask_b32_e64 v7, 0, 1, vcc
	v_lshl_add_u32 v9, v7, 2, v9
	ds_read_b32 v12, v9
	v_addc_co_u32_e32 v10, vcc, 0, v5, vcc
	v_sub_u32_e32 v11, v63, v10
	s_waitcnt lgkmcnt(0)
	v_add_f32_e32 v12, v12, v3
	v_ashrrev_i32_e32 v13, 31, v12
	v_bitop3_b32 v12, v13, v12, s87 bitop3:0x36
	v_and_or_b32 v11, v12, s97, v11
	s_nop 1
	v_max_u32_dpp v12, v11, v11 quad_perm:[1,0,3,2] row_mask:0xf bank_mask:0xf bound_ctrl:1
	s_nop 1
	v_max_u32_dpp v12, v12, v12 quad_perm:[2,3,0,1] row_mask:0xf bank_mask:0xf bound_ctrl:1
	s_nop 1
	v_max_u32_dpp v12, v12, v12 row_half_mirror row_mask:0xf bank_mask:0xf bound_ctrl:1
	s_nop 1
	v_max_u32_dpp v12, v12, v12 row_mirror row_mask:0xf bank_mask:0xf bound_ctrl:1
	v_cmp_eq_u32_e32 vcc, v11, v12
	v_cndmask_b32_e64 v8, v8, v12, s[12:13]
	s_nop 0
	v_cndmask_b32_e64 v11, 0, 1, vcc
	v_lshl_add_u32 v9, v11, 2, v9
	ds_read_b32 v12, v9
	v_addc_co_u32_e32 v5, vcc, v7, v5, vcc
	v_sub_u32_e32 v7, v63, v5
	s_waitcnt lgkmcnt(0)
	v_add_f32_e32 v12, v12, v3
	v_ashrrev_i32_e32 v13, 31, v12
	v_bitop3_b32 v12, v13, v12, s87 bitop3:0x36
	v_and_or_b32 v7, v12, s97, v7
	s_nop 1
	v_max_u32_dpp v12, v7, v7 quad_perm:[1,0,3,2] row_mask:0xf bank_mask:0xf bound_ctrl:1
	s_nop 1
	v_max_u32_dpp v12, v12, v12 quad_perm:[2,3,0,1] row_mask:0xf bank_mask:0xf bound_ctrl:1
	s_nop 1
	v_max_u32_dpp v12, v12, v12 row_half_mirror row_mask:0xf bank_mask:0xf bound_ctrl:1
	s_nop 1
	v_max_u32_dpp v12, v12, v12 row_mirror row_mask:0xf bank_mask:0xf bound_ctrl:1
	v_cmp_eq_u32_e32 vcc, v7, v12
	v_cndmask_b32_e64 v8, v8, v12, s[14:15]
	s_nop 0
	v_cndmask_b32_e64 v7, 0, 1, vcc
	v_lshl_add_u32 v9, v7, 2, v9
	ds_read_b32 v12, v9
	v_addc_co_u32_e32 v10, vcc, v10, v11, vcc
	v_sub_u32_e32 v11, v63, v10
	s_waitcnt lgkmcnt(0)
	v_add_f32_e32 v12, v12, v3
	v_ashrrev_i32_e32 v13, 31, v12
	v_bitop3_b32 v12, v13, v12, s87 bitop3:0x36
	v_and_or_b32 v11, v12, s97, v11
	s_nop 1
	v_max_u32_dpp v12, v11, v11 quad_perm:[1,0,3,2] row_mask:0xf bank_mask:0xf bound_ctrl:1
	s_nop 1
	v_max_u32_dpp v12, v12, v12 quad_perm:[2,3,0,1] row_mask:0xf bank_mask:0xf bound_ctrl:1
	s_nop 1
	v_max_u32_dpp v12, v12, v12 row_half_mirror row_mask:0xf bank_mask:0xf bound_ctrl:1
	s_nop 1
	v_max_u32_dpp v12, v12, v12 row_mirror row_mask:0xf bank_mask:0xf bound_ctrl:1
	v_cmp_eq_u32_e32 vcc, v11, v12
	v_cndmask_b32_e64 v8, v8, v12, s[16:17]
	s_nop 0
	v_cndmask_b32_e64 v11, 0, 1, vcc
	v_lshl_add_u32 v9, v11, 2, v9
	ds_read_b32 v12, v9
	v_addc_co_u32_e32 v5, vcc, v5, v7, vcc
	v_sub_u32_e32 v7, v63, v5
	s_waitcnt lgkmcnt(0)
	v_add_f32_e32 v12, v12, v3
	v_ashrrev_i32_e32 v13, 31, v12
	v_bitop3_b32 v12, v13, v12, s87 bitop3:0x36
	v_and_or_b32 v7, v12, s97, v7
	s_nop 1
	v_max_u32_dpp v12, v7, v7 quad_perm:[1,0,3,2] row_mask:0xf bank_mask:0xf bound_ctrl:1
	s_nop 1
	v_max_u32_dpp v12, v12, v12 quad_perm:[2,3,0,1] row_mask:0xf bank_mask:0xf bound_ctrl:1
	s_nop 1
	v_max_u32_dpp v12, v12, v12 row_half_mirror row_mask:0xf bank_mask:0xf bound_ctrl:1
	s_nop 1
	v_max_u32_dpp v12, v12, v12 row_mirror row_mask:0xf bank_mask:0xf bound_ctrl:1
	v_cmp_eq_u32_e32 vcc, v7, v12
	v_cndmask_b32_e64 v8, v8, v12, s[18:19]
	s_nop 0
	v_cndmask_b32_e64 v7, 0, 1, vcc
	v_lshl_add_u32 v9, v7, 2, v9
	ds_read_b32 v12, v9
	v_addc_co_u32_e32 v10, vcc, v10, v11, vcc
	v_sub_u32_e32 v11, v63, v10
	s_waitcnt lgkmcnt(0)
	v_add_f32_e32 v12, v12, v3
	v_ashrrev_i32_e32 v13, 31, v12
	v_bitop3_b32 v12, v13, v12, s87 bitop3:0x36
	v_and_or_b32 v11, v12, s97, v11
	s_nop 1
	v_max_u32_dpp v12, v11, v11 quad_perm:[1,0,3,2] row_mask:0xf bank_mask:0xf bound_ctrl:1
	s_nop 1
	v_max_u32_dpp v12, v12, v12 quad_perm:[2,3,0,1] row_mask:0xf bank_mask:0xf bound_ctrl:1
	s_nop 1
	v_max_u32_dpp v12, v12, v12 row_half_mirror row_mask:0xf bank_mask:0xf bound_ctrl:1
	s_nop 1
	v_max_u32_dpp v12, v12, v12 row_mirror row_mask:0xf bank_mask:0xf bound_ctrl:1
	v_cmp_eq_u32_e32 vcc, v11, v12
	v_cndmask_b32_e64 v8, v8, v12, s[20:21]
	s_nop 0
	v_cndmask_b32_e64 v11, 0, 1, vcc
	v_lshl_add_u32 v9, v11, 2, v9
	ds_read_b32 v12, v9
	v_addc_co_u32_e32 v5, vcc, v5, v7, vcc
	v_sub_u32_e32 v7, v63, v5
	s_waitcnt lgkmcnt(0)
	v_add_f32_e32 v12, v12, v3
	v_ashrrev_i32_e32 v13, 31, v12
	v_bitop3_b32 v12, v13, v12, s87 bitop3:0x36
	v_and_or_b32 v7, v12, s97, v7
	s_nop 1
	v_max_u32_dpp v12, v7, v7 quad_perm:[1,0,3,2] row_mask:0xf bank_mask:0xf bound_ctrl:1
	s_nop 1
	v_max_u32_dpp v12, v12, v12 quad_perm:[2,3,0,1] row_mask:0xf bank_mask:0xf bound_ctrl:1
	s_nop 1
	v_max_u32_dpp v12, v12, v12 row_half_mirror row_mask:0xf bank_mask:0xf bound_ctrl:1
	s_nop 1
	v_max_u32_dpp v12, v12, v12 row_mirror row_mask:0xf bank_mask:0xf bound_ctrl:1
	v_cmp_eq_u32_e32 vcc, v7, v12
	v_cndmask_b32_e64 v8, v8, v12, s[22:23]
	s_nop 0
	v_cndmask_b32_e64 v7, 0, 1, vcc
	v_lshl_add_u32 v9, v7, 2, v9
	ds_read_b32 v12, v9
	v_addc_co_u32_e32 v10, vcc, v10, v11, vcc
	v_sub_u32_e32 v11, v63, v10
	s_waitcnt lgkmcnt(0)
	v_add_f32_e32 v12, v12, v3
	v_ashrrev_i32_e32 v13, 31, v12
	v_bitop3_b32 v12, v13, v12, s87 bitop3:0x36
	v_and_or_b32 v11, v12, s97, v11
	s_nop 1
	v_max_u32_dpp v12, v11, v11 quad_perm:[1,0,3,2] row_mask:0xf bank_mask:0xf bound_ctrl:1
	s_nop 1
	v_max_u32_dpp v12, v12, v12 quad_perm:[2,3,0,1] row_mask:0xf bank_mask:0xf bound_ctrl:1
	s_nop 1
	v_max_u32_dpp v12, v12, v12 row_half_mirror row_mask:0xf bank_mask:0xf bound_ctrl:1
	s_nop 1
	v_max_u32_dpp v12, v12, v12 row_mirror row_mask:0xf bank_mask:0xf bound_ctrl:1
	v_cmp_eq_u32_e32 vcc, v11, v12
	v_cndmask_b32_e64 v8, v8, v12, s[24:25]
	s_nop 0
	v_cndmask_b32_e64 v11, 0, 1, vcc
	v_lshl_add_u32 v9, v11, 2, v9
	ds_read_b32 v12, v9
	v_addc_co_u32_e32 v5, vcc, v5, v7, vcc
	v_sub_u32_e32 v7, v63, v5
	s_waitcnt lgkmcnt(0)
	v_add_f32_e32 v12, v12, v3
	v_ashrrev_i32_e32 v13, 31, v12
	v_bitop3_b32 v12, v13, v12, s87 bitop3:0x36
	v_and_or_b32 v7, v12, s97, v7
	s_nop 1
	v_max_u32_dpp v12, v7, v7 quad_perm:[1,0,3,2] row_mask:0xf bank_mask:0xf bound_ctrl:1
	s_nop 1
	v_max_u32_dpp v12, v12, v12 quad_perm:[2,3,0,1] row_mask:0xf bank_mask:0xf bound_ctrl:1
	s_nop 1
	v_max_u32_dpp v12, v12, v12 row_half_mirror row_mask:0xf bank_mask:0xf bound_ctrl:1
	s_nop 1
	v_max_u32_dpp v12, v12, v12 row_mirror row_mask:0xf bank_mask:0xf bound_ctrl:1
	v_cmp_eq_u32_e32 vcc, v7, v12
	v_cndmask_b32_e64 v8, v8, v12, s[26:27]
	s_nop 0
	v_cndmask_b32_e64 v7, 0, 1, vcc
	v_lshl_add_u32 v9, v7, 2, v9
	ds_read_b32 v12, v9
	v_addc_co_u32_e32 v10, vcc, v10, v11, vcc
	v_sub_u32_e32 v11, v63, v10
	s_waitcnt lgkmcnt(0)
	v_add_f32_e32 v12, v12, v3
	v_ashrrev_i32_e32 v13, 31, v12
	v_bitop3_b32 v12, v13, v12, s87 bitop3:0x36
	v_and_or_b32 v11, v12, s97, v11
	s_nop 1
	v_max_u32_dpp v12, v11, v11 quad_perm:[1,0,3,2] row_mask:0xf bank_mask:0xf bound_ctrl:1
	s_nop 1
	v_max_u32_dpp v12, v12, v12 quad_perm:[2,3,0,1] row_mask:0xf bank_mask:0xf bound_ctrl:1
	s_nop 1
	v_max_u32_dpp v12, v12, v12 row_half_mirror row_mask:0xf bank_mask:0xf bound_ctrl:1
	s_nop 1
	v_max_u32_dpp v12, v12, v12 row_mirror row_mask:0xf bank_mask:0xf bound_ctrl:1
	v_cmp_eq_u32_e32 vcc, v11, v12
	v_cndmask_b32_e64 v8, v8, v12, s[28:29]
	s_nop 0
	v_cndmask_b32_e64 v11, 0, 1, vcc
	v_lshl_add_u32 v9, v11, 2, v9
	ds_read_b32 v12, v9
	v_addc_co_u32_e32 v5, vcc, v5, v7, vcc
	v_sub_u32_e32 v7, v63, v5
	s_waitcnt lgkmcnt(0)
	v_add_f32_e32 v12, v12, v3
	v_ashrrev_i32_e32 v13, 31, v12
	v_bitop3_b32 v12, v13, v12, s87 bitop3:0x36
	v_and_or_b32 v7, v12, s97, v7
	s_nop 1
	v_max_u32_dpp v12, v7, v7 quad_perm:[1,0,3,2] row_mask:0xf bank_mask:0xf bound_ctrl:1
	s_nop 1
	v_max_u32_dpp v12, v12, v12 quad_perm:[2,3,0,1] row_mask:0xf bank_mask:0xf bound_ctrl:1
	s_nop 1
	v_max_u32_dpp v12, v12, v12 row_half_mirror row_mask:0xf bank_mask:0xf bound_ctrl:1
	s_nop 1
	v_max_u32_dpp v12, v12, v12 row_mirror row_mask:0xf bank_mask:0xf bound_ctrl:1
	v_cmp_eq_u32_e32 vcc, v7, v12
	v_cndmask_b32_e64 v8, v8, v12, s[30:31]
	s_nop 0
	v_cndmask_b32_e64 v7, 0, 1, vcc
	v_lshl_add_u32 v9, v7, 2, v9
	ds_read_b32 v12, v9
	v_addc_co_u32_e32 v10, vcc, v10, v11, vcc
	v_sub_u32_e32 v11, v63, v10
	s_waitcnt lgkmcnt(0)
	v_add_f32_e32 v12, v12, v3
	v_ashrrev_i32_e32 v13, 31, v12
	v_bitop3_b32 v12, v13, v12, s87 bitop3:0x36
	v_and_or_b32 v11, v12, s97, v11
	s_nop 1
	v_max_u32_dpp v12, v11, v11 quad_perm:[1,0,3,2] row_mask:0xf bank_mask:0xf bound_ctrl:1
	s_nop 1
	v_max_u32_dpp v12, v12, v12 quad_perm:[2,3,0,1] row_mask:0xf bank_mask:0xf bound_ctrl:1
	s_nop 1
	v_max_u32_dpp v12, v12, v12 row_half_mirror row_mask:0xf bank_mask:0xf bound_ctrl:1
	s_nop 1
	v_max_u32_dpp v12, v12, v12 row_mirror row_mask:0xf bank_mask:0xf bound_ctrl:1
	v_cmp_eq_u32_e32 vcc, v11, v12
	v_cndmask_b32_e64 v8, v8, v12, s[34:35]
	s_nop 0
	v_cndmask_b32_e64 v11, 0, 1, vcc
	v_lshl_add_u32 v9, v11, 2, v9
	ds_read_b32 v12, v9
	v_addc_co_u32_e32 v5, vcc, v5, v7, vcc
	v_sub_u32_e32 v7, v63, v5
	s_waitcnt lgkmcnt(0)
	v_add_f32_e32 v12, v12, v3
	v_ashrrev_i32_e32 v13, 31, v12
	v_bitop3_b32 v12, v13, v12, s87 bitop3:0x36
	v_and_or_b32 v7, v12, s97, v7
	s_nop 1
	v_max_u32_dpp v12, v7, v7 quad_perm:[1,0,3,2] row_mask:0xf bank_mask:0xf bound_ctrl:1
	s_nop 1
	v_max_u32_dpp v12, v12, v12 quad_perm:[2,3,0,1] row_mask:0xf bank_mask:0xf bound_ctrl:1
	s_nop 1
	v_max_u32_dpp v12, v12, v12 row_half_mirror row_mask:0xf bank_mask:0xf bound_ctrl:1
	s_nop 1
	v_max_u32_dpp v12, v12, v12 row_mirror row_mask:0xf bank_mask:0xf bound_ctrl:1
	v_cmp_eq_u32_e32 vcc, v7, v12
	v_cndmask_b32_e64 v8, v8, v12, s[36:37]
	s_nop 0
	v_cndmask_b32_e64 v7, 0, 1, vcc
	v_lshl_add_u32 v9, v7, 2, v9
	v_addc_co_u32_e32 v10, vcc, v10, v11, vcc
	ds_read_b32 v11, v9
	v_sub_u32_e32 v10, v63, v10
	s_waitcnt lgkmcnt(0)
	v_add_f32_e32 v11, v11, v3
	v_ashrrev_i32_e32 v12, 31, v11
	v_bitop3_b32 v11, v12, v11, s87 bitop3:0x36
	v_and_or_b32 v10, v11, s97, v10
	s_nop 1
	v_max_u32_dpp v11, v10, v10 quad_perm:[1,0,3,2] row_mask:0xf bank_mask:0xf bound_ctrl:1
	s_nop 1
	v_max_u32_dpp v11, v11, v11 quad_perm:[2,3,0,1] row_mask:0xf bank_mask:0xf bound_ctrl:1
	s_nop 1
	v_max_u32_dpp v11, v11, v11 row_half_mirror row_mask:0xf bank_mask:0xf bound_ctrl:1
	s_nop 1
	v_max_u32_dpp v11, v11, v11 row_mirror row_mask:0xf bank_mask:0xf bound_ctrl:1
	v_cmp_eq_u32_e32 vcc, v10, v11
	v_cndmask_b32_e64 v8, v8, v11, s[38:39]
	s_nop 0
	v_cndmask_b32_e64 v10, 0, 1, vcc
	v_addc_co_u32_e32 v5, vcc, v5, v7, vcc
	v_lshl_add_u32 v7, v10, 2, v9
	ds_read_b32 v7, v7
	v_sub_u32_e32 v5, v63, v5
	s_waitcnt lgkmcnt(0)
	v_add_f32_e32 v3, v7, v3
	v_ashrrev_i32_e32 v7, 31, v3
	v_bitop3_b32 v3, v7, v3, s87 bitop3:0x36
	v_and_or_b32 v3, v3, s97, v5
	s_nop 1
	v_max_u32_dpp v3, v3, v3 quad_perm:[1,0,3,2] row_mask:0xf bank_mask:0xf bound_ctrl:1
	s_nop 1
	v_max_u32_dpp v3, v3, v3 quad_perm:[2,3,0,1] row_mask:0xf bank_mask:0xf bound_ctrl:1
	s_nop 1
	v_max_u32_dpp v3, v3, v3 row_half_mirror row_mask:0xf bank_mask:0xf bound_ctrl:1
	s_nop 1
	v_max_u32_dpp v3, v3, v3 row_mirror row_mask:0xf bank_mask:0xf bound_ctrl:1
	v_cndmask_b32_e64 v3, v8, v3, s[40:41]
	v_cmp_lt_i32_e32 vcc, -1, v3
	v_not_b32_e32 v5, v3
	v_bitop3_b32 v8, v3, 15, v3 bitop3:0xc
	v_cndmask_b32_e64 v7, v78, -1, vcc
	v_bitop3_b32 v7, v7, v3, s97 bitop3:0x78
	v_max_u32_dpp v3, v3, v3 quad_perm:[1,0,3,2] row_mask:0xf bank_mask:0xf bound_ctrl:1
	v_lshrrev_b32_e32 v5, 2, v5
	v_and_b32_e32 v5, 60, v5
	v_max_u32_dpp v3, v3, v3 quad_perm:[2,3,0,1] row_mask:0xf bank_mask:0xf bound_ctrl:1
	v_add_u32_e32 v5, v60, v5
	v_lshl_add_u32 v8, v8, 2, v60
	v_max_u32_dpp v3, v3, v3 row_half_mirror row_mask:0xf bank_mask:0xf bound_ctrl:1
	ds_read_b32 v5, v5 offset:64
	ds_read_b32 v10, v8 offset:128
	v_max_u32_dpp v3, v3, v3 row_mirror row_mask:0xf bank_mask:0xf bound_ctrl:1
	v_cmp_lt_i32_e32 vcc, -1, v3
	s_waitcnt lgkmcnt(0)
	v_lshl_add_u32 v5, v5, 7, v10
	v_cndmask_b32_e64 v8, v78, -1, vcc
	v_bitop3_b32 v3, v8, v3, s97 bitop3:0x78
	v_sub_f32_e32 v3, v7, v3
	v_mul_f32_e32 v3, 0x3fb8aa3b, v3
	v_exp_f32_e32 v3, v3
	v_add_u32_e32 v8, 1, v2
	v_ashrrev_i32_e32 v9, 31, v8
	v_lshlrev_b64 v[8:9], 9, v[8:9]
	v_add_f32_dpp v7, v3, v3 quad_perm:[1,0,3,2] row_mask:0xf bank_mask:0xf bound_ctrl:1
	v_or_b32_e32 v8, v8, v79
	v_lshl_add_u64 v[10:11], s[50:51], 0, v[8:9]
	v_add_f32_dpp v7, v7, v7 quad_perm:[2,3,0,1] row_mask:0xf bank_mask:0xf bound_ctrl:1
	global_store_dword v[10:11], v5, off
	v_lshl_add_u64 v[8:9], s[58:59], 0, v[8:9]
	v_add_f32_dpp v7, v7, v7 row_half_mirror row_mask:0xf bank_mask:0xf bound_ctrl:1
	s_nop 1
	v_add_f32_dpp v7, v7, v7 row_mirror row_mask:0xf bank_mask:0xf bound_ctrl:1
	v_div_scale_f32 v5, s[46:47], v7, v7, v3
	v_rcp_f32_e32 v10, v5
	s_nop 0
	v_fma_f32 v11, -v5, v10, 1.0
	v_fmac_f32_e32 v10, v11, v10
	v_div_scale_f32 v11, vcc, v3, v7, v3
	v_mul_f32_e32 v12, v11, v10
	v_fma_f32 v13, -v5, v12, v11
	v_fmac_f32_e32 v12, v13, v10
	v_fma_f32 v5, -v5, v12, v11
	v_div_fmas_f32 v5, v5, v10, v12
	v_div_fixup_f32 v3, v5, v7, v3
	v_cmp_lt_i32_e32 vcc, -1, v81
	global_store_dword v[8:9], v3, off
	s_nop 0
	v_cndmask_b32_e64 v3, v78, -1, vcc
	v_cmp_lt_i32_e32 vcc, -1, v6
	v_bitop3_b32 v3, v3, v81, s96 bitop3:0x78
	s_nop 0
	v_cndmask_b32_e64 v5, v78, -1, vcc
	v_bitop3_b32 v5, v5, v6, s96 bitop3:0x78
	ds_write_b32 v62, v5
	v_bitop3_b32 v5, v81, s77, v81 bitop3:0xc
	ds_write_b32 v62, v5 offset:64
	v_bitop3_b32 v5, v6, s77, v6 bitop3:0xc
	ds_write_b32 v62, v5 offset:128
	ds_read_b32 v5, v60
	s_waitcnt lgkmcnt(0)
	v_add_f32_e32 v5, v5, v3
	v_ashrrev_i32_e32 v6, 31, v5
	v_bitop3_b32 v5, v6, v5, s87 bitop3:0x36
	v_and_or_b32 v5, v5, s97, v63
	s_nop 1
	v_max_u32_dpp v6, v5, v5 quad_perm:[1,0,3,2] row_mask:0xf bank_mask:0xf bound_ctrl:1
	s_nop 1
	v_max_u32_dpp v6, v6, v6 quad_perm:[2,3,0,1] row_mask:0xf bank_mask:0xf bound_ctrl:1
	s_nop 1
	v_max_u32_dpp v6, v6, v6 row_half_mirror row_mask:0xf bank_mask:0xf bound_ctrl:1
	s_nop 1
	v_max_u32_dpp v6, v6, v6 row_mirror row_mask:0xf bank_mask:0xf bound_ctrl:1
	v_cmp_eq_u32_e32 vcc, v5, v6
	v_cndmask_b32_e64 v7, 0, v6, s[8:9]
	s_nop 0
	v_cndmask_b32_e64 v5, 0, 1, vcc
	v_lshl_add_u32 v8, v5, 2, v60
	ds_read_b32 v9, v8
	v_subbrev_co_u32_e32 v6, vcc, 0, v63, vcc
	s_waitcnt lgkmcnt(0)
	v_add_f32_e32 v9, v9, v3
	v_ashrrev_i32_e32 v10, 31, v9
	v_bitop3_b32 v9, v10, v9, s87 bitop3:0x36
	v_and_or_b32 v6, v9, s97, v6
	s_nop 1
	v_max_u32_dpp v9, v6, v6 quad_perm:[1,0,3,2] row_mask:0xf bank_mask:0xf bound_ctrl:1
	s_nop 1
	v_max_u32_dpp v9, v9, v9 quad_perm:[2,3,0,1] row_mask:0xf bank_mask:0xf bound_ctrl:1
	s_nop 1
	v_max_u32_dpp v9, v9, v9 row_half_mirror row_mask:0xf bank_mask:0xf bound_ctrl:1
	s_nop 1
	v_max_u32_dpp v9, v9, v9 row_mirror row_mask:0xf bank_mask:0xf bound_ctrl:1
	v_cmp_eq_u32_e32 vcc, v6, v9
	v_cndmask_b32_e64 v7, v7, v9, s[10:11]
	s_nop 0
	v_cndmask_b32_e64 v6, 0, 1, vcc
	v_lshl_add_u32 v8, v6, 2, v8
	ds_read_b32 v11, v8
	v_addc_co_u32_e32 v9, vcc, 0, v5, vcc
	v_sub_u32_e32 v10, v63, v9
	s_waitcnt lgkmcnt(0)
	v_add_f32_e32 v11, v11, v3
	v_ashrrev_i32_e32 v12, 31, v11
	v_bitop3_b32 v11, v12, v11, s87 bitop3:0x36
	v_and_or_b32 v10, v11, s97, v10
	s_nop 1
	v_max_u32_dpp v11, v10, v10 quad_perm:[1,0,3,2] row_mask:0xf bank_mask:0xf bound_ctrl:1
	s_nop 1
	v_max_u32_dpp v11, v11, v11 quad_perm:[2,3,0,1] row_mask:0xf bank_mask:0xf bound_ctrl:1
	s_nop 1
	v_max_u32_dpp v11, v11, v11 row_half_mirror row_mask:0xf bank_mask:0xf bound_ctrl:1
	s_nop 1
	v_max_u32_dpp v11, v11, v11 row_mirror row_mask:0xf bank_mask:0xf bound_ctrl:1
	v_cmp_eq_u32_e32 vcc, v10, v11
	v_cndmask_b32_e64 v7, v7, v11, s[12:13]
	s_nop 0
	v_cndmask_b32_e64 v10, 0, 1, vcc
	v_lshl_add_u32 v8, v10, 2, v8
	ds_read_b32 v11, v8
	v_addc_co_u32_e32 v5, vcc, v6, v5, vcc
	v_sub_u32_e32 v6, v63, v5
	s_waitcnt lgkmcnt(0)
	v_add_f32_e32 v11, v11, v3
	v_ashrrev_i32_e32 v12, 31, v11
	v_bitop3_b32 v11, v12, v11, s87 bitop3:0x36
	v_and_or_b32 v6, v11, s97, v6
	s_nop 1
	v_max_u32_dpp v11, v6, v6 quad_perm:[1,0,3,2] row_mask:0xf bank_mask:0xf bound_ctrl:1
	s_nop 1
	v_max_u32_dpp v11, v11, v11 quad_perm:[2,3,0,1] row_mask:0xf bank_mask:0xf bound_ctrl:1
	s_nop 1
	v_max_u32_dpp v11, v11, v11 row_half_mirror row_mask:0xf bank_mask:0xf bound_ctrl:1
	s_nop 1
	v_max_u32_dpp v11, v11, v11 row_mirror row_mask:0xf bank_mask:0xf bound_ctrl:1
	v_cmp_eq_u32_e32 vcc, v6, v11
	v_cndmask_b32_e64 v7, v7, v11, s[14:15]
	s_nop 0
	v_cndmask_b32_e64 v6, 0, 1, vcc
	v_lshl_add_u32 v8, v6, 2, v8
	ds_read_b32 v11, v8
	v_addc_co_u32_e32 v9, vcc, v9, v10, vcc
	v_sub_u32_e32 v10, v63, v9
	s_waitcnt lgkmcnt(0)
	v_add_f32_e32 v11, v11, v3
	v_ashrrev_i32_e32 v12, 31, v11
	v_bitop3_b32 v11, v12, v11, s87 bitop3:0x36
	v_and_or_b32 v10, v11, s97, v10
	s_nop 1
	v_max_u32_dpp v11, v10, v10 quad_perm:[1,0,3,2] row_mask:0xf bank_mask:0xf bound_ctrl:1
	s_nop 1
	v_max_u32_dpp v11, v11, v11 quad_perm:[2,3,0,1] row_mask:0xf bank_mask:0xf bound_ctrl:1
	s_nop 1
	v_max_u32_dpp v11, v11, v11 row_half_mirror row_mask:0xf bank_mask:0xf bound_ctrl:1
	s_nop 1
	v_max_u32_dpp v11, v11, v11 row_mirror row_mask:0xf bank_mask:0xf bound_ctrl:1
	v_cmp_eq_u32_e32 vcc, v10, v11
	v_cndmask_b32_e64 v7, v7, v11, s[16:17]
	s_nop 0
	v_cndmask_b32_e64 v10, 0, 1, vcc
	v_lshl_add_u32 v8, v10, 2, v8
	ds_read_b32 v11, v8
	v_addc_co_u32_e32 v5, vcc, v5, v6, vcc
	v_sub_u32_e32 v6, v63, v5
	s_waitcnt lgkmcnt(0)
	v_add_f32_e32 v11, v11, v3
	v_ashrrev_i32_e32 v12, 31, v11
	v_bitop3_b32 v11, v12, v11, s87 bitop3:0x36
	v_and_or_b32 v6, v11, s97, v6
	s_nop 1
	v_max_u32_dpp v11, v6, v6 quad_perm:[1,0,3,2] row_mask:0xf bank_mask:0xf bound_ctrl:1
	s_nop 1
	v_max_u32_dpp v11, v11, v11 quad_perm:[2,3,0,1] row_mask:0xf bank_mask:0xf bound_ctrl:1
	s_nop 1
	v_max_u32_dpp v11, v11, v11 row_half_mirror row_mask:0xf bank_mask:0xf bound_ctrl:1
	s_nop 1
	v_max_u32_dpp v11, v11, v11 row_mirror row_mask:0xf bank_mask:0xf bound_ctrl:1
	v_cmp_eq_u32_e32 vcc, v6, v11
	v_cndmask_b32_e64 v7, v7, v11, s[18:19]
	s_nop 0
	v_cndmask_b32_e64 v6, 0, 1, vcc
	v_lshl_add_u32 v8, v6, 2, v8
	ds_read_b32 v11, v8
	v_addc_co_u32_e32 v9, vcc, v9, v10, vcc
	v_sub_u32_e32 v10, v63, v9
	s_waitcnt lgkmcnt(0)
	v_add_f32_e32 v11, v11, v3
	v_ashrrev_i32_e32 v12, 31, v11
	v_bitop3_b32 v11, v12, v11, s87 bitop3:0x36
	v_and_or_b32 v10, v11, s97, v10
	s_nop 1
	v_max_u32_dpp v11, v10, v10 quad_perm:[1,0,3,2] row_mask:0xf bank_mask:0xf bound_ctrl:1
	s_nop 1
	v_max_u32_dpp v11, v11, v11 quad_perm:[2,3,0,1] row_mask:0xf bank_mask:0xf bound_ctrl:1
	s_nop 1
	v_max_u32_dpp v11, v11, v11 row_half_mirror row_mask:0xf bank_mask:0xf bound_ctrl:1
	s_nop 1
	v_max_u32_dpp v11, v11, v11 row_mirror row_mask:0xf bank_mask:0xf bound_ctrl:1
	v_cmp_eq_u32_e32 vcc, v10, v11
	v_cndmask_b32_e64 v7, v7, v11, s[20:21]
	s_nop 0
	v_cndmask_b32_e64 v10, 0, 1, vcc
	v_lshl_add_u32 v8, v10, 2, v8
	ds_read_b32 v11, v8
	v_addc_co_u32_e32 v5, vcc, v5, v6, vcc
	v_sub_u32_e32 v6, v63, v5
	s_waitcnt lgkmcnt(0)
	v_add_f32_e32 v11, v11, v3
	v_ashrrev_i32_e32 v12, 31, v11
	v_bitop3_b32 v11, v12, v11, s87 bitop3:0x36
	v_and_or_b32 v6, v11, s97, v6
	s_nop 1
	v_max_u32_dpp v11, v6, v6 quad_perm:[1,0,3,2] row_mask:0xf bank_mask:0xf bound_ctrl:1
	s_nop 1
	v_max_u32_dpp v11, v11, v11 quad_perm:[2,3,0,1] row_mask:0xf bank_mask:0xf bound_ctrl:1
	s_nop 1
	v_max_u32_dpp v11, v11, v11 row_half_mirror row_mask:0xf bank_mask:0xf bound_ctrl:1
	s_nop 1
	v_max_u32_dpp v11, v11, v11 row_mirror row_mask:0xf bank_mask:0xf bound_ctrl:1
	v_cmp_eq_u32_e32 vcc, v6, v11
	v_cndmask_b32_e64 v7, v7, v11, s[22:23]
	s_nop 0
	v_cndmask_b32_e64 v6, 0, 1, vcc
	v_lshl_add_u32 v8, v6, 2, v8
	ds_read_b32 v11, v8
	v_addc_co_u32_e32 v9, vcc, v9, v10, vcc
	v_sub_u32_e32 v10, v63, v9
	s_waitcnt lgkmcnt(0)
	v_add_f32_e32 v11, v11, v3
	v_ashrrev_i32_e32 v12, 31, v11
	v_bitop3_b32 v11, v12, v11, s87 bitop3:0x36
	v_and_or_b32 v10, v11, s97, v10
	s_nop 1
	v_max_u32_dpp v11, v10, v10 quad_perm:[1,0,3,2] row_mask:0xf bank_mask:0xf bound_ctrl:1
	s_nop 1
	v_max_u32_dpp v11, v11, v11 quad_perm:[2,3,0,1] row_mask:0xf bank_mask:0xf bound_ctrl:1
	s_nop 1
	v_max_u32_dpp v11, v11, v11 row_half_mirror row_mask:0xf bank_mask:0xf bound_ctrl:1
	s_nop 1
	v_max_u32_dpp v11, v11, v11 row_mirror row_mask:0xf bank_mask:0xf bound_ctrl:1
	v_cmp_eq_u32_e32 vcc, v10, v11
	v_cndmask_b32_e64 v7, v7, v11, s[24:25]
	s_nop 0
	v_cndmask_b32_e64 v10, 0, 1, vcc
	v_lshl_add_u32 v8, v10, 2, v8
	ds_read_b32 v11, v8
	v_addc_co_u32_e32 v5, vcc, v5, v6, vcc
	v_sub_u32_e32 v6, v63, v5
	s_waitcnt lgkmcnt(0)
	v_add_f32_e32 v11, v11, v3
	v_ashrrev_i32_e32 v12, 31, v11
	v_bitop3_b32 v11, v12, v11, s87 bitop3:0x36
	v_and_or_b32 v6, v11, s97, v6
	s_nop 1
	v_max_u32_dpp v11, v6, v6 quad_perm:[1,0,3,2] row_mask:0xf bank_mask:0xf bound_ctrl:1
	s_nop 1
	v_max_u32_dpp v11, v11, v11 quad_perm:[2,3,0,1] row_mask:0xf bank_mask:0xf bound_ctrl:1
	s_nop 1
	v_max_u32_dpp v11, v11, v11 row_half_mirror row_mask:0xf bank_mask:0xf bound_ctrl:1
	s_nop 1
	v_max_u32_dpp v11, v11, v11 row_mirror row_mask:0xf bank_mask:0xf bound_ctrl:1
	v_cmp_eq_u32_e32 vcc, v6, v11
	v_cndmask_b32_e64 v7, v7, v11, s[26:27]
	s_nop 0
	v_cndmask_b32_e64 v6, 0, 1, vcc
	v_lshl_add_u32 v8, v6, 2, v8
	ds_read_b32 v11, v8
	v_addc_co_u32_e32 v9, vcc, v9, v10, vcc
	v_sub_u32_e32 v10, v63, v9
	s_waitcnt lgkmcnt(0)
	v_add_f32_e32 v11, v11, v3
	v_ashrrev_i32_e32 v12, 31, v11
	v_bitop3_b32 v11, v12, v11, s87 bitop3:0x36
	v_and_or_b32 v10, v11, s97, v10
	s_nop 1
	v_max_u32_dpp v11, v10, v10 quad_perm:[1,0,3,2] row_mask:0xf bank_mask:0xf bound_ctrl:1
	s_nop 1
	v_max_u32_dpp v11, v11, v11 quad_perm:[2,3,0,1] row_mask:0xf bank_mask:0xf bound_ctrl:1
	s_nop 1
	v_max_u32_dpp v11, v11, v11 row_half_mirror row_mask:0xf bank_mask:0xf bound_ctrl:1
	s_nop 1
	v_max_u32_dpp v11, v11, v11 row_mirror row_mask:0xf bank_mask:0xf bound_ctrl:1
	v_cmp_eq_u32_e32 vcc, v10, v11
	v_cndmask_b32_e64 v7, v7, v11, s[28:29]
	s_nop 0
	v_cndmask_b32_e64 v10, 0, 1, vcc
	v_lshl_add_u32 v8, v10, 2, v8
	ds_read_b32 v11, v8
	v_addc_co_u32_e32 v5, vcc, v5, v6, vcc
	v_sub_u32_e32 v6, v63, v5
	s_waitcnt lgkmcnt(0)
	v_add_f32_e32 v11, v11, v3
	v_ashrrev_i32_e32 v12, 31, v11
	v_bitop3_b32 v11, v12, v11, s87 bitop3:0x36
	v_and_or_b32 v6, v11, s97, v6
	s_nop 1
	v_max_u32_dpp v11, v6, v6 quad_perm:[1,0,3,2] row_mask:0xf bank_mask:0xf bound_ctrl:1
	s_nop 1
	v_max_u32_dpp v11, v11, v11 quad_perm:[2,3,0,1] row_mask:0xf bank_mask:0xf bound_ctrl:1
	s_nop 1
	v_max_u32_dpp v11, v11, v11 row_half_mirror row_mask:0xf bank_mask:0xf bound_ctrl:1
	s_nop 1
	v_max_u32_dpp v11, v11, v11 row_mirror row_mask:0xf bank_mask:0xf bound_ctrl:1
	v_cmp_eq_u32_e32 vcc, v6, v11
	v_cndmask_b32_e64 v7, v7, v11, s[30:31]
	s_nop 0
	v_cndmask_b32_e64 v6, 0, 1, vcc
	v_lshl_add_u32 v8, v6, 2, v8
	ds_read_b32 v11, v8
	v_addc_co_u32_e32 v9, vcc, v9, v10, vcc
	v_sub_u32_e32 v10, v63, v9
	s_waitcnt lgkmcnt(0)
	v_add_f32_e32 v11, v11, v3
	v_ashrrev_i32_e32 v12, 31, v11
	v_bitop3_b32 v11, v12, v11, s87 bitop3:0x36
	v_and_or_b32 v10, v11, s97, v10
	s_nop 1
	v_max_u32_dpp v11, v10, v10 quad_perm:[1,0,3,2] row_mask:0xf bank_mask:0xf bound_ctrl:1
	s_nop 1
	v_max_u32_dpp v11, v11, v11 quad_perm:[2,3,0,1] row_mask:0xf bank_mask:0xf bound_ctrl:1
	s_nop 1
	v_max_u32_dpp v11, v11, v11 row_half_mirror row_mask:0xf bank_mask:0xf bound_ctrl:1
	s_nop 1
	v_max_u32_dpp v11, v11, v11 row_mirror row_mask:0xf bank_mask:0xf bound_ctrl:1
	v_cmp_eq_u32_e32 vcc, v10, v11
	v_cndmask_b32_e64 v7, v7, v11, s[34:35]
	s_nop 0
	v_cndmask_b32_e64 v10, 0, 1, vcc
	v_lshl_add_u32 v8, v10, 2, v8
	ds_read_b32 v11, v8
	v_addc_co_u32_e32 v5, vcc, v5, v6, vcc
	v_sub_u32_e32 v6, v63, v5
	s_waitcnt lgkmcnt(0)
	v_add_f32_e32 v11, v11, v3
	v_ashrrev_i32_e32 v12, 31, v11
	v_bitop3_b32 v11, v12, v11, s87 bitop3:0x36
	v_and_or_b32 v6, v11, s97, v6
	s_nop 1
	v_max_u32_dpp v11, v6, v6 quad_perm:[1,0,3,2] row_mask:0xf bank_mask:0xf bound_ctrl:1
	s_nop 1
	v_max_u32_dpp v11, v11, v11 quad_perm:[2,3,0,1] row_mask:0xf bank_mask:0xf bound_ctrl:1
	s_nop 1
	v_max_u32_dpp v11, v11, v11 row_half_mirror row_mask:0xf bank_mask:0xf bound_ctrl:1
	s_nop 1
	v_max_u32_dpp v11, v11, v11 row_mirror row_mask:0xf bank_mask:0xf bound_ctrl:1
	v_cmp_eq_u32_e32 vcc, v6, v11
	v_cndmask_b32_e64 v7, v7, v11, s[36:37]
	s_nop 0
	v_cndmask_b32_e64 v6, 0, 1, vcc
	v_lshl_add_u32 v8, v6, 2, v8
	v_addc_co_u32_e32 v9, vcc, v9, v10, vcc
	ds_read_b32 v10, v8
	v_sub_u32_e32 v9, v63, v9
	s_waitcnt lgkmcnt(0)
	v_add_f32_e32 v10, v10, v3
	v_ashrrev_i32_e32 v11, 31, v10
	v_bitop3_b32 v10, v11, v10, s87 bitop3:0x36
	v_and_or_b32 v9, v10, s97, v9
	s_nop 1
	v_max_u32_dpp v10, v9, v9 quad_perm:[1,0,3,2] row_mask:0xf bank_mask:0xf bound_ctrl:1
	s_nop 1
	v_max_u32_dpp v10, v10, v10 quad_perm:[2,3,0,1] row_mask:0xf bank_mask:0xf bound_ctrl:1
	s_nop 1
	v_max_u32_dpp v10, v10, v10 row_half_mirror row_mask:0xf bank_mask:0xf bound_ctrl:1
	s_nop 1
	v_max_u32_dpp v10, v10, v10 row_mirror row_mask:0xf bank_mask:0xf bound_ctrl:1
	v_cmp_eq_u32_e32 vcc, v9, v10
	v_cndmask_b32_e64 v7, v7, v10, s[38:39]
	s_nop 0
	v_cndmask_b32_e64 v9, 0, 1, vcc
	v_addc_co_u32_e32 v5, vcc, v5, v6, vcc
	v_lshl_add_u32 v6, v9, 2, v8
	ds_read_b32 v6, v6
	v_sub_u32_e32 v5, v63, v5
	s_waitcnt lgkmcnt(0)
	v_add_f32_e32 v3, v6, v3
	v_ashrrev_i32_e32 v6, 31, v3
	v_bitop3_b32 v3, v6, v3, s87 bitop3:0x36
	v_and_or_b32 v3, v3, s97, v5
	s_nop 1
	v_max_u32_dpp v3, v3, v3 quad_perm:[1,0,3,2] row_mask:0xf bank_mask:0xf bound_ctrl:1
	s_nop 1
	v_max_u32_dpp v3, v3, v3 quad_perm:[2,3,0,1] row_mask:0xf bank_mask:0xf bound_ctrl:1
	s_nop 1
	v_max_u32_dpp v3, v3, v3 row_half_mirror row_mask:0xf bank_mask:0xf bound_ctrl:1
	s_nop 1
	v_max_u32_dpp v3, v3, v3 row_mirror row_mask:0xf bank_mask:0xf bound_ctrl:1
	v_cndmask_b32_e64 v3, v7, v3, s[40:41]
	v_cmp_lt_i32_e32 vcc, -1, v3
	v_not_b32_e32 v5, v3
	v_bitop3_b32 v7, v3, 15, v3 bitop3:0xc
	v_cndmask_b32_e64 v6, v78, -1, vcc
	v_bitop3_b32 v6, v6, v3, s97 bitop3:0x78
	v_max_u32_dpp v3, v3, v3 quad_perm:[1,0,3,2] row_mask:0xf bank_mask:0xf bound_ctrl:1
	v_lshrrev_b32_e32 v5, 2, v5
	v_and_b32_e32 v5, 60, v5
	v_max_u32_dpp v3, v3, v3 quad_perm:[2,3,0,1] row_mask:0xf bank_mask:0xf bound_ctrl:1
	v_add_u32_e32 v5, v60, v5
	v_lshl_add_u32 v7, v7, 2, v60
	v_max_u32_dpp v3, v3, v3 row_half_mirror row_mask:0xf bank_mask:0xf bound_ctrl:1
	ds_read_b32 v5, v5 offset:64
	ds_read_b32 v8, v7 offset:128
	v_max_u32_dpp v3, v3, v3 row_mirror row_mask:0xf bank_mask:0xf bound_ctrl:1
	v_cmp_lt_i32_e32 vcc, -1, v3
	s_waitcnt lgkmcnt(0)
	v_lshl_add_u32 v5, v5, 7, v8
	v_cndmask_b32_e64 v7, v78, -1, vcc
	v_bitop3_b32 v3, v7, v3, s97 bitop3:0x78
	v_sub_f32_e32 v3, v6, v3
	v_mul_f32_e32 v3, 0x3fb8aa3b, v3
	v_exp_f32_e32 v3, v3
	s_nop 1
	v_add_f32_dpp v6, v3, v3 quad_perm:[1,0,3,2] row_mask:0xf bank_mask:0xf bound_ctrl:1
	s_nop 1
	v_add_f32_dpp v6, v6, v6 quad_perm:[2,3,0,1] row_mask:0xf bank_mask:0xf bound_ctrl:1
	s_nop 1
	v_add_f32_dpp v6, v6, v6 row_half_mirror row_mask:0xf bank_mask:0xf bound_ctrl:1
	s_nop 1
	v_add_f32_dpp v10, v6, v6 row_mirror row_mask:0xf bank_mask:0xf bound_ctrl:1
	v_add_u32_e32 v6, 2, v2
	v_ashrrev_i32_e32 v7, 31, v6
	v_lshlrev_b64 v[6:7], 9, v[6:7]
	v_or_b32_e32 v6, v6, v79
	v_lshl_add_u64 v[8:9], s[50:51], 0, v[6:7]
	global_store_dword v[8:9], v5, off
	v_div_scale_f32 v5, s[46:47], v10, v10, v3
	v_rcp_f32_e32 v8, v5
	v_lshl_add_u64 v[6:7], s[58:59], 0, v[6:7]
	v_add_u32_e32 v2, 3, v2
	v_fma_f32 v9, -v5, v8, 1.0
	v_fmac_f32_e32 v8, v9, v8
	v_div_scale_f32 v9, vcc, v3, v10, v3
	v_mul_f32_e32 v11, v9, v8
	v_fma_f32 v12, -v5, v11, v9
	v_fmac_f32_e32 v11, v12, v8
	v_fma_f32 v5, -v5, v11, v9
	v_div_fmas_f32 v5, v5, v8, v11
	v_div_fixup_f32 v3, v5, v10, v3
	v_cmp_lt_i32_e32 vcc, -1, v80
	global_store_dword v[6:7], v3, off
	s_nop 0
	v_cndmask_b32_e64 v3, v78, -1, vcc
	v_cmp_lt_i32_e32 vcc, -1, v4
	v_bitop3_b32 v3, v3, v80, s96 bitop3:0x78
	s_nop 0
	v_cndmask_b32_e64 v5, v78, -1, vcc
	v_bitop3_b32 v5, v5, v4, s96 bitop3:0x78
	ds_write_b32 v62, v5
	v_bitop3_b32 v4, v4, s77, v4 bitop3:0xc
	ds_write_b32 v62, v4 offset:128
	ds_read_b32 v4, v60
	v_bitop3_b32 v5, v80, s77, v80 bitop3:0xc
	ds_write_b32 v62, v5 offset:64
	s_waitcnt lgkmcnt(1)
	v_add_f32_e32 v4, v4, v3
	v_ashrrev_i32_e32 v5, 31, v4
	v_bitop3_b32 v4, v5, v4, s87 bitop3:0x36
	v_and_or_b32 v4, v4, s97, v63
	s_nop 1
	v_max_u32_dpp v5, v4, v4 quad_perm:[1,0,3,2] row_mask:0xf bank_mask:0xf bound_ctrl:1
	s_nop 1
	v_max_u32_dpp v5, v5, v5 quad_perm:[2,3,0,1] row_mask:0xf bank_mask:0xf bound_ctrl:1
	s_nop 1
	v_max_u32_dpp v5, v5, v5 row_half_mirror row_mask:0xf bank_mask:0xf bound_ctrl:1
	s_nop 1
	v_max_u32_dpp v5, v5, v5 row_mirror row_mask:0xf bank_mask:0xf bound_ctrl:1
	v_cmp_eq_u32_e32 vcc, v4, v5
	v_cndmask_b32_e64 v6, 0, v5, s[8:9]
	s_nop 0
	v_cndmask_b32_e64 v4, 0, 1, vcc
	v_lshl_add_u32 v7, v4, 2, v60
	ds_read_b32 v8, v7
	v_subbrev_co_u32_e32 v5, vcc, 0, v63, vcc
	s_waitcnt lgkmcnt(0)
	v_add_f32_e32 v8, v8, v3
	v_ashrrev_i32_e32 v9, 31, v8
	v_bitop3_b32 v8, v9, v8, s87 bitop3:0x36
	v_and_or_b32 v5, v8, s97, v5
	s_nop 1
	v_max_u32_dpp v8, v5, v5 quad_perm:[1,0,3,2] row_mask:0xf bank_mask:0xf bound_ctrl:1
	s_nop 1
	v_max_u32_dpp v8, v8, v8 quad_perm:[2,3,0,1] row_mask:0xf bank_mask:0xf bound_ctrl:1
	s_nop 1
	v_max_u32_dpp v8, v8, v8 row_half_mirror row_mask:0xf bank_mask:0xf bound_ctrl:1
	s_nop 1
	v_max_u32_dpp v8, v8, v8 row_mirror row_mask:0xf bank_mask:0xf bound_ctrl:1
	v_cmp_eq_u32_e32 vcc, v5, v8
	v_cndmask_b32_e64 v6, v6, v8, s[10:11]
	s_nop 0
	v_cndmask_b32_e64 v5, 0, 1, vcc
	v_lshl_add_u32 v7, v5, 2, v7
	ds_read_b32 v10, v7
	v_addc_co_u32_e32 v8, vcc, 0, v4, vcc
	v_sub_u32_e32 v9, v63, v8
	s_waitcnt lgkmcnt(0)
	v_add_f32_e32 v10, v10, v3
	v_ashrrev_i32_e32 v11, 31, v10
	v_bitop3_b32 v10, v11, v10, s87 bitop3:0x36
	v_and_or_b32 v9, v10, s97, v9
	s_nop 1
	v_max_u32_dpp v10, v9, v9 quad_perm:[1,0,3,2] row_mask:0xf bank_mask:0xf bound_ctrl:1
	s_nop 1
	v_max_u32_dpp v10, v10, v10 quad_perm:[2,3,0,1] row_mask:0xf bank_mask:0xf bound_ctrl:1
	s_nop 1
	v_max_u32_dpp v10, v10, v10 row_half_mirror row_mask:0xf bank_mask:0xf bound_ctrl:1
	s_nop 1
	v_max_u32_dpp v10, v10, v10 row_mirror row_mask:0xf bank_mask:0xf bound_ctrl:1
	v_cmp_eq_u32_e32 vcc, v9, v10
	v_cndmask_b32_e64 v6, v6, v10, s[12:13]
	s_nop 0
	v_cndmask_b32_e64 v9, 0, 1, vcc
	v_lshl_add_u32 v7, v9, 2, v7
	ds_read_b32 v10, v7
	v_addc_co_u32_e32 v4, vcc, v5, v4, vcc
	v_sub_u32_e32 v5, v63, v4
	s_waitcnt lgkmcnt(0)
	v_add_f32_e32 v10, v10, v3
	v_ashrrev_i32_e32 v11, 31, v10
	v_bitop3_b32 v10, v11, v10, s87 bitop3:0x36
	v_and_or_b32 v5, v10, s97, v5
	s_nop 1
	v_max_u32_dpp v10, v5, v5 quad_perm:[1,0,3,2] row_mask:0xf bank_mask:0xf bound_ctrl:1
	s_nop 1
	v_max_u32_dpp v10, v10, v10 quad_perm:[2,3,0,1] row_mask:0xf bank_mask:0xf bound_ctrl:1
	s_nop 1
	v_max_u32_dpp v10, v10, v10 row_half_mirror row_mask:0xf bank_mask:0xf bound_ctrl:1
	s_nop 1
	v_max_u32_dpp v10, v10, v10 row_mirror row_mask:0xf bank_mask:0xf bound_ctrl:1
	v_cmp_eq_u32_e32 vcc, v5, v10
	v_cndmask_b32_e64 v6, v6, v10, s[14:15]
	s_nop 0
	v_cndmask_b32_e64 v5, 0, 1, vcc
	v_lshl_add_u32 v7, v5, 2, v7
	ds_read_b32 v10, v7
	v_addc_co_u32_e32 v8, vcc, v8, v9, vcc
	v_sub_u32_e32 v9, v63, v8
	s_waitcnt lgkmcnt(0)
	v_add_f32_e32 v10, v10, v3
	v_ashrrev_i32_e32 v11, 31, v10
	v_bitop3_b32 v10, v11, v10, s87 bitop3:0x36
	v_and_or_b32 v9, v10, s97, v9
	s_nop 1
	v_max_u32_dpp v10, v9, v9 quad_perm:[1,0,3,2] row_mask:0xf bank_mask:0xf bound_ctrl:1
	s_nop 1
	v_max_u32_dpp v10, v10, v10 quad_perm:[2,3,0,1] row_mask:0xf bank_mask:0xf bound_ctrl:1
	s_nop 1
	v_max_u32_dpp v10, v10, v10 row_half_mirror row_mask:0xf bank_mask:0xf bound_ctrl:1
	s_nop 1
	v_max_u32_dpp v10, v10, v10 row_mirror row_mask:0xf bank_mask:0xf bound_ctrl:1
	v_cmp_eq_u32_e32 vcc, v9, v10
	v_cndmask_b32_e64 v6, v6, v10, s[16:17]
	s_nop 0
	v_cndmask_b32_e64 v9, 0, 1, vcc
	v_lshl_add_u32 v7, v9, 2, v7
	ds_read_b32 v10, v7
	v_addc_co_u32_e32 v4, vcc, v4, v5, vcc
	v_sub_u32_e32 v5, v63, v4
	s_waitcnt lgkmcnt(0)
	v_add_f32_e32 v10, v10, v3
	v_ashrrev_i32_e32 v11, 31, v10
	v_bitop3_b32 v10, v11, v10, s87 bitop3:0x36
	v_and_or_b32 v5, v10, s97, v5
	s_nop 1
	v_max_u32_dpp v10, v5, v5 quad_perm:[1,0,3,2] row_mask:0xf bank_mask:0xf bound_ctrl:1
	s_nop 1
	v_max_u32_dpp v10, v10, v10 quad_perm:[2,3,0,1] row_mask:0xf bank_mask:0xf bound_ctrl:1
	s_nop 1
	v_max_u32_dpp v10, v10, v10 row_half_mirror row_mask:0xf bank_mask:0xf bound_ctrl:1
	s_nop 1
	v_max_u32_dpp v10, v10, v10 row_mirror row_mask:0xf bank_mask:0xf bound_ctrl:1
	v_cmp_eq_u32_e32 vcc, v5, v10
	v_cndmask_b32_e64 v6, v6, v10, s[18:19]
	s_nop 0
	v_cndmask_b32_e64 v5, 0, 1, vcc
	v_lshl_add_u32 v7, v5, 2, v7
	ds_read_b32 v10, v7
	v_addc_co_u32_e32 v8, vcc, v8, v9, vcc
	v_sub_u32_e32 v9, v63, v8
	s_waitcnt lgkmcnt(0)
	v_add_f32_e32 v10, v10, v3
	v_ashrrev_i32_e32 v11, 31, v10
	v_bitop3_b32 v10, v11, v10, s87 bitop3:0x36
	v_and_or_b32 v9, v10, s97, v9
	s_nop 1
	v_max_u32_dpp v10, v9, v9 quad_perm:[1,0,3,2] row_mask:0xf bank_mask:0xf bound_ctrl:1
	s_nop 1
	v_max_u32_dpp v10, v10, v10 quad_perm:[2,3,0,1] row_mask:0xf bank_mask:0xf bound_ctrl:1
	s_nop 1
	v_max_u32_dpp v10, v10, v10 row_half_mirror row_mask:0xf bank_mask:0xf bound_ctrl:1
	s_nop 1
	v_max_u32_dpp v10, v10, v10 row_mirror row_mask:0xf bank_mask:0xf bound_ctrl:1
	v_cmp_eq_u32_e32 vcc, v9, v10
	v_cndmask_b32_e64 v6, v6, v10, s[20:21]
	s_nop 0
	v_cndmask_b32_e64 v9, 0, 1, vcc
	v_lshl_add_u32 v7, v9, 2, v7
	ds_read_b32 v10, v7
	v_addc_co_u32_e32 v4, vcc, v4, v5, vcc
	v_sub_u32_e32 v5, v63, v4
	s_waitcnt lgkmcnt(0)
	v_add_f32_e32 v10, v10, v3
	v_ashrrev_i32_e32 v11, 31, v10
	v_bitop3_b32 v10, v11, v10, s87 bitop3:0x36
	v_and_or_b32 v5, v10, s97, v5
	s_nop 1
	v_max_u32_dpp v10, v5, v5 quad_perm:[1,0,3,2] row_mask:0xf bank_mask:0xf bound_ctrl:1
	s_nop 1
	v_max_u32_dpp v10, v10, v10 quad_perm:[2,3,0,1] row_mask:0xf bank_mask:0xf bound_ctrl:1
	s_nop 1
	v_max_u32_dpp v10, v10, v10 row_half_mirror row_mask:0xf bank_mask:0xf bound_ctrl:1
	s_nop 1
	v_max_u32_dpp v10, v10, v10 row_mirror row_mask:0xf bank_mask:0xf bound_ctrl:1
	v_cmp_eq_u32_e32 vcc, v5, v10
	v_cndmask_b32_e64 v6, v6, v10, s[22:23]
	s_nop 0
	v_cndmask_b32_e64 v5, 0, 1, vcc
	v_lshl_add_u32 v7, v5, 2, v7
	ds_read_b32 v10, v7
	v_addc_co_u32_e32 v8, vcc, v8, v9, vcc
	v_sub_u32_e32 v9, v63, v8
	s_waitcnt lgkmcnt(0)
	v_add_f32_e32 v10, v10, v3
	v_ashrrev_i32_e32 v11, 31, v10
	v_bitop3_b32 v10, v11, v10, s87 bitop3:0x36
	v_and_or_b32 v9, v10, s97, v9
	s_nop 1
	v_max_u32_dpp v10, v9, v9 quad_perm:[1,0,3,2] row_mask:0xf bank_mask:0xf bound_ctrl:1
	s_nop 1
	v_max_u32_dpp v10, v10, v10 quad_perm:[2,3,0,1] row_mask:0xf bank_mask:0xf bound_ctrl:1
	s_nop 1
	v_max_u32_dpp v10, v10, v10 row_half_mirror row_mask:0xf bank_mask:0xf bound_ctrl:1
	s_nop 1
	v_max_u32_dpp v10, v10, v10 row_mirror row_mask:0xf bank_mask:0xf bound_ctrl:1
	v_cmp_eq_u32_e32 vcc, v9, v10
	v_cndmask_b32_e64 v6, v6, v10, s[24:25]
	s_nop 0
	v_cndmask_b32_e64 v9, 0, 1, vcc
	v_lshl_add_u32 v7, v9, 2, v7
	ds_read_b32 v10, v7
	v_addc_co_u32_e32 v4, vcc, v4, v5, vcc
	v_sub_u32_e32 v5, v63, v4
	s_waitcnt lgkmcnt(0)
	v_add_f32_e32 v10, v10, v3
	v_ashrrev_i32_e32 v11, 31, v10
	v_bitop3_b32 v10, v11, v10, s87 bitop3:0x36
	v_and_or_b32 v5, v10, s97, v5
	s_nop 1
	v_max_u32_dpp v10, v5, v5 quad_perm:[1,0,3,2] row_mask:0xf bank_mask:0xf bound_ctrl:1
	s_nop 1
	v_max_u32_dpp v10, v10, v10 quad_perm:[2,3,0,1] row_mask:0xf bank_mask:0xf bound_ctrl:1
	s_nop 1
	v_max_u32_dpp v10, v10, v10 row_half_mirror row_mask:0xf bank_mask:0xf bound_ctrl:1
	s_nop 1
	v_max_u32_dpp v10, v10, v10 row_mirror row_mask:0xf bank_mask:0xf bound_ctrl:1
	v_cmp_eq_u32_e32 vcc, v5, v10
	v_cndmask_b32_e64 v6, v6, v10, s[26:27]
	s_nop 0
	v_cndmask_b32_e64 v5, 0, 1, vcc
	v_lshl_add_u32 v7, v5, 2, v7
	ds_read_b32 v10, v7
	v_addc_co_u32_e32 v8, vcc, v8, v9, vcc
	v_sub_u32_e32 v9, v63, v8
	s_waitcnt lgkmcnt(0)
	v_add_f32_e32 v10, v10, v3
	v_ashrrev_i32_e32 v11, 31, v10
	v_bitop3_b32 v10, v11, v10, s87 bitop3:0x36
	v_and_or_b32 v9, v10, s97, v9
	s_nop 1
	v_max_u32_dpp v10, v9, v9 quad_perm:[1,0,3,2] row_mask:0xf bank_mask:0xf bound_ctrl:1
	s_nop 1
	v_max_u32_dpp v10, v10, v10 quad_perm:[2,3,0,1] row_mask:0xf bank_mask:0xf bound_ctrl:1
	s_nop 1
	v_max_u32_dpp v10, v10, v10 row_half_mirror row_mask:0xf bank_mask:0xf bound_ctrl:1
	s_nop 1
	v_max_u32_dpp v10, v10, v10 row_mirror row_mask:0xf bank_mask:0xf bound_ctrl:1
	v_cmp_eq_u32_e32 vcc, v9, v10
	v_cndmask_b32_e64 v6, v6, v10, s[28:29]
	s_nop 0
	v_cndmask_b32_e64 v9, 0, 1, vcc
	v_lshl_add_u32 v7, v9, 2, v7
	ds_read_b32 v10, v7
	v_addc_co_u32_e32 v4, vcc, v4, v5, vcc
	v_sub_u32_e32 v5, v63, v4
	s_waitcnt lgkmcnt(0)
	v_add_f32_e32 v10, v10, v3
	v_ashrrev_i32_e32 v11, 31, v10
	v_bitop3_b32 v10, v11, v10, s87 bitop3:0x36
	v_and_or_b32 v5, v10, s97, v5
	s_nop 1
	v_max_u32_dpp v10, v5, v5 quad_perm:[1,0,3,2] row_mask:0xf bank_mask:0xf bound_ctrl:1
	s_nop 1
	v_max_u32_dpp v10, v10, v10 quad_perm:[2,3,0,1] row_mask:0xf bank_mask:0xf bound_ctrl:1
	s_nop 1
	v_max_u32_dpp v10, v10, v10 row_half_mirror row_mask:0xf bank_mask:0xf bound_ctrl:1
	s_nop 1
	v_max_u32_dpp v10, v10, v10 row_mirror row_mask:0xf bank_mask:0xf bound_ctrl:1
	v_cmp_eq_u32_e32 vcc, v5, v10
	v_cndmask_b32_e64 v6, v6, v10, s[30:31]
	s_nop 0
	v_cndmask_b32_e64 v5, 0, 1, vcc
	v_lshl_add_u32 v7, v5, 2, v7
	ds_read_b32 v10, v7
	v_addc_co_u32_e32 v8, vcc, v8, v9, vcc
	v_sub_u32_e32 v9, v63, v8
	s_waitcnt lgkmcnt(0)
	v_add_f32_e32 v10, v10, v3
	v_ashrrev_i32_e32 v11, 31, v10
	v_bitop3_b32 v10, v11, v10, s87 bitop3:0x36
	v_and_or_b32 v9, v10, s97, v9
	s_nop 1
	v_max_u32_dpp v10, v9, v9 quad_perm:[1,0,3,2] row_mask:0xf bank_mask:0xf bound_ctrl:1
	s_nop 1
	v_max_u32_dpp v10, v10, v10 quad_perm:[2,3,0,1] row_mask:0xf bank_mask:0xf bound_ctrl:1
	s_nop 1
	v_max_u32_dpp v10, v10, v10 row_half_mirror row_mask:0xf bank_mask:0xf bound_ctrl:1
	s_nop 1
	v_max_u32_dpp v10, v10, v10 row_mirror row_mask:0xf bank_mask:0xf bound_ctrl:1
	v_cmp_eq_u32_e32 vcc, v9, v10
	v_cndmask_b32_e64 v6, v6, v10, s[34:35]
	s_nop 0
	v_cndmask_b32_e64 v9, 0, 1, vcc
	v_lshl_add_u32 v7, v9, 2, v7
	ds_read_b32 v10, v7
	v_addc_co_u32_e32 v4, vcc, v4, v5, vcc
	v_sub_u32_e32 v5, v63, v4
	s_waitcnt lgkmcnt(0)
	v_add_f32_e32 v10, v10, v3
	v_ashrrev_i32_e32 v11, 31, v10
	v_bitop3_b32 v10, v11, v10, s87 bitop3:0x36
	v_and_or_b32 v5, v10, s97, v5
	s_nop 1
	v_max_u32_dpp v10, v5, v5 quad_perm:[1,0,3,2] row_mask:0xf bank_mask:0xf bound_ctrl:1
	s_nop 1
	v_max_u32_dpp v10, v10, v10 quad_perm:[2,3,0,1] row_mask:0xf bank_mask:0xf bound_ctrl:1
	s_nop 1
	v_max_u32_dpp v10, v10, v10 row_half_mirror row_mask:0xf bank_mask:0xf bound_ctrl:1
	s_nop 1
	v_max_u32_dpp v10, v10, v10 row_mirror row_mask:0xf bank_mask:0xf bound_ctrl:1
	v_cmp_eq_u32_e32 vcc, v5, v10
	v_cndmask_b32_e64 v6, v6, v10, s[36:37]
	s_nop 0
	v_cndmask_b32_e64 v5, 0, 1, vcc
	v_lshl_add_u32 v7, v5, 2, v7
	v_addc_co_u32_e32 v8, vcc, v8, v9, vcc
	ds_read_b32 v9, v7
	v_sub_u32_e32 v8, v63, v8
	s_waitcnt lgkmcnt(0)
	v_add_f32_e32 v9, v9, v3
	v_ashrrev_i32_e32 v10, 31, v9
	v_bitop3_b32 v9, v10, v9, s87 bitop3:0x36
	v_and_or_b32 v8, v9, s97, v8
	s_nop 1
	v_max_u32_dpp v9, v8, v8 quad_perm:[1,0,3,2] row_mask:0xf bank_mask:0xf bound_ctrl:1
	s_nop 1
	v_max_u32_dpp v9, v9, v9 quad_perm:[2,3,0,1] row_mask:0xf bank_mask:0xf bound_ctrl:1
	s_nop 1
	v_max_u32_dpp v9, v9, v9 row_half_mirror row_mask:0xf bank_mask:0xf bound_ctrl:1
	s_nop 1
	v_max_u32_dpp v9, v9, v9 row_mirror row_mask:0xf bank_mask:0xf bound_ctrl:1
	v_cmp_eq_u32_e32 vcc, v8, v9
	v_cndmask_b32_e64 v6, v6, v9, s[38:39]
	s_nop 0
	v_cndmask_b32_e64 v8, 0, 1, vcc
	v_addc_co_u32_e32 v4, vcc, v4, v5, vcc
	v_lshl_add_u32 v5, v8, 2, v7
	ds_read_b32 v5, v5
	v_sub_u32_e32 v4, v63, v4
	s_waitcnt lgkmcnt(0)
	v_add_f32_e32 v3, v5, v3
	v_ashrrev_i32_e32 v5, 31, v3
	v_bitop3_b32 v3, v5, v3, s87 bitop3:0x36
	v_and_or_b32 v3, v3, s97, v4
	s_nop 1
	v_max_u32_dpp v3, v3, v3 quad_perm:[1,0,3,2] row_mask:0xf bank_mask:0xf bound_ctrl:1
	s_nop 1
	v_max_u32_dpp v3, v3, v3 quad_perm:[2,3,0,1] row_mask:0xf bank_mask:0xf bound_ctrl:1
	s_nop 1
	v_max_u32_dpp v3, v3, v3 row_half_mirror row_mask:0xf bank_mask:0xf bound_ctrl:1
	s_nop 1
	v_max_u32_dpp v3, v3, v3 row_mirror row_mask:0xf bank_mask:0xf bound_ctrl:1
	v_cndmask_b32_e64 v3, v6, v3, s[40:41]
	v_cmp_lt_i32_e32 vcc, -1, v3
	v_not_b32_e32 v4, v3
	v_bitop3_b32 v6, v3, 15, v3 bitop3:0xc
	v_cndmask_b32_e64 v5, v78, -1, vcc
	v_bitop3_b32 v5, v5, v3, s97 bitop3:0x78
	v_max_u32_dpp v3, v3, v3 quad_perm:[1,0,3,2] row_mask:0xf bank_mask:0xf bound_ctrl:1
	v_lshrrev_b32_e32 v4, 2, v4
	v_and_b32_e32 v4, 60, v4
	v_max_u32_dpp v3, v3, v3 quad_perm:[2,3,0,1] row_mask:0xf bank_mask:0xf bound_ctrl:1
	v_add_u32_e32 v4, v60, v4
	v_lshl_add_u32 v6, v6, 2, v60
	v_max_u32_dpp v3, v3, v3 row_half_mirror row_mask:0xf bank_mask:0xf bound_ctrl:1
	ds_read_b32 v4, v4 offset:64
	ds_read_b32 v6, v6 offset:128
	v_max_u32_dpp v3, v3, v3 row_mirror row_mask:0xf bank_mask:0xf bound_ctrl:1
	v_cmp_lt_i32_e32 vcc, -1, v3
	s_waitcnt lgkmcnt(0)
	v_lshl_add_u32 v6, v4, 7, v6
	v_cndmask_b32_e64 v7, v78, -1, vcc
	v_bitop3_b32 v3, v7, v3, s97 bitop3:0x78
	v_sub_f32_e32 v3, v5, v3
	v_mul_f32_e32 v3, 0x3fb8aa3b, v3
	v_exp_f32_e32 v7, v3
	s_nop 1
	v_add_f32_dpp v3, v7, v7 quad_perm:[1,0,3,2] row_mask:0xf bank_mask:0xf bound_ctrl:1
	s_nop 1
	v_add_f32_dpp v3, v3, v3 quad_perm:[2,3,0,1] row_mask:0xf bank_mask:0xf bound_ctrl:1
	s_nop 1
	v_add_f32_dpp v3, v3, v3 row_half_mirror row_mask:0xf bank_mask:0xf bound_ctrl:1
	s_nop 1
	v_add_f32_dpp v8, v3, v3 row_mirror row_mask:0xf bank_mask:0xf bound_ctrl:1
	v_ashrrev_i32_e32 v3, 31, v2
	v_lshlrev_b64 v[2:3], 9, v[2:3]
	v_or_b32_e32 v2, v2, v79
	v_lshl_add_u64 v[4:5], s[50:51], 0, v[2:3]
	global_store_dword v[4:5], v6, off
	v_div_scale_f32 v4, s[46:47], v8, v8, v7
	v_rcp_f32_e32 v5, v4
	v_lshl_add_u64 v[2:3], s[58:59], 0, v[2:3]
	v_fma_f32 v6, -v4, v5, 1.0
	v_fmac_f32_e32 v5, v6, v5
	v_div_scale_f32 v6, vcc, v7, v8, v7
	v_mul_f32_e32 v9, v6, v5
	v_fma_f32 v10, -v4, v9, v6
	v_fmac_f32_e32 v9, v10, v5
	v_fma_f32 v4, -v4, v9, v6
	v_div_fmas_f32 v4, v4, v5, v9
	v_cmp_le_i32_e32 vcc, s44, v46
	v_div_fixup_f32 v4, v4, v8, v7
	s_or_b64 s[70:71], vcc, s[70:71]
	global_store_dword v[2:3], v4, off
	s_andn2_b64 exec, exec, s[70:71]
	s_cbranch_execnz .LBB0_2020
	s_branch .LBB0_2014

.LBB0_2886:
	v_add_u32_e32 v2, v59, v53
	v_ashrrev_i32_e32 v3, 31, v2
	v_lshlrev_b64 v[2:3], 12, v[2:3]
	v_lshl_add_u64 v[56:57], v[54:55], 0, v[2:3]
	global_load_dwordx4 v[42:45], v[56:57], off
	global_load_dwordx4 v[38:41], v[56:57], off offset:64
	global_load_dwordx4 v[34:37], v[56:57], off offset:128
	global_load_dwordx4 v[30:33], v[56:57], off offset:192
	global_load_dwordx4 v[216:219], v[56:57], off offset:256
	global_load_dwordx4 v[220:223], v[56:57], off offset:320
	global_load_dwordx4 v[224:227], v[56:57], off offset:384
	global_load_dwordx4 v[228:231], v[56:57], off offset:448
	ds_read_b128 v[2:5], v65
	ds_read_b128 v[6:9], v65 offset:64
	v_add_u32_e32 v46, 8, v46
	s_waitcnt vmcnt(7) lgkmcnt(1)
	v_mfma_f32_16x16x32_bf16 v[2:5], v[42:45], v[2:5], 0
	ds_read_b128 v[10:13], v65 offset:4672
	ds_read_b128 v[14:17], v65 offset:9280
	ds_read_b128 v[18:21], v65 offset:13888
	s_waitcnt vmcnt(6) lgkmcnt(3)
	v_mfma_f32_16x16x32_bf16 v[2:5], v[38:41], v[6:9], v[2:5]
	ds_read_b128 v[6:9], v65 offset:128
	ds_read_b128 v[22:25], v65 offset:18496
	ds_read_b128 v[26:29], v65 offset:23104
	s_waitcnt vmcnt(5) lgkmcnt(2)
	v_mfma_f32_16x16x32_bf16 v[2:5], v[34:37], v[6:9], v[2:5]
	ds_read_b128 v[6:9], v65 offset:192
	ds_read_b128 v[80:83], v65 offset:27712
	s_waitcnt vmcnt(4) lgkmcnt(1)
	v_mfma_f32_16x16x32_bf16 v[2:5], v[30:33], v[6:9], v[2:5]
	ds_read_b128 v[6:9], v65 offset:4608
	s_waitcnt lgkmcnt(0)
	v_mfma_f32_16x16x32_bf16 v[6:9], v[42:45], v[6:9], 0
	v_mfma_f32_16x16x32_bf16 v[6:9], v[38:41], v[10:13], v[6:9]
	ds_read_b128 v[10:13], v65 offset:4736
	s_waitcnt lgkmcnt(0)
	v_mfma_f32_16x16x32_bf16 v[6:9], v[34:37], v[10:13], v[6:9]
	ds_read_b128 v[10:13], v65 offset:4800
	s_waitcnt lgkmcnt(0)
	v_mfma_f32_16x16x32_bf16 v[6:9], v[30:33], v[10:13], v[6:9]
	ds_read_b128 v[10:13], v65 offset:9216
	s_waitcnt lgkmcnt(0)
	v_mfma_f32_16x16x32_bf16 v[10:13], v[42:45], v[10:13], 0
	v_mfma_f32_16x16x32_bf16 v[10:13], v[38:41], v[14:17], v[10:13]
	ds_read_b128 v[14:17], v65 offset:9344
	s_waitcnt lgkmcnt(0)
	v_mfma_f32_16x16x32_bf16 v[10:13], v[34:37], v[14:17], v[10:13]
	ds_read_b128 v[14:17], v65 offset:9408
	s_waitcnt lgkmcnt(0)
	v_mfma_f32_16x16x32_bf16 v[10:13], v[30:33], v[14:17], v[10:13]
	ds_read_b128 v[14:17], v65 offset:13824
	s_waitcnt lgkmcnt(0)
	v_mfma_f32_16x16x32_bf16 v[14:17], v[42:45], v[14:17], 0
	v_mfma_f32_16x16x32_bf16 v[14:17], v[38:41], v[18:21], v[14:17]
	ds_read_b128 v[18:21], v65 offset:13952
	s_waitcnt lgkmcnt(0)
	v_mfma_f32_16x16x32_bf16 v[14:17], v[34:37], v[18:21], v[14:17]
	ds_read_b128 v[18:21], v65 offset:14016
	s_waitcnt lgkmcnt(0)
	v_mfma_f32_16x16x32_bf16 v[14:17], v[30:33], v[18:21], v[14:17]
	ds_read_b128 v[18:21], v65 offset:18432
	s_waitcnt lgkmcnt(0)
	v_mfma_f32_16x16x32_bf16 v[18:21], v[42:45], v[18:21], 0
	v_mfma_f32_16x16x32_bf16 v[18:21], v[38:41], v[22:25], v[18:21]
	ds_read_b128 v[22:25], v65 offset:18560
	s_waitcnt lgkmcnt(0)
	v_mfma_f32_16x16x32_bf16 v[18:21], v[34:37], v[22:25], v[18:21]
	ds_read_b128 v[22:25], v65 offset:18624
	s_waitcnt lgkmcnt(0)
	v_mfma_f32_16x16x32_bf16 v[18:21], v[30:33], v[22:25], v[18:21]
	ds_read_b128 v[22:25], v65 offset:23040
	s_waitcnt lgkmcnt(0)
	v_mfma_f32_16x16x32_bf16 v[22:25], v[42:45], v[22:25], 0
	v_mfma_f32_16x16x32_bf16 v[22:25], v[38:41], v[26:29], v[22:25]
	ds_read_b128 v[26:29], v65 offset:23168
	s_waitcnt lgkmcnt(0)
	v_mfma_f32_16x16x32_bf16 v[22:25], v[34:37], v[26:29], v[22:25]
	ds_read_b128 v[26:29], v65 offset:23232
	s_waitcnt lgkmcnt(0)
	v_mfma_f32_16x16x32_bf16 v[22:25], v[30:33], v[26:29], v[22:25]
	ds_read_b128 v[26:29], v65 offset:27648
	s_waitcnt lgkmcnt(0)
	v_mfma_f32_16x16x32_bf16 v[26:29], v[42:45], v[26:29], 0
	v_mfma_f32_16x16x32_bf16 v[26:29], v[38:41], v[80:83], v[26:29]
	ds_read_b128 v[80:83], v65 offset:27776
	s_waitcnt lgkmcnt(0)
	v_mfma_f32_16x16x32_bf16 v[26:29], v[34:37], v[80:83], v[26:29]
	ds_read_b128 v[80:83], v65 offset:27840
	s_waitcnt lgkmcnt(0)
	v_mfma_f32_16x16x32_bf16 v[26:29], v[30:33], v[80:83], v[26:29]
	ds_read_b128 v[80:83], v65 offset:32256
	s_waitcnt lgkmcnt(0)
	v_mfma_f32_16x16x32_bf16 v[42:45], v[42:45], v[80:83], 0
	ds_read_b128 v[80:83], v65 offset:32320
	s_waitcnt lgkmcnt(0)
	v_mfma_f32_16x16x32_bf16 v[38:41], v[38:41], v[80:83], v[42:45]
	s_nop 4
	ds_read_b128 v[42:45], v65 offset:32384
	s_waitcnt lgkmcnt(0)
	v_mfma_f32_16x16x32_bf16 v[34:37], v[34:37], v[42:45], v[38:41]
	s_nop 2
	ds_read_b128 v[38:41], v65 offset:32448
	s_waitcnt lgkmcnt(0)
	v_mfma_f32_16x16x32_bf16 v[30:33], v[30:33], v[38:41], v[34:37]
	s_nop 2
	v_ashrrev_i32_e32 v34, 31, v2
	v_bitop3_b32 v2, v34, v2, s70 bitop3:0x36
	v_ashrrev_i32_e32 v34, 31, v6
	v_bitop3_b32 v6, v34, v6, s70 bitop3:0x36
	v_ashrrev_i32_e32 v34, 31, v10
	v_bitop3_b32 v10, v34, v10, s70 bitop3:0x36
	v_ashrrev_i32_e32 v34, 31, v14
	v_bitop3_b32 v14, v34, v14, s70 bitop3:0x36
	v_ashrrev_i32_e32 v34, 31, v18
	v_bitop3_b32 v18, v34, v18, s70 bitop3:0x36
	v_ashrrev_i32_e32 v34, 31, v22
	v_bitop3_b32 v22, v34, v22, s70 bitop3:0x36
	v_ashrrev_i32_e32 v34, 31, v26
	v_bitop3_b32 v26, v34, v26, s70 bitop3:0x36
	v_ashrrev_i32_e32 v34, 31, v30
	v_bitop3_b32 v30, v34, v30, s70 bitop3:0x36
	v_and_or_b32 v2, v2, s71, v61
	v_and_or_b32 v6, v6, s71, v66
	v_and_or_b32 v10, v10, s71, v67
	v_and_or_b32 v14, v14, s71, v68
	v_and_or_b32 v18, v18, s71, v69
	v_and_or_b32 v22, v22, s71, v70
	v_and_or_b32 v26, v26, s71, v71
	v_and_or_b32 v30, v30, s71, v72
	v_max_u32_e32 v34, v2, v6
	v_min_u32_e32 v2, v2, v6
	v_max_u32_e32 v6, v10, v14
	v_min_u32_e32 v10, v10, v14
	v_max_u32_e32 v14, v18, v22
	v_min_u32_e32 v18, v18, v22
	v_max_u32_e32 v22, v26, v30
	v_min_u32_e32 v26, v26, v30
	v_max_u32_e32 v30, v34, v6
	v_min_u32_e32 v6, v34, v6
	v_max_u32_e32 v34, v2, v10
	v_min_u32_e32 v2, v2, v10
	v_max_u32_e32 v10, v14, v22
	v_min_u32_e32 v14, v14, v22
	v_max_u32_e32 v22, v18, v26
	v_min_u32_e32 v18, v18, v26
	v_max_u32_e32 v26, v34, v6
	v_min_u32_e32 v6, v34, v6
	v_max_u32_e32 v34, v22, v14
	v_min_u32_e32 v14, v22, v14
	v_max_u32_e32 v22, v30, v10
	v_min_u32_e32 v10, v30, v10
	v_max_u32_e32 v30, v26, v34
	v_min_u32_e32 v26, v26, v34
	v_max_u32_e32 v34, v6, v14
	v_min_u32_e32 v6, v6, v14
	v_max_u32_e32 v14, v2, v18
	v_min_u32_e32 v2, v2, v18
	v_max_u32_e32 v18, v34, v10
	v_min_u32_e32 v10, v34, v10
	v_max_u32_e32 v34, v14, v26
	v_min_u32_e32 v14, v14, v26
	v_max_u32_e32 v26, v30, v18
	v_min_u32_e32 v18, v30, v18
	v_max_u32_e32 v30, v34, v10
	v_min_u32_e32 v10, v34, v10
	v_max_u32_e32 v34, v14, v6
	v_min_u32_e32 v6, v14, v6
	v_max_u32_dpp v14, v22, v22 quad_perm:[1,0,3,2] row_mask:0xf bank_mask:0xf bound_ctrl:1
	s_nop 1
	v_max_u32_dpp v14, v14, v14 quad_perm:[2,3,0,1] row_mask:0xf bank_mask:0xf bound_ctrl:1
	s_nop 1
	v_max_u32_dpp v14, v14, v14 row_half_mirror row_mask:0xf bank_mask:0xf bound_ctrl:1
	s_nop 1
	v_max_u32_dpp v14, v14, v14 row_mirror row_mask:0xf bank_mask:0xf bound_ctrl:1
	v_cmp_eq_u32_e32 vcc, v22, v14
	v_cndmask_b32_e64 v35, 0, v14, s[10:11]
	s_nop 0
	v_cndmask_b32_e32 v14, v22, v26, vcc
	v_cndmask_b32_e32 v22, v26, v18, vcc
	v_cndmask_b32_e32 v18, v18, v30, vcc
	v_cndmask_b32_e32 v26, v30, v10, vcc
	v_cndmask_b32_e32 v10, v10, v34, vcc
	v_cndmask_b32_e32 v30, v34, v6, vcc
	v_max_u32_dpp v34, v14, v14 quad_perm:[1,0,3,2] row_mask:0xf bank_mask:0xf bound_ctrl:1
	v_cndmask_b32_e32 v6, v6, v2, vcc
	v_cndmask_b32_e64 v2, v2, 0, vcc
	v_max_u32_dpp v34, v34, v34 quad_perm:[2,3,0,1] row_mask:0xf bank_mask:0xf bound_ctrl:1
	s_nop 1
	v_max_u32_dpp v34, v34, v34 row_half_mirror row_mask:0xf bank_mask:0xf bound_ctrl:1
	s_nop 1
	v_max_u32_dpp v34, v34, v34 row_mirror row_mask:0xf bank_mask:0xf bound_ctrl:1
	v_cmp_eq_u32_e32 vcc, v14, v34
	v_cndmask_b32_e64 v35, v35, v34, s[12:13]
	s_nop 0
	v_cndmask_b32_e32 v14, v14, v22, vcc
	v_cndmask_b32_e32 v22, v22, v18, vcc
	v_cndmask_b32_e32 v18, v18, v26, vcc
	v_max_u32_dpp v34, v14, v14 quad_perm:[1,0,3,2] row_mask:0xf bank_mask:0xf bound_ctrl:1
	v_cndmask_b32_e32 v26, v26, v10, vcc
	v_cndmask_b32_e32 v10, v10, v30, vcc
	v_max_u32_dpp v34, v34, v34 quad_perm:[2,3,0,1] row_mask:0xf bank_mask:0xf bound_ctrl:1
	v_cndmask_b32_e32 v30, v30, v6, vcc
	v_cndmask_b32_e32 v6, v6, v2, vcc
	v_max_u32_dpp v34, v34, v34 row_half_mirror row_mask:0xf bank_mask:0xf bound_ctrl:1
	v_cndmask_b32_e64 v2, v2, 0, vcc
	s_nop 0
	v_max_u32_dpp v34, v34, v34 row_mirror row_mask:0xf bank_mask:0xf bound_ctrl:1
	v_cmp_eq_u32_e32 vcc, v14, v34
	v_cndmask_b32_e64 v35, v35, v34, s[14:15]
	s_nop 0
	v_cndmask_b32_e32 v14, v14, v22, vcc
	v_cndmask_b32_e32 v22, v22, v18, vcc
	v_cndmask_b32_e32 v18, v18, v26, vcc
	v_max_u32_dpp v34, v14, v14 quad_perm:[1,0,3,2] row_mask:0xf bank_mask:0xf bound_ctrl:1
	v_cndmask_b32_e32 v26, v26, v10, vcc
	v_cndmask_b32_e32 v10, v10, v30, vcc
	v_max_u32_dpp v34, v34, v34 quad_perm:[2,3,0,1] row_mask:0xf bank_mask:0xf bound_ctrl:1
	v_cndmask_b32_e32 v30, v30, v6, vcc
	v_cndmask_b32_e32 v6, v6, v2, vcc
	v_max_u32_dpp v34, v34, v34 row_half_mirror row_mask:0xf bank_mask:0xf bound_ctrl:1
	v_cndmask_b32_e64 v2, v2, 0, vcc
	s_nop 0
	v_max_u32_dpp v34, v34, v34 row_mirror row_mask:0xf bank_mask:0xf bound_ctrl:1
	v_cmp_eq_u32_e32 vcc, v14, v34
	v_cndmask_b32_e64 v35, v35, v34, s[16:17]
	s_nop 0
	v_cndmask_b32_e32 v14, v14, v22, vcc
	v_cndmask_b32_e32 v22, v22, v18, vcc
	v_cndmask_b32_e32 v18, v18, v26, vcc
	v_max_u32_dpp v34, v14, v14 quad_perm:[1,0,3,2] row_mask:0xf bank_mask:0xf bound_ctrl:1
	v_cndmask_b32_e32 v26, v26, v10, vcc
	v_cndmask_b32_e32 v10, v10, v30, vcc
	v_max_u32_dpp v34, v34, v34 quad_perm:[2,3,0,1] row_mask:0xf bank_mask:0xf bound_ctrl:1
	v_cndmask_b32_e32 v30, v30, v6, vcc
	v_cndmask_b32_e32 v6, v6, v2, vcc
	v_max_u32_dpp v34, v34, v34 row_half_mirror row_mask:0xf bank_mask:0xf bound_ctrl:1
	v_cndmask_b32_e64 v2, v2, 0, vcc
	s_nop 0
	v_max_u32_dpp v34, v34, v34 row_mirror row_mask:0xf bank_mask:0xf bound_ctrl:1
	v_cmp_eq_u32_e32 vcc, v14, v34
	v_cndmask_b32_e64 v35, v35, v34, s[18:19]
	s_nop 0
	v_cndmask_b32_e32 v14, v14, v22, vcc
	v_cndmask_b32_e32 v22, v22, v18, vcc
	v_cndmask_b32_e32 v18, v18, v26, vcc
	v_max_u32_dpp v34, v14, v14 quad_perm:[1,0,3,2] row_mask:0xf bank_mask:0xf bound_ctrl:1
	v_cndmask_b32_e32 v26, v26, v10, vcc
	v_cndmask_b32_e32 v10, v10, v30, vcc
	v_max_u32_dpp v34, v34, v34 quad_perm:[2,3,0,1] row_mask:0xf bank_mask:0xf bound_ctrl:1
	v_cndmask_b32_e32 v30, v30, v6, vcc
	v_cndmask_b32_e32 v6, v6, v2, vcc
	v_max_u32_dpp v34, v34, v34 row_half_mirror row_mask:0xf bank_mask:0xf bound_ctrl:1
	v_cndmask_b32_e64 v2, v2, 0, vcc
	s_nop 0
	v_max_u32_dpp v34, v34, v34 row_mirror row_mask:0xf bank_mask:0xf bound_ctrl:1
	v_cmp_eq_u32_e32 vcc, v14, v34
	v_cndmask_b32_e64 v35, v35, v34, s[20:21]
	s_nop 0
	v_cndmask_b32_e32 v14, v14, v22, vcc
	v_cndmask_b32_e32 v22, v22, v18, vcc
	v_cndmask_b32_e32 v18, v18, v26, vcc
	v_max_u32_dpp v34, v14, v14 quad_perm:[1,0,3,2] row_mask:0xf bank_mask:0xf bound_ctrl:1
	v_cndmask_b32_e32 v26, v26, v10, vcc
	v_cndmask_b32_e32 v10, v10, v30, vcc
	v_max_u32_dpp v34, v34, v34 quad_perm:[2,3,0,1] row_mask:0xf bank_mask:0xf bound_ctrl:1
	v_cndmask_b32_e32 v30, v30, v6, vcc
	v_cndmask_b32_e32 v6, v6, v2, vcc
	v_max_u32_dpp v34, v34, v34 row_half_mirror row_mask:0xf bank_mask:0xf bound_ctrl:1
	v_cndmask_b32_e64 v2, v2, 0, vcc
	s_nop 0
	v_max_u32_dpp v34, v34, v34 row_mirror row_mask:0xf bank_mask:0xf bound_ctrl:1
	v_cmp_eq_u32_e32 vcc, v14, v34
	v_cndmask_b32_e64 v35, v35, v34, s[22:23]
	s_nop 0
	v_cndmask_b32_e32 v14, v14, v22, vcc
	v_cndmask_b32_e32 v22, v22, v18, vcc
	v_cndmask_b32_e32 v18, v18, v26, vcc
	v_max_u32_dpp v34, v14, v14 quad_perm:[1,0,3,2] row_mask:0xf bank_mask:0xf bound_ctrl:1
	v_cndmask_b32_e32 v26, v26, v10, vcc
	v_cndmask_b32_e32 v10, v10, v30, vcc
	v_max_u32_dpp v34, v34, v34 quad_perm:[2,3,0,1] row_mask:0xf bank_mask:0xf bound_ctrl:1
	v_cndmask_b32_e32 v30, v30, v6, vcc
	v_cndmask_b32_e32 v6, v6, v2, vcc
	v_max_u32_dpp v34, v34, v34 row_half_mirror row_mask:0xf bank_mask:0xf bound_ctrl:1
	v_cndmask_b32_e64 v2, v2, 0, vcc
	s_nop 0
	v_max_u32_dpp v34, v34, v34 row_mirror row_mask:0xf bank_mask:0xf bound_ctrl:1
	v_cmp_eq_u32_e32 vcc, v14, v34
	v_cndmask_b32_e64 v35, v35, v34, s[24:25]
	s_nop 0
	v_cndmask_b32_e32 v14, v14, v22, vcc
	v_cndmask_b32_e32 v22, v22, v18, vcc
	v_cndmask_b32_e32 v18, v18, v26, vcc
	v_max_u32_dpp v34, v14, v14 quad_perm:[1,0,3,2] row_mask:0xf bank_mask:0xf bound_ctrl:1
	v_cndmask_b32_e32 v26, v26, v10, vcc
	v_cndmask_b32_e32 v10, v10, v30, vcc
	v_max_u32_dpp v34, v34, v34 quad_perm:[2,3,0,1] row_mask:0xf bank_mask:0xf bound_ctrl:1
	v_cndmask_b32_e32 v30, v30, v6, vcc
	v_cndmask_b32_e32 v6, v6, v2, vcc
	v_max_u32_dpp v34, v34, v34 row_half_mirror row_mask:0xf bank_mask:0xf bound_ctrl:1
	v_cndmask_b32_e64 v2, v2, 0, vcc
	s_nop 0
	v_max_u32_dpp v34, v34, v34 row_mirror row_mask:0xf bank_mask:0xf bound_ctrl:1
	v_cmp_eq_u32_e32 vcc, v14, v34
	v_cndmask_b32_e64 v35, v35, v34, s[26:27]
	s_nop 0
	v_cndmask_b32_e32 v14, v14, v22, vcc
	v_cndmask_b32_e32 v22, v22, v18, vcc
	v_cndmask_b32_e32 v18, v18, v26, vcc
	v_cndmask_b32_e32 v26, v26, v10, vcc
	v_cndmask_b32_e32 v10, v10, v30, vcc
	v_cndmask_b32_e32 v30, v30, v6, vcc
	v_cndmask_b32_e32 v2, v6, v2, vcc
	v_max_u32_dpp v6, v14, v14 quad_perm:[1,0,3,2] row_mask:0xf bank_mask:0xf bound_ctrl:1
	s_nop 1
	v_max_u32_dpp v6, v6, v6 quad_perm:[2,3,0,1] row_mask:0xf bank_mask:0xf bound_ctrl:1
	s_nop 1
	v_max_u32_dpp v6, v6, v6 row_half_mirror row_mask:0xf bank_mask:0xf bound_ctrl:1
	s_nop 1
	v_max_u32_dpp v6, v6, v6 row_mirror row_mask:0xf bank_mask:0xf bound_ctrl:1
	v_cmp_eq_u32_e32 vcc, v14, v6
	v_cndmask_b32_e64 v34, v35, v6, s[28:29]
	s_nop 0
	v_cndmask_b32_e32 v6, v14, v22, vcc
	v_cndmask_b32_e32 v14, v22, v18, vcc
	v_cndmask_b32_e32 v18, v18, v26, vcc
	v_cndmask_b32_e32 v22, v26, v10, vcc
	v_max_u32_dpp v26, v6, v6 quad_perm:[1,0,3,2] row_mask:0xf bank_mask:0xf bound_ctrl:1
	v_cndmask_b32_e32 v10, v10, v30, vcc
	v_cndmask_b32_e32 v2, v30, v2, vcc
	v_max_u32_dpp v26, v26, v26 quad_perm:[2,3,0,1] row_mask:0xf bank_mask:0xf bound_ctrl:1
	s_nop 1
	v_max_u32_dpp v26, v26, v26 row_half_mirror row_mask:0xf bank_mask:0xf bound_ctrl:1
	s_nop 1
	v_max_u32_dpp v26, v26, v26 row_mirror row_mask:0xf bank_mask:0xf bound_ctrl:1
	v_cmp_eq_u32_e32 vcc, v6, v26
	v_cndmask_b32_e64 v30, v34, v26, s[30:31]
	s_nop 0
	v_cndmask_b32_e32 v6, v6, v14, vcc
	v_cndmask_b32_e32 v14, v14, v18, vcc
	v_cndmask_b32_e32 v18, v18, v22, vcc
	v_cndmask_b32_e32 v22, v22, v10, vcc
	v_cndmask_b32_e32 v2, v10, v2, vcc
	v_max_u32_dpp v10, v6, v6 quad_perm:[1,0,3,2] row_mask:0xf bank_mask:0xf bound_ctrl:1
	s_nop 1
	v_max_u32_dpp v10, v10, v10 quad_perm:[2,3,0,1] row_mask:0xf bank_mask:0xf bound_ctrl:1
	s_nop 1
	v_max_u32_dpp v10, v10, v10 row_half_mirror row_mask:0xf bank_mask:0xf bound_ctrl:1
	s_nop 1
	v_max_u32_dpp v10, v10, v10 row_mirror row_mask:0xf bank_mask:0xf bound_ctrl:1
	v_cmp_eq_u32_e32 vcc, v6, v10
	v_cndmask_b32_e64 v26, v30, v10, s[34:35]
	s_nop 0
	v_cndmask_b32_e32 v6, v6, v14, vcc
	v_cndmask_b32_e32 v10, v14, v18, vcc
	v_cndmask_b32_e32 v14, v18, v22, vcc
	v_max_u32_dpp v18, v6, v6 quad_perm:[1,0,3,2] row_mask:0xf bank_mask:0xf bound_ctrl:1
	v_cndmask_b32_e32 v2, v22, v2, vcc
	s_nop 0
	v_max_u32_dpp v18, v18, v18 quad_perm:[2,3,0,1] row_mask:0xf bank_mask:0xf bound_ctrl:1
	s_nop 1
	v_max_u32_dpp v18, v18, v18 row_half_mirror row_mask:0xf bank_mask:0xf bound_ctrl:1
	s_nop 1
	v_max_u32_dpp v18, v18, v18 row_mirror row_mask:0xf bank_mask:0xf bound_ctrl:1
	v_cmp_eq_u32_e32 vcc, v6, v18
	v_cndmask_b32_e64 v22, v26, v18, s[36:37]
	s_nop 0
	v_cndmask_b32_e32 v6, v6, v10, vcc
	v_cndmask_b32_e32 v10, v10, v14, vcc
	v_cndmask_b32_e32 v2, v14, v2, vcc
	v_max_u32_dpp v14, v6, v6 quad_perm:[1,0,3,2] row_mask:0xf bank_mask:0xf bound_ctrl:1
	s_nop 1
	v_max_u32_dpp v14, v14, v14 quad_perm:[2,3,0,1] row_mask:0xf bank_mask:0xf bound_ctrl:1
	s_nop 1
	v_max_u32_dpp v14, v14, v14 row_half_mirror row_mask:0xf bank_mask:0xf bound_ctrl:1
	s_nop 1
	v_max_u32_dpp v14, v14, v14 row_mirror row_mask:0xf bank_mask:0xf bound_ctrl:1
	v_cmp_eq_u32_e32 vcc, v6, v14
	v_cndmask_b32_e64 v18, v22, v14, s[38:39]
	s_nop 0
	v_cndmask_b32_e32 v6, v6, v10, vcc
	v_cndmask_b32_e32 v2, v10, v2, vcc
	s_nop 0
	v_max_u32_dpp v10, v6, v6 quad_perm:[1,0,3,2] row_mask:0xf bank_mask:0xf bound_ctrl:1
	s_nop 1
	v_max_u32_dpp v10, v10, v10 quad_perm:[2,3,0,1] row_mask:0xf bank_mask:0xf bound_ctrl:1
	s_nop 1
	v_max_u32_dpp v10, v10, v10 row_half_mirror row_mask:0xf bank_mask:0xf bound_ctrl:1
	s_nop 1
	v_max_u32_dpp v10, v10, v10 row_mirror row_mask:0xf bank_mask:0xf bound_ctrl:1
	v_cmp_eq_u32_e32 vcc, v6, v10
	v_cndmask_b32_e64 v14, v18, v10, s[40:41]
	v_ashrrev_i32_e32 v10, 31, v19
	v_cndmask_b32_e32 v2, v6, v2, vcc
	v_ashrrev_i32_e32 v6, 31, v11
	v_bitop3_b32 v6, v6, v11, s70 bitop3:0x36
	v_max_u32_dpp v2, v2, v2 quad_perm:[1,0,3,2] row_mask:0xf bank_mask:0xf bound_ctrl:1
	v_ashrrev_i32_e32 v11, 31, v23
	v_bitop3_b32 v10, v10, v19, s70 bitop3:0x36
	v_max_u32_dpp v2, v2, v2 quad_perm:[2,3,0,1] row_mask:0xf bank_mask:0xf bound_ctrl:1
	v_bitop3_b32 v11, v11, v23, s70 bitop3:0x36
	v_and_or_b32 v6, v6, s71, v67
	v_max_u32_dpp v2, v2, v2 row_half_mirror row_mask:0xf bank_mask:0xf bound_ctrl:1
	v_and_or_b32 v10, v10, s71, v69
	v_and_or_b32 v11, v11, s71, v70
	v_max_u32_dpp v2, v2, v2 row_mirror row_mask:0xf bank_mask:0xf bound_ctrl:1
	v_cndmask_b32_e64 v83, v14, v2, s[42:43]
	v_ashrrev_i32_e32 v2, 31, v3
	v_bitop3_b32 v2, v2, v3, s70 bitop3:0x36
	v_ashrrev_i32_e32 v3, 31, v7
	v_bitop3_b32 v3, v3, v7, s70 bitop3:0x36
	v_ashrrev_i32_e32 v7, 31, v15
	v_bitop3_b32 v7, v7, v15, s70 bitop3:0x36
	v_ashrrev_i32_e32 v14, 31, v27
	v_ashrrev_i32_e32 v15, 31, v31
	v_bitop3_b32 v14, v14, v27, s70 bitop3:0x36
	v_bitop3_b32 v15, v15, v31, s70 bitop3:0x36
	v_and_or_b32 v2, v2, s71, v61
	v_and_or_b32 v3, v3, s71, v66
	v_and_or_b32 v7, v7, s71, v68
	v_and_or_b32 v14, v14, s71, v71
	v_and_or_b32 v15, v15, s71, v72
	v_max_u32_e32 v18, v2, v3
	v_min_u32_e32 v2, v2, v3
	v_max_u32_e32 v3, v6, v7
	v_min_u32_e32 v6, v6, v7
	v_max_u32_e32 v7, v10, v11
	v_min_u32_e32 v10, v10, v11
	v_max_u32_e32 v11, v14, v15
	v_min_u32_e32 v14, v14, v15
	v_max_u32_e32 v15, v18, v3
	v_min_u32_e32 v3, v18, v3
	v_max_u32_e32 v18, v2, v6
	v_min_u32_e32 v2, v2, v6
	v_max_u32_e32 v6, v7, v11
	v_min_u32_e32 v7, v7, v11
	v_max_u32_e32 v11, v10, v14
	v_min_u32_e32 v10, v10, v14
	v_max_u32_e32 v14, v18, v3
	v_min_u32_e32 v3, v18, v3
	v_max_u32_e32 v18, v11, v7
	v_min_u32_e32 v7, v11, v7
	v_max_u32_e32 v11, v15, v6
	v_min_u32_e32 v6, v15, v6
	v_max_u32_e32 v15, v14, v18
	v_min_u32_e32 v14, v14, v18
	v_max_u32_e32 v18, v3, v7
	v_min_u32_e32 v3, v3, v7
	v_max_u32_e32 v7, v2, v10
	v_min_u32_e32 v2, v2, v10
	v_max_u32_e32 v10, v18, v6
	v_min_u32_e32 v6, v18, v6
	v_max_u32_e32 v18, v7, v14
	v_min_u32_e32 v7, v7, v14
	v_max_u32_e32 v14, v15, v10
	v_min_u32_e32 v10, v15, v10
	v_max_u32_e32 v15, v18, v6
	v_min_u32_e32 v6, v18, v6
	v_max_u32_e32 v18, v7, v3
	v_min_u32_e32 v3, v7, v3
	v_max_u32_dpp v7, v11, v11 quad_perm:[1,0,3,2] row_mask:0xf bank_mask:0xf bound_ctrl:1
	s_nop 1
	v_max_u32_dpp v7, v7, v7 quad_perm:[2,3,0,1] row_mask:0xf bank_mask:0xf bound_ctrl:1
	s_nop 1
	v_max_u32_dpp v7, v7, v7 row_half_mirror row_mask:0xf bank_mask:0xf bound_ctrl:1
	s_nop 1
	v_max_u32_dpp v7, v7, v7 row_mirror row_mask:0xf bank_mask:0xf bound_ctrl:1
	v_cmp_eq_u32_e32 vcc, v11, v7
	v_cndmask_b32_e64 v19, 0, v7, s[10:11]
	s_nop 0
	v_cndmask_b32_e32 v7, v11, v14, vcc
	v_cndmask_b32_e32 v11, v14, v10, vcc
	v_cndmask_b32_e32 v10, v10, v15, vcc
	v_cndmask_b32_e32 v14, v15, v6, vcc
	v_cndmask_b32_e32 v6, v6, v18, vcc
	v_cndmask_b32_e32 v15, v18, v3, vcc
	v_max_u32_dpp v18, v7, v7 quad_perm:[1,0,3,2] row_mask:0xf bank_mask:0xf bound_ctrl:1
	v_cndmask_b32_e32 v3, v3, v2, vcc
	v_cndmask_b32_e64 v2, v2, 0, vcc
	v_max_u32_dpp v18, v18, v18 quad_perm:[2,3,0,1] row_mask:0xf bank_mask:0xf bound_ctrl:1
	s_nop 1
	v_max_u32_dpp v18, v18, v18 row_half_mirror row_mask:0xf bank_mask:0xf bound_ctrl:1
	s_nop 1
	v_max_u32_dpp v18, v18, v18 row_mirror row_mask:0xf bank_mask:0xf bound_ctrl:1
	v_cmp_eq_u32_e32 vcc, v7, v18
	v_cndmask_b32_e64 v19, v19, v18, s[12:13]
	s_nop 0
	v_cndmask_b32_e32 v7, v7, v11, vcc
	v_cndmask_b32_e32 v11, v11, v10, vcc
	v_cndmask_b32_e32 v10, v10, v14, vcc
	v_max_u32_dpp v18, v7, v7 quad_perm:[1,0,3,2] row_mask:0xf bank_mask:0xf bound_ctrl:1
	v_cndmask_b32_e32 v14, v14, v6, vcc
	v_cndmask_b32_e32 v6, v6, v15, vcc
	v_max_u32_dpp v18, v18, v18 quad_perm:[2,3,0,1] row_mask:0xf bank_mask:0xf bound_ctrl:1
	v_cndmask_b32_e32 v15, v15, v3, vcc
	v_cndmask_b32_e32 v3, v3, v2, vcc
	v_max_u32_dpp v18, v18, v18 row_half_mirror row_mask:0xf bank_mask:0xf bound_ctrl:1
	v_cndmask_b32_e64 v2, v2, 0, vcc
	s_nop 0
	v_max_u32_dpp v18, v18, v18 row_mirror row_mask:0xf bank_mask:0xf bound_ctrl:1
	v_cmp_eq_u32_e32 vcc, v7, v18
	v_cndmask_b32_e64 v19, v19, v18, s[14:15]
	s_nop 0
	v_cndmask_b32_e32 v7, v7, v11, vcc
	v_cndmask_b32_e32 v11, v11, v10, vcc
	v_cndmask_b32_e32 v10, v10, v14, vcc
	v_max_u32_dpp v18, v7, v7 quad_perm:[1,0,3,2] row_mask:0xf bank_mask:0xf bound_ctrl:1
	v_cndmask_b32_e32 v14, v14, v6, vcc
	v_cndmask_b32_e32 v6, v6, v15, vcc
	v_max_u32_dpp v18, v18, v18 quad_perm:[2,3,0,1] row_mask:0xf bank_mask:0xf bound_ctrl:1
	v_cndmask_b32_e32 v15, v15, v3, vcc
	v_cndmask_b32_e32 v3, v3, v2, vcc
	v_max_u32_dpp v18, v18, v18 row_half_mirror row_mask:0xf bank_mask:0xf bound_ctrl:1
	v_cndmask_b32_e64 v2, v2, 0, vcc
	s_nop 0
	v_max_u32_dpp v18, v18, v18 row_mirror row_mask:0xf bank_mask:0xf bound_ctrl:1
	v_cmp_eq_u32_e32 vcc, v7, v18
	v_cndmask_b32_e64 v19, v19, v18, s[16:17]
	s_nop 0
	v_cndmask_b32_e32 v7, v7, v11, vcc
	v_cndmask_b32_e32 v11, v11, v10, vcc
	v_cndmask_b32_e32 v10, v10, v14, vcc
	v_max_u32_dpp v18, v7, v7 quad_perm:[1,0,3,2] row_mask:0xf bank_mask:0xf bound_ctrl:1
	v_cndmask_b32_e32 v14, v14, v6, vcc
	v_cndmask_b32_e32 v6, v6, v15, vcc
	v_max_u32_dpp v18, v18, v18 quad_perm:[2,3,0,1] row_mask:0xf bank_mask:0xf bound_ctrl:1
	v_cndmask_b32_e32 v15, v15, v3, vcc
	v_cndmask_b32_e32 v3, v3, v2, vcc
	v_max_u32_dpp v18, v18, v18 row_half_mirror row_mask:0xf bank_mask:0xf bound_ctrl:1
	v_cndmask_b32_e64 v2, v2, 0, vcc
	s_nop 0
	v_max_u32_dpp v18, v18, v18 row_mirror row_mask:0xf bank_mask:0xf bound_ctrl:1
	v_cmp_eq_u32_e32 vcc, v7, v18
	v_cndmask_b32_e64 v19, v19, v18, s[18:19]
	s_nop 0
	v_cndmask_b32_e32 v7, v7, v11, vcc
	v_cndmask_b32_e32 v11, v11, v10, vcc
	v_cndmask_b32_e32 v10, v10, v14, vcc
	v_max_u32_dpp v18, v7, v7 quad_perm:[1,0,3,2] row_mask:0xf bank_mask:0xf bound_ctrl:1
	v_cndmask_b32_e32 v14, v14, v6, vcc
	v_cndmask_b32_e32 v6, v6, v15, vcc
	v_max_u32_dpp v18, v18, v18 quad_perm:[2,3,0,1] row_mask:0xf bank_mask:0xf bound_ctrl:1
	v_cndmask_b32_e32 v15, v15, v3, vcc
	v_cndmask_b32_e32 v3, v3, v2, vcc
	v_max_u32_dpp v18, v18, v18 row_half_mirror row_mask:0xf bank_mask:0xf bound_ctrl:1
	v_cndmask_b32_e64 v2, v2, 0, vcc
	s_nop 0
	v_max_u32_dpp v18, v18, v18 row_mirror row_mask:0xf bank_mask:0xf bound_ctrl:1
	v_cmp_eq_u32_e32 vcc, v7, v18
	v_cndmask_b32_e64 v19, v19, v18, s[20:21]
	s_nop 0
	v_cndmask_b32_e32 v7, v7, v11, vcc
	v_cndmask_b32_e32 v11, v11, v10, vcc
	v_cndmask_b32_e32 v10, v10, v14, vcc
	v_max_u32_dpp v18, v7, v7 quad_perm:[1,0,3,2] row_mask:0xf bank_mask:0xf bound_ctrl:1
	v_cndmask_b32_e32 v14, v14, v6, vcc
	v_cndmask_b32_e32 v6, v6, v15, vcc
	v_max_u32_dpp v18, v18, v18 quad_perm:[2,3,0,1] row_mask:0xf bank_mask:0xf bound_ctrl:1
	v_cndmask_b32_e32 v15, v15, v3, vcc
	v_cndmask_b32_e32 v3, v3, v2, vcc
	v_max_u32_dpp v18, v18, v18 row_half_mirror row_mask:0xf bank_mask:0xf bound_ctrl:1
	v_cndmask_b32_e64 v2, v2, 0, vcc
	s_nop 0
	v_max_u32_dpp v18, v18, v18 row_mirror row_mask:0xf bank_mask:0xf bound_ctrl:1
	v_cmp_eq_u32_e32 vcc, v7, v18
	v_cndmask_b32_e64 v19, v19, v18, s[22:23]
	s_nop 0
	v_cndmask_b32_e32 v7, v7, v11, vcc
	v_cndmask_b32_e32 v11, v11, v10, vcc
	v_cndmask_b32_e32 v10, v10, v14, vcc
	v_max_u32_dpp v18, v7, v7 quad_perm:[1,0,3,2] row_mask:0xf bank_mask:0xf bound_ctrl:1
	v_cndmask_b32_e32 v14, v14, v6, vcc
	v_cndmask_b32_e32 v6, v6, v15, vcc
	v_max_u32_dpp v18, v18, v18 quad_perm:[2,3,0,1] row_mask:0xf bank_mask:0xf bound_ctrl:1
	v_cndmask_b32_e32 v15, v15, v3, vcc
	v_cndmask_b32_e32 v3, v3, v2, vcc
	v_max_u32_dpp v18, v18, v18 row_half_mirror row_mask:0xf bank_mask:0xf bound_ctrl:1
	v_cndmask_b32_e64 v2, v2, 0, vcc
	s_nop 0
	v_max_u32_dpp v18, v18, v18 row_mirror row_mask:0xf bank_mask:0xf bound_ctrl:1
	v_cmp_eq_u32_e32 vcc, v7, v18
	v_cndmask_b32_e64 v19, v19, v18, s[24:25]
	s_nop 0
	v_cndmask_b32_e32 v7, v7, v11, vcc
	v_cndmask_b32_e32 v11, v11, v10, vcc
	v_cndmask_b32_e32 v10, v10, v14, vcc
	v_max_u32_dpp v18, v7, v7 quad_perm:[1,0,3,2] row_mask:0xf bank_mask:0xf bound_ctrl:1
	v_cndmask_b32_e32 v14, v14, v6, vcc
	v_cndmask_b32_e32 v6, v6, v15, vcc
	v_max_u32_dpp v18, v18, v18 quad_perm:[2,3,0,1] row_mask:0xf bank_mask:0xf bound_ctrl:1
	v_cndmask_b32_e32 v15, v15, v3, vcc
	v_cndmask_b32_e32 v3, v3, v2, vcc
	v_max_u32_dpp v18, v18, v18 row_half_mirror row_mask:0xf bank_mask:0xf bound_ctrl:1
	v_cndmask_b32_e64 v2, v2, 0, vcc
	s_nop 0
	v_max_u32_dpp v18, v18, v18 row_mirror row_mask:0xf bank_mask:0xf bound_ctrl:1
	v_cmp_eq_u32_e32 vcc, v7, v18
	v_cndmask_b32_e64 v19, v19, v18, s[26:27]
	s_nop 0
	v_cndmask_b32_e32 v7, v7, v11, vcc
	v_cndmask_b32_e32 v11, v11, v10, vcc
	v_cndmask_b32_e32 v10, v10, v14, vcc
	v_cndmask_b32_e32 v14, v14, v6, vcc
	v_cndmask_b32_e32 v6, v6, v15, vcc
	v_cndmask_b32_e32 v15, v15, v3, vcc
	v_cndmask_b32_e32 v2, v3, v2, vcc
	v_max_u32_dpp v3, v7, v7 quad_perm:[1,0,3,2] row_mask:0xf bank_mask:0xf bound_ctrl:1
	s_nop 1
	v_max_u32_dpp v3, v3, v3 quad_perm:[2,3,0,1] row_mask:0xf bank_mask:0xf bound_ctrl:1
	s_nop 1
	v_max_u32_dpp v3, v3, v3 row_half_mirror row_mask:0xf bank_mask:0xf bound_ctrl:1
	s_nop 1
	v_max_u32_dpp v3, v3, v3 row_mirror row_mask:0xf bank_mask:0xf bound_ctrl:1
	v_cmp_eq_u32_e32 vcc, v7, v3
	v_cndmask_b32_e64 v18, v19, v3, s[28:29]
	s_nop 0
	v_cndmask_b32_e32 v3, v7, v11, vcc
	v_cndmask_b32_e32 v7, v11, v10, vcc
	v_cndmask_b32_e32 v10, v10, v14, vcc
	v_cndmask_b32_e32 v11, v14, v6, vcc
	v_max_u32_dpp v14, v3, v3 quad_perm:[1,0,3,2] row_mask:0xf bank_mask:0xf bound_ctrl:1
	v_cndmask_b32_e32 v6, v6, v15, vcc
	v_cndmask_b32_e32 v2, v15, v2, vcc
	v_max_u32_dpp v14, v14, v14 quad_perm:[2,3,0,1] row_mask:0xf bank_mask:0xf bound_ctrl:1
	s_nop 1
	v_max_u32_dpp v14, v14, v14 row_half_mirror row_mask:0xf bank_mask:0xf bound_ctrl:1
	s_nop 1
	v_max_u32_dpp v14, v14, v14 row_mirror row_mask:0xf bank_mask:0xf bound_ctrl:1
	v_cmp_eq_u32_e32 vcc, v3, v14
	v_cndmask_b32_e64 v15, v18, v14, s[30:31]
	s_nop 0
	v_cndmask_b32_e32 v3, v3, v7, vcc
	v_cndmask_b32_e32 v7, v7, v10, vcc
	v_cndmask_b32_e32 v10, v10, v11, vcc
	v_cndmask_b32_e32 v11, v11, v6, vcc
	v_cndmask_b32_e32 v2, v6, v2, vcc
	v_max_u32_dpp v6, v3, v3 quad_perm:[1,0,3,2] row_mask:0xf bank_mask:0xf bound_ctrl:1
	s_nop 1
	v_max_u32_dpp v6, v6, v6 quad_perm:[2,3,0,1] row_mask:0xf bank_mask:0xf bound_ctrl:1
	s_nop 1
	v_max_u32_dpp v6, v6, v6 row_half_mirror row_mask:0xf bank_mask:0xf bound_ctrl:1
	s_nop 1
	v_max_u32_dpp v6, v6, v6 row_mirror row_mask:0xf bank_mask:0xf bound_ctrl:1
	v_cmp_eq_u32_e32 vcc, v3, v6
	v_cndmask_b32_e64 v14, v15, v6, s[34:35]
	s_nop 0
	v_cndmask_b32_e32 v3, v3, v7, vcc
	v_cndmask_b32_e32 v6, v7, v10, vcc
	v_cndmask_b32_e32 v7, v10, v11, vcc
	v_max_u32_dpp v10, v3, v3 quad_perm:[1,0,3,2] row_mask:0xf bank_mask:0xf bound_ctrl:1
	v_cndmask_b32_e32 v2, v11, v2, vcc
	s_nop 0
	v_max_u32_dpp v10, v10, v10 quad_perm:[2,3,0,1] row_mask:0xf bank_mask:0xf bound_ctrl:1
	s_nop 1
	v_max_u32_dpp v10, v10, v10 row_half_mirror row_mask:0xf bank_mask:0xf bound_ctrl:1
	s_nop 1
	v_max_u32_dpp v10, v10, v10 row_mirror row_mask:0xf bank_mask:0xf bound_ctrl:1
	v_cmp_eq_u32_e32 vcc, v3, v10
	v_cndmask_b32_e64 v11, v14, v10, s[36:37]
	s_nop 0
	v_cndmask_b32_e32 v3, v3, v6, vcc
	v_cndmask_b32_e32 v6, v6, v7, vcc
	v_cndmask_b32_e32 v2, v7, v2, vcc
	v_max_u32_dpp v7, v3, v3 quad_perm:[1,0,3,2] row_mask:0xf bank_mask:0xf bound_ctrl:1
	s_nop 1
	v_max_u32_dpp v7, v7, v7 quad_perm:[2,3,0,1] row_mask:0xf bank_mask:0xf bound_ctrl:1
	s_nop 1
	v_max_u32_dpp v7, v7, v7 row_half_mirror row_mask:0xf bank_mask:0xf bound_ctrl:1
	s_nop 1
	v_max_u32_dpp v7, v7, v7 row_mirror row_mask:0xf bank_mask:0xf bound_ctrl:1
	v_cmp_eq_u32_e32 vcc, v3, v7
	v_cndmask_b32_e64 v10, v11, v7, s[38:39]
	v_ashrrev_i32_e32 v11, 31, v32
	v_cndmask_b32_e32 v3, v3, v6, vcc
	v_cndmask_b32_e32 v2, v6, v2, vcc
	v_bitop3_b32 v11, v11, v32, s70 bitop3:0x36
	v_max_u32_dpp v6, v3, v3 quad_perm:[1,0,3,2] row_mask:0xf bank_mask:0xf bound_ctrl:1
	v_and_or_b32 v11, v11, s71, v72
	s_nop 0
	v_max_u32_dpp v6, v6, v6 quad_perm:[2,3,0,1] row_mask:0xf bank_mask:0xf bound_ctrl:1
	s_nop 1
	v_max_u32_dpp v6, v6, v6 row_half_mirror row_mask:0xf bank_mask:0xf bound_ctrl:1
	s_nop 1
	v_max_u32_dpp v6, v6, v6 row_mirror row_mask:0xf bank_mask:0xf bound_ctrl:1
	v_cmp_eq_u32_e32 vcc, v3, v6
	v_cndmask_b32_e64 v7, v10, v6, s[40:41]
	v_ashrrev_i32_e32 v6, 31, v16
	v_cndmask_b32_e32 v2, v3, v2, vcc
	v_ashrrev_i32_e32 v3, 31, v8
	v_bitop3_b32 v3, v3, v8, s70 bitop3:0x36
	v_max_u32_dpp v2, v2, v2 quad_perm:[1,0,3,2] row_mask:0xf bank_mask:0xf bound_ctrl:1
	v_ashrrev_i32_e32 v8, 31, v24
	v_ashrrev_i32_e32 v10, 31, v28
	v_max_u32_dpp v2, v2, v2 quad_perm:[2,3,0,1] row_mask:0xf bank_mask:0xf bound_ctrl:1
	v_bitop3_b32 v6, v6, v16, s70 bitop3:0x36
	v_bitop3_b32 v8, v8, v24, s70 bitop3:0x36
	v_max_u32_dpp v2, v2, v2 row_half_mirror row_mask:0xf bank_mask:0xf bound_ctrl:1
	v_bitop3_b32 v10, v10, v28, s70 bitop3:0x36
	v_and_or_b32 v3, v3, s71, v66
	v_max_u32_dpp v2, v2, v2 row_mirror row_mask:0xf bank_mask:0xf bound_ctrl:1
	v_cndmask_b32_e64 v82, v7, v2, s[42:43]
	v_ashrrev_i32_e32 v2, 31, v4
	v_bitop3_b32 v2, v2, v4, s70 bitop3:0x36
	v_ashrrev_i32_e32 v4, 31, v12
	v_ashrrev_i32_e32 v7, 31, v20
	v_bitop3_b32 v4, v4, v12, s70 bitop3:0x36
	v_bitop3_b32 v7, v7, v20, s70 bitop3:0x36
	v_and_or_b32 v2, v2, s71, v61
	v_and_or_b32 v4, v4, s71, v67
	v_and_or_b32 v6, v6, s71, v68
	v_and_or_b32 v7, v7, s71, v69
	v_and_or_b32 v8, v8, s71, v70
	v_and_or_b32 v10, v10, s71, v71
	v_max_u32_e32 v12, v2, v3
	v_min_u32_e32 v2, v2, v3
	v_max_u32_e32 v3, v4, v6
	v_min_u32_e32 v4, v4, v6
	v_max_u32_e32 v6, v7, v8
	v_min_u32_e32 v7, v7, v8
	v_max_u32_e32 v8, v10, v11
	v_min_u32_e32 v10, v10, v11
	v_max_u32_e32 v11, v12, v3
	v_min_u32_e32 v3, v12, v3
	v_max_u32_e32 v12, v2, v4
	v_min_u32_e32 v2, v2, v4
	v_max_u32_e32 v4, v6, v8
	v_min_u32_e32 v6, v6, v8
	v_max_u32_e32 v8, v7, v10
	v_min_u32_e32 v7, v7, v10
	v_max_u32_e32 v10, v12, v3
	v_min_u32_e32 v3, v12, v3
	v_max_u32_e32 v12, v8, v6
	v_min_u32_e32 v6, v8, v6
	v_max_u32_e32 v8, v11, v4
	v_min_u32_e32 v4, v11, v4
	v_max_u32_e32 v11, v10, v12
	v_min_u32_e32 v10, v10, v12
	v_max_u32_e32 v12, v3, v6
	v_min_u32_e32 v3, v3, v6
	v_max_u32_e32 v6, v2, v7
	v_min_u32_e32 v2, v2, v7
	v_max_u32_e32 v7, v12, v4
	v_min_u32_e32 v4, v12, v4
	v_max_u32_e32 v12, v6, v10
	v_min_u32_e32 v6, v6, v10
	v_max_u32_e32 v10, v11, v7
	v_min_u32_e32 v7, v11, v7
	v_max_u32_e32 v11, v12, v4
	v_min_u32_e32 v4, v12, v4
	v_max_u32_e32 v12, v6, v3
	v_min_u32_e32 v3, v6, v3
	v_max_u32_dpp v6, v8, v8 quad_perm:[1,0,3,2] row_mask:0xf bank_mask:0xf bound_ctrl:1
	s_nop 1
	v_max_u32_dpp v6, v6, v6 quad_perm:[2,3,0,1] row_mask:0xf bank_mask:0xf bound_ctrl:1
	s_nop 1
	v_max_u32_dpp v6, v6, v6 row_half_mirror row_mask:0xf bank_mask:0xf bound_ctrl:1
	s_nop 1
	v_max_u32_dpp v6, v6, v6 row_mirror row_mask:0xf bank_mask:0xf bound_ctrl:1
	v_cmp_eq_u32_e32 vcc, v8, v6
	v_cndmask_b32_e64 v14, 0, v6, s[10:11]
	s_nop 0
	v_cndmask_b32_e32 v6, v8, v10, vcc
	v_cndmask_b32_e32 v8, v10, v7, vcc
	v_cndmask_b32_e32 v7, v7, v11, vcc
	v_cndmask_b32_e32 v10, v11, v4, vcc
	v_cndmask_b32_e32 v4, v4, v12, vcc
	v_cndmask_b32_e32 v11, v12, v3, vcc
	v_max_u32_dpp v12, v6, v6 quad_perm:[1,0,3,2] row_mask:0xf bank_mask:0xf bound_ctrl:1
	v_cndmask_b32_e32 v3, v3, v2, vcc
	v_cndmask_b32_e64 v2, v2, 0, vcc
	v_max_u32_dpp v12, v12, v12 quad_perm:[2,3,0,1] row_mask:0xf bank_mask:0xf bound_ctrl:1
	s_nop 1
	v_max_u32_dpp v12, v12, v12 row_half_mirror row_mask:0xf bank_mask:0xf bound_ctrl:1
	s_nop 1
	v_max_u32_dpp v12, v12, v12 row_mirror row_mask:0xf bank_mask:0xf bound_ctrl:1
	v_cmp_eq_u32_e32 vcc, v6, v12
	v_cndmask_b32_e64 v14, v14, v12, s[12:13]
	s_nop 0
	v_cndmask_b32_e32 v6, v6, v8, vcc
	v_cndmask_b32_e32 v8, v8, v7, vcc
	v_cndmask_b32_e32 v7, v7, v10, vcc
	v_max_u32_dpp v12, v6, v6 quad_perm:[1,0,3,2] row_mask:0xf bank_mask:0xf bound_ctrl:1
	v_cndmask_b32_e32 v10, v10, v4, vcc
	v_cndmask_b32_e32 v4, v4, v11, vcc
	v_max_u32_dpp v12, v12, v12 quad_perm:[2,3,0,1] row_mask:0xf bank_mask:0xf bound_ctrl:1
	v_cndmask_b32_e32 v11, v11, v3, vcc
	v_cndmask_b32_e32 v3, v3, v2, vcc
	v_max_u32_dpp v12, v12, v12 row_half_mirror row_mask:0xf bank_mask:0xf bound_ctrl:1
	v_cndmask_b32_e64 v2, v2, 0, vcc
	s_nop 0
	v_max_u32_dpp v12, v12, v12 row_mirror row_mask:0xf bank_mask:0xf bound_ctrl:1
	v_cmp_eq_u32_e32 vcc, v6, v12
	v_cndmask_b32_e64 v14, v14, v12, s[14:15]
	s_nop 0
	v_cndmask_b32_e32 v6, v6, v8, vcc
	v_cndmask_b32_e32 v8, v8, v7, vcc
	v_cndmask_b32_e32 v7, v7, v10, vcc
	v_max_u32_dpp v12, v6, v6 quad_perm:[1,0,3,2] row_mask:0xf bank_mask:0xf bound_ctrl:1
	v_cndmask_b32_e32 v10, v10, v4, vcc
	v_cndmask_b32_e32 v4, v4, v11, vcc
	v_max_u32_dpp v12, v12, v12 quad_perm:[2,3,0,1] row_mask:0xf bank_mask:0xf bound_ctrl:1
	v_cndmask_b32_e32 v11, v11, v3, vcc
	v_cndmask_b32_e32 v3, v3, v2, vcc
	v_max_u32_dpp v12, v12, v12 row_half_mirror row_mask:0xf bank_mask:0xf bound_ctrl:1
	v_cndmask_b32_e64 v2, v2, 0, vcc
	s_nop 0
	v_max_u32_dpp v12, v12, v12 row_mirror row_mask:0xf bank_mask:0xf bound_ctrl:1
	v_cmp_eq_u32_e32 vcc, v6, v12
	v_cndmask_b32_e64 v14, v14, v12, s[16:17]
	s_nop 0
	v_cndmask_b32_e32 v6, v6, v8, vcc
	v_cndmask_b32_e32 v8, v8, v7, vcc
	v_cndmask_b32_e32 v7, v7, v10, vcc
	v_max_u32_dpp v12, v6, v6 quad_perm:[1,0,3,2] row_mask:0xf bank_mask:0xf bound_ctrl:1
	v_cndmask_b32_e32 v10, v10, v4, vcc
	v_cndmask_b32_e32 v4, v4, v11, vcc
	v_max_u32_dpp v12, v12, v12 quad_perm:[2,3,0,1] row_mask:0xf bank_mask:0xf bound_ctrl:1
	v_cndmask_b32_e32 v11, v11, v3, vcc
	v_cndmask_b32_e32 v3, v3, v2, vcc
	v_max_u32_dpp v12, v12, v12 row_half_mirror row_mask:0xf bank_mask:0xf bound_ctrl:1
	v_cndmask_b32_e64 v2, v2, 0, vcc
	s_nop 0
	v_max_u32_dpp v12, v12, v12 row_mirror row_mask:0xf bank_mask:0xf bound_ctrl:1
	v_cmp_eq_u32_e32 vcc, v6, v12
	v_cndmask_b32_e64 v14, v14, v12, s[18:19]
	s_nop 0
	v_cndmask_b32_e32 v6, v6, v8, vcc
	v_cndmask_b32_e32 v8, v8, v7, vcc
	v_cndmask_b32_e32 v7, v7, v10, vcc
	v_max_u32_dpp v12, v6, v6 quad_perm:[1,0,3,2] row_mask:0xf bank_mask:0xf bound_ctrl:1
	v_cndmask_b32_e32 v10, v10, v4, vcc
	v_cndmask_b32_e32 v4, v4, v11, vcc
	v_max_u32_dpp v12, v12, v12 quad_perm:[2,3,0,1] row_mask:0xf bank_mask:0xf bound_ctrl:1
	v_cndmask_b32_e32 v11, v11, v3, vcc
	v_cndmask_b32_e32 v3, v3, v2, vcc
	v_max_u32_dpp v12, v12, v12 row_half_mirror row_mask:0xf bank_mask:0xf bound_ctrl:1
	v_cndmask_b32_e64 v2, v2, 0, vcc
	s_nop 0
	v_max_u32_dpp v12, v12, v12 row_mirror row_mask:0xf bank_mask:0xf bound_ctrl:1
	v_cmp_eq_u32_e32 vcc, v6, v12
	v_cndmask_b32_e64 v14, v14, v12, s[20:21]
	s_nop 0
	v_cndmask_b32_e32 v6, v6, v8, vcc
	v_cndmask_b32_e32 v8, v8, v7, vcc
	v_cndmask_b32_e32 v7, v7, v10, vcc
	v_max_u32_dpp v12, v6, v6 quad_perm:[1,0,3,2] row_mask:0xf bank_mask:0xf bound_ctrl:1
	v_cndmask_b32_e32 v10, v10, v4, vcc
	v_cndmask_b32_e32 v4, v4, v11, vcc
	v_max_u32_dpp v12, v12, v12 quad_perm:[2,3,0,1] row_mask:0xf bank_mask:0xf bound_ctrl:1
	v_cndmask_b32_e32 v11, v11, v3, vcc
	v_cndmask_b32_e32 v3, v3, v2, vcc
	v_max_u32_dpp v12, v12, v12 row_half_mirror row_mask:0xf bank_mask:0xf bound_ctrl:1
	v_cndmask_b32_e64 v2, v2, 0, vcc
	s_nop 0
	v_max_u32_dpp v12, v12, v12 row_mirror row_mask:0xf bank_mask:0xf bound_ctrl:1
	v_cmp_eq_u32_e32 vcc, v6, v12
	v_cndmask_b32_e64 v14, v14, v12, s[22:23]
	s_nop 0
	v_cndmask_b32_e32 v6, v6, v8, vcc
	v_cndmask_b32_e32 v8, v8, v7, vcc
	v_cndmask_b32_e32 v7, v7, v10, vcc
	v_max_u32_dpp v12, v6, v6 quad_perm:[1,0,3,2] row_mask:0xf bank_mask:0xf bound_ctrl:1
	v_cndmask_b32_e32 v10, v10, v4, vcc
	v_cndmask_b32_e32 v4, v4, v11, vcc
	v_max_u32_dpp v12, v12, v12 quad_perm:[2,3,0,1] row_mask:0xf bank_mask:0xf bound_ctrl:1
	v_cndmask_b32_e32 v11, v11, v3, vcc
	v_cndmask_b32_e32 v3, v3, v2, vcc
	v_max_u32_dpp v12, v12, v12 row_half_mirror row_mask:0xf bank_mask:0xf bound_ctrl:1
	v_cndmask_b32_e64 v2, v2, 0, vcc
	s_nop 0
	v_max_u32_dpp v12, v12, v12 row_mirror row_mask:0xf bank_mask:0xf bound_ctrl:1
	v_cmp_eq_u32_e32 vcc, v6, v12
	v_cndmask_b32_e64 v14, v14, v12, s[24:25]
	s_nop 0
	v_cndmask_b32_e32 v6, v6, v8, vcc
	v_cndmask_b32_e32 v8, v8, v7, vcc
	v_cndmask_b32_e32 v7, v7, v10, vcc
	v_max_u32_dpp v12, v6, v6 quad_perm:[1,0,3,2] row_mask:0xf bank_mask:0xf bound_ctrl:1
	v_cndmask_b32_e32 v10, v10, v4, vcc
	v_cndmask_b32_e32 v4, v4, v11, vcc
	v_max_u32_dpp v12, v12, v12 quad_perm:[2,3,0,1] row_mask:0xf bank_mask:0xf bound_ctrl:1
	v_cndmask_b32_e32 v11, v11, v3, vcc
	v_cndmask_b32_e32 v3, v3, v2, vcc
	v_max_u32_dpp v12, v12, v12 row_half_mirror row_mask:0xf bank_mask:0xf bound_ctrl:1
	v_cndmask_b32_e64 v2, v2, 0, vcc
	s_nop 0
	v_max_u32_dpp v12, v12, v12 row_mirror row_mask:0xf bank_mask:0xf bound_ctrl:1
	v_cmp_eq_u32_e32 vcc, v6, v12
	v_cndmask_b32_e64 v14, v14, v12, s[26:27]
	s_nop 0
	v_cndmask_b32_e32 v6, v6, v8, vcc
	v_cndmask_b32_e32 v8, v8, v7, vcc
	v_cndmask_b32_e32 v7, v7, v10, vcc
	v_cndmask_b32_e32 v10, v10, v4, vcc
	v_cndmask_b32_e32 v4, v4, v11, vcc
	v_cndmask_b32_e32 v11, v11, v3, vcc
	v_cndmask_b32_e32 v2, v3, v2, vcc
	v_max_u32_dpp v3, v6, v6 quad_perm:[1,0,3,2] row_mask:0xf bank_mask:0xf bound_ctrl:1
	s_nop 1
	v_max_u32_dpp v3, v3, v3 quad_perm:[2,3,0,1] row_mask:0xf bank_mask:0xf bound_ctrl:1
	s_nop 1
	v_max_u32_dpp v3, v3, v3 row_half_mirror row_mask:0xf bank_mask:0xf bound_ctrl:1
	s_nop 1
	v_max_u32_dpp v3, v3, v3 row_mirror row_mask:0xf bank_mask:0xf bound_ctrl:1
	v_cmp_eq_u32_e32 vcc, v6, v3
	v_cndmask_b32_e64 v12, v14, v3, s[28:29]
	s_nop 0
	v_cndmask_b32_e32 v3, v6, v8, vcc
	v_cndmask_b32_e32 v6, v8, v7, vcc
	v_cndmask_b32_e32 v7, v7, v10, vcc
	v_cndmask_b32_e32 v8, v10, v4, vcc
	v_max_u32_dpp v10, v3, v3 quad_perm:[1,0,3,2] row_mask:0xf bank_mask:0xf bound_ctrl:1
	v_cndmask_b32_e32 v4, v4, v11, vcc
	v_cndmask_b32_e32 v2, v11, v2, vcc
	v_max_u32_dpp v10, v10, v10 quad_perm:[2,3,0,1] row_mask:0xf bank_mask:0xf bound_ctrl:1
	s_nop 1
	v_max_u32_dpp v10, v10, v10 row_half_mirror row_mask:0xf bank_mask:0xf bound_ctrl:1
	s_nop 1
	v_max_u32_dpp v10, v10, v10 row_mirror row_mask:0xf bank_mask:0xf bound_ctrl:1
	v_cmp_eq_u32_e32 vcc, v3, v10
	v_cndmask_b32_e64 v11, v12, v10, s[30:31]
	s_nop 0
	v_cndmask_b32_e32 v3, v3, v6, vcc
	v_cndmask_b32_e32 v6, v6, v7, vcc
	v_cndmask_b32_e32 v7, v7, v8, vcc
	v_cndmask_b32_e32 v8, v8, v4, vcc
	v_cndmask_b32_e32 v2, v4, v2, vcc
	v_max_u32_dpp v4, v3, v3 quad_perm:[1,0,3,2] row_mask:0xf bank_mask:0xf bound_ctrl:1
	s_nop 1
	v_max_u32_dpp v4, v4, v4 quad_perm:[2,3,0,1] row_mask:0xf bank_mask:0xf bound_ctrl:1
	s_nop 1
	v_max_u32_dpp v4, v4, v4 row_half_mirror row_mask:0xf bank_mask:0xf bound_ctrl:1
	s_nop 1
	v_max_u32_dpp v4, v4, v4 row_mirror row_mask:0xf bank_mask:0xf bound_ctrl:1
	v_cmp_eq_u32_e32 vcc, v3, v4
	v_cndmask_b32_e64 v10, v11, v4, s[34:35]
	s_nop 0
	v_cndmask_b32_e32 v3, v3, v6, vcc
	v_cndmask_b32_e32 v4, v6, v7, vcc
	v_cndmask_b32_e32 v6, v7, v8, vcc
	v_max_u32_dpp v7, v3, v3 quad_perm:[1,0,3,2] row_mask:0xf bank_mask:0xf bound_ctrl:1
	v_cndmask_b32_e32 v2, v8, v2, vcc
	s_nop 0
	v_max_u32_dpp v7, v7, v7 quad_perm:[2,3,0,1] row_mask:0xf bank_mask:0xf bound_ctrl:1
	s_nop 1
	v_max_u32_dpp v7, v7, v7 row_half_mirror row_mask:0xf bank_mask:0xf bound_ctrl:1
	s_nop 1
	v_max_u32_dpp v7, v7, v7 row_mirror row_mask:0xf bank_mask:0xf bound_ctrl:1
	v_cmp_eq_u32_e32 vcc, v3, v7
	v_cndmask_b32_e64 v8, v10, v7, s[36:37]
	s_nop 0
	v_cndmask_b32_e32 v3, v3, v4, vcc
	v_cndmask_b32_e32 v4, v4, v6, vcc
	v_cndmask_b32_e32 v2, v6, v2, vcc
	v_max_u32_dpp v6, v3, v3 quad_perm:[1,0,3,2] row_mask:0xf bank_mask:0xf bound_ctrl:1
	s_nop 1
	v_max_u32_dpp v6, v6, v6 quad_perm:[2,3,0,1] row_mask:0xf bank_mask:0xf bound_ctrl:1
	s_nop 1
	v_max_u32_dpp v6, v6, v6 row_half_mirror row_mask:0xf bank_mask:0xf bound_ctrl:1
	s_nop 1
	v_max_u32_dpp v6, v6, v6 row_mirror row_mask:0xf bank_mask:0xf bound_ctrl:1
	v_cmp_eq_u32_e32 vcc, v3, v6
	v_cndmask_b32_e64 v7, v8, v6, s[38:39]
	v_ashrrev_i32_e32 v8, 31, v29
	v_cndmask_b32_e32 v3, v3, v4, vcc
	v_cndmask_b32_e32 v2, v4, v2, vcc
	v_bitop3_b32 v8, v8, v29, s70 bitop3:0x36
	v_max_u32_dpp v4, v3, v3 quad_perm:[1,0,3,2] row_mask:0xf bank_mask:0xf bound_ctrl:1
	v_and_or_b32 v8, v8, s71, v71
	s_nop 0
	v_max_u32_dpp v4, v4, v4 quad_perm:[2,3,0,1] row_mask:0xf bank_mask:0xf bound_ctrl:1
	s_nop 1
	v_max_u32_dpp v4, v4, v4 row_half_mirror row_mask:0xf bank_mask:0xf bound_ctrl:1
	s_nop 1
	v_max_u32_dpp v4, v4, v4 row_mirror row_mask:0xf bank_mask:0xf bound_ctrl:1
	v_cmp_eq_u32_e32 vcc, v3, v4
	v_cndmask_b32_e64 v6, v7, v4, s[40:41]
	v_ashrrev_i32_e32 v4, 31, v13
	v_cndmask_b32_e32 v2, v3, v2, vcc
	v_ashrrev_i32_e32 v3, 31, v9
	v_bitop3_b32 v3, v3, v9, s70 bitop3:0x36
	v_max_u32_dpp v2, v2, v2 quad_perm:[1,0,3,2] row_mask:0xf bank_mask:0xf bound_ctrl:1
	v_ashrrev_i32_e32 v7, 31, v25
	v_ashrrev_i32_e32 v9, 31, v33
	v_max_u32_dpp v2, v2, v2 quad_perm:[2,3,0,1] row_mask:0xf bank_mask:0xf bound_ctrl:1
	v_bitop3_b32 v4, v4, v13, s70 bitop3:0x36
	v_bitop3_b32 v7, v7, v25, s70 bitop3:0x36
	v_max_u32_dpp v2, v2, v2 row_half_mirror row_mask:0xf bank_mask:0xf bound_ctrl:1
	v_bitop3_b32 v9, v9, v33, s70 bitop3:0x36
	v_and_or_b32 v3, v3, s71, v66
	v_max_u32_dpp v2, v2, v2 row_mirror row_mask:0xf bank_mask:0xf bound_ctrl:1
	v_cndmask_b32_e64 v81, v6, v2, s[42:43]
	v_ashrrev_i32_e32 v2, 31, v5
	v_bitop3_b32 v2, v2, v5, s70 bitop3:0x36
	v_ashrrev_i32_e32 v5, 31, v17
	v_ashrrev_i32_e32 v6, 31, v21
	v_bitop3_b32 v5, v5, v17, s70 bitop3:0x36
	v_bitop3_b32 v6, v6, v21, s70 bitop3:0x36
	v_and_or_b32 v2, v2, s71, v61
	v_and_or_b32 v4, v4, s71, v67
	v_and_or_b32 v5, v5, s71, v68
	v_and_or_b32 v6, v6, s71, v69
	v_and_or_b32 v7, v7, s71, v70
	v_and_or_b32 v9, v9, s71, v72
	v_max_u32_e32 v10, v2, v3
	v_min_u32_e32 v2, v2, v3
	v_max_u32_e32 v3, v4, v5
	v_min_u32_e32 v4, v4, v5
	v_max_u32_e32 v5, v6, v7
	v_min_u32_e32 v6, v6, v7
	v_max_u32_e32 v7, v8, v9
	v_min_u32_e32 v8, v8, v9
	v_max_u32_e32 v9, v10, v3
	v_min_u32_e32 v3, v10, v3
	v_max_u32_e32 v10, v2, v4
	v_min_u32_e32 v2, v2, v4
	v_max_u32_e32 v4, v5, v7
	v_min_u32_e32 v5, v5, v7
	v_max_u32_e32 v7, v6, v8
	v_min_u32_e32 v6, v6, v8
	v_max_u32_e32 v8, v10, v3
	v_min_u32_e32 v3, v10, v3
	v_max_u32_e32 v10, v7, v5
	v_min_u32_e32 v5, v7, v5
	v_max_u32_e32 v7, v9, v4
	v_min_u32_e32 v4, v9, v4
	v_max_u32_e32 v9, v8, v10
	v_min_u32_e32 v8, v8, v10
	v_max_u32_e32 v10, v3, v5
	v_min_u32_e32 v3, v3, v5
	v_max_u32_e32 v5, v2, v6
	v_min_u32_e32 v2, v2, v6
	v_max_u32_e32 v6, v10, v4
	v_min_u32_e32 v4, v10, v4
	v_max_u32_e32 v10, v5, v8
	v_min_u32_e32 v5, v5, v8
	v_max_u32_e32 v8, v9, v6
	v_min_u32_e32 v6, v9, v6
	v_max_u32_e32 v9, v10, v4
	v_min_u32_e32 v4, v10, v4
	v_max_u32_e32 v10, v5, v3
	v_min_u32_e32 v3, v5, v3
	v_max_u32_dpp v5, v7, v7 quad_perm:[1,0,3,2] row_mask:0xf bank_mask:0xf bound_ctrl:1
	s_nop 1
	v_max_u32_dpp v5, v5, v5 quad_perm:[2,3,0,1] row_mask:0xf bank_mask:0xf bound_ctrl:1
	s_nop 1
	v_max_u32_dpp v5, v5, v5 row_half_mirror row_mask:0xf bank_mask:0xf bound_ctrl:1
	s_nop 1
	v_max_u32_dpp v5, v5, v5 row_mirror row_mask:0xf bank_mask:0xf bound_ctrl:1
	v_cmp_eq_u32_e32 vcc, v7, v5
	v_cndmask_b32_e64 v11, 0, v5, s[10:11]
	s_nop 0
	v_cndmask_b32_e32 v5, v7, v8, vcc
	v_cndmask_b32_e32 v7, v8, v6, vcc
	v_cndmask_b32_e32 v6, v6, v9, vcc
	v_cndmask_b32_e32 v8, v9, v4, vcc
	v_cndmask_b32_e32 v4, v4, v10, vcc
	v_cndmask_b32_e32 v9, v10, v3, vcc
	v_max_u32_dpp v10, v5, v5 quad_perm:[1,0,3,2] row_mask:0xf bank_mask:0xf bound_ctrl:1
	v_cndmask_b32_e32 v3, v3, v2, vcc
	v_cndmask_b32_e64 v2, v2, 0, vcc
	v_max_u32_dpp v10, v10, v10 quad_perm:[2,3,0,1] row_mask:0xf bank_mask:0xf bound_ctrl:1
	s_nop 1
	v_max_u32_dpp v10, v10, v10 row_half_mirror row_mask:0xf bank_mask:0xf bound_ctrl:1
	s_nop 1
	v_max_u32_dpp v10, v10, v10 row_mirror row_mask:0xf bank_mask:0xf bound_ctrl:1
	v_cmp_eq_u32_e32 vcc, v5, v10
	v_cndmask_b32_e64 v11, v11, v10, s[12:13]
	s_nop 0
	v_cndmask_b32_e32 v5, v5, v7, vcc
	v_cndmask_b32_e32 v7, v7, v6, vcc
	v_cndmask_b32_e32 v6, v6, v8, vcc
	v_max_u32_dpp v10, v5, v5 quad_perm:[1,0,3,2] row_mask:0xf bank_mask:0xf bound_ctrl:1
	v_cndmask_b32_e32 v8, v8, v4, vcc
	v_cndmask_b32_e32 v4, v4, v9, vcc
	v_max_u32_dpp v10, v10, v10 quad_perm:[2,3,0,1] row_mask:0xf bank_mask:0xf bound_ctrl:1
	v_cndmask_b32_e32 v9, v9, v3, vcc
	v_cndmask_b32_e32 v3, v3, v2, vcc
	v_max_u32_dpp v10, v10, v10 row_half_mirror row_mask:0xf bank_mask:0xf bound_ctrl:1
	v_cndmask_b32_e64 v2, v2, 0, vcc
	s_nop 0
	v_max_u32_dpp v10, v10, v10 row_mirror row_mask:0xf bank_mask:0xf bound_ctrl:1
	v_cmp_eq_u32_e32 vcc, v5, v10
	v_cndmask_b32_e64 v11, v11, v10, s[14:15]
	s_nop 0
	v_cndmask_b32_e32 v5, v5, v7, vcc
	v_cndmask_b32_e32 v7, v7, v6, vcc
	v_cndmask_b32_e32 v6, v6, v8, vcc
	v_max_u32_dpp v10, v5, v5 quad_perm:[1,0,3,2] row_mask:0xf bank_mask:0xf bound_ctrl:1
	v_cndmask_b32_e32 v8, v8, v4, vcc
	v_cndmask_b32_e32 v4, v4, v9, vcc
	v_max_u32_dpp v10, v10, v10 quad_perm:[2,3,0,1] row_mask:0xf bank_mask:0xf bound_ctrl:1
	v_cndmask_b32_e32 v9, v9, v3, vcc
	v_cndmask_b32_e32 v3, v3, v2, vcc
	v_max_u32_dpp v10, v10, v10 row_half_mirror row_mask:0xf bank_mask:0xf bound_ctrl:1
	v_cndmask_b32_e64 v2, v2, 0, vcc
	s_nop 0
	v_max_u32_dpp v10, v10, v10 row_mirror row_mask:0xf bank_mask:0xf bound_ctrl:1
	v_cmp_eq_u32_e32 vcc, v5, v10
	v_cndmask_b32_e64 v11, v11, v10, s[16:17]
	s_nop 0
	v_cndmask_b32_e32 v5, v5, v7, vcc
	v_cndmask_b32_e32 v7, v7, v6, vcc
	v_cndmask_b32_e32 v6, v6, v8, vcc
	v_max_u32_dpp v10, v5, v5 quad_perm:[1,0,3,2] row_mask:0xf bank_mask:0xf bound_ctrl:1
	v_cndmask_b32_e32 v8, v8, v4, vcc
	v_cndmask_b32_e32 v4, v4, v9, vcc
	v_max_u32_dpp v10, v10, v10 quad_perm:[2,3,0,1] row_mask:0xf bank_mask:0xf bound_ctrl:1
	v_cndmask_b32_e32 v9, v9, v3, vcc
	v_cndmask_b32_e32 v3, v3, v2, vcc
	v_max_u32_dpp v10, v10, v10 row_half_mirror row_mask:0xf bank_mask:0xf bound_ctrl:1
	v_cndmask_b32_e64 v2, v2, 0, vcc
	s_nop 0
	v_max_u32_dpp v10, v10, v10 row_mirror row_mask:0xf bank_mask:0xf bound_ctrl:1
	v_cmp_eq_u32_e32 vcc, v5, v10
	v_cndmask_b32_e64 v11, v11, v10, s[18:19]
	s_nop 0
	v_cndmask_b32_e32 v5, v5, v7, vcc
	v_cndmask_b32_e32 v7, v7, v6, vcc
	v_cndmask_b32_e32 v6, v6, v8, vcc
	v_max_u32_dpp v10, v5, v5 quad_perm:[1,0,3,2] row_mask:0xf bank_mask:0xf bound_ctrl:1
	v_cndmask_b32_e32 v8, v8, v4, vcc
	v_cndmask_b32_e32 v4, v4, v9, vcc
	v_max_u32_dpp v10, v10, v10 quad_perm:[2,3,0,1] row_mask:0xf bank_mask:0xf bound_ctrl:1
	v_cndmask_b32_e32 v9, v9, v3, vcc
	v_cndmask_b32_e32 v3, v3, v2, vcc
	v_max_u32_dpp v10, v10, v10 row_half_mirror row_mask:0xf bank_mask:0xf bound_ctrl:1
	v_cndmask_b32_e64 v2, v2, 0, vcc
	s_nop 0
	v_max_u32_dpp v10, v10, v10 row_mirror row_mask:0xf bank_mask:0xf bound_ctrl:1
	v_cmp_eq_u32_e32 vcc, v5, v10
	v_cndmask_b32_e64 v11, v11, v10, s[20:21]
	s_nop 0
	v_cndmask_b32_e32 v5, v5, v7, vcc
	v_cndmask_b32_e32 v7, v7, v6, vcc
	v_cndmask_b32_e32 v6, v6, v8, vcc
	v_max_u32_dpp v10, v5, v5 quad_perm:[1,0,3,2] row_mask:0xf bank_mask:0xf bound_ctrl:1
	v_cndmask_b32_e32 v8, v8, v4, vcc
	v_cndmask_b32_e32 v4, v4, v9, vcc
	v_max_u32_dpp v10, v10, v10 quad_perm:[2,3,0,1] row_mask:0xf bank_mask:0xf bound_ctrl:1
	v_cndmask_b32_e32 v9, v9, v3, vcc
	v_cndmask_b32_e32 v3, v3, v2, vcc
	v_max_u32_dpp v10, v10, v10 row_half_mirror row_mask:0xf bank_mask:0xf bound_ctrl:1
	v_cndmask_b32_e64 v2, v2, 0, vcc
	s_nop 0
	v_max_u32_dpp v10, v10, v10 row_mirror row_mask:0xf bank_mask:0xf bound_ctrl:1
	v_cmp_eq_u32_e32 vcc, v5, v10
	v_cndmask_b32_e64 v11, v11, v10, s[22:23]
	s_nop 0
	v_cndmask_b32_e32 v5, v5, v7, vcc
	v_cndmask_b32_e32 v7, v7, v6, vcc
	v_cndmask_b32_e32 v6, v6, v8, vcc
	v_max_u32_dpp v10, v5, v5 quad_perm:[1,0,3,2] row_mask:0xf bank_mask:0xf bound_ctrl:1
	v_cndmask_b32_e32 v8, v8, v4, vcc
	v_cndmask_b32_e32 v4, v4, v9, vcc
	v_max_u32_dpp v10, v10, v10 quad_perm:[2,3,0,1] row_mask:0xf bank_mask:0xf bound_ctrl:1
	v_cndmask_b32_e32 v9, v9, v3, vcc
	v_cndmask_b32_e32 v3, v3, v2, vcc
	v_max_u32_dpp v10, v10, v10 row_half_mirror row_mask:0xf bank_mask:0xf bound_ctrl:1
	v_cndmask_b32_e64 v2, v2, 0, vcc
	s_nop 0
	v_max_u32_dpp v10, v10, v10 row_mirror row_mask:0xf bank_mask:0xf bound_ctrl:1
	v_cmp_eq_u32_e32 vcc, v5, v10
	v_cndmask_b32_e64 v11, v11, v10, s[24:25]
	s_nop 0
	v_cndmask_b32_e32 v5, v5, v7, vcc
	v_cndmask_b32_e32 v7, v7, v6, vcc
	v_cndmask_b32_e32 v6, v6, v8, vcc
	v_max_u32_dpp v10, v5, v5 quad_perm:[1,0,3,2] row_mask:0xf bank_mask:0xf bound_ctrl:1
	v_cndmask_b32_e32 v8, v8, v4, vcc
	v_cndmask_b32_e32 v4, v4, v9, vcc
	v_max_u32_dpp v10, v10, v10 quad_perm:[2,3,0,1] row_mask:0xf bank_mask:0xf bound_ctrl:1
	v_cndmask_b32_e32 v9, v9, v3, vcc
	v_cndmask_b32_e32 v3, v3, v2, vcc
	v_max_u32_dpp v10, v10, v10 row_half_mirror row_mask:0xf bank_mask:0xf bound_ctrl:1
	v_cndmask_b32_e64 v2, v2, 0, vcc
	s_nop 0
	v_max_u32_dpp v10, v10, v10 row_mirror row_mask:0xf bank_mask:0xf bound_ctrl:1
	v_cmp_eq_u32_e32 vcc, v5, v10
	v_cndmask_b32_e64 v11, v11, v10, s[26:27]
	s_nop 0
	v_cndmask_b32_e32 v5, v5, v7, vcc
	v_cndmask_b32_e32 v7, v7, v6, vcc
	v_cndmask_b32_e32 v6, v6, v8, vcc
	v_cndmask_b32_e32 v8, v8, v4, vcc
	v_cndmask_b32_e32 v4, v4, v9, vcc
	v_cndmask_b32_e32 v9, v9, v3, vcc
	v_cndmask_b32_e32 v2, v3, v2, vcc
	v_max_u32_dpp v3, v5, v5 quad_perm:[1,0,3,2] row_mask:0xf bank_mask:0xf bound_ctrl:1
	s_nop 1
	v_max_u32_dpp v3, v3, v3 quad_perm:[2,3,0,1] row_mask:0xf bank_mask:0xf bound_ctrl:1
	s_nop 1
	v_max_u32_dpp v3, v3, v3 row_half_mirror row_mask:0xf bank_mask:0xf bound_ctrl:1
	s_nop 1
	v_max_u32_dpp v3, v3, v3 row_mirror row_mask:0xf bank_mask:0xf bound_ctrl:1
	v_cmp_eq_u32_e32 vcc, v5, v3
	v_cndmask_b32_e64 v10, v11, v3, s[28:29]
	s_nop 0
	v_cndmask_b32_e32 v3, v5, v7, vcc
	v_cndmask_b32_e32 v5, v7, v6, vcc
	v_cndmask_b32_e32 v6, v6, v8, vcc
	v_cndmask_b32_e32 v7, v8, v4, vcc
	v_max_u32_dpp v8, v3, v3 quad_perm:[1,0,3,2] row_mask:0xf bank_mask:0xf bound_ctrl:1
	v_cndmask_b32_e32 v4, v4, v9, vcc
	v_cndmask_b32_e32 v2, v9, v2, vcc
	v_max_u32_dpp v8, v8, v8 quad_perm:[2,3,0,1] row_mask:0xf bank_mask:0xf bound_ctrl:1
	s_nop 1
	v_max_u32_dpp v8, v8, v8 row_half_mirror row_mask:0xf bank_mask:0xf bound_ctrl:1
	s_nop 1
	v_max_u32_dpp v8, v8, v8 row_mirror row_mask:0xf bank_mask:0xf bound_ctrl:1
	v_cmp_eq_u32_e32 vcc, v3, v8
	v_cndmask_b32_e64 v9, v10, v8, s[30:31]
	s_nop 0
	v_cndmask_b32_e32 v3, v3, v5, vcc
	v_cndmask_b32_e32 v5, v5, v6, vcc
	v_cndmask_b32_e32 v6, v6, v7, vcc
	v_cndmask_b32_e32 v7, v7, v4, vcc
	v_cndmask_b32_e32 v2, v4, v2, vcc
	v_max_u32_dpp v4, v3, v3 quad_perm:[1,0,3,2] row_mask:0xf bank_mask:0xf bound_ctrl:1
	s_nop 1
	v_max_u32_dpp v4, v4, v4 quad_perm:[2,3,0,1] row_mask:0xf bank_mask:0xf bound_ctrl:1
	s_nop 1
	v_max_u32_dpp v4, v4, v4 row_half_mirror row_mask:0xf bank_mask:0xf bound_ctrl:1
	s_nop 1
	v_max_u32_dpp v4, v4, v4 row_mirror row_mask:0xf bank_mask:0xf bound_ctrl:1
	v_cmp_eq_u32_e32 vcc, v3, v4
	v_cndmask_b32_e64 v8, v9, v4, s[34:35]
	s_nop 0
	v_cndmask_b32_e32 v3, v3, v5, vcc
	v_cndmask_b32_e32 v4, v5, v6, vcc
	v_cndmask_b32_e32 v5, v6, v7, vcc
	v_max_u32_dpp v6, v3, v3 quad_perm:[1,0,3,2] row_mask:0xf bank_mask:0xf bound_ctrl:1
	v_cndmask_b32_e32 v2, v7, v2, vcc
	s_nop 0
	v_max_u32_dpp v6, v6, v6 quad_perm:[2,3,0,1] row_mask:0xf bank_mask:0xf bound_ctrl:1
	s_nop 1
	v_max_u32_dpp v6, v6, v6 row_half_mirror row_mask:0xf bank_mask:0xf bound_ctrl:1
	s_nop 1
	v_max_u32_dpp v6, v6, v6 row_mirror row_mask:0xf bank_mask:0xf bound_ctrl:1
	v_cmp_eq_u32_e32 vcc, v3, v6
	v_cndmask_b32_e64 v7, v8, v6, s[36:37]
	s_nop 0
	v_cndmask_b32_e32 v3, v3, v4, vcc
	v_cndmask_b32_e32 v4, v4, v5, vcc
	v_cndmask_b32_e32 v2, v5, v2, vcc
	v_max_u32_dpp v5, v3, v3 quad_perm:[1,0,3,2] row_mask:0xf bank_mask:0xf bound_ctrl:1
	s_nop 1
	v_max_u32_dpp v5, v5, v5 quad_perm:[2,3,0,1] row_mask:0xf bank_mask:0xf bound_ctrl:1
	s_nop 1
	v_max_u32_dpp v5, v5, v5 row_half_mirror row_mask:0xf bank_mask:0xf bound_ctrl:1
	s_nop 1
	v_max_u32_dpp v5, v5, v5 row_mirror row_mask:0xf bank_mask:0xf bound_ctrl:1
	v_cmp_eq_u32_e32 vcc, v3, v5
	v_cndmask_b32_e64 v6, v7, v5, s[38:39]
	s_nop 0
	v_cndmask_b32_e32 v3, v3, v4, vcc
	v_cndmask_b32_e32 v2, v4, v2, vcc
	s_nop 0
	v_max_u32_dpp v4, v3, v3 quad_perm:[1,0,3,2] row_mask:0xf bank_mask:0xf bound_ctrl:1
	s_nop 1
	v_max_u32_dpp v4, v4, v4 quad_perm:[2,3,0,1] row_mask:0xf bank_mask:0xf bound_ctrl:1
	s_nop 1
	v_max_u32_dpp v4, v4, v4 row_half_mirror row_mask:0xf bank_mask:0xf bound_ctrl:1
	s_nop 1
	v_max_u32_dpp v4, v4, v4 row_mirror row_mask:0xf bank_mask:0xf bound_ctrl:1
	v_cmp_eq_u32_e32 vcc, v3, v4
	v_cndmask_b32_e64 v5, v6, v4, s[40:41]
	s_nop 0
	v_cndmask_b32_e32 v2, v3, v2, vcc
	s_nop 1
	v_max_u32_dpp v2, v2, v2 quad_perm:[1,0,3,2] row_mask:0xf bank_mask:0xf bound_ctrl:1
	s_nop 1
	v_max_u32_dpp v2, v2, v2 quad_perm:[2,3,0,1] row_mask:0xf bank_mask:0xf bound_ctrl:1
	s_nop 1
	v_max_u32_dpp v2, v2, v2 row_half_mirror row_mask:0xf bank_mask:0xf bound_ctrl:1
	s_nop 1
	v_max_u32_dpp v2, v2, v2 row_mirror row_mask:0xf bank_mask:0xf bound_ctrl:1
	v_cndmask_b32_e64 v80, v5, v2, s[42:43]
	s_waitcnt vmcnt(0)
	v_mov_b32_e32 v14, v216
	v_mov_b32_e32 v15, v217
	v_mov_b32_e32 v16, v218
	v_mov_b32_e32 v17, v219
	v_mov_b32_e32 v10, v220
	v_mov_b32_e32 v11, v221
	v_mov_b32_e32 v12, v222
	v_mov_b32_e32 v13, v223
	v_mov_b32_e32 v6, v224
	v_mov_b32_e32 v7, v225
	v_mov_b32_e32 v8, v226
	v_mov_b32_e32 v9, v227
	v_mov_b32_e32 v2, v228
	v_mov_b32_e32 v3, v229
	v_mov_b32_e32 v4, v230
	v_mov_b32_e32 v5, v231
	ds_read_b128 v[18:21], v65 offset:36864
	ds_read_b128 v[22:25], v65 offset:36928
	s_waitcnt vmcnt(3) lgkmcnt(1)
	v_mfma_f32_16x16x32_bf16 v[18:21], v[14:17], v[18:21], 0
	ds_read_b128 v[26:29], v65 offset:41536
	ds_read_b128 v[30:33], v65 offset:46144
	ds_read_b128 v[34:37], v65 offset:50752
	s_waitcnt vmcnt(2) lgkmcnt(3)
	v_mfma_f32_16x16x32_bf16 v[18:21], v[10:13], v[22:25], v[18:21]
	ds_read_b128 v[22:25], v65 offset:36992
	ds_read_b128 v[38:41], v65 offset:55360
	ds_read_b128 v[42:45], v65 offset:59968
	s_waitcnt vmcnt(1) lgkmcnt(2)
	v_mfma_f32_16x16x32_bf16 v[18:21], v[6:9], v[22:25], v[18:21]
	ds_read_b128 v[22:25], v65 offset:37056
	ds_read_b128 v[84:87], v65 offset:64576
	s_waitcnt vmcnt(0) lgkmcnt(1)
	v_mfma_f32_16x16x32_bf16 v[18:21], v[2:5], v[22:25], v[18:21]
	ds_read_b128 v[22:25], v65 offset:41472
	s_waitcnt lgkmcnt(0)
	v_mfma_f32_16x16x32_bf16 v[22:25], v[14:17], v[22:25], 0
	v_mfma_f32_16x16x32_bf16 v[22:25], v[10:13], v[26:29], v[22:25]
	ds_read_b128 v[26:29], v65 offset:41600
	s_waitcnt lgkmcnt(0)
	v_mfma_f32_16x16x32_bf16 v[22:25], v[6:9], v[26:29], v[22:25]
	ds_read_b128 v[26:29], v65 offset:41664
	s_waitcnt lgkmcnt(0)
	v_mfma_f32_16x16x32_bf16 v[22:25], v[2:5], v[26:29], v[22:25]
	ds_read_b128 v[26:29], v65 offset:46080
	s_waitcnt lgkmcnt(0)
	v_mfma_f32_16x16x32_bf16 v[26:29], v[14:17], v[26:29], 0
	v_mfma_f32_16x16x32_bf16 v[26:29], v[10:13], v[30:33], v[26:29]
	ds_read_b128 v[30:33], v65 offset:46208
	s_waitcnt lgkmcnt(0)
	v_mfma_f32_16x16x32_bf16 v[26:29], v[6:9], v[30:33], v[26:29]
	ds_read_b128 v[30:33], v65 offset:46272
	s_waitcnt lgkmcnt(0)
	v_mfma_f32_16x16x32_bf16 v[26:29], v[2:5], v[30:33], v[26:29]
	ds_read_b128 v[30:33], v65 offset:50688
	s_waitcnt lgkmcnt(0)
	v_mfma_f32_16x16x32_bf16 v[30:33], v[14:17], v[30:33], 0
	v_mfma_f32_16x16x32_bf16 v[30:33], v[10:13], v[34:37], v[30:33]
	ds_read_b128 v[34:37], v65 offset:50816
	s_waitcnt lgkmcnt(0)
	v_mfma_f32_16x16x32_bf16 v[30:33], v[6:9], v[34:37], v[30:33]
	ds_read_b128 v[34:37], v65 offset:50880
	s_waitcnt lgkmcnt(0)
	v_mfma_f32_16x16x32_bf16 v[30:33], v[2:5], v[34:37], v[30:33]
	ds_read_b128 v[34:37], v65 offset:55296
	s_waitcnt lgkmcnt(0)
	v_mfma_f32_16x16x32_bf16 v[34:37], v[14:17], v[34:37], 0
	v_mfma_f32_16x16x32_bf16 v[34:37], v[10:13], v[38:41], v[34:37]
	ds_read_b128 v[38:41], v65 offset:55424
	s_waitcnt lgkmcnt(0)
	v_mfma_f32_16x16x32_bf16 v[34:37], v[6:9], v[38:41], v[34:37]
	ds_read_b128 v[38:41], v65 offset:55488
	s_waitcnt lgkmcnt(0)
	v_mfma_f32_16x16x32_bf16 v[34:37], v[2:5], v[38:41], v[34:37]
	ds_read_b128 v[38:41], v65 offset:59904
	s_waitcnt lgkmcnt(0)
	v_mfma_f32_16x16x32_bf16 v[38:41], v[14:17], v[38:41], 0
	v_mfma_f32_16x16x32_bf16 v[38:41], v[10:13], v[42:45], v[38:41]
	ds_read_b128 v[42:45], v65 offset:60032
	s_waitcnt lgkmcnt(0)
	v_mfma_f32_16x16x32_bf16 v[38:41], v[6:9], v[42:45], v[38:41]
	ds_read_b128 v[42:45], v65 offset:60096
	s_waitcnt lgkmcnt(0)
	v_mfma_f32_16x16x32_bf16 v[38:41], v[2:5], v[42:45], v[38:41]
	ds_read_b128 v[42:45], v65 offset:64512
	s_waitcnt lgkmcnt(0)
	v_mfma_f32_16x16x32_bf16 v[42:45], v[14:17], v[42:45], 0
	v_mfma_f32_16x16x32_bf16 v[42:45], v[10:13], v[84:87], v[42:45]
	ds_read_b128 v[84:87], v65 offset:64640
	s_waitcnt lgkmcnt(0)
	v_mfma_f32_16x16x32_bf16 v[42:45], v[6:9], v[84:87], v[42:45]
	ds_read_b128 v[84:87], v65 offset:64704
	s_waitcnt lgkmcnt(0)
	v_mfma_f32_16x16x32_bf16 v[42:45], v[2:5], v[84:87], v[42:45]
	ds_read_b128 v[84:87], v73
	s_waitcnt lgkmcnt(0)
	v_mfma_f32_16x16x32_bf16 v[14:17], v[14:17], v[84:87], 0
	ds_read_b128 v[84:87], v74
	s_waitcnt lgkmcnt(0)
	v_mfma_f32_16x16x32_bf16 v[10:13], v[10:13], v[84:87], v[14:17]
	s_nop 4
	ds_read_b128 v[14:17], v75
	s_waitcnt lgkmcnt(0)
	v_mfma_f32_16x16x32_bf16 v[6:9], v[6:9], v[14:17], v[10:13]
	s_nop 2
	ds_read_b128 v[10:13], v76
	s_waitcnt lgkmcnt(0)
	v_mfma_f32_16x16x32_bf16 v[2:5], v[2:5], v[10:13], v[6:9]
	v_ashrrev_i32_e32 v10, 31, v34
	s_nop 1
	v_ashrrev_i32_e32 v6, 31, v18
	v_ashrrev_i32_e32 v7, 31, v22
	v_ashrrev_i32_e32 v8, 31, v26
	v_ashrrev_i32_e32 v9, 31, v30
	v_ashrrev_i32_e32 v11, 31, v38
	v_ashrrev_i32_e32 v12, 31, v42
	v_ashrrev_i32_e32 v13, 31, v2
	v_bitop3_b32 v6, v6, v18, s70 bitop3:0x36
	v_bitop3_b32 v7, v7, v22, s70 bitop3:0x36
	v_bitop3_b32 v8, v8, v26, s70 bitop3:0x36
	v_bitop3_b32 v9, v9, v30, s70 bitop3:0x36
	v_bitop3_b32 v10, v10, v34, s70 bitop3:0x36
	v_bitop3_b32 v11, v11, v38, s70 bitop3:0x36
	v_bitop3_b32 v12, v12, v42, s70 bitop3:0x36
	v_bitop3_b32 v2, v13, v2, s70 bitop3:0x36
	v_and_or_b32 v6, v6, s71, v61
	v_and_or_b32 v7, v7, s71, v66
	v_and_or_b32 v8, v8, s71, v67
	v_and_or_b32 v9, v9, s71, v68
	v_and_or_b32 v10, v10, s71, v69
	v_and_or_b32 v11, v11, s71, v70
	v_and_or_b32 v12, v12, s71, v71
	v_and_or_b32 v2, v2, s71, v72
	v_max_u32_e32 v13, v6, v7
	v_min_u32_e32 v6, v6, v7
	v_max_u32_e32 v7, v8, v9
	v_min_u32_e32 v8, v8, v9
	v_max_u32_e32 v9, v10, v11
	v_min_u32_e32 v10, v10, v11
	v_max_u32_e32 v11, v12, v2
	v_min_u32_e32 v2, v12, v2
	v_max_u32_e32 v12, v13, v7
	v_min_u32_e32 v7, v13, v7
	v_max_u32_e32 v13, v6, v8
	v_min_u32_e32 v6, v6, v8
	v_max_u32_e32 v8, v9, v11
	v_min_u32_e32 v9, v9, v11
	v_max_u32_e32 v11, v10, v2
	v_min_u32_e32 v2, v10, v2
	v_max_u32_e32 v10, v13, v7
	v_min_u32_e32 v7, v13, v7
	v_max_u32_e32 v13, v11, v9
	v_min_u32_e32 v9, v11, v9
	v_max_u32_e32 v11, v12, v8
	v_min_u32_e32 v8, v12, v8
	v_max_u32_e32 v12, v10, v13
	v_min_u32_e32 v10, v10, v13
	v_max_u32_e32 v13, v7, v9
	v_min_u32_e32 v7, v7, v9
	v_max_u32_e32 v9, v6, v2
	v_min_u32_e32 v2, v6, v2
	v_max_u32_e32 v6, v13, v8
	v_min_u32_e32 v8, v13, v8
	v_max_u32_e32 v13, v9, v10
	v_min_u32_e32 v9, v9, v10
	v_max_u32_e32 v10, v12, v6
	v_min_u32_e32 v6, v12, v6
	v_max_u32_e32 v12, v13, v8
	v_min_u32_e32 v8, v13, v8
	v_max_u32_e32 v13, v9, v7
	v_min_u32_e32 v7, v9, v7
	v_max_u32_dpp v9, v11, v11 quad_perm:[1,0,3,2] row_mask:0xf bank_mask:0xf bound_ctrl:1
	s_nop 1
	v_max_u32_dpp v9, v9, v9 quad_perm:[2,3,0,1] row_mask:0xf bank_mask:0xf bound_ctrl:1
	s_nop 1
	v_max_u32_dpp v9, v9, v9 row_half_mirror row_mask:0xf bank_mask:0xf bound_ctrl:1
	s_nop 1
	v_max_u32_dpp v9, v9, v9 row_mirror row_mask:0xf bank_mask:0xf bound_ctrl:1
	v_cmp_eq_u32_e32 vcc, v11, v9
	v_cndmask_b32_e64 v14, 0, v9, s[10:11]
	s_nop 0
	v_cndmask_b32_e32 v9, v11, v10, vcc
	v_cndmask_b32_e32 v10, v10, v6, vcc
	v_cndmask_b32_e32 v6, v6, v12, vcc
	v_cndmask_b32_e32 v11, v12, v8, vcc
	v_cndmask_b32_e32 v8, v8, v13, vcc
	v_cndmask_b32_e32 v12, v13, v7, vcc
	v_max_u32_dpp v13, v9, v9 quad_perm:[1,0,3,2] row_mask:0xf bank_mask:0xf bound_ctrl:1
	v_cndmask_b32_e32 v7, v7, v2, vcc
	v_cndmask_b32_e64 v2, v2, 0, vcc
	v_max_u32_dpp v13, v13, v13 quad_perm:[2,3,0,1] row_mask:0xf bank_mask:0xf bound_ctrl:1
	s_nop 1
	v_max_u32_dpp v13, v13, v13 row_half_mirror row_mask:0xf bank_mask:0xf bound_ctrl:1
	s_nop 1
	v_max_u32_dpp v13, v13, v13 row_mirror row_mask:0xf bank_mask:0xf bound_ctrl:1
	v_cmp_eq_u32_e32 vcc, v9, v13
	v_cndmask_b32_e64 v14, v14, v13, s[12:13]
	s_nop 0
	v_cndmask_b32_e32 v9, v9, v10, vcc
	v_cndmask_b32_e32 v10, v10, v6, vcc
	v_cndmask_b32_e32 v6, v6, v11, vcc
	v_max_u32_dpp v13, v9, v9 quad_perm:[1,0,3,2] row_mask:0xf bank_mask:0xf bound_ctrl:1
	v_cndmask_b32_e32 v11, v11, v8, vcc
	v_cndmask_b32_e32 v8, v8, v12, vcc
	v_max_u32_dpp v13, v13, v13 quad_perm:[2,3,0,1] row_mask:0xf bank_mask:0xf bound_ctrl:1
	v_cndmask_b32_e32 v12, v12, v7, vcc
	v_cndmask_b32_e32 v7, v7, v2, vcc
	v_max_u32_dpp v13, v13, v13 row_half_mirror row_mask:0xf bank_mask:0xf bound_ctrl:1
	v_cndmask_b32_e64 v2, v2, 0, vcc
	s_nop 0
	v_max_u32_dpp v13, v13, v13 row_mirror row_mask:0xf bank_mask:0xf bound_ctrl:1
	v_cmp_eq_u32_e32 vcc, v9, v13
	v_cndmask_b32_e64 v14, v14, v13, s[14:15]
	s_nop 0
	v_cndmask_b32_e32 v9, v9, v10, vcc
	v_cndmask_b32_e32 v10, v10, v6, vcc
	v_cndmask_b32_e32 v6, v6, v11, vcc
	v_max_u32_dpp v13, v9, v9 quad_perm:[1,0,3,2] row_mask:0xf bank_mask:0xf bound_ctrl:1
	v_cndmask_b32_e32 v11, v11, v8, vcc
	v_cndmask_b32_e32 v8, v8, v12, vcc
	v_max_u32_dpp v13, v13, v13 quad_perm:[2,3,0,1] row_mask:0xf bank_mask:0xf bound_ctrl:1
	v_cndmask_b32_e32 v12, v12, v7, vcc
	v_cndmask_b32_e32 v7, v7, v2, vcc
	v_max_u32_dpp v13, v13, v13 row_half_mirror row_mask:0xf bank_mask:0xf bound_ctrl:1
	v_cndmask_b32_e64 v2, v2, 0, vcc
	s_nop 0
	v_max_u32_dpp v13, v13, v13 row_mirror row_mask:0xf bank_mask:0xf bound_ctrl:1
	v_cmp_eq_u32_e32 vcc, v9, v13
	v_cndmask_b32_e64 v14, v14, v13, s[16:17]
	s_nop 0
	v_cndmask_b32_e32 v9, v9, v10, vcc
	v_cndmask_b32_e32 v10, v10, v6, vcc
	v_cndmask_b32_e32 v6, v6, v11, vcc
	v_max_u32_dpp v13, v9, v9 quad_perm:[1,0,3,2] row_mask:0xf bank_mask:0xf bound_ctrl:1
	v_cndmask_b32_e32 v11, v11, v8, vcc
	v_cndmask_b32_e32 v8, v8, v12, vcc
	v_max_u32_dpp v13, v13, v13 quad_perm:[2,3,0,1] row_mask:0xf bank_mask:0xf bound_ctrl:1
	v_cndmask_b32_e32 v12, v12, v7, vcc
	v_cndmask_b32_e32 v7, v7, v2, vcc
	v_max_u32_dpp v13, v13, v13 row_half_mirror row_mask:0xf bank_mask:0xf bound_ctrl:1
	v_cndmask_b32_e64 v2, v2, 0, vcc
	s_nop 0
	v_max_u32_dpp v13, v13, v13 row_mirror row_mask:0xf bank_mask:0xf bound_ctrl:1
	v_cmp_eq_u32_e32 vcc, v9, v13
	v_cndmask_b32_e64 v14, v14, v13, s[18:19]
	s_nop 0
	v_cndmask_b32_e32 v9, v9, v10, vcc
	v_cndmask_b32_e32 v10, v10, v6, vcc
	v_cndmask_b32_e32 v6, v6, v11, vcc
	v_max_u32_dpp v13, v9, v9 quad_perm:[1,0,3,2] row_mask:0xf bank_mask:0xf bound_ctrl:1
	v_cndmask_b32_e32 v11, v11, v8, vcc
	v_cndmask_b32_e32 v8, v8, v12, vcc
	v_max_u32_dpp v13, v13, v13 quad_perm:[2,3,0,1] row_mask:0xf bank_mask:0xf bound_ctrl:1
	v_cndmask_b32_e32 v12, v12, v7, vcc
	v_cndmask_b32_e32 v7, v7, v2, vcc
	v_max_u32_dpp v13, v13, v13 row_half_mirror row_mask:0xf bank_mask:0xf bound_ctrl:1
	v_cndmask_b32_e64 v2, v2, 0, vcc
	s_nop 0
	v_max_u32_dpp v13, v13, v13 row_mirror row_mask:0xf bank_mask:0xf bound_ctrl:1
	v_cmp_eq_u32_e32 vcc, v9, v13
	v_cndmask_b32_e64 v14, v14, v13, s[20:21]
	s_nop 0
	v_cndmask_b32_e32 v9, v9, v10, vcc
	v_cndmask_b32_e32 v10, v10, v6, vcc
	v_cndmask_b32_e32 v6, v6, v11, vcc
	v_max_u32_dpp v13, v9, v9 quad_perm:[1,0,3,2] row_mask:0xf bank_mask:0xf bound_ctrl:1
	v_cndmask_b32_e32 v11, v11, v8, vcc
	v_cndmask_b32_e32 v8, v8, v12, vcc
	v_max_u32_dpp v13, v13, v13 quad_perm:[2,3,0,1] row_mask:0xf bank_mask:0xf bound_ctrl:1
	v_cndmask_b32_e32 v12, v12, v7, vcc
	v_cndmask_b32_e32 v7, v7, v2, vcc
	v_max_u32_dpp v13, v13, v13 row_half_mirror row_mask:0xf bank_mask:0xf bound_ctrl:1
	v_cndmask_b32_e64 v2, v2, 0, vcc
	s_nop 0
	v_max_u32_dpp v13, v13, v13 row_mirror row_mask:0xf bank_mask:0xf bound_ctrl:1
	v_cmp_eq_u32_e32 vcc, v9, v13
	v_cndmask_b32_e64 v14, v14, v13, s[22:23]
	s_nop 0
	v_cndmask_b32_e32 v9, v9, v10, vcc
	v_cndmask_b32_e32 v10, v10, v6, vcc
	v_cndmask_b32_e32 v6, v6, v11, vcc
	v_max_u32_dpp v13, v9, v9 quad_perm:[1,0,3,2] row_mask:0xf bank_mask:0xf bound_ctrl:1
	v_cndmask_b32_e32 v11, v11, v8, vcc
	v_cndmask_b32_e32 v8, v8, v12, vcc
	v_max_u32_dpp v13, v13, v13 quad_perm:[2,3,0,1] row_mask:0xf bank_mask:0xf bound_ctrl:1
	v_cndmask_b32_e32 v12, v12, v7, vcc
	v_cndmask_b32_e32 v7, v7, v2, vcc
	v_max_u32_dpp v13, v13, v13 row_half_mirror row_mask:0xf bank_mask:0xf bound_ctrl:1
	v_cndmask_b32_e64 v2, v2, 0, vcc
	s_nop 0
	v_max_u32_dpp v13, v13, v13 row_mirror row_mask:0xf bank_mask:0xf bound_ctrl:1
	v_cmp_eq_u32_e32 vcc, v9, v13
	v_cndmask_b32_e64 v14, v14, v13, s[24:25]
	s_nop 0
	v_cndmask_b32_e32 v9, v9, v10, vcc
	v_cndmask_b32_e32 v10, v10, v6, vcc
	v_cndmask_b32_e32 v6, v6, v11, vcc
	v_max_u32_dpp v13, v9, v9 quad_perm:[1,0,3,2] row_mask:0xf bank_mask:0xf bound_ctrl:1
	v_cndmask_b32_e32 v11, v11, v8, vcc
	v_cndmask_b32_e32 v8, v8, v12, vcc
	v_max_u32_dpp v13, v13, v13 quad_perm:[2,3,0,1] row_mask:0xf bank_mask:0xf bound_ctrl:1
	v_cndmask_b32_e32 v12, v12, v7, vcc
	v_cndmask_b32_e32 v7, v7, v2, vcc
	v_max_u32_dpp v13, v13, v13 row_half_mirror row_mask:0xf bank_mask:0xf bound_ctrl:1
	v_cndmask_b32_e64 v2, v2, 0, vcc
	s_nop 0
	v_max_u32_dpp v13, v13, v13 row_mirror row_mask:0xf bank_mask:0xf bound_ctrl:1
	v_cmp_eq_u32_e32 vcc, v9, v13
	v_cndmask_b32_e64 v14, v14, v13, s[26:27]
	s_nop 0
	v_cndmask_b32_e32 v9, v9, v10, vcc
	v_cndmask_b32_e32 v10, v10, v6, vcc
	v_cndmask_b32_e32 v6, v6, v11, vcc
	v_cndmask_b32_e32 v11, v11, v8, vcc
	v_cndmask_b32_e32 v8, v8, v12, vcc
	v_cndmask_b32_e32 v12, v12, v7, vcc
	v_cndmask_b32_e32 v2, v7, v2, vcc
	v_max_u32_dpp v7, v9, v9 quad_perm:[1,0,3,2] row_mask:0xf bank_mask:0xf bound_ctrl:1
	s_nop 1
	v_max_u32_dpp v7, v7, v7 quad_perm:[2,3,0,1] row_mask:0xf bank_mask:0xf bound_ctrl:1
	s_nop 1
	v_max_u32_dpp v7, v7, v7 row_half_mirror row_mask:0xf bank_mask:0xf bound_ctrl:1
	s_nop 1
	v_max_u32_dpp v7, v7, v7 row_mirror row_mask:0xf bank_mask:0xf bound_ctrl:1
	v_cmp_eq_u32_e32 vcc, v9, v7
	v_cndmask_b32_e64 v13, v14, v7, s[28:29]
	s_nop 0
	v_cndmask_b32_e32 v7, v9, v10, vcc
	v_cndmask_b32_e32 v9, v10, v6, vcc
	v_cndmask_b32_e32 v6, v6, v11, vcc
	v_cndmask_b32_e32 v10, v11, v8, vcc
	v_max_u32_dpp v11, v7, v7 quad_perm:[1,0,3,2] row_mask:0xf bank_mask:0xf bound_ctrl:1
	v_cndmask_b32_e32 v8, v8, v12, vcc
	v_cndmask_b32_e32 v2, v12, v2, vcc
	v_max_u32_dpp v11, v11, v11 quad_perm:[2,3,0,1] row_mask:0xf bank_mask:0xf bound_ctrl:1
	s_nop 1
	v_max_u32_dpp v11, v11, v11 row_half_mirror row_mask:0xf bank_mask:0xf bound_ctrl:1
	s_nop 1
	v_max_u32_dpp v11, v11, v11 row_mirror row_mask:0xf bank_mask:0xf bound_ctrl:1
	v_cmp_eq_u32_e32 vcc, v7, v11
	v_cndmask_b32_e64 v12, v13, v11, s[30:31]
	v_ashrrev_i32_e32 v13, 31, v3
	v_cndmask_b32_e32 v7, v7, v9, vcc
	v_cndmask_b32_e32 v9, v9, v6, vcc
	v_cndmask_b32_e32 v6, v6, v10, vcc
	v_cndmask_b32_e32 v10, v10, v8, vcc
	v_cndmask_b32_e32 v2, v8, v2, vcc
	v_max_u32_dpp v8, v7, v7 quad_perm:[1,0,3,2] row_mask:0xf bank_mask:0xf bound_ctrl:1
	v_bitop3_b32 v3, v13, v3, s70 bitop3:0x36
	v_and_or_b32 v3, v3, s71, v72
	v_max_u32_dpp v8, v8, v8 quad_perm:[2,3,0,1] row_mask:0xf bank_mask:0xf bound_ctrl:1
	s_nop 1
	v_max_u32_dpp v8, v8, v8 row_half_mirror row_mask:0xf bank_mask:0xf bound_ctrl:1
	s_nop 1
	v_max_u32_dpp v8, v8, v8 row_mirror row_mask:0xf bank_mask:0xf bound_ctrl:1
	v_cmp_eq_u32_e32 vcc, v7, v8
	v_cndmask_b32_e64 v11, v12, v8, s[34:35]
	v_ashrrev_i32_e32 v12, 31, v43
	v_cndmask_b32_e32 v7, v7, v9, vcc
	v_cndmask_b32_e32 v8, v9, v6, vcc
	v_cndmask_b32_e32 v6, v6, v10, vcc
	v_max_u32_dpp v9, v7, v7 quad_perm:[1,0,3,2] row_mask:0xf bank_mask:0xf bound_ctrl:1
	v_cndmask_b32_e32 v2, v10, v2, vcc
	v_bitop3_b32 v12, v12, v43, s70 bitop3:0x36
	v_max_u32_dpp v9, v9, v9 quad_perm:[2,3,0,1] row_mask:0xf bank_mask:0xf bound_ctrl:1
	v_and_or_b32 v12, v12, s71, v71
	s_nop 0
	v_max_u32_dpp v9, v9, v9 row_half_mirror row_mask:0xf bank_mask:0xf bound_ctrl:1
	s_nop 1
	v_max_u32_dpp v9, v9, v9 row_mirror row_mask:0xf bank_mask:0xf bound_ctrl:1
	v_cmp_eq_u32_e32 vcc, v7, v9
	v_cndmask_b32_e64 v10, v11, v9, s[36:37]
	v_ashrrev_i32_e32 v11, 31, v39
	v_cndmask_b32_e32 v7, v7, v8, vcc
	v_cndmask_b32_e32 v8, v8, v6, vcc
	v_cndmask_b32_e32 v2, v6, v2, vcc
	v_max_u32_dpp v6, v7, v7 quad_perm:[1,0,3,2] row_mask:0xf bank_mask:0xf bound_ctrl:1
	v_bitop3_b32 v11, v11, v39, s70 bitop3:0x36
	v_and_or_b32 v11, v11, s71, v70
	v_max_u32_dpp v6, v6, v6 quad_perm:[2,3,0,1] row_mask:0xf bank_mask:0xf bound_ctrl:1
	s_nop 1
	v_max_u32_dpp v6, v6, v6 row_half_mirror row_mask:0xf bank_mask:0xf bound_ctrl:1
	s_nop 1
	v_max_u32_dpp v6, v6, v6 row_mirror row_mask:0xf bank_mask:0xf bound_ctrl:1
	v_cmp_eq_u32_e32 vcc, v7, v6
	v_cndmask_b32_e64 v9, v10, v6, s[38:39]
	v_ashrrev_i32_e32 v10, 31, v35
	v_cndmask_b32_e32 v6, v7, v8, vcc
	v_cndmask_b32_e32 v2, v8, v2, vcc
	v_bitop3_b32 v10, v10, v35, s70 bitop3:0x36
	v_max_u32_dpp v7, v6, v6 quad_perm:[1,0,3,2] row_mask:0xf bank_mask:0xf bound_ctrl:1
	v_and_or_b32 v10, v10, s71, v69
	s_nop 0
	v_max_u32_dpp v7, v7, v7 quad_perm:[2,3,0,1] row_mask:0xf bank_mask:0xf bound_ctrl:1
	s_nop 1
	v_max_u32_dpp v7, v7, v7 row_half_mirror row_mask:0xf bank_mask:0xf bound_ctrl:1
	s_nop 1
	v_max_u32_dpp v7, v7, v7 row_mirror row_mask:0xf bank_mask:0xf bound_ctrl:1
	v_cmp_eq_u32_e32 vcc, v6, v7
	v_cndmask_b32_e64 v8, v9, v7, s[40:41]
	v_ashrrev_i32_e32 v7, 31, v27
	v_cndmask_b32_e32 v2, v6, v2, vcc
	v_ashrrev_i32_e32 v6, 31, v23
	v_ashrrev_i32_e32 v9, 31, v31
	v_max_u32_dpp v2, v2, v2 quad_perm:[1,0,3,2] row_mask:0xf bank_mask:0xf bound_ctrl:1
	v_bitop3_b32 v6, v6, v23, s70 bitop3:0x36
	v_bitop3_b32 v7, v7, v27, s70 bitop3:0x36
	v_max_u32_dpp v2, v2, v2 quad_perm:[2,3,0,1] row_mask:0xf bank_mask:0xf bound_ctrl:1
	v_bitop3_b32 v9, v9, v31, s70 bitop3:0x36
	v_and_or_b32 v6, v6, s71, v66
	v_max_u32_dpp v2, v2, v2 row_half_mirror row_mask:0xf bank_mask:0xf bound_ctrl:1
	v_and_or_b32 v7, v7, s71, v67
	v_and_or_b32 v9, v9, s71, v68
	v_max_u32_dpp v2, v2, v2 row_mirror row_mask:0xf bank_mask:0xf bound_ctrl:1
	v_cndmask_b32_e64 v8, v8, v2, s[42:43]
	v_ashrrev_i32_e32 v2, 31, v19
	v_bitop3_b32 v2, v2, v19, s70 bitop3:0x36
	v_and_or_b32 v2, v2, s71, v61
	v_max_u32_e32 v13, v2, v6
	v_min_u32_e32 v2, v2, v6
	v_max_u32_e32 v6, v7, v9
	v_min_u32_e32 v7, v7, v9
	v_max_u32_e32 v9, v10, v11
	v_min_u32_e32 v10, v10, v11
	v_max_u32_e32 v11, v12, v3
	v_min_u32_e32 v3, v12, v3
	v_max_u32_e32 v12, v13, v6
	v_min_u32_e32 v6, v13, v6
	v_max_u32_e32 v13, v2, v7
	v_min_u32_e32 v2, v2, v7
	v_max_u32_e32 v7, v9, v11
	v_min_u32_e32 v9, v9, v11
	v_max_u32_e32 v11, v10, v3
	v_min_u32_e32 v3, v10, v3
	v_max_u32_e32 v10, v13, v6
	v_min_u32_e32 v6, v13, v6
	v_max_u32_e32 v13, v11, v9
	v_min_u32_e32 v9, v11, v9
	v_max_u32_e32 v11, v12, v7
	v_min_u32_e32 v7, v12, v7
	v_max_u32_e32 v12, v10, v13
	v_min_u32_e32 v10, v10, v13
	v_max_u32_e32 v13, v6, v9
	v_min_u32_e32 v6, v6, v9
	v_max_u32_e32 v9, v2, v3
	v_min_u32_e32 v2, v2, v3
	v_max_u32_e32 v3, v13, v7
	v_min_u32_e32 v7, v13, v7
	v_max_u32_e32 v13, v9, v10
	v_min_u32_e32 v9, v9, v10
	v_max_u32_e32 v10, v12, v3
	v_min_u32_e32 v3, v12, v3
	v_max_u32_e32 v12, v13, v7
	v_min_u32_e32 v7, v13, v7
	v_max_u32_e32 v13, v9, v6
	v_min_u32_e32 v6, v9, v6
	v_max_u32_dpp v9, v11, v11 quad_perm:[1,0,3,2] row_mask:0xf bank_mask:0xf bound_ctrl:1
	s_nop 1
	v_max_u32_dpp v9, v9, v9 quad_perm:[2,3,0,1] row_mask:0xf bank_mask:0xf bound_ctrl:1
	s_nop 1
	v_max_u32_dpp v9, v9, v9 row_half_mirror row_mask:0xf bank_mask:0xf bound_ctrl:1
	s_nop 1
	v_max_u32_dpp v9, v9, v9 row_mirror row_mask:0xf bank_mask:0xf bound_ctrl:1
	v_cmp_eq_u32_e32 vcc, v11, v9
	v_cndmask_b32_e64 v14, 0, v9, s[10:11]
	s_nop 0
	v_cndmask_b32_e32 v9, v11, v10, vcc
	v_cndmask_b32_e32 v10, v10, v3, vcc
	v_cndmask_b32_e32 v3, v3, v12, vcc
	v_cndmask_b32_e32 v11, v12, v7, vcc
	v_cndmask_b32_e32 v7, v7, v13, vcc
	v_cndmask_b32_e32 v12, v13, v6, vcc
	v_max_u32_dpp v13, v9, v9 quad_perm:[1,0,3,2] row_mask:0xf bank_mask:0xf bound_ctrl:1
	v_cndmask_b32_e32 v6, v6, v2, vcc
	v_cndmask_b32_e64 v2, v2, 0, vcc
	v_max_u32_dpp v13, v13, v13 quad_perm:[2,3,0,1] row_mask:0xf bank_mask:0xf bound_ctrl:1
	s_nop 1
	v_max_u32_dpp v13, v13, v13 row_half_mirror row_mask:0xf bank_mask:0xf bound_ctrl:1
	s_nop 1
	v_max_u32_dpp v13, v13, v13 row_mirror row_mask:0xf bank_mask:0xf bound_ctrl:1
	v_cmp_eq_u32_e32 vcc, v9, v13
	v_cndmask_b32_e64 v14, v14, v13, s[12:13]
	s_nop 0
	v_cndmask_b32_e32 v9, v9, v10, vcc
	v_cndmask_b32_e32 v10, v10, v3, vcc
	v_cndmask_b32_e32 v3, v3, v11, vcc
	v_max_u32_dpp v13, v9, v9 quad_perm:[1,0,3,2] row_mask:0xf bank_mask:0xf bound_ctrl:1
	v_cndmask_b32_e32 v11, v11, v7, vcc
	v_cndmask_b32_e32 v7, v7, v12, vcc
	v_max_u32_dpp v13, v13, v13 quad_perm:[2,3,0,1] row_mask:0xf bank_mask:0xf bound_ctrl:1
	v_cndmask_b32_e32 v12, v12, v6, vcc
	v_cndmask_b32_e32 v6, v6, v2, vcc
	v_max_u32_dpp v13, v13, v13 row_half_mirror row_mask:0xf bank_mask:0xf bound_ctrl:1
	v_cndmask_b32_e64 v2, v2, 0, vcc
	s_nop 0
	v_max_u32_dpp v13, v13, v13 row_mirror row_mask:0xf bank_mask:0xf bound_ctrl:1
	v_cmp_eq_u32_e32 vcc, v9, v13
	v_cndmask_b32_e64 v14, v14, v13, s[14:15]
	s_nop 0
	v_cndmask_b32_e32 v9, v9, v10, vcc
	v_cndmask_b32_e32 v10, v10, v3, vcc
	v_cndmask_b32_e32 v3, v3, v11, vcc
	v_max_u32_dpp v13, v9, v9 quad_perm:[1,0,3,2] row_mask:0xf bank_mask:0xf bound_ctrl:1
	v_cndmask_b32_e32 v11, v11, v7, vcc
	v_cndmask_b32_e32 v7, v7, v12, vcc
	v_max_u32_dpp v13, v13, v13 quad_perm:[2,3,0,1] row_mask:0xf bank_mask:0xf bound_ctrl:1
	v_cndmask_b32_e32 v12, v12, v6, vcc
	v_cndmask_b32_e32 v6, v6, v2, vcc
	v_max_u32_dpp v13, v13, v13 row_half_mirror row_mask:0xf bank_mask:0xf bound_ctrl:1
	v_cndmask_b32_e64 v2, v2, 0, vcc
	s_nop 0
	v_max_u32_dpp v13, v13, v13 row_mirror row_mask:0xf bank_mask:0xf bound_ctrl:1
	v_cmp_eq_u32_e32 vcc, v9, v13
	v_cndmask_b32_e64 v14, v14, v13, s[16:17]
	s_nop 0
	v_cndmask_b32_e32 v9, v9, v10, vcc
	v_cndmask_b32_e32 v10, v10, v3, vcc
	v_cndmask_b32_e32 v3, v3, v11, vcc
	v_max_u32_dpp v13, v9, v9 quad_perm:[1,0,3,2] row_mask:0xf bank_mask:0xf bound_ctrl:1
	v_cndmask_b32_e32 v11, v11, v7, vcc
	v_cndmask_b32_e32 v7, v7, v12, vcc
	v_max_u32_dpp v13, v13, v13 quad_perm:[2,3,0,1] row_mask:0xf bank_mask:0xf bound_ctrl:1
	v_cndmask_b32_e32 v12, v12, v6, vcc
	v_cndmask_b32_e32 v6, v6, v2, vcc
	v_max_u32_dpp v13, v13, v13 row_half_mirror row_mask:0xf bank_mask:0xf bound_ctrl:1
	v_cndmask_b32_e64 v2, v2, 0, vcc
	s_nop 0
	v_max_u32_dpp v13, v13, v13 row_mirror row_mask:0xf bank_mask:0xf bound_ctrl:1
	v_cmp_eq_u32_e32 vcc, v9, v13
	v_cndmask_b32_e64 v14, v14, v13, s[18:19]
	s_nop 0
	v_cndmask_b32_e32 v9, v9, v10, vcc
	v_cndmask_b32_e32 v10, v10, v3, vcc
	v_cndmask_b32_e32 v3, v3, v11, vcc
	v_max_u32_dpp v13, v9, v9 quad_perm:[1,0,3,2] row_mask:0xf bank_mask:0xf bound_ctrl:1
	v_cndmask_b32_e32 v11, v11, v7, vcc
	v_cndmask_b32_e32 v7, v7, v12, vcc
	v_max_u32_dpp v13, v13, v13 quad_perm:[2,3,0,1] row_mask:0xf bank_mask:0xf bound_ctrl:1
	v_cndmask_b32_e32 v12, v12, v6, vcc
	v_cndmask_b32_e32 v6, v6, v2, vcc
	v_max_u32_dpp v13, v13, v13 row_half_mirror row_mask:0xf bank_mask:0xf bound_ctrl:1
	v_cndmask_b32_e64 v2, v2, 0, vcc
	s_nop 0
	v_max_u32_dpp v13, v13, v13 row_mirror row_mask:0xf bank_mask:0xf bound_ctrl:1
	v_cmp_eq_u32_e32 vcc, v9, v13
	v_cndmask_b32_e64 v14, v14, v13, s[20:21]
	s_nop 0
	v_cndmask_b32_e32 v9, v9, v10, vcc
	v_cndmask_b32_e32 v10, v10, v3, vcc
	v_cndmask_b32_e32 v3, v3, v11, vcc
	v_max_u32_dpp v13, v9, v9 quad_perm:[1,0,3,2] row_mask:0xf bank_mask:0xf bound_ctrl:1
	v_cndmask_b32_e32 v11, v11, v7, vcc
	v_cndmask_b32_e32 v7, v7, v12, vcc
	v_max_u32_dpp v13, v13, v13 quad_perm:[2,3,0,1] row_mask:0xf bank_mask:0xf bound_ctrl:1
	v_cndmask_b32_e32 v12, v12, v6, vcc
	v_cndmask_b32_e32 v6, v6, v2, vcc
	v_max_u32_dpp v13, v13, v13 row_half_mirror row_mask:0xf bank_mask:0xf bound_ctrl:1
	v_cndmask_b32_e64 v2, v2, 0, vcc
	s_nop 0
	v_max_u32_dpp v13, v13, v13 row_mirror row_mask:0xf bank_mask:0xf bound_ctrl:1
	v_cmp_eq_u32_e32 vcc, v9, v13
	v_cndmask_b32_e64 v14, v14, v13, s[22:23]
	s_nop 0
	v_cndmask_b32_e32 v9, v9, v10, vcc
	v_cndmask_b32_e32 v10, v10, v3, vcc
	v_cndmask_b32_e32 v3, v3, v11, vcc
	v_max_u32_dpp v13, v9, v9 quad_perm:[1,0,3,2] row_mask:0xf bank_mask:0xf bound_ctrl:1
	v_cndmask_b32_e32 v11, v11, v7, vcc
	v_cndmask_b32_e32 v7, v7, v12, vcc
	v_max_u32_dpp v13, v13, v13 quad_perm:[2,3,0,1] row_mask:0xf bank_mask:0xf bound_ctrl:1
	v_cndmask_b32_e32 v12, v12, v6, vcc
	v_cndmask_b32_e32 v6, v6, v2, vcc
	v_max_u32_dpp v13, v13, v13 row_half_mirror row_mask:0xf bank_mask:0xf bound_ctrl:1
	v_cndmask_b32_e64 v2, v2, 0, vcc
	s_nop 0
	v_max_u32_dpp v13, v13, v13 row_mirror row_mask:0xf bank_mask:0xf bound_ctrl:1
	v_cmp_eq_u32_e32 vcc, v9, v13
	v_cndmask_b32_e64 v14, v14, v13, s[24:25]
	s_nop 0
	v_cndmask_b32_e32 v9, v9, v10, vcc
	v_cndmask_b32_e32 v10, v10, v3, vcc
	v_cndmask_b32_e32 v3, v3, v11, vcc
	v_max_u32_dpp v13, v9, v9 quad_perm:[1,0,3,2] row_mask:0xf bank_mask:0xf bound_ctrl:1
	v_cndmask_b32_e32 v11, v11, v7, vcc
	v_cndmask_b32_e32 v7, v7, v12, vcc
	v_max_u32_dpp v13, v13, v13 quad_perm:[2,3,0,1] row_mask:0xf bank_mask:0xf bound_ctrl:1
	v_cndmask_b32_e32 v12, v12, v6, vcc
	v_cndmask_b32_e32 v6, v6, v2, vcc
	v_max_u32_dpp v13, v13, v13 row_half_mirror row_mask:0xf bank_mask:0xf bound_ctrl:1
	v_cndmask_b32_e64 v2, v2, 0, vcc
	s_nop 0
	v_max_u32_dpp v13, v13, v13 row_mirror row_mask:0xf bank_mask:0xf bound_ctrl:1
	v_cmp_eq_u32_e32 vcc, v9, v13
	v_cndmask_b32_e64 v14, v14, v13, s[26:27]
	s_nop 0
	v_cndmask_b32_e32 v9, v9, v10, vcc
	v_cndmask_b32_e32 v10, v10, v3, vcc
	v_cndmask_b32_e32 v3, v3, v11, vcc
	v_cndmask_b32_e32 v11, v11, v7, vcc
	v_cndmask_b32_e32 v7, v7, v12, vcc
	v_cndmask_b32_e32 v12, v12, v6, vcc
	v_cndmask_b32_e32 v2, v6, v2, vcc
	v_max_u32_dpp v6, v9, v9 quad_perm:[1,0,3,2] row_mask:0xf bank_mask:0xf bound_ctrl:1
	s_nop 1
	v_max_u32_dpp v6, v6, v6 quad_perm:[2,3,0,1] row_mask:0xf bank_mask:0xf bound_ctrl:1
	s_nop 1
	v_max_u32_dpp v6, v6, v6 row_half_mirror row_mask:0xf bank_mask:0xf bound_ctrl:1
	s_nop 1
	v_max_u32_dpp v6, v6, v6 row_mirror row_mask:0xf bank_mask:0xf bound_ctrl:1
	v_cmp_eq_u32_e32 vcc, v9, v6
	v_cndmask_b32_e64 v13, v14, v6, s[28:29]
	s_nop 0
	v_cndmask_b32_e32 v6, v9, v10, vcc
	v_cndmask_b32_e32 v9, v10, v3, vcc
	v_cndmask_b32_e32 v3, v3, v11, vcc
	v_cndmask_b32_e32 v10, v11, v7, vcc
	v_max_u32_dpp v11, v6, v6 quad_perm:[1,0,3,2] row_mask:0xf bank_mask:0xf bound_ctrl:1
	v_cndmask_b32_e32 v7, v7, v12, vcc
	v_cndmask_b32_e32 v2, v12, v2, vcc
	v_max_u32_dpp v11, v11, v11 quad_perm:[2,3,0,1] row_mask:0xf bank_mask:0xf bound_ctrl:1
	s_nop 1
	v_max_u32_dpp v11, v11, v11 row_half_mirror row_mask:0xf bank_mask:0xf bound_ctrl:1
	s_nop 1
	v_max_u32_dpp v11, v11, v11 row_mirror row_mask:0xf bank_mask:0xf bound_ctrl:1
	v_cmp_eq_u32_e32 vcc, v6, v11
	v_cndmask_b32_e64 v12, v13, v11, s[30:31]
	v_ashrrev_i32_e32 v13, 31, v4
	v_cndmask_b32_e32 v6, v6, v9, vcc
	v_cndmask_b32_e32 v9, v9, v3, vcc
	v_cndmask_b32_e32 v3, v3, v10, vcc
	v_cndmask_b32_e32 v10, v10, v7, vcc
	v_cndmask_b32_e32 v2, v7, v2, vcc
	v_max_u32_dpp v7, v6, v6 quad_perm:[1,0,3,2] row_mask:0xf bank_mask:0xf bound_ctrl:1
	v_bitop3_b32 v4, v13, v4, s70 bitop3:0x36
	v_and_or_b32 v4, v4, s71, v72
	v_max_u32_dpp v7, v7, v7 quad_perm:[2,3,0,1] row_mask:0xf bank_mask:0xf bound_ctrl:1
	s_nop 1
	v_max_u32_dpp v7, v7, v7 row_half_mirror row_mask:0xf bank_mask:0xf bound_ctrl:1
	s_nop 1
	v_max_u32_dpp v7, v7, v7 row_mirror row_mask:0xf bank_mask:0xf bound_ctrl:1
	v_cmp_eq_u32_e32 vcc, v6, v7
	v_cndmask_b32_e64 v11, v12, v7, s[34:35]
	v_ashrrev_i32_e32 v12, 31, v44
	v_cndmask_b32_e32 v6, v6, v9, vcc
	v_cndmask_b32_e32 v7, v9, v3, vcc
	v_cndmask_b32_e32 v3, v3, v10, vcc
	v_max_u32_dpp v9, v6, v6 quad_perm:[1,0,3,2] row_mask:0xf bank_mask:0xf bound_ctrl:1
	v_cndmask_b32_e32 v2, v10, v2, vcc
	v_bitop3_b32 v12, v12, v44, s70 bitop3:0x36
	v_max_u32_dpp v9, v9, v9 quad_perm:[2,3,0,1] row_mask:0xf bank_mask:0xf bound_ctrl:1
	v_and_or_b32 v12, v12, s71, v71
	s_nop 0
	v_max_u32_dpp v9, v9, v9 row_half_mirror row_mask:0xf bank_mask:0xf bound_ctrl:1
	s_nop 1
	v_max_u32_dpp v9, v9, v9 row_mirror row_mask:0xf bank_mask:0xf bound_ctrl:1
	v_cmp_eq_u32_e32 vcc, v6, v9
	v_cndmask_b32_e64 v10, v11, v9, s[36:37]
	v_ashrrev_i32_e32 v11, 31, v40
	v_cndmask_b32_e32 v6, v6, v7, vcc
	v_cndmask_b32_e32 v7, v7, v3, vcc
	v_cndmask_b32_e32 v2, v3, v2, vcc
	v_max_u32_dpp v3, v6, v6 quad_perm:[1,0,3,2] row_mask:0xf bank_mask:0xf bound_ctrl:1
	v_bitop3_b32 v11, v11, v40, s70 bitop3:0x36
	v_and_or_b32 v11, v11, s71, v70
	v_max_u32_dpp v3, v3, v3 quad_perm:[2,3,0,1] row_mask:0xf bank_mask:0xf bound_ctrl:1
	s_nop 1
	v_max_u32_dpp v3, v3, v3 row_half_mirror row_mask:0xf bank_mask:0xf bound_ctrl:1
	s_nop 1
	v_max_u32_dpp v3, v3, v3 row_mirror row_mask:0xf bank_mask:0xf bound_ctrl:1
	v_cmp_eq_u32_e32 vcc, v6, v3
	v_cndmask_b32_e64 v9, v10, v3, s[38:39]
	v_ashrrev_i32_e32 v10, 31, v36
	v_cndmask_b32_e32 v3, v6, v7, vcc
	v_cndmask_b32_e32 v2, v7, v2, vcc
	v_bitop3_b32 v10, v10, v36, s70 bitop3:0x36
	v_max_u32_dpp v6, v3, v3 quad_perm:[1,0,3,2] row_mask:0xf bank_mask:0xf bound_ctrl:1
	v_and_or_b32 v10, v10, s71, v69
	s_nop 0
	v_max_u32_dpp v6, v6, v6 quad_perm:[2,3,0,1] row_mask:0xf bank_mask:0xf bound_ctrl:1
	s_nop 1
	v_max_u32_dpp v6, v6, v6 row_half_mirror row_mask:0xf bank_mask:0xf bound_ctrl:1
	s_nop 1
	v_max_u32_dpp v6, v6, v6 row_mirror row_mask:0xf bank_mask:0xf bound_ctrl:1
	v_cmp_eq_u32_e32 vcc, v3, v6
	v_cndmask_b32_e64 v7, v9, v6, s[40:41]
	v_ashrrev_i32_e32 v6, 31, v28
	v_cndmask_b32_e32 v2, v3, v2, vcc
	v_ashrrev_i32_e32 v3, 31, v24
	v_ashrrev_i32_e32 v9, 31, v32
	v_max_u32_dpp v2, v2, v2 quad_perm:[1,0,3,2] row_mask:0xf bank_mask:0xf bound_ctrl:1
	v_bitop3_b32 v3, v3, v24, s70 bitop3:0x36
	v_bitop3_b32 v6, v6, v28, s70 bitop3:0x36
	v_max_u32_dpp v2, v2, v2 quad_perm:[2,3,0,1] row_mask:0xf bank_mask:0xf bound_ctrl:1
	v_bitop3_b32 v9, v9, v32, s70 bitop3:0x36
	v_and_or_b32 v3, v3, s71, v66
	v_max_u32_dpp v2, v2, v2 row_half_mirror row_mask:0xf bank_mask:0xf bound_ctrl:1
	v_and_or_b32 v6, v6, s71, v67
	v_and_or_b32 v9, v9, s71, v68
	v_max_u32_dpp v2, v2, v2 row_mirror row_mask:0xf bank_mask:0xf bound_ctrl:1
	v_cndmask_b32_e64 v7, v7, v2, s[42:43]
	v_ashrrev_i32_e32 v2, 31, v20
	v_bitop3_b32 v2, v2, v20, s70 bitop3:0x36
	v_and_or_b32 v2, v2, s71, v61
	v_max_u32_e32 v13, v2, v3
	v_min_u32_e32 v2, v2, v3
	v_max_u32_e32 v3, v6, v9
	v_min_u32_e32 v6, v6, v9
	v_max_u32_e32 v9, v10, v11
	v_min_u32_e32 v10, v10, v11
	v_max_u32_e32 v11, v12, v4
	v_min_u32_e32 v4, v12, v4
	v_max_u32_e32 v12, v13, v3
	v_min_u32_e32 v3, v13, v3
	v_max_u32_e32 v13, v2, v6
	v_min_u32_e32 v2, v2, v6
	v_max_u32_e32 v6, v9, v11
	v_min_u32_e32 v9, v9, v11
	v_max_u32_e32 v11, v10, v4
	v_min_u32_e32 v4, v10, v4
	v_max_u32_e32 v10, v13, v3
	v_min_u32_e32 v3, v13, v3
	v_max_u32_e32 v13, v11, v9
	v_min_u32_e32 v9, v11, v9
	v_max_u32_e32 v11, v12, v6
	v_min_u32_e32 v6, v12, v6
	v_max_u32_e32 v12, v10, v13
	v_min_u32_e32 v10, v10, v13
	v_max_u32_e32 v13, v3, v9
	v_min_u32_e32 v3, v3, v9
	v_max_u32_e32 v9, v2, v4
	v_min_u32_e32 v2, v2, v4
	v_max_u32_e32 v4, v13, v6
	v_min_u32_e32 v6, v13, v6
	v_max_u32_e32 v13, v9, v10
	v_min_u32_e32 v9, v9, v10
	v_max_u32_e32 v10, v12, v4
	v_min_u32_e32 v4, v12, v4
	v_max_u32_e32 v12, v13, v6
	v_min_u32_e32 v6, v13, v6
	v_max_u32_e32 v13, v9, v3
	v_min_u32_e32 v3, v9, v3
	v_max_u32_dpp v9, v11, v11 quad_perm:[1,0,3,2] row_mask:0xf bank_mask:0xf bound_ctrl:1
	s_nop 1
	v_max_u32_dpp v9, v9, v9 quad_perm:[2,3,0,1] row_mask:0xf bank_mask:0xf bound_ctrl:1
	s_nop 1
	v_max_u32_dpp v9, v9, v9 row_half_mirror row_mask:0xf bank_mask:0xf bound_ctrl:1
	s_nop 1
	v_max_u32_dpp v9, v9, v9 row_mirror row_mask:0xf bank_mask:0xf bound_ctrl:1
	v_cmp_eq_u32_e32 vcc, v11, v9
	v_cndmask_b32_e64 v14, 0, v9, s[10:11]
	s_nop 0
	v_cndmask_b32_e32 v9, v11, v10, vcc
	v_cndmask_b32_e32 v10, v10, v4, vcc
	v_cndmask_b32_e32 v4, v4, v12, vcc
	v_cndmask_b32_e32 v11, v12, v6, vcc
	v_cndmask_b32_e32 v6, v6, v13, vcc
	v_cndmask_b32_e32 v12, v13, v3, vcc
	v_max_u32_dpp v13, v9, v9 quad_perm:[1,0,3,2] row_mask:0xf bank_mask:0xf bound_ctrl:1
	v_cndmask_b32_e32 v3, v3, v2, vcc
	v_cndmask_b32_e64 v2, v2, 0, vcc
	v_max_u32_dpp v13, v13, v13 quad_perm:[2,3,0,1] row_mask:0xf bank_mask:0xf bound_ctrl:1
	s_nop 1
	v_max_u32_dpp v13, v13, v13 row_half_mirror row_mask:0xf bank_mask:0xf bound_ctrl:1
	s_nop 1
	v_max_u32_dpp v13, v13, v13 row_mirror row_mask:0xf bank_mask:0xf bound_ctrl:1
	v_cmp_eq_u32_e32 vcc, v9, v13
	v_cndmask_b32_e64 v14, v14, v13, s[12:13]
	s_nop 0
	v_cndmask_b32_e32 v9, v9, v10, vcc
	v_cndmask_b32_e32 v10, v10, v4, vcc
	v_cndmask_b32_e32 v4, v4, v11, vcc
	v_max_u32_dpp v13, v9, v9 quad_perm:[1,0,3,2] row_mask:0xf bank_mask:0xf bound_ctrl:1
	v_cndmask_b32_e32 v11, v11, v6, vcc
	v_cndmask_b32_e32 v6, v6, v12, vcc
	v_max_u32_dpp v13, v13, v13 quad_perm:[2,3,0,1] row_mask:0xf bank_mask:0xf bound_ctrl:1
	v_cndmask_b32_e32 v12, v12, v3, vcc
	v_cndmask_b32_e32 v3, v3, v2, vcc
	v_max_u32_dpp v13, v13, v13 row_half_mirror row_mask:0xf bank_mask:0xf bound_ctrl:1
	v_cndmask_b32_e64 v2, v2, 0, vcc
	s_nop 0
	v_max_u32_dpp v13, v13, v13 row_mirror row_mask:0xf bank_mask:0xf bound_ctrl:1
	v_cmp_eq_u32_e32 vcc, v9, v13
	v_cndmask_b32_e64 v14, v14, v13, s[14:15]
	s_nop 0
	v_cndmask_b32_e32 v9, v9, v10, vcc
	v_cndmask_b32_e32 v10, v10, v4, vcc
	v_cndmask_b32_e32 v4, v4, v11, vcc
	v_max_u32_dpp v13, v9, v9 quad_perm:[1,0,3,2] row_mask:0xf bank_mask:0xf bound_ctrl:1
	v_cndmask_b32_e32 v11, v11, v6, vcc
	v_cndmask_b32_e32 v6, v6, v12, vcc
	v_max_u32_dpp v13, v13, v13 quad_perm:[2,3,0,1] row_mask:0xf bank_mask:0xf bound_ctrl:1
	v_cndmask_b32_e32 v12, v12, v3, vcc
	v_cndmask_b32_e32 v3, v3, v2, vcc
	v_max_u32_dpp v13, v13, v13 row_half_mirror row_mask:0xf bank_mask:0xf bound_ctrl:1
	v_cndmask_b32_e64 v2, v2, 0, vcc
	s_nop 0
	v_max_u32_dpp v13, v13, v13 row_mirror row_mask:0xf bank_mask:0xf bound_ctrl:1
	v_cmp_eq_u32_e32 vcc, v9, v13
	v_cndmask_b32_e64 v14, v14, v13, s[16:17]
	s_nop 0
	v_cndmask_b32_e32 v9, v9, v10, vcc
	v_cndmask_b32_e32 v10, v10, v4, vcc
	v_cndmask_b32_e32 v4, v4, v11, vcc
	v_max_u32_dpp v13, v9, v9 quad_perm:[1,0,3,2] row_mask:0xf bank_mask:0xf bound_ctrl:1
	v_cndmask_b32_e32 v11, v11, v6, vcc
	v_cndmask_b32_e32 v6, v6, v12, vcc
	v_max_u32_dpp v13, v13, v13 quad_perm:[2,3,0,1] row_mask:0xf bank_mask:0xf bound_ctrl:1
	v_cndmask_b32_e32 v12, v12, v3, vcc
	v_cndmask_b32_e32 v3, v3, v2, vcc
	v_max_u32_dpp v13, v13, v13 row_half_mirror row_mask:0xf bank_mask:0xf bound_ctrl:1
	v_cndmask_b32_e64 v2, v2, 0, vcc
	s_nop 0
	v_max_u32_dpp v13, v13, v13 row_mirror row_mask:0xf bank_mask:0xf bound_ctrl:1
	v_cmp_eq_u32_e32 vcc, v9, v13
	v_cndmask_b32_e64 v14, v14, v13, s[18:19]
	s_nop 0
	v_cndmask_b32_e32 v9, v9, v10, vcc
	v_cndmask_b32_e32 v10, v10, v4, vcc
	v_cndmask_b32_e32 v4, v4, v11, vcc
	v_max_u32_dpp v13, v9, v9 quad_perm:[1,0,3,2] row_mask:0xf bank_mask:0xf bound_ctrl:1
	v_cndmask_b32_e32 v11, v11, v6, vcc
	v_cndmask_b32_e32 v6, v6, v12, vcc
	v_max_u32_dpp v13, v13, v13 quad_perm:[2,3,0,1] row_mask:0xf bank_mask:0xf bound_ctrl:1
	v_cndmask_b32_e32 v12, v12, v3, vcc
	v_cndmask_b32_e32 v3, v3, v2, vcc
	v_max_u32_dpp v13, v13, v13 row_half_mirror row_mask:0xf bank_mask:0xf bound_ctrl:1
	v_cndmask_b32_e64 v2, v2, 0, vcc
	s_nop 0
	v_max_u32_dpp v13, v13, v13 row_mirror row_mask:0xf bank_mask:0xf bound_ctrl:1
	v_cmp_eq_u32_e32 vcc, v9, v13
	v_cndmask_b32_e64 v14, v14, v13, s[20:21]
	s_nop 0
	v_cndmask_b32_e32 v9, v9, v10, vcc
	v_cndmask_b32_e32 v10, v10, v4, vcc
	v_cndmask_b32_e32 v4, v4, v11, vcc
	v_max_u32_dpp v13, v9, v9 quad_perm:[1,0,3,2] row_mask:0xf bank_mask:0xf bound_ctrl:1
	v_cndmask_b32_e32 v11, v11, v6, vcc
	v_cndmask_b32_e32 v6, v6, v12, vcc
	v_max_u32_dpp v13, v13, v13 quad_perm:[2,3,0,1] row_mask:0xf bank_mask:0xf bound_ctrl:1
	v_cndmask_b32_e32 v12, v12, v3, vcc
	v_cndmask_b32_e32 v3, v3, v2, vcc
	v_max_u32_dpp v13, v13, v13 row_half_mirror row_mask:0xf bank_mask:0xf bound_ctrl:1
	v_cndmask_b32_e64 v2, v2, 0, vcc
	s_nop 0
	v_max_u32_dpp v13, v13, v13 row_mirror row_mask:0xf bank_mask:0xf bound_ctrl:1
	v_cmp_eq_u32_e32 vcc, v9, v13
	v_cndmask_b32_e64 v14, v14, v13, s[22:23]
	s_nop 0
	v_cndmask_b32_e32 v9, v9, v10, vcc
	v_cndmask_b32_e32 v10, v10, v4, vcc
	v_cndmask_b32_e32 v4, v4, v11, vcc
	v_max_u32_dpp v13, v9, v9 quad_perm:[1,0,3,2] row_mask:0xf bank_mask:0xf bound_ctrl:1
	v_cndmask_b32_e32 v11, v11, v6, vcc
	v_cndmask_b32_e32 v6, v6, v12, vcc
	v_max_u32_dpp v13, v13, v13 quad_perm:[2,3,0,1] row_mask:0xf bank_mask:0xf bound_ctrl:1
	v_cndmask_b32_e32 v12, v12, v3, vcc
	v_cndmask_b32_e32 v3, v3, v2, vcc
	v_max_u32_dpp v13, v13, v13 row_half_mirror row_mask:0xf bank_mask:0xf bound_ctrl:1
	v_cndmask_b32_e64 v2, v2, 0, vcc
	s_nop 0
	v_max_u32_dpp v13, v13, v13 row_mirror row_mask:0xf bank_mask:0xf bound_ctrl:1
	v_cmp_eq_u32_e32 vcc, v9, v13
	v_cndmask_b32_e64 v14, v14, v13, s[24:25]
	s_nop 0
	v_cndmask_b32_e32 v9, v9, v10, vcc
	v_cndmask_b32_e32 v10, v10, v4, vcc
	v_cndmask_b32_e32 v4, v4, v11, vcc
	v_max_u32_dpp v13, v9, v9 quad_perm:[1,0,3,2] row_mask:0xf bank_mask:0xf bound_ctrl:1
	v_cndmask_b32_e32 v11, v11, v6, vcc
	v_cndmask_b32_e32 v6, v6, v12, vcc
	v_max_u32_dpp v13, v13, v13 quad_perm:[2,3,0,1] row_mask:0xf bank_mask:0xf bound_ctrl:1
	v_cndmask_b32_e32 v12, v12, v3, vcc
	v_cndmask_b32_e32 v3, v3, v2, vcc
	v_max_u32_dpp v13, v13, v13 row_half_mirror row_mask:0xf bank_mask:0xf bound_ctrl:1
	v_cndmask_b32_e64 v2, v2, 0, vcc
	s_nop 0
	v_max_u32_dpp v13, v13, v13 row_mirror row_mask:0xf bank_mask:0xf bound_ctrl:1
	v_cmp_eq_u32_e32 vcc, v9, v13
	v_cndmask_b32_e64 v14, v14, v13, s[26:27]
	s_nop 0
	v_cndmask_b32_e32 v9, v9, v10, vcc
	v_cndmask_b32_e32 v10, v10, v4, vcc
	v_cndmask_b32_e32 v4, v4, v11, vcc
	v_cndmask_b32_e32 v11, v11, v6, vcc
	v_cndmask_b32_e32 v6, v6, v12, vcc
	v_cndmask_b32_e32 v12, v12, v3, vcc
	v_cndmask_b32_e32 v2, v3, v2, vcc
	v_max_u32_dpp v3, v9, v9 quad_perm:[1,0,3,2] row_mask:0xf bank_mask:0xf bound_ctrl:1
	s_nop 1
	v_max_u32_dpp v3, v3, v3 quad_perm:[2,3,0,1] row_mask:0xf bank_mask:0xf bound_ctrl:1
	s_nop 1
	v_max_u32_dpp v3, v3, v3 row_half_mirror row_mask:0xf bank_mask:0xf bound_ctrl:1
	s_nop 1
	v_max_u32_dpp v3, v3, v3 row_mirror row_mask:0xf bank_mask:0xf bound_ctrl:1
	v_cmp_eq_u32_e32 vcc, v9, v3
	v_cndmask_b32_e64 v13, v14, v3, s[28:29]
	s_nop 0
	v_cndmask_b32_e32 v3, v9, v10, vcc
	v_cndmask_b32_e32 v9, v10, v4, vcc
	v_cndmask_b32_e32 v4, v4, v11, vcc
	v_cndmask_b32_e32 v10, v11, v6, vcc
	v_max_u32_dpp v11, v3, v3 quad_perm:[1,0,3,2] row_mask:0xf bank_mask:0xf bound_ctrl:1
	v_cndmask_b32_e32 v6, v6, v12, vcc
	v_cndmask_b32_e32 v2, v12, v2, vcc
	v_max_u32_dpp v11, v11, v11 quad_perm:[2,3,0,1] row_mask:0xf bank_mask:0xf bound_ctrl:1
	s_nop 1
	v_max_u32_dpp v11, v11, v11 row_half_mirror row_mask:0xf bank_mask:0xf bound_ctrl:1
	s_nop 1
	v_max_u32_dpp v11, v11, v11 row_mirror row_mask:0xf bank_mask:0xf bound_ctrl:1
	v_cmp_eq_u32_e32 vcc, v3, v11
	v_cndmask_b32_e64 v12, v13, v11, s[30:31]
	v_ashrrev_i32_e32 v13, 31, v5
	v_cndmask_b32_e32 v3, v3, v9, vcc
	v_cndmask_b32_e32 v9, v9, v4, vcc
	v_cndmask_b32_e32 v4, v4, v10, vcc
	v_cndmask_b32_e32 v10, v10, v6, vcc
	v_cndmask_b32_e32 v2, v6, v2, vcc
	v_max_u32_dpp v6, v3, v3 quad_perm:[1,0,3,2] row_mask:0xf bank_mask:0xf bound_ctrl:1
	v_bitop3_b32 v5, v13, v5, s70 bitop3:0x36
	v_and_or_b32 v5, v5, s71, v72
	v_max_u32_dpp v6, v6, v6 quad_perm:[2,3,0,1] row_mask:0xf bank_mask:0xf bound_ctrl:1
	s_nop 1
	v_max_u32_dpp v6, v6, v6 row_half_mirror row_mask:0xf bank_mask:0xf bound_ctrl:1
	s_nop 1
	v_max_u32_dpp v6, v6, v6 row_mirror row_mask:0xf bank_mask:0xf bound_ctrl:1
	v_cmp_eq_u32_e32 vcc, v3, v6
	v_cndmask_b32_e64 v11, v12, v6, s[34:35]
	v_ashrrev_i32_e32 v12, 31, v45
	v_cndmask_b32_e32 v3, v3, v9, vcc
	v_cndmask_b32_e32 v6, v9, v4, vcc
	v_cndmask_b32_e32 v4, v4, v10, vcc
	v_max_u32_dpp v9, v3, v3 quad_perm:[1,0,3,2] row_mask:0xf bank_mask:0xf bound_ctrl:1
	v_cndmask_b32_e32 v2, v10, v2, vcc
	v_bitop3_b32 v12, v12, v45, s70 bitop3:0x36
	v_max_u32_dpp v9, v9, v9 quad_perm:[2,3,0,1] row_mask:0xf bank_mask:0xf bound_ctrl:1
	v_and_or_b32 v12, v12, s71, v71
	s_nop 0
	v_max_u32_dpp v9, v9, v9 row_half_mirror row_mask:0xf bank_mask:0xf bound_ctrl:1
	s_nop 1
	v_max_u32_dpp v9, v9, v9 row_mirror row_mask:0xf bank_mask:0xf bound_ctrl:1
	v_cmp_eq_u32_e32 vcc, v3, v9
	v_cndmask_b32_e64 v10, v11, v9, s[36:37]
	v_ashrrev_i32_e32 v11, 31, v41
	v_cndmask_b32_e32 v3, v3, v6, vcc
	v_cndmask_b32_e32 v6, v6, v4, vcc
	v_cndmask_b32_e32 v2, v4, v2, vcc
	v_max_u32_dpp v4, v3, v3 quad_perm:[1,0,3,2] row_mask:0xf bank_mask:0xf bound_ctrl:1
	v_bitop3_b32 v11, v11, v41, s70 bitop3:0x36
	v_and_or_b32 v11, v11, s71, v70
	v_max_u32_dpp v4, v4, v4 quad_perm:[2,3,0,1] row_mask:0xf bank_mask:0xf bound_ctrl:1
	s_nop 1
	v_max_u32_dpp v4, v4, v4 row_half_mirror row_mask:0xf bank_mask:0xf bound_ctrl:1
	s_nop 1
	v_max_u32_dpp v4, v4, v4 row_mirror row_mask:0xf bank_mask:0xf bound_ctrl:1
	v_cmp_eq_u32_e32 vcc, v3, v4
	v_cndmask_b32_e64 v9, v10, v4, s[38:39]
	v_ashrrev_i32_e32 v10, 31, v37
	v_cndmask_b32_e32 v3, v3, v6, vcc
	v_cndmask_b32_e32 v2, v6, v2, vcc
	v_bitop3_b32 v10, v10, v37, s70 bitop3:0x36
	v_max_u32_dpp v4, v3, v3 quad_perm:[1,0,3,2] row_mask:0xf bank_mask:0xf bound_ctrl:1
	v_and_or_b32 v10, v10, s71, v69
	s_nop 0
	v_max_u32_dpp v4, v4, v4 quad_perm:[2,3,0,1] row_mask:0xf bank_mask:0xf bound_ctrl:1
	s_nop 1
	v_max_u32_dpp v4, v4, v4 row_half_mirror row_mask:0xf bank_mask:0xf bound_ctrl:1
	s_nop 1
	v_max_u32_dpp v4, v4, v4 row_mirror row_mask:0xf bank_mask:0xf bound_ctrl:1
	v_cmp_eq_u32_e32 vcc, v3, v4
	v_cndmask_b32_e64 v6, v9, v4, s[40:41]
	v_ashrrev_i32_e32 v4, 31, v29
	v_cndmask_b32_e32 v2, v3, v2, vcc
	v_ashrrev_i32_e32 v3, 31, v25
	v_ashrrev_i32_e32 v9, 31, v33
	v_max_u32_dpp v2, v2, v2 quad_perm:[1,0,3,2] row_mask:0xf bank_mask:0xf bound_ctrl:1
	v_bitop3_b32 v3, v3, v25, s70 bitop3:0x36
	v_bitop3_b32 v4, v4, v29, s70 bitop3:0x36
	v_max_u32_dpp v2, v2, v2 quad_perm:[2,3,0,1] row_mask:0xf bank_mask:0xf bound_ctrl:1
	v_bitop3_b32 v9, v9, v33, s70 bitop3:0x36
	v_and_or_b32 v3, v3, s71, v66
	v_max_u32_dpp v2, v2, v2 row_half_mirror row_mask:0xf bank_mask:0xf bound_ctrl:1
	v_and_or_b32 v4, v4, s71, v67
	v_and_or_b32 v9, v9, s71, v68
	v_max_u32_dpp v2, v2, v2 row_mirror row_mask:0xf bank_mask:0xf bound_ctrl:1
	v_cndmask_b32_e64 v6, v6, v2, s[42:43]
	v_ashrrev_i32_e32 v2, 31, v21
	v_bitop3_b32 v2, v2, v21, s70 bitop3:0x36
	v_and_or_b32 v2, v2, s71, v61
	v_max_u32_e32 v13, v2, v3
	v_min_u32_e32 v2, v2, v3
	v_max_u32_e32 v3, v4, v9
	v_min_u32_e32 v4, v4, v9
	v_max_u32_e32 v9, v10, v11
	v_min_u32_e32 v10, v10, v11
	v_max_u32_e32 v11, v12, v5
	v_min_u32_e32 v5, v12, v5
	v_max_u32_e32 v12, v13, v3
	v_min_u32_e32 v3, v13, v3
	v_max_u32_e32 v13, v2, v4
	v_min_u32_e32 v2, v2, v4
	v_max_u32_e32 v4, v9, v11
	v_min_u32_e32 v9, v9, v11
	v_max_u32_e32 v11, v10, v5
	v_min_u32_e32 v5, v10, v5
	v_max_u32_e32 v10, v13, v3
	v_min_u32_e32 v3, v13, v3
	v_max_u32_e32 v13, v11, v9
	v_min_u32_e32 v9, v11, v9
	v_max_u32_e32 v11, v12, v4
	v_min_u32_e32 v4, v12, v4
	v_max_u32_e32 v12, v10, v13
	v_min_u32_e32 v10, v10, v13
	v_max_u32_e32 v13, v3, v9
	v_min_u32_e32 v3, v3, v9
	v_max_u32_e32 v9, v2, v5
	v_min_u32_e32 v2, v2, v5
	v_max_u32_e32 v5, v13, v4
	v_min_u32_e32 v4, v13, v4
	v_max_u32_e32 v13, v9, v10
	v_min_u32_e32 v9, v9, v10
	v_max_u32_e32 v10, v12, v5
	v_min_u32_e32 v5, v12, v5
	v_max_u32_e32 v12, v13, v4
	v_min_u32_e32 v4, v13, v4
	v_max_u32_e32 v13, v9, v3
	v_min_u32_e32 v3, v9, v3
	v_max_u32_dpp v9, v11, v11 quad_perm:[1,0,3,2] row_mask:0xf bank_mask:0xf bound_ctrl:1
	s_nop 1
	v_max_u32_dpp v9, v9, v9 quad_perm:[2,3,0,1] row_mask:0xf bank_mask:0xf bound_ctrl:1
	s_nop 1
	v_max_u32_dpp v9, v9, v9 row_half_mirror row_mask:0xf bank_mask:0xf bound_ctrl:1
	s_nop 1
	v_max_u32_dpp v9, v9, v9 row_mirror row_mask:0xf bank_mask:0xf bound_ctrl:1
	v_cmp_eq_u32_e32 vcc, v11, v9
	v_cndmask_b32_e64 v14, 0, v9, s[10:11]
	s_nop 0
	v_cndmask_b32_e32 v9, v11, v10, vcc
	v_cndmask_b32_e32 v10, v10, v5, vcc
	v_cndmask_b32_e32 v5, v5, v12, vcc
	v_cndmask_b32_e32 v11, v12, v4, vcc
	v_cndmask_b32_e32 v4, v4, v13, vcc
	v_cndmask_b32_e32 v12, v13, v3, vcc
	v_max_u32_dpp v13, v9, v9 quad_perm:[1,0,3,2] row_mask:0xf bank_mask:0xf bound_ctrl:1
	v_cndmask_b32_e32 v3, v3, v2, vcc
	v_cndmask_b32_e64 v2, v2, 0, vcc
	v_max_u32_dpp v13, v13, v13 quad_perm:[2,3,0,1] row_mask:0xf bank_mask:0xf bound_ctrl:1
	s_nop 1
	v_max_u32_dpp v13, v13, v13 row_half_mirror row_mask:0xf bank_mask:0xf bound_ctrl:1
	s_nop 1
	v_max_u32_dpp v13, v13, v13 row_mirror row_mask:0xf bank_mask:0xf bound_ctrl:1
	v_cmp_eq_u32_e32 vcc, v9, v13
	v_cndmask_b32_e64 v14, v14, v13, s[12:13]
	s_nop 0
	v_cndmask_b32_e32 v9, v9, v10, vcc
	v_cndmask_b32_e32 v10, v10, v5, vcc
	v_cndmask_b32_e32 v5, v5, v11, vcc
	v_max_u32_dpp v13, v9, v9 quad_perm:[1,0,3,2] row_mask:0xf bank_mask:0xf bound_ctrl:1
	v_cndmask_b32_e32 v11, v11, v4, vcc
	v_cndmask_b32_e32 v4, v4, v12, vcc
	v_max_u32_dpp v13, v13, v13 quad_perm:[2,3,0,1] row_mask:0xf bank_mask:0xf bound_ctrl:1
	v_cndmask_b32_e32 v12, v12, v3, vcc
	v_cndmask_b32_e32 v3, v3, v2, vcc
	v_max_u32_dpp v13, v13, v13 row_half_mirror row_mask:0xf bank_mask:0xf bound_ctrl:1
	v_cndmask_b32_e64 v2, v2, 0, vcc
	s_nop 0
	v_max_u32_dpp v13, v13, v13 row_mirror row_mask:0xf bank_mask:0xf bound_ctrl:1
	v_cmp_eq_u32_e32 vcc, v9, v13
	v_cndmask_b32_e64 v14, v14, v13, s[14:15]
	s_nop 0
	v_cndmask_b32_e32 v9, v9, v10, vcc
	v_cndmask_b32_e32 v10, v10, v5, vcc
	v_cndmask_b32_e32 v5, v5, v11, vcc
	v_max_u32_dpp v13, v9, v9 quad_perm:[1,0,3,2] row_mask:0xf bank_mask:0xf bound_ctrl:1
	v_cndmask_b32_e32 v11, v11, v4, vcc
	v_cndmask_b32_e32 v4, v4, v12, vcc
	v_max_u32_dpp v13, v13, v13 quad_perm:[2,3,0,1] row_mask:0xf bank_mask:0xf bound_ctrl:1
	v_cndmask_b32_e32 v12, v12, v3, vcc
	v_cndmask_b32_e32 v3, v3, v2, vcc
	v_max_u32_dpp v13, v13, v13 row_half_mirror row_mask:0xf bank_mask:0xf bound_ctrl:1
	v_cndmask_b32_e64 v2, v2, 0, vcc
	s_nop 0
	v_max_u32_dpp v13, v13, v13 row_mirror row_mask:0xf bank_mask:0xf bound_ctrl:1
	v_cmp_eq_u32_e32 vcc, v9, v13
	v_cndmask_b32_e64 v14, v14, v13, s[16:17]
	s_nop 0
	v_cndmask_b32_e32 v9, v9, v10, vcc
	v_cndmask_b32_e32 v10, v10, v5, vcc
	v_cndmask_b32_e32 v5, v5, v11, vcc
	v_max_u32_dpp v13, v9, v9 quad_perm:[1,0,3,2] row_mask:0xf bank_mask:0xf bound_ctrl:1
	v_cndmask_b32_e32 v11, v11, v4, vcc
	v_cndmask_b32_e32 v4, v4, v12, vcc
	v_max_u32_dpp v13, v13, v13 quad_perm:[2,3,0,1] row_mask:0xf bank_mask:0xf bound_ctrl:1
	v_cndmask_b32_e32 v12, v12, v3, vcc
	v_cndmask_b32_e32 v3, v3, v2, vcc
	v_max_u32_dpp v13, v13, v13 row_half_mirror row_mask:0xf bank_mask:0xf bound_ctrl:1
	v_cndmask_b32_e64 v2, v2, 0, vcc
	s_nop 0
	v_max_u32_dpp v13, v13, v13 row_mirror row_mask:0xf bank_mask:0xf bound_ctrl:1
	v_cmp_eq_u32_e32 vcc, v9, v13
	v_cndmask_b32_e64 v14, v14, v13, s[18:19]
	s_nop 0
	v_cndmask_b32_e32 v9, v9, v10, vcc
	v_cndmask_b32_e32 v10, v10, v5, vcc
	v_cndmask_b32_e32 v5, v5, v11, vcc
	v_max_u32_dpp v13, v9, v9 quad_perm:[1,0,3,2] row_mask:0xf bank_mask:0xf bound_ctrl:1
	v_cndmask_b32_e32 v11, v11, v4, vcc
	v_cndmask_b32_e32 v4, v4, v12, vcc
	v_max_u32_dpp v13, v13, v13 quad_perm:[2,3,0,1] row_mask:0xf bank_mask:0xf bound_ctrl:1
	v_cndmask_b32_e32 v12, v12, v3, vcc
	v_cndmask_b32_e32 v3, v3, v2, vcc
	v_max_u32_dpp v13, v13, v13 row_half_mirror row_mask:0xf bank_mask:0xf bound_ctrl:1
	v_cndmask_b32_e64 v2, v2, 0, vcc
	s_nop 0
	v_max_u32_dpp v13, v13, v13 row_mirror row_mask:0xf bank_mask:0xf bound_ctrl:1
	v_cmp_eq_u32_e32 vcc, v9, v13
	v_cndmask_b32_e64 v14, v14, v13, s[20:21]
	s_nop 0
	v_cndmask_b32_e32 v9, v9, v10, vcc
	v_cndmask_b32_e32 v10, v10, v5, vcc
	v_cndmask_b32_e32 v5, v5, v11, vcc
	v_max_u32_dpp v13, v9, v9 quad_perm:[1,0,3,2] row_mask:0xf bank_mask:0xf bound_ctrl:1
	v_cndmask_b32_e32 v11, v11, v4, vcc
	v_cndmask_b32_e32 v4, v4, v12, vcc
	v_max_u32_dpp v13, v13, v13 quad_perm:[2,3,0,1] row_mask:0xf bank_mask:0xf bound_ctrl:1
	v_cndmask_b32_e32 v12, v12, v3, vcc
	v_cndmask_b32_e32 v3, v3, v2, vcc
	v_max_u32_dpp v13, v13, v13 row_half_mirror row_mask:0xf bank_mask:0xf bound_ctrl:1
	v_cndmask_b32_e64 v2, v2, 0, vcc
	s_nop 0
	v_max_u32_dpp v13, v13, v13 row_mirror row_mask:0xf bank_mask:0xf bound_ctrl:1
	v_cmp_eq_u32_e32 vcc, v9, v13
	v_cndmask_b32_e64 v14, v14, v13, s[22:23]
	s_nop 0
	v_cndmask_b32_e32 v9, v9, v10, vcc
	v_cndmask_b32_e32 v10, v10, v5, vcc
	v_cndmask_b32_e32 v5, v5, v11, vcc
	v_max_u32_dpp v13, v9, v9 quad_perm:[1,0,3,2] row_mask:0xf bank_mask:0xf bound_ctrl:1
	v_cndmask_b32_e32 v11, v11, v4, vcc
	v_cndmask_b32_e32 v4, v4, v12, vcc
	v_max_u32_dpp v13, v13, v13 quad_perm:[2,3,0,1] row_mask:0xf bank_mask:0xf bound_ctrl:1
	v_cndmask_b32_e32 v12, v12, v3, vcc
	v_cndmask_b32_e32 v3, v3, v2, vcc
	v_max_u32_dpp v13, v13, v13 row_half_mirror row_mask:0xf bank_mask:0xf bound_ctrl:1
	v_cndmask_b32_e64 v2, v2, 0, vcc
	s_nop 0
	v_max_u32_dpp v13, v13, v13 row_mirror row_mask:0xf bank_mask:0xf bound_ctrl:1
	v_cmp_eq_u32_e32 vcc, v9, v13
	v_cndmask_b32_e64 v14, v14, v13, s[24:25]
	s_nop 0
	v_cndmask_b32_e32 v9, v9, v10, vcc
	v_cndmask_b32_e32 v10, v10, v5, vcc
	v_cndmask_b32_e32 v5, v5, v11, vcc
	v_max_u32_dpp v13, v9, v9 quad_perm:[1,0,3,2] row_mask:0xf bank_mask:0xf bound_ctrl:1
	v_cndmask_b32_e32 v11, v11, v4, vcc
	v_cndmask_b32_e32 v4, v4, v12, vcc
	v_max_u32_dpp v13, v13, v13 quad_perm:[2,3,0,1] row_mask:0xf bank_mask:0xf bound_ctrl:1
	v_cndmask_b32_e32 v12, v12, v3, vcc
	v_cndmask_b32_e32 v3, v3, v2, vcc
	v_max_u32_dpp v13, v13, v13 row_half_mirror row_mask:0xf bank_mask:0xf bound_ctrl:1
	v_cndmask_b32_e64 v2, v2, 0, vcc
	s_nop 0
	v_max_u32_dpp v13, v13, v13 row_mirror row_mask:0xf bank_mask:0xf bound_ctrl:1
	v_cmp_eq_u32_e32 vcc, v9, v13
	v_cndmask_b32_e64 v14, v14, v13, s[26:27]
	s_nop 0
	v_cndmask_b32_e32 v9, v9, v10, vcc
	v_cndmask_b32_e32 v10, v10, v5, vcc
	v_cndmask_b32_e32 v5, v5, v11, vcc
	v_cndmask_b32_e32 v11, v11, v4, vcc
	v_cndmask_b32_e32 v4, v4, v12, vcc
	v_cndmask_b32_e32 v12, v12, v3, vcc
	v_cndmask_b32_e32 v2, v3, v2, vcc
	v_max_u32_dpp v3, v9, v9 quad_perm:[1,0,3,2] row_mask:0xf bank_mask:0xf bound_ctrl:1
	s_nop 1
	v_max_u32_dpp v3, v3, v3 quad_perm:[2,3,0,1] row_mask:0xf bank_mask:0xf bound_ctrl:1
	s_nop 1
	v_max_u32_dpp v3, v3, v3 row_half_mirror row_mask:0xf bank_mask:0xf bound_ctrl:1
	s_nop 1
	v_max_u32_dpp v3, v3, v3 row_mirror row_mask:0xf bank_mask:0xf bound_ctrl:1
	v_cmp_eq_u32_e32 vcc, v9, v3
	v_cndmask_b32_e64 v13, v14, v3, s[28:29]
	s_nop 0
	v_cndmask_b32_e32 v3, v9, v10, vcc
	v_cndmask_b32_e32 v9, v10, v5, vcc
	v_cndmask_b32_e32 v5, v5, v11, vcc
	v_cndmask_b32_e32 v10, v11, v4, vcc
	v_max_u32_dpp v11, v3, v3 quad_perm:[1,0,3,2] row_mask:0xf bank_mask:0xf bound_ctrl:1
	v_cndmask_b32_e32 v4, v4, v12, vcc
	v_cndmask_b32_e32 v2, v12, v2, vcc
	v_max_u32_dpp v11, v11, v11 quad_perm:[2,3,0,1] row_mask:0xf bank_mask:0xf bound_ctrl:1
	s_nop 1
	v_max_u32_dpp v11, v11, v11 row_half_mirror row_mask:0xf bank_mask:0xf bound_ctrl:1
	s_nop 1
	v_max_u32_dpp v11, v11, v11 row_mirror row_mask:0xf bank_mask:0xf bound_ctrl:1
	v_cmp_eq_u32_e32 vcc, v3, v11
	v_cndmask_b32_e64 v12, v13, v11, s[30:31]
	s_nop 0
	v_cndmask_b32_e32 v3, v3, v9, vcc
	v_cndmask_b32_e32 v9, v9, v5, vcc
	v_cndmask_b32_e32 v5, v5, v10, vcc
	v_cndmask_b32_e32 v10, v10, v4, vcc
	v_cndmask_b32_e32 v2, v4, v2, vcc
	v_max_u32_dpp v4, v3, v3 quad_perm:[1,0,3,2] row_mask:0xf bank_mask:0xf bound_ctrl:1
	s_nop 1
	v_max_u32_dpp v4, v4, v4 quad_perm:[2,3,0,1] row_mask:0xf bank_mask:0xf bound_ctrl:1
	s_nop 1
	v_max_u32_dpp v4, v4, v4 row_half_mirror row_mask:0xf bank_mask:0xf bound_ctrl:1
	s_nop 1
	v_max_u32_dpp v4, v4, v4 row_mirror row_mask:0xf bank_mask:0xf bound_ctrl:1
	v_cmp_eq_u32_e32 vcc, v3, v4
	v_cndmask_b32_e64 v11, v12, v4, s[34:35]
	s_nop 0
	v_cndmask_b32_e32 v3, v3, v9, vcc
	v_cndmask_b32_e32 v4, v9, v5, vcc
	v_cndmask_b32_e32 v5, v5, v10, vcc
	v_max_u32_dpp v9, v3, v3 quad_perm:[1,0,3,2] row_mask:0xf bank_mask:0xf bound_ctrl:1
	v_cndmask_b32_e32 v2, v10, v2, vcc
	s_nop 0
	v_max_u32_dpp v9, v9, v9 quad_perm:[2,3,0,1] row_mask:0xf bank_mask:0xf bound_ctrl:1
	s_nop 1
	v_max_u32_dpp v9, v9, v9 row_half_mirror row_mask:0xf bank_mask:0xf bound_ctrl:1
	s_nop 1
	v_max_u32_dpp v9, v9, v9 row_mirror row_mask:0xf bank_mask:0xf bound_ctrl:1
	v_cmp_eq_u32_e32 vcc, v3, v9
	v_cndmask_b32_e64 v10, v11, v9, s[36:37]
	s_nop 0
	v_cndmask_b32_e32 v3, v3, v4, vcc
	v_cndmask_b32_e32 v4, v4, v5, vcc
	v_cndmask_b32_e32 v2, v5, v2, vcc
	v_max_u32_dpp v5, v3, v3 quad_perm:[1,0,3,2] row_mask:0xf bank_mask:0xf bound_ctrl:1
	s_nop 1
	v_max_u32_dpp v5, v5, v5 quad_perm:[2,3,0,1] row_mask:0xf bank_mask:0xf bound_ctrl:1
	s_nop 1
	v_max_u32_dpp v5, v5, v5 row_half_mirror row_mask:0xf bank_mask:0xf bound_ctrl:1
	s_nop 1
	v_max_u32_dpp v5, v5, v5 row_mirror row_mask:0xf bank_mask:0xf bound_ctrl:1
	v_cmp_eq_u32_e32 vcc, v3, v5
	v_cndmask_b32_e64 v9, v10, v5, s[38:39]
	s_nop 0
	v_cndmask_b32_e32 v3, v3, v4, vcc
	v_cndmask_b32_e32 v2, v4, v2, vcc
	s_nop 0
	v_max_u32_dpp v4, v3, v3 quad_perm:[1,0,3,2] row_mask:0xf bank_mask:0xf bound_ctrl:1
	s_nop 1
	v_max_u32_dpp v4, v4, v4 quad_perm:[2,3,0,1] row_mask:0xf bank_mask:0xf bound_ctrl:1
	s_nop 1
	v_max_u32_dpp v4, v4, v4 row_half_mirror row_mask:0xf bank_mask:0xf bound_ctrl:1
	s_nop 1
	v_max_u32_dpp v4, v4, v4 row_mirror row_mask:0xf bank_mask:0xf bound_ctrl:1
	v_cmp_eq_u32_e32 vcc, v3, v4
	v_cndmask_b32_e64 v5, v9, v4, s[40:41]
	s_nop 0
	v_cndmask_b32_e32 v2, v3, v2, vcc
	v_cmp_lt_i32_e32 vcc, -1, v83
	s_nop 0
	v_max_u32_dpp v2, v2, v2 quad_perm:[1,0,3,2] row_mask:0xf bank_mask:0xf bound_ctrl:1
	v_cndmask_b32_e64 v3, v78, -1, vcc
	v_cmp_lt_i32_e32 vcc, -1, v8
	v_max_u32_dpp v2, v2, v2 quad_perm:[2,3,0,1] row_mask:0xf bank_mask:0xf bound_ctrl:1
	v_bitop3_b32 v3, v3, v83, s71 bitop3:0x78
	s_nop 0
	v_max_u32_dpp v2, v2, v2 row_half_mirror row_mask:0xf bank_mask:0xf bound_ctrl:1
	s_nop 1
	v_max_u32_dpp v2, v2, v2 row_mirror row_mask:0xf bank_mask:0xf bound_ctrl:1
	v_cndmask_b32_e64 v4, v5, v2, s[42:43]
	v_cndmask_b32_e64 v5, v78, -1, vcc
	v_bitop3_b32 v5, v5, v8, s71 bitop3:0x78
	ds_write_b32 v62, v5
	v_bitop3_b32 v5, v83, s63, v83 bitop3:0xc
	ds_write_b32 v62, v5 offset:64
	v_bitop3_b32 v5, v8, s63, v8 bitop3:0xc
	ds_write_b32 v62, v5 offset:128
	ds_read_b32 v5, v60
	v_add_u32_e32 v2, v64, v53
	v_add_u32_e32 v53, 0x80, v53
	s_waitcnt lgkmcnt(0)
	v_add_f32_e32 v5, v5, v3
	v_ashrrev_i32_e32 v8, 31, v5
	v_bitop3_b32 v5, v8, v5, s70 bitop3:0x36
	v_and_or_b32 v5, v5, s77, v63
	s_nop 1
	v_max_u32_dpp v8, v5, v5 quad_perm:[1,0,3,2] row_mask:0xf bank_mask:0xf bound_ctrl:1
	s_nop 1
	v_max_u32_dpp v8, v8, v8 quad_perm:[2,3,0,1] row_mask:0xf bank_mask:0xf bound_ctrl:1
	s_nop 1
	v_max_u32_dpp v8, v8, v8 row_half_mirror row_mask:0xf bank_mask:0xf bound_ctrl:1
	s_nop 1
	v_max_u32_dpp v8, v8, v8 row_mirror row_mask:0xf bank_mask:0xf bound_ctrl:1
	v_cmp_eq_u32_e32 vcc, v5, v8
	v_cndmask_b32_e64 v9, 0, v8, s[10:11]
	s_nop 0
	v_cndmask_b32_e64 v5, 0, 1, vcc
	v_lshl_add_u32 v10, v5, 2, v60
	ds_read_b32 v11, v10
	v_subbrev_co_u32_e32 v8, vcc, 0, v63, vcc
	s_waitcnt lgkmcnt(0)
	v_add_f32_e32 v11, v11, v3
	v_ashrrev_i32_e32 v12, 31, v11
	v_bitop3_b32 v11, v12, v11, s70 bitop3:0x36
	v_and_or_b32 v8, v11, s77, v8
	s_nop 1
	v_max_u32_dpp v11, v8, v8 quad_perm:[1,0,3,2] row_mask:0xf bank_mask:0xf bound_ctrl:1
	s_nop 1
	v_max_u32_dpp v11, v11, v11 quad_perm:[2,3,0,1] row_mask:0xf bank_mask:0xf bound_ctrl:1
	s_nop 1
	v_max_u32_dpp v11, v11, v11 row_half_mirror row_mask:0xf bank_mask:0xf bound_ctrl:1
	s_nop 1
	v_max_u32_dpp v11, v11, v11 row_mirror row_mask:0xf bank_mask:0xf bound_ctrl:1
	v_cmp_eq_u32_e32 vcc, v8, v11
	v_cndmask_b32_e64 v9, v9, v11, s[12:13]
	s_nop 0
	v_cndmask_b32_e64 v8, 0, 1, vcc
	v_lshl_add_u32 v10, v8, 2, v10
	ds_read_b32 v13, v10
	v_addc_co_u32_e32 v11, vcc, 0, v5, vcc
	v_sub_u32_e32 v12, v63, v11
	s_waitcnt lgkmcnt(0)
	v_add_f32_e32 v13, v13, v3
	v_ashrrev_i32_e32 v14, 31, v13
	v_bitop3_b32 v13, v14, v13, s70 bitop3:0x36
	v_and_or_b32 v12, v13, s77, v12
	s_nop 1
	v_max_u32_dpp v13, v12, v12 quad_perm:[1,0,3,2] row_mask:0xf bank_mask:0xf bound_ctrl:1
	s_nop 1
	v_max_u32_dpp v13, v13, v13 quad_perm:[2,3,0,1] row_mask:0xf bank_mask:0xf bound_ctrl:1
	s_nop 1
	v_max_u32_dpp v13, v13, v13 row_half_mirror row_mask:0xf bank_mask:0xf bound_ctrl:1
	s_nop 1
	v_max_u32_dpp v13, v13, v13 row_mirror row_mask:0xf bank_mask:0xf bound_ctrl:1
	v_cmp_eq_u32_e32 vcc, v12, v13
	v_cndmask_b32_e64 v9, v9, v13, s[14:15]
	s_nop 0
	v_cndmask_b32_e64 v12, 0, 1, vcc
	v_lshl_add_u32 v10, v12, 2, v10
	ds_read_b32 v13, v10
	v_addc_co_u32_e32 v5, vcc, v8, v5, vcc
	v_sub_u32_e32 v8, v63, v5
	s_waitcnt lgkmcnt(0)
	v_add_f32_e32 v13, v13, v3
	v_ashrrev_i32_e32 v14, 31, v13
	v_bitop3_b32 v13, v14, v13, s70 bitop3:0x36
	v_and_or_b32 v8, v13, s77, v8
	s_nop 1
	v_max_u32_dpp v13, v8, v8 quad_perm:[1,0,3,2] row_mask:0xf bank_mask:0xf bound_ctrl:1
	s_nop 1
	v_max_u32_dpp v13, v13, v13 quad_perm:[2,3,0,1] row_mask:0xf bank_mask:0xf bound_ctrl:1
	s_nop 1
	v_max_u32_dpp v13, v13, v13 row_half_mirror row_mask:0xf bank_mask:0xf bound_ctrl:1
	s_nop 1
	v_max_u32_dpp v13, v13, v13 row_mirror row_mask:0xf bank_mask:0xf bound_ctrl:1
	v_cmp_eq_u32_e32 vcc, v8, v13
	v_cndmask_b32_e64 v9, v9, v13, s[16:17]
	s_nop 0
	v_cndmask_b32_e64 v8, 0, 1, vcc
	v_lshl_add_u32 v10, v8, 2, v10
	ds_read_b32 v13, v10
	v_addc_co_u32_e32 v11, vcc, v11, v12, vcc
	v_sub_u32_e32 v12, v63, v11
	s_waitcnt lgkmcnt(0)
	v_add_f32_e32 v13, v13, v3
	v_ashrrev_i32_e32 v14, 31, v13
	v_bitop3_b32 v13, v14, v13, s70 bitop3:0x36
	v_and_or_b32 v12, v13, s77, v12
	s_nop 1
	v_max_u32_dpp v13, v12, v12 quad_perm:[1,0,3,2] row_mask:0xf bank_mask:0xf bound_ctrl:1
	s_nop 1
	v_max_u32_dpp v13, v13, v13 quad_perm:[2,3,0,1] row_mask:0xf bank_mask:0xf bound_ctrl:1
	s_nop 1
	v_max_u32_dpp v13, v13, v13 row_half_mirror row_mask:0xf bank_mask:0xf bound_ctrl:1
	s_nop 1
	v_max_u32_dpp v13, v13, v13 row_mirror row_mask:0xf bank_mask:0xf bound_ctrl:1
	v_cmp_eq_u32_e32 vcc, v12, v13
	v_cndmask_b32_e64 v9, v9, v13, s[18:19]
	s_nop 0
	v_cndmask_b32_e64 v12, 0, 1, vcc
	v_lshl_add_u32 v10, v12, 2, v10
	ds_read_b32 v13, v10
	v_addc_co_u32_e32 v5, vcc, v5, v8, vcc
	v_sub_u32_e32 v8, v63, v5
	s_waitcnt lgkmcnt(0)
	v_add_f32_e32 v13, v13, v3
	v_ashrrev_i32_e32 v14, 31, v13
	v_bitop3_b32 v13, v14, v13, s70 bitop3:0x36
	v_and_or_b32 v8, v13, s77, v8
	s_nop 1
	v_max_u32_dpp v13, v8, v8 quad_perm:[1,0,3,2] row_mask:0xf bank_mask:0xf bound_ctrl:1
	s_nop 1
	v_max_u32_dpp v13, v13, v13 quad_perm:[2,3,0,1] row_mask:0xf bank_mask:0xf bound_ctrl:1
	s_nop 1
	v_max_u32_dpp v13, v13, v13 row_half_mirror row_mask:0xf bank_mask:0xf bound_ctrl:1
	s_nop 1
	v_max_u32_dpp v13, v13, v13 row_mirror row_mask:0xf bank_mask:0xf bound_ctrl:1
	v_cmp_eq_u32_e32 vcc, v8, v13
	v_cndmask_b32_e64 v9, v9, v13, s[20:21]
	s_nop 0
	v_cndmask_b32_e64 v8, 0, 1, vcc
	v_lshl_add_u32 v10, v8, 2, v10
	ds_read_b32 v13, v10
	v_addc_co_u32_e32 v11, vcc, v11, v12, vcc
	v_sub_u32_e32 v12, v63, v11
	s_waitcnt lgkmcnt(0)
	v_add_f32_e32 v13, v13, v3
	v_ashrrev_i32_e32 v14, 31, v13
	v_bitop3_b32 v13, v14, v13, s70 bitop3:0x36
	v_and_or_b32 v12, v13, s77, v12
	s_nop 1
	v_max_u32_dpp v13, v12, v12 quad_perm:[1,0,3,2] row_mask:0xf bank_mask:0xf bound_ctrl:1
	s_nop 1
	v_max_u32_dpp v13, v13, v13 quad_perm:[2,3,0,1] row_mask:0xf bank_mask:0xf bound_ctrl:1
	s_nop 1
	v_max_u32_dpp v13, v13, v13 row_half_mirror row_mask:0xf bank_mask:0xf bound_ctrl:1
	s_nop 1
	v_max_u32_dpp v13, v13, v13 row_mirror row_mask:0xf bank_mask:0xf bound_ctrl:1
	v_cmp_eq_u32_e32 vcc, v12, v13
	v_cndmask_b32_e64 v9, v9, v13, s[22:23]
	s_nop 0
	v_cndmask_b32_e64 v12, 0, 1, vcc
	v_lshl_add_u32 v10, v12, 2, v10
	ds_read_b32 v13, v10
	v_addc_co_u32_e32 v5, vcc, v5, v8, vcc
	v_sub_u32_e32 v8, v63, v5
	s_waitcnt lgkmcnt(0)
	v_add_f32_e32 v13, v13, v3
	v_ashrrev_i32_e32 v14, 31, v13
	v_bitop3_b32 v13, v14, v13, s70 bitop3:0x36
	v_and_or_b32 v8, v13, s77, v8
	s_nop 1
	v_max_u32_dpp v13, v8, v8 quad_perm:[1,0,3,2] row_mask:0xf bank_mask:0xf bound_ctrl:1
	s_nop 1
	v_max_u32_dpp v13, v13, v13 quad_perm:[2,3,0,1] row_mask:0xf bank_mask:0xf bound_ctrl:1
	s_nop 1
	v_max_u32_dpp v13, v13, v13 row_half_mirror row_mask:0xf bank_mask:0xf bound_ctrl:1
	s_nop 1
	v_max_u32_dpp v13, v13, v13 row_mirror row_mask:0xf bank_mask:0xf bound_ctrl:1
	v_cmp_eq_u32_e32 vcc, v8, v13
	v_cndmask_b32_e64 v9, v9, v13, s[24:25]
	s_nop 0
	v_cndmask_b32_e64 v8, 0, 1, vcc
	v_lshl_add_u32 v10, v8, 2, v10
	ds_read_b32 v13, v10
	v_addc_co_u32_e32 v11, vcc, v11, v12, vcc
	v_sub_u32_e32 v12, v63, v11
	s_waitcnt lgkmcnt(0)
	v_add_f32_e32 v13, v13, v3
	v_ashrrev_i32_e32 v14, 31, v13
	v_bitop3_b32 v13, v14, v13, s70 bitop3:0x36
	v_and_or_b32 v12, v13, s77, v12
	s_nop 1
	v_max_u32_dpp v13, v12, v12 quad_perm:[1,0,3,2] row_mask:0xf bank_mask:0xf bound_ctrl:1
	s_nop 1
	v_max_u32_dpp v13, v13, v13 quad_perm:[2,3,0,1] row_mask:0xf bank_mask:0xf bound_ctrl:1
	s_nop 1
	v_max_u32_dpp v13, v13, v13 row_half_mirror row_mask:0xf bank_mask:0xf bound_ctrl:1
	s_nop 1
	v_max_u32_dpp v13, v13, v13 row_mirror row_mask:0xf bank_mask:0xf bound_ctrl:1
	v_cmp_eq_u32_e32 vcc, v12, v13
	v_cndmask_b32_e64 v9, v9, v13, s[26:27]
	s_nop 0
	v_cndmask_b32_e64 v12, 0, 1, vcc
	v_lshl_add_u32 v10, v12, 2, v10
	ds_read_b32 v13, v10
	v_addc_co_u32_e32 v5, vcc, v5, v8, vcc
	v_sub_u32_e32 v8, v63, v5
	s_waitcnt lgkmcnt(0)
	v_add_f32_e32 v13, v13, v3
	v_ashrrev_i32_e32 v14, 31, v13
	v_bitop3_b32 v13, v14, v13, s70 bitop3:0x36
	v_and_or_b32 v8, v13, s77, v8
	s_nop 1
	v_max_u32_dpp v13, v8, v8 quad_perm:[1,0,3,2] row_mask:0xf bank_mask:0xf bound_ctrl:1
	s_nop 1
	v_max_u32_dpp v13, v13, v13 quad_perm:[2,3,0,1] row_mask:0xf bank_mask:0xf bound_ctrl:1
	s_nop 1
	v_max_u32_dpp v13, v13, v13 row_half_mirror row_mask:0xf bank_mask:0xf bound_ctrl:1
	s_nop 1
	v_max_u32_dpp v13, v13, v13 row_mirror row_mask:0xf bank_mask:0xf bound_ctrl:1
	v_cmp_eq_u32_e32 vcc, v8, v13
	v_cndmask_b32_e64 v9, v9, v13, s[28:29]
	s_nop 0
	v_cndmask_b32_e64 v8, 0, 1, vcc
	v_lshl_add_u32 v10, v8, 2, v10
	ds_read_b32 v13, v10
	v_addc_co_u32_e32 v11, vcc, v11, v12, vcc
	v_sub_u32_e32 v12, v63, v11
	s_waitcnt lgkmcnt(0)
	v_add_f32_e32 v13, v13, v3
	v_ashrrev_i32_e32 v14, 31, v13
	v_bitop3_b32 v13, v14, v13, s70 bitop3:0x36
	v_and_or_b32 v12, v13, s77, v12
	s_nop 1
	v_max_u32_dpp v13, v12, v12 quad_perm:[1,0,3,2] row_mask:0xf bank_mask:0xf bound_ctrl:1
	s_nop 1
	v_max_u32_dpp v13, v13, v13 quad_perm:[2,3,0,1] row_mask:0xf bank_mask:0xf bound_ctrl:1
	s_nop 1
	v_max_u32_dpp v13, v13, v13 row_half_mirror row_mask:0xf bank_mask:0xf bound_ctrl:1
	s_nop 1
	v_max_u32_dpp v13, v13, v13 row_mirror row_mask:0xf bank_mask:0xf bound_ctrl:1
	v_cmp_eq_u32_e32 vcc, v12, v13
	v_cndmask_b32_e64 v9, v9, v13, s[30:31]
	s_nop 0
	v_cndmask_b32_e64 v12, 0, 1, vcc
	v_lshl_add_u32 v10, v12, 2, v10
	ds_read_b32 v13, v10
	v_addc_co_u32_e32 v5, vcc, v5, v8, vcc
	v_sub_u32_e32 v8, v63, v5
	s_waitcnt lgkmcnt(0)
	v_add_f32_e32 v13, v13, v3
	v_ashrrev_i32_e32 v14, 31, v13
	v_bitop3_b32 v13, v14, v13, s70 bitop3:0x36
	v_and_or_b32 v8, v13, s77, v8
	s_nop 1
	v_max_u32_dpp v13, v8, v8 quad_perm:[1,0,3,2] row_mask:0xf bank_mask:0xf bound_ctrl:1
	s_nop 1
	v_max_u32_dpp v13, v13, v13 quad_perm:[2,3,0,1] row_mask:0xf bank_mask:0xf bound_ctrl:1
	s_nop 1
	v_max_u32_dpp v13, v13, v13 row_half_mirror row_mask:0xf bank_mask:0xf bound_ctrl:1
	s_nop 1
	v_max_u32_dpp v13, v13, v13 row_mirror row_mask:0xf bank_mask:0xf bound_ctrl:1
	v_cmp_eq_u32_e32 vcc, v8, v13
	v_cndmask_b32_e64 v9, v9, v13, s[34:35]
	s_nop 0
	v_cndmask_b32_e64 v8, 0, 1, vcc
	v_lshl_add_u32 v10, v8, 2, v10
	ds_read_b32 v13, v10
	v_addc_co_u32_e32 v11, vcc, v11, v12, vcc
	v_sub_u32_e32 v12, v63, v11
	s_waitcnt lgkmcnt(0)
	v_add_f32_e32 v13, v13, v3
	v_ashrrev_i32_e32 v14, 31, v13
	v_bitop3_b32 v13, v14, v13, s70 bitop3:0x36
	v_and_or_b32 v12, v13, s77, v12
	s_nop 1
	v_max_u32_dpp v13, v12, v12 quad_perm:[1,0,3,2] row_mask:0xf bank_mask:0xf bound_ctrl:1
	s_nop 1
	v_max_u32_dpp v13, v13, v13 quad_perm:[2,3,0,1] row_mask:0xf bank_mask:0xf bound_ctrl:1
	s_nop 1
	v_max_u32_dpp v13, v13, v13 row_half_mirror row_mask:0xf bank_mask:0xf bound_ctrl:1
	s_nop 1
	v_max_u32_dpp v13, v13, v13 row_mirror row_mask:0xf bank_mask:0xf bound_ctrl:1
	v_cmp_eq_u32_e32 vcc, v12, v13
	v_cndmask_b32_e64 v9, v9, v13, s[36:37]
	s_nop 0
	v_cndmask_b32_e64 v12, 0, 1, vcc
	v_lshl_add_u32 v10, v12, 2, v10
	ds_read_b32 v13, v10
	v_addc_co_u32_e32 v5, vcc, v5, v8, vcc
	v_sub_u32_e32 v8, v63, v5
	s_waitcnt lgkmcnt(0)
	v_add_f32_e32 v13, v13, v3
	v_ashrrev_i32_e32 v14, 31, v13
	v_bitop3_b32 v13, v14, v13, s70 bitop3:0x36
	v_and_or_b32 v8, v13, s77, v8
	s_nop 1
	v_max_u32_dpp v13, v8, v8 quad_perm:[1,0,3,2] row_mask:0xf bank_mask:0xf bound_ctrl:1
	s_nop 1
	v_max_u32_dpp v13, v13, v13 quad_perm:[2,3,0,1] row_mask:0xf bank_mask:0xf bound_ctrl:1
	s_nop 1
	v_max_u32_dpp v13, v13, v13 row_half_mirror row_mask:0xf bank_mask:0xf bound_ctrl:1
	s_nop 1
	v_max_u32_dpp v13, v13, v13 row_mirror row_mask:0xf bank_mask:0xf bound_ctrl:1
	v_cmp_eq_u32_e32 vcc, v8, v13
	v_cndmask_b32_e64 v9, v9, v13, s[38:39]
	s_nop 0
	v_cndmask_b32_e64 v8, 0, 1, vcc
	v_lshl_add_u32 v10, v8, 2, v10
	v_addc_co_u32_e32 v11, vcc, v11, v12, vcc
	ds_read_b32 v12, v10
	v_sub_u32_e32 v11, v63, v11
	s_waitcnt lgkmcnt(0)
	v_add_f32_e32 v12, v12, v3
	v_ashrrev_i32_e32 v13, 31, v12
	v_bitop3_b32 v12, v13, v12, s70 bitop3:0x36
	v_and_or_b32 v11, v12, s77, v11
	s_nop 1
	v_max_u32_dpp v12, v11, v11 quad_perm:[1,0,3,2] row_mask:0xf bank_mask:0xf bound_ctrl:1
	s_nop 1
	v_max_u32_dpp v12, v12, v12 quad_perm:[2,3,0,1] row_mask:0xf bank_mask:0xf bound_ctrl:1
	s_nop 1
	v_max_u32_dpp v12, v12, v12 row_half_mirror row_mask:0xf bank_mask:0xf bound_ctrl:1
	s_nop 1
	v_max_u32_dpp v12, v12, v12 row_mirror row_mask:0xf bank_mask:0xf bound_ctrl:1
	v_cmp_eq_u32_e32 vcc, v11, v12
	v_cndmask_b32_e64 v9, v9, v12, s[40:41]
	s_nop 0
	v_cndmask_b32_e64 v11, 0, 1, vcc
	v_addc_co_u32_e32 v5, vcc, v5, v8, vcc
	v_lshl_add_u32 v8, v11, 2, v10
	ds_read_b32 v8, v8
	v_sub_u32_e32 v5, v63, v5
	s_waitcnt lgkmcnt(0)
	v_add_f32_e32 v3, v8, v3
	v_ashrrev_i32_e32 v8, 31, v3
	v_bitop3_b32 v3, v8, v3, s70 bitop3:0x36
	v_and_or_b32 v3, v3, s77, v5
	s_nop 1
	v_max_u32_dpp v3, v3, v3 quad_perm:[1,0,3,2] row_mask:0xf bank_mask:0xf bound_ctrl:1
	s_nop 1
	v_max_u32_dpp v3, v3, v3 quad_perm:[2,3,0,1] row_mask:0xf bank_mask:0xf bound_ctrl:1
	s_nop 1
	v_max_u32_dpp v3, v3, v3 row_half_mirror row_mask:0xf bank_mask:0xf bound_ctrl:1
	s_nop 1
	v_max_u32_dpp v3, v3, v3 row_mirror row_mask:0xf bank_mask:0xf bound_ctrl:1
	v_cndmask_b32_e64 v3, v9, v3, s[42:43]
	v_cmp_lt_i32_e32 vcc, -1, v3
	v_not_b32_e32 v5, v3
	v_bitop3_b32 v9, v3, 15, v3 bitop3:0xc
	v_cndmask_b32_e64 v8, v78, -1, vcc
	v_bitop3_b32 v8, v8, v3, s77 bitop3:0x78
	v_max_u32_dpp v3, v3, v3 quad_perm:[1,0,3,2] row_mask:0xf bank_mask:0xf bound_ctrl:1
	v_lshrrev_b32_e32 v5, 2, v5
	v_and_b32_e32 v5, 60, v5
	v_max_u32_dpp v3, v3, v3 quad_perm:[2,3,0,1] row_mask:0xf bank_mask:0xf bound_ctrl:1
	v_add_u32_e32 v5, v60, v5
	v_lshl_add_u32 v9, v9, 2, v60
	v_max_u32_dpp v3, v3, v3 row_half_mirror row_mask:0xf bank_mask:0xf bound_ctrl:1
	ds_read_b32 v5, v5 offset:64
	ds_read_b32 v9, v9 offset:128
	v_max_u32_dpp v3, v3, v3 row_mirror row_mask:0xf bank_mask:0xf bound_ctrl:1
	v_cmp_lt_i32_e32 vcc, -1, v3
	s_waitcnt lgkmcnt(0)
	v_lshl_add_u32 v5, v5, 7, v9
	v_cndmask_b32_e64 v10, v78, -1, vcc
	v_bitop3_b32 v3, v10, v3, s77 bitop3:0x78
	v_sub_f32_e32 v3, v8, v3
	v_mul_f32_e32 v3, 0x3fb8aa3b, v3
	v_exp_f32_e32 v12, v3
	s_nop 1
	v_add_f32_dpp v3, v12, v12 quad_perm:[1,0,3,2] row_mask:0xf bank_mask:0xf bound_ctrl:1
	s_nop 1
	v_add_f32_dpp v3, v3, v3 quad_perm:[2,3,0,1] row_mask:0xf bank_mask:0xf bound_ctrl:1
	s_nop 1
	v_add_f32_dpp v3, v3, v3 row_half_mirror row_mask:0xf bank_mask:0xf bound_ctrl:1
	s_nop 1
	v_add_f32_dpp v13, v3, v3 row_mirror row_mask:0xf bank_mask:0xf bound_ctrl:1
	v_ashrrev_i32_e32 v3, 31, v2
	v_lshlrev_b64 v[8:9], 9, v[2:3]
	v_or_b32_e32 v8, v8, v79
	v_lshl_add_u64 v[10:11], s[44:45], 0, v[8:9]
	v_div_scale_f32 v3, s[54:55], v13, v13, v12
	global_store_dword v[10:11], v5, off
	v_rcp_f32_e32 v5, v3
	v_lshl_add_u64 v[8:9], s[48:49], 0, v[8:9]
	v_fma_f32 v10, -v3, v5, 1.0
	v_fmac_f32_e32 v5, v10, v5
	v_div_scale_f32 v10, vcc, v12, v13, v12
	v_mul_f32_e32 v11, v10, v5
	v_fma_f32 v14, -v3, v11, v10
	v_fmac_f32_e32 v11, v14, v5
	v_fma_f32 v3, -v3, v11, v10
	v_div_fmas_f32 v3, v3, v5, v11
	v_div_fixup_f32 v3, v3, v13, v12
	v_cmp_lt_i32_e32 vcc, -1, v82
	global_store_dword v[8:9], v3, off
	s_nop 0
	v_cndmask_b32_e64 v3, v78, -1, vcc
	v_cmp_lt_i32_e32 vcc, -1, v7
	v_bitop3_b32 v3, v3, v82, s71 bitop3:0x78
	s_nop 0
	v_cndmask_b32_e64 v5, v78, -1, vcc
	v_bitop3_b32 v5, v5, v7, s71 bitop3:0x78
	ds_write_b32 v62, v5
	v_bitop3_b32 v5, v82, s63, v82 bitop3:0xc
	ds_write_b32 v62, v5 offset:64
	v_bitop3_b32 v5, v7, s63, v7 bitop3:0xc
	ds_write_b32 v62, v5 offset:128
	ds_read_b32 v5, v60
	s_waitcnt lgkmcnt(0)
	v_add_f32_e32 v5, v5, v3
	v_ashrrev_i32_e32 v7, 31, v5
	v_bitop3_b32 v5, v7, v5, s70 bitop3:0x36
	v_and_or_b32 v5, v5, s77, v63
	s_nop 1
	v_max_u32_dpp v7, v5, v5 quad_perm:[1,0,3,2] row_mask:0xf bank_mask:0xf bound_ctrl:1
	s_nop 1
	v_max_u32_dpp v7, v7, v7 quad_perm:[2,3,0,1] row_mask:0xf bank_mask:0xf bound_ctrl:1
	s_nop 1
	v_max_u32_dpp v7, v7, v7 row_half_mirror row_mask:0xf bank_mask:0xf bound_ctrl:1
	s_nop 1
	v_max_u32_dpp v7, v7, v7 row_mirror row_mask:0xf bank_mask:0xf bound_ctrl:1
	v_cmp_eq_u32_e32 vcc, v5, v7
	v_cndmask_b32_e64 v8, 0, v7, s[10:11]
	s_nop 0
	v_cndmask_b32_e64 v5, 0, 1, vcc
	v_lshl_add_u32 v9, v5, 2, v60
	ds_read_b32 v10, v9
	v_subbrev_co_u32_e32 v7, vcc, 0, v63, vcc
	s_waitcnt lgkmcnt(0)
	v_add_f32_e32 v10, v10, v3
	v_ashrrev_i32_e32 v11, 31, v10
	v_bitop3_b32 v10, v11, v10, s70 bitop3:0x36
	v_and_or_b32 v7, v10, s77, v7
	s_nop 1
	v_max_u32_dpp v10, v7, v7 quad_perm:[1,0,3,2] row_mask:0xf bank_mask:0xf bound_ctrl:1
	s_nop 1
	v_max_u32_dpp v10, v10, v10 quad_perm:[2,3,0,1] row_mask:0xf bank_mask:0xf bound_ctrl:1
	s_nop 1
	v_max_u32_dpp v10, v10, v10 row_half_mirror row_mask:0xf bank_mask:0xf bound_ctrl:1
	s_nop 1
	v_max_u32_dpp v10, v10, v10 row_mirror row_mask:0xf bank_mask:0xf bound_ctrl:1
	v_cmp_eq_u32_e32 vcc, v7, v10
	v_cndmask_b32_e64 v8, v8, v10, s[12:13]
	s_nop 0
	v_cndmask_b32_e64 v7, 0, 1, vcc
	v_lshl_add_u32 v9, v7, 2, v9
	ds_read_b32 v12, v9
	v_addc_co_u32_e32 v10, vcc, 0, v5, vcc
	v_sub_u32_e32 v11, v63, v10
	s_waitcnt lgkmcnt(0)
	v_add_f32_e32 v12, v12, v3
	v_ashrrev_i32_e32 v13, 31, v12
	v_bitop3_b32 v12, v13, v12, s70 bitop3:0x36
	v_and_or_b32 v11, v12, s77, v11
	s_nop 1
	v_max_u32_dpp v12, v11, v11 quad_perm:[1,0,3,2] row_mask:0xf bank_mask:0xf bound_ctrl:1
	s_nop 1
	v_max_u32_dpp v12, v12, v12 quad_perm:[2,3,0,1] row_mask:0xf bank_mask:0xf bound_ctrl:1
	s_nop 1
	v_max_u32_dpp v12, v12, v12 row_half_mirror row_mask:0xf bank_mask:0xf bound_ctrl:1
	s_nop 1
	v_max_u32_dpp v12, v12, v12 row_mirror row_mask:0xf bank_mask:0xf bound_ctrl:1
	v_cmp_eq_u32_e32 vcc, v11, v12
	v_cndmask_b32_e64 v8, v8, v12, s[14:15]
	s_nop 0
	v_cndmask_b32_e64 v11, 0, 1, vcc
	v_lshl_add_u32 v9, v11, 2, v9
	ds_read_b32 v12, v9
	v_addc_co_u32_e32 v5, vcc, v7, v5, vcc
	v_sub_u32_e32 v7, v63, v5
	s_waitcnt lgkmcnt(0)
	v_add_f32_e32 v12, v12, v3
	v_ashrrev_i32_e32 v13, 31, v12
	v_bitop3_b32 v12, v13, v12, s70 bitop3:0x36
	v_and_or_b32 v7, v12, s77, v7
	s_nop 1
	v_max_u32_dpp v12, v7, v7 quad_perm:[1,0,3,2] row_mask:0xf bank_mask:0xf bound_ctrl:1
	s_nop 1
	v_max_u32_dpp v12, v12, v12 quad_perm:[2,3,0,1] row_mask:0xf bank_mask:0xf bound_ctrl:1
	s_nop 1
	v_max_u32_dpp v12, v12, v12 row_half_mirror row_mask:0xf bank_mask:0xf bound_ctrl:1
	s_nop 1
	v_max_u32_dpp v12, v12, v12 row_mirror row_mask:0xf bank_mask:0xf bound_ctrl:1
	v_cmp_eq_u32_e32 vcc, v7, v12
	v_cndmask_b32_e64 v8, v8, v12, s[16:17]
	s_nop 0
	v_cndmask_b32_e64 v7, 0, 1, vcc
	v_lshl_add_u32 v9, v7, 2, v9
	ds_read_b32 v12, v9
	v_addc_co_u32_e32 v10, vcc, v10, v11, vcc
	v_sub_u32_e32 v11, v63, v10
	s_waitcnt lgkmcnt(0)
	v_add_f32_e32 v12, v12, v3
	v_ashrrev_i32_e32 v13, 31, v12
	v_bitop3_b32 v12, v13, v12, s70 bitop3:0x36
	v_and_or_b32 v11, v12, s77, v11
	s_nop 1
	v_max_u32_dpp v12, v11, v11 quad_perm:[1,0,3,2] row_mask:0xf bank_mask:0xf bound_ctrl:1
	s_nop 1
	v_max_u32_dpp v12, v12, v12 quad_perm:[2,3,0,1] row_mask:0xf bank_mask:0xf bound_ctrl:1
	s_nop 1
	v_max_u32_dpp v12, v12, v12 row_half_mirror row_mask:0xf bank_mask:0xf bound_ctrl:1
	s_nop 1
	v_max_u32_dpp v12, v12, v12 row_mirror row_mask:0xf bank_mask:0xf bound_ctrl:1
	v_cmp_eq_u32_e32 vcc, v11, v12
	v_cndmask_b32_e64 v8, v8, v12, s[18:19]
	s_nop 0
	v_cndmask_b32_e64 v11, 0, 1, vcc
	v_lshl_add_u32 v9, v11, 2, v9
	ds_read_b32 v12, v9
	v_addc_co_u32_e32 v5, vcc, v5, v7, vcc
	v_sub_u32_e32 v7, v63, v5
	s_waitcnt lgkmcnt(0)
	v_add_f32_e32 v12, v12, v3
	v_ashrrev_i32_e32 v13, 31, v12
	v_bitop3_b32 v12, v13, v12, s70 bitop3:0x36
	v_and_or_b32 v7, v12, s77, v7
	s_nop 1
	v_max_u32_dpp v12, v7, v7 quad_perm:[1,0,3,2] row_mask:0xf bank_mask:0xf bound_ctrl:1
	s_nop 1
	v_max_u32_dpp v12, v12, v12 quad_perm:[2,3,0,1] row_mask:0xf bank_mask:0xf bound_ctrl:1
	s_nop 1
	v_max_u32_dpp v12, v12, v12 row_half_mirror row_mask:0xf bank_mask:0xf bound_ctrl:1
	s_nop 1
	v_max_u32_dpp v12, v12, v12 row_mirror row_mask:0xf bank_mask:0xf bound_ctrl:1
	v_cmp_eq_u32_e32 vcc, v7, v12
	v_cndmask_b32_e64 v8, v8, v12, s[20:21]
	s_nop 0
	v_cndmask_b32_e64 v7, 0, 1, vcc
	v_lshl_add_u32 v9, v7, 2, v9
	ds_read_b32 v12, v9
	v_addc_co_u32_e32 v10, vcc, v10, v11, vcc
	v_sub_u32_e32 v11, v63, v10
	s_waitcnt lgkmcnt(0)
	v_add_f32_e32 v12, v12, v3
	v_ashrrev_i32_e32 v13, 31, v12
	v_bitop3_b32 v12, v13, v12, s70 bitop3:0x36
	v_and_or_b32 v11, v12, s77, v11
	s_nop 1
	v_max_u32_dpp v12, v11, v11 quad_perm:[1,0,3,2] row_mask:0xf bank_mask:0xf bound_ctrl:1
	s_nop 1
	v_max_u32_dpp v12, v12, v12 quad_perm:[2,3,0,1] row_mask:0xf bank_mask:0xf bound_ctrl:1
	s_nop 1
	v_max_u32_dpp v12, v12, v12 row_half_mirror row_mask:0xf bank_mask:0xf bound_ctrl:1
	s_nop 1
	v_max_u32_dpp v12, v12, v12 row_mirror row_mask:0xf bank_mask:0xf bound_ctrl:1
	v_cmp_eq_u32_e32 vcc, v11, v12
	v_cndmask_b32_e64 v8, v8, v12, s[22:23]
	s_nop 0
	v_cndmask_b32_e64 v11, 0, 1, vcc
	v_lshl_add_u32 v9, v11, 2, v9
	ds_read_b32 v12, v9
	v_addc_co_u32_e32 v5, vcc, v5, v7, vcc
	v_sub_u32_e32 v7, v63, v5
	s_waitcnt lgkmcnt(0)
	v_add_f32_e32 v12, v12, v3
	v_ashrrev_i32_e32 v13, 31, v12
	v_bitop3_b32 v12, v13, v12, s70 bitop3:0x36
	v_and_or_b32 v7, v12, s77, v7
	s_nop 1
	v_max_u32_dpp v12, v7, v7 quad_perm:[1,0,3,2] row_mask:0xf bank_mask:0xf bound_ctrl:1
	s_nop 1
	v_max_u32_dpp v12, v12, v12 quad_perm:[2,3,0,1] row_mask:0xf bank_mask:0xf bound_ctrl:1
	s_nop 1
	v_max_u32_dpp v12, v12, v12 row_half_mirror row_mask:0xf bank_mask:0xf bound_ctrl:1
	s_nop 1
	v_max_u32_dpp v12, v12, v12 row_mirror row_mask:0xf bank_mask:0xf bound_ctrl:1
	v_cmp_eq_u32_e32 vcc, v7, v12
	v_cndmask_b32_e64 v8, v8, v12, s[24:25]
	s_nop 0
	v_cndmask_b32_e64 v7, 0, 1, vcc
	v_lshl_add_u32 v9, v7, 2, v9
	ds_read_b32 v12, v9
	v_addc_co_u32_e32 v10, vcc, v10, v11, vcc
	v_sub_u32_e32 v11, v63, v10
	s_waitcnt lgkmcnt(0)
	v_add_f32_e32 v12, v12, v3
	v_ashrrev_i32_e32 v13, 31, v12
	v_bitop3_b32 v12, v13, v12, s70 bitop3:0x36
	v_and_or_b32 v11, v12, s77, v11
	s_nop 1
	v_max_u32_dpp v12, v11, v11 quad_perm:[1,0,3,2] row_mask:0xf bank_mask:0xf bound_ctrl:1
	s_nop 1
	v_max_u32_dpp v12, v12, v12 quad_perm:[2,3,0,1] row_mask:0xf bank_mask:0xf bound_ctrl:1
	s_nop 1
	v_max_u32_dpp v12, v12, v12 row_half_mirror row_mask:0xf bank_mask:0xf bound_ctrl:1
	s_nop 1
	v_max_u32_dpp v12, v12, v12 row_mirror row_mask:0xf bank_mask:0xf bound_ctrl:1
	v_cmp_eq_u32_e32 vcc, v11, v12
	v_cndmask_b32_e64 v8, v8, v12, s[26:27]
	s_nop 0
	v_cndmask_b32_e64 v11, 0, 1, vcc
	v_lshl_add_u32 v9, v11, 2, v9
	ds_read_b32 v12, v9
	v_addc_co_u32_e32 v5, vcc, v5, v7, vcc
	v_sub_u32_e32 v7, v63, v5
	s_waitcnt lgkmcnt(0)
	v_add_f32_e32 v12, v12, v3
	v_ashrrev_i32_e32 v13, 31, v12
	v_bitop3_b32 v12, v13, v12, s70 bitop3:0x36
	v_and_or_b32 v7, v12, s77, v7
	s_nop 1
	v_max_u32_dpp v12, v7, v7 quad_perm:[1,0,3,2] row_mask:0xf bank_mask:0xf bound_ctrl:1
	s_nop 1
	v_max_u32_dpp v12, v12, v12 quad_perm:[2,3,0,1] row_mask:0xf bank_mask:0xf bound_ctrl:1
	s_nop 1
	v_max_u32_dpp v12, v12, v12 row_half_mirror row_mask:0xf bank_mask:0xf bound_ctrl:1
	s_nop 1
	v_max_u32_dpp v12, v12, v12 row_mirror row_mask:0xf bank_mask:0xf bound_ctrl:1
	v_cmp_eq_u32_e32 vcc, v7, v12
	v_cndmask_b32_e64 v8, v8, v12, s[28:29]
	s_nop 0
	v_cndmask_b32_e64 v7, 0, 1, vcc
	v_lshl_add_u32 v9, v7, 2, v9
	ds_read_b32 v12, v9
	v_addc_co_u32_e32 v10, vcc, v10, v11, vcc
	v_sub_u32_e32 v11, v63, v10
	s_waitcnt lgkmcnt(0)
	v_add_f32_e32 v12, v12, v3
	v_ashrrev_i32_e32 v13, 31, v12
	v_bitop3_b32 v12, v13, v12, s70 bitop3:0x36
	v_and_or_b32 v11, v12, s77, v11
	s_nop 1
	v_max_u32_dpp v12, v11, v11 quad_perm:[1,0,3,2] row_mask:0xf bank_mask:0xf bound_ctrl:1
	s_nop 1
	v_max_u32_dpp v12, v12, v12 quad_perm:[2,3,0,1] row_mask:0xf bank_mask:0xf bound_ctrl:1
	s_nop 1
	v_max_u32_dpp v12, v12, v12 row_half_mirror row_mask:0xf bank_mask:0xf bound_ctrl:1
	s_nop 1
	v_max_u32_dpp v12, v12, v12 row_mirror row_mask:0xf bank_mask:0xf bound_ctrl:1
	v_cmp_eq_u32_e32 vcc, v11, v12
	v_cndmask_b32_e64 v8, v8, v12, s[30:31]
	s_nop 0
	v_cndmask_b32_e64 v11, 0, 1, vcc
	v_lshl_add_u32 v9, v11, 2, v9
	ds_read_b32 v12, v9
	v_addc_co_u32_e32 v5, vcc, v5, v7, vcc
	v_sub_u32_e32 v7, v63, v5
	s_waitcnt lgkmcnt(0)
	v_add_f32_e32 v12, v12, v3
	v_ashrrev_i32_e32 v13, 31, v12
	v_bitop3_b32 v12, v13, v12, s70 bitop3:0x36
	v_and_or_b32 v7, v12, s77, v7
	s_nop 1
	v_max_u32_dpp v12, v7, v7 quad_perm:[1,0,3,2] row_mask:0xf bank_mask:0xf bound_ctrl:1
	s_nop 1
	v_max_u32_dpp v12, v12, v12 quad_perm:[2,3,0,1] row_mask:0xf bank_mask:0xf bound_ctrl:1
	s_nop 1
	v_max_u32_dpp v12, v12, v12 row_half_mirror row_mask:0xf bank_mask:0xf bound_ctrl:1
	s_nop 1
	v_max_u32_dpp v12, v12, v12 row_mirror row_mask:0xf bank_mask:0xf bound_ctrl:1
	v_cmp_eq_u32_e32 vcc, v7, v12
	v_cndmask_b32_e64 v8, v8, v12, s[34:35]
	s_nop 0
	v_cndmask_b32_e64 v7, 0, 1, vcc
	v_lshl_add_u32 v9, v7, 2, v9
	ds_read_b32 v12, v9
	v_addc_co_u32_e32 v10, vcc, v10, v11, vcc
	v_sub_u32_e32 v11, v63, v10
	s_waitcnt lgkmcnt(0)
	v_add_f32_e32 v12, v12, v3
	v_ashrrev_i32_e32 v13, 31, v12
	v_bitop3_b32 v12, v13, v12, s70 bitop3:0x36
	v_and_or_b32 v11, v12, s77, v11
	s_nop 1
	v_max_u32_dpp v12, v11, v11 quad_perm:[1,0,3,2] row_mask:0xf bank_mask:0xf bound_ctrl:1
	s_nop 1
	v_max_u32_dpp v12, v12, v12 quad_perm:[2,3,0,1] row_mask:0xf bank_mask:0xf bound_ctrl:1
	s_nop 1
	v_max_u32_dpp v12, v12, v12 row_half_mirror row_mask:0xf bank_mask:0xf bound_ctrl:1
	s_nop 1
	v_max_u32_dpp v12, v12, v12 row_mirror row_mask:0xf bank_mask:0xf bound_ctrl:1
	v_cmp_eq_u32_e32 vcc, v11, v12
	v_cndmask_b32_e64 v8, v8, v12, s[36:37]
	s_nop 0
	v_cndmask_b32_e64 v11, 0, 1, vcc
	v_lshl_add_u32 v9, v11, 2, v9
	ds_read_b32 v12, v9
	v_addc_co_u32_e32 v5, vcc, v5, v7, vcc
	v_sub_u32_e32 v7, v63, v5
	s_waitcnt lgkmcnt(0)
	v_add_f32_e32 v12, v12, v3
	v_ashrrev_i32_e32 v13, 31, v12
	v_bitop3_b32 v12, v13, v12, s70 bitop3:0x36
	v_and_or_b32 v7, v12, s77, v7
	s_nop 1
	v_max_u32_dpp v12, v7, v7 quad_perm:[1,0,3,2] row_mask:0xf bank_mask:0xf bound_ctrl:1
	s_nop 1
	v_max_u32_dpp v12, v12, v12 quad_perm:[2,3,0,1] row_mask:0xf bank_mask:0xf bound_ctrl:1
	s_nop 1
	v_max_u32_dpp v12, v12, v12 row_half_mirror row_mask:0xf bank_mask:0xf bound_ctrl:1
	s_nop 1
	v_max_u32_dpp v12, v12, v12 row_mirror row_mask:0xf bank_mask:0xf bound_ctrl:1
	v_cmp_eq_u32_e32 vcc, v7, v12
	v_cndmask_b32_e64 v8, v8, v12, s[38:39]
	s_nop 0
	v_cndmask_b32_e64 v7, 0, 1, vcc
	v_lshl_add_u32 v9, v7, 2, v9
	v_addc_co_u32_e32 v10, vcc, v10, v11, vcc
	ds_read_b32 v11, v9
	v_sub_u32_e32 v10, v63, v10
	s_waitcnt lgkmcnt(0)
	v_add_f32_e32 v11, v11, v3
	v_ashrrev_i32_e32 v12, 31, v11
	v_bitop3_b32 v11, v12, v11, s70 bitop3:0x36
	v_and_or_b32 v10, v11, s77, v10
	s_nop 1
	v_max_u32_dpp v11, v10, v10 quad_perm:[1,0,3,2] row_mask:0xf bank_mask:0xf bound_ctrl:1
	s_nop 1
	v_max_u32_dpp v11, v11, v11 quad_perm:[2,3,0,1] row_mask:0xf bank_mask:0xf bound_ctrl:1
	s_nop 1
	v_max_u32_dpp v11, v11, v11 row_half_mirror row_mask:0xf bank_mask:0xf bound_ctrl:1
	s_nop 1
	v_max_u32_dpp v11, v11, v11 row_mirror row_mask:0xf bank_mask:0xf bound_ctrl:1
	v_cmp_eq_u32_e32 vcc, v10, v11
	v_cndmask_b32_e64 v8, v8, v11, s[40:41]
	s_nop 0
	v_cndmask_b32_e64 v10, 0, 1, vcc
	v_addc_co_u32_e32 v5, vcc, v5, v7, vcc
	v_lshl_add_u32 v7, v10, 2, v9
	ds_read_b32 v7, v7
	v_sub_u32_e32 v5, v63, v5
	s_waitcnt lgkmcnt(0)
	v_add_f32_e32 v3, v7, v3
	v_ashrrev_i32_e32 v7, 31, v3
	v_bitop3_b32 v3, v7, v3, s70 bitop3:0x36
	v_and_or_b32 v3, v3, s77, v5
	s_nop 1
	v_max_u32_dpp v3, v3, v3 quad_perm:[1,0,3,2] row_mask:0xf bank_mask:0xf bound_ctrl:1
	s_nop 1
	v_max_u32_dpp v3, v3, v3 quad_perm:[2,3,0,1] row_mask:0xf bank_mask:0xf bound_ctrl:1
	s_nop 1
	v_max_u32_dpp v3, v3, v3 row_half_mirror row_mask:0xf bank_mask:0xf bound_ctrl:1
	s_nop 1
	v_max_u32_dpp v3, v3, v3 row_mirror row_mask:0xf bank_mask:0xf bound_ctrl:1
	v_cndmask_b32_e64 v3, v8, v3, s[42:43]
	v_cmp_lt_i32_e32 vcc, -1, v3
	v_not_b32_e32 v5, v3
	v_bitop3_b32 v8, v3, 15, v3 bitop3:0xc
	v_cndmask_b32_e64 v7, v78, -1, vcc
	v_bitop3_b32 v7, v7, v3, s77 bitop3:0x78
	v_max_u32_dpp v3, v3, v3 quad_perm:[1,0,3,2] row_mask:0xf bank_mask:0xf bound_ctrl:1
	v_lshrrev_b32_e32 v5, 2, v5
	v_and_b32_e32 v5, 60, v5
	v_max_u32_dpp v3, v3, v3 quad_perm:[2,3,0,1] row_mask:0xf bank_mask:0xf bound_ctrl:1
	v_add_u32_e32 v5, v60, v5
	v_lshl_add_u32 v8, v8, 2, v60
	v_max_u32_dpp v3, v3, v3 row_half_mirror row_mask:0xf bank_mask:0xf bound_ctrl:1
	ds_read_b32 v5, v5 offset:64
	ds_read_b32 v10, v8 offset:128
	v_max_u32_dpp v3, v3, v3 row_mirror row_mask:0xf bank_mask:0xf bound_ctrl:1
	v_cmp_lt_i32_e32 vcc, -1, v3
	s_waitcnt lgkmcnt(0)
	v_lshl_add_u32 v5, v5, 7, v10
	v_cndmask_b32_e64 v8, v78, -1, vcc
	v_bitop3_b32 v3, v8, v3, s77 bitop3:0x78
	v_sub_f32_e32 v3, v7, v3
	v_mul_f32_e32 v3, 0x3fb8aa3b, v3
	v_exp_f32_e32 v3, v3
	v_add_u32_e32 v8, 1, v2
	v_ashrrev_i32_e32 v9, 31, v8
	v_lshlrev_b64 v[8:9], 9, v[8:9]
	v_add_f32_dpp v7, v3, v3 quad_perm:[1,0,3,2] row_mask:0xf bank_mask:0xf bound_ctrl:1
	v_or_b32_e32 v8, v8, v79
	v_lshl_add_u64 v[10:11], s[44:45], 0, v[8:9]
	v_add_f32_dpp v7, v7, v7 quad_perm:[2,3,0,1] row_mask:0xf bank_mask:0xf bound_ctrl:1
	global_store_dword v[10:11], v5, off
	v_lshl_add_u64 v[8:9], s[48:49], 0, v[8:9]
	v_add_f32_dpp v7, v7, v7 row_half_mirror row_mask:0xf bank_mask:0xf bound_ctrl:1
	s_nop 1
	v_add_f32_dpp v7, v7, v7 row_mirror row_mask:0xf bank_mask:0xf bound_ctrl:1
	v_div_scale_f32 v5, s[54:55], v7, v7, v3
	v_rcp_f32_e32 v10, v5
	s_nop 0
	v_fma_f32 v11, -v5, v10, 1.0
	v_fmac_f32_e32 v10, v11, v10
	v_div_scale_f32 v11, vcc, v3, v7, v3
	v_mul_f32_e32 v12, v11, v10
	v_fma_f32 v13, -v5, v12, v11
	v_fmac_f32_e32 v12, v13, v10
	v_fma_f32 v5, -v5, v12, v11
	v_div_fmas_f32 v5, v5, v10, v12
	v_div_fixup_f32 v3, v5, v7, v3
	v_cmp_lt_i32_e32 vcc, -1, v81
	global_store_dword v[8:9], v3, off
	s_nop 0
	v_cndmask_b32_e64 v3, v78, -1, vcc
	v_cmp_lt_i32_e32 vcc, -1, v6
	v_bitop3_b32 v3, v3, v81, s71 bitop3:0x78
	s_nop 0
	v_cndmask_b32_e64 v5, v78, -1, vcc
	v_bitop3_b32 v5, v5, v6, s71 bitop3:0x78
	ds_write_b32 v62, v5
	v_bitop3_b32 v5, v81, s63, v81 bitop3:0xc
	ds_write_b32 v62, v5 offset:64
	v_bitop3_b32 v5, v6, s63, v6 bitop3:0xc
	ds_write_b32 v62, v5 offset:128
	ds_read_b32 v5, v60
	s_waitcnt lgkmcnt(0)
	v_add_f32_e32 v5, v5, v3
	v_ashrrev_i32_e32 v6, 31, v5
	v_bitop3_b32 v5, v6, v5, s70 bitop3:0x36
	v_and_or_b32 v5, v5, s77, v63
	s_nop 1
	v_max_u32_dpp v6, v5, v5 quad_perm:[1,0,3,2] row_mask:0xf bank_mask:0xf bound_ctrl:1
	s_nop 1
	v_max_u32_dpp v6, v6, v6 quad_perm:[2,3,0,1] row_mask:0xf bank_mask:0xf bound_ctrl:1
	s_nop 1
	v_max_u32_dpp v6, v6, v6 row_half_mirror row_mask:0xf bank_mask:0xf bound_ctrl:1
	s_nop 1
	v_max_u32_dpp v6, v6, v6 row_mirror row_mask:0xf bank_mask:0xf bound_ctrl:1
	v_cmp_eq_u32_e32 vcc, v5, v6
	v_cndmask_b32_e64 v7, 0, v6, s[10:11]
	s_nop 0
	v_cndmask_b32_e64 v5, 0, 1, vcc
	v_lshl_add_u32 v8, v5, 2, v60
	ds_read_b32 v9, v8
	v_subbrev_co_u32_e32 v6, vcc, 0, v63, vcc
	s_waitcnt lgkmcnt(0)
	v_add_f32_e32 v9, v9, v3
	v_ashrrev_i32_e32 v10, 31, v9
	v_bitop3_b32 v9, v10, v9, s70 bitop3:0x36
	v_and_or_b32 v6, v9, s77, v6
	s_nop 1
	v_max_u32_dpp v9, v6, v6 quad_perm:[1,0,3,2] row_mask:0xf bank_mask:0xf bound_ctrl:1
	s_nop 1
	v_max_u32_dpp v9, v9, v9 quad_perm:[2,3,0,1] row_mask:0xf bank_mask:0xf bound_ctrl:1
	s_nop 1
	v_max_u32_dpp v9, v9, v9 row_half_mirror row_mask:0xf bank_mask:0xf bound_ctrl:1
	s_nop 1
	v_max_u32_dpp v9, v9, v9 row_mirror row_mask:0xf bank_mask:0xf bound_ctrl:1
	v_cmp_eq_u32_e32 vcc, v6, v9
	v_cndmask_b32_e64 v7, v7, v9, s[12:13]
	s_nop 0
	v_cndmask_b32_e64 v6, 0, 1, vcc
	v_lshl_add_u32 v8, v6, 2, v8
	ds_read_b32 v11, v8
	v_addc_co_u32_e32 v9, vcc, 0, v5, vcc
	v_sub_u32_e32 v10, v63, v9
	s_waitcnt lgkmcnt(0)
	v_add_f32_e32 v11, v11, v3
	v_ashrrev_i32_e32 v12, 31, v11
	v_bitop3_b32 v11, v12, v11, s70 bitop3:0x36
	v_and_or_b32 v10, v11, s77, v10
	s_nop 1
	v_max_u32_dpp v11, v10, v10 quad_perm:[1,0,3,2] row_mask:0xf bank_mask:0xf bound_ctrl:1
	s_nop 1
	v_max_u32_dpp v11, v11, v11 quad_perm:[2,3,0,1] row_mask:0xf bank_mask:0xf bound_ctrl:1
	s_nop 1
	v_max_u32_dpp v11, v11, v11 row_half_mirror row_mask:0xf bank_mask:0xf bound_ctrl:1
	s_nop 1
	v_max_u32_dpp v11, v11, v11 row_mirror row_mask:0xf bank_mask:0xf bound_ctrl:1
	v_cmp_eq_u32_e32 vcc, v10, v11
	v_cndmask_b32_e64 v7, v7, v11, s[14:15]
	s_nop 0
	v_cndmask_b32_e64 v10, 0, 1, vcc
	v_lshl_add_u32 v8, v10, 2, v8
	ds_read_b32 v11, v8
	v_addc_co_u32_e32 v5, vcc, v6, v5, vcc
	v_sub_u32_e32 v6, v63, v5
	s_waitcnt lgkmcnt(0)
	v_add_f32_e32 v11, v11, v3
	v_ashrrev_i32_e32 v12, 31, v11
	v_bitop3_b32 v11, v12, v11, s70 bitop3:0x36
	v_and_or_b32 v6, v11, s77, v6
	s_nop 1
	v_max_u32_dpp v11, v6, v6 quad_perm:[1,0,3,2] row_mask:0xf bank_mask:0xf bound_ctrl:1
	s_nop 1
	v_max_u32_dpp v11, v11, v11 quad_perm:[2,3,0,1] row_mask:0xf bank_mask:0xf bound_ctrl:1
	s_nop 1
	v_max_u32_dpp v11, v11, v11 row_half_mirror row_mask:0xf bank_mask:0xf bound_ctrl:1
	s_nop 1
	v_max_u32_dpp v11, v11, v11 row_mirror row_mask:0xf bank_mask:0xf bound_ctrl:1
	v_cmp_eq_u32_e32 vcc, v6, v11
	v_cndmask_b32_e64 v7, v7, v11, s[16:17]
	s_nop 0
	v_cndmask_b32_e64 v6, 0, 1, vcc
	v_lshl_add_u32 v8, v6, 2, v8
	ds_read_b32 v11, v8
	v_addc_co_u32_e32 v9, vcc, v9, v10, vcc
	v_sub_u32_e32 v10, v63, v9
	s_waitcnt lgkmcnt(0)
	v_add_f32_e32 v11, v11, v3
	v_ashrrev_i32_e32 v12, 31, v11
	v_bitop3_b32 v11, v12, v11, s70 bitop3:0x36
	v_and_or_b32 v10, v11, s77, v10
	s_nop 1
	v_max_u32_dpp v11, v10, v10 quad_perm:[1,0,3,2] row_mask:0xf bank_mask:0xf bound_ctrl:1
	s_nop 1
	v_max_u32_dpp v11, v11, v11 quad_perm:[2,3,0,1] row_mask:0xf bank_mask:0xf bound_ctrl:1
	s_nop 1
	v_max_u32_dpp v11, v11, v11 row_half_mirror row_mask:0xf bank_mask:0xf bound_ctrl:1
	s_nop 1
	v_max_u32_dpp v11, v11, v11 row_mirror row_mask:0xf bank_mask:0xf bound_ctrl:1
	v_cmp_eq_u32_e32 vcc, v10, v11
	v_cndmask_b32_e64 v7, v7, v11, s[18:19]
	s_nop 0
	v_cndmask_b32_e64 v10, 0, 1, vcc
	v_lshl_add_u32 v8, v10, 2, v8
	ds_read_b32 v11, v8
	v_addc_co_u32_e32 v5, vcc, v5, v6, vcc
	v_sub_u32_e32 v6, v63, v5
	s_waitcnt lgkmcnt(0)
	v_add_f32_e32 v11, v11, v3
	v_ashrrev_i32_e32 v12, 31, v11
	v_bitop3_b32 v11, v12, v11, s70 bitop3:0x36
	v_and_or_b32 v6, v11, s77, v6
	s_nop 1
	v_max_u32_dpp v11, v6, v6 quad_perm:[1,0,3,2] row_mask:0xf bank_mask:0xf bound_ctrl:1
	s_nop 1
	v_max_u32_dpp v11, v11, v11 quad_perm:[2,3,0,1] row_mask:0xf bank_mask:0xf bound_ctrl:1
	s_nop 1
	v_max_u32_dpp v11, v11, v11 row_half_mirror row_mask:0xf bank_mask:0xf bound_ctrl:1
	s_nop 1
	v_max_u32_dpp v11, v11, v11 row_mirror row_mask:0xf bank_mask:0xf bound_ctrl:1
	v_cmp_eq_u32_e32 vcc, v6, v11
	v_cndmask_b32_e64 v7, v7, v11, s[20:21]
	s_nop 0
	v_cndmask_b32_e64 v6, 0, 1, vcc
	v_lshl_add_u32 v8, v6, 2, v8
	ds_read_b32 v11, v8
	v_addc_co_u32_e32 v9, vcc, v9, v10, vcc
	v_sub_u32_e32 v10, v63, v9
	s_waitcnt lgkmcnt(0)
	v_add_f32_e32 v11, v11, v3
	v_ashrrev_i32_e32 v12, 31, v11
	v_bitop3_b32 v11, v12, v11, s70 bitop3:0x36
	v_and_or_b32 v10, v11, s77, v10
	s_nop 1
	v_max_u32_dpp v11, v10, v10 quad_perm:[1,0,3,2] row_mask:0xf bank_mask:0xf bound_ctrl:1
	s_nop 1
	v_max_u32_dpp v11, v11, v11 quad_perm:[2,3,0,1] row_mask:0xf bank_mask:0xf bound_ctrl:1
	s_nop 1
	v_max_u32_dpp v11, v11, v11 row_half_mirror row_mask:0xf bank_mask:0xf bound_ctrl:1
	s_nop 1
	v_max_u32_dpp v11, v11, v11 row_mirror row_mask:0xf bank_mask:0xf bound_ctrl:1
	v_cmp_eq_u32_e32 vcc, v10, v11
	v_cndmask_b32_e64 v7, v7, v11, s[22:23]
	s_nop 0
	v_cndmask_b32_e64 v10, 0, 1, vcc
	v_lshl_add_u32 v8, v10, 2, v8
	ds_read_b32 v11, v8
	v_addc_co_u32_e32 v5, vcc, v5, v6, vcc
	v_sub_u32_e32 v6, v63, v5
	s_waitcnt lgkmcnt(0)
	v_add_f32_e32 v11, v11, v3
	v_ashrrev_i32_e32 v12, 31, v11
	v_bitop3_b32 v11, v12, v11, s70 bitop3:0x36
	v_and_or_b32 v6, v11, s77, v6
	s_nop 1
	v_max_u32_dpp v11, v6, v6 quad_perm:[1,0,3,2] row_mask:0xf bank_mask:0xf bound_ctrl:1
	s_nop 1
	v_max_u32_dpp v11, v11, v11 quad_perm:[2,3,0,1] row_mask:0xf bank_mask:0xf bound_ctrl:1
	s_nop 1
	v_max_u32_dpp v11, v11, v11 row_half_mirror row_mask:0xf bank_mask:0xf bound_ctrl:1
	s_nop 1
	v_max_u32_dpp v11, v11, v11 row_mirror row_mask:0xf bank_mask:0xf bound_ctrl:1
	v_cmp_eq_u32_e32 vcc, v6, v11
	v_cndmask_b32_e64 v7, v7, v11, s[24:25]
	s_nop 0
	v_cndmask_b32_e64 v6, 0, 1, vcc
	v_lshl_add_u32 v8, v6, 2, v8
	ds_read_b32 v11, v8
	v_addc_co_u32_e32 v9, vcc, v9, v10, vcc
	v_sub_u32_e32 v10, v63, v9
	s_waitcnt lgkmcnt(0)
	v_add_f32_e32 v11, v11, v3
	v_ashrrev_i32_e32 v12, 31, v11
	v_bitop3_b32 v11, v12, v11, s70 bitop3:0x36
	v_and_or_b32 v10, v11, s77, v10
	s_nop 1
	v_max_u32_dpp v11, v10, v10 quad_perm:[1,0,3,2] row_mask:0xf bank_mask:0xf bound_ctrl:1
	s_nop 1
	v_max_u32_dpp v11, v11, v11 quad_perm:[2,3,0,1] row_mask:0xf bank_mask:0xf bound_ctrl:1
	s_nop 1
	v_max_u32_dpp v11, v11, v11 row_half_mirror row_mask:0xf bank_mask:0xf bound_ctrl:1
	s_nop 1
	v_max_u32_dpp v11, v11, v11 row_mirror row_mask:0xf bank_mask:0xf bound_ctrl:1
	v_cmp_eq_u32_e32 vcc, v10, v11
	v_cndmask_b32_e64 v7, v7, v11, s[26:27]
	s_nop 0
	v_cndmask_b32_e64 v10, 0, 1, vcc
	v_lshl_add_u32 v8, v10, 2, v8
	ds_read_b32 v11, v8
	v_addc_co_u32_e32 v5, vcc, v5, v6, vcc
	v_sub_u32_e32 v6, v63, v5
	s_waitcnt lgkmcnt(0)
	v_add_f32_e32 v11, v11, v3
	v_ashrrev_i32_e32 v12, 31, v11
	v_bitop3_b32 v11, v12, v11, s70 bitop3:0x36
	v_and_or_b32 v6, v11, s77, v6
	s_nop 1
	v_max_u32_dpp v11, v6, v6 quad_perm:[1,0,3,2] row_mask:0xf bank_mask:0xf bound_ctrl:1
	s_nop 1
	v_max_u32_dpp v11, v11, v11 quad_perm:[2,3,0,1] row_mask:0xf bank_mask:0xf bound_ctrl:1
	s_nop 1
	v_max_u32_dpp v11, v11, v11 row_half_mirror row_mask:0xf bank_mask:0xf bound_ctrl:1
	s_nop 1
	v_max_u32_dpp v11, v11, v11 row_mirror row_mask:0xf bank_mask:0xf bound_ctrl:1
	v_cmp_eq_u32_e32 vcc, v6, v11
	v_cndmask_b32_e64 v7, v7, v11, s[28:29]
	s_nop 0
	v_cndmask_b32_e64 v6, 0, 1, vcc
	v_lshl_add_u32 v8, v6, 2, v8
	ds_read_b32 v11, v8
	v_addc_co_u32_e32 v9, vcc, v9, v10, vcc
	v_sub_u32_e32 v10, v63, v9
	s_waitcnt lgkmcnt(0)
	v_add_f32_e32 v11, v11, v3
	v_ashrrev_i32_e32 v12, 31, v11
	v_bitop3_b32 v11, v12, v11, s70 bitop3:0x36
	v_and_or_b32 v10, v11, s77, v10
	s_nop 1
	v_max_u32_dpp v11, v10, v10 quad_perm:[1,0,3,2] row_mask:0xf bank_mask:0xf bound_ctrl:1
	s_nop 1
	v_max_u32_dpp v11, v11, v11 quad_perm:[2,3,0,1] row_mask:0xf bank_mask:0xf bound_ctrl:1
	s_nop 1
	v_max_u32_dpp v11, v11, v11 row_half_mirror row_mask:0xf bank_mask:0xf bound_ctrl:1
	s_nop 1
	v_max_u32_dpp v11, v11, v11 row_mirror row_mask:0xf bank_mask:0xf bound_ctrl:1
	v_cmp_eq_u32_e32 vcc, v10, v11
	v_cndmask_b32_e64 v7, v7, v11, s[30:31]
	s_nop 0
	v_cndmask_b32_e64 v10, 0, 1, vcc
	v_lshl_add_u32 v8, v10, 2, v8
	ds_read_b32 v11, v8
	v_addc_co_u32_e32 v5, vcc, v5, v6, vcc
	v_sub_u32_e32 v6, v63, v5
	s_waitcnt lgkmcnt(0)
	v_add_f32_e32 v11, v11, v3
	v_ashrrev_i32_e32 v12, 31, v11
	v_bitop3_b32 v11, v12, v11, s70 bitop3:0x36
	v_and_or_b32 v6, v11, s77, v6
	s_nop 1
	v_max_u32_dpp v11, v6, v6 quad_perm:[1,0,3,2] row_mask:0xf bank_mask:0xf bound_ctrl:1
	s_nop 1
	v_max_u32_dpp v11, v11, v11 quad_perm:[2,3,0,1] row_mask:0xf bank_mask:0xf bound_ctrl:1
	s_nop 1
	v_max_u32_dpp v11, v11, v11 row_half_mirror row_mask:0xf bank_mask:0xf bound_ctrl:1
	s_nop 1
	v_max_u32_dpp v11, v11, v11 row_mirror row_mask:0xf bank_mask:0xf bound_ctrl:1
	v_cmp_eq_u32_e32 vcc, v6, v11
	v_cndmask_b32_e64 v7, v7, v11, s[34:35]
	s_nop 0
	v_cndmask_b32_e64 v6, 0, 1, vcc
	v_lshl_add_u32 v8, v6, 2, v8
	ds_read_b32 v11, v8
	v_addc_co_u32_e32 v9, vcc, v9, v10, vcc
	v_sub_u32_e32 v10, v63, v9
	s_waitcnt lgkmcnt(0)
	v_add_f32_e32 v11, v11, v3
	v_ashrrev_i32_e32 v12, 31, v11
	v_bitop3_b32 v11, v12, v11, s70 bitop3:0x36
	v_and_or_b32 v10, v11, s77, v10
	s_nop 1
	v_max_u32_dpp v11, v10, v10 quad_perm:[1,0,3,2] row_mask:0xf bank_mask:0xf bound_ctrl:1
	s_nop 1
	v_max_u32_dpp v11, v11, v11 quad_perm:[2,3,0,1] row_mask:0xf bank_mask:0xf bound_ctrl:1
	s_nop 1
	v_max_u32_dpp v11, v11, v11 row_half_mirror row_mask:0xf bank_mask:0xf bound_ctrl:1
	s_nop 1
	v_max_u32_dpp v11, v11, v11 row_mirror row_mask:0xf bank_mask:0xf bound_ctrl:1
	v_cmp_eq_u32_e32 vcc, v10, v11
	v_cndmask_b32_e64 v7, v7, v11, s[36:37]
	s_nop 0
	v_cndmask_b32_e64 v10, 0, 1, vcc
	v_lshl_add_u32 v8, v10, 2, v8
	ds_read_b32 v11, v8
	v_addc_co_u32_e32 v5, vcc, v5, v6, vcc
	v_sub_u32_e32 v6, v63, v5
	s_waitcnt lgkmcnt(0)
	v_add_f32_e32 v11, v11, v3
	v_ashrrev_i32_e32 v12, 31, v11
	v_bitop3_b32 v11, v12, v11, s70 bitop3:0x36
	v_and_or_b32 v6, v11, s77, v6
	s_nop 1
	v_max_u32_dpp v11, v6, v6 quad_perm:[1,0,3,2] row_mask:0xf bank_mask:0xf bound_ctrl:1
	s_nop 1
	v_max_u32_dpp v11, v11, v11 quad_perm:[2,3,0,1] row_mask:0xf bank_mask:0xf bound_ctrl:1
	s_nop 1
	v_max_u32_dpp v11, v11, v11 row_half_mirror row_mask:0xf bank_mask:0xf bound_ctrl:1
	s_nop 1
	v_max_u32_dpp v11, v11, v11 row_mirror row_mask:0xf bank_mask:0xf bound_ctrl:1
	v_cmp_eq_u32_e32 vcc, v6, v11
	v_cndmask_b32_e64 v7, v7, v11, s[38:39]
	s_nop 0
	v_cndmask_b32_e64 v6, 0, 1, vcc
	v_lshl_add_u32 v8, v6, 2, v8
	v_addc_co_u32_e32 v9, vcc, v9, v10, vcc
	ds_read_b32 v10, v8
	v_sub_u32_e32 v9, v63, v9
	s_waitcnt lgkmcnt(0)
	v_add_f32_e32 v10, v10, v3
	v_ashrrev_i32_e32 v11, 31, v10
	v_bitop3_b32 v10, v11, v10, s70 bitop3:0x36
	v_and_or_b32 v9, v10, s77, v9
	s_nop 1
	v_max_u32_dpp v10, v9, v9 quad_perm:[1,0,3,2] row_mask:0xf bank_mask:0xf bound_ctrl:1
	s_nop 1
	v_max_u32_dpp v10, v10, v10 quad_perm:[2,3,0,1] row_mask:0xf bank_mask:0xf bound_ctrl:1
	s_nop 1
	v_max_u32_dpp v10, v10, v10 row_half_mirror row_mask:0xf bank_mask:0xf bound_ctrl:1
	s_nop 1
	v_max_u32_dpp v10, v10, v10 row_mirror row_mask:0xf bank_mask:0xf bound_ctrl:1
	v_cmp_eq_u32_e32 vcc, v9, v10
	v_cndmask_b32_e64 v7, v7, v10, s[40:41]
	s_nop 0
	v_cndmask_b32_e64 v9, 0, 1, vcc
	v_addc_co_u32_e32 v5, vcc, v5, v6, vcc
	v_lshl_add_u32 v6, v9, 2, v8
	ds_read_b32 v6, v6
	v_sub_u32_e32 v5, v63, v5
	s_waitcnt lgkmcnt(0)
	v_add_f32_e32 v3, v6, v3
	v_ashrrev_i32_e32 v6, 31, v3
	v_bitop3_b32 v3, v6, v3, s70 bitop3:0x36
	v_and_or_b32 v3, v3, s77, v5
	s_nop 1
	v_max_u32_dpp v3, v3, v3 quad_perm:[1,0,3,2] row_mask:0xf bank_mask:0xf bound_ctrl:1
	s_nop 1
	v_max_u32_dpp v3, v3, v3 quad_perm:[2,3,0,1] row_mask:0xf bank_mask:0xf bound_ctrl:1
	s_nop 1
	v_max_u32_dpp v3, v3, v3 row_half_mirror row_mask:0xf bank_mask:0xf bound_ctrl:1
	s_nop 1
	v_max_u32_dpp v3, v3, v3 row_mirror row_mask:0xf bank_mask:0xf bound_ctrl:1
	v_cndmask_b32_e64 v3, v7, v3, s[42:43]
	v_cmp_lt_i32_e32 vcc, -1, v3
	v_not_b32_e32 v5, v3
	v_bitop3_b32 v7, v3, 15, v3 bitop3:0xc
	v_cndmask_b32_e64 v6, v78, -1, vcc
	v_bitop3_b32 v6, v6, v3, s77 bitop3:0x78
	v_max_u32_dpp v3, v3, v3 quad_perm:[1,0,3,2] row_mask:0xf bank_mask:0xf bound_ctrl:1
	v_lshrrev_b32_e32 v5, 2, v5
	v_and_b32_e32 v5, 60, v5
	v_max_u32_dpp v3, v3, v3 quad_perm:[2,3,0,1] row_mask:0xf bank_mask:0xf bound_ctrl:1
	v_add_u32_e32 v5, v60, v5
	v_lshl_add_u32 v7, v7, 2, v60
	v_max_u32_dpp v3, v3, v3 row_half_mirror row_mask:0xf bank_mask:0xf bound_ctrl:1
	ds_read_b32 v5, v5 offset:64
	ds_read_b32 v8, v7 offset:128
	v_max_u32_dpp v3, v3, v3 row_mirror row_mask:0xf bank_mask:0xf bound_ctrl:1
	v_cmp_lt_i32_e32 vcc, -1, v3
	s_waitcnt lgkmcnt(0)
	v_lshl_add_u32 v5, v5, 7, v8
	v_cndmask_b32_e64 v7, v78, -1, vcc
	v_bitop3_b32 v3, v7, v3, s77 bitop3:0x78
	v_sub_f32_e32 v3, v6, v3
	v_mul_f32_e32 v3, 0x3fb8aa3b, v3
	v_exp_f32_e32 v3, v3
	s_nop 1
	v_add_f32_dpp v6, v3, v3 quad_perm:[1,0,3,2] row_mask:0xf bank_mask:0xf bound_ctrl:1
	s_nop 1
	v_add_f32_dpp v6, v6, v6 quad_perm:[2,3,0,1] row_mask:0xf bank_mask:0xf bound_ctrl:1
	s_nop 1
	v_add_f32_dpp v6, v6, v6 row_half_mirror row_mask:0xf bank_mask:0xf bound_ctrl:1
	s_nop 1
	v_add_f32_dpp v10, v6, v6 row_mirror row_mask:0xf bank_mask:0xf bound_ctrl:1
	v_add_u32_e32 v6, 2, v2
	v_ashrrev_i32_e32 v7, 31, v6
	v_lshlrev_b64 v[6:7], 9, v[6:7]
	v_or_b32_e32 v6, v6, v79
	v_lshl_add_u64 v[8:9], s[44:45], 0, v[6:7]
	global_store_dword v[8:9], v5, off
	v_div_scale_f32 v5, s[54:55], v10, v10, v3
	v_rcp_f32_e32 v8, v5
	v_lshl_add_u64 v[6:7], s[48:49], 0, v[6:7]
	v_add_u32_e32 v2, 3, v2
	v_fma_f32 v9, -v5, v8, 1.0
	v_fmac_f32_e32 v8, v9, v8
	v_div_scale_f32 v9, vcc, v3, v10, v3
	v_mul_f32_e32 v11, v9, v8
	v_fma_f32 v12, -v5, v11, v9
	v_fmac_f32_e32 v11, v12, v8
	v_fma_f32 v5, -v5, v11, v9
	v_div_fmas_f32 v5, v5, v8, v11
	v_div_fixup_f32 v3, v5, v10, v3
	v_cmp_lt_i32_e32 vcc, -1, v80
	global_store_dword v[6:7], v3, off
	s_nop 0
	v_cndmask_b32_e64 v3, v78, -1, vcc
	v_cmp_lt_i32_e32 vcc, -1, v4
	v_bitop3_b32 v3, v3, v80, s71 bitop3:0x78
	s_nop 0
	v_cndmask_b32_e64 v5, v78, -1, vcc
	v_bitop3_b32 v5, v5, v4, s71 bitop3:0x78
	ds_write_b32 v62, v5
	v_bitop3_b32 v4, v4, s63, v4 bitop3:0xc
	ds_write_b32 v62, v4 offset:128
	ds_read_b32 v4, v60
	v_bitop3_b32 v5, v80, s63, v80 bitop3:0xc
	ds_write_b32 v62, v5 offset:64
	s_waitcnt lgkmcnt(1)
	v_add_f32_e32 v4, v4, v3
	v_ashrrev_i32_e32 v5, 31, v4
	v_bitop3_b32 v4, v5, v4, s70 bitop3:0x36
	v_and_or_b32 v4, v4, s77, v63
	s_nop 1
	v_max_u32_dpp v5, v4, v4 quad_perm:[1,0,3,2] row_mask:0xf bank_mask:0xf bound_ctrl:1
	s_nop 1
	v_max_u32_dpp v5, v5, v5 quad_perm:[2,3,0,1] row_mask:0xf bank_mask:0xf bound_ctrl:1
	s_nop 1
	v_max_u32_dpp v5, v5, v5 row_half_mirror row_mask:0xf bank_mask:0xf bound_ctrl:1
	s_nop 1
	v_max_u32_dpp v5, v5, v5 row_mirror row_mask:0xf bank_mask:0xf bound_ctrl:1
	v_cmp_eq_u32_e32 vcc, v4, v5
	v_cndmask_b32_e64 v6, 0, v5, s[10:11]
	s_nop 0
	v_cndmask_b32_e64 v4, 0, 1, vcc
	v_lshl_add_u32 v7, v4, 2, v60
	ds_read_b32 v8, v7
	v_subbrev_co_u32_e32 v5, vcc, 0, v63, vcc
	s_waitcnt lgkmcnt(0)
	v_add_f32_e32 v8, v8, v3
	v_ashrrev_i32_e32 v9, 31, v8
	v_bitop3_b32 v8, v9, v8, s70 bitop3:0x36
	v_and_or_b32 v5, v8, s77, v5
	s_nop 1
	v_max_u32_dpp v8, v5, v5 quad_perm:[1,0,3,2] row_mask:0xf bank_mask:0xf bound_ctrl:1
	s_nop 1
	v_max_u32_dpp v8, v8, v8 quad_perm:[2,3,0,1] row_mask:0xf bank_mask:0xf bound_ctrl:1
	s_nop 1
	v_max_u32_dpp v8, v8, v8 row_half_mirror row_mask:0xf bank_mask:0xf bound_ctrl:1
	s_nop 1
	v_max_u32_dpp v8, v8, v8 row_mirror row_mask:0xf bank_mask:0xf bound_ctrl:1
	v_cmp_eq_u32_e32 vcc, v5, v8
	v_cndmask_b32_e64 v6, v6, v8, s[12:13]
	s_nop 0
	v_cndmask_b32_e64 v5, 0, 1, vcc
	v_lshl_add_u32 v7, v5, 2, v7
	ds_read_b32 v10, v7
	v_addc_co_u32_e32 v8, vcc, 0, v4, vcc
	v_sub_u32_e32 v9, v63, v8
	s_waitcnt lgkmcnt(0)
	v_add_f32_e32 v10, v10, v3
	v_ashrrev_i32_e32 v11, 31, v10
	v_bitop3_b32 v10, v11, v10, s70 bitop3:0x36
	v_and_or_b32 v9, v10, s77, v9
	s_nop 1
	v_max_u32_dpp v10, v9, v9 quad_perm:[1,0,3,2] row_mask:0xf bank_mask:0xf bound_ctrl:1
	s_nop 1
	v_max_u32_dpp v10, v10, v10 quad_perm:[2,3,0,1] row_mask:0xf bank_mask:0xf bound_ctrl:1
	s_nop 1
	v_max_u32_dpp v10, v10, v10 row_half_mirror row_mask:0xf bank_mask:0xf bound_ctrl:1
	s_nop 1
	v_max_u32_dpp v10, v10, v10 row_mirror row_mask:0xf bank_mask:0xf bound_ctrl:1
	v_cmp_eq_u32_e32 vcc, v9, v10
	v_cndmask_b32_e64 v6, v6, v10, s[14:15]
	s_nop 0
	v_cndmask_b32_e64 v9, 0, 1, vcc
	v_lshl_add_u32 v7, v9, 2, v7
	ds_read_b32 v10, v7
	v_addc_co_u32_e32 v4, vcc, v5, v4, vcc
	v_sub_u32_e32 v5, v63, v4
	s_waitcnt lgkmcnt(0)
	v_add_f32_e32 v10, v10, v3
	v_ashrrev_i32_e32 v11, 31, v10
	v_bitop3_b32 v10, v11, v10, s70 bitop3:0x36
	v_and_or_b32 v5, v10, s77, v5
	s_nop 1
	v_max_u32_dpp v10, v5, v5 quad_perm:[1,0,3,2] row_mask:0xf bank_mask:0xf bound_ctrl:1
	s_nop 1
	v_max_u32_dpp v10, v10, v10 quad_perm:[2,3,0,1] row_mask:0xf bank_mask:0xf bound_ctrl:1
	s_nop 1
	v_max_u32_dpp v10, v10, v10 row_half_mirror row_mask:0xf bank_mask:0xf bound_ctrl:1
	s_nop 1
	v_max_u32_dpp v10, v10, v10 row_mirror row_mask:0xf bank_mask:0xf bound_ctrl:1
	v_cmp_eq_u32_e32 vcc, v5, v10
	v_cndmask_b32_e64 v6, v6, v10, s[16:17]
	s_nop 0
	v_cndmask_b32_e64 v5, 0, 1, vcc
	v_lshl_add_u32 v7, v5, 2, v7
	ds_read_b32 v10, v7
	v_addc_co_u32_e32 v8, vcc, v8, v9, vcc
	v_sub_u32_e32 v9, v63, v8
	s_waitcnt lgkmcnt(0)
	v_add_f32_e32 v10, v10, v3
	v_ashrrev_i32_e32 v11, 31, v10
	v_bitop3_b32 v10, v11, v10, s70 bitop3:0x36
	v_and_or_b32 v9, v10, s77, v9
	s_nop 1
	v_max_u32_dpp v10, v9, v9 quad_perm:[1,0,3,2] row_mask:0xf bank_mask:0xf bound_ctrl:1
	s_nop 1
	v_max_u32_dpp v10, v10, v10 quad_perm:[2,3,0,1] row_mask:0xf bank_mask:0xf bound_ctrl:1
	s_nop 1
	v_max_u32_dpp v10, v10, v10 row_half_mirror row_mask:0xf bank_mask:0xf bound_ctrl:1
	s_nop 1
	v_max_u32_dpp v10, v10, v10 row_mirror row_mask:0xf bank_mask:0xf bound_ctrl:1
	v_cmp_eq_u32_e32 vcc, v9, v10
	v_cndmask_b32_e64 v6, v6, v10, s[18:19]
	s_nop 0
	v_cndmask_b32_e64 v9, 0, 1, vcc
	v_lshl_add_u32 v7, v9, 2, v7
	ds_read_b32 v10, v7
	v_addc_co_u32_e32 v4, vcc, v4, v5, vcc
	v_sub_u32_e32 v5, v63, v4
	s_waitcnt lgkmcnt(0)
	v_add_f32_e32 v10, v10, v3
	v_ashrrev_i32_e32 v11, 31, v10
	v_bitop3_b32 v10, v11, v10, s70 bitop3:0x36
	v_and_or_b32 v5, v10, s77, v5
	s_nop 1
	v_max_u32_dpp v10, v5, v5 quad_perm:[1,0,3,2] row_mask:0xf bank_mask:0xf bound_ctrl:1
	s_nop 1
	v_max_u32_dpp v10, v10, v10 quad_perm:[2,3,0,1] row_mask:0xf bank_mask:0xf bound_ctrl:1
	s_nop 1
	v_max_u32_dpp v10, v10, v10 row_half_mirror row_mask:0xf bank_mask:0xf bound_ctrl:1
	s_nop 1
	v_max_u32_dpp v10, v10, v10 row_mirror row_mask:0xf bank_mask:0xf bound_ctrl:1
	v_cmp_eq_u32_e32 vcc, v5, v10
	v_cndmask_b32_e64 v6, v6, v10, s[20:21]
	s_nop 0
	v_cndmask_b32_e64 v5, 0, 1, vcc
	v_lshl_add_u32 v7, v5, 2, v7
	ds_read_b32 v10, v7
	v_addc_co_u32_e32 v8, vcc, v8, v9, vcc
	v_sub_u32_e32 v9, v63, v8
	s_waitcnt lgkmcnt(0)
	v_add_f32_e32 v10, v10, v3
	v_ashrrev_i32_e32 v11, 31, v10
	v_bitop3_b32 v10, v11, v10, s70 bitop3:0x36
	v_and_or_b32 v9, v10, s77, v9
	s_nop 1
	v_max_u32_dpp v10, v9, v9 quad_perm:[1,0,3,2] row_mask:0xf bank_mask:0xf bound_ctrl:1
	s_nop 1
	v_max_u32_dpp v10, v10, v10 quad_perm:[2,3,0,1] row_mask:0xf bank_mask:0xf bound_ctrl:1
	s_nop 1
	v_max_u32_dpp v10, v10, v10 row_half_mirror row_mask:0xf bank_mask:0xf bound_ctrl:1
	s_nop 1
	v_max_u32_dpp v10, v10, v10 row_mirror row_mask:0xf bank_mask:0xf bound_ctrl:1
	v_cmp_eq_u32_e32 vcc, v9, v10
	v_cndmask_b32_e64 v6, v6, v10, s[22:23]
	s_nop 0
	v_cndmask_b32_e64 v9, 0, 1, vcc
	v_lshl_add_u32 v7, v9, 2, v7
	ds_read_b32 v10, v7
	v_addc_co_u32_e32 v4, vcc, v4, v5, vcc
	v_sub_u32_e32 v5, v63, v4
	s_waitcnt lgkmcnt(0)
	v_add_f32_e32 v10, v10, v3
	v_ashrrev_i32_e32 v11, 31, v10
	v_bitop3_b32 v10, v11, v10, s70 bitop3:0x36
	v_and_or_b32 v5, v10, s77, v5
	s_nop 1
	v_max_u32_dpp v10, v5, v5 quad_perm:[1,0,3,2] row_mask:0xf bank_mask:0xf bound_ctrl:1
	s_nop 1
	v_max_u32_dpp v10, v10, v10 quad_perm:[2,3,0,1] row_mask:0xf bank_mask:0xf bound_ctrl:1
	s_nop 1
	v_max_u32_dpp v10, v10, v10 row_half_mirror row_mask:0xf bank_mask:0xf bound_ctrl:1
	s_nop 1
	v_max_u32_dpp v10, v10, v10 row_mirror row_mask:0xf bank_mask:0xf bound_ctrl:1
	v_cmp_eq_u32_e32 vcc, v5, v10
	v_cndmask_b32_e64 v6, v6, v10, s[24:25]
	s_nop 0
	v_cndmask_b32_e64 v5, 0, 1, vcc
	v_lshl_add_u32 v7, v5, 2, v7
	ds_read_b32 v10, v7
	v_addc_co_u32_e32 v8, vcc, v8, v9, vcc
	v_sub_u32_e32 v9, v63, v8
	s_waitcnt lgkmcnt(0)
	v_add_f32_e32 v10, v10, v3
	v_ashrrev_i32_e32 v11, 31, v10
	v_bitop3_b32 v10, v11, v10, s70 bitop3:0x36
	v_and_or_b32 v9, v10, s77, v9
	s_nop 1
	v_max_u32_dpp v10, v9, v9 quad_perm:[1,0,3,2] row_mask:0xf bank_mask:0xf bound_ctrl:1
	s_nop 1
	v_max_u32_dpp v10, v10, v10 quad_perm:[2,3,0,1] row_mask:0xf bank_mask:0xf bound_ctrl:1
	s_nop 1
	v_max_u32_dpp v10, v10, v10 row_half_mirror row_mask:0xf bank_mask:0xf bound_ctrl:1
	s_nop 1
	v_max_u32_dpp v10, v10, v10 row_mirror row_mask:0xf bank_mask:0xf bound_ctrl:1
	v_cmp_eq_u32_e32 vcc, v9, v10
	v_cndmask_b32_e64 v6, v6, v10, s[26:27]
	s_nop 0
	v_cndmask_b32_e64 v9, 0, 1, vcc
	v_lshl_add_u32 v7, v9, 2, v7
	ds_read_b32 v10, v7
	v_addc_co_u32_e32 v4, vcc, v4, v5, vcc
	v_sub_u32_e32 v5, v63, v4
	s_waitcnt lgkmcnt(0)
	v_add_f32_e32 v10, v10, v3
	v_ashrrev_i32_e32 v11, 31, v10
	v_bitop3_b32 v10, v11, v10, s70 bitop3:0x36
	v_and_or_b32 v5, v10, s77, v5
	s_nop 1
	v_max_u32_dpp v10, v5, v5 quad_perm:[1,0,3,2] row_mask:0xf bank_mask:0xf bound_ctrl:1
	s_nop 1
	v_max_u32_dpp v10, v10, v10 quad_perm:[2,3,0,1] row_mask:0xf bank_mask:0xf bound_ctrl:1
	s_nop 1
	v_max_u32_dpp v10, v10, v10 row_half_mirror row_mask:0xf bank_mask:0xf bound_ctrl:1
	s_nop 1
	v_max_u32_dpp v10, v10, v10 row_mirror row_mask:0xf bank_mask:0xf bound_ctrl:1
	v_cmp_eq_u32_e32 vcc, v5, v10
	v_cndmask_b32_e64 v6, v6, v10, s[28:29]
	s_nop 0
	v_cndmask_b32_e64 v5, 0, 1, vcc
	v_lshl_add_u32 v7, v5, 2, v7
	ds_read_b32 v10, v7
	v_addc_co_u32_e32 v8, vcc, v8, v9, vcc
	v_sub_u32_e32 v9, v63, v8
	s_waitcnt lgkmcnt(0)
	v_add_f32_e32 v10, v10, v3
	v_ashrrev_i32_e32 v11, 31, v10
	v_bitop3_b32 v10, v11, v10, s70 bitop3:0x36
	v_and_or_b32 v9, v10, s77, v9
	s_nop 1
	v_max_u32_dpp v10, v9, v9 quad_perm:[1,0,3,2] row_mask:0xf bank_mask:0xf bound_ctrl:1
	s_nop 1
	v_max_u32_dpp v10, v10, v10 quad_perm:[2,3,0,1] row_mask:0xf bank_mask:0xf bound_ctrl:1
	s_nop 1
	v_max_u32_dpp v10, v10, v10 row_half_mirror row_mask:0xf bank_mask:0xf bound_ctrl:1
	s_nop 1
	v_max_u32_dpp v10, v10, v10 row_mirror row_mask:0xf bank_mask:0xf bound_ctrl:1
	v_cmp_eq_u32_e32 vcc, v9, v10
	v_cndmask_b32_e64 v6, v6, v10, s[30:31]
	s_nop 0
	v_cndmask_b32_e64 v9, 0, 1, vcc
	v_lshl_add_u32 v7, v9, 2, v7
	ds_read_b32 v10, v7
	v_addc_co_u32_e32 v4, vcc, v4, v5, vcc
	v_sub_u32_e32 v5, v63, v4
	s_waitcnt lgkmcnt(0)
	v_add_f32_e32 v10, v10, v3
	v_ashrrev_i32_e32 v11, 31, v10
	v_bitop3_b32 v10, v11, v10, s70 bitop3:0x36
	v_and_or_b32 v5, v10, s77, v5
	s_nop 1
	v_max_u32_dpp v10, v5, v5 quad_perm:[1,0,3,2] row_mask:0xf bank_mask:0xf bound_ctrl:1
	s_nop 1
	v_max_u32_dpp v10, v10, v10 quad_perm:[2,3,0,1] row_mask:0xf bank_mask:0xf bound_ctrl:1
	s_nop 1
	v_max_u32_dpp v10, v10, v10 row_half_mirror row_mask:0xf bank_mask:0xf bound_ctrl:1
	s_nop 1
	v_max_u32_dpp v10, v10, v10 row_mirror row_mask:0xf bank_mask:0xf bound_ctrl:1
	v_cmp_eq_u32_e32 vcc, v5, v10
	v_cndmask_b32_e64 v6, v6, v10, s[34:35]
	s_nop 0
	v_cndmask_b32_e64 v5, 0, 1, vcc
	v_lshl_add_u32 v7, v5, 2, v7
	ds_read_b32 v10, v7
	v_addc_co_u32_e32 v8, vcc, v8, v9, vcc
	v_sub_u32_e32 v9, v63, v8
	s_waitcnt lgkmcnt(0)
	v_add_f32_e32 v10, v10, v3
	v_ashrrev_i32_e32 v11, 31, v10
	v_bitop3_b32 v10, v11, v10, s70 bitop3:0x36
	v_and_or_b32 v9, v10, s77, v9
	s_nop 1
	v_max_u32_dpp v10, v9, v9 quad_perm:[1,0,3,2] row_mask:0xf bank_mask:0xf bound_ctrl:1
	s_nop 1
	v_max_u32_dpp v10, v10, v10 quad_perm:[2,3,0,1] row_mask:0xf bank_mask:0xf bound_ctrl:1
	s_nop 1
	v_max_u32_dpp v10, v10, v10 row_half_mirror row_mask:0xf bank_mask:0xf bound_ctrl:1
	s_nop 1
	v_max_u32_dpp v10, v10, v10 row_mirror row_mask:0xf bank_mask:0xf bound_ctrl:1
	v_cmp_eq_u32_e32 vcc, v9, v10
	v_cndmask_b32_e64 v6, v6, v10, s[36:37]
	s_nop 0
	v_cndmask_b32_e64 v9, 0, 1, vcc
	v_lshl_add_u32 v7, v9, 2, v7
	ds_read_b32 v10, v7
	v_addc_co_u32_e32 v4, vcc, v4, v5, vcc
	v_sub_u32_e32 v5, v63, v4
	s_waitcnt lgkmcnt(0)
	v_add_f32_e32 v10, v10, v3
	v_ashrrev_i32_e32 v11, 31, v10
	v_bitop3_b32 v10, v11, v10, s70 bitop3:0x36
	v_and_or_b32 v5, v10, s77, v5
	s_nop 1
	v_max_u32_dpp v10, v5, v5 quad_perm:[1,0,3,2] row_mask:0xf bank_mask:0xf bound_ctrl:1
	s_nop 1
	v_max_u32_dpp v10, v10, v10 quad_perm:[2,3,0,1] row_mask:0xf bank_mask:0xf bound_ctrl:1
	s_nop 1
	v_max_u32_dpp v10, v10, v10 row_half_mirror row_mask:0xf bank_mask:0xf bound_ctrl:1
	s_nop 1
	v_max_u32_dpp v10, v10, v10 row_mirror row_mask:0xf bank_mask:0xf bound_ctrl:1
	v_cmp_eq_u32_e32 vcc, v5, v10
	v_cndmask_b32_e64 v6, v6, v10, s[38:39]
	s_nop 0
	v_cndmask_b32_e64 v5, 0, 1, vcc
	v_lshl_add_u32 v7, v5, 2, v7
	v_addc_co_u32_e32 v8, vcc, v8, v9, vcc
	ds_read_b32 v9, v7
	v_sub_u32_e32 v8, v63, v8
	s_waitcnt lgkmcnt(0)
	v_add_f32_e32 v9, v9, v3
	v_ashrrev_i32_e32 v10, 31, v9
	v_bitop3_b32 v9, v10, v9, s70 bitop3:0x36
	v_and_or_b32 v8, v9, s77, v8
	s_nop 1
	v_max_u32_dpp v9, v8, v8 quad_perm:[1,0,3,2] row_mask:0xf bank_mask:0xf bound_ctrl:1
	s_nop 1
	v_max_u32_dpp v9, v9, v9 quad_perm:[2,3,0,1] row_mask:0xf bank_mask:0xf bound_ctrl:1
	s_nop 1
	v_max_u32_dpp v9, v9, v9 row_half_mirror row_mask:0xf bank_mask:0xf bound_ctrl:1
	s_nop 1
	v_max_u32_dpp v9, v9, v9 row_mirror row_mask:0xf bank_mask:0xf bound_ctrl:1
	v_cmp_eq_u32_e32 vcc, v8, v9
	v_cndmask_b32_e64 v6, v6, v9, s[40:41]
	s_nop 0
	v_cndmask_b32_e64 v8, 0, 1, vcc
	v_addc_co_u32_e32 v4, vcc, v4, v5, vcc
	v_lshl_add_u32 v5, v8, 2, v7
	ds_read_b32 v5, v5
	v_sub_u32_e32 v4, v63, v4
	s_waitcnt lgkmcnt(0)
	v_add_f32_e32 v3, v5, v3
	v_ashrrev_i32_e32 v5, 31, v3
	v_bitop3_b32 v3, v5, v3, s70 bitop3:0x36
	v_and_or_b32 v3, v3, s77, v4
	s_nop 1
	v_max_u32_dpp v3, v3, v3 quad_perm:[1,0,3,2] row_mask:0xf bank_mask:0xf bound_ctrl:1
	s_nop 1
	v_max_u32_dpp v3, v3, v3 quad_perm:[2,3,0,1] row_mask:0xf bank_mask:0xf bound_ctrl:1
	s_nop 1
	v_max_u32_dpp v3, v3, v3 row_half_mirror row_mask:0xf bank_mask:0xf bound_ctrl:1
	s_nop 1
	v_max_u32_dpp v3, v3, v3 row_mirror row_mask:0xf bank_mask:0xf bound_ctrl:1
	v_cndmask_b32_e64 v3, v6, v3, s[42:43]
	v_cmp_lt_i32_e32 vcc, -1, v3
	v_not_b32_e32 v4, v3
	v_bitop3_b32 v6, v3, 15, v3 bitop3:0xc
	v_cndmask_b32_e64 v5, v78, -1, vcc
	v_bitop3_b32 v5, v5, v3, s77 bitop3:0x78
	v_max_u32_dpp v3, v3, v3 quad_perm:[1,0,3,2] row_mask:0xf bank_mask:0xf bound_ctrl:1
	v_lshrrev_b32_e32 v4, 2, v4
	v_and_b32_e32 v4, 60, v4
	v_max_u32_dpp v3, v3, v3 quad_perm:[2,3,0,1] row_mask:0xf bank_mask:0xf bound_ctrl:1
	v_add_u32_e32 v4, v60, v4
	v_lshl_add_u32 v6, v6, 2, v60
	v_max_u32_dpp v3, v3, v3 row_half_mirror row_mask:0xf bank_mask:0xf bound_ctrl:1
	ds_read_b32 v4, v4 offset:64
	ds_read_b32 v6, v6 offset:128
	v_max_u32_dpp v3, v3, v3 row_mirror row_mask:0xf bank_mask:0xf bound_ctrl:1
	v_cmp_lt_i32_e32 vcc, -1, v3
	s_waitcnt lgkmcnt(0)
	v_lshl_add_u32 v6, v4, 7, v6
	v_cndmask_b32_e64 v7, v78, -1, vcc
	v_bitop3_b32 v3, v7, v3, s77 bitop3:0x78
	v_sub_f32_e32 v3, v5, v3
	v_mul_f32_e32 v3, 0x3fb8aa3b, v3
	v_exp_f32_e32 v7, v3
	s_nop 1
	v_add_f32_dpp v3, v7, v7 quad_perm:[1,0,3,2] row_mask:0xf bank_mask:0xf bound_ctrl:1
	s_nop 1
	v_add_f32_dpp v3, v3, v3 quad_perm:[2,3,0,1] row_mask:0xf bank_mask:0xf bound_ctrl:1
	s_nop 1
	v_add_f32_dpp v3, v3, v3 row_half_mirror row_mask:0xf bank_mask:0xf bound_ctrl:1
	s_nop 1
	v_add_f32_dpp v8, v3, v3 row_mirror row_mask:0xf bank_mask:0xf bound_ctrl:1
	v_ashrrev_i32_e32 v3, 31, v2
	v_lshlrev_b64 v[2:3], 9, v[2:3]
	v_or_b32_e32 v2, v2, v79
	v_lshl_add_u64 v[4:5], s[44:45], 0, v[2:3]
	global_store_dword v[4:5], v6, off
	v_div_scale_f32 v4, s[54:55], v8, v8, v7
	v_rcp_f32_e32 v5, v4
	v_lshl_add_u64 v[2:3], s[48:49], 0, v[2:3]
	v_fma_f32 v6, -v4, v5, 1.0
	v_fmac_f32_e32 v5, v6, v5
	v_div_scale_f32 v6, vcc, v7, v8, v7
	v_mul_f32_e32 v9, v6, v5
	v_fma_f32 v10, -v4, v9, v6
	v_fmac_f32_e32 v9, v10, v5
	v_fma_f32 v4, -v4, v9, v6
	v_div_fmas_f32 v4, v4, v5, v9
	v_cmp_le_i32_e32 vcc, s2, v46
	v_div_fixup_f32 v4, v4, v8, v7
	s_or_b64 s[60:61], vcc, s[60:61]
	global_store_dword v[2:3], v4, off
	s_andn2_b64 exec, exec, s[60:61]
	s_cbranch_execnz .LBB0_2886
	s_branch .LBB0_2880
